# dil loop: next group's bias-table reads issued right after the row-sum adds so their latency hides under the PV MFMAs
# speedup vs baseline: 1.0111x; 1.0111x over previous
; #define LAS __attribute__((address_space(3)))
; #define GAS __attribute__((address_space(1)))
; __device__ __forceinline__ void dil_unit(LAS unsigned char* lds, bf16_t* proj, int seq, int hd, int T0, int rho) {
;     int tid_ = threadIdx.x; asm volatile("" : "+v"(tid_));
;     const int tid = tid_, lane = tid & 63, r32 = lane & 31, hi = lane >> 5, wid = __builtin_amdgcn_readfirstlane(tid >> 6);
;     bf16_t* base = proj + (size_t)seq * SEQ * NIN;
;     LAS unsigned char* wbuf = lds + wid * 4096;
;     const LAS unsigned char* vp = wbuf + ((lane >> 4) & 1) * 32 + (lane & 3) * 8 + (4 * hi + ((lane & 15) >> 2)) * 64;
;     const int P0 = T0 + rho;
;     bf16x8 qr[4];
; #pragma unroll
;     for (int ks = 0; ks < 4; ++ks) qr[ks] = *(const GAS bf16x8*)(base + (size_t)(P0 + 16 * r32) * NIN + PC_LQ + hd * 64 + 16 * ks + 8 * hi);
;     f32x16 o0 = {}, o1 = {}; float l = 0.f;
;     const bool bound = (T0 < 1024) || (T0 >= 15360);
; __device__ __forceinline__ void attn_phase(unsigned char* ws, int l, LAS unsigned char* lds, int G) {
;     ...
;     for (int bu = vb; bu < 1152; bu += G) {
;         const int sh = bu >> 6, rem = bu & 63, T0 = (rem >> 1) * 512, rho = (rem & 1) * 8 + wid;
;         dil_unit(lds, proj, sh / 6, sh % 6, T0, rho);
.LBB0_554:
	s_lshr_b32 s82, s33, 8
	s_mul_i32 s82, s82, 13
	s_add_i32 s82, s82, s33
	s_ashr_i32 s2, s33, 6
	s_mul_hi_i32 s7, s2, 0x2aaaaaab
	s_lshl_b32 s3, s82, 8
	s_lshr_b32 s8, s7, 31
	s_and_b32 s6, s3, 0x3e00
	s_lshl_b32 s3, s82, 3
	s_add_i32 s7, s7, s8
	s_and_b32 s3, s3, 8
	s_mul_i32 s8, s7, 6
	s_add_i32 s3, s3, s64
	s_sub_i32 s8, s2, s8
	s_mul_hi_i32 s2, s7, 0x6000000
	s_mul_i32 s7, s7, 0x6000000
	v_mov_b32_e32 v2, v154
	s_add_u32 s56, s48, s7
	s_addc_u32 s57, s49, s2
	v_and_b32_e32 v105, 31, v2
	s_add_i32 s76, s3, s6
	v_lshl_add_u32 v3, v105, 4, s76
	v_mov_b64_e32 v[0:1], s[56:57]
	s_lshl_b32 s58, s8, 6
	v_bfe_u32 v106, v2, 5, 1
	v_mad_u64_u32 v[0:1], s[2:3], v3, s65, v[0:1]
	s_ashr_i32 s59, s58, 31
	v_lshl_add_u64 v[0:1], s[58:59], 1, v[0:1]
	v_lshlrev_b32_e32 v80, 4, v106
	v_lshl_add_u64 v[0:1], v[0:1], 0, v[80:81]
	global_load_dwordx4 v[48:51], v[0:1], off offset:1280
	global_load_dwordx4 v[52:55], v[0:1], off offset:1312
	global_load_dwordx4 v[56:59], v[0:1], off offset:1344
	global_load_dwordx4 v[60:63], v[0:1], off offset:1376
	v_readfirstlane_b32 s2, v2
	s_lshl_b32 s2, s2, 6
	s_and_b32 s2, s2, 0xfffff000
	v_lshlrev_b32_e32 v0, 1, v2
	v_lshlrev_b32_e32 v104, 3, v2
	v_lshlrev_b32_e32 v107, 2, v106
	v_lshrrev_b32_e32 v1, 2, v2
	v_and_b32_e32 v103, 63, v2
	v_and_b32_e32 v0, 32, v0
	v_and_b32_e32 v98, 24, v104
	v_and_or_b32 v1, v1, 3, v107
	s_add_i32 s77, s2, 0
	v_lshlrev_b32_e32 v108, 6, v1
	v_lshlrev_b32_e32 v1, 3, v106
	v_add3_u32 v109, s77, v0, v98
	s_addk_i32 s6, 0xc400
	v_lshrrev_b32_e32 v110, 2, v103
	v_lshlrev_b32_e32 v0, 4, v103
	s_mov_b64 s[2:3], -1
	s_cmp_gt_u32 s6, 0xffffc7ff
	v_lshlrev_b32_e32 v100, 1, v98
	s_mul_i32 s6, s8, 0x1c00
	v_lshlrev_b32_e32 v82, 1, v1
	v_or_b32_e32 v111, 16, v110
	v_add_u32_e32 v112, s77, v0
	s_cbranch_scc0 .LBB0_558
	s_movk_i32 s100, 0x1800
	s_add_i32 s101, s6, 0x15c00
	s_lshl_b32 s90, s58, 1
	s_add_u32 s82, s56, s90
	s_addc_u32 s83, s57, 0
	s_add_u32 s82, s82, 0x1200
	s_addc_u32 s83, s83, 0
	s_sub_i32 s90, s76, 64
	s_mul_i32 s90, s90, 0x1800
	s_add_u32 s84, s82, s90
	s_addc_u32 s85, s83, 0
	s_sub_i32 s90, s76, 256
	s_mul_i32 s90, s90, 0x1800
	s_add_u32 s86, s82, s90
	s_addc_u32 s87, s83, 0
	s_sub_i32 s90, s76, 1024
	s_mul_i32 s90, s90, 0x1800
	s_add_u32 s88, s82, s90
	s_addc_u32 s89, s83, 0
	v_lshlrev_b32_e32 v153, 1, v98
	v_mad_u32_u24 v80, v105, s100, v82
	v_mad_u32_u24 v100, v110, s100, v153
	v_add_u32_e32 v149, 0x18000, v100
	v_lshlrev_b32_e32 v83, 2, v105
	v_mad_u32_u24 v83, v83, s100, v82
	v_lshlrev_b32_e32 v101, 2, v110
	v_mad_u32_u24 v101, v101, s100, v153
	v_add_u32_e32 v150, 0x60000, v101
	v_lshlrev_b32_e32 v99, 4, v105
	v_mad_u32_u24 v99, v99, s100, v82
	v_lshlrev_b32_e32 v148, 4, v110
	v_mad_u32_u24 v148, v148, s100, v153
	v_add_u32_e32 v151, 0x180000, v148
	v_lshrrev_b32_e32 v249, 3, v103
	v_and_b32_e32 v250, 7, v103
	v_lshlrev_b32_e32 v250, 4, v250
	v_add_u32_e32 v235, 0, v249
	v_mad_u32_u24 v235, v235, s100, v250
	v_add_u32_e32 v236, 8, v249
	v_mad_u32_u24 v236, v236, s100, v250
	v_add_u32_e32 v237, 16, v249
	v_mad_u32_u24 v237, v237, s100, v250
	v_add_u32_e32 v238, 24, v249
	v_mad_u32_u24 v238, v238, s100, v250
	v_add_u32_e32 v239, 0, v249
	v_lshlrev_b32_e32 v239, 2, v239
	v_mad_u32_u24 v239, v239, s100, v250
	v_add_u32_e32 v240, 8, v249
	v_lshlrev_b32_e32 v240, 2, v240
	v_mad_u32_u24 v240, v240, s100, v250
	v_add_u32_e32 v241, 16, v249
	v_lshlrev_b32_e32 v241, 2, v241
	v_mad_u32_u24 v241, v241, s100, v250
	v_add_u32_e32 v242, 24, v249
	v_lshlrev_b32_e32 v242, 2, v242
	v_mad_u32_u24 v242, v242, s100, v250
	v_add_u32_e32 v243, 0, v249
	v_lshlrev_b32_e32 v243, 4, v243
	v_mad_u32_u24 v243, v243, s100, v250
	v_add_u32_e32 v244, 8, v249
	v_lshlrev_b32_e32 v244, 4, v244
	v_mad_u32_u24 v244, v244, s100, v250
	v_add_u32_e32 v245, 16, v249
	v_lshlrev_b32_e32 v245, 4, v245
	v_mad_u32_u24 v245, v245, s100, v250
	v_add_u32_e32 v246, 24, v249
	v_lshlrev_b32_e32 v246, 4, v246
	v_mad_u32_u24 v246, v246, s100, v250
	v_and_b32_e32 v247, 7, v249
	v_lshlrev_b32_e32 v247, 4, v247
	v_xor_b32_e32 v247, v247, v112
	v_and_b32_e32 v153, 7, v105
	v_or_b32_e32 v248, 0, v106
	v_xor_b32_e32 v248, v248, v153
	v_lshlrev_b32_e32 v248, 4, v248
	v_lshl_add_u32 v248, v105, 7, v248
	v_add_u32_e32 v248, s77, v248
	v_or_b32_e32 v249, 2, v106
	v_xor_b32_e32 v249, v249, v153
	v_lshlrev_b32_e32 v249, 4, v249
	v_lshl_add_u32 v249, v105, 7, v249
	v_add_u32_e32 v249, s77, v249
	v_or_b32_e32 v250, 4, v106
	v_xor_b32_e32 v250, v250, v153
	v_lshlrev_b32_e32 v250, 4, v250
	v_lshl_add_u32 v250, v105, 7, v250
	v_add_u32_e32 v250, s77, v250
	v_or_b32_e32 v251, 6, v106
	v_xor_b32_e32 v251, v251, v153
	v_lshlrev_b32_e32 v251, 4, v251
	v_lshl_add_u32 v251, v105, 7, v251
	v_add_u32_e32 v251, s77, v251
	v_lshlrev_b32_e32 v153, 1, v98
	v_mul_u32_u24_e32 v228, 17, v105
	v_sub_u32_e32 v228, v107, v228
	s_mul_i32 s90, s58, 153
	s_lshr_b32 s90, s90, 1
	s_add_i32 s90, s90, 34876
	v_lshl_add_u32 v228, v228, 2, s90
	v_lshlrev_b32_e32 v229, 2, v105
	v_sub_u32_e32 v229, v107, v229
	s_add_i32 s90, s101, 5104
	v_lshl_add_u32 v229, v229, 2, s90
	v_sub_u32_e32 v230, v107, v105
	s_add_i32 s90, s101, 6364
	v_lshl_add_u32 v230, v230, 2, s90
	v_add_u32_e32 v231, v109, v108
	v_mov_b64_e32 v[232:233], 0
	v_mov_b64_e32 v[0:1], 0
	v_mov_b64_e32 v[2:3], 0
	v_mov_b64_e32 v[4:5], 0
	v_mov_b64_e32 v[6:7], 0
	v_mov_b64_e32 v[8:9], 0
	v_mov_b64_e32 v[10:11], 0
	v_mov_b64_e32 v[12:13], 0
	v_mov_b64_e32 v[14:15], 0
	v_mov_b64_e32 v[16:17], 0
	v_mov_b64_e32 v[18:19], 0
	v_mov_b64_e32 v[20:21], 0
	v_mov_b64_e32 v[22:23], 0
	v_mov_b64_e32 v[24:25], 0
	v_mov_b64_e32 v[26:27], 0
	v_mov_b64_e32 v[28:29], 0
	v_mov_b64_e32 v[30:31], 0
	global_load_dwordx4 v[116:119], v235, s[84:85]
	global_load_dwordx4 v[120:123], v236, s[84:85]
	global_load_dwordx4 v[124:127], v237, s[84:85]
	global_load_dwordx4 v[128:131], v238, s[84:85]
	global_load_dwordx4 v[132:135], v100, s[84:85] offset:768
	global_load_dwordx4 v[136:139], v149, s[84:85] offset:768
	global_load_dwordx4 v[140:143], v100, s[84:85] offset:832
	global_load_dwordx4 v[144:147], v149, s[84:85] offset:832
	s_add_u32 s84, s84, 0x30000
	s_addc_u32 s85, s85, 0
	global_load_dwordx4 v[156:159], v235, s[84:85]
	global_load_dwordx4 v[160:163], v236, s[84:85]
	global_load_dwordx4 v[164:167], v237, s[84:85]
	global_load_dwordx4 v[168:171], v238, s[84:85]
	global_load_dwordx4 v[172:175], v100, s[84:85] offset:768
	global_load_dwordx4 v[176:179], v149, s[84:85] offset:768
	global_load_dwordx4 v[180:183], v100, s[84:85] offset:832
	global_load_dwordx4 v[184:187], v149, s[84:85] offset:832
	s_add_u32 s84, s84, 0x30000
	s_addc_u32 s85, s85, 0
	global_load_dwordx4 v[188:191], v235, s[84:85]
	global_load_dwordx4 v[192:195], v236, s[84:85]
	global_load_dwordx4 v[196:199], v237, s[84:85]
	global_load_dwordx4 v[200:203], v238, s[84:85]
	global_load_dwordx4 v[204:207], v100, s[84:85] offset:768
	global_load_dwordx4 v[208:211], v149, s[84:85] offset:768
	global_load_dwordx4 v[212:215], v100, s[84:85] offset:832
	global_load_dwordx4 v[216:219], v149, s[84:85] offset:832
	s_add_u32 s84, s84, 0x30000
	s_addc_u32 s85, s85, 0
	s_waitcnt vmcnt(16)
	ds_write_b128 v247, v[116:119]
	ds_write_b128 v247, v[120:123] offset:1024
	ds_write_b128 v247, v[124:127] offset:2048
	ds_write_b128 v247, v[128:131] offset:3072
	ds_read_b128 v[116:119], v248
	ds_read_b128 v[120:123], v249
	ds_read_b128 v[124:127], v250
	ds_read_b128 v[128:131], v251
	ds_write_b128 v112, v[132:135]
	ds_write_b128 v112, v[136:139] offset:1024
	ds_write_b128 v112, v[140:143] offset:2048
	ds_write_b128 v112, v[144:147] offset:3072
	v_mov_b32_e32 v115, v228
	ds_read2_b32 v[32:33], v115 offset0:0 offset1:1
	ds_read2_b32 v[34:35], v115 offset0:2 offset1:3
	ds_read2_b32 v[36:37], v115 offset0:8 offset1:9
	ds_read2_b32 v[38:39], v115 offset0:10 offset1:11
	ds_read2_b32 v[40:41], v115 offset0:17 offset1:18
	ds_read2_b32 v[42:43], v115 offset0:19 offset1:20
	ds_read2_b32 v[44:45], v115 offset0:25 offset1:26
	ds_read2_b32 v[46:47], v115 offset0:27 offset1:28
	s_waitcnt lgkmcnt(0)
	v_mfma_f32_32x32x16_bf16 v[32:47], v[116:119], v[48:51], v[32:47]
	ds_read_b64_tr_b16 v[72:73], v231
	ds_read_b64_tr_b16 v[74:75], v231 offset:512
	ds_read_b64_tr_b16 v[76:77], v231 offset:2048
	ds_read_b64_tr_b16 v[78:79], v231 offset:2560
	ds_read_b64_tr_b16 v[220:221], v231 offset:1024
	ds_read_b64_tr_b16 v[222:223], v231 offset:1536
	ds_read_b64_tr_b16 v[224:225], v231 offset:3072
	ds_read_b64_tr_b16 v[226:227], v231 offset:3584
	s_waitcnt vmcnt(8)
	ds_write_b128 v247, v[156:159]
	ds_write_b128 v247, v[160:163] offset:1024
	ds_write_b128 v247, v[164:167] offset:2048
	ds_write_b128 v247, v[168:171] offset:3072
	ds_read_b128 v[156:159], v248
	ds_read_b128 v[160:163], v249
	ds_read_b128 v[164:167], v250
	ds_read_b128 v[168:171], v251
	ds_write_b128 v112, v[172:175]
	ds_write_b128 v112, v[176:179] offset:1024
	ds_write_b128 v112, v[180:183] offset:2048
	ds_write_b128 v112, v[184:187] offset:3072
	v_mfma_f32_32x32x16_bf16 v[32:47], v[120:123], v[52:55], v[32:47]
	v_mfma_f32_32x32x16_bf16 v[32:47], v[124:127], v[56:59], v[32:47]
	v_mfma_f32_32x32x16_bf16 v[32:47], v[128:131], v[60:63], v[32:47]
	s_nop 11
	v_exp_f32_e32 v32, v32
	v_exp_f32_e32 v33, v33
	v_exp_f32_e32 v34, v34
	v_exp_f32_e32 v35, v35
	v_exp_f32_e32 v36, v36
	v_exp_f32_e32 v37, v37
	v_exp_f32_e32 v38, v38
	v_exp_f32_e32 v39, v39
	v_exp_f32_e32 v40, v40
	v_exp_f32_e32 v41, v41
	v_exp_f32_e32 v42, v42
	v_exp_f32_e32 v43, v43
	v_exp_f32_e32 v44, v44
	v_exp_f32_e32 v45, v45
	v_exp_f32_e32 v46, v46
	v_exp_f32_e32 v47, v47
	v_cvt_pk_bf16_f32 v64, v32, v33
	v_cvt_pk_bf16_f32 v65, v34, v35
	v_cvt_pk_bf16_f32 v66, v36, v37
	v_cvt_pk_bf16_f32 v67, v38, v39
	v_cvt_pk_bf16_f32 v68, v40, v41
	v_cvt_pk_bf16_f32 v69, v42, v43
	v_cvt_pk_bf16_f32 v70, v44, v45
	v_cvt_pk_bf16_f32 v71, v46, v47
	v_pk_add_f32 v[232:233], v[232:233], v[32:33]
	v_pk_add_f32 v[232:233], v[232:233], v[34:35]
	v_pk_add_f32 v[232:233], v[232:233], v[36:37]
	v_pk_add_f32 v[232:233], v[232:233], v[38:39]
	v_pk_add_f32 v[232:233], v[232:233], v[40:41]
	v_pk_add_f32 v[232:233], v[232:233], v[42:43]
	v_pk_add_f32 v[232:233], v[232:233], v[44:45]
	v_pk_add_f32 v[232:233], v[232:233], v[46:47]
	ds_read2_b32 v[32:33], v115 offset0:34 offset1:35
	ds_read2_b32 v[34:35], v115 offset0:36 offset1:37
	ds_read2_b32 v[36:37], v115 offset0:42 offset1:43
	ds_read2_b32 v[38:39], v115 offset0:44 offset1:45
	ds_read2_b32 v[40:41], v115 offset0:51 offset1:52
	ds_read2_b32 v[42:43], v115 offset0:53 offset1:54
	ds_read2_b32 v[44:45], v115 offset0:59 offset1:60
	ds_read2_b32 v[46:47], v115 offset0:61 offset1:62
	s_waitcnt lgkmcnt(15)
	v_mfma_f32_32x32x16_bf16 v[0:15], v[64:67], v[72:75], v[0:15]
	v_mfma_f32_32x32x16_bf16 v[16:31], v[64:67], v[76:79], v[16:31]
	v_mfma_f32_32x32x16_bf16 v[0:15], v[68:71], v[220:223], v[0:15]
	v_mfma_f32_32x32x16_bf16 v[16:31], v[68:71], v[224:227], v[16:31]
	global_load_dwordx4 v[116:119], v235, s[84:85]
	global_load_dwordx4 v[120:123], v236, s[84:85]
	global_load_dwordx4 v[124:127], v237, s[84:85]
	global_load_dwordx4 v[128:131], v238, s[84:85]
	global_load_dwordx4 v[132:135], v100, s[84:85] offset:768
	global_load_dwordx4 v[136:139], v149, s[84:85] offset:768
	global_load_dwordx4 v[140:143], v100, s[84:85] offset:832
	global_load_dwordx4 v[144:147], v149, s[84:85] offset:832
	s_add_u32 s84, s84, 0x30000
	s_addc_u32 s85, s85, 0
	s_waitcnt lgkmcnt(0)
	v_mfma_f32_32x32x16_bf16 v[32:47], v[156:159], v[48:51], v[32:47]
	ds_read_b64_tr_b16 v[72:73], v231
	ds_read_b64_tr_b16 v[74:75], v231 offset:512
	ds_read_b64_tr_b16 v[76:77], v231 offset:2048
	ds_read_b64_tr_b16 v[78:79], v231 offset:2560
	ds_read_b64_tr_b16 v[220:221], v231 offset:1024
	ds_read_b64_tr_b16 v[222:223], v231 offset:1536
	ds_read_b64_tr_b16 v[224:225], v231 offset:3072
	ds_read_b64_tr_b16 v[226:227], v231 offset:3584
	s_waitcnt vmcnt(8)
	ds_write_b128 v247, v[188:191]
	ds_write_b128 v247, v[192:195] offset:1024
	ds_write_b128 v247, v[196:199] offset:2048
	ds_write_b128 v247, v[200:203] offset:3072
	ds_read_b128 v[188:191], v248
	ds_read_b128 v[192:195], v249
	ds_read_b128 v[196:199], v250
	ds_read_b128 v[200:203], v251
	ds_write_b128 v112, v[204:207]
	ds_write_b128 v112, v[208:211] offset:1024
	ds_write_b128 v112, v[212:215] offset:2048
	ds_write_b128 v112, v[216:219] offset:3072
	v_mfma_f32_32x32x16_bf16 v[32:47], v[160:163], v[52:55], v[32:47]
	v_mfma_f32_32x32x16_bf16 v[32:47], v[164:167], v[56:59], v[32:47]
	v_mfma_f32_32x32x16_bf16 v[32:47], v[168:171], v[60:63], v[32:47]
	s_nop 11
	v_exp_f32_e32 v32, v32
	v_exp_f32_e32 v33, v33
	v_exp_f32_e32 v34, v34
	v_exp_f32_e32 v35, v35
	v_exp_f32_e32 v36, v36
	v_exp_f32_e32 v37, v37
	v_exp_f32_e32 v38, v38
	v_exp_f32_e32 v39, v39
	v_exp_f32_e32 v40, v40
	v_exp_f32_e32 v41, v41
	v_exp_f32_e32 v42, v42
	v_exp_f32_e32 v43, v43
	v_exp_f32_e32 v44, v44
	v_exp_f32_e32 v45, v45
	v_exp_f32_e32 v46, v46
	v_exp_f32_e32 v47, v47
	v_cvt_pk_bf16_f32 v64, v32, v33
	v_cvt_pk_bf16_f32 v65, v34, v35
	v_cvt_pk_bf16_f32 v66, v36, v37
	v_cvt_pk_bf16_f32 v67, v38, v39
	v_cvt_pk_bf16_f32 v68, v40, v41
	v_cvt_pk_bf16_f32 v69, v42, v43
	v_cvt_pk_bf16_f32 v70, v44, v45
	v_cvt_pk_bf16_f32 v71, v46, v47
	v_pk_add_f32 v[232:233], v[232:233], v[32:33]
	v_pk_add_f32 v[232:233], v[232:233], v[34:35]
	v_pk_add_f32 v[232:233], v[232:233], v[36:37]
	v_pk_add_f32 v[232:233], v[232:233], v[38:39]
	v_pk_add_f32 v[232:233], v[232:233], v[40:41]
	v_pk_add_f32 v[232:233], v[232:233], v[42:43]
	v_pk_add_f32 v[232:233], v[232:233], v[44:45]
	v_pk_add_f32 v[232:233], v[232:233], v[46:47]
	ds_read2_b32 v[32:33], v115 offset0:68 offset1:69
	ds_read2_b32 v[34:35], v115 offset0:70 offset1:71
	ds_read2_b32 v[36:37], v115 offset0:76 offset1:77
	ds_read2_b32 v[38:39], v115 offset0:78 offset1:79
	ds_read2_b32 v[40:41], v115 offset0:85 offset1:86
	ds_read2_b32 v[42:43], v115 offset0:87 offset1:88
	ds_read2_b32 v[44:45], v115 offset0:93 offset1:94
	ds_read2_b32 v[46:47], v115 offset0:95 offset1:96
	s_waitcnt lgkmcnt(15)
	v_mfma_f32_32x32x16_bf16 v[0:15], v[64:67], v[72:75], v[0:15]
	v_mfma_f32_32x32x16_bf16 v[16:31], v[64:67], v[76:79], v[16:31]
	v_mfma_f32_32x32x16_bf16 v[0:15], v[68:71], v[220:223], v[0:15]
	v_mfma_f32_32x32x16_bf16 v[16:31], v[68:71], v[224:227], v[16:31]
	global_load_dwordx4 v[156:159], v235, s[84:85]
	global_load_dwordx4 v[160:163], v236, s[84:85]
	global_load_dwordx4 v[164:167], v237, s[84:85]
	global_load_dwordx4 v[168:171], v238, s[84:85]
	global_load_dwordx4 v[172:175], v100, s[84:85] offset:768
	global_load_dwordx4 v[176:179], v149, s[84:85] offset:768
	global_load_dwordx4 v[180:183], v100, s[84:85] offset:832
	global_load_dwordx4 v[184:187], v149, s[84:85] offset:832
	s_add_u32 s84, s84, 0x30000
	s_addc_u32 s85, s85, 0
	s_waitcnt lgkmcnt(0)
	v_mfma_f32_32x32x16_bf16 v[32:47], v[188:191], v[48:51], v[32:47]
	ds_read_b64_tr_b16 v[72:73], v231
	ds_read_b64_tr_b16 v[74:75], v231 offset:512
	ds_read_b64_tr_b16 v[76:77], v231 offset:2048
	ds_read_b64_tr_b16 v[78:79], v231 offset:2560
	ds_read_b64_tr_b16 v[220:221], v231 offset:1024
	ds_read_b64_tr_b16 v[222:223], v231 offset:1536
	ds_read_b64_tr_b16 v[224:225], v231 offset:3072
	ds_read_b64_tr_b16 v[226:227], v231 offset:3584
	s_waitcnt vmcnt(8)
	ds_write_b128 v247, v[116:119]
	ds_write_b128 v247, v[120:123] offset:1024
	ds_write_b128 v247, v[124:127] offset:2048
	ds_write_b128 v247, v[128:131] offset:3072
	ds_read_b128 v[116:119], v248
	ds_read_b128 v[120:123], v249
	ds_read_b128 v[124:127], v250
	ds_read_b128 v[128:131], v251
	ds_write_b128 v112, v[132:135]
	ds_write_b128 v112, v[136:139] offset:1024
	ds_write_b128 v112, v[140:143] offset:2048
	ds_write_b128 v112, v[144:147] offset:3072
	v_mfma_f32_32x32x16_bf16 v[32:47], v[192:195], v[52:55], v[32:47]
	v_mfma_f32_32x32x16_bf16 v[32:47], v[196:199], v[56:59], v[32:47]
	v_mfma_f32_32x32x16_bf16 v[32:47], v[200:203], v[60:63], v[32:47]
	s_nop 11
	v_exp_f32_e32 v32, v32
	v_exp_f32_e32 v33, v33
	v_exp_f32_e32 v34, v34
	v_exp_f32_e32 v35, v35
	v_exp_f32_e32 v36, v36
	v_exp_f32_e32 v37, v37
	v_exp_f32_e32 v38, v38
	v_exp_f32_e32 v39, v39
	v_exp_f32_e32 v40, v40
	v_exp_f32_e32 v41, v41
	v_exp_f32_e32 v42, v42
	v_exp_f32_e32 v43, v43
	v_exp_f32_e32 v44, v44
	v_exp_f32_e32 v45, v45
	v_exp_f32_e32 v46, v46
	v_exp_f32_e32 v47, v47
	v_cvt_pk_bf16_f32 v64, v32, v33
	v_cvt_pk_bf16_f32 v65, v34, v35
	v_cvt_pk_bf16_f32 v66, v36, v37
	v_cvt_pk_bf16_f32 v67, v38, v39
	v_cvt_pk_bf16_f32 v68, v40, v41
	v_cvt_pk_bf16_f32 v69, v42, v43
	v_cvt_pk_bf16_f32 v70, v44, v45
	v_cvt_pk_bf16_f32 v71, v46, v47
	v_pk_add_f32 v[232:233], v[232:233], v[32:33]
	v_pk_add_f32 v[232:233], v[232:233], v[34:35]
	v_pk_add_f32 v[232:233], v[232:233], v[36:37]
	v_pk_add_f32 v[232:233], v[232:233], v[38:39]
	v_pk_add_f32 v[232:233], v[232:233], v[40:41]
	v_pk_add_f32 v[232:233], v[232:233], v[42:43]
	v_pk_add_f32 v[232:233], v[232:233], v[44:45]
	v_pk_add_f32 v[232:233], v[232:233], v[46:47]
	ds_read2_b32 v[32:33], v115 offset0:102 offset1:103
	ds_read2_b32 v[34:35], v115 offset0:104 offset1:105
	ds_read2_b32 v[36:37], v115 offset0:110 offset1:111
	ds_read2_b32 v[38:39], v115 offset0:112 offset1:113
	ds_read2_b32 v[40:41], v115 offset0:119 offset1:120
	ds_read2_b32 v[42:43], v115 offset0:121 offset1:122
	ds_read2_b32 v[44:45], v115 offset0:127 offset1:128
	ds_read2_b32 v[46:47], v115 offset0:129 offset1:130
	s_waitcnt lgkmcnt(15)
	v_mfma_f32_32x32x16_bf16 v[0:15], v[64:67], v[72:75], v[0:15]
	v_mfma_f32_32x32x16_bf16 v[16:31], v[64:67], v[76:79], v[16:31]
	v_mfma_f32_32x32x16_bf16 v[0:15], v[68:71], v[220:223], v[0:15]
	v_mfma_f32_32x32x16_bf16 v[16:31], v[68:71], v[224:227], v[16:31]
	global_load_dwordx4 v[188:191], v235, s[84:85]
	global_load_dwordx4 v[192:195], v236, s[84:85]
	global_load_dwordx4 v[196:199], v237, s[84:85]
	global_load_dwordx4 v[200:203], v238, s[84:85]
	global_load_dwordx4 v[204:207], v100, s[84:85] offset:768
	global_load_dwordx4 v[208:211], v149, s[84:85] offset:768
	global_load_dwordx4 v[212:215], v100, s[84:85] offset:832
	global_load_dwordx4 v[216:219], v149, s[84:85] offset:832
	s_add_u32 s84, s84, 0x30000
	s_addc_u32 s85, s85, 0
	s_waitcnt lgkmcnt(0)
	v_mfma_f32_32x32x16_bf16 v[32:47], v[116:119], v[48:51], v[32:47]
	ds_read_b64_tr_b16 v[72:73], v231
	ds_read_b64_tr_b16 v[74:75], v231 offset:512
	ds_read_b64_tr_b16 v[76:77], v231 offset:2048
	ds_read_b64_tr_b16 v[78:79], v231 offset:2560
	ds_read_b64_tr_b16 v[220:221], v231 offset:1024
	ds_read_b64_tr_b16 v[222:223], v231 offset:1536
	ds_read_b64_tr_b16 v[224:225], v231 offset:3072
	ds_read_b64_tr_b16 v[226:227], v231 offset:3584
	s_waitcnt vmcnt(8)
	ds_write_b128 v247, v[156:159]
	ds_write_b128 v247, v[160:163] offset:1024
	ds_write_b128 v247, v[164:167] offset:2048
	ds_write_b128 v247, v[168:171] offset:3072
	ds_read_b128 v[156:159], v248
	ds_read_b128 v[160:163], v249
	ds_read_b128 v[164:167], v250
	ds_read_b128 v[168:171], v251
	ds_write_b128 v112, v[172:175]
	ds_write_b128 v112, v[176:179] offset:1024
	ds_write_b128 v112, v[180:183] offset:2048
	ds_write_b128 v112, v[184:187] offset:3072
	v_mfma_f32_32x32x16_bf16 v[32:47], v[120:123], v[52:55], v[32:47]
	v_mfma_f32_32x32x16_bf16 v[32:47], v[124:127], v[56:59], v[32:47]
	v_mfma_f32_32x32x16_bf16 v[32:47], v[128:131], v[60:63], v[32:47]
	s_nop 11
	v_exp_f32_e32 v32, v32
	v_exp_f32_e32 v33, v33
	v_exp_f32_e32 v34, v34
	v_exp_f32_e32 v35, v35
	v_exp_f32_e32 v36, v36
	v_exp_f32_e32 v37, v37
	v_exp_f32_e32 v38, v38
	v_exp_f32_e32 v39, v39
	v_exp_f32_e32 v40, v40
	v_exp_f32_e32 v41, v41
	v_exp_f32_e32 v42, v42
	v_exp_f32_e32 v43, v43
	v_exp_f32_e32 v44, v44
	v_exp_f32_e32 v45, v45
	v_exp_f32_e32 v46, v46
	v_exp_f32_e32 v47, v47
	v_cvt_pk_bf16_f32 v64, v32, v33
	v_cvt_pk_bf16_f32 v65, v34, v35
	v_cvt_pk_bf16_f32 v66, v36, v37
	v_cvt_pk_bf16_f32 v67, v38, v39
	v_cvt_pk_bf16_f32 v68, v40, v41
	v_cvt_pk_bf16_f32 v69, v42, v43
	v_cvt_pk_bf16_f32 v70, v44, v45
	v_cvt_pk_bf16_f32 v71, v46, v47
	v_pk_add_f32 v[232:233], v[232:233], v[32:33]
	v_pk_add_f32 v[232:233], v[232:233], v[34:35]
	v_pk_add_f32 v[232:233], v[232:233], v[36:37]
	v_pk_add_f32 v[232:233], v[232:233], v[38:39]
	v_pk_add_f32 v[232:233], v[232:233], v[40:41]
	v_pk_add_f32 v[232:233], v[232:233], v[42:43]
	v_pk_add_f32 v[232:233], v[232:233], v[44:45]
	v_pk_add_f32 v[232:233], v[232:233], v[46:47]
	ds_read2_b32 v[32:33], v115 offset0:136 offset1:137
	ds_read2_b32 v[34:35], v115 offset0:138 offset1:139
	ds_read2_b32 v[36:37], v115 offset0:144 offset1:145
	ds_read2_b32 v[38:39], v115 offset0:146 offset1:147
	ds_read2_b32 v[40:41], v115 offset0:153 offset1:154
	ds_read2_b32 v[42:43], v115 offset0:155 offset1:156
	ds_read2_b32 v[44:45], v115 offset0:161 offset1:162
	ds_read2_b32 v[46:47], v115 offset0:163 offset1:164
	s_waitcnt lgkmcnt(15)
	v_mfma_f32_32x32x16_bf16 v[0:15], v[64:67], v[72:75], v[0:15]
	v_mfma_f32_32x32x16_bf16 v[16:31], v[64:67], v[76:79], v[16:31]
	v_mfma_f32_32x32x16_bf16 v[0:15], v[68:71], v[220:223], v[0:15]
	v_mfma_f32_32x32x16_bf16 v[16:31], v[68:71], v[224:227], v[16:31]
	global_load_dwordx4 v[116:119], v235, s[84:85]
	global_load_dwordx4 v[120:123], v236, s[84:85]
	global_load_dwordx4 v[124:127], v237, s[84:85]
	global_load_dwordx4 v[128:131], v238, s[84:85]
	global_load_dwordx4 v[132:135], v100, s[84:85] offset:768
	global_load_dwordx4 v[136:139], v149, s[84:85] offset:768
	global_load_dwordx4 v[140:143], v100, s[84:85] offset:832
	global_load_dwordx4 v[144:147], v149, s[84:85] offset:832
	s_add_u32 s84, s84, 0x30000
	s_addc_u32 s85, s85, 0
	s_waitcnt lgkmcnt(0)
	v_mfma_f32_32x32x16_bf16 v[32:47], v[156:159], v[48:51], v[32:47]
	ds_read_b64_tr_b16 v[72:73], v231
	ds_read_b64_tr_b16 v[74:75], v231 offset:512
	ds_read_b64_tr_b16 v[76:77], v231 offset:2048
	ds_read_b64_tr_b16 v[78:79], v231 offset:2560
	ds_read_b64_tr_b16 v[220:221], v231 offset:1024
	ds_read_b64_tr_b16 v[222:223], v231 offset:1536
	ds_read_b64_tr_b16 v[224:225], v231 offset:3072
	ds_read_b64_tr_b16 v[226:227], v231 offset:3584
	s_waitcnt vmcnt(8)
	ds_write_b128 v247, v[188:191]
	ds_write_b128 v247, v[192:195] offset:1024
	ds_write_b128 v247, v[196:199] offset:2048
	ds_write_b128 v247, v[200:203] offset:3072
	ds_read_b128 v[188:191], v248
	ds_read_b128 v[192:195], v249
	ds_read_b128 v[196:199], v250
	ds_read_b128 v[200:203], v251
	ds_write_b128 v112, v[204:207]
	ds_write_b128 v112, v[208:211] offset:1024
	ds_write_b128 v112, v[212:215] offset:2048
	ds_write_b128 v112, v[216:219] offset:3072
	v_mfma_f32_32x32x16_bf16 v[32:47], v[160:163], v[52:55], v[32:47]
	v_mfma_f32_32x32x16_bf16 v[32:47], v[164:167], v[56:59], v[32:47]
	v_mfma_f32_32x32x16_bf16 v[32:47], v[168:171], v[60:63], v[32:47]
	s_nop 11
	v_exp_f32_e32 v32, v32
	v_exp_f32_e32 v33, v33
	v_exp_f32_e32 v34, v34
	v_exp_f32_e32 v35, v35
	v_exp_f32_e32 v36, v36
	v_exp_f32_e32 v37, v37
	v_exp_f32_e32 v38, v38
	v_exp_f32_e32 v39, v39
	v_exp_f32_e32 v40, v40
	v_exp_f32_e32 v41, v41
	v_exp_f32_e32 v42, v42
	v_exp_f32_e32 v43, v43
	v_exp_f32_e32 v44, v44
	v_exp_f32_e32 v45, v45
	v_exp_f32_e32 v46, v46
	v_exp_f32_e32 v47, v47
	v_cvt_pk_bf16_f32 v64, v32, v33
	v_cvt_pk_bf16_f32 v65, v34, v35
	v_cvt_pk_bf16_f32 v66, v36, v37
	v_cvt_pk_bf16_f32 v67, v38, v39
	v_cvt_pk_bf16_f32 v68, v40, v41
	v_cvt_pk_bf16_f32 v69, v42, v43
	v_cvt_pk_bf16_f32 v70, v44, v45
	v_cvt_pk_bf16_f32 v71, v46, v47
	v_pk_add_f32 v[232:233], v[232:233], v[32:33]
	v_pk_add_f32 v[232:233], v[232:233], v[34:35]
	v_pk_add_f32 v[232:233], v[232:233], v[36:37]
	v_pk_add_f32 v[232:233], v[232:233], v[38:39]
	v_pk_add_f32 v[232:233], v[232:233], v[40:41]
	v_pk_add_f32 v[232:233], v[232:233], v[42:43]
	v_pk_add_f32 v[232:233], v[232:233], v[44:45]
	v_pk_add_f32 v[232:233], v[232:233], v[46:47]
	ds_read2_b32 v[32:33], v115 offset0:170 offset1:171
	ds_read2_b32 v[34:35], v115 offset0:172 offset1:173
	ds_read2_b32 v[36:37], v115 offset0:178 offset1:179
	ds_read2_b32 v[38:39], v115 offset0:180 offset1:181
	ds_read2_b32 v[40:41], v115 offset0:187 offset1:188
	ds_read2_b32 v[42:43], v115 offset0:189 offset1:190
	ds_read2_b32 v[44:45], v115 offset0:195 offset1:196
	ds_read2_b32 v[46:47], v115 offset0:197 offset1:198
	s_waitcnt lgkmcnt(15)
	v_mfma_f32_32x32x16_bf16 v[0:15], v[64:67], v[72:75], v[0:15]
	v_mfma_f32_32x32x16_bf16 v[16:31], v[64:67], v[76:79], v[16:31]
	v_mfma_f32_32x32x16_bf16 v[0:15], v[68:71], v[220:223], v[0:15]
	v_mfma_f32_32x32x16_bf16 v[16:31], v[68:71], v[224:227], v[16:31]
	global_load_dwordx4 v[156:159], v235, s[84:85]
	global_load_dwordx4 v[160:163], v236, s[84:85]
	global_load_dwordx4 v[164:167], v237, s[84:85]
	global_load_dwordx4 v[168:171], v238, s[84:85]
	global_load_dwordx4 v[172:175], v100, s[84:85] offset:768
	global_load_dwordx4 v[176:179], v149, s[84:85] offset:768
	global_load_dwordx4 v[180:183], v100, s[84:85] offset:832
	global_load_dwordx4 v[184:187], v149, s[84:85] offset:832
	s_add_u32 s84, s84, 0x30000
	s_addc_u32 s85, s85, 0
	s_waitcnt lgkmcnt(0)
	v_mfma_f32_32x32x16_bf16 v[32:47], v[188:191], v[48:51], v[32:47]
	ds_read_b64_tr_b16 v[72:73], v231
	ds_read_b64_tr_b16 v[74:75], v231 offset:512
	ds_read_b64_tr_b16 v[76:77], v231 offset:2048
	ds_read_b64_tr_b16 v[78:79], v231 offset:2560
	ds_read_b64_tr_b16 v[220:221], v231 offset:1024
	ds_read_b64_tr_b16 v[222:223], v231 offset:1536
	ds_read_b64_tr_b16 v[224:225], v231 offset:3072
	ds_read_b64_tr_b16 v[226:227], v231 offset:3584
	s_waitcnt vmcnt(8)
	ds_write_b128 v247, v[116:119]
	ds_write_b128 v247, v[120:123] offset:1024
	ds_write_b128 v247, v[124:127] offset:2048
	ds_write_b128 v247, v[128:131] offset:3072
	ds_read_b128 v[116:119], v248
	ds_read_b128 v[120:123], v249
	ds_read_b128 v[124:127], v250
	ds_read_b128 v[128:131], v251
	ds_write_b128 v112, v[132:135]
	ds_write_b128 v112, v[136:139] offset:1024
	ds_write_b128 v112, v[140:143] offset:2048
	ds_write_b128 v112, v[144:147] offset:3072
	v_mfma_f32_32x32x16_bf16 v[32:47], v[192:195], v[52:55], v[32:47]
	v_mfma_f32_32x32x16_bf16 v[32:47], v[196:199], v[56:59], v[32:47]
	v_mfma_f32_32x32x16_bf16 v[32:47], v[200:203], v[60:63], v[32:47]
	s_nop 11
	v_exp_f32_e32 v32, v32
	v_exp_f32_e32 v33, v33
	v_exp_f32_e32 v34, v34
	v_exp_f32_e32 v35, v35
	v_exp_f32_e32 v36, v36
	v_exp_f32_e32 v37, v37
	v_exp_f32_e32 v38, v38
	v_exp_f32_e32 v39, v39
	v_exp_f32_e32 v40, v40
	v_exp_f32_e32 v41, v41
	v_exp_f32_e32 v42, v42
	v_exp_f32_e32 v43, v43
	v_exp_f32_e32 v44, v44
	v_exp_f32_e32 v45, v45
	v_exp_f32_e32 v46, v46
	v_exp_f32_e32 v47, v47
	v_cvt_pk_bf16_f32 v64, v32, v33
	v_cvt_pk_bf16_f32 v65, v34, v35
	v_cvt_pk_bf16_f32 v66, v36, v37
	v_cvt_pk_bf16_f32 v67, v38, v39
	v_cvt_pk_bf16_f32 v68, v40, v41
	v_cvt_pk_bf16_f32 v69, v42, v43
	v_cvt_pk_bf16_f32 v70, v44, v45
	v_cvt_pk_bf16_f32 v71, v46, v47
	v_pk_add_f32 v[232:233], v[232:233], v[32:33]
	v_pk_add_f32 v[232:233], v[232:233], v[34:35]
	v_pk_add_f32 v[232:233], v[232:233], v[36:37]
	v_pk_add_f32 v[232:233], v[232:233], v[38:39]
	v_pk_add_f32 v[232:233], v[232:233], v[40:41]
	v_pk_add_f32 v[232:233], v[232:233], v[42:43]
	v_pk_add_f32 v[232:233], v[232:233], v[44:45]
	v_pk_add_f32 v[232:233], v[232:233], v[46:47]
	ds_read2_b32 v[32:33], v115 offset0:204 offset1:205
	ds_read2_b32 v[34:35], v115 offset0:206 offset1:207
	ds_read2_b32 v[36:37], v115 offset0:212 offset1:213
	ds_read2_b32 v[38:39], v115 offset0:214 offset1:215
	ds_read2_b32 v[40:41], v115 offset0:221 offset1:222
	ds_read2_b32 v[42:43], v115 offset0:223 offset1:224
	ds_read2_b32 v[44:45], v115 offset0:229 offset1:230
	ds_read2_b32 v[46:47], v115 offset0:231 offset1:232
	s_waitcnt lgkmcnt(15)
	v_mfma_f32_32x32x16_bf16 v[0:15], v[64:67], v[72:75], v[0:15]
	v_mfma_f32_32x32x16_bf16 v[16:31], v[64:67], v[76:79], v[16:31]
	v_mfma_f32_32x32x16_bf16 v[0:15], v[68:71], v[220:223], v[0:15]
	v_mfma_f32_32x32x16_bf16 v[16:31], v[68:71], v[224:227], v[16:31]
	global_load_dwordx4 v[188:191], v235, s[84:85]
	global_load_dwordx4 v[192:195], v236, s[84:85]
	global_load_dwordx4 v[196:199], v237, s[84:85]
	global_load_dwordx4 v[200:203], v238, s[84:85]
	global_load_dwordx4 v[204:207], v100, s[84:85] offset:768
	global_load_dwordx4 v[208:211], v149, s[84:85] offset:768
	global_load_dwordx4 v[212:215], v100, s[84:85] offset:832
	global_load_dwordx4 v[216:219], v149, s[84:85] offset:832
	s_add_u32 s84, s84, 0x30000
	s_addc_u32 s85, s85, 0
	s_waitcnt lgkmcnt(0)
	v_mfma_f32_32x32x16_bf16 v[32:47], v[116:119], v[48:51], v[32:47]
	ds_read_b64_tr_b16 v[72:73], v231
	ds_read_b64_tr_b16 v[74:75], v231 offset:512
	ds_read_b64_tr_b16 v[76:77], v231 offset:2048
	ds_read_b64_tr_b16 v[78:79], v231 offset:2560
	ds_read_b64_tr_b16 v[220:221], v231 offset:1024
	ds_read_b64_tr_b16 v[222:223], v231 offset:1536
	ds_read_b64_tr_b16 v[224:225], v231 offset:3072
	ds_read_b64_tr_b16 v[226:227], v231 offset:3584
	s_waitcnt vmcnt(8)
	ds_write_b128 v247, v[156:159]
	ds_write_b128 v247, v[160:163] offset:1024
	ds_write_b128 v247, v[164:167] offset:2048
	ds_write_b128 v247, v[168:171] offset:3072
	ds_read_b128 v[156:159], v248
	ds_read_b128 v[160:163], v249
	ds_read_b128 v[164:167], v250
	ds_read_b128 v[168:171], v251
	ds_write_b128 v112, v[172:175]
	ds_write_b128 v112, v[176:179] offset:1024
	ds_write_b128 v112, v[180:183] offset:2048
	ds_write_b128 v112, v[184:187] offset:3072
	v_mfma_f32_32x32x16_bf16 v[32:47], v[120:123], v[52:55], v[32:47]
	v_mfma_f32_32x32x16_bf16 v[32:47], v[124:127], v[56:59], v[32:47]
	v_mfma_f32_32x32x16_bf16 v[32:47], v[128:131], v[60:63], v[32:47]
	s_nop 11
	v_exp_f32_e32 v32, v32
	v_exp_f32_e32 v33, v33
	v_exp_f32_e32 v34, v34
	v_exp_f32_e32 v35, v35
	v_exp_f32_e32 v36, v36
	v_exp_f32_e32 v37, v37
	v_exp_f32_e32 v38, v38
	v_exp_f32_e32 v39, v39
	v_exp_f32_e32 v40, v40
	v_exp_f32_e32 v41, v41
	v_exp_f32_e32 v42, v42
	v_exp_f32_e32 v43, v43
	v_exp_f32_e32 v44, v44
	v_exp_f32_e32 v45, v45
	v_exp_f32_e32 v46, v46
	v_exp_f32_e32 v47, v47
	v_cvt_pk_bf16_f32 v64, v32, v33
	v_cvt_pk_bf16_f32 v65, v34, v35
	v_cvt_pk_bf16_f32 v66, v36, v37
	v_cvt_pk_bf16_f32 v67, v38, v39
	v_cvt_pk_bf16_f32 v68, v40, v41
	v_cvt_pk_bf16_f32 v69, v42, v43
	v_cvt_pk_bf16_f32 v70, v44, v45
	v_cvt_pk_bf16_f32 v71, v46, v47
	v_pk_add_f32 v[232:233], v[232:233], v[32:33]
	v_pk_add_f32 v[232:233], v[232:233], v[34:35]
	v_pk_add_f32 v[232:233], v[232:233], v[36:37]
	v_pk_add_f32 v[232:233], v[232:233], v[38:39]
	v_pk_add_f32 v[232:233], v[232:233], v[40:41]
	v_pk_add_f32 v[232:233], v[232:233], v[42:43]
	v_pk_add_f32 v[232:233], v[232:233], v[44:45]
	v_pk_add_f32 v[232:233], v[232:233], v[46:47]
	v_add_u32_e32 v115, 952, v115
	ds_read2_b32 v[32:33], v115 offset0:0 offset1:1
	ds_read2_b32 v[34:35], v115 offset0:2 offset1:3
	ds_read2_b32 v[36:37], v115 offset0:8 offset1:9
	ds_read2_b32 v[38:39], v115 offset0:10 offset1:11
	ds_read2_b32 v[40:41], v115 offset0:17 offset1:18
	ds_read2_b32 v[42:43], v115 offset0:19 offset1:20
	ds_read2_b32 v[44:45], v115 offset0:25 offset1:26
	ds_read2_b32 v[46:47], v115 offset0:27 offset1:28
	s_waitcnt lgkmcnt(15)
	v_mfma_f32_32x32x16_bf16 v[0:15], v[64:67], v[72:75], v[0:15]
	v_mfma_f32_32x32x16_bf16 v[16:31], v[64:67], v[76:79], v[16:31]
	v_mfma_f32_32x32x16_bf16 v[0:15], v[68:71], v[220:223], v[0:15]
	v_mfma_f32_32x32x16_bf16 v[16:31], v[68:71], v[224:227], v[16:31]
	global_load_dwordx4 v[116:119], v235, s[84:85]
	global_load_dwordx4 v[120:123], v236, s[84:85]
	global_load_dwordx4 v[124:127], v237, s[84:85]
	global_load_dwordx4 v[128:131], v238, s[84:85]
	global_load_dwordx4 v[132:135], v100, s[84:85] offset:768
	global_load_dwordx4 v[136:139], v149, s[84:85] offset:768
	global_load_dwordx4 v[140:143], v100, s[84:85] offset:832
	global_load_dwordx4 v[144:147], v149, s[84:85] offset:832
	s_add_u32 s84, s84, 0x30000
	s_addc_u32 s85, s85, 0
	s_waitcnt lgkmcnt(0)
	v_mfma_f32_32x32x16_bf16 v[32:47], v[156:159], v[48:51], v[32:47]
	ds_read_b64_tr_b16 v[72:73], v231
	ds_read_b64_tr_b16 v[74:75], v231 offset:512
	ds_read_b64_tr_b16 v[76:77], v231 offset:2048
	ds_read_b64_tr_b16 v[78:79], v231 offset:2560
	ds_read_b64_tr_b16 v[220:221], v231 offset:1024
	ds_read_b64_tr_b16 v[222:223], v231 offset:1536
	ds_read_b64_tr_b16 v[224:225], v231 offset:3072
	ds_read_b64_tr_b16 v[226:227], v231 offset:3584
	s_waitcnt vmcnt(8)
	ds_write_b128 v247, v[188:191]
	ds_write_b128 v247, v[192:195] offset:1024
	ds_write_b128 v247, v[196:199] offset:2048
	ds_write_b128 v247, v[200:203] offset:3072
	ds_read_b128 v[188:191], v248
	ds_read_b128 v[192:195], v249
	ds_read_b128 v[196:199], v250
	ds_read_b128 v[200:203], v251
	ds_write_b128 v112, v[204:207]
	ds_write_b128 v112, v[208:211] offset:1024
	ds_write_b128 v112, v[212:215] offset:2048
	ds_write_b128 v112, v[216:219] offset:3072
	v_mfma_f32_32x32x16_bf16 v[32:47], v[160:163], v[52:55], v[32:47]
	v_mfma_f32_32x32x16_bf16 v[32:47], v[164:167], v[56:59], v[32:47]
	v_mfma_f32_32x32x16_bf16 v[32:47], v[168:171], v[60:63], v[32:47]
	s_nop 11
	v_exp_f32_e32 v32, v32
	v_exp_f32_e32 v33, v33
	v_exp_f32_e32 v34, v34
	v_exp_f32_e32 v35, v35
	v_exp_f32_e32 v36, v36
	v_exp_f32_e32 v37, v37
	v_exp_f32_e32 v38, v38
	v_exp_f32_e32 v39, v39
	v_exp_f32_e32 v40, v40
	v_exp_f32_e32 v41, v41
	v_exp_f32_e32 v42, v42
	v_exp_f32_e32 v43, v43
	v_exp_f32_e32 v44, v44
	v_exp_f32_e32 v45, v45
	v_exp_f32_e32 v46, v46
	v_exp_f32_e32 v47, v47
	v_cvt_pk_bf16_f32 v64, v32, v33
	v_cvt_pk_bf16_f32 v65, v34, v35
	v_cvt_pk_bf16_f32 v66, v36, v37
	v_cvt_pk_bf16_f32 v67, v38, v39
	v_cvt_pk_bf16_f32 v68, v40, v41
	v_cvt_pk_bf16_f32 v69, v42, v43
	v_cvt_pk_bf16_f32 v70, v44, v45
	v_cvt_pk_bf16_f32 v71, v46, v47
	v_pk_add_f32 v[232:233], v[232:233], v[32:33]
	v_pk_add_f32 v[232:233], v[232:233], v[34:35]
	v_pk_add_f32 v[232:233], v[232:233], v[36:37]
	v_pk_add_f32 v[232:233], v[232:233], v[38:39]
	v_pk_add_f32 v[232:233], v[232:233], v[40:41]
	v_pk_add_f32 v[232:233], v[232:233], v[42:43]
	v_pk_add_f32 v[232:233], v[232:233], v[44:45]
	v_pk_add_f32 v[232:233], v[232:233], v[46:47]
	ds_read2_b32 v[32:33], v115 offset0:34 offset1:35
	ds_read2_b32 v[34:35], v115 offset0:36 offset1:37
	ds_read2_b32 v[36:37], v115 offset0:42 offset1:43
	ds_read2_b32 v[38:39], v115 offset0:44 offset1:45
	ds_read2_b32 v[40:41], v115 offset0:51 offset1:52
	ds_read2_b32 v[42:43], v115 offset0:53 offset1:54
	ds_read2_b32 v[44:45], v115 offset0:59 offset1:60
	ds_read2_b32 v[46:47], v115 offset0:61 offset1:62
	s_waitcnt lgkmcnt(15)
	v_mfma_f32_32x32x16_bf16 v[0:15], v[64:67], v[72:75], v[0:15]
	v_mfma_f32_32x32x16_bf16 v[16:31], v[64:67], v[76:79], v[16:31]
	v_mfma_f32_32x32x16_bf16 v[0:15], v[68:71], v[220:223], v[0:15]
	v_mfma_f32_32x32x16_bf16 v[16:31], v[68:71], v[224:227], v[16:31]
	global_load_dwordx4 v[156:159], v235, s[84:85]
	global_load_dwordx4 v[160:163], v236, s[84:85]
	global_load_dwordx4 v[164:167], v237, s[84:85]
	global_load_dwordx4 v[168:171], v238, s[84:85]
	global_load_dwordx4 v[172:175], v100, s[84:85] offset:768
	global_load_dwordx4 v[176:179], v149, s[84:85] offset:768
	global_load_dwordx4 v[180:183], v100, s[84:85] offset:832
	global_load_dwordx4 v[184:187], v149, s[84:85] offset:832
	s_add_u32 s84, s84, 0x30000
	s_addc_u32 s85, s85, 0
	s_waitcnt lgkmcnt(0)
	v_mfma_f32_32x32x16_bf16 v[32:47], v[188:191], v[48:51], v[32:47]
	ds_read_b64_tr_b16 v[72:73], v231
	ds_read_b64_tr_b16 v[74:75], v231 offset:512
	ds_read_b64_tr_b16 v[76:77], v231 offset:2048
	ds_read_b64_tr_b16 v[78:79], v231 offset:2560
	ds_read_b64_tr_b16 v[220:221], v231 offset:1024
	ds_read_b64_tr_b16 v[222:223], v231 offset:1536
	ds_read_b64_tr_b16 v[224:225], v231 offset:3072
	ds_read_b64_tr_b16 v[226:227], v231 offset:3584
	s_waitcnt vmcnt(8)
	ds_write_b128 v247, v[116:119]
	ds_write_b128 v247, v[120:123] offset:1024
	ds_write_b128 v247, v[124:127] offset:2048
	ds_write_b128 v247, v[128:131] offset:3072
	ds_read_b128 v[116:119], v248
	ds_read_b128 v[120:123], v249
	ds_read_b128 v[124:127], v250
	ds_read_b128 v[128:131], v251
	ds_write_b128 v112, v[132:135]
	ds_write_b128 v112, v[136:139] offset:1024
	ds_write_b128 v112, v[140:143] offset:2048
	ds_write_b128 v112, v[144:147] offset:3072
	v_mfma_f32_32x32x16_bf16 v[32:47], v[192:195], v[52:55], v[32:47]
	v_mfma_f32_32x32x16_bf16 v[32:47], v[196:199], v[56:59], v[32:47]
	v_mfma_f32_32x32x16_bf16 v[32:47], v[200:203], v[60:63], v[32:47]
	s_nop 11
	v_exp_f32_e32 v32, v32
	v_exp_f32_e32 v33, v33
	v_exp_f32_e32 v34, v34
	v_exp_f32_e32 v35, v35
	v_exp_f32_e32 v36, v36
	v_exp_f32_e32 v37, v37
	v_exp_f32_e32 v38, v38
	v_exp_f32_e32 v39, v39
	v_exp_f32_e32 v40, v40
	v_exp_f32_e32 v41, v41
	v_exp_f32_e32 v42, v42
	v_exp_f32_e32 v43, v43
	v_exp_f32_e32 v44, v44
	v_exp_f32_e32 v45, v45
	v_exp_f32_e32 v46, v46
	v_exp_f32_e32 v47, v47
	v_cvt_pk_bf16_f32 v64, v32, v33
	v_cvt_pk_bf16_f32 v65, v34, v35
	v_cvt_pk_bf16_f32 v66, v36, v37
	v_cvt_pk_bf16_f32 v67, v38, v39
	v_cvt_pk_bf16_f32 v68, v40, v41
	v_cvt_pk_bf16_f32 v69, v42, v43
	v_cvt_pk_bf16_f32 v70, v44, v45
	v_cvt_pk_bf16_f32 v71, v46, v47
	v_pk_add_f32 v[232:233], v[232:233], v[32:33]
	v_pk_add_f32 v[232:233], v[232:233], v[34:35]
	v_pk_add_f32 v[232:233], v[232:233], v[36:37]
	v_pk_add_f32 v[232:233], v[232:233], v[38:39]
	v_pk_add_f32 v[232:233], v[232:233], v[40:41]
	v_pk_add_f32 v[232:233], v[232:233], v[42:43]
	v_pk_add_f32 v[232:233], v[232:233], v[44:45]
	v_pk_add_f32 v[232:233], v[232:233], v[46:47]
	ds_read2_b32 v[32:33], v115 offset0:68 offset1:69
	ds_read2_b32 v[34:35], v115 offset0:70 offset1:71
	ds_read2_b32 v[36:37], v115 offset0:76 offset1:77
	ds_read2_b32 v[38:39], v115 offset0:78 offset1:79
	ds_read2_b32 v[40:41], v115 offset0:85 offset1:86
	ds_read2_b32 v[42:43], v115 offset0:87 offset1:88
	ds_read2_b32 v[44:45], v115 offset0:93 offset1:94
	ds_read2_b32 v[46:47], v115 offset0:95 offset1:96
	s_waitcnt lgkmcnt(15)
	v_mfma_f32_32x32x16_bf16 v[0:15], v[64:67], v[72:75], v[0:15]
	v_mfma_f32_32x32x16_bf16 v[16:31], v[64:67], v[76:79], v[16:31]
	v_mfma_f32_32x32x16_bf16 v[0:15], v[68:71], v[220:223], v[0:15]
	v_mfma_f32_32x32x16_bf16 v[16:31], v[68:71], v[224:227], v[16:31]
	global_load_dwordx4 v[188:191], v235, s[84:85]
	global_load_dwordx4 v[192:195], v236, s[84:85]
	global_load_dwordx4 v[196:199], v237, s[84:85]
	global_load_dwordx4 v[200:203], v238, s[84:85]
	global_load_dwordx4 v[204:207], v100, s[84:85] offset:768
	global_load_dwordx4 v[208:211], v149, s[84:85] offset:768
	global_load_dwordx4 v[212:215], v100, s[84:85] offset:832
	global_load_dwordx4 v[216:219], v149, s[84:85] offset:832
	s_add_u32 s84, s84, 0x30000
	s_addc_u32 s85, s85, 0
	s_waitcnt lgkmcnt(0)
	v_mfma_f32_32x32x16_bf16 v[32:47], v[116:119], v[48:51], v[32:47]
	ds_read_b64_tr_b16 v[72:73], v231
	ds_read_b64_tr_b16 v[74:75], v231 offset:512
	ds_read_b64_tr_b16 v[76:77], v231 offset:2048
	ds_read_b64_tr_b16 v[78:79], v231 offset:2560
	ds_read_b64_tr_b16 v[220:221], v231 offset:1024
	ds_read_b64_tr_b16 v[222:223], v231 offset:1536
	ds_read_b64_tr_b16 v[224:225], v231 offset:3072
	ds_read_b64_tr_b16 v[226:227], v231 offset:3584
	s_waitcnt vmcnt(8)
	ds_write_b128 v247, v[156:159]
	ds_write_b128 v247, v[160:163] offset:1024
	ds_write_b128 v247, v[164:167] offset:2048
	ds_write_b128 v247, v[168:171] offset:3072
	ds_read_b128 v[156:159], v248
	ds_read_b128 v[160:163], v249
	ds_read_b128 v[164:167], v250
	ds_read_b128 v[168:171], v251
	ds_write_b128 v112, v[172:175]
	ds_write_b128 v112, v[176:179] offset:1024
	ds_write_b128 v112, v[180:183] offset:2048
	ds_write_b128 v112, v[184:187] offset:3072
	v_mfma_f32_32x32x16_bf16 v[32:47], v[120:123], v[52:55], v[32:47]
	v_mfma_f32_32x32x16_bf16 v[32:47], v[124:127], v[56:59], v[32:47]
	v_mfma_f32_32x32x16_bf16 v[32:47], v[128:131], v[60:63], v[32:47]
	s_nop 11
	v_exp_f32_e32 v32, v32
	v_exp_f32_e32 v33, v33
	v_exp_f32_e32 v34, v34
	v_exp_f32_e32 v35, v35
	v_exp_f32_e32 v36, v36
	v_exp_f32_e32 v37, v37
	v_exp_f32_e32 v38, v38
	v_exp_f32_e32 v39, v39
	v_exp_f32_e32 v40, v40
	v_exp_f32_e32 v41, v41
	v_exp_f32_e32 v42, v42
	v_exp_f32_e32 v43, v43
	v_exp_f32_e32 v44, v44
	v_exp_f32_e32 v45, v45
	v_exp_f32_e32 v46, v46
	v_exp_f32_e32 v47, v47
	v_cvt_pk_bf16_f32 v64, v32, v33
	v_cvt_pk_bf16_f32 v65, v34, v35
	v_cvt_pk_bf16_f32 v66, v36, v37
	v_cvt_pk_bf16_f32 v67, v38, v39
	v_cvt_pk_bf16_f32 v68, v40, v41
	v_cvt_pk_bf16_f32 v69, v42, v43
	v_cvt_pk_bf16_f32 v70, v44, v45
	v_cvt_pk_bf16_f32 v71, v46, v47
	v_pk_add_f32 v[232:233], v[232:233], v[32:33]
	v_pk_add_f32 v[232:233], v[232:233], v[34:35]
	v_pk_add_f32 v[232:233], v[232:233], v[36:37]
	v_pk_add_f32 v[232:233], v[232:233], v[38:39]
	v_pk_add_f32 v[232:233], v[232:233], v[40:41]
	v_pk_add_f32 v[232:233], v[232:233], v[42:43]
	v_pk_add_f32 v[232:233], v[232:233], v[44:45]
	v_pk_add_f32 v[232:233], v[232:233], v[46:47]
	ds_read2_b32 v[32:33], v115 offset0:102 offset1:103
	ds_read2_b32 v[34:35], v115 offset0:104 offset1:105
	ds_read2_b32 v[36:37], v115 offset0:110 offset1:111
	ds_read2_b32 v[38:39], v115 offset0:112 offset1:113
	ds_read2_b32 v[40:41], v115 offset0:119 offset1:120
	ds_read2_b32 v[42:43], v115 offset0:121 offset1:122
	ds_read2_b32 v[44:45], v115 offset0:127 offset1:128
	ds_read2_b32 v[46:47], v115 offset0:129 offset1:130
	s_waitcnt lgkmcnt(15)
	v_mfma_f32_32x32x16_bf16 v[0:15], v[64:67], v[72:75], v[0:15]
	v_mfma_f32_32x32x16_bf16 v[16:31], v[64:67], v[76:79], v[16:31]
	v_mfma_f32_32x32x16_bf16 v[0:15], v[68:71], v[220:223], v[0:15]
	v_mfma_f32_32x32x16_bf16 v[16:31], v[68:71], v[224:227], v[16:31]
	global_load_dwordx4 v[116:119], v235, s[84:85]
	global_load_dwordx4 v[120:123], v236, s[84:85]
	global_load_dwordx4 v[124:127], v237, s[84:85]
	global_load_dwordx4 v[128:131], v238, s[84:85]
	global_load_dwordx4 v[132:135], v100, s[84:85] offset:768
	global_load_dwordx4 v[136:139], v149, s[84:85] offset:768
	global_load_dwordx4 v[140:143], v100, s[84:85] offset:832
	global_load_dwordx4 v[144:147], v149, s[84:85] offset:832
	s_add_u32 s84, s84, 0x30000
	s_addc_u32 s85, s85, 0
	s_waitcnt lgkmcnt(0)
	v_mfma_f32_32x32x16_bf16 v[32:47], v[156:159], v[48:51], v[32:47]
	ds_read_b64_tr_b16 v[72:73], v231
	ds_read_b64_tr_b16 v[74:75], v231 offset:512
	ds_read_b64_tr_b16 v[76:77], v231 offset:2048
	ds_read_b64_tr_b16 v[78:79], v231 offset:2560
	ds_read_b64_tr_b16 v[220:221], v231 offset:1024
	ds_read_b64_tr_b16 v[222:223], v231 offset:1536
	ds_read_b64_tr_b16 v[224:225], v231 offset:3072
	ds_read_b64_tr_b16 v[226:227], v231 offset:3584
	s_waitcnt vmcnt(8)
	ds_write_b128 v247, v[188:191]
	ds_write_b128 v247, v[192:195] offset:1024
	ds_write_b128 v247, v[196:199] offset:2048
	ds_write_b128 v247, v[200:203] offset:3072
	ds_read_b128 v[188:191], v248
	ds_read_b128 v[192:195], v249
	ds_read_b128 v[196:199], v250
	ds_read_b128 v[200:203], v251
	ds_write_b128 v112, v[204:207]
	ds_write_b128 v112, v[208:211] offset:1024
	ds_write_b128 v112, v[212:215] offset:2048
	ds_write_b128 v112, v[216:219] offset:3072
	v_mfma_f32_32x32x16_bf16 v[32:47], v[160:163], v[52:55], v[32:47]
	v_mfma_f32_32x32x16_bf16 v[32:47], v[164:167], v[56:59], v[32:47]
	v_mfma_f32_32x32x16_bf16 v[32:47], v[168:171], v[60:63], v[32:47]
	s_nop 11
	v_exp_f32_e32 v32, v32
	v_exp_f32_e32 v33, v33
	v_exp_f32_e32 v34, v34
	v_exp_f32_e32 v35, v35
	v_exp_f32_e32 v36, v36
	v_exp_f32_e32 v37, v37
	v_exp_f32_e32 v38, v38
	v_exp_f32_e32 v39, v39
	v_exp_f32_e32 v40, v40
	v_exp_f32_e32 v41, v41
	v_exp_f32_e32 v42, v42
	v_exp_f32_e32 v43, v43
	v_exp_f32_e32 v44, v44
	v_exp_f32_e32 v45, v45
	v_exp_f32_e32 v46, v46
	v_exp_f32_e32 v47, v47
	v_cvt_pk_bf16_f32 v64, v32, v33
	v_cvt_pk_bf16_f32 v65, v34, v35
	v_cvt_pk_bf16_f32 v66, v36, v37
	v_cvt_pk_bf16_f32 v67, v38, v39
	v_cvt_pk_bf16_f32 v68, v40, v41
	v_cvt_pk_bf16_f32 v69, v42, v43
	v_cvt_pk_bf16_f32 v70, v44, v45
	v_cvt_pk_bf16_f32 v71, v46, v47
	v_pk_add_f32 v[232:233], v[232:233], v[32:33]
	v_pk_add_f32 v[232:233], v[232:233], v[34:35]
	v_pk_add_f32 v[232:233], v[232:233], v[36:37]
	v_pk_add_f32 v[232:233], v[232:233], v[38:39]
	v_pk_add_f32 v[232:233], v[232:233], v[40:41]
	v_pk_add_f32 v[232:233], v[232:233], v[42:43]
	v_pk_add_f32 v[232:233], v[232:233], v[44:45]
	v_pk_add_f32 v[232:233], v[232:233], v[46:47]
	ds_read2_b32 v[32:33], v115 offset0:136 offset1:137
	ds_read2_b32 v[34:35], v115 offset0:138 offset1:139
	ds_read2_b32 v[36:37], v115 offset0:144 offset1:145
	ds_read2_b32 v[38:39], v115 offset0:146 offset1:147
	ds_read2_b32 v[40:41], v115 offset0:153 offset1:154
	ds_read2_b32 v[42:43], v115 offset0:155 offset1:156
	ds_read2_b32 v[44:45], v115 offset0:161 offset1:162
	ds_read2_b32 v[46:47], v115 offset0:163 offset1:164
	s_waitcnt lgkmcnt(15)
	v_mfma_f32_32x32x16_bf16 v[0:15], v[64:67], v[72:75], v[0:15]
	v_mfma_f32_32x32x16_bf16 v[16:31], v[64:67], v[76:79], v[16:31]
	v_mfma_f32_32x32x16_bf16 v[0:15], v[68:71], v[220:223], v[0:15]
	v_mfma_f32_32x32x16_bf16 v[16:31], v[68:71], v[224:227], v[16:31]
	global_load_dwordx4 v[156:159], v235, s[84:85]
	global_load_dwordx4 v[160:163], v236, s[84:85]
	global_load_dwordx4 v[164:167], v237, s[84:85]
	global_load_dwordx4 v[168:171], v238, s[84:85]
	global_load_dwordx4 v[172:175], v100, s[84:85] offset:768
	global_load_dwordx4 v[176:179], v149, s[84:85] offset:768
	global_load_dwordx4 v[180:183], v100, s[84:85] offset:832
	global_load_dwordx4 v[184:187], v149, s[84:85] offset:832
	s_add_u32 s84, s84, 0x30000
	s_addc_u32 s85, s85, 0
	s_waitcnt lgkmcnt(0)
	v_mfma_f32_32x32x16_bf16 v[32:47], v[188:191], v[48:51], v[32:47]
	ds_read_b64_tr_b16 v[72:73], v231
	ds_read_b64_tr_b16 v[74:75], v231 offset:512
	ds_read_b64_tr_b16 v[76:77], v231 offset:2048
	ds_read_b64_tr_b16 v[78:79], v231 offset:2560
	ds_read_b64_tr_b16 v[220:221], v231 offset:1024
	ds_read_b64_tr_b16 v[222:223], v231 offset:1536
	ds_read_b64_tr_b16 v[224:225], v231 offset:3072
	ds_read_b64_tr_b16 v[226:227], v231 offset:3584
	s_waitcnt vmcnt(8)
	ds_write_b128 v247, v[116:119]
	ds_write_b128 v247, v[120:123] offset:1024
	ds_write_b128 v247, v[124:127] offset:2048
	ds_write_b128 v247, v[128:131] offset:3072
	ds_read_b128 v[116:119], v248
	ds_read_b128 v[120:123], v249
	ds_read_b128 v[124:127], v250
	ds_read_b128 v[128:131], v251
	ds_write_b128 v112, v[132:135]
	ds_write_b128 v112, v[136:139] offset:1024
	ds_write_b128 v112, v[140:143] offset:2048
	ds_write_b128 v112, v[144:147] offset:3072
	v_mfma_f32_32x32x16_bf16 v[32:47], v[192:195], v[52:55], v[32:47]
	v_mfma_f32_32x32x16_bf16 v[32:47], v[196:199], v[56:59], v[32:47]
	v_mfma_f32_32x32x16_bf16 v[32:47], v[200:203], v[60:63], v[32:47]
	s_nop 11
	v_exp_f32_e32 v32, v32
	v_exp_f32_e32 v33, v33
	v_exp_f32_e32 v34, v34
	v_exp_f32_e32 v35, v35
	v_exp_f32_e32 v36, v36
	v_exp_f32_e32 v37, v37
	v_exp_f32_e32 v38, v38
	v_exp_f32_e32 v39, v39
	v_exp_f32_e32 v40, v40
	v_exp_f32_e32 v41, v41
	v_exp_f32_e32 v42, v42
	v_exp_f32_e32 v43, v43
	v_exp_f32_e32 v44, v44
	v_exp_f32_e32 v45, v45
	v_exp_f32_e32 v46, v46
	v_exp_f32_e32 v47, v47
	v_cvt_pk_bf16_f32 v64, v32, v33
	v_cvt_pk_bf16_f32 v65, v34, v35
	v_cvt_pk_bf16_f32 v66, v36, v37
	v_cvt_pk_bf16_f32 v67, v38, v39
	v_cvt_pk_bf16_f32 v68, v40, v41
	v_cvt_pk_bf16_f32 v69, v42, v43
	v_cvt_pk_bf16_f32 v70, v44, v45
	v_cvt_pk_bf16_f32 v71, v46, v47
	v_pk_add_f32 v[232:233], v[232:233], v[32:33]
	v_pk_add_f32 v[232:233], v[232:233], v[34:35]
	v_pk_add_f32 v[232:233], v[232:233], v[36:37]
	v_pk_add_f32 v[232:233], v[232:233], v[38:39]
	v_pk_add_f32 v[232:233], v[232:233], v[40:41]
	v_pk_add_f32 v[232:233], v[232:233], v[42:43]
	v_pk_add_f32 v[232:233], v[232:233], v[44:45]
	v_pk_add_f32 v[232:233], v[232:233], v[46:47]
	ds_read2_b32 v[32:33], v115 offset0:170 offset1:171
	ds_read2_b32 v[34:35], v115 offset0:172 offset1:173
	ds_read2_b32 v[36:37], v115 offset0:178 offset1:179
	ds_read2_b32 v[38:39], v115 offset0:180 offset1:181
	ds_read2_b32 v[40:41], v115 offset0:187 offset1:188
	ds_read2_b32 v[42:43], v115 offset0:189 offset1:190
	ds_read2_b32 v[44:45], v115 offset0:195 offset1:196
	ds_read2_b32 v[46:47], v115 offset0:197 offset1:198
	s_waitcnt lgkmcnt(15)
	v_mfma_f32_32x32x16_bf16 v[0:15], v[64:67], v[72:75], v[0:15]
	v_mfma_f32_32x32x16_bf16 v[16:31], v[64:67], v[76:79], v[16:31]
	v_mfma_f32_32x32x16_bf16 v[0:15], v[68:71], v[220:223], v[0:15]
	v_mfma_f32_32x32x16_bf16 v[16:31], v[68:71], v[224:227], v[16:31]
	global_load_dwordx4 v[188:191], v235, s[84:85]
	global_load_dwordx4 v[192:195], v236, s[84:85]
	global_load_dwordx4 v[196:199], v237, s[84:85]
	global_load_dwordx4 v[200:203], v238, s[84:85]
	global_load_dwordx4 v[204:207], v100, s[84:85] offset:768
	global_load_dwordx4 v[208:211], v149, s[84:85] offset:768
	global_load_dwordx4 v[212:215], v100, s[84:85] offset:832
	global_load_dwordx4 v[216:219], v149, s[84:85] offset:832
	s_add_u32 s84, s84, 0x30000
	s_addc_u32 s85, s85, 0
	s_waitcnt lgkmcnt(0)
	v_mfma_f32_32x32x16_bf16 v[32:47], v[116:119], v[48:51], v[32:47]
	ds_read_b64_tr_b16 v[72:73], v231
	ds_read_b64_tr_b16 v[74:75], v231 offset:512
	ds_read_b64_tr_b16 v[76:77], v231 offset:2048
	ds_read_b64_tr_b16 v[78:79], v231 offset:2560
	ds_read_b64_tr_b16 v[220:221], v231 offset:1024
	ds_read_b64_tr_b16 v[222:223], v231 offset:1536
	ds_read_b64_tr_b16 v[224:225], v231 offset:3072
	ds_read_b64_tr_b16 v[226:227], v231 offset:3584
	s_waitcnt vmcnt(8)
	ds_write_b128 v247, v[156:159]
	ds_write_b128 v247, v[160:163] offset:1024
	ds_write_b128 v247, v[164:167] offset:2048
	ds_write_b128 v247, v[168:171] offset:3072
	ds_read_b128 v[156:159], v248
	ds_read_b128 v[160:163], v249
	ds_read_b128 v[164:167], v250
	ds_read_b128 v[168:171], v251
	ds_write_b128 v112, v[172:175]
	ds_write_b128 v112, v[176:179] offset:1024
	ds_write_b128 v112, v[180:183] offset:2048
	ds_write_b128 v112, v[184:187] offset:3072
	v_mfma_f32_32x32x16_bf16 v[32:47], v[120:123], v[52:55], v[32:47]
	v_mfma_f32_32x32x16_bf16 v[32:47], v[124:127], v[56:59], v[32:47]
	v_mfma_f32_32x32x16_bf16 v[32:47], v[128:131], v[60:63], v[32:47]
	s_nop 11
	v_exp_f32_e32 v32, v32
	v_exp_f32_e32 v33, v33
	v_exp_f32_e32 v34, v34
	v_exp_f32_e32 v35, v35
	v_exp_f32_e32 v36, v36
	v_exp_f32_e32 v37, v37
	v_exp_f32_e32 v38, v38
	v_exp_f32_e32 v39, v39
	v_exp_f32_e32 v40, v40
	v_exp_f32_e32 v41, v41
	v_exp_f32_e32 v42, v42
	v_exp_f32_e32 v43, v43
	v_exp_f32_e32 v44, v44
	v_exp_f32_e32 v45, v45
	v_exp_f32_e32 v46, v46
	v_exp_f32_e32 v47, v47
	v_cvt_pk_bf16_f32 v64, v32, v33
	v_cvt_pk_bf16_f32 v65, v34, v35
	v_cvt_pk_bf16_f32 v66, v36, v37
	v_cvt_pk_bf16_f32 v67, v38, v39
	v_cvt_pk_bf16_f32 v68, v40, v41
	v_cvt_pk_bf16_f32 v69, v42, v43
	v_cvt_pk_bf16_f32 v70, v44, v45
	v_cvt_pk_bf16_f32 v71, v46, v47
	v_pk_add_f32 v[232:233], v[232:233], v[32:33]
	v_pk_add_f32 v[232:233], v[232:233], v[34:35]
	v_pk_add_f32 v[232:233], v[232:233], v[36:37]
	v_pk_add_f32 v[232:233], v[232:233], v[38:39]
	v_pk_add_f32 v[232:233], v[232:233], v[40:41]
	v_pk_add_f32 v[232:233], v[232:233], v[42:43]
	v_pk_add_f32 v[232:233], v[232:233], v[44:45]
	v_pk_add_f32 v[232:233], v[232:233], v[46:47]
	ds_read2_b32 v[32:33], v115 offset0:204 offset1:205
	ds_read2_b32 v[34:35], v115 offset0:206 offset1:207
	ds_read2_b32 v[36:37], v115 offset0:212 offset1:213
	ds_read2_b32 v[38:39], v115 offset0:214 offset1:215
	ds_read2_b32 v[40:41], v115 offset0:221 offset1:222
	ds_read2_b32 v[42:43], v115 offset0:223 offset1:224
	ds_read2_b32 v[44:45], v115 offset0:229 offset1:230
	ds_read2_b32 v[46:47], v115 offset0:231 offset1:232
	s_waitcnt lgkmcnt(15)
	v_mfma_f32_32x32x16_bf16 v[0:15], v[64:67], v[72:75], v[0:15]
	v_mfma_f32_32x32x16_bf16 v[16:31], v[64:67], v[76:79], v[16:31]
	v_mfma_f32_32x32x16_bf16 v[0:15], v[68:71], v[220:223], v[0:15]
	v_mfma_f32_32x32x16_bf16 v[16:31], v[68:71], v[224:227], v[16:31]
	global_load_dwordx4 v[116:119], v235, s[84:85]
	global_load_dwordx4 v[120:123], v236, s[84:85]
	global_load_dwordx4 v[124:127], v237, s[84:85]
	global_load_dwordx4 v[128:131], v238, s[84:85]
	global_load_dwordx4 v[132:135], v100, s[84:85] offset:768
	global_load_dwordx4 v[136:139], v149, s[84:85] offset:768
	global_load_dwordx4 v[140:143], v100, s[84:85] offset:832
	global_load_dwordx4 v[144:147], v149, s[84:85] offset:832
	s_add_u32 s84, s84, 0x30000
	s_addc_u32 s85, s85, 0
	s_waitcnt lgkmcnt(0)
	v_mfma_f32_32x32x16_bf16 v[32:47], v[156:159], v[48:51], v[32:47]
	ds_read_b64_tr_b16 v[72:73], v231
	ds_read_b64_tr_b16 v[74:75], v231 offset:512
	ds_read_b64_tr_b16 v[76:77], v231 offset:2048
	ds_read_b64_tr_b16 v[78:79], v231 offset:2560
	ds_read_b64_tr_b16 v[220:221], v231 offset:1024
	ds_read_b64_tr_b16 v[222:223], v231 offset:1536
	ds_read_b64_tr_b16 v[224:225], v231 offset:3072
	ds_read_b64_tr_b16 v[226:227], v231 offset:3584
	s_waitcnt vmcnt(8)
	ds_write_b128 v247, v[188:191]
	ds_write_b128 v247, v[192:195] offset:1024
	ds_write_b128 v247, v[196:199] offset:2048
	ds_write_b128 v247, v[200:203] offset:3072
	ds_read_b128 v[188:191], v248
	ds_read_b128 v[192:195], v249
	ds_read_b128 v[196:199], v250
	ds_read_b128 v[200:203], v251
	ds_write_b128 v112, v[204:207]
	ds_write_b128 v112, v[208:211] offset:1024
	ds_write_b128 v112, v[212:215] offset:2048
	ds_write_b128 v112, v[216:219] offset:3072
	v_mfma_f32_32x32x16_bf16 v[32:47], v[160:163], v[52:55], v[32:47]
	v_mfma_f32_32x32x16_bf16 v[32:47], v[164:167], v[56:59], v[32:47]
	v_mfma_f32_32x32x16_bf16 v[32:47], v[168:171], v[60:63], v[32:47]
	s_nop 11
	v_exp_f32_e32 v32, v32
	v_exp_f32_e32 v33, v33
	v_exp_f32_e32 v34, v34
	v_exp_f32_e32 v35, v35
	v_exp_f32_e32 v36, v36
	v_exp_f32_e32 v37, v37
	v_exp_f32_e32 v38, v38
	v_exp_f32_e32 v39, v39
	v_exp_f32_e32 v40, v40
	v_exp_f32_e32 v41, v41
	v_exp_f32_e32 v42, v42
	v_exp_f32_e32 v43, v43
	v_exp_f32_e32 v44, v44
	v_exp_f32_e32 v45, v45
	v_exp_f32_e32 v46, v46
	v_exp_f32_e32 v47, v47
	v_cvt_pk_bf16_f32 v64, v32, v33
	v_cvt_pk_bf16_f32 v65, v34, v35
	v_cvt_pk_bf16_f32 v66, v36, v37
	v_cvt_pk_bf16_f32 v67, v38, v39
	v_cvt_pk_bf16_f32 v68, v40, v41
	v_cvt_pk_bf16_f32 v69, v42, v43
	v_cvt_pk_bf16_f32 v70, v44, v45
	v_cvt_pk_bf16_f32 v71, v46, v47
	v_pk_add_f32 v[232:233], v[232:233], v[32:33]
	v_pk_add_f32 v[232:233], v[232:233], v[34:35]
	v_pk_add_f32 v[232:233], v[232:233], v[36:37]
	v_pk_add_f32 v[232:233], v[232:233], v[38:39]
	v_pk_add_f32 v[232:233], v[232:233], v[40:41]
	v_pk_add_f32 v[232:233], v[232:233], v[42:43]
	v_pk_add_f32 v[232:233], v[232:233], v[44:45]
	v_pk_add_f32 v[232:233], v[232:233], v[46:47]
	v_add_u32_e32 v115, 952, v115
	ds_read2_b32 v[32:33], v115 offset0:0 offset1:1
	ds_read2_b32 v[34:35], v115 offset0:2 offset1:3
	ds_read2_b32 v[36:37], v115 offset0:8 offset1:9
	ds_read2_b32 v[38:39], v115 offset0:10 offset1:11
	ds_read2_b32 v[40:41], v115 offset0:17 offset1:18
	ds_read2_b32 v[42:43], v115 offset0:19 offset1:20
	ds_read2_b32 v[44:45], v115 offset0:25 offset1:26
	ds_read2_b32 v[46:47], v115 offset0:27 offset1:28
	s_waitcnt lgkmcnt(15)
	v_mfma_f32_32x32x16_bf16 v[0:15], v[64:67], v[72:75], v[0:15]
	v_mfma_f32_32x32x16_bf16 v[16:31], v[64:67], v[76:79], v[16:31]
	v_mfma_f32_32x32x16_bf16 v[0:15], v[68:71], v[220:223], v[0:15]
	v_mfma_f32_32x32x16_bf16 v[16:31], v[68:71], v[224:227], v[16:31]
	global_load_dwordx4 v[156:159], v235, s[84:85]
	global_load_dwordx4 v[160:163], v236, s[84:85]
	global_load_dwordx4 v[164:167], v237, s[84:85]
	global_load_dwordx4 v[168:171], v238, s[84:85]
	global_load_dwordx4 v[172:175], v100, s[84:85] offset:768
	global_load_dwordx4 v[176:179], v149, s[84:85] offset:768
	global_load_dwordx4 v[180:183], v100, s[84:85] offset:832
	global_load_dwordx4 v[184:187], v149, s[84:85] offset:832
	s_add_u32 s84, s84, 0x30000
	s_addc_u32 s85, s85, 0
	s_waitcnt lgkmcnt(0)
	v_mfma_f32_32x32x16_bf16 v[32:47], v[188:191], v[48:51], v[32:47]
	ds_read_b64_tr_b16 v[72:73], v231
	ds_read_b64_tr_b16 v[74:75], v231 offset:512
	ds_read_b64_tr_b16 v[76:77], v231 offset:2048
	ds_read_b64_tr_b16 v[78:79], v231 offset:2560
	ds_read_b64_tr_b16 v[220:221], v231 offset:1024
	ds_read_b64_tr_b16 v[222:223], v231 offset:1536
	ds_read_b64_tr_b16 v[224:225], v231 offset:3072
	ds_read_b64_tr_b16 v[226:227], v231 offset:3584
	s_waitcnt vmcnt(8)
	ds_write_b128 v247, v[116:119]
	ds_write_b128 v247, v[120:123] offset:1024
	ds_write_b128 v247, v[124:127] offset:2048
	ds_write_b128 v247, v[128:131] offset:3072
	ds_read_b128 v[116:119], v248
	ds_read_b128 v[120:123], v249
	ds_read_b128 v[124:127], v250
	ds_read_b128 v[128:131], v251
	ds_write_b128 v112, v[132:135]
	ds_write_b128 v112, v[136:139] offset:1024
	ds_write_b128 v112, v[140:143] offset:2048
	ds_write_b128 v112, v[144:147] offset:3072
	v_mfma_f32_32x32x16_bf16 v[32:47], v[192:195], v[52:55], v[32:47]
	v_mfma_f32_32x32x16_bf16 v[32:47], v[196:199], v[56:59], v[32:47]
	v_mfma_f32_32x32x16_bf16 v[32:47], v[200:203], v[60:63], v[32:47]
	s_nop 11
	v_exp_f32_e32 v32, v32
	v_exp_f32_e32 v33, v33
	v_exp_f32_e32 v34, v34
	v_exp_f32_e32 v35, v35
	v_exp_f32_e32 v36, v36
	v_exp_f32_e32 v37, v37
	v_exp_f32_e32 v38, v38
	v_exp_f32_e32 v39, v39
	v_exp_f32_e32 v40, v40
	v_exp_f32_e32 v41, v41
	v_exp_f32_e32 v42, v42
	v_exp_f32_e32 v43, v43
	v_exp_f32_e32 v44, v44
	v_exp_f32_e32 v45, v45
	v_exp_f32_e32 v46, v46
	v_exp_f32_e32 v47, v47
	v_cvt_pk_bf16_f32 v64, v32, v33
	v_cvt_pk_bf16_f32 v65, v34, v35
	v_cvt_pk_bf16_f32 v66, v36, v37
	v_cvt_pk_bf16_f32 v67, v38, v39
	v_cvt_pk_bf16_f32 v68, v40, v41
	v_cvt_pk_bf16_f32 v69, v42, v43
	v_cvt_pk_bf16_f32 v70, v44, v45
	v_cvt_pk_bf16_f32 v71, v46, v47
	v_pk_add_f32 v[232:233], v[232:233], v[32:33]
	v_pk_add_f32 v[232:233], v[232:233], v[34:35]
	v_pk_add_f32 v[232:233], v[232:233], v[36:37]
	v_pk_add_f32 v[232:233], v[232:233], v[38:39]
	v_pk_add_f32 v[232:233], v[232:233], v[40:41]
	v_pk_add_f32 v[232:233], v[232:233], v[42:43]
	v_pk_add_f32 v[232:233], v[232:233], v[44:45]
	v_pk_add_f32 v[232:233], v[232:233], v[46:47]
	ds_read2_b32 v[32:33], v115 offset0:34 offset1:35
	ds_read2_b32 v[34:35], v115 offset0:36 offset1:37
	ds_read2_b32 v[36:37], v115 offset0:42 offset1:43
	ds_read2_b32 v[38:39], v115 offset0:44 offset1:45
	ds_read2_b32 v[40:41], v115 offset0:51 offset1:52
	ds_read2_b32 v[42:43], v115 offset0:53 offset1:54
	ds_read2_b32 v[44:45], v115 offset0:59 offset1:60
	ds_read2_b32 v[46:47], v115 offset0:61 offset1:62
	s_waitcnt lgkmcnt(15)
	v_mfma_f32_32x32x16_bf16 v[0:15], v[64:67], v[72:75], v[0:15]
	v_mfma_f32_32x32x16_bf16 v[16:31], v[64:67], v[76:79], v[16:31]
	v_mfma_f32_32x32x16_bf16 v[0:15], v[68:71], v[220:223], v[0:15]
	v_mfma_f32_32x32x16_bf16 v[16:31], v[68:71], v[224:227], v[16:31]
	global_load_dwordx4 v[188:191], v235, s[84:85]
	global_load_dwordx4 v[192:195], v236, s[84:85]
	global_load_dwordx4 v[196:199], v237, s[84:85]
	global_load_dwordx4 v[200:203], v238, s[84:85]
	global_load_dwordx4 v[204:207], v100, s[84:85] offset:768
	global_load_dwordx4 v[208:211], v149, s[84:85] offset:768
	global_load_dwordx4 v[212:215], v100, s[84:85] offset:832
	global_load_dwordx4 v[216:219], v149, s[84:85] offset:832
	s_add_u32 s84, s84, 0x30000
	s_addc_u32 s85, s85, 0
	s_waitcnt lgkmcnt(0)
	v_mfma_f32_32x32x16_bf16 v[32:47], v[116:119], v[48:51], v[32:47]
	ds_read_b64_tr_b16 v[72:73], v231
	ds_read_b64_tr_b16 v[74:75], v231 offset:512
	ds_read_b64_tr_b16 v[76:77], v231 offset:2048
	ds_read_b64_tr_b16 v[78:79], v231 offset:2560
	ds_read_b64_tr_b16 v[220:221], v231 offset:1024
	ds_read_b64_tr_b16 v[222:223], v231 offset:1536
	ds_read_b64_tr_b16 v[224:225], v231 offset:3072
	ds_read_b64_tr_b16 v[226:227], v231 offset:3584
	s_waitcnt vmcnt(8)
	ds_write_b128 v247, v[156:159]
	ds_write_b128 v247, v[160:163] offset:1024
	ds_write_b128 v247, v[164:167] offset:2048
	ds_write_b128 v247, v[168:171] offset:3072
	ds_read_b128 v[156:159], v248
	ds_read_b128 v[160:163], v249
	ds_read_b128 v[164:167], v250
	ds_read_b128 v[168:171], v251
	ds_write_b128 v112, v[172:175]
	ds_write_b128 v112, v[176:179] offset:1024
	ds_write_b128 v112, v[180:183] offset:2048
	ds_write_b128 v112, v[184:187] offset:3072
	v_mfma_f32_32x32x16_bf16 v[32:47], v[120:123], v[52:55], v[32:47]
	v_mfma_f32_32x32x16_bf16 v[32:47], v[124:127], v[56:59], v[32:47]
	v_mfma_f32_32x32x16_bf16 v[32:47], v[128:131], v[60:63], v[32:47]
	s_nop 11
	v_exp_f32_e32 v32, v32
	v_exp_f32_e32 v33, v33
	v_exp_f32_e32 v34, v34
	v_exp_f32_e32 v35, v35
	v_exp_f32_e32 v36, v36
	v_exp_f32_e32 v37, v37
	v_exp_f32_e32 v38, v38
	v_exp_f32_e32 v39, v39
	v_exp_f32_e32 v40, v40
	v_exp_f32_e32 v41, v41
	v_exp_f32_e32 v42, v42
	v_exp_f32_e32 v43, v43
	v_exp_f32_e32 v44, v44
	v_exp_f32_e32 v45, v45
	v_exp_f32_e32 v46, v46
	v_exp_f32_e32 v47, v47
	v_cvt_pk_bf16_f32 v64, v32, v33
	v_cvt_pk_bf16_f32 v65, v34, v35
	v_cvt_pk_bf16_f32 v66, v36, v37
	v_cvt_pk_bf16_f32 v67, v38, v39
	v_cvt_pk_bf16_f32 v68, v40, v41
	v_cvt_pk_bf16_f32 v69, v42, v43
	v_cvt_pk_bf16_f32 v70, v44, v45
	v_cvt_pk_bf16_f32 v71, v46, v47
	v_pk_add_f32 v[232:233], v[232:233], v[32:33]
	v_pk_add_f32 v[232:233], v[232:233], v[34:35]
	v_pk_add_f32 v[232:233], v[232:233], v[36:37]
	v_pk_add_f32 v[232:233], v[232:233], v[38:39]
	v_pk_add_f32 v[232:233], v[232:233], v[40:41]
	v_pk_add_f32 v[232:233], v[232:233], v[42:43]
	v_pk_add_f32 v[232:233], v[232:233], v[44:45]
	v_pk_add_f32 v[232:233], v[232:233], v[46:47]
	ds_read2_b32 v[32:33], v115 offset0:68 offset1:69
	ds_read2_b32 v[34:35], v115 offset0:70 offset1:71
	ds_read2_b32 v[36:37], v115 offset0:76 offset1:77
	ds_read2_b32 v[38:39], v115 offset0:78 offset1:79
	ds_read2_b32 v[40:41], v115 offset0:85 offset1:86
	ds_read2_b32 v[42:43], v115 offset0:87 offset1:88
	ds_read2_b32 v[44:45], v115 offset0:93 offset1:94
	ds_read2_b32 v[46:47], v115 offset0:95 offset1:96
	s_waitcnt lgkmcnt(15)
	v_mfma_f32_32x32x16_bf16 v[0:15], v[64:67], v[72:75], v[0:15]
	v_mfma_f32_32x32x16_bf16 v[16:31], v[64:67], v[76:79], v[16:31]
	v_mfma_f32_32x32x16_bf16 v[0:15], v[68:71], v[220:223], v[0:15]
	v_mfma_f32_32x32x16_bf16 v[16:31], v[68:71], v[224:227], v[16:31]
	global_load_dwordx4 v[116:119], v235, s[84:85]
	global_load_dwordx4 v[120:123], v236, s[84:85]
	global_load_dwordx4 v[124:127], v237, s[84:85]
	global_load_dwordx4 v[128:131], v238, s[84:85]
	global_load_dwordx4 v[132:135], v100, s[84:85] offset:768
	global_load_dwordx4 v[136:139], v149, s[84:85] offset:768
	global_load_dwordx4 v[140:143], v100, s[84:85] offset:832
	global_load_dwordx4 v[144:147], v149, s[84:85] offset:832
	s_add_u32 s84, s84, 0x30000
	s_addc_u32 s85, s85, 0
	s_waitcnt lgkmcnt(0)
	v_mfma_f32_32x32x16_bf16 v[32:47], v[156:159], v[48:51], v[32:47]
	ds_read_b64_tr_b16 v[72:73], v231
	ds_read_b64_tr_b16 v[74:75], v231 offset:512
	ds_read_b64_tr_b16 v[76:77], v231 offset:2048
	ds_read_b64_tr_b16 v[78:79], v231 offset:2560
	ds_read_b64_tr_b16 v[220:221], v231 offset:1024
	ds_read_b64_tr_b16 v[222:223], v231 offset:1536
	ds_read_b64_tr_b16 v[224:225], v231 offset:3072
	ds_read_b64_tr_b16 v[226:227], v231 offset:3584
	s_waitcnt vmcnt(8)
	ds_write_b128 v247, v[188:191]
	ds_write_b128 v247, v[192:195] offset:1024
	ds_write_b128 v247, v[196:199] offset:2048
	ds_write_b128 v247, v[200:203] offset:3072
	ds_read_b128 v[188:191], v248
	ds_read_b128 v[192:195], v249
	ds_read_b128 v[196:199], v250
	ds_read_b128 v[200:203], v251
	ds_write_b128 v112, v[204:207]
	ds_write_b128 v112, v[208:211] offset:1024
	ds_write_b128 v112, v[212:215] offset:2048
	ds_write_b128 v112, v[216:219] offset:3072
	v_mfma_f32_32x32x16_bf16 v[32:47], v[160:163], v[52:55], v[32:47]
	v_mfma_f32_32x32x16_bf16 v[32:47], v[164:167], v[56:59], v[32:47]
	v_mfma_f32_32x32x16_bf16 v[32:47], v[168:171], v[60:63], v[32:47]
	s_nop 11
	v_exp_f32_e32 v32, v32
	v_exp_f32_e32 v33, v33
	v_exp_f32_e32 v34, v34
	v_exp_f32_e32 v35, v35
	v_exp_f32_e32 v36, v36
	v_exp_f32_e32 v37, v37
	v_exp_f32_e32 v38, v38
	v_exp_f32_e32 v39, v39
	v_exp_f32_e32 v40, v40
	v_exp_f32_e32 v41, v41
	v_exp_f32_e32 v42, v42
	v_exp_f32_e32 v43, v43
	v_exp_f32_e32 v44, v44
	v_exp_f32_e32 v45, v45
	v_exp_f32_e32 v46, v46
	v_exp_f32_e32 v47, v47
	v_cvt_pk_bf16_f32 v64, v32, v33
	v_cvt_pk_bf16_f32 v65, v34, v35
	v_cvt_pk_bf16_f32 v66, v36, v37
	v_cvt_pk_bf16_f32 v67, v38, v39
	v_cvt_pk_bf16_f32 v68, v40, v41
	v_cvt_pk_bf16_f32 v69, v42, v43
	v_cvt_pk_bf16_f32 v70, v44, v45
	v_cvt_pk_bf16_f32 v71, v46, v47
	v_pk_add_f32 v[232:233], v[232:233], v[32:33]
	v_pk_add_f32 v[232:233], v[232:233], v[34:35]
	v_pk_add_f32 v[232:233], v[232:233], v[36:37]
	v_pk_add_f32 v[232:233], v[232:233], v[38:39]
	v_pk_add_f32 v[232:233], v[232:233], v[40:41]
	v_pk_add_f32 v[232:233], v[232:233], v[42:43]
	v_pk_add_f32 v[232:233], v[232:233], v[44:45]
	v_pk_add_f32 v[232:233], v[232:233], v[46:47]
	ds_read2_b32 v[32:33], v115 offset0:102 offset1:103
	ds_read2_b32 v[34:35], v115 offset0:104 offset1:105
	ds_read2_b32 v[36:37], v115 offset0:110 offset1:111
	ds_read2_b32 v[38:39], v115 offset0:112 offset1:113
	ds_read2_b32 v[40:41], v115 offset0:119 offset1:120
	ds_read2_b32 v[42:43], v115 offset0:121 offset1:122
	ds_read2_b32 v[44:45], v115 offset0:127 offset1:128
	ds_read2_b32 v[46:47], v115 offset0:129 offset1:130
	s_waitcnt lgkmcnt(15)
	v_mfma_f32_32x32x16_bf16 v[0:15], v[64:67], v[72:75], v[0:15]
	v_mfma_f32_32x32x16_bf16 v[16:31], v[64:67], v[76:79], v[16:31]
	v_mfma_f32_32x32x16_bf16 v[0:15], v[68:71], v[220:223], v[0:15]
	v_mfma_f32_32x32x16_bf16 v[16:31], v[68:71], v[224:227], v[16:31]
	global_load_dwordx4 v[156:159], v235, s[84:85]
	global_load_dwordx4 v[160:163], v236, s[84:85]
	global_load_dwordx4 v[164:167], v237, s[84:85]
	global_load_dwordx4 v[168:171], v238, s[84:85]
	global_load_dwordx4 v[172:175], v100, s[84:85] offset:768
	global_load_dwordx4 v[176:179], v149, s[84:85] offset:768
	global_load_dwordx4 v[180:183], v100, s[84:85] offset:832
	global_load_dwordx4 v[184:187], v149, s[84:85] offset:832
	s_waitcnt lgkmcnt(0)
	v_mfma_f32_32x32x16_bf16 v[32:47], v[188:191], v[48:51], v[32:47]
	ds_read_b64_tr_b16 v[72:73], v231
	ds_read_b64_tr_b16 v[74:75], v231 offset:512
	ds_read_b64_tr_b16 v[76:77], v231 offset:2048
	ds_read_b64_tr_b16 v[78:79], v231 offset:2560
	ds_read_b64_tr_b16 v[220:221], v231 offset:1024
	ds_read_b64_tr_b16 v[222:223], v231 offset:1536
	ds_read_b64_tr_b16 v[224:225], v231 offset:3072
	ds_read_b64_tr_b16 v[226:227], v231 offset:3584
	s_waitcnt vmcnt(8)
	ds_write_b128 v247, v[116:119]
	ds_write_b128 v247, v[120:123] offset:1024
	ds_write_b128 v247, v[124:127] offset:2048
	ds_write_b128 v247, v[128:131] offset:3072
	ds_read_b128 v[116:119], v248
	ds_read_b128 v[120:123], v249
	ds_read_b128 v[124:127], v250
	ds_read_b128 v[128:131], v251
	ds_write_b128 v112, v[132:135]
	ds_write_b128 v112, v[136:139] offset:1024
	ds_write_b128 v112, v[140:143] offset:2048
	ds_write_b128 v112, v[144:147] offset:3072
	v_mfma_f32_32x32x16_bf16 v[32:47], v[192:195], v[52:55], v[32:47]
	v_mfma_f32_32x32x16_bf16 v[32:47], v[196:199], v[56:59], v[32:47]
	v_mfma_f32_32x32x16_bf16 v[32:47], v[200:203], v[60:63], v[32:47]
	s_nop 11
	v_exp_f32_e32 v32, v32
	v_exp_f32_e32 v33, v33
	v_exp_f32_e32 v34, v34
	v_exp_f32_e32 v35, v35
	v_exp_f32_e32 v36, v36
	v_exp_f32_e32 v37, v37
	v_exp_f32_e32 v38, v38
	v_exp_f32_e32 v39, v39
	v_exp_f32_e32 v40, v40
	v_exp_f32_e32 v41, v41
	v_exp_f32_e32 v42, v42
	v_exp_f32_e32 v43, v43
	v_exp_f32_e32 v44, v44
	v_exp_f32_e32 v45, v45
	v_exp_f32_e32 v46, v46
	v_exp_f32_e32 v47, v47
	v_cvt_pk_bf16_f32 v64, v32, v33
	v_cvt_pk_bf16_f32 v65, v34, v35
	v_cvt_pk_bf16_f32 v66, v36, v37
	v_cvt_pk_bf16_f32 v67, v38, v39
	v_cvt_pk_bf16_f32 v68, v40, v41
	v_cvt_pk_bf16_f32 v69, v42, v43
	v_cvt_pk_bf16_f32 v70, v44, v45
	v_cvt_pk_bf16_f32 v71, v46, v47
	v_pk_add_f32 v[232:233], v[232:233], v[32:33]
	v_pk_add_f32 v[232:233], v[232:233], v[34:35]
	v_pk_add_f32 v[232:233], v[232:233], v[36:37]
	v_pk_add_f32 v[232:233], v[232:233], v[38:39]
	v_pk_add_f32 v[232:233], v[232:233], v[40:41]
	v_pk_add_f32 v[232:233], v[232:233], v[42:43]
	v_pk_add_f32 v[232:233], v[232:233], v[44:45]
	v_pk_add_f32 v[232:233], v[232:233], v[46:47]
	ds_read2_b32 v[32:33], v115 offset0:136 offset1:137
	ds_read2_b32 v[34:35], v115 offset0:138 offset1:139
	ds_read2_b32 v[36:37], v115 offset0:144 offset1:145
	ds_read2_b32 v[38:39], v115 offset0:146 offset1:147
	ds_read2_b32 v[40:41], v115 offset0:153 offset1:154
	ds_read2_b32 v[42:43], v115 offset0:155 offset1:156
	ds_read2_b32 v[44:45], v115 offset0:161 offset1:162
	ds_read2_b32 v[46:47], v115 offset0:163 offset1:164
	s_waitcnt lgkmcnt(15)
	v_mfma_f32_32x32x16_bf16 v[0:15], v[64:67], v[72:75], v[0:15]
	v_mfma_f32_32x32x16_bf16 v[16:31], v[64:67], v[76:79], v[16:31]
	v_mfma_f32_32x32x16_bf16 v[0:15], v[68:71], v[220:223], v[0:15]
	v_mfma_f32_32x32x16_bf16 v[16:31], v[68:71], v[224:227], v[16:31]
	global_load_dwordx4 v[188:191], v239, s[86:87]
	global_load_dwordx4 v[192:195], v240, s[86:87]
	global_load_dwordx4 v[196:199], v241, s[86:87]
	global_load_dwordx4 v[200:203], v242, s[86:87]
	global_load_dwordx4 v[204:207], v101, s[86:87] offset:768
	global_load_dwordx4 v[208:211], v150, s[86:87] offset:768
	global_load_dwordx4 v[212:215], v101, s[86:87] offset:832
	global_load_dwordx4 v[216:219], v150, s[86:87] offset:832
	s_add_u32 s86, s86, 0xc0000
	s_addc_u32 s87, s87, 0
	s_waitcnt lgkmcnt(0)
	v_mfma_f32_32x32x16_bf16 v[32:47], v[116:119], v[48:51], v[32:47]
	ds_read_b64_tr_b16 v[72:73], v231
	ds_read_b64_tr_b16 v[74:75], v231 offset:512
	ds_read_b64_tr_b16 v[76:77], v231 offset:2048
	ds_read_b64_tr_b16 v[78:79], v231 offset:2560
	ds_read_b64_tr_b16 v[220:221], v231 offset:1024
	ds_read_b64_tr_b16 v[222:223], v231 offset:1536
	ds_read_b64_tr_b16 v[224:225], v231 offset:3072
	ds_read_b64_tr_b16 v[226:227], v231 offset:3584
	s_waitcnt vmcnt(8)
	ds_write_b128 v247, v[156:159]
	ds_write_b128 v247, v[160:163] offset:1024
	ds_write_b128 v247, v[164:167] offset:2048
	ds_write_b128 v247, v[168:171] offset:3072
	ds_read_b128 v[156:159], v248
	ds_read_b128 v[160:163], v249
	ds_read_b128 v[164:167], v250
	ds_read_b128 v[168:171], v251
	ds_write_b128 v112, v[172:175]
	ds_write_b128 v112, v[176:179] offset:1024
	ds_write_b128 v112, v[180:183] offset:2048
	ds_write_b128 v112, v[184:187] offset:3072
	v_mfma_f32_32x32x16_bf16 v[32:47], v[120:123], v[52:55], v[32:47]
	v_mfma_f32_32x32x16_bf16 v[32:47], v[124:127], v[56:59], v[32:47]
	v_mfma_f32_32x32x16_bf16 v[32:47], v[128:131], v[60:63], v[32:47]
	s_nop 11
	v_exp_f32_e32 v32, v32
	v_exp_f32_e32 v33, v33
	v_exp_f32_e32 v34, v34
	v_exp_f32_e32 v35, v35
	v_exp_f32_e32 v36, v36
	v_exp_f32_e32 v37, v37
	v_exp_f32_e32 v38, v38
	v_exp_f32_e32 v39, v39
	v_exp_f32_e32 v40, v40
	v_exp_f32_e32 v41, v41
	v_exp_f32_e32 v42, v42
	v_exp_f32_e32 v43, v43
	v_exp_f32_e32 v44, v44
	v_exp_f32_e32 v45, v45
	v_exp_f32_e32 v46, v46
	v_exp_f32_e32 v47, v47
	v_cvt_pk_bf16_f32 v64, v32, v33
	v_cvt_pk_bf16_f32 v65, v34, v35
	v_cvt_pk_bf16_f32 v66, v36, v37
	v_cvt_pk_bf16_f32 v67, v38, v39
	v_cvt_pk_bf16_f32 v68, v40, v41
	v_cvt_pk_bf16_f32 v69, v42, v43
	v_cvt_pk_bf16_f32 v70, v44, v45
	v_cvt_pk_bf16_f32 v71, v46, v47
	v_pk_add_f32 v[232:233], v[232:233], v[32:33]
	v_pk_add_f32 v[232:233], v[232:233], v[34:35]
	v_pk_add_f32 v[232:233], v[232:233], v[36:37]
	v_pk_add_f32 v[232:233], v[232:233], v[38:39]
	v_pk_add_f32 v[232:233], v[232:233], v[40:41]
	v_pk_add_f32 v[232:233], v[232:233], v[42:43]
	v_pk_add_f32 v[232:233], v[232:233], v[44:45]
	v_pk_add_f32 v[232:233], v[232:233], v[46:47]
	ds_read2_b32 v[32:33], v115 offset0:170 offset1:171
	ds_read2_b32 v[34:35], v115 offset0:172 offset1:173
	ds_read2_b32 v[36:37], v115 offset0:178 offset1:179
	ds_read2_b32 v[38:39], v115 offset0:180 offset1:181
	ds_read2_b32 v[40:41], v115 offset0:187 offset1:188
	ds_read2_b32 v[42:43], v115 offset0:189 offset1:190
	ds_read2_b32 v[44:45], v115 offset0:195 offset1:196
	ds_read2_b32 v[46:47], v115 offset0:197 offset1:198
	s_waitcnt lgkmcnt(15)
	v_mfma_f32_32x32x16_bf16 v[0:15], v[64:67], v[72:75], v[0:15]
	v_mfma_f32_32x32x16_bf16 v[16:31], v[64:67], v[76:79], v[16:31]
	v_mfma_f32_32x32x16_bf16 v[0:15], v[68:71], v[220:223], v[0:15]
	v_mfma_f32_32x32x16_bf16 v[16:31], v[68:71], v[224:227], v[16:31]
	global_load_dwordx4 v[116:119], v239, s[86:87]
	global_load_dwordx4 v[120:123], v240, s[86:87]
	global_load_dwordx4 v[124:127], v241, s[86:87]
	global_load_dwordx4 v[128:131], v242, s[86:87]
	global_load_dwordx4 v[132:135], v101, s[86:87] offset:768
	global_load_dwordx4 v[136:139], v150, s[86:87] offset:768
	global_load_dwordx4 v[140:143], v101, s[86:87] offset:832
	global_load_dwordx4 v[144:147], v150, s[86:87] offset:832
	s_add_u32 s86, s86, 0xc0000
	s_addc_u32 s87, s87, 0
	s_waitcnt lgkmcnt(0)
	v_mfma_f32_32x32x16_bf16 v[32:47], v[156:159], v[48:51], v[32:47]
	ds_read_b64_tr_b16 v[72:73], v231
	ds_read_b64_tr_b16 v[74:75], v231 offset:512
	ds_read_b64_tr_b16 v[76:77], v231 offset:2048
	ds_read_b64_tr_b16 v[78:79], v231 offset:2560
	ds_read_b64_tr_b16 v[220:221], v231 offset:1024
	ds_read_b64_tr_b16 v[222:223], v231 offset:1536
	ds_read_b64_tr_b16 v[224:225], v231 offset:3072
	ds_read_b64_tr_b16 v[226:227], v231 offset:3584
	s_waitcnt vmcnt(8)
	ds_write_b128 v247, v[188:191]
	ds_write_b128 v247, v[192:195] offset:1024
	ds_write_b128 v247, v[196:199] offset:2048
	ds_write_b128 v247, v[200:203] offset:3072
	ds_read_b128 v[188:191], v248
	ds_read_b128 v[192:195], v249
	ds_read_b128 v[196:199], v250
	ds_read_b128 v[200:203], v251
	ds_write_b128 v112, v[204:207]
	ds_write_b128 v112, v[208:211] offset:1024
	ds_write_b128 v112, v[212:215] offset:2048
	ds_write_b128 v112, v[216:219] offset:3072
	v_mfma_f32_32x32x16_bf16 v[32:47], v[160:163], v[52:55], v[32:47]
	v_mfma_f32_32x32x16_bf16 v[32:47], v[164:167], v[56:59], v[32:47]
	v_mfma_f32_32x32x16_bf16 v[32:47], v[168:171], v[60:63], v[32:47]
	s_nop 11
	v_exp_f32_e32 v32, v32
	v_exp_f32_e32 v33, v33
	v_exp_f32_e32 v34, v34
	v_exp_f32_e32 v35, v35
	v_exp_f32_e32 v36, v36
	v_exp_f32_e32 v37, v37
	v_exp_f32_e32 v38, v38
	v_exp_f32_e32 v39, v39
	v_exp_f32_e32 v40, v40
	v_exp_f32_e32 v41, v41
	v_exp_f32_e32 v42, v42
	v_exp_f32_e32 v43, v43
	v_exp_f32_e32 v44, v44
	v_exp_f32_e32 v45, v45
	v_exp_f32_e32 v46, v46
	v_exp_f32_e32 v47, v47
	v_cvt_pk_bf16_f32 v64, v32, v33
	v_cvt_pk_bf16_f32 v65, v34, v35
	v_cvt_pk_bf16_f32 v66, v36, v37
	v_cvt_pk_bf16_f32 v67, v38, v39
	v_cvt_pk_bf16_f32 v68, v40, v41
	v_cvt_pk_bf16_f32 v69, v42, v43
	v_cvt_pk_bf16_f32 v70, v44, v45
	v_cvt_pk_bf16_f32 v71, v46, v47
	v_pk_add_f32 v[232:233], v[232:233], v[32:33]
	v_pk_add_f32 v[232:233], v[232:233], v[34:35]
	v_pk_add_f32 v[232:233], v[232:233], v[36:37]
	v_pk_add_f32 v[232:233], v[232:233], v[38:39]
	v_pk_add_f32 v[232:233], v[232:233], v[40:41]
	v_pk_add_f32 v[232:233], v[232:233], v[42:43]
	v_pk_add_f32 v[232:233], v[232:233], v[44:45]
	v_pk_add_f32 v[232:233], v[232:233], v[46:47]
	v_mov_b32_e32 v115, v229
	ds_read2_b32 v[32:33], v115 offset0:0 offset1:1
	ds_read2_b32 v[34:35], v115 offset0:2 offset1:3
	ds_read2_b32 v[36:37], v115 offset0:8 offset1:9
	ds_read2_b32 v[38:39], v115 offset0:10 offset1:11
	ds_read2_b32 v[40:41], v115 offset0:16 offset1:17
	ds_read2_b32 v[42:43], v115 offset0:18 offset1:19
	ds_read2_b32 v[44:45], v115 offset0:24 offset1:25
	ds_read2_b32 v[46:47], v115 offset0:26 offset1:27
	s_waitcnt lgkmcnt(15)
	v_mfma_f32_32x32x16_bf16 v[0:15], v[64:67], v[72:75], v[0:15]
	v_mfma_f32_32x32x16_bf16 v[16:31], v[64:67], v[76:79], v[16:31]
	v_mfma_f32_32x32x16_bf16 v[0:15], v[68:71], v[220:223], v[0:15]
	v_mfma_f32_32x32x16_bf16 v[16:31], v[68:71], v[224:227], v[16:31]
	global_load_dwordx4 v[156:159], v239, s[86:87]
	global_load_dwordx4 v[160:163], v240, s[86:87]
	global_load_dwordx4 v[164:167], v241, s[86:87]
	global_load_dwordx4 v[168:171], v242, s[86:87]
	global_load_dwordx4 v[172:175], v101, s[86:87] offset:768
	global_load_dwordx4 v[176:179], v150, s[86:87] offset:768
	global_load_dwordx4 v[180:183], v101, s[86:87] offset:832
	global_load_dwordx4 v[184:187], v150, s[86:87] offset:832
	s_add_u32 s86, s86, 0xc0000
	s_addc_u32 s87, s87, 0
	s_waitcnt lgkmcnt(0)
	v_mfma_f32_32x32x16_bf16 v[32:47], v[188:191], v[48:51], v[32:47]
	ds_read_b64_tr_b16 v[72:73], v231
	ds_read_b64_tr_b16 v[74:75], v231 offset:512
	ds_read_b64_tr_b16 v[76:77], v231 offset:2048
	ds_read_b64_tr_b16 v[78:79], v231 offset:2560
	ds_read_b64_tr_b16 v[220:221], v231 offset:1024
	ds_read_b64_tr_b16 v[222:223], v231 offset:1536
	ds_read_b64_tr_b16 v[224:225], v231 offset:3072
	ds_read_b64_tr_b16 v[226:227], v231 offset:3584
	s_waitcnt vmcnt(8)
	ds_write_b128 v247, v[116:119]
	ds_write_b128 v247, v[120:123] offset:1024
	ds_write_b128 v247, v[124:127] offset:2048
	ds_write_b128 v247, v[128:131] offset:3072
	ds_read_b128 v[116:119], v248
	ds_read_b128 v[120:123], v249
	ds_read_b128 v[124:127], v250
	ds_read_b128 v[128:131], v251
	ds_write_b128 v112, v[132:135]
	ds_write_b128 v112, v[136:139] offset:1024
	ds_write_b128 v112, v[140:143] offset:2048
	ds_write_b128 v112, v[144:147] offset:3072
	v_mfma_f32_32x32x16_bf16 v[32:47], v[192:195], v[52:55], v[32:47]
	v_mfma_f32_32x32x16_bf16 v[32:47], v[196:199], v[56:59], v[32:47]
	v_mfma_f32_32x32x16_bf16 v[32:47], v[200:203], v[60:63], v[32:47]
	s_nop 11
	v_exp_f32_e32 v32, v32
	v_exp_f32_e32 v33, v33
	v_exp_f32_e32 v34, v34
	v_exp_f32_e32 v35, v35
	v_exp_f32_e32 v36, v36
	v_exp_f32_e32 v37, v37
	v_exp_f32_e32 v38, v38
	v_exp_f32_e32 v39, v39
	v_exp_f32_e32 v40, v40
	v_exp_f32_e32 v41, v41
	v_exp_f32_e32 v42, v42
	v_exp_f32_e32 v43, v43
	v_exp_f32_e32 v44, v44
	v_exp_f32_e32 v45, v45
	v_exp_f32_e32 v46, v46
	v_exp_f32_e32 v47, v47
	v_cvt_pk_bf16_f32 v64, v32, v33
	v_cvt_pk_bf16_f32 v65, v34, v35
	v_cvt_pk_bf16_f32 v66, v36, v37
	v_cvt_pk_bf16_f32 v67, v38, v39
	v_cvt_pk_bf16_f32 v68, v40, v41
	v_cvt_pk_bf16_f32 v69, v42, v43
	v_cvt_pk_bf16_f32 v70, v44, v45
	v_cvt_pk_bf16_f32 v71, v46, v47
	v_pk_add_f32 v[232:233], v[232:233], v[32:33]
	v_pk_add_f32 v[232:233], v[232:233], v[34:35]
	v_pk_add_f32 v[232:233], v[232:233], v[36:37]
	v_pk_add_f32 v[232:233], v[232:233], v[38:39]
	v_pk_add_f32 v[232:233], v[232:233], v[40:41]
	v_pk_add_f32 v[232:233], v[232:233], v[42:43]
	v_pk_add_f32 v[232:233], v[232:233], v[44:45]
	v_pk_add_f32 v[232:233], v[232:233], v[46:47]
	ds_read2_b32 v[32:33], v115 offset0:32 offset1:33
	ds_read2_b32 v[34:35], v115 offset0:34 offset1:35
	ds_read2_b32 v[36:37], v115 offset0:40 offset1:41
	ds_read2_b32 v[38:39], v115 offset0:42 offset1:43
	ds_read2_b32 v[40:41], v115 offset0:48 offset1:49
	ds_read2_b32 v[42:43], v115 offset0:50 offset1:51
	ds_read2_b32 v[44:45], v115 offset0:56 offset1:57
	ds_read2_b32 v[46:47], v115 offset0:58 offset1:59
	s_waitcnt lgkmcnt(15)
	v_mfma_f32_32x32x16_bf16 v[0:15], v[64:67], v[72:75], v[0:15]
	v_mfma_f32_32x32x16_bf16 v[16:31], v[64:67], v[76:79], v[16:31]
	v_mfma_f32_32x32x16_bf16 v[0:15], v[68:71], v[220:223], v[0:15]
	v_mfma_f32_32x32x16_bf16 v[16:31], v[68:71], v[224:227], v[16:31]
	global_load_dwordx4 v[188:191], v239, s[86:87]
	global_load_dwordx4 v[192:195], v240, s[86:87]
	global_load_dwordx4 v[196:199], v241, s[86:87]
	global_load_dwordx4 v[200:203], v242, s[86:87]
	global_load_dwordx4 v[204:207], v101, s[86:87] offset:768
	global_load_dwordx4 v[208:211], v150, s[86:87] offset:768
	global_load_dwordx4 v[212:215], v101, s[86:87] offset:832
	global_load_dwordx4 v[216:219], v150, s[86:87] offset:832
	s_add_u32 s86, s86, 0xc0000
	s_addc_u32 s87, s87, 0
	s_waitcnt lgkmcnt(0)
	v_mfma_f32_32x32x16_bf16 v[32:47], v[116:119], v[48:51], v[32:47]
	ds_read_b64_tr_b16 v[72:73], v231
	ds_read_b64_tr_b16 v[74:75], v231 offset:512
	ds_read_b64_tr_b16 v[76:77], v231 offset:2048
	ds_read_b64_tr_b16 v[78:79], v231 offset:2560
	ds_read_b64_tr_b16 v[220:221], v231 offset:1024
	ds_read_b64_tr_b16 v[222:223], v231 offset:1536
	ds_read_b64_tr_b16 v[224:225], v231 offset:3072
	ds_read_b64_tr_b16 v[226:227], v231 offset:3584
	s_waitcnt vmcnt(8)
	ds_write_b128 v247, v[156:159]
	ds_write_b128 v247, v[160:163] offset:1024
	ds_write_b128 v247, v[164:167] offset:2048
	ds_write_b128 v247, v[168:171] offset:3072
	ds_read_b128 v[156:159], v248
	ds_read_b128 v[160:163], v249
	ds_read_b128 v[164:167], v250
	ds_read_b128 v[168:171], v251
	ds_write_b128 v112, v[172:175]
	ds_write_b128 v112, v[176:179] offset:1024
	ds_write_b128 v112, v[180:183] offset:2048
	ds_write_b128 v112, v[184:187] offset:3072
	v_mfma_f32_32x32x16_bf16 v[32:47], v[120:123], v[52:55], v[32:47]
	v_mfma_f32_32x32x16_bf16 v[32:47], v[124:127], v[56:59], v[32:47]
	v_mfma_f32_32x32x16_bf16 v[32:47], v[128:131], v[60:63], v[32:47]
	s_nop 11
	v_exp_f32_e32 v32, v32
	v_exp_f32_e32 v33, v33
	v_exp_f32_e32 v34, v34
	v_exp_f32_e32 v35, v35
	v_exp_f32_e32 v36, v36
	v_exp_f32_e32 v37, v37
	v_exp_f32_e32 v38, v38
	v_exp_f32_e32 v39, v39
	v_exp_f32_e32 v40, v40
	v_exp_f32_e32 v41, v41
	v_exp_f32_e32 v42, v42
	v_exp_f32_e32 v43, v43
	v_exp_f32_e32 v44, v44
	v_exp_f32_e32 v45, v45
	v_exp_f32_e32 v46, v46
	v_exp_f32_e32 v47, v47
	v_cvt_pk_bf16_f32 v64, v32, v33
	v_cvt_pk_bf16_f32 v65, v34, v35
	v_cvt_pk_bf16_f32 v66, v36, v37
	v_cvt_pk_bf16_f32 v67, v38, v39
	v_cvt_pk_bf16_f32 v68, v40, v41
	v_cvt_pk_bf16_f32 v69, v42, v43
	v_cvt_pk_bf16_f32 v70, v44, v45
	v_cvt_pk_bf16_f32 v71, v46, v47
	v_pk_add_f32 v[232:233], v[232:233], v[32:33]
	v_pk_add_f32 v[232:233], v[232:233], v[34:35]
	v_pk_add_f32 v[232:233], v[232:233], v[36:37]
	v_pk_add_f32 v[232:233], v[232:233], v[38:39]
	v_pk_add_f32 v[232:233], v[232:233], v[40:41]
	v_pk_add_f32 v[232:233], v[232:233], v[42:43]
	v_pk_add_f32 v[232:233], v[232:233], v[44:45]
	v_pk_add_f32 v[232:233], v[232:233], v[46:47]
	ds_read2_b32 v[32:33], v115 offset0:64 offset1:65
	ds_read2_b32 v[34:35], v115 offset0:66 offset1:67
	ds_read2_b32 v[36:37], v115 offset0:72 offset1:73
	ds_read2_b32 v[38:39], v115 offset0:74 offset1:75
	ds_read2_b32 v[40:41], v115 offset0:80 offset1:81
	ds_read2_b32 v[42:43], v115 offset0:82 offset1:83
	ds_read2_b32 v[44:45], v115 offset0:88 offset1:89
	ds_read2_b32 v[46:47], v115 offset0:90 offset1:91
	s_waitcnt lgkmcnt(15)
	v_mfma_f32_32x32x16_bf16 v[0:15], v[64:67], v[72:75], v[0:15]
	v_mfma_f32_32x32x16_bf16 v[16:31], v[64:67], v[76:79], v[16:31]
	v_mfma_f32_32x32x16_bf16 v[0:15], v[68:71], v[220:223], v[0:15]
	v_mfma_f32_32x32x16_bf16 v[16:31], v[68:71], v[224:227], v[16:31]
	global_load_dwordx4 v[116:119], v239, s[86:87]
	global_load_dwordx4 v[120:123], v240, s[86:87]
	global_load_dwordx4 v[124:127], v241, s[86:87]
	global_load_dwordx4 v[128:131], v242, s[86:87]
	global_load_dwordx4 v[132:135], v101, s[86:87] offset:768
	global_load_dwordx4 v[136:139], v150, s[86:87] offset:768
	global_load_dwordx4 v[140:143], v101, s[86:87] offset:832
	global_load_dwordx4 v[144:147], v150, s[86:87] offset:832
	s_add_u32 s86, s86, 0xc0000
	s_addc_u32 s87, s87, 0
	s_waitcnt lgkmcnt(0)
	v_mfma_f32_32x32x16_bf16 v[32:47], v[156:159], v[48:51], v[32:47]
	ds_read_b64_tr_b16 v[72:73], v231
	ds_read_b64_tr_b16 v[74:75], v231 offset:512
	ds_read_b64_tr_b16 v[76:77], v231 offset:2048
	ds_read_b64_tr_b16 v[78:79], v231 offset:2560
	ds_read_b64_tr_b16 v[220:221], v231 offset:1024
	ds_read_b64_tr_b16 v[222:223], v231 offset:1536
	ds_read_b64_tr_b16 v[224:225], v231 offset:3072
	ds_read_b64_tr_b16 v[226:227], v231 offset:3584
	s_waitcnt vmcnt(8)
	ds_write_b128 v247, v[188:191]
	ds_write_b128 v247, v[192:195] offset:1024
	ds_write_b128 v247, v[196:199] offset:2048
	ds_write_b128 v247, v[200:203] offset:3072
	ds_read_b128 v[188:191], v248
	ds_read_b128 v[192:195], v249
	ds_read_b128 v[196:199], v250
	ds_read_b128 v[200:203], v251
	ds_write_b128 v112, v[204:207]
	ds_write_b128 v112, v[208:211] offset:1024
	ds_write_b128 v112, v[212:215] offset:2048
	ds_write_b128 v112, v[216:219] offset:3072
	v_mfma_f32_32x32x16_bf16 v[32:47], v[160:163], v[52:55], v[32:47]
	v_mfma_f32_32x32x16_bf16 v[32:47], v[164:167], v[56:59], v[32:47]
	v_mfma_f32_32x32x16_bf16 v[32:47], v[168:171], v[60:63], v[32:47]
	s_nop 11
	v_exp_f32_e32 v32, v32
	v_exp_f32_e32 v33, v33
	v_exp_f32_e32 v34, v34
	v_exp_f32_e32 v35, v35
	v_exp_f32_e32 v36, v36
	v_exp_f32_e32 v37, v37
	v_exp_f32_e32 v38, v38
	v_exp_f32_e32 v39, v39
	v_exp_f32_e32 v40, v40
	v_exp_f32_e32 v41, v41
	v_exp_f32_e32 v42, v42
	v_exp_f32_e32 v43, v43
	v_exp_f32_e32 v44, v44
	v_exp_f32_e32 v45, v45
	v_exp_f32_e32 v46, v46
	v_exp_f32_e32 v47, v47
	v_cvt_pk_bf16_f32 v64, v32, v33
	v_cvt_pk_bf16_f32 v65, v34, v35
	v_cvt_pk_bf16_f32 v66, v36, v37
	v_cvt_pk_bf16_f32 v67, v38, v39
	v_cvt_pk_bf16_f32 v68, v40, v41
	v_cvt_pk_bf16_f32 v69, v42, v43
	v_cvt_pk_bf16_f32 v70, v44, v45
	v_cvt_pk_bf16_f32 v71, v46, v47
	v_pk_add_f32 v[232:233], v[232:233], v[32:33]
	v_pk_add_f32 v[232:233], v[232:233], v[34:35]
	v_pk_add_f32 v[232:233], v[232:233], v[36:37]
	v_pk_add_f32 v[232:233], v[232:233], v[38:39]
	v_pk_add_f32 v[232:233], v[232:233], v[40:41]
	v_pk_add_f32 v[232:233], v[232:233], v[42:43]
	v_pk_add_f32 v[232:233], v[232:233], v[44:45]
	v_pk_add_f32 v[232:233], v[232:233], v[46:47]
	ds_read2_b32 v[32:33], v115 offset0:96 offset1:97
	ds_read2_b32 v[34:35], v115 offset0:98 offset1:99
	ds_read2_b32 v[36:37], v115 offset0:104 offset1:105
	ds_read2_b32 v[38:39], v115 offset0:106 offset1:107
	ds_read2_b32 v[40:41], v115 offset0:112 offset1:113
	ds_read2_b32 v[42:43], v115 offset0:114 offset1:115
	ds_read2_b32 v[44:45], v115 offset0:120 offset1:121
	ds_read2_b32 v[46:47], v115 offset0:122 offset1:123
	s_waitcnt lgkmcnt(15)
	v_mfma_f32_32x32x16_bf16 v[0:15], v[64:67], v[72:75], v[0:15]
	v_mfma_f32_32x32x16_bf16 v[16:31], v[64:67], v[76:79], v[16:31]
	v_mfma_f32_32x32x16_bf16 v[0:15], v[68:71], v[220:223], v[0:15]
	v_mfma_f32_32x32x16_bf16 v[16:31], v[68:71], v[224:227], v[16:31]
	global_load_dwordx4 v[156:159], v239, s[86:87]
	global_load_dwordx4 v[160:163], v240, s[86:87]
	global_load_dwordx4 v[164:167], v241, s[86:87]
	global_load_dwordx4 v[168:171], v242, s[86:87]
	global_load_dwordx4 v[172:175], v101, s[86:87] offset:768
	global_load_dwordx4 v[176:179], v150, s[86:87] offset:768
	global_load_dwordx4 v[180:183], v101, s[86:87] offset:832
	global_load_dwordx4 v[184:187], v150, s[86:87] offset:832
	s_add_u32 s86, s86, 0xc0000
	s_addc_u32 s87, s87, 0
	s_waitcnt lgkmcnt(0)
	v_mfma_f32_32x32x16_bf16 v[32:47], v[188:191], v[48:51], v[32:47]
	ds_read_b64_tr_b16 v[72:73], v231
	ds_read_b64_tr_b16 v[74:75], v231 offset:512
	ds_read_b64_tr_b16 v[76:77], v231 offset:2048
	ds_read_b64_tr_b16 v[78:79], v231 offset:2560
	ds_read_b64_tr_b16 v[220:221], v231 offset:1024
	ds_read_b64_tr_b16 v[222:223], v231 offset:1536
	ds_read_b64_tr_b16 v[224:225], v231 offset:3072
	ds_read_b64_tr_b16 v[226:227], v231 offset:3584
	s_waitcnt vmcnt(8)
	ds_write_b128 v247, v[116:119]
	ds_write_b128 v247, v[120:123] offset:1024
	ds_write_b128 v247, v[124:127] offset:2048
	ds_write_b128 v247, v[128:131] offset:3072
	ds_read_b128 v[116:119], v248
	ds_read_b128 v[120:123], v249
	ds_read_b128 v[124:127], v250
	ds_read_b128 v[128:131], v251
	ds_write_b128 v112, v[132:135]
	ds_write_b128 v112, v[136:139] offset:1024
	ds_write_b128 v112, v[140:143] offset:2048
	ds_write_b128 v112, v[144:147] offset:3072
	v_mfma_f32_32x32x16_bf16 v[32:47], v[192:195], v[52:55], v[32:47]
	v_mfma_f32_32x32x16_bf16 v[32:47], v[196:199], v[56:59], v[32:47]
	v_mfma_f32_32x32x16_bf16 v[32:47], v[200:203], v[60:63], v[32:47]
	s_nop 11
	v_exp_f32_e32 v32, v32
	v_exp_f32_e32 v33, v33
	v_exp_f32_e32 v34, v34
	v_exp_f32_e32 v35, v35
	v_exp_f32_e32 v36, v36
	v_exp_f32_e32 v37, v37
	v_exp_f32_e32 v38, v38
	v_exp_f32_e32 v39, v39
	v_exp_f32_e32 v40, v40
	v_exp_f32_e32 v41, v41
	v_exp_f32_e32 v42, v42
	v_exp_f32_e32 v43, v43
	v_exp_f32_e32 v44, v44
	v_exp_f32_e32 v45, v45
	v_exp_f32_e32 v46, v46
	v_exp_f32_e32 v47, v47
	v_cvt_pk_bf16_f32 v64, v32, v33
	v_cvt_pk_bf16_f32 v65, v34, v35
	v_cvt_pk_bf16_f32 v66, v36, v37
	v_cvt_pk_bf16_f32 v67, v38, v39
	v_cvt_pk_bf16_f32 v68, v40, v41
	v_cvt_pk_bf16_f32 v69, v42, v43
	v_cvt_pk_bf16_f32 v70, v44, v45
	v_cvt_pk_bf16_f32 v71, v46, v47
	v_pk_add_f32 v[232:233], v[232:233], v[32:33]
	v_pk_add_f32 v[232:233], v[232:233], v[34:35]
	v_pk_add_f32 v[232:233], v[232:233], v[36:37]
	v_pk_add_f32 v[232:233], v[232:233], v[38:39]
	v_pk_add_f32 v[232:233], v[232:233], v[40:41]
	v_pk_add_f32 v[232:233], v[232:233], v[42:43]
	v_pk_add_f32 v[232:233], v[232:233], v[44:45]
	v_pk_add_f32 v[232:233], v[232:233], v[46:47]
	ds_read2_b32 v[32:33], v115 offset0:128 offset1:129
	ds_read2_b32 v[34:35], v115 offset0:130 offset1:131
	ds_read2_b32 v[36:37], v115 offset0:136 offset1:137
	ds_read2_b32 v[38:39], v115 offset0:138 offset1:139
	ds_read2_b32 v[40:41], v115 offset0:144 offset1:145
	ds_read2_b32 v[42:43], v115 offset0:146 offset1:147
	ds_read2_b32 v[44:45], v115 offset0:152 offset1:153
	ds_read2_b32 v[46:47], v115 offset0:154 offset1:155
	s_waitcnt lgkmcnt(15)
	v_mfma_f32_32x32x16_bf16 v[0:15], v[64:67], v[72:75], v[0:15]
	v_mfma_f32_32x32x16_bf16 v[16:31], v[64:67], v[76:79], v[16:31]
	v_mfma_f32_32x32x16_bf16 v[0:15], v[68:71], v[220:223], v[0:15]
	v_mfma_f32_32x32x16_bf16 v[16:31], v[68:71], v[224:227], v[16:31]
	global_load_dwordx4 v[188:191], v239, s[86:87]
	global_load_dwordx4 v[192:195], v240, s[86:87]
	global_load_dwordx4 v[196:199], v241, s[86:87]
	global_load_dwordx4 v[200:203], v242, s[86:87]
	global_load_dwordx4 v[204:207], v101, s[86:87] offset:768
	global_load_dwordx4 v[208:211], v150, s[86:87] offset:768
	global_load_dwordx4 v[212:215], v101, s[86:87] offset:832
	global_load_dwordx4 v[216:219], v150, s[86:87] offset:832
	s_add_u32 s86, s86, 0xc0000
	s_addc_u32 s87, s87, 0
	s_waitcnt lgkmcnt(0)
	v_mfma_f32_32x32x16_bf16 v[32:47], v[116:119], v[48:51], v[32:47]
	ds_read_b64_tr_b16 v[72:73], v231
	ds_read_b64_tr_b16 v[74:75], v231 offset:512
	ds_read_b64_tr_b16 v[76:77], v231 offset:2048
	ds_read_b64_tr_b16 v[78:79], v231 offset:2560
	ds_read_b64_tr_b16 v[220:221], v231 offset:1024
	ds_read_b64_tr_b16 v[222:223], v231 offset:1536
	ds_read_b64_tr_b16 v[224:225], v231 offset:3072
	ds_read_b64_tr_b16 v[226:227], v231 offset:3584
	s_waitcnt vmcnt(8)
	ds_write_b128 v247, v[156:159]
	ds_write_b128 v247, v[160:163] offset:1024
	ds_write_b128 v247, v[164:167] offset:2048
	ds_write_b128 v247, v[168:171] offset:3072
	ds_read_b128 v[156:159], v248
	ds_read_b128 v[160:163], v249
	ds_read_b128 v[164:167], v250
	ds_read_b128 v[168:171], v251
	ds_write_b128 v112, v[172:175]
	ds_write_b128 v112, v[176:179] offset:1024
	ds_write_b128 v112, v[180:183] offset:2048
	ds_write_b128 v112, v[184:187] offset:3072
	v_mfma_f32_32x32x16_bf16 v[32:47], v[120:123], v[52:55], v[32:47]
	v_mfma_f32_32x32x16_bf16 v[32:47], v[124:127], v[56:59], v[32:47]
	v_mfma_f32_32x32x16_bf16 v[32:47], v[128:131], v[60:63], v[32:47]
	s_nop 11
	v_exp_f32_e32 v32, v32
	v_exp_f32_e32 v33, v33
	v_exp_f32_e32 v34, v34
	v_exp_f32_e32 v35, v35
	v_exp_f32_e32 v36, v36
	v_exp_f32_e32 v37, v37
	v_exp_f32_e32 v38, v38
	v_exp_f32_e32 v39, v39
	v_exp_f32_e32 v40, v40
	v_exp_f32_e32 v41, v41
	v_exp_f32_e32 v42, v42
	v_exp_f32_e32 v43, v43
	v_exp_f32_e32 v44, v44
	v_exp_f32_e32 v45, v45
	v_exp_f32_e32 v46, v46
	v_exp_f32_e32 v47, v47
	v_cvt_pk_bf16_f32 v64, v32, v33
	v_cvt_pk_bf16_f32 v65, v34, v35
	v_cvt_pk_bf16_f32 v66, v36, v37
	v_cvt_pk_bf16_f32 v67, v38, v39
	v_cvt_pk_bf16_f32 v68, v40, v41
	v_cvt_pk_bf16_f32 v69, v42, v43
	v_cvt_pk_bf16_f32 v70, v44, v45
	v_cvt_pk_bf16_f32 v71, v46, v47
	v_pk_add_f32 v[232:233], v[232:233], v[32:33]
	v_pk_add_f32 v[232:233], v[232:233], v[34:35]
	v_pk_add_f32 v[232:233], v[232:233], v[36:37]
	v_pk_add_f32 v[232:233], v[232:233], v[38:39]
	v_pk_add_f32 v[232:233], v[232:233], v[40:41]
	v_pk_add_f32 v[232:233], v[232:233], v[42:43]
	v_pk_add_f32 v[232:233], v[232:233], v[44:45]
	v_pk_add_f32 v[232:233], v[232:233], v[46:47]
	ds_read2_b32 v[32:33], v115 offset0:160 offset1:161
	ds_read2_b32 v[34:35], v115 offset0:162 offset1:163
	ds_read2_b32 v[36:37], v115 offset0:168 offset1:169
	ds_read2_b32 v[38:39], v115 offset0:170 offset1:171
	ds_read2_b32 v[40:41], v115 offset0:176 offset1:177
	ds_read2_b32 v[42:43], v115 offset0:178 offset1:179
	ds_read2_b32 v[44:45], v115 offset0:184 offset1:185
	ds_read2_b32 v[46:47], v115 offset0:186 offset1:187
	s_waitcnt lgkmcnt(15)
	v_mfma_f32_32x32x16_bf16 v[0:15], v[64:67], v[72:75], v[0:15]
	v_mfma_f32_32x32x16_bf16 v[16:31], v[64:67], v[76:79], v[16:31]
	v_mfma_f32_32x32x16_bf16 v[0:15], v[68:71], v[220:223], v[0:15]
	v_mfma_f32_32x32x16_bf16 v[16:31], v[68:71], v[224:227], v[16:31]
	global_load_dwordx4 v[116:119], v239, s[86:87]
	global_load_dwordx4 v[120:123], v240, s[86:87]
	global_load_dwordx4 v[124:127], v241, s[86:87]
	global_load_dwordx4 v[128:131], v242, s[86:87]
	global_load_dwordx4 v[132:135], v101, s[86:87] offset:768
	global_load_dwordx4 v[136:139], v150, s[86:87] offset:768
	global_load_dwordx4 v[140:143], v101, s[86:87] offset:832
	global_load_dwordx4 v[144:147], v150, s[86:87] offset:832
	s_waitcnt lgkmcnt(0)
	v_mfma_f32_32x32x16_bf16 v[32:47], v[156:159], v[48:51], v[32:47]
	ds_read_b64_tr_b16 v[72:73], v231
	ds_read_b64_tr_b16 v[74:75], v231 offset:512
	ds_read_b64_tr_b16 v[76:77], v231 offset:2048
	ds_read_b64_tr_b16 v[78:79], v231 offset:2560
	ds_read_b64_tr_b16 v[220:221], v231 offset:1024
	ds_read_b64_tr_b16 v[222:223], v231 offset:1536
	ds_read_b64_tr_b16 v[224:225], v231 offset:3072
	ds_read_b64_tr_b16 v[226:227], v231 offset:3584
	s_waitcnt vmcnt(8)
	ds_write_b128 v247, v[188:191]
	ds_write_b128 v247, v[192:195] offset:1024
	ds_write_b128 v247, v[196:199] offset:2048
	ds_write_b128 v247, v[200:203] offset:3072
	ds_read_b128 v[188:191], v248
	ds_read_b128 v[192:195], v249
	ds_read_b128 v[196:199], v250
	ds_read_b128 v[200:203], v251
	ds_write_b128 v112, v[204:207]
	ds_write_b128 v112, v[208:211] offset:1024
	ds_write_b128 v112, v[212:215] offset:2048
	ds_write_b128 v112, v[216:219] offset:3072
	v_mfma_f32_32x32x16_bf16 v[32:47], v[160:163], v[52:55], v[32:47]
	v_mfma_f32_32x32x16_bf16 v[32:47], v[164:167], v[56:59], v[32:47]
	v_mfma_f32_32x32x16_bf16 v[32:47], v[168:171], v[60:63], v[32:47]
	s_nop 11
	v_exp_f32_e32 v32, v32
	v_exp_f32_e32 v33, v33
	v_exp_f32_e32 v34, v34
	v_exp_f32_e32 v35, v35
	v_exp_f32_e32 v36, v36
	v_exp_f32_e32 v37, v37
	v_exp_f32_e32 v38, v38
	v_exp_f32_e32 v39, v39
	v_exp_f32_e32 v40, v40
	v_exp_f32_e32 v41, v41
	v_exp_f32_e32 v42, v42
	v_exp_f32_e32 v43, v43
	v_exp_f32_e32 v44, v44
	v_exp_f32_e32 v45, v45
	v_exp_f32_e32 v46, v46
	v_exp_f32_e32 v47, v47
	v_cvt_pk_bf16_f32 v64, v32, v33
	v_cvt_pk_bf16_f32 v65, v34, v35
	v_cvt_pk_bf16_f32 v66, v36, v37
	v_cvt_pk_bf16_f32 v67, v38, v39
	v_cvt_pk_bf16_f32 v68, v40, v41
	v_cvt_pk_bf16_f32 v69, v42, v43
	v_cvt_pk_bf16_f32 v70, v44, v45
	v_cvt_pk_bf16_f32 v71, v46, v47
	v_pk_add_f32 v[232:233], v[232:233], v[32:33]
	v_pk_add_f32 v[232:233], v[232:233], v[34:35]
	v_pk_add_f32 v[232:233], v[232:233], v[36:37]
	v_pk_add_f32 v[232:233], v[232:233], v[38:39]
	v_pk_add_f32 v[232:233], v[232:233], v[40:41]
	v_pk_add_f32 v[232:233], v[232:233], v[42:43]
	v_pk_add_f32 v[232:233], v[232:233], v[44:45]
	v_pk_add_f32 v[232:233], v[232:233], v[46:47]
	ds_read2_b32 v[32:33], v115 offset0:192 offset1:193
	ds_read2_b32 v[34:35], v115 offset0:194 offset1:195
	ds_read2_b32 v[36:37], v115 offset0:200 offset1:201
	ds_read2_b32 v[38:39], v115 offset0:202 offset1:203
	ds_read2_b32 v[40:41], v115 offset0:208 offset1:209
	ds_read2_b32 v[42:43], v115 offset0:210 offset1:211
	ds_read2_b32 v[44:45], v115 offset0:216 offset1:217
	ds_read2_b32 v[46:47], v115 offset0:218 offset1:219
	s_waitcnt lgkmcnt(15)
	v_mfma_f32_32x32x16_bf16 v[0:15], v[64:67], v[72:75], v[0:15]
	v_mfma_f32_32x32x16_bf16 v[16:31], v[64:67], v[76:79], v[16:31]
	v_mfma_f32_32x32x16_bf16 v[0:15], v[68:71], v[220:223], v[0:15]
	v_mfma_f32_32x32x16_bf16 v[16:31], v[68:71], v[224:227], v[16:31]
	global_load_dwordx4 v[156:159], v243, s[88:89]
	global_load_dwordx4 v[160:163], v244, s[88:89]
	global_load_dwordx4 v[164:167], v245, s[88:89]
	global_load_dwordx4 v[168:171], v246, s[88:89]
	global_load_dwordx4 v[172:175], v148, s[88:89] offset:768
	global_load_dwordx4 v[176:179], v151, s[88:89] offset:768
	global_load_dwordx4 v[180:183], v148, s[88:89] offset:832
	global_load_dwordx4 v[184:187], v151, s[88:89] offset:832
	s_add_u32 s88, s88, 0x300000
	s_addc_u32 s89, s89, 0
	s_waitcnt lgkmcnt(0)
	v_mfma_f32_32x32x16_bf16 v[32:47], v[188:191], v[48:51], v[32:47]
	ds_read_b64_tr_b16 v[72:73], v231
	ds_read_b64_tr_b16 v[74:75], v231 offset:512
	ds_read_b64_tr_b16 v[76:77], v231 offset:2048
	ds_read_b64_tr_b16 v[78:79], v231 offset:2560
	ds_read_b64_tr_b16 v[220:221], v231 offset:1024
	ds_read_b64_tr_b16 v[222:223], v231 offset:1536
	ds_read_b64_tr_b16 v[224:225], v231 offset:3072
	ds_read_b64_tr_b16 v[226:227], v231 offset:3584
	s_waitcnt vmcnt(8)
	ds_write_b128 v247, v[116:119]
	ds_write_b128 v247, v[120:123] offset:1024
	ds_write_b128 v247, v[124:127] offset:2048
	ds_write_b128 v247, v[128:131] offset:3072
	ds_read_b128 v[116:119], v248
	ds_read_b128 v[120:123], v249
	ds_read_b128 v[124:127], v250
	ds_read_b128 v[128:131], v251
	ds_write_b128 v112, v[132:135]
	ds_write_b128 v112, v[136:139] offset:1024
	ds_write_b128 v112, v[140:143] offset:2048
	ds_write_b128 v112, v[144:147] offset:3072
	v_mfma_f32_32x32x16_bf16 v[32:47], v[192:195], v[52:55], v[32:47]
	v_mfma_f32_32x32x16_bf16 v[32:47], v[196:199], v[56:59], v[32:47]
	v_mfma_f32_32x32x16_bf16 v[32:47], v[200:203], v[60:63], v[32:47]
	s_nop 11
	v_exp_f32_e32 v32, v32
	v_exp_f32_e32 v33, v33
	v_exp_f32_e32 v34, v34
	v_exp_f32_e32 v35, v35
	v_exp_f32_e32 v36, v36
	v_exp_f32_e32 v37, v37
	v_exp_f32_e32 v38, v38
	v_exp_f32_e32 v39, v39
	v_exp_f32_e32 v40, v40
	v_exp_f32_e32 v41, v41
	v_exp_f32_e32 v42, v42
	v_exp_f32_e32 v43, v43
	v_exp_f32_e32 v44, v44
	v_exp_f32_e32 v45, v45
	v_exp_f32_e32 v46, v46
	v_exp_f32_e32 v47, v47
	v_cvt_pk_bf16_f32 v64, v32, v33
	v_cvt_pk_bf16_f32 v65, v34, v35
	v_cvt_pk_bf16_f32 v66, v36, v37
	v_cvt_pk_bf16_f32 v67, v38, v39
	v_cvt_pk_bf16_f32 v68, v40, v41
	v_cvt_pk_bf16_f32 v69, v42, v43
	v_cvt_pk_bf16_f32 v70, v44, v45
	v_cvt_pk_bf16_f32 v71, v46, v47
	v_pk_add_f32 v[232:233], v[232:233], v[32:33]
	v_pk_add_f32 v[232:233], v[232:233], v[34:35]
	v_pk_add_f32 v[232:233], v[232:233], v[36:37]
	v_pk_add_f32 v[232:233], v[232:233], v[38:39]
	v_pk_add_f32 v[232:233], v[232:233], v[40:41]
	v_pk_add_f32 v[232:233], v[232:233], v[42:43]
	v_pk_add_f32 v[232:233], v[232:233], v[44:45]
	v_pk_add_f32 v[232:233], v[232:233], v[46:47]
	ds_read2_b32 v[32:33], v115 offset0:224 offset1:225
	ds_read2_b32 v[34:35], v115 offset0:226 offset1:227
	ds_read2_b32 v[36:37], v115 offset0:232 offset1:233
	ds_read2_b32 v[38:39], v115 offset0:234 offset1:235
	ds_read2_b32 v[40:41], v115 offset0:240 offset1:241
	ds_read2_b32 v[42:43], v115 offset0:242 offset1:243
	ds_read2_b32 v[44:45], v115 offset0:248 offset1:249
	ds_read2_b32 v[46:47], v115 offset0:250 offset1:251
	s_waitcnt lgkmcnt(15)
	v_mfma_f32_32x32x16_bf16 v[0:15], v[64:67], v[72:75], v[0:15]
	v_mfma_f32_32x32x16_bf16 v[16:31], v[64:67], v[76:79], v[16:31]
	v_mfma_f32_32x32x16_bf16 v[0:15], v[68:71], v[220:223], v[0:15]
	v_mfma_f32_32x32x16_bf16 v[16:31], v[68:71], v[224:227], v[16:31]
	global_load_dwordx4 v[188:191], v243, s[88:89]
	global_load_dwordx4 v[192:195], v244, s[88:89]
	global_load_dwordx4 v[196:199], v245, s[88:89]
	global_load_dwordx4 v[200:203], v246, s[88:89]
	global_load_dwordx4 v[204:207], v148, s[88:89] offset:768
	global_load_dwordx4 v[208:211], v151, s[88:89] offset:768
	global_load_dwordx4 v[212:215], v148, s[88:89] offset:832
	global_load_dwordx4 v[216:219], v151, s[88:89] offset:832
	s_add_u32 s88, s88, 0x300000
	s_addc_u32 s89, s89, 0
	s_waitcnt lgkmcnt(0)
	v_mfma_f32_32x32x16_bf16 v[32:47], v[116:119], v[48:51], v[32:47]
	ds_read_b64_tr_b16 v[72:73], v231
	ds_read_b64_tr_b16 v[74:75], v231 offset:512
	ds_read_b64_tr_b16 v[76:77], v231 offset:2048
	ds_read_b64_tr_b16 v[78:79], v231 offset:2560
	ds_read_b64_tr_b16 v[220:221], v231 offset:1024
	ds_read_b64_tr_b16 v[222:223], v231 offset:1536
	ds_read_b64_tr_b16 v[224:225], v231 offset:3072
	ds_read_b64_tr_b16 v[226:227], v231 offset:3584
	s_waitcnt vmcnt(8)
	ds_write_b128 v247, v[156:159]
	ds_write_b128 v247, v[160:163] offset:1024
	ds_write_b128 v247, v[164:167] offset:2048
	ds_write_b128 v247, v[168:171] offset:3072
	ds_read_b128 v[156:159], v248
	ds_read_b128 v[160:163], v249
	ds_read_b128 v[164:167], v250
	ds_read_b128 v[168:171], v251
	ds_write_b128 v112, v[172:175]
	ds_write_b128 v112, v[176:179] offset:1024
	ds_write_b128 v112, v[180:183] offset:2048
	ds_write_b128 v112, v[184:187] offset:3072
	v_mfma_f32_32x32x16_bf16 v[32:47], v[120:123], v[52:55], v[32:47]
	v_mfma_f32_32x32x16_bf16 v[32:47], v[124:127], v[56:59], v[32:47]
	v_mfma_f32_32x32x16_bf16 v[32:47], v[128:131], v[60:63], v[32:47]
	s_nop 11
	v_exp_f32_e32 v32, v32
	v_exp_f32_e32 v33, v33
	v_exp_f32_e32 v34, v34
	v_exp_f32_e32 v35, v35
	v_exp_f32_e32 v36, v36
	v_exp_f32_e32 v37, v37
	v_exp_f32_e32 v38, v38
	v_exp_f32_e32 v39, v39
	v_exp_f32_e32 v40, v40
	v_exp_f32_e32 v41, v41
	v_exp_f32_e32 v42, v42
	v_exp_f32_e32 v43, v43
	v_exp_f32_e32 v44, v44
	v_exp_f32_e32 v45, v45
	v_exp_f32_e32 v46, v46
	v_exp_f32_e32 v47, v47
	v_cvt_pk_bf16_f32 v64, v32, v33
	v_cvt_pk_bf16_f32 v65, v34, v35
	v_cvt_pk_bf16_f32 v66, v36, v37
	v_cvt_pk_bf16_f32 v67, v38, v39
	v_cvt_pk_bf16_f32 v68, v40, v41
	v_cvt_pk_bf16_f32 v69, v42, v43
	v_cvt_pk_bf16_f32 v70, v44, v45
	v_cvt_pk_bf16_f32 v71, v46, v47
	v_pk_add_f32 v[232:233], v[232:233], v[32:33]
	v_pk_add_f32 v[232:233], v[232:233], v[34:35]
	v_pk_add_f32 v[232:233], v[232:233], v[36:37]
	v_pk_add_f32 v[232:233], v[232:233], v[38:39]
	v_pk_add_f32 v[232:233], v[232:233], v[40:41]
	v_pk_add_f32 v[232:233], v[232:233], v[42:43]
	v_pk_add_f32 v[232:233], v[232:233], v[44:45]
	v_pk_add_f32 v[232:233], v[232:233], v[46:47]
	v_mov_b32_e32 v115, v230
	ds_read2_b32 v[32:33], v115 offset0:0 offset1:1
	ds_read2_b32 v[34:35], v115 offset0:2 offset1:3
	ds_read2_b32 v[36:37], v115 offset0:8 offset1:9
	ds_read2_b32 v[38:39], v115 offset0:10 offset1:11
	ds_read2_b32 v[40:41], v115 offset0:16 offset1:17
	ds_read2_b32 v[42:43], v115 offset0:18 offset1:19
	ds_read2_b32 v[44:45], v115 offset0:24 offset1:25
	ds_read2_b32 v[46:47], v115 offset0:26 offset1:27
	s_waitcnt lgkmcnt(15)
	v_mfma_f32_32x32x16_bf16 v[0:15], v[64:67], v[72:75], v[0:15]
	v_mfma_f32_32x32x16_bf16 v[16:31], v[64:67], v[76:79], v[16:31]
	v_mfma_f32_32x32x16_bf16 v[0:15], v[68:71], v[220:223], v[0:15]
	v_mfma_f32_32x32x16_bf16 v[16:31], v[68:71], v[224:227], v[16:31]
	global_load_dwordx4 v[116:119], v243, s[88:89]
	global_load_dwordx4 v[120:123], v244, s[88:89]
	global_load_dwordx4 v[124:127], v245, s[88:89]
	global_load_dwordx4 v[128:131], v246, s[88:89]
	global_load_dwordx4 v[132:135], v148, s[88:89] offset:768
	global_load_dwordx4 v[136:139], v151, s[88:89] offset:768
	global_load_dwordx4 v[140:143], v148, s[88:89] offset:832
	global_load_dwordx4 v[144:147], v151, s[88:89] offset:832
	s_add_u32 s88, s88, 0x300000
	s_addc_u32 s89, s89, 0
	s_waitcnt lgkmcnt(0)
	v_mfma_f32_32x32x16_bf16 v[32:47], v[156:159], v[48:51], v[32:47]
	ds_read_b64_tr_b16 v[72:73], v231
	ds_read_b64_tr_b16 v[74:75], v231 offset:512
	ds_read_b64_tr_b16 v[76:77], v231 offset:2048
	ds_read_b64_tr_b16 v[78:79], v231 offset:2560
	ds_read_b64_tr_b16 v[220:221], v231 offset:1024
	ds_read_b64_tr_b16 v[222:223], v231 offset:1536
	ds_read_b64_tr_b16 v[224:225], v231 offset:3072
	ds_read_b64_tr_b16 v[226:227], v231 offset:3584
	s_waitcnt vmcnt(8)
	ds_write_b128 v247, v[188:191]
	ds_write_b128 v247, v[192:195] offset:1024
	ds_write_b128 v247, v[196:199] offset:2048
	ds_write_b128 v247, v[200:203] offset:3072
	ds_read_b128 v[188:191], v248
	ds_read_b128 v[192:195], v249
	ds_read_b128 v[196:199], v250
	ds_read_b128 v[200:203], v251
	ds_write_b128 v112, v[204:207]
	ds_write_b128 v112, v[208:211] offset:1024
	ds_write_b128 v112, v[212:215] offset:2048
	ds_write_b128 v112, v[216:219] offset:3072
	v_mfma_f32_32x32x16_bf16 v[32:47], v[160:163], v[52:55], v[32:47]
	v_mfma_f32_32x32x16_bf16 v[32:47], v[164:167], v[56:59], v[32:47]
	v_mfma_f32_32x32x16_bf16 v[32:47], v[168:171], v[60:63], v[32:47]
	s_nop 11
	v_exp_f32_e32 v32, v32
	v_exp_f32_e32 v33, v33
	v_exp_f32_e32 v34, v34
	v_exp_f32_e32 v35, v35
	v_exp_f32_e32 v36, v36
	v_exp_f32_e32 v37, v37
	v_exp_f32_e32 v38, v38
	v_exp_f32_e32 v39, v39
	v_exp_f32_e32 v40, v40
	v_exp_f32_e32 v41, v41
	v_exp_f32_e32 v42, v42
	v_exp_f32_e32 v43, v43
	v_exp_f32_e32 v44, v44
	v_exp_f32_e32 v45, v45
	v_exp_f32_e32 v46, v46
	v_exp_f32_e32 v47, v47
	v_cvt_pk_bf16_f32 v64, v32, v33
	v_cvt_pk_bf16_f32 v65, v34, v35
	v_cvt_pk_bf16_f32 v66, v36, v37
	v_cvt_pk_bf16_f32 v67, v38, v39
	v_cvt_pk_bf16_f32 v68, v40, v41
	v_cvt_pk_bf16_f32 v69, v42, v43
	v_cvt_pk_bf16_f32 v70, v44, v45
	v_cvt_pk_bf16_f32 v71, v46, v47
	v_pk_add_f32 v[232:233], v[232:233], v[32:33]
	v_pk_add_f32 v[232:233], v[232:233], v[34:35]
	v_pk_add_f32 v[232:233], v[232:233], v[36:37]
	v_pk_add_f32 v[232:233], v[232:233], v[38:39]
	v_pk_add_f32 v[232:233], v[232:233], v[40:41]
	v_pk_add_f32 v[232:233], v[232:233], v[42:43]
	v_pk_add_f32 v[232:233], v[232:233], v[44:45]
	v_pk_add_f32 v[232:233], v[232:233], v[46:47]
	ds_read2_b32 v[32:33], v115 offset0:32 offset1:33
	ds_read2_b32 v[34:35], v115 offset0:34 offset1:35
	ds_read2_b32 v[36:37], v115 offset0:40 offset1:41
	ds_read2_b32 v[38:39], v115 offset0:42 offset1:43
	ds_read2_b32 v[40:41], v115 offset0:48 offset1:49
	ds_read2_b32 v[42:43], v115 offset0:50 offset1:51
	ds_read2_b32 v[44:45], v115 offset0:56 offset1:57
	ds_read2_b32 v[46:47], v115 offset0:58 offset1:59
	s_waitcnt lgkmcnt(15)
	v_mfma_f32_32x32x16_bf16 v[0:15], v[64:67], v[72:75], v[0:15]
	v_mfma_f32_32x32x16_bf16 v[16:31], v[64:67], v[76:79], v[16:31]
	v_mfma_f32_32x32x16_bf16 v[0:15], v[68:71], v[220:223], v[0:15]
	v_mfma_f32_32x32x16_bf16 v[16:31], v[68:71], v[224:227], v[16:31]
	global_load_dwordx4 v[156:159], v243, s[88:89]
	global_load_dwordx4 v[160:163], v244, s[88:89]
	global_load_dwordx4 v[164:167], v245, s[88:89]
	global_load_dwordx4 v[168:171], v246, s[88:89]
	global_load_dwordx4 v[172:175], v148, s[88:89] offset:768
	global_load_dwordx4 v[176:179], v151, s[88:89] offset:768
	global_load_dwordx4 v[180:183], v148, s[88:89] offset:832
	global_load_dwordx4 v[184:187], v151, s[88:89] offset:832
	s_add_u32 s88, s88, 0x300000
	s_addc_u32 s89, s89, 0
	s_waitcnt lgkmcnt(0)
	v_mfma_f32_32x32x16_bf16 v[32:47], v[188:191], v[48:51], v[32:47]
	ds_read_b64_tr_b16 v[72:73], v231
	ds_read_b64_tr_b16 v[74:75], v231 offset:512
	ds_read_b64_tr_b16 v[76:77], v231 offset:2048
	ds_read_b64_tr_b16 v[78:79], v231 offset:2560
	ds_read_b64_tr_b16 v[220:221], v231 offset:1024
	ds_read_b64_tr_b16 v[222:223], v231 offset:1536
	ds_read_b64_tr_b16 v[224:225], v231 offset:3072
	ds_read_b64_tr_b16 v[226:227], v231 offset:3584
	s_waitcnt vmcnt(8)
	ds_write_b128 v247, v[116:119]
	ds_write_b128 v247, v[120:123] offset:1024
	ds_write_b128 v247, v[124:127] offset:2048
	ds_write_b128 v247, v[128:131] offset:3072
	ds_read_b128 v[116:119], v248
	ds_read_b128 v[120:123], v249
	ds_read_b128 v[124:127], v250
	ds_read_b128 v[128:131], v251
	ds_write_b128 v112, v[132:135]
	ds_write_b128 v112, v[136:139] offset:1024
	ds_write_b128 v112, v[140:143] offset:2048
	ds_write_b128 v112, v[144:147] offset:3072
	v_mfma_f32_32x32x16_bf16 v[32:47], v[192:195], v[52:55], v[32:47]
	v_mfma_f32_32x32x16_bf16 v[32:47], v[196:199], v[56:59], v[32:47]
	v_mfma_f32_32x32x16_bf16 v[32:47], v[200:203], v[60:63], v[32:47]
	s_nop 11
	v_exp_f32_e32 v32, v32
	v_exp_f32_e32 v33, v33
	v_exp_f32_e32 v34, v34
	v_exp_f32_e32 v35, v35
	v_exp_f32_e32 v36, v36
	v_exp_f32_e32 v37, v37
	v_exp_f32_e32 v38, v38
	v_exp_f32_e32 v39, v39
	v_exp_f32_e32 v40, v40
	v_exp_f32_e32 v41, v41
	v_exp_f32_e32 v42, v42
	v_exp_f32_e32 v43, v43
	v_exp_f32_e32 v44, v44
	v_exp_f32_e32 v45, v45
	v_exp_f32_e32 v46, v46
	v_exp_f32_e32 v47, v47
	v_cvt_pk_bf16_f32 v64, v32, v33
	v_cvt_pk_bf16_f32 v65, v34, v35
	v_cvt_pk_bf16_f32 v66, v36, v37
	v_cvt_pk_bf16_f32 v67, v38, v39
	v_cvt_pk_bf16_f32 v68, v40, v41
	v_cvt_pk_bf16_f32 v69, v42, v43
	v_cvt_pk_bf16_f32 v70, v44, v45
	v_cvt_pk_bf16_f32 v71, v46, v47
	v_pk_add_f32 v[232:233], v[232:233], v[32:33]
	v_pk_add_f32 v[232:233], v[232:233], v[34:35]
	v_pk_add_f32 v[232:233], v[232:233], v[36:37]
	v_pk_add_f32 v[232:233], v[232:233], v[38:39]
	v_pk_add_f32 v[232:233], v[232:233], v[40:41]
	v_pk_add_f32 v[232:233], v[232:233], v[42:43]
	v_pk_add_f32 v[232:233], v[232:233], v[44:45]
	v_pk_add_f32 v[232:233], v[232:233], v[46:47]
	ds_read2_b32 v[32:33], v115 offset0:64 offset1:65
	ds_read2_b32 v[34:35], v115 offset0:66 offset1:67
	ds_read2_b32 v[36:37], v115 offset0:72 offset1:73
	ds_read2_b32 v[38:39], v115 offset0:74 offset1:75
	ds_read2_b32 v[40:41], v115 offset0:80 offset1:81
	ds_read2_b32 v[42:43], v115 offset0:82 offset1:83
	ds_read2_b32 v[44:45], v115 offset0:88 offset1:89
	ds_read2_b32 v[46:47], v115 offset0:90 offset1:91
	s_waitcnt lgkmcnt(15)
	v_mfma_f32_32x32x16_bf16 v[0:15], v[64:67], v[72:75], v[0:15]
	v_mfma_f32_32x32x16_bf16 v[16:31], v[64:67], v[76:79], v[16:31]
	v_mfma_f32_32x32x16_bf16 v[0:15], v[68:71], v[220:223], v[0:15]
	v_mfma_f32_32x32x16_bf16 v[16:31], v[68:71], v[224:227], v[16:31]
	global_load_dwordx4 v[188:191], v243, s[88:89]
	global_load_dwordx4 v[192:195], v244, s[88:89]
	global_load_dwordx4 v[196:199], v245, s[88:89]
	global_load_dwordx4 v[200:203], v246, s[88:89]
	global_load_dwordx4 v[204:207], v148, s[88:89] offset:768
	global_load_dwordx4 v[208:211], v151, s[88:89] offset:768
	global_load_dwordx4 v[212:215], v148, s[88:89] offset:832
	global_load_dwordx4 v[216:219], v151, s[88:89] offset:832
	s_waitcnt lgkmcnt(0)
	v_mfma_f32_32x32x16_bf16 v[32:47], v[116:119], v[48:51], v[32:47]
	ds_read_b64_tr_b16 v[72:73], v231
	ds_read_b64_tr_b16 v[74:75], v231 offset:512
	ds_read_b64_tr_b16 v[76:77], v231 offset:2048
	ds_read_b64_tr_b16 v[78:79], v231 offset:2560
	ds_read_b64_tr_b16 v[220:221], v231 offset:1024
	ds_read_b64_tr_b16 v[222:223], v231 offset:1536
	ds_read_b64_tr_b16 v[224:225], v231 offset:3072
	ds_read_b64_tr_b16 v[226:227], v231 offset:3584
	s_waitcnt vmcnt(8)
	ds_write_b128 v247, v[156:159]
	ds_write_b128 v247, v[160:163] offset:1024
	ds_write_b128 v247, v[164:167] offset:2048
	ds_write_b128 v247, v[168:171] offset:3072
	ds_read_b128 v[156:159], v248
	ds_read_b128 v[160:163], v249
	ds_read_b128 v[164:167], v250
	ds_read_b128 v[168:171], v251
	ds_write_b128 v112, v[172:175]
	ds_write_b128 v112, v[176:179] offset:1024
	ds_write_b128 v112, v[180:183] offset:2048
	ds_write_b128 v112, v[184:187] offset:3072
	v_mfma_f32_32x32x16_bf16 v[32:47], v[120:123], v[52:55], v[32:47]
	v_mfma_f32_32x32x16_bf16 v[32:47], v[124:127], v[56:59], v[32:47]
	v_mfma_f32_32x32x16_bf16 v[32:47], v[128:131], v[60:63], v[32:47]
	s_nop 11
	v_exp_f32_e32 v32, v32
	v_exp_f32_e32 v33, v33
	v_exp_f32_e32 v34, v34
	v_exp_f32_e32 v35, v35
	v_exp_f32_e32 v36, v36
	v_exp_f32_e32 v37, v37
	v_exp_f32_e32 v38, v38
	v_exp_f32_e32 v39, v39
	v_exp_f32_e32 v40, v40
	v_exp_f32_e32 v41, v41
	v_exp_f32_e32 v42, v42
	v_exp_f32_e32 v43, v43
	v_exp_f32_e32 v44, v44
	v_exp_f32_e32 v45, v45
	v_exp_f32_e32 v46, v46
	v_exp_f32_e32 v47, v47
	v_cvt_pk_bf16_f32 v64, v32, v33
	v_cvt_pk_bf16_f32 v65, v34, v35
	v_cvt_pk_bf16_f32 v66, v36, v37
	v_cvt_pk_bf16_f32 v67, v38, v39
	v_cvt_pk_bf16_f32 v68, v40, v41
	v_cvt_pk_bf16_f32 v69, v42, v43
	v_cvt_pk_bf16_f32 v70, v44, v45
	v_cvt_pk_bf16_f32 v71, v46, v47
	v_pk_add_f32 v[232:233], v[232:233], v[32:33]
	v_pk_add_f32 v[232:233], v[232:233], v[34:35]
	v_pk_add_f32 v[232:233], v[232:233], v[36:37]
	v_pk_add_f32 v[232:233], v[232:233], v[38:39]
	v_pk_add_f32 v[232:233], v[232:233], v[40:41]
	v_pk_add_f32 v[232:233], v[232:233], v[42:43]
	v_pk_add_f32 v[232:233], v[232:233], v[44:45]
	v_pk_add_f32 v[232:233], v[232:233], v[46:47]
	ds_read2_b32 v[32:33], v115 offset0:96 offset1:97
	ds_read2_b32 v[34:35], v115 offset0:98 offset1:99
	ds_read2_b32 v[36:37], v115 offset0:104 offset1:105
	ds_read2_b32 v[38:39], v115 offset0:106 offset1:107
	ds_read2_b32 v[40:41], v115 offset0:112 offset1:113
	ds_read2_b32 v[42:43], v115 offset0:114 offset1:115
	ds_read2_b32 v[44:45], v115 offset0:120 offset1:121
	ds_read2_b32 v[46:47], v115 offset0:122 offset1:123
	s_waitcnt lgkmcnt(15)
	v_mfma_f32_32x32x16_bf16 v[0:15], v[64:67], v[72:75], v[0:15]
	v_mfma_f32_32x32x16_bf16 v[16:31], v[64:67], v[76:79], v[16:31]
	v_mfma_f32_32x32x16_bf16 v[0:15], v[68:71], v[220:223], v[0:15]
	v_mfma_f32_32x32x16_bf16 v[16:31], v[68:71], v[224:227], v[16:31]
	s_waitcnt lgkmcnt(0)
	v_mfma_f32_32x32x16_bf16 v[32:47], v[156:159], v[48:51], v[32:47]
	ds_read_b64_tr_b16 v[72:73], v231
	ds_read_b64_tr_b16 v[74:75], v231 offset:512
	ds_read_b64_tr_b16 v[76:77], v231 offset:2048
	ds_read_b64_tr_b16 v[78:79], v231 offset:2560
	ds_read_b64_tr_b16 v[220:221], v231 offset:1024
	ds_read_b64_tr_b16 v[222:223], v231 offset:1536
	ds_read_b64_tr_b16 v[224:225], v231 offset:3072
	ds_read_b64_tr_b16 v[226:227], v231 offset:3584
	s_waitcnt vmcnt(0)
	ds_write_b128 v247, v[188:191]
	ds_write_b128 v247, v[192:195] offset:1024
	ds_write_b128 v247, v[196:199] offset:2048
	ds_write_b128 v247, v[200:203] offset:3072
	ds_read_b128 v[188:191], v248
	ds_read_b128 v[192:195], v249
	ds_read_b128 v[196:199], v250
	ds_read_b128 v[200:203], v251
	ds_write_b128 v112, v[204:207]
	ds_write_b128 v112, v[208:211] offset:1024
	ds_write_b128 v112, v[212:215] offset:2048
	ds_write_b128 v112, v[216:219] offset:3072
	v_mfma_f32_32x32x16_bf16 v[32:47], v[160:163], v[52:55], v[32:47]
	v_mfma_f32_32x32x16_bf16 v[32:47], v[164:167], v[56:59], v[32:47]
	v_mfma_f32_32x32x16_bf16 v[32:47], v[168:171], v[60:63], v[32:47]
	s_nop 11
	v_exp_f32_e32 v32, v32
	v_exp_f32_e32 v33, v33
	v_exp_f32_e32 v34, v34
	v_exp_f32_e32 v35, v35
	v_exp_f32_e32 v36, v36
	v_exp_f32_e32 v37, v37
	v_exp_f32_e32 v38, v38
	v_exp_f32_e32 v39, v39
	v_exp_f32_e32 v40, v40
	v_exp_f32_e32 v41, v41
	v_exp_f32_e32 v42, v42
	v_exp_f32_e32 v43, v43
	v_exp_f32_e32 v44, v44
	v_exp_f32_e32 v45, v45
	v_exp_f32_e32 v46, v46
	v_exp_f32_e32 v47, v47
	v_cvt_pk_bf16_f32 v64, v32, v33
	v_cvt_pk_bf16_f32 v65, v34, v35
	v_cvt_pk_bf16_f32 v66, v36, v37
	v_cvt_pk_bf16_f32 v67, v38, v39
	v_cvt_pk_bf16_f32 v68, v40, v41
	v_cvt_pk_bf16_f32 v69, v42, v43
	v_cvt_pk_bf16_f32 v70, v44, v45
	v_cvt_pk_bf16_f32 v71, v46, v47
	v_pk_add_f32 v[232:233], v[232:233], v[32:33]
	v_pk_add_f32 v[232:233], v[232:233], v[34:35]
	v_pk_add_f32 v[232:233], v[232:233], v[36:37]
	v_pk_add_f32 v[232:233], v[232:233], v[38:39]
	v_pk_add_f32 v[232:233], v[232:233], v[40:41]
	v_pk_add_f32 v[232:233], v[232:233], v[42:43]
	v_pk_add_f32 v[232:233], v[232:233], v[44:45]
	v_pk_add_f32 v[232:233], v[232:233], v[46:47]
	ds_read2_b32 v[32:33], v115 offset0:128 offset1:129
	ds_read2_b32 v[34:35], v115 offset0:130 offset1:131
	ds_read2_b32 v[36:37], v115 offset0:136 offset1:137
	ds_read2_b32 v[38:39], v115 offset0:138 offset1:139
	ds_read2_b32 v[40:41], v115 offset0:144 offset1:145
	ds_read2_b32 v[42:43], v115 offset0:146 offset1:147
	ds_read2_b32 v[44:45], v115 offset0:152 offset1:153
	ds_read2_b32 v[46:47], v115 offset0:154 offset1:155
	s_waitcnt lgkmcnt(15)
	v_mfma_f32_32x32x16_bf16 v[0:15], v[64:67], v[72:75], v[0:15]
	v_mfma_f32_32x32x16_bf16 v[16:31], v[64:67], v[76:79], v[16:31]
	v_mfma_f32_32x32x16_bf16 v[0:15], v[68:71], v[220:223], v[0:15]
	v_mfma_f32_32x32x16_bf16 v[16:31], v[68:71], v[224:227], v[16:31]
	s_waitcnt lgkmcnt(0)
	v_mfma_f32_32x32x16_bf16 v[32:47], v[188:191], v[48:51], v[32:47]
	ds_read_b64_tr_b16 v[72:73], v231
	ds_read_b64_tr_b16 v[74:75], v231 offset:512
	ds_read_b64_tr_b16 v[76:77], v231 offset:2048
	ds_read_b64_tr_b16 v[78:79], v231 offset:2560
	ds_read_b64_tr_b16 v[220:221], v231 offset:1024
	ds_read_b64_tr_b16 v[222:223], v231 offset:1536
	ds_read_b64_tr_b16 v[224:225], v231 offset:3072
	ds_read_b64_tr_b16 v[226:227], v231 offset:3584
	v_mfma_f32_32x32x16_bf16 v[32:47], v[192:195], v[52:55], v[32:47]
	v_mfma_f32_32x32x16_bf16 v[32:47], v[196:199], v[56:59], v[32:47]
	v_mfma_f32_32x32x16_bf16 v[32:47], v[200:203], v[60:63], v[32:47]
	s_nop 11
	v_exp_f32_e32 v32, v32
	v_exp_f32_e32 v33, v33
	v_exp_f32_e32 v34, v34
	v_exp_f32_e32 v35, v35
	v_exp_f32_e32 v36, v36
	v_exp_f32_e32 v37, v37
	v_exp_f32_e32 v38, v38
	v_exp_f32_e32 v39, v39
	v_exp_f32_e32 v40, v40
	v_exp_f32_e32 v41, v41
	v_exp_f32_e32 v42, v42
	v_exp_f32_e32 v43, v43
	v_exp_f32_e32 v44, v44
	v_exp_f32_e32 v45, v45
	v_exp_f32_e32 v46, v46
	v_exp_f32_e32 v47, v47
	v_cvt_pk_bf16_f32 v64, v32, v33
	v_cvt_pk_bf16_f32 v65, v34, v35
	v_cvt_pk_bf16_f32 v66, v36, v37
	v_cvt_pk_bf16_f32 v67, v38, v39
	v_cvt_pk_bf16_f32 v68, v40, v41
	v_cvt_pk_bf16_f32 v69, v42, v43
	v_cvt_pk_bf16_f32 v70, v44, v45
	v_cvt_pk_bf16_f32 v71, v46, v47
	v_pk_add_f32 v[232:233], v[232:233], v[32:33]
	v_pk_add_f32 v[232:233], v[232:233], v[34:35]
	v_pk_add_f32 v[232:233], v[232:233], v[36:37]
	v_pk_add_f32 v[232:233], v[232:233], v[38:39]
	v_pk_add_f32 v[232:233], v[232:233], v[40:41]
	v_pk_add_f32 v[232:233], v[232:233], v[42:43]
	v_pk_add_f32 v[232:233], v[232:233], v[44:45]
	v_pk_add_f32 v[232:233], v[232:233], v[46:47]
	s_waitcnt lgkmcnt(0)
	v_mfma_f32_32x32x16_bf16 v[0:15], v[64:67], v[72:75], v[0:15]
	v_mfma_f32_32x32x16_bf16 v[16:31], v[64:67], v[76:79], v[16:31]
	v_mfma_f32_32x32x16_bf16 v[0:15], v[68:71], v[220:223], v[0:15]
	v_mfma_f32_32x32x16_bf16 v[16:31], v[68:71], v[224:227], v[16:31]
	v_add_f32_e32 v113, v232, v233
	v_or_b32_e32 v114, 1, v107
	v_or_b32_e32 v97, 2, v107
	v_or_b32_e32 v96, 3, v107
	v_or_b32_e32 v95, 8, v107
	v_or_b32_e32 v94, 9, v107
	v_or_b32_e32 v93, 10, v107
	v_or_b32_e32 v92, 11, v107
	v_or_b32_e32 v91, 16, v107
	v_or_b32_e32 v90, 17, v107
	v_or_b32_e32 v89, 18, v107
	v_or_b32_e32 v88, 19, v107
	v_or_b32_e32 v87, 24, v107
	v_or_b32_e32 v86, 25, v107
	v_or_b32_e32 v85, 26, v107
	v_or_b32_e32 v84, 27, v107
	s_nop 11
	s_branch .LBB0_553
; #define LAS __attribute__((address_space(3)))
; #define GAS __attribute__((address_space(1)))
; __device__ __forceinline__ void dil_unit(LAS unsigned char* lds, bf16_t* proj, int seq, int hd, int T0, int rho) {
;     ...
;     const int tid = tid_, lane = tid & 63, r32 = lane & 31, hi = lane >> 5, wid = __builtin_amdgcn_readfirstlane(tid >> 6);
;     bf16_t* base = proj + (size_t)seq * SEQ * NIN;
;     LAS unsigned char* wbuf = lds + wid * 4096;
;     const LAS unsigned char* vp = wbuf + ((lane >> 4) & 1) * 32 + (lane & 3) * 8 + (4 * hi + ((lane & 15) >> 2)) * 64;
;     const int P0 = T0 + rho;
;     bf16x8 qr[4];
; #pragma unroll
;     for (int ks = 0; ks < 4; ++ks) qr[ks] = *(const GAS bf16x8*)(base + (size_t)(P0 + 16 * r32) * NIN + PC_LQ + hd * 64 + 16 * ks + 8 * hi);
;     f32x16 o0 = {}, o1 = {}; float l = 0.f;
;     const bool bound = (T0 < 1024) || (T0 >= 15360);
.LBB0_558:
	s_movk_i32 s100, 0x1800
	s_add_i32 s101, s6, 0x15c00
	s_lshl_b32 s90, s58, 1
	s_add_u32 s82, s56, s90
	s_addc_u32 s83, s57, 0
	s_add_u32 s82, s82, 0x1200
	s_addc_u32 s83, s83, 0
	s_sub_i32 s90, s76, 64
	s_mul_i32 s90, s90, 0x1800
	s_add_u32 s84, s82, s90
	s_addc_u32 s85, s83, 0
	s_sub_i32 s90, s76, 256
	s_mul_i32 s90, s90, 0x1800
	s_add_u32 s86, s82, s90
	s_addc_u32 s87, s83, 0
	s_sub_i32 s90, s76, 1024
	s_mul_i32 s90, s90, 0x1800
	s_add_u32 s88, s82, s90
	s_addc_u32 s89, s83, 0
	v_lshlrev_b32_e32 v153, 1, v98
	v_mad_u32_u24 v80, v105, s100, v82
	v_mad_u32_u24 v100, v110, s100, v153
	v_add_u32_e32 v149, 0x18000, v100
	v_lshlrev_b32_e32 v83, 2, v105
	v_mad_u32_u24 v83, v83, s100, v82
	v_lshlrev_b32_e32 v101, 2, v110
	v_mad_u32_u24 v101, v101, s100, v153
	v_add_u32_e32 v150, 0x60000, v101
	v_lshlrev_b32_e32 v99, 4, v105
	v_mad_u32_u24 v99, v99, s100, v82
	v_lshlrev_b32_e32 v148, 4, v110
	v_mad_u32_u24 v148, v148, s100, v153
	v_add_u32_e32 v151, 0x180000, v148
	v_lshrrev_b32_e32 v249, 3, v103
	v_and_b32_e32 v250, 7, v103
	v_lshlrev_b32_e32 v250, 4, v250
	v_add_u32_e32 v235, 0, v249
	v_add_u32_e32 v236, 8, v249
	v_add_u32_e32 v237, 16, v249
	v_add_u32_e32 v238, 24, v249
	v_add_u32_e32 v239, 0, v249
	v_lshlrev_b32_e32 v239, 2, v239
	v_add_u32_e32 v240, 8, v249
	v_lshlrev_b32_e32 v240, 2, v240
	v_add_u32_e32 v241, 16, v249
	v_lshlrev_b32_e32 v241, 2, v241
	v_add_u32_e32 v242, 24, v249
	v_lshlrev_b32_e32 v242, 2, v242
	v_add_u32_e32 v243, 0, v249
	v_lshlrev_b32_e32 v243, 4, v243
	v_add_u32_e32 v244, 8, v249
	v_lshlrev_b32_e32 v244, 4, v244
	v_add_u32_e32 v245, 16, v249
	v_lshlrev_b32_e32 v245, 4, v245
	v_add_u32_e32 v246, 24, v249
	v_lshlrev_b32_e32 v246, 4, v246
	v_mov_b32_e32 v252, v250
	v_mov_b32_e32 v100, v110
	v_add_u32_e32 v149, 16, v100
	v_lshlrev_b32_e32 v101, 2, v110
	v_add_u32_e32 v150, 64, v101
	v_lshlrev_b32_e32 v148, 4, v110
	v_add_u32_e32 v151, 256, v148
	s_mov_b32 s98, 0x4000
	s_mov_b32 s99, 0x3fff
	v_and_b32_e32 v247, 7, v249
	v_lshlrev_b32_e32 v247, 4, v247
	v_xor_b32_e32 v247, v247, v112
	v_and_b32_e32 v153, 7, v105
	v_or_b32_e32 v248, 0, v106
	v_xor_b32_e32 v248, v248, v153
	v_lshlrev_b32_e32 v248, 4, v248
	v_lshl_add_u32 v248, v105, 7, v248
	v_add_u32_e32 v248, s77, v248
	v_or_b32_e32 v249, 2, v106
	v_xor_b32_e32 v249, v249, v153
	v_lshlrev_b32_e32 v249, 4, v249
	v_lshl_add_u32 v249, v105, 7, v249
	v_add_u32_e32 v249, s77, v249
	v_or_b32_e32 v250, 4, v106
	v_xor_b32_e32 v250, v250, v153
	v_lshlrev_b32_e32 v250, 4, v250
	v_lshl_add_u32 v250, v105, 7, v250
	v_add_u32_e32 v250, s77, v250
	v_or_b32_e32 v251, 6, v106
	v_xor_b32_e32 v251, v251, v153
	v_lshlrev_b32_e32 v251, 4, v251
	v_lshl_add_u32 v251, v105, 7, v251
	v_add_u32_e32 v251, s77, v251
	v_lshlrev_b32_e32 v153, 1, v98
	v_mul_u32_u24_e32 v228, 17, v105
	v_sub_u32_e32 v228, v107, v228
	s_mul_i32 s90, s58, 153
	s_lshr_b32 s90, s90, 1
	s_add_i32 s90, s90, 34876
	v_lshl_add_u32 v228, v228, 2, s90
	v_lshlrev_b32_e32 v229, 2, v105
	v_sub_u32_e32 v229, v107, v229
	s_add_i32 s90, s101, 5104
	v_lshl_add_u32 v229, v229, 2, s90
	v_sub_u32_e32 v230, v107, v105
	s_add_i32 s90, s101, 6364
	v_lshl_add_u32 v230, v230, 2, s90
	v_add_u32_e32 v231, v109, v108
	v_mov_b64_e32 v[232:233], 0
	v_mov_b64_e32 v[0:1], 0
	v_mov_b64_e32 v[2:3], 0
	v_mov_b64_e32 v[4:5], 0
	v_mov_b64_e32 v[6:7], 0
	v_mov_b64_e32 v[8:9], 0
	v_mov_b64_e32 v[10:11], 0
	v_mov_b64_e32 v[12:13], 0
	v_mov_b64_e32 v[14:15], 0
	v_mov_b64_e32 v[16:17], 0
	v_mov_b64_e32 v[18:19], 0
	v_mov_b64_e32 v[20:21], 0
	v_mov_b64_e32 v[22:23], 0
	v_mov_b64_e32 v[24:25], 0
	v_mov_b64_e32 v[26:27], 0
	v_mov_b64_e32 v[28:29], 0
	v_mov_b64_e32 v[30:31], 0
	s_add_i32 s90, s76, -64
	v_add_u32_e32 v80, s90, v235
	v_add_u32_e32 v83, s90, v236
	v_add_u32_e32 v99, s90, v237
	v_add_u32_e32 v253, s90, v238
	v_add_u32_e32 v254, s90, v100
	v_add_u32_e32 v255, s90, v149
	v_med3_i32 v80, v80, 0, s99
	v_med3_i32 v83, v83, 0, s99
	v_med3_i32 v99, v99, 0, s99
	v_med3_i32 v253, v253, 0, s99
	v_med3_i32 v254, v254, 0, s99
	v_med3_i32 v255, v255, 0, s99
	v_mad_u32_u24 v80, v80, s100, v252
	v_mad_u32_u24 v83, v83, s100, v252
	v_mad_u32_u24 v99, v99, s100, v252
	v_mad_u32_u24 v253, v253, s100, v252
	v_mad_u32_u24 v254, v254, s100, v153
	v_mad_u32_u24 v255, v255, s100, v153
	global_load_dwordx4 v[116:119], v80, s[82:83]
	global_load_dwordx4 v[120:123], v83, s[82:83]
	global_load_dwordx4 v[124:127], v99, s[82:83]
	global_load_dwordx4 v[128:131], v253, s[82:83]
	global_load_dwordx4 v[132:135], v254, s[82:83] offset:768
	global_load_dwordx4 v[136:139], v255, s[82:83] offset:768
	global_load_dwordx4 v[140:143], v254, s[82:83] offset:832
	global_load_dwordx4 v[144:147], v255, s[82:83] offset:832
	s_add_i32 s90, s76, -32
	v_add_u32_e32 v80, s90, v235
	v_add_u32_e32 v83, s90, v236
	v_add_u32_e32 v99, s90, v237
	v_add_u32_e32 v253, s90, v238
	v_add_u32_e32 v254, s90, v100
	v_add_u32_e32 v255, s90, v149
	v_med3_i32 v80, v80, 0, s99
	v_med3_i32 v83, v83, 0, s99
	v_med3_i32 v99, v99, 0, s99
	v_med3_i32 v253, v253, 0, s99
	v_med3_i32 v254, v254, 0, s99
	v_med3_i32 v255, v255, 0, s99
	v_mad_u32_u24 v80, v80, s100, v252
	v_mad_u32_u24 v83, v83, s100, v252
	v_mad_u32_u24 v99, v99, s100, v252
	v_mad_u32_u24 v253, v253, s100, v252
	v_mad_u32_u24 v254, v254, s100, v153
	v_mad_u32_u24 v255, v255, s100, v153
	global_load_dwordx4 v[156:159], v80, s[82:83]
	global_load_dwordx4 v[160:163], v83, s[82:83]
	global_load_dwordx4 v[164:167], v99, s[82:83]
	global_load_dwordx4 v[168:171], v253, s[82:83]
	global_load_dwordx4 v[172:175], v254, s[82:83] offset:768
	global_load_dwordx4 v[176:179], v255, s[82:83] offset:768
	global_load_dwordx4 v[180:183], v254, s[82:83] offset:832
	global_load_dwordx4 v[184:187], v255, s[82:83] offset:832
	s_add_i32 s90, s76, 0
	v_add_u32_e32 v80, s90, v235
	v_add_u32_e32 v83, s90, v236
	v_add_u32_e32 v99, s90, v237
	v_add_u32_e32 v253, s90, v238
	v_add_u32_e32 v254, s90, v100
	v_add_u32_e32 v255, s90, v149
	v_med3_i32 v80, v80, 0, s99
	v_med3_i32 v83, v83, 0, s99
	v_med3_i32 v99, v99, 0, s99
	v_med3_i32 v253, v253, 0, s99
	v_med3_i32 v254, v254, 0, s99
	v_med3_i32 v255, v255, 0, s99
	v_mad_u32_u24 v80, v80, s100, v252
	v_mad_u32_u24 v83, v83, s100, v252
	v_mad_u32_u24 v99, v99, s100, v252
	v_mad_u32_u24 v253, v253, s100, v252
	v_mad_u32_u24 v254, v254, s100, v153
	v_mad_u32_u24 v255, v255, s100, v153
	global_load_dwordx4 v[188:191], v80, s[82:83]
	global_load_dwordx4 v[192:195], v83, s[82:83]
	global_load_dwordx4 v[196:199], v99, s[82:83]
	global_load_dwordx4 v[200:203], v253, s[82:83]
	global_load_dwordx4 v[204:207], v254, s[82:83] offset:768
	global_load_dwordx4 v[208:211], v255, s[82:83] offset:768
	global_load_dwordx4 v[212:215], v254, s[82:83] offset:832
	global_load_dwordx4 v[216:219], v255, s[82:83] offset:832
	s_waitcnt vmcnt(16)
	ds_write_b128 v247, v[116:119]
	ds_write_b128 v247, v[120:123] offset:1024
	ds_write_b128 v247, v[124:127] offset:2048
	ds_write_b128 v247, v[128:131] offset:3072
	ds_read_b128 v[116:119], v248
	ds_read_b128 v[120:123], v249
	ds_read_b128 v[124:127], v250
	ds_read_b128 v[128:131], v251
	ds_write_b128 v112, v[132:135]
	ds_write_b128 v112, v[136:139] offset:1024
	ds_write_b128 v112, v[140:143] offset:2048
	ds_write_b128 v112, v[144:147] offset:3072
	v_mov_b32_e32 v115, v228
	ds_read2_b32 v[32:33], v115 offset0:0 offset1:1
	ds_read2_b32 v[34:35], v115 offset0:2 offset1:3
	ds_read2_b32 v[36:37], v115 offset0:8 offset1:9
	ds_read2_b32 v[38:39], v115 offset0:10 offset1:11
	ds_read2_b32 v[40:41], v115 offset0:17 offset1:18
	ds_read2_b32 v[42:43], v115 offset0:19 offset1:20
	ds_read2_b32 v[44:45], v115 offset0:25 offset1:26
	ds_read2_b32 v[46:47], v115 offset0:27 offset1:28
	s_waitcnt lgkmcnt(0)
	v_mfma_f32_32x32x16_bf16 v[32:47], v[116:119], v[48:51], v[32:47]
	ds_read_b64_tr_b16 v[72:73], v231
	ds_read_b64_tr_b16 v[74:75], v231 offset:512
	ds_read_b64_tr_b16 v[76:77], v231 offset:2048
	ds_read_b64_tr_b16 v[78:79], v231 offset:2560
	ds_read_b64_tr_b16 v[220:221], v231 offset:1024
	ds_read_b64_tr_b16 v[222:223], v231 offset:1536
	ds_read_b64_tr_b16 v[224:225], v231 offset:3072
	ds_read_b64_tr_b16 v[226:227], v231 offset:3584
	s_waitcnt vmcnt(8)
	ds_write_b128 v247, v[156:159]
	ds_write_b128 v247, v[160:163] offset:1024
	ds_write_b128 v247, v[164:167] offset:2048
	ds_write_b128 v247, v[168:171] offset:3072
	ds_read_b128 v[156:159], v248
	ds_read_b128 v[160:163], v249
	ds_read_b128 v[164:167], v250
	ds_read_b128 v[168:171], v251
	ds_write_b128 v112, v[172:175]
	ds_write_b128 v112, v[176:179] offset:1024
	ds_write_b128 v112, v[180:183] offset:2048
	ds_write_b128 v112, v[184:187] offset:3072
	v_mfma_f32_32x32x16_bf16 v[32:47], v[120:123], v[52:55], v[32:47]
	v_mfma_f32_32x32x16_bf16 v[32:47], v[124:127], v[56:59], v[32:47]
	v_mfma_f32_32x32x16_bf16 v[32:47], v[128:131], v[60:63], v[32:47]
	s_nop 11
	v_exp_f32_e32 v32, v32
	v_exp_f32_e32 v33, v33
	v_exp_f32_e32 v34, v34
	v_exp_f32_e32 v35, v35
	v_exp_f32_e32 v36, v36
	v_exp_f32_e32 v37, v37
	v_exp_f32_e32 v38, v38
	v_exp_f32_e32 v39, v39
	v_exp_f32_e32 v40, v40
	v_exp_f32_e32 v41, v41
	v_exp_f32_e32 v42, v42
	v_exp_f32_e32 v43, v43
	v_exp_f32_e32 v44, v44
	v_exp_f32_e32 v45, v45
	v_exp_f32_e32 v46, v46
	v_exp_f32_e32 v47, v47
	s_add_i32 s90, s76, -64
	v_add_u32_e32 v84, s90, v107
	v_add_u32_e32 v85, 0, v84
	v_add_u32_e32 v86, 1, v84
	v_add_u32_e32 v87, 2, v84
	v_add_u32_e32 v88, 3, v84
	v_cmp_gt_u32_e64 s[30:31], s98, v85
	v_cmp_gt_u32_e64 s[36:37], s98, v86
	v_cmp_gt_u32_e64 s[78:79], s98, v87
	v_cmp_gt_u32_e64 s[50:51], s98, v88
	v_cndmask_b32_e64 v32, 0, v32, s[30:31]
	v_add_u32_e32 v85, 8, v84
	v_cmp_gt_u32_e64 s[30:31], s98, v85
	v_cndmask_b32_e64 v33, 0, v33, s[36:37]
	v_add_u32_e32 v86, 9, v84
	v_cmp_gt_u32_e64 s[36:37], s98, v86
	v_cndmask_b32_e64 v34, 0, v34, s[78:79]
	v_add_u32_e32 v87, 10, v84
	v_cmp_gt_u32_e64 s[78:79], s98, v87
	v_cndmask_b32_e64 v35, 0, v35, s[50:51]
	v_add_u32_e32 v88, 11, v84
	v_cmp_gt_u32_e64 s[50:51], s98, v88
	v_cndmask_b32_e64 v36, 0, v36, s[30:31]
	v_add_u32_e32 v85, 16, v84
	v_cmp_gt_u32_e64 s[30:31], s98, v85
	v_cndmask_b32_e64 v37, 0, v37, s[36:37]
	v_add_u32_e32 v86, 17, v84
	v_cmp_gt_u32_e64 s[36:37], s98, v86
	v_cndmask_b32_e64 v38, 0, v38, s[78:79]
	v_add_u32_e32 v87, 18, v84
	v_cmp_gt_u32_e64 s[78:79], s98, v87
	v_cndmask_b32_e64 v39, 0, v39, s[50:51]
	v_add_u32_e32 v88, 19, v84
	v_cmp_gt_u32_e64 s[50:51], s98, v88
	v_cndmask_b32_e64 v40, 0, v40, s[30:31]
	v_add_u32_e32 v85, 24, v84
	v_cmp_gt_u32_e64 s[30:31], s98, v85
	v_cndmask_b32_e64 v41, 0, v41, s[36:37]
	v_add_u32_e32 v86, 25, v84
	v_cmp_gt_u32_e64 s[36:37], s98, v86
	v_cndmask_b32_e64 v42, 0, v42, s[78:79]
	v_add_u32_e32 v87, 26, v84
	v_cmp_gt_u32_e64 s[78:79], s98, v87
	v_cndmask_b32_e64 v43, 0, v43, s[50:51]
	v_add_u32_e32 v88, 27, v84
	v_cmp_gt_u32_e64 s[50:51], s98, v88
	v_nop
	v_cndmask_b32_e64 v44, 0, v44, s[30:31]
	v_cndmask_b32_e64 v45, 0, v45, s[36:37]
	v_cndmask_b32_e64 v46, 0, v46, s[78:79]
	v_cndmask_b32_e64 v47, 0, v47, s[50:51]
	v_cvt_pk_bf16_f32 v64, v32, v33
	v_cvt_pk_bf16_f32 v65, v34, v35
	v_cvt_pk_bf16_f32 v66, v36, v37
	v_cvt_pk_bf16_f32 v67, v38, v39
	v_cvt_pk_bf16_f32 v68, v40, v41
	v_cvt_pk_bf16_f32 v69, v42, v43
	v_cvt_pk_bf16_f32 v70, v44, v45
	v_cvt_pk_bf16_f32 v71, v46, v47
	v_pk_add_f32 v[232:233], v[232:233], v[32:33]
	v_pk_add_f32 v[232:233], v[232:233], v[34:35]
	v_pk_add_f32 v[232:233], v[232:233], v[36:37]
	v_pk_add_f32 v[232:233], v[232:233], v[38:39]
	v_pk_add_f32 v[232:233], v[232:233], v[40:41]
	v_pk_add_f32 v[232:233], v[232:233], v[42:43]
	v_pk_add_f32 v[232:233], v[232:233], v[44:45]
	v_pk_add_f32 v[232:233], v[232:233], v[46:47]
	ds_read2_b32 v[32:33], v115 offset0:34 offset1:35
	ds_read2_b32 v[34:35], v115 offset0:36 offset1:37
	ds_read2_b32 v[36:37], v115 offset0:42 offset1:43
	ds_read2_b32 v[38:39], v115 offset0:44 offset1:45
	ds_read2_b32 v[40:41], v115 offset0:51 offset1:52
	ds_read2_b32 v[42:43], v115 offset0:53 offset1:54
	ds_read2_b32 v[44:45], v115 offset0:59 offset1:60
	ds_read2_b32 v[46:47], v115 offset0:61 offset1:62
	s_waitcnt lgkmcnt(15)
	v_mfma_f32_32x32x16_bf16 v[0:15], v[64:67], v[72:75], v[0:15]
	v_mfma_f32_32x32x16_bf16 v[16:31], v[64:67], v[76:79], v[16:31]
	v_mfma_f32_32x32x16_bf16 v[0:15], v[68:71], v[220:223], v[0:15]
	v_mfma_f32_32x32x16_bf16 v[16:31], v[68:71], v[224:227], v[16:31]
	s_add_i32 s90, s76, 32
	v_add_u32_e32 v80, s90, v235
	v_add_u32_e32 v83, s90, v236
	v_add_u32_e32 v99, s90, v237
	v_add_u32_e32 v253, s90, v238
	v_add_u32_e32 v254, s90, v100
	v_add_u32_e32 v255, s90, v149
	v_med3_i32 v80, v80, 0, s99
	v_med3_i32 v83, v83, 0, s99
	v_med3_i32 v99, v99, 0, s99
	v_med3_i32 v253, v253, 0, s99
	v_med3_i32 v254, v254, 0, s99
	v_med3_i32 v255, v255, 0, s99
	v_mad_u32_u24 v80, v80, s100, v252
	v_mad_u32_u24 v83, v83, s100, v252
	v_mad_u32_u24 v99, v99, s100, v252
	v_mad_u32_u24 v253, v253, s100, v252
	v_mad_u32_u24 v254, v254, s100, v153
	v_mad_u32_u24 v255, v255, s100, v153
	global_load_dwordx4 v[116:119], v80, s[82:83]
	global_load_dwordx4 v[120:123], v83, s[82:83]
	global_load_dwordx4 v[124:127], v99, s[82:83]
	global_load_dwordx4 v[128:131], v253, s[82:83]
	global_load_dwordx4 v[132:135], v254, s[82:83] offset:768
	global_load_dwordx4 v[136:139], v255, s[82:83] offset:768
	global_load_dwordx4 v[140:143], v254, s[82:83] offset:832
	global_load_dwordx4 v[144:147], v255, s[82:83] offset:832
	s_waitcnt lgkmcnt(0)
	v_mfma_f32_32x32x16_bf16 v[32:47], v[156:159], v[48:51], v[32:47]
	ds_read_b64_tr_b16 v[72:73], v231
	ds_read_b64_tr_b16 v[74:75], v231 offset:512
	ds_read_b64_tr_b16 v[76:77], v231 offset:2048
	ds_read_b64_tr_b16 v[78:79], v231 offset:2560
	ds_read_b64_tr_b16 v[220:221], v231 offset:1024
	ds_read_b64_tr_b16 v[222:223], v231 offset:1536
	ds_read_b64_tr_b16 v[224:225], v231 offset:3072
	ds_read_b64_tr_b16 v[226:227], v231 offset:3584
	s_waitcnt vmcnt(8)
	ds_write_b128 v247, v[188:191]
	ds_write_b128 v247, v[192:195] offset:1024
	ds_write_b128 v247, v[196:199] offset:2048
	ds_write_b128 v247, v[200:203] offset:3072
	ds_read_b128 v[188:191], v248
	ds_read_b128 v[192:195], v249
	ds_read_b128 v[196:199], v250
	ds_read_b128 v[200:203], v251
	ds_write_b128 v112, v[204:207]
	ds_write_b128 v112, v[208:211] offset:1024
	ds_write_b128 v112, v[212:215] offset:2048
	ds_write_b128 v112, v[216:219] offset:3072
	v_mfma_f32_32x32x16_bf16 v[32:47], v[160:163], v[52:55], v[32:47]
	v_mfma_f32_32x32x16_bf16 v[32:47], v[164:167], v[56:59], v[32:47]
	v_mfma_f32_32x32x16_bf16 v[32:47], v[168:171], v[60:63], v[32:47]
	s_nop 11
	v_exp_f32_e32 v32, v32
	v_exp_f32_e32 v33, v33
	v_exp_f32_e32 v34, v34
	v_exp_f32_e32 v35, v35
	v_exp_f32_e32 v36, v36
	v_exp_f32_e32 v37, v37
	v_exp_f32_e32 v38, v38
	v_exp_f32_e32 v39, v39
	v_exp_f32_e32 v40, v40
	v_exp_f32_e32 v41, v41
	v_exp_f32_e32 v42, v42
	v_exp_f32_e32 v43, v43
	v_exp_f32_e32 v44, v44
	v_exp_f32_e32 v45, v45
	v_exp_f32_e32 v46, v46
	v_exp_f32_e32 v47, v47
	s_add_i32 s90, s76, -32
	v_add_u32_e32 v84, s90, v107
	v_add_u32_e32 v85, 0, v84
	v_add_u32_e32 v86, 1, v84
	v_add_u32_e32 v87, 2, v84
	v_add_u32_e32 v88, 3, v84
	v_cmp_gt_u32_e64 s[30:31], s98, v85
	v_cmp_gt_u32_e64 s[36:37], s98, v86
	v_cmp_gt_u32_e64 s[78:79], s98, v87
	v_cmp_gt_u32_e64 s[50:51], s98, v88
	v_cndmask_b32_e64 v32, 0, v32, s[30:31]
	v_add_u32_e32 v85, 8, v84
	v_cmp_gt_u32_e64 s[30:31], s98, v85
	v_cndmask_b32_e64 v33, 0, v33, s[36:37]
	v_add_u32_e32 v86, 9, v84
	v_cmp_gt_u32_e64 s[36:37], s98, v86
	v_cndmask_b32_e64 v34, 0, v34, s[78:79]
	v_add_u32_e32 v87, 10, v84
	v_cmp_gt_u32_e64 s[78:79], s98, v87
	v_cndmask_b32_e64 v35, 0, v35, s[50:51]
	v_add_u32_e32 v88, 11, v84
	v_cmp_gt_u32_e64 s[50:51], s98, v88
	v_cndmask_b32_e64 v36, 0, v36, s[30:31]
	v_add_u32_e32 v85, 16, v84
	v_cmp_gt_u32_e64 s[30:31], s98, v85
	v_cndmask_b32_e64 v37, 0, v37, s[36:37]
	v_add_u32_e32 v86, 17, v84
	v_cmp_gt_u32_e64 s[36:37], s98, v86
	v_cndmask_b32_e64 v38, 0, v38, s[78:79]
	v_add_u32_e32 v87, 18, v84
	v_cmp_gt_u32_e64 s[78:79], s98, v87
	v_cndmask_b32_e64 v39, 0, v39, s[50:51]
	v_add_u32_e32 v88, 19, v84
	v_cmp_gt_u32_e64 s[50:51], s98, v88
	v_cndmask_b32_e64 v40, 0, v40, s[30:31]
	v_add_u32_e32 v85, 24, v84
	v_cmp_gt_u32_e64 s[30:31], s98, v85
	v_cndmask_b32_e64 v41, 0, v41, s[36:37]
	v_add_u32_e32 v86, 25, v84
	v_cmp_gt_u32_e64 s[36:37], s98, v86
	v_cndmask_b32_e64 v42, 0, v42, s[78:79]
	v_add_u32_e32 v87, 26, v84
	v_cmp_gt_u32_e64 s[78:79], s98, v87
	v_cndmask_b32_e64 v43, 0, v43, s[50:51]
	v_add_u32_e32 v88, 27, v84
	v_cmp_gt_u32_e64 s[50:51], s98, v88
	v_nop
	v_cndmask_b32_e64 v44, 0, v44, s[30:31]
	v_cndmask_b32_e64 v45, 0, v45, s[36:37]
	v_cndmask_b32_e64 v46, 0, v46, s[78:79]
	v_cndmask_b32_e64 v47, 0, v47, s[50:51]
	v_cvt_pk_bf16_f32 v64, v32, v33
	v_cvt_pk_bf16_f32 v65, v34, v35
	v_cvt_pk_bf16_f32 v66, v36, v37
	v_cvt_pk_bf16_f32 v67, v38, v39
	v_cvt_pk_bf16_f32 v68, v40, v41
	v_cvt_pk_bf16_f32 v69, v42, v43
	v_cvt_pk_bf16_f32 v70, v44, v45
	v_cvt_pk_bf16_f32 v71, v46, v47
	v_pk_add_f32 v[232:233], v[232:233], v[32:33]
	v_pk_add_f32 v[232:233], v[232:233], v[34:35]
	v_pk_add_f32 v[232:233], v[232:233], v[36:37]
	v_pk_add_f32 v[232:233], v[232:233], v[38:39]
	v_pk_add_f32 v[232:233], v[232:233], v[40:41]
	v_pk_add_f32 v[232:233], v[232:233], v[42:43]
	v_pk_add_f32 v[232:233], v[232:233], v[44:45]
	v_pk_add_f32 v[232:233], v[232:233], v[46:47]
	ds_read2_b32 v[32:33], v115 offset0:68 offset1:69
	ds_read2_b32 v[34:35], v115 offset0:70 offset1:71
	ds_read2_b32 v[36:37], v115 offset0:76 offset1:77
	ds_read2_b32 v[38:39], v115 offset0:78 offset1:79
	ds_read2_b32 v[40:41], v115 offset0:85 offset1:86
	ds_read2_b32 v[42:43], v115 offset0:87 offset1:88
	ds_read2_b32 v[44:45], v115 offset0:93 offset1:94
	ds_read2_b32 v[46:47], v115 offset0:95 offset1:96
	s_waitcnt lgkmcnt(15)
	v_mfma_f32_32x32x16_bf16 v[0:15], v[64:67], v[72:75], v[0:15]
	v_mfma_f32_32x32x16_bf16 v[16:31], v[64:67], v[76:79], v[16:31]
	v_mfma_f32_32x32x16_bf16 v[0:15], v[68:71], v[220:223], v[0:15]
	v_mfma_f32_32x32x16_bf16 v[16:31], v[68:71], v[224:227], v[16:31]
	s_add_i32 s90, s76, 64
	v_add_u32_e32 v80, s90, v235
	v_add_u32_e32 v83, s90, v236
	v_add_u32_e32 v99, s90, v237
	v_add_u32_e32 v253, s90, v238
	v_add_u32_e32 v254, s90, v100
	v_add_u32_e32 v255, s90, v149
	v_med3_i32 v80, v80, 0, s99
	v_med3_i32 v83, v83, 0, s99
	v_med3_i32 v99, v99, 0, s99
	v_med3_i32 v253, v253, 0, s99
	v_med3_i32 v254, v254, 0, s99
	v_med3_i32 v255, v255, 0, s99
	v_mad_u32_u24 v80, v80, s100, v252
	v_mad_u32_u24 v83, v83, s100, v252
	v_mad_u32_u24 v99, v99, s100, v252
	v_mad_u32_u24 v253, v253, s100, v252
	v_mad_u32_u24 v254, v254, s100, v153
	v_mad_u32_u24 v255, v255, s100, v153
	global_load_dwordx4 v[156:159], v80, s[82:83]
	global_load_dwordx4 v[160:163], v83, s[82:83]
	global_load_dwordx4 v[164:167], v99, s[82:83]
	global_load_dwordx4 v[168:171], v253, s[82:83]
	global_load_dwordx4 v[172:175], v254, s[82:83] offset:768
	global_load_dwordx4 v[176:179], v255, s[82:83] offset:768
	global_load_dwordx4 v[180:183], v254, s[82:83] offset:832
	global_load_dwordx4 v[184:187], v255, s[82:83] offset:832
	s_waitcnt lgkmcnt(0)
	v_mfma_f32_32x32x16_bf16 v[32:47], v[188:191], v[48:51], v[32:47]
	ds_read_b64_tr_b16 v[72:73], v231
	ds_read_b64_tr_b16 v[74:75], v231 offset:512
	ds_read_b64_tr_b16 v[76:77], v231 offset:2048
	ds_read_b64_tr_b16 v[78:79], v231 offset:2560
	ds_read_b64_tr_b16 v[220:221], v231 offset:1024
	ds_read_b64_tr_b16 v[222:223], v231 offset:1536
	ds_read_b64_tr_b16 v[224:225], v231 offset:3072
	ds_read_b64_tr_b16 v[226:227], v231 offset:3584
	s_waitcnt vmcnt(8)
	ds_write_b128 v247, v[116:119]
	ds_write_b128 v247, v[120:123] offset:1024
	ds_write_b128 v247, v[124:127] offset:2048
	ds_write_b128 v247, v[128:131] offset:3072
	ds_read_b128 v[116:119], v248
	ds_read_b128 v[120:123], v249
	ds_read_b128 v[124:127], v250
	ds_read_b128 v[128:131], v251
	ds_write_b128 v112, v[132:135]
	ds_write_b128 v112, v[136:139] offset:1024
	ds_write_b128 v112, v[140:143] offset:2048
	ds_write_b128 v112, v[144:147] offset:3072
	v_mfma_f32_32x32x16_bf16 v[32:47], v[192:195], v[52:55], v[32:47]
	v_mfma_f32_32x32x16_bf16 v[32:47], v[196:199], v[56:59], v[32:47]
	v_mfma_f32_32x32x16_bf16 v[32:47], v[200:203], v[60:63], v[32:47]
	s_nop 11
	v_exp_f32_e32 v32, v32
	v_exp_f32_e32 v33, v33
	v_exp_f32_e32 v34, v34
	v_exp_f32_e32 v35, v35
	v_exp_f32_e32 v36, v36
	v_exp_f32_e32 v37, v37
	v_exp_f32_e32 v38, v38
	v_exp_f32_e32 v39, v39
	v_exp_f32_e32 v40, v40
	v_exp_f32_e32 v41, v41
	v_exp_f32_e32 v42, v42
	v_exp_f32_e32 v43, v43
	v_exp_f32_e32 v44, v44
	v_exp_f32_e32 v45, v45
	v_exp_f32_e32 v46, v46
	v_exp_f32_e32 v47, v47
	s_add_i32 s90, s76, 0
	v_add_u32_e32 v84, s90, v107
	v_add_u32_e32 v85, 0, v84
	v_add_u32_e32 v86, 1, v84
	v_add_u32_e32 v87, 2, v84
	v_add_u32_e32 v88, 3, v84
	v_cmp_gt_u32_e64 s[30:31], s98, v85
	v_cmp_gt_u32_e64 s[36:37], s98, v86
	v_cmp_gt_u32_e64 s[78:79], s98, v87
	v_cmp_gt_u32_e64 s[50:51], s98, v88
	v_cndmask_b32_e64 v32, 0, v32, s[30:31]
	v_add_u32_e32 v85, 8, v84
	v_cmp_gt_u32_e64 s[30:31], s98, v85
	v_cndmask_b32_e64 v33, 0, v33, s[36:37]
	v_add_u32_e32 v86, 9, v84
	v_cmp_gt_u32_e64 s[36:37], s98, v86
	v_cndmask_b32_e64 v34, 0, v34, s[78:79]
	v_add_u32_e32 v87, 10, v84
	v_cmp_gt_u32_e64 s[78:79], s98, v87
	v_cndmask_b32_e64 v35, 0, v35, s[50:51]
	v_add_u32_e32 v88, 11, v84
	v_cmp_gt_u32_e64 s[50:51], s98, v88
	v_cndmask_b32_e64 v36, 0, v36, s[30:31]
	v_add_u32_e32 v85, 16, v84
	v_cmp_gt_u32_e64 s[30:31], s98, v85
	v_cndmask_b32_e64 v37, 0, v37, s[36:37]
	v_add_u32_e32 v86, 17, v84
	v_cmp_gt_u32_e64 s[36:37], s98, v86
	v_cndmask_b32_e64 v38, 0, v38, s[78:79]
	v_add_u32_e32 v87, 18, v84
	v_cmp_gt_u32_e64 s[78:79], s98, v87
	v_cndmask_b32_e64 v39, 0, v39, s[50:51]
	v_add_u32_e32 v88, 19, v84
	v_cmp_gt_u32_e64 s[50:51], s98, v88
	v_cndmask_b32_e64 v40, 0, v40, s[30:31]
	v_add_u32_e32 v85, 24, v84
	v_cmp_gt_u32_e64 s[30:31], s98, v85
	v_cndmask_b32_e64 v41, 0, v41, s[36:37]
	v_add_u32_e32 v86, 25, v84
	v_cmp_gt_u32_e64 s[36:37], s98, v86
	v_cndmask_b32_e64 v42, 0, v42, s[78:79]
	v_add_u32_e32 v87, 26, v84
	v_cmp_gt_u32_e64 s[78:79], s98, v87
	v_cndmask_b32_e64 v43, 0, v43, s[50:51]
	v_add_u32_e32 v88, 27, v84
	v_cmp_gt_u32_e64 s[50:51], s98, v88
	v_nop
	v_cndmask_b32_e64 v44, 0, v44, s[30:31]
	v_cndmask_b32_e64 v45, 0, v45, s[36:37]
	v_cndmask_b32_e64 v46, 0, v46, s[78:79]
	v_cndmask_b32_e64 v47, 0, v47, s[50:51]
	v_cvt_pk_bf16_f32 v64, v32, v33
	v_cvt_pk_bf16_f32 v65, v34, v35
	v_cvt_pk_bf16_f32 v66, v36, v37
	v_cvt_pk_bf16_f32 v67, v38, v39
	v_cvt_pk_bf16_f32 v68, v40, v41
	v_cvt_pk_bf16_f32 v69, v42, v43
	v_cvt_pk_bf16_f32 v70, v44, v45
	v_cvt_pk_bf16_f32 v71, v46, v47
	v_pk_add_f32 v[232:233], v[232:233], v[32:33]
	v_pk_add_f32 v[232:233], v[232:233], v[34:35]
	v_pk_add_f32 v[232:233], v[232:233], v[36:37]
	v_pk_add_f32 v[232:233], v[232:233], v[38:39]
	v_pk_add_f32 v[232:233], v[232:233], v[40:41]
	v_pk_add_f32 v[232:233], v[232:233], v[42:43]
	v_pk_add_f32 v[232:233], v[232:233], v[44:45]
	v_pk_add_f32 v[232:233], v[232:233], v[46:47]
	ds_read2_b32 v[32:33], v115 offset0:102 offset1:103
	ds_read2_b32 v[34:35], v115 offset0:104 offset1:105
	ds_read2_b32 v[36:37], v115 offset0:110 offset1:111
	ds_read2_b32 v[38:39], v115 offset0:112 offset1:113
	ds_read2_b32 v[40:41], v115 offset0:119 offset1:120
	ds_read2_b32 v[42:43], v115 offset0:121 offset1:122
	ds_read2_b32 v[44:45], v115 offset0:127 offset1:128
	ds_read2_b32 v[46:47], v115 offset0:129 offset1:130
	s_waitcnt lgkmcnt(15)
	v_mfma_f32_32x32x16_bf16 v[0:15], v[64:67], v[72:75], v[0:15]
	v_mfma_f32_32x32x16_bf16 v[16:31], v[64:67], v[76:79], v[16:31]
	v_mfma_f32_32x32x16_bf16 v[0:15], v[68:71], v[220:223], v[0:15]
	v_mfma_f32_32x32x16_bf16 v[16:31], v[68:71], v[224:227], v[16:31]
	s_add_i32 s90, s76, 96
	v_add_u32_e32 v80, s90, v235
	v_add_u32_e32 v83, s90, v236
	v_add_u32_e32 v99, s90, v237
	v_add_u32_e32 v253, s90, v238
	v_add_u32_e32 v254, s90, v100
	v_add_u32_e32 v255, s90, v149
	v_med3_i32 v80, v80, 0, s99
	v_med3_i32 v83, v83, 0, s99
	v_med3_i32 v99, v99, 0, s99
	v_med3_i32 v253, v253, 0, s99
	v_med3_i32 v254, v254, 0, s99
	v_med3_i32 v255, v255, 0, s99
	v_mad_u32_u24 v80, v80, s100, v252
	v_mad_u32_u24 v83, v83, s100, v252
	v_mad_u32_u24 v99, v99, s100, v252
	v_mad_u32_u24 v253, v253, s100, v252
	v_mad_u32_u24 v254, v254, s100, v153
	v_mad_u32_u24 v255, v255, s100, v153
	global_load_dwordx4 v[188:191], v80, s[82:83]
	global_load_dwordx4 v[192:195], v83, s[82:83]
	global_load_dwordx4 v[196:199], v99, s[82:83]
	global_load_dwordx4 v[200:203], v253, s[82:83]
	global_load_dwordx4 v[204:207], v254, s[82:83] offset:768
	global_load_dwordx4 v[208:211], v255, s[82:83] offset:768
	global_load_dwordx4 v[212:215], v254, s[82:83] offset:832
	global_load_dwordx4 v[216:219], v255, s[82:83] offset:832
	s_waitcnt lgkmcnt(0)
	v_mfma_f32_32x32x16_bf16 v[32:47], v[116:119], v[48:51], v[32:47]
	ds_read_b64_tr_b16 v[72:73], v231
	ds_read_b64_tr_b16 v[74:75], v231 offset:512
	ds_read_b64_tr_b16 v[76:77], v231 offset:2048
	ds_read_b64_tr_b16 v[78:79], v231 offset:2560
	ds_read_b64_tr_b16 v[220:221], v231 offset:1024
	ds_read_b64_tr_b16 v[222:223], v231 offset:1536
	ds_read_b64_tr_b16 v[224:225], v231 offset:3072
	ds_read_b64_tr_b16 v[226:227], v231 offset:3584
	s_waitcnt vmcnt(8)
	ds_write_b128 v247, v[156:159]
	ds_write_b128 v247, v[160:163] offset:1024
	ds_write_b128 v247, v[164:167] offset:2048
	ds_write_b128 v247, v[168:171] offset:3072
	ds_read_b128 v[156:159], v248
	ds_read_b128 v[160:163], v249
	ds_read_b128 v[164:167], v250
	ds_read_b128 v[168:171], v251
	ds_write_b128 v112, v[172:175]
	ds_write_b128 v112, v[176:179] offset:1024
	ds_write_b128 v112, v[180:183] offset:2048
	ds_write_b128 v112, v[184:187] offset:3072
	v_mfma_f32_32x32x16_bf16 v[32:47], v[120:123], v[52:55], v[32:47]
	v_mfma_f32_32x32x16_bf16 v[32:47], v[124:127], v[56:59], v[32:47]
	v_mfma_f32_32x32x16_bf16 v[32:47], v[128:131], v[60:63], v[32:47]
	s_nop 11
	v_exp_f32_e32 v32, v32
	v_exp_f32_e32 v33, v33
	v_exp_f32_e32 v34, v34
	v_exp_f32_e32 v35, v35
	v_exp_f32_e32 v36, v36
	v_exp_f32_e32 v37, v37
	v_exp_f32_e32 v38, v38
	v_exp_f32_e32 v39, v39
	v_exp_f32_e32 v40, v40
	v_exp_f32_e32 v41, v41
	v_exp_f32_e32 v42, v42
	v_exp_f32_e32 v43, v43
	v_exp_f32_e32 v44, v44
	v_exp_f32_e32 v45, v45
	v_exp_f32_e32 v46, v46
	v_exp_f32_e32 v47, v47
	s_add_i32 s90, s76, 32
	v_add_u32_e32 v84, s90, v107
	v_add_u32_e32 v85, 0, v84
	v_add_u32_e32 v86, 1, v84
	v_add_u32_e32 v87, 2, v84
	v_add_u32_e32 v88, 3, v84
	v_cmp_gt_u32_e64 s[30:31], s98, v85
	v_cmp_gt_u32_e64 s[36:37], s98, v86
	v_cmp_gt_u32_e64 s[78:79], s98, v87
	v_cmp_gt_u32_e64 s[50:51], s98, v88
	v_cndmask_b32_e64 v32, 0, v32, s[30:31]
	v_add_u32_e32 v85, 8, v84
	v_cmp_gt_u32_e64 s[30:31], s98, v85
	v_cndmask_b32_e64 v33, 0, v33, s[36:37]
	v_add_u32_e32 v86, 9, v84
	v_cmp_gt_u32_e64 s[36:37], s98, v86
	v_cndmask_b32_e64 v34, 0, v34, s[78:79]
	v_add_u32_e32 v87, 10, v84
	v_cmp_gt_u32_e64 s[78:79], s98, v87
	v_cndmask_b32_e64 v35, 0, v35, s[50:51]
	v_add_u32_e32 v88, 11, v84
	v_cmp_gt_u32_e64 s[50:51], s98, v88
	v_cndmask_b32_e64 v36, 0, v36, s[30:31]
	v_add_u32_e32 v85, 16, v84
	v_cmp_gt_u32_e64 s[30:31], s98, v85
	v_cndmask_b32_e64 v37, 0, v37, s[36:37]
	v_add_u32_e32 v86, 17, v84
	v_cmp_gt_u32_e64 s[36:37], s98, v86
	v_cndmask_b32_e64 v38, 0, v38, s[78:79]
	v_add_u32_e32 v87, 18, v84
	v_cmp_gt_u32_e64 s[78:79], s98, v87
	v_cndmask_b32_e64 v39, 0, v39, s[50:51]
	v_add_u32_e32 v88, 19, v84
	v_cmp_gt_u32_e64 s[50:51], s98, v88
	v_cndmask_b32_e64 v40, 0, v40, s[30:31]
	v_add_u32_e32 v85, 24, v84
	v_cmp_gt_u32_e64 s[30:31], s98, v85
	v_cndmask_b32_e64 v41, 0, v41, s[36:37]
	v_add_u32_e32 v86, 25, v84
	v_cmp_gt_u32_e64 s[36:37], s98, v86
	v_cndmask_b32_e64 v42, 0, v42, s[78:79]
	v_add_u32_e32 v87, 26, v84
	v_cmp_gt_u32_e64 s[78:79], s98, v87
	v_cndmask_b32_e64 v43, 0, v43, s[50:51]
	v_add_u32_e32 v88, 27, v84
	v_cmp_gt_u32_e64 s[50:51], s98, v88
	v_nop
	v_cndmask_b32_e64 v44, 0, v44, s[30:31]
	v_cndmask_b32_e64 v45, 0, v45, s[36:37]
	v_cndmask_b32_e64 v46, 0, v46, s[78:79]
	v_cndmask_b32_e64 v47, 0, v47, s[50:51]
	v_cvt_pk_bf16_f32 v64, v32, v33
	v_cvt_pk_bf16_f32 v65, v34, v35
	v_cvt_pk_bf16_f32 v66, v36, v37
	v_cvt_pk_bf16_f32 v67, v38, v39
	v_cvt_pk_bf16_f32 v68, v40, v41
	v_cvt_pk_bf16_f32 v69, v42, v43
	v_cvt_pk_bf16_f32 v70, v44, v45
	v_cvt_pk_bf16_f32 v71, v46, v47
	v_pk_add_f32 v[232:233], v[232:233], v[32:33]
	v_pk_add_f32 v[232:233], v[232:233], v[34:35]
	v_pk_add_f32 v[232:233], v[232:233], v[36:37]
	v_pk_add_f32 v[232:233], v[232:233], v[38:39]
	v_pk_add_f32 v[232:233], v[232:233], v[40:41]
	v_pk_add_f32 v[232:233], v[232:233], v[42:43]
	v_pk_add_f32 v[232:233], v[232:233], v[44:45]
	v_pk_add_f32 v[232:233], v[232:233], v[46:47]
	ds_read2_b32 v[32:33], v115 offset0:136 offset1:137
	ds_read2_b32 v[34:35], v115 offset0:138 offset1:139
	ds_read2_b32 v[36:37], v115 offset0:144 offset1:145
	ds_read2_b32 v[38:39], v115 offset0:146 offset1:147
	ds_read2_b32 v[40:41], v115 offset0:153 offset1:154
	ds_read2_b32 v[42:43], v115 offset0:155 offset1:156
	ds_read2_b32 v[44:45], v115 offset0:161 offset1:162
	ds_read2_b32 v[46:47], v115 offset0:163 offset1:164
	s_waitcnt lgkmcnt(15)
	v_mfma_f32_32x32x16_bf16 v[0:15], v[64:67], v[72:75], v[0:15]
	v_mfma_f32_32x32x16_bf16 v[16:31], v[64:67], v[76:79], v[16:31]
	v_mfma_f32_32x32x16_bf16 v[0:15], v[68:71], v[220:223], v[0:15]
	v_mfma_f32_32x32x16_bf16 v[16:31], v[68:71], v[224:227], v[16:31]
	s_add_i32 s90, s76, 128
	v_add_u32_e32 v80, s90, v235
	v_add_u32_e32 v83, s90, v236
	v_add_u32_e32 v99, s90, v237
	v_add_u32_e32 v253, s90, v238
	v_add_u32_e32 v254, s90, v100
	v_add_u32_e32 v255, s90, v149
	v_med3_i32 v80, v80, 0, s99
	v_med3_i32 v83, v83, 0, s99
	v_med3_i32 v99, v99, 0, s99
	v_med3_i32 v253, v253, 0, s99
	v_med3_i32 v254, v254, 0, s99
	v_med3_i32 v255, v255, 0, s99
	v_mad_u32_u24 v80, v80, s100, v252
	v_mad_u32_u24 v83, v83, s100, v252
	v_mad_u32_u24 v99, v99, s100, v252
	v_mad_u32_u24 v253, v253, s100, v252
	v_mad_u32_u24 v254, v254, s100, v153
	v_mad_u32_u24 v255, v255, s100, v153
	global_load_dwordx4 v[116:119], v80, s[82:83]
	global_load_dwordx4 v[120:123], v83, s[82:83]
	global_load_dwordx4 v[124:127], v99, s[82:83]
	global_load_dwordx4 v[128:131], v253, s[82:83]
	global_load_dwordx4 v[132:135], v254, s[82:83] offset:768
	global_load_dwordx4 v[136:139], v255, s[82:83] offset:768
	global_load_dwordx4 v[140:143], v254, s[82:83] offset:832
	global_load_dwordx4 v[144:147], v255, s[82:83] offset:832
	s_waitcnt lgkmcnt(0)
	v_mfma_f32_32x32x16_bf16 v[32:47], v[156:159], v[48:51], v[32:47]
	ds_read_b64_tr_b16 v[72:73], v231
	ds_read_b64_tr_b16 v[74:75], v231 offset:512
	ds_read_b64_tr_b16 v[76:77], v231 offset:2048
	ds_read_b64_tr_b16 v[78:79], v231 offset:2560
	ds_read_b64_tr_b16 v[220:221], v231 offset:1024
	ds_read_b64_tr_b16 v[222:223], v231 offset:1536
	ds_read_b64_tr_b16 v[224:225], v231 offset:3072
	ds_read_b64_tr_b16 v[226:227], v231 offset:3584
	s_waitcnt vmcnt(8)
	ds_write_b128 v247, v[188:191]
	ds_write_b128 v247, v[192:195] offset:1024
	ds_write_b128 v247, v[196:199] offset:2048
	ds_write_b128 v247, v[200:203] offset:3072
	ds_read_b128 v[188:191], v248
	ds_read_b128 v[192:195], v249
	ds_read_b128 v[196:199], v250
	ds_read_b128 v[200:203], v251
	ds_write_b128 v112, v[204:207]
	ds_write_b128 v112, v[208:211] offset:1024
	ds_write_b128 v112, v[212:215] offset:2048
	ds_write_b128 v112, v[216:219] offset:3072
	v_mfma_f32_32x32x16_bf16 v[32:47], v[160:163], v[52:55], v[32:47]
	v_mfma_f32_32x32x16_bf16 v[32:47], v[164:167], v[56:59], v[32:47]
	v_mfma_f32_32x32x16_bf16 v[32:47], v[168:171], v[60:63], v[32:47]
	s_nop 11
	v_exp_f32_e32 v32, v32
	v_exp_f32_e32 v33, v33
	v_exp_f32_e32 v34, v34
	v_exp_f32_e32 v35, v35
	v_exp_f32_e32 v36, v36
	v_exp_f32_e32 v37, v37
	v_exp_f32_e32 v38, v38
	v_exp_f32_e32 v39, v39
	v_exp_f32_e32 v40, v40
	v_exp_f32_e32 v41, v41
	v_exp_f32_e32 v42, v42
	v_exp_f32_e32 v43, v43
	v_exp_f32_e32 v44, v44
	v_exp_f32_e32 v45, v45
	v_exp_f32_e32 v46, v46
	v_exp_f32_e32 v47, v47
	s_add_i32 s90, s76, 64
	v_add_u32_e32 v84, s90, v107
	v_add_u32_e32 v85, 0, v84
	v_add_u32_e32 v86, 1, v84
	v_add_u32_e32 v87, 2, v84
	v_add_u32_e32 v88, 3, v84
	v_cmp_gt_u32_e64 s[30:31], s98, v85
	v_cmp_gt_u32_e64 s[36:37], s98, v86
	v_cmp_gt_u32_e64 s[78:79], s98, v87
	v_cmp_gt_u32_e64 s[50:51], s98, v88
	v_cndmask_b32_e64 v32, 0, v32, s[30:31]
	v_add_u32_e32 v85, 8, v84
	v_cmp_gt_u32_e64 s[30:31], s98, v85
	v_cndmask_b32_e64 v33, 0, v33, s[36:37]
	v_add_u32_e32 v86, 9, v84
	v_cmp_gt_u32_e64 s[36:37], s98, v86
	v_cndmask_b32_e64 v34, 0, v34, s[78:79]
	v_add_u32_e32 v87, 10, v84
	v_cmp_gt_u32_e64 s[78:79], s98, v87
	v_cndmask_b32_e64 v35, 0, v35, s[50:51]
	v_add_u32_e32 v88, 11, v84
	v_cmp_gt_u32_e64 s[50:51], s98, v88
	v_cndmask_b32_e64 v36, 0, v36, s[30:31]
	v_add_u32_e32 v85, 16, v84
	v_cmp_gt_u32_e64 s[30:31], s98, v85
	v_cndmask_b32_e64 v37, 0, v37, s[36:37]
	v_add_u32_e32 v86, 17, v84
	v_cmp_gt_u32_e64 s[36:37], s98, v86
	v_cndmask_b32_e64 v38, 0, v38, s[78:79]
	v_add_u32_e32 v87, 18, v84
	v_cmp_gt_u32_e64 s[78:79], s98, v87
	v_cndmask_b32_e64 v39, 0, v39, s[50:51]
	v_add_u32_e32 v88, 19, v84
	v_cmp_gt_u32_e64 s[50:51], s98, v88
	v_cndmask_b32_e64 v40, 0, v40, s[30:31]
	v_add_u32_e32 v85, 24, v84
	v_cmp_gt_u32_e64 s[30:31], s98, v85
	v_cndmask_b32_e64 v41, 0, v41, s[36:37]
	v_add_u32_e32 v86, 25, v84
	v_cmp_gt_u32_e64 s[36:37], s98, v86
	v_cndmask_b32_e64 v42, 0, v42, s[78:79]
	v_add_u32_e32 v87, 26, v84
	v_cmp_gt_u32_e64 s[78:79], s98, v87
	v_cndmask_b32_e64 v43, 0, v43, s[50:51]
	v_add_u32_e32 v88, 27, v84
	v_cmp_gt_u32_e64 s[50:51], s98, v88
	v_nop
	v_cndmask_b32_e64 v44, 0, v44, s[30:31]
	v_cndmask_b32_e64 v45, 0, v45, s[36:37]
	v_cndmask_b32_e64 v46, 0, v46, s[78:79]
	v_cndmask_b32_e64 v47, 0, v47, s[50:51]
	v_cvt_pk_bf16_f32 v64, v32, v33
	v_cvt_pk_bf16_f32 v65, v34, v35
	v_cvt_pk_bf16_f32 v66, v36, v37
	v_cvt_pk_bf16_f32 v67, v38, v39
	v_cvt_pk_bf16_f32 v68, v40, v41
	v_cvt_pk_bf16_f32 v69, v42, v43
	v_cvt_pk_bf16_f32 v70, v44, v45
	v_cvt_pk_bf16_f32 v71, v46, v47
	v_pk_add_f32 v[232:233], v[232:233], v[32:33]
	v_pk_add_f32 v[232:233], v[232:233], v[34:35]
	v_pk_add_f32 v[232:233], v[232:233], v[36:37]
	v_pk_add_f32 v[232:233], v[232:233], v[38:39]
	v_pk_add_f32 v[232:233], v[232:233], v[40:41]
	v_pk_add_f32 v[232:233], v[232:233], v[42:43]
	v_pk_add_f32 v[232:233], v[232:233], v[44:45]
	v_pk_add_f32 v[232:233], v[232:233], v[46:47]
	ds_read2_b32 v[32:33], v115 offset0:170 offset1:171
	ds_read2_b32 v[34:35], v115 offset0:172 offset1:173
	ds_read2_b32 v[36:37], v115 offset0:178 offset1:179
	ds_read2_b32 v[38:39], v115 offset0:180 offset1:181
	ds_read2_b32 v[40:41], v115 offset0:187 offset1:188
	ds_read2_b32 v[42:43], v115 offset0:189 offset1:190
	ds_read2_b32 v[44:45], v115 offset0:195 offset1:196
	ds_read2_b32 v[46:47], v115 offset0:197 offset1:198
	s_waitcnt lgkmcnt(15)
	v_mfma_f32_32x32x16_bf16 v[0:15], v[64:67], v[72:75], v[0:15]
	v_mfma_f32_32x32x16_bf16 v[16:31], v[64:67], v[76:79], v[16:31]
	v_mfma_f32_32x32x16_bf16 v[0:15], v[68:71], v[220:223], v[0:15]
	v_mfma_f32_32x32x16_bf16 v[16:31], v[68:71], v[224:227], v[16:31]
	s_add_i32 s90, s76, 160
	v_add_u32_e32 v80, s90, v235
	v_add_u32_e32 v83, s90, v236
	v_add_u32_e32 v99, s90, v237
	v_add_u32_e32 v253, s90, v238
	v_add_u32_e32 v254, s90, v100
	v_add_u32_e32 v255, s90, v149
	v_med3_i32 v80, v80, 0, s99
	v_med3_i32 v83, v83, 0, s99
	v_med3_i32 v99, v99, 0, s99
	v_med3_i32 v253, v253, 0, s99
	v_med3_i32 v254, v254, 0, s99
	v_med3_i32 v255, v255, 0, s99
	v_mad_u32_u24 v80, v80, s100, v252
	v_mad_u32_u24 v83, v83, s100, v252
	v_mad_u32_u24 v99, v99, s100, v252
	v_mad_u32_u24 v253, v253, s100, v252
	v_mad_u32_u24 v254, v254, s100, v153
	v_mad_u32_u24 v255, v255, s100, v153
	global_load_dwordx4 v[156:159], v80, s[82:83]
	global_load_dwordx4 v[160:163], v83, s[82:83]
	global_load_dwordx4 v[164:167], v99, s[82:83]
	global_load_dwordx4 v[168:171], v253, s[82:83]
	global_load_dwordx4 v[172:175], v254, s[82:83] offset:768
	global_load_dwordx4 v[176:179], v255, s[82:83] offset:768
	global_load_dwordx4 v[180:183], v254, s[82:83] offset:832
	global_load_dwordx4 v[184:187], v255, s[82:83] offset:832
	s_waitcnt lgkmcnt(0)
	v_mfma_f32_32x32x16_bf16 v[32:47], v[188:191], v[48:51], v[32:47]
	ds_read_b64_tr_b16 v[72:73], v231
	ds_read_b64_tr_b16 v[74:75], v231 offset:512
	ds_read_b64_tr_b16 v[76:77], v231 offset:2048
	ds_read_b64_tr_b16 v[78:79], v231 offset:2560
	ds_read_b64_tr_b16 v[220:221], v231 offset:1024
	ds_read_b64_tr_b16 v[222:223], v231 offset:1536
	ds_read_b64_tr_b16 v[224:225], v231 offset:3072
	ds_read_b64_tr_b16 v[226:227], v231 offset:3584
	s_waitcnt vmcnt(8)
	ds_write_b128 v247, v[116:119]
	ds_write_b128 v247, v[120:123] offset:1024
	ds_write_b128 v247, v[124:127] offset:2048
	ds_write_b128 v247, v[128:131] offset:3072
	ds_read_b128 v[116:119], v248
	ds_read_b128 v[120:123], v249
	ds_read_b128 v[124:127], v250
	ds_read_b128 v[128:131], v251
	ds_write_b128 v112, v[132:135]
	ds_write_b128 v112, v[136:139] offset:1024
	ds_write_b128 v112, v[140:143] offset:2048
	ds_write_b128 v112, v[144:147] offset:3072
	v_mfma_f32_32x32x16_bf16 v[32:47], v[192:195], v[52:55], v[32:47]
	v_mfma_f32_32x32x16_bf16 v[32:47], v[196:199], v[56:59], v[32:47]
	v_mfma_f32_32x32x16_bf16 v[32:47], v[200:203], v[60:63], v[32:47]
	s_nop 11
	v_exp_f32_e32 v32, v32
	v_exp_f32_e32 v33, v33
	v_exp_f32_e32 v34, v34
	v_exp_f32_e32 v35, v35
	v_exp_f32_e32 v36, v36
	v_exp_f32_e32 v37, v37
	v_exp_f32_e32 v38, v38
	v_exp_f32_e32 v39, v39
	v_exp_f32_e32 v40, v40
	v_exp_f32_e32 v41, v41
	v_exp_f32_e32 v42, v42
	v_exp_f32_e32 v43, v43
	v_exp_f32_e32 v44, v44
	v_exp_f32_e32 v45, v45
	v_exp_f32_e32 v46, v46
	v_exp_f32_e32 v47, v47
	s_add_i32 s90, s76, 96
	v_add_u32_e32 v84, s90, v107
	v_add_u32_e32 v85, 0, v84
	v_add_u32_e32 v86, 1, v84
	v_add_u32_e32 v87, 2, v84
	v_add_u32_e32 v88, 3, v84
	v_cmp_gt_u32_e64 s[30:31], s98, v85
	v_cmp_gt_u32_e64 s[36:37], s98, v86
	v_cmp_gt_u32_e64 s[78:79], s98, v87
	v_cmp_gt_u32_e64 s[50:51], s98, v88
	v_cndmask_b32_e64 v32, 0, v32, s[30:31]
	v_add_u32_e32 v85, 8, v84
	v_cmp_gt_u32_e64 s[30:31], s98, v85
	v_cndmask_b32_e64 v33, 0, v33, s[36:37]
	v_add_u32_e32 v86, 9, v84
	v_cmp_gt_u32_e64 s[36:37], s98, v86
	v_cndmask_b32_e64 v34, 0, v34, s[78:79]
	v_add_u32_e32 v87, 10, v84
	v_cmp_gt_u32_e64 s[78:79], s98, v87
	v_cndmask_b32_e64 v35, 0, v35, s[50:51]
	v_add_u32_e32 v88, 11, v84
	v_cmp_gt_u32_e64 s[50:51], s98, v88
	v_cndmask_b32_e64 v36, 0, v36, s[30:31]
	v_add_u32_e32 v85, 16, v84
	v_cmp_gt_u32_e64 s[30:31], s98, v85
	v_cndmask_b32_e64 v37, 0, v37, s[36:37]
	v_add_u32_e32 v86, 17, v84
	v_cmp_gt_u32_e64 s[36:37], s98, v86
	v_cndmask_b32_e64 v38, 0, v38, s[78:79]
	v_add_u32_e32 v87, 18, v84
	v_cmp_gt_u32_e64 s[78:79], s98, v87
	v_cndmask_b32_e64 v39, 0, v39, s[50:51]
	v_add_u32_e32 v88, 19, v84
	v_cmp_gt_u32_e64 s[50:51], s98, v88
	v_cndmask_b32_e64 v40, 0, v40, s[30:31]
	v_add_u32_e32 v85, 24, v84
	v_cmp_gt_u32_e64 s[30:31], s98, v85
	v_cndmask_b32_e64 v41, 0, v41, s[36:37]
	v_add_u32_e32 v86, 25, v84
	v_cmp_gt_u32_e64 s[36:37], s98, v86
	v_cndmask_b32_e64 v42, 0, v42, s[78:79]
	v_add_u32_e32 v87, 26, v84
	v_cmp_gt_u32_e64 s[78:79], s98, v87
	v_cndmask_b32_e64 v43, 0, v43, s[50:51]
	v_add_u32_e32 v88, 27, v84
	v_cmp_gt_u32_e64 s[50:51], s98, v88
	v_nop
	v_cndmask_b32_e64 v44, 0, v44, s[30:31]
	v_cndmask_b32_e64 v45, 0, v45, s[36:37]
	v_cndmask_b32_e64 v46, 0, v46, s[78:79]
	v_cndmask_b32_e64 v47, 0, v47, s[50:51]
	v_cvt_pk_bf16_f32 v64, v32, v33
	v_cvt_pk_bf16_f32 v65, v34, v35
	v_cvt_pk_bf16_f32 v66, v36, v37
	v_cvt_pk_bf16_f32 v67, v38, v39
	v_cvt_pk_bf16_f32 v68, v40, v41
	v_cvt_pk_bf16_f32 v69, v42, v43
	v_cvt_pk_bf16_f32 v70, v44, v45
	v_cvt_pk_bf16_f32 v71, v46, v47
	v_pk_add_f32 v[232:233], v[232:233], v[32:33]
	v_pk_add_f32 v[232:233], v[232:233], v[34:35]
	v_pk_add_f32 v[232:233], v[232:233], v[36:37]
	v_pk_add_f32 v[232:233], v[232:233], v[38:39]
	v_pk_add_f32 v[232:233], v[232:233], v[40:41]
	v_pk_add_f32 v[232:233], v[232:233], v[42:43]
	v_pk_add_f32 v[232:233], v[232:233], v[44:45]
	v_pk_add_f32 v[232:233], v[232:233], v[46:47]
	ds_read2_b32 v[32:33], v115 offset0:204 offset1:205
	ds_read2_b32 v[34:35], v115 offset0:206 offset1:207
	ds_read2_b32 v[36:37], v115 offset0:212 offset1:213
	ds_read2_b32 v[38:39], v115 offset0:214 offset1:215
	ds_read2_b32 v[40:41], v115 offset0:221 offset1:222
	ds_read2_b32 v[42:43], v115 offset0:223 offset1:224
	ds_read2_b32 v[44:45], v115 offset0:229 offset1:230
	ds_read2_b32 v[46:47], v115 offset0:231 offset1:232
	s_waitcnt lgkmcnt(15)
	v_mfma_f32_32x32x16_bf16 v[0:15], v[64:67], v[72:75], v[0:15]
	v_mfma_f32_32x32x16_bf16 v[16:31], v[64:67], v[76:79], v[16:31]
	v_mfma_f32_32x32x16_bf16 v[0:15], v[68:71], v[220:223], v[0:15]
	v_mfma_f32_32x32x16_bf16 v[16:31], v[68:71], v[224:227], v[16:31]
	s_add_i32 s90, s76, 192
	v_add_u32_e32 v80, s90, v235
	v_add_u32_e32 v83, s90, v236
	v_add_u32_e32 v99, s90, v237
	v_add_u32_e32 v253, s90, v238
	v_add_u32_e32 v254, s90, v100
	v_add_u32_e32 v255, s90, v149
	v_med3_i32 v80, v80, 0, s99
	v_med3_i32 v83, v83, 0, s99
	v_med3_i32 v99, v99, 0, s99
	v_med3_i32 v253, v253, 0, s99
	v_med3_i32 v254, v254, 0, s99
	v_med3_i32 v255, v255, 0, s99
	v_mad_u32_u24 v80, v80, s100, v252
	v_mad_u32_u24 v83, v83, s100, v252
	v_mad_u32_u24 v99, v99, s100, v252
	v_mad_u32_u24 v253, v253, s100, v252
	v_mad_u32_u24 v254, v254, s100, v153
	v_mad_u32_u24 v255, v255, s100, v153
	global_load_dwordx4 v[188:191], v80, s[82:83]
	global_load_dwordx4 v[192:195], v83, s[82:83]
	global_load_dwordx4 v[196:199], v99, s[82:83]
	global_load_dwordx4 v[200:203], v253, s[82:83]
	global_load_dwordx4 v[204:207], v254, s[82:83] offset:768
	global_load_dwordx4 v[208:211], v255, s[82:83] offset:768
	global_load_dwordx4 v[212:215], v254, s[82:83] offset:832
	global_load_dwordx4 v[216:219], v255, s[82:83] offset:832
	s_waitcnt lgkmcnt(0)
	v_mfma_f32_32x32x16_bf16 v[32:47], v[116:119], v[48:51], v[32:47]
	ds_read_b64_tr_b16 v[72:73], v231
	ds_read_b64_tr_b16 v[74:75], v231 offset:512
	ds_read_b64_tr_b16 v[76:77], v231 offset:2048
	ds_read_b64_tr_b16 v[78:79], v231 offset:2560
	ds_read_b64_tr_b16 v[220:221], v231 offset:1024
	ds_read_b64_tr_b16 v[222:223], v231 offset:1536
	ds_read_b64_tr_b16 v[224:225], v231 offset:3072
	ds_read_b64_tr_b16 v[226:227], v231 offset:3584
	s_waitcnt vmcnt(8)
	ds_write_b128 v247, v[156:159]
	ds_write_b128 v247, v[160:163] offset:1024
	ds_write_b128 v247, v[164:167] offset:2048
	ds_write_b128 v247, v[168:171] offset:3072
	ds_read_b128 v[156:159], v248
	ds_read_b128 v[160:163], v249
	ds_read_b128 v[164:167], v250
	ds_read_b128 v[168:171], v251
	ds_write_b128 v112, v[172:175]
	ds_write_b128 v112, v[176:179] offset:1024
	ds_write_b128 v112, v[180:183] offset:2048
	ds_write_b128 v112, v[184:187] offset:3072
	v_mfma_f32_32x32x16_bf16 v[32:47], v[120:123], v[52:55], v[32:47]
	v_mfma_f32_32x32x16_bf16 v[32:47], v[124:127], v[56:59], v[32:47]
	v_mfma_f32_32x32x16_bf16 v[32:47], v[128:131], v[60:63], v[32:47]
	s_nop 11
	v_exp_f32_e32 v32, v32
	v_exp_f32_e32 v33, v33
	v_exp_f32_e32 v34, v34
	v_exp_f32_e32 v35, v35
	v_exp_f32_e32 v36, v36
	v_exp_f32_e32 v37, v37
	v_exp_f32_e32 v38, v38
	v_exp_f32_e32 v39, v39
	v_exp_f32_e32 v40, v40
	v_exp_f32_e32 v41, v41
	v_exp_f32_e32 v42, v42
	v_exp_f32_e32 v43, v43
	v_exp_f32_e32 v44, v44
	v_exp_f32_e32 v45, v45
	v_exp_f32_e32 v46, v46
	v_exp_f32_e32 v47, v47
	s_add_i32 s90, s76, 128
	v_add_u32_e32 v84, s90, v107
	v_add_u32_e32 v85, 0, v84
	v_add_u32_e32 v86, 1, v84
	v_add_u32_e32 v87, 2, v84
	v_add_u32_e32 v88, 3, v84
	v_cmp_gt_u32_e64 s[30:31], s98, v85
	v_cmp_gt_u32_e64 s[36:37], s98, v86
	v_cmp_gt_u32_e64 s[78:79], s98, v87
	v_cmp_gt_u32_e64 s[50:51], s98, v88
	v_cndmask_b32_e64 v32, 0, v32, s[30:31]
	v_add_u32_e32 v85, 8, v84
	v_cmp_gt_u32_e64 s[30:31], s98, v85
	v_cndmask_b32_e64 v33, 0, v33, s[36:37]
	v_add_u32_e32 v86, 9, v84
	v_cmp_gt_u32_e64 s[36:37], s98, v86
	v_cndmask_b32_e64 v34, 0, v34, s[78:79]
	v_add_u32_e32 v87, 10, v84
	v_cmp_gt_u32_e64 s[78:79], s98, v87
	v_cndmask_b32_e64 v35, 0, v35, s[50:51]
	v_add_u32_e32 v88, 11, v84
	v_cmp_gt_u32_e64 s[50:51], s98, v88
	v_cndmask_b32_e64 v36, 0, v36, s[30:31]
	v_add_u32_e32 v85, 16, v84
	v_cmp_gt_u32_e64 s[30:31], s98, v85
	v_cndmask_b32_e64 v37, 0, v37, s[36:37]
	v_add_u32_e32 v86, 17, v84
	v_cmp_gt_u32_e64 s[36:37], s98, v86
	v_cndmask_b32_e64 v38, 0, v38, s[78:79]
	v_add_u32_e32 v87, 18, v84
	v_cmp_gt_u32_e64 s[78:79], s98, v87
	v_cndmask_b32_e64 v39, 0, v39, s[50:51]
	v_add_u32_e32 v88, 19, v84
	v_cmp_gt_u32_e64 s[50:51], s98, v88
	v_cndmask_b32_e64 v40, 0, v40, s[30:31]
	v_add_u32_e32 v85, 24, v84
	v_cmp_gt_u32_e64 s[30:31], s98, v85
	v_cndmask_b32_e64 v41, 0, v41, s[36:37]
	v_add_u32_e32 v86, 25, v84
	v_cmp_gt_u32_e64 s[36:37], s98, v86
	v_cndmask_b32_e64 v42, 0, v42, s[78:79]
	v_add_u32_e32 v87, 26, v84
	v_cmp_gt_u32_e64 s[78:79], s98, v87
	v_cndmask_b32_e64 v43, 0, v43, s[50:51]
	v_add_u32_e32 v88, 27, v84
	v_cmp_gt_u32_e64 s[50:51], s98, v88
	v_nop
	v_cndmask_b32_e64 v44, 0, v44, s[30:31]
	v_cndmask_b32_e64 v45, 0, v45, s[36:37]
	v_cndmask_b32_e64 v46, 0, v46, s[78:79]
	v_cndmask_b32_e64 v47, 0, v47, s[50:51]
	v_cvt_pk_bf16_f32 v64, v32, v33
	v_cvt_pk_bf16_f32 v65, v34, v35
	v_cvt_pk_bf16_f32 v66, v36, v37
	v_cvt_pk_bf16_f32 v67, v38, v39
	v_cvt_pk_bf16_f32 v68, v40, v41
	v_cvt_pk_bf16_f32 v69, v42, v43
	v_cvt_pk_bf16_f32 v70, v44, v45
	v_cvt_pk_bf16_f32 v71, v46, v47
	v_pk_add_f32 v[232:233], v[232:233], v[32:33]
	v_pk_add_f32 v[232:233], v[232:233], v[34:35]
	v_pk_add_f32 v[232:233], v[232:233], v[36:37]
	v_pk_add_f32 v[232:233], v[232:233], v[38:39]
	v_pk_add_f32 v[232:233], v[232:233], v[40:41]
	v_pk_add_f32 v[232:233], v[232:233], v[42:43]
	v_pk_add_f32 v[232:233], v[232:233], v[44:45]
	v_pk_add_f32 v[232:233], v[232:233], v[46:47]
	v_add_u32_e32 v115, 952, v115
	ds_read2_b32 v[32:33], v115 offset0:0 offset1:1
	ds_read2_b32 v[34:35], v115 offset0:2 offset1:3
	ds_read2_b32 v[36:37], v115 offset0:8 offset1:9
	ds_read2_b32 v[38:39], v115 offset0:10 offset1:11
	ds_read2_b32 v[40:41], v115 offset0:17 offset1:18
	ds_read2_b32 v[42:43], v115 offset0:19 offset1:20
	ds_read2_b32 v[44:45], v115 offset0:25 offset1:26
	ds_read2_b32 v[46:47], v115 offset0:27 offset1:28
	s_waitcnt lgkmcnt(15)
	v_mfma_f32_32x32x16_bf16 v[0:15], v[64:67], v[72:75], v[0:15]
	v_mfma_f32_32x32x16_bf16 v[16:31], v[64:67], v[76:79], v[16:31]
	v_mfma_f32_32x32x16_bf16 v[0:15], v[68:71], v[220:223], v[0:15]
	v_mfma_f32_32x32x16_bf16 v[16:31], v[68:71], v[224:227], v[16:31]
	s_add_i32 s90, s76, 224
	v_add_u32_e32 v80, s90, v235
	v_add_u32_e32 v83, s90, v236
	v_add_u32_e32 v99, s90, v237
	v_add_u32_e32 v253, s90, v238
	v_add_u32_e32 v254, s90, v100
	v_add_u32_e32 v255, s90, v149
	v_med3_i32 v80, v80, 0, s99
	v_med3_i32 v83, v83, 0, s99
	v_med3_i32 v99, v99, 0, s99
	v_med3_i32 v253, v253, 0, s99
	v_med3_i32 v254, v254, 0, s99
	v_med3_i32 v255, v255, 0, s99
	v_mad_u32_u24 v80, v80, s100, v252
	v_mad_u32_u24 v83, v83, s100, v252
	v_mad_u32_u24 v99, v99, s100, v252
	v_mad_u32_u24 v253, v253, s100, v252
	v_mad_u32_u24 v254, v254, s100, v153
	v_mad_u32_u24 v255, v255, s100, v153
	global_load_dwordx4 v[116:119], v80, s[82:83]
	global_load_dwordx4 v[120:123], v83, s[82:83]
	global_load_dwordx4 v[124:127], v99, s[82:83]
	global_load_dwordx4 v[128:131], v253, s[82:83]
	global_load_dwordx4 v[132:135], v254, s[82:83] offset:768
	global_load_dwordx4 v[136:139], v255, s[82:83] offset:768
	global_load_dwordx4 v[140:143], v254, s[82:83] offset:832
	global_load_dwordx4 v[144:147], v255, s[82:83] offset:832
	s_waitcnt lgkmcnt(0)
	v_mfma_f32_32x32x16_bf16 v[32:47], v[156:159], v[48:51], v[32:47]
	ds_read_b64_tr_b16 v[72:73], v231
	ds_read_b64_tr_b16 v[74:75], v231 offset:512
	ds_read_b64_tr_b16 v[76:77], v231 offset:2048
	ds_read_b64_tr_b16 v[78:79], v231 offset:2560
	ds_read_b64_tr_b16 v[220:221], v231 offset:1024
	ds_read_b64_tr_b16 v[222:223], v231 offset:1536
	ds_read_b64_tr_b16 v[224:225], v231 offset:3072
	ds_read_b64_tr_b16 v[226:227], v231 offset:3584
	s_waitcnt vmcnt(8)
	ds_write_b128 v247, v[188:191]
	ds_write_b128 v247, v[192:195] offset:1024
	ds_write_b128 v247, v[196:199] offset:2048
	ds_write_b128 v247, v[200:203] offset:3072
	ds_read_b128 v[188:191], v248
	ds_read_b128 v[192:195], v249
	ds_read_b128 v[196:199], v250
	ds_read_b128 v[200:203], v251
	ds_write_b128 v112, v[204:207]
	ds_write_b128 v112, v[208:211] offset:1024
	ds_write_b128 v112, v[212:215] offset:2048
	ds_write_b128 v112, v[216:219] offset:3072
	v_mfma_f32_32x32x16_bf16 v[32:47], v[160:163], v[52:55], v[32:47]
	v_mfma_f32_32x32x16_bf16 v[32:47], v[164:167], v[56:59], v[32:47]
	v_mfma_f32_32x32x16_bf16 v[32:47], v[168:171], v[60:63], v[32:47]
	s_nop 11
	v_exp_f32_e32 v32, v32
	v_exp_f32_e32 v33, v33
	v_exp_f32_e32 v34, v34
	v_exp_f32_e32 v35, v35
	v_exp_f32_e32 v36, v36
	v_exp_f32_e32 v37, v37
	v_exp_f32_e32 v38, v38
	v_exp_f32_e32 v39, v39
	v_exp_f32_e32 v40, v40
	v_exp_f32_e32 v41, v41
	v_exp_f32_e32 v42, v42
	v_exp_f32_e32 v43, v43
	v_exp_f32_e32 v44, v44
	v_exp_f32_e32 v45, v45
	v_exp_f32_e32 v46, v46
	v_exp_f32_e32 v47, v47
	s_add_i32 s90, s76, 160
	v_add_u32_e32 v84, s90, v107
	v_add_u32_e32 v85, 0, v84
	v_add_u32_e32 v86, 1, v84
	v_add_u32_e32 v87, 2, v84
	v_add_u32_e32 v88, 3, v84
	v_cmp_gt_u32_e64 s[30:31], s98, v85
	v_cmp_gt_u32_e64 s[36:37], s98, v86
	v_cmp_gt_u32_e64 s[78:79], s98, v87
	v_cmp_gt_u32_e64 s[50:51], s98, v88
	v_cndmask_b32_e64 v32, 0, v32, s[30:31]
	v_add_u32_e32 v85, 8, v84
	v_cmp_gt_u32_e64 s[30:31], s98, v85
	v_cndmask_b32_e64 v33, 0, v33, s[36:37]
	v_add_u32_e32 v86, 9, v84
	v_cmp_gt_u32_e64 s[36:37], s98, v86
	v_cndmask_b32_e64 v34, 0, v34, s[78:79]
	v_add_u32_e32 v87, 10, v84
	v_cmp_gt_u32_e64 s[78:79], s98, v87
	v_cndmask_b32_e64 v35, 0, v35, s[50:51]
	v_add_u32_e32 v88, 11, v84
	v_cmp_gt_u32_e64 s[50:51], s98, v88
	v_cndmask_b32_e64 v36, 0, v36, s[30:31]
	v_add_u32_e32 v85, 16, v84
	v_cmp_gt_u32_e64 s[30:31], s98, v85
	v_cndmask_b32_e64 v37, 0, v37, s[36:37]
	v_add_u32_e32 v86, 17, v84
	v_cmp_gt_u32_e64 s[36:37], s98, v86
	v_cndmask_b32_e64 v38, 0, v38, s[78:79]
	v_add_u32_e32 v87, 18, v84
	v_cmp_gt_u32_e64 s[78:79], s98, v87
	v_cndmask_b32_e64 v39, 0, v39, s[50:51]
	v_add_u32_e32 v88, 19, v84
	v_cmp_gt_u32_e64 s[50:51], s98, v88
	v_cndmask_b32_e64 v40, 0, v40, s[30:31]
	v_add_u32_e32 v85, 24, v84
	v_cmp_gt_u32_e64 s[30:31], s98, v85
	v_cndmask_b32_e64 v41, 0, v41, s[36:37]
	v_add_u32_e32 v86, 25, v84
	v_cmp_gt_u32_e64 s[36:37], s98, v86
	v_cndmask_b32_e64 v42, 0, v42, s[78:79]
	v_add_u32_e32 v87, 26, v84
	v_cmp_gt_u32_e64 s[78:79], s98, v87
	v_cndmask_b32_e64 v43, 0, v43, s[50:51]
	v_add_u32_e32 v88, 27, v84
	v_cmp_gt_u32_e64 s[50:51], s98, v88
	v_nop
	v_cndmask_b32_e64 v44, 0, v44, s[30:31]
	v_cndmask_b32_e64 v45, 0, v45, s[36:37]
	v_cndmask_b32_e64 v46, 0, v46, s[78:79]
	v_cndmask_b32_e64 v47, 0, v47, s[50:51]
	v_cvt_pk_bf16_f32 v64, v32, v33
	v_cvt_pk_bf16_f32 v65, v34, v35
	v_cvt_pk_bf16_f32 v66, v36, v37
	v_cvt_pk_bf16_f32 v67, v38, v39
	v_cvt_pk_bf16_f32 v68, v40, v41
	v_cvt_pk_bf16_f32 v69, v42, v43
	v_cvt_pk_bf16_f32 v70, v44, v45
	v_cvt_pk_bf16_f32 v71, v46, v47
	v_pk_add_f32 v[232:233], v[232:233], v[32:33]
	v_pk_add_f32 v[232:233], v[232:233], v[34:35]
	v_pk_add_f32 v[232:233], v[232:233], v[36:37]
	v_pk_add_f32 v[232:233], v[232:233], v[38:39]
	v_pk_add_f32 v[232:233], v[232:233], v[40:41]
	v_pk_add_f32 v[232:233], v[232:233], v[42:43]
	v_pk_add_f32 v[232:233], v[232:233], v[44:45]
	v_pk_add_f32 v[232:233], v[232:233], v[46:47]
	ds_read2_b32 v[32:33], v115 offset0:34 offset1:35
	ds_read2_b32 v[34:35], v115 offset0:36 offset1:37
	ds_read2_b32 v[36:37], v115 offset0:42 offset1:43
	ds_read2_b32 v[38:39], v115 offset0:44 offset1:45
	ds_read2_b32 v[40:41], v115 offset0:51 offset1:52
	ds_read2_b32 v[42:43], v115 offset0:53 offset1:54
	ds_read2_b32 v[44:45], v115 offset0:59 offset1:60
	ds_read2_b32 v[46:47], v115 offset0:61 offset1:62
	s_waitcnt lgkmcnt(15)
	v_mfma_f32_32x32x16_bf16 v[0:15], v[64:67], v[72:75], v[0:15]
	v_mfma_f32_32x32x16_bf16 v[16:31], v[64:67], v[76:79], v[16:31]
	v_mfma_f32_32x32x16_bf16 v[0:15], v[68:71], v[220:223], v[0:15]
	v_mfma_f32_32x32x16_bf16 v[16:31], v[68:71], v[224:227], v[16:31]
	s_add_i32 s90, s76, 256
	v_add_u32_e32 v80, s90, v235
	v_add_u32_e32 v83, s90, v236
	v_add_u32_e32 v99, s90, v237
	v_add_u32_e32 v253, s90, v238
	v_add_u32_e32 v254, s90, v100
	v_add_u32_e32 v255, s90, v149
	v_med3_i32 v80, v80, 0, s99
	v_med3_i32 v83, v83, 0, s99
	v_med3_i32 v99, v99, 0, s99
	v_med3_i32 v253, v253, 0, s99
	v_med3_i32 v254, v254, 0, s99
	v_med3_i32 v255, v255, 0, s99
	v_mad_u32_u24 v80, v80, s100, v252
	v_mad_u32_u24 v83, v83, s100, v252
	v_mad_u32_u24 v99, v99, s100, v252
	v_mad_u32_u24 v253, v253, s100, v252
	v_mad_u32_u24 v254, v254, s100, v153
	v_mad_u32_u24 v255, v255, s100, v153
	global_load_dwordx4 v[156:159], v80, s[82:83]
	global_load_dwordx4 v[160:163], v83, s[82:83]
	global_load_dwordx4 v[164:167], v99, s[82:83]
	global_load_dwordx4 v[168:171], v253, s[82:83]
	global_load_dwordx4 v[172:175], v254, s[82:83] offset:768
	global_load_dwordx4 v[176:179], v255, s[82:83] offset:768
	global_load_dwordx4 v[180:183], v254, s[82:83] offset:832
	global_load_dwordx4 v[184:187], v255, s[82:83] offset:832
	s_waitcnt lgkmcnt(0)
	v_mfma_f32_32x32x16_bf16 v[32:47], v[188:191], v[48:51], v[32:47]
	ds_read_b64_tr_b16 v[72:73], v231
	ds_read_b64_tr_b16 v[74:75], v231 offset:512
	ds_read_b64_tr_b16 v[76:77], v231 offset:2048
	ds_read_b64_tr_b16 v[78:79], v231 offset:2560
	ds_read_b64_tr_b16 v[220:221], v231 offset:1024
	ds_read_b64_tr_b16 v[222:223], v231 offset:1536
	ds_read_b64_tr_b16 v[224:225], v231 offset:3072
	ds_read_b64_tr_b16 v[226:227], v231 offset:3584
	s_waitcnt vmcnt(8)
	ds_write_b128 v247, v[116:119]
	ds_write_b128 v247, v[120:123] offset:1024
	ds_write_b128 v247, v[124:127] offset:2048
	ds_write_b128 v247, v[128:131] offset:3072
	ds_read_b128 v[116:119], v248
	ds_read_b128 v[120:123], v249
	ds_read_b128 v[124:127], v250
	ds_read_b128 v[128:131], v251
	ds_write_b128 v112, v[132:135]
	ds_write_b128 v112, v[136:139] offset:1024
	ds_write_b128 v112, v[140:143] offset:2048
	ds_write_b128 v112, v[144:147] offset:3072
	v_mfma_f32_32x32x16_bf16 v[32:47], v[192:195], v[52:55], v[32:47]
	v_mfma_f32_32x32x16_bf16 v[32:47], v[196:199], v[56:59], v[32:47]
	v_mfma_f32_32x32x16_bf16 v[32:47], v[200:203], v[60:63], v[32:47]
	s_nop 11
	v_exp_f32_e32 v32, v32
	v_exp_f32_e32 v33, v33
	v_exp_f32_e32 v34, v34
	v_exp_f32_e32 v35, v35
	v_exp_f32_e32 v36, v36
	v_exp_f32_e32 v37, v37
	v_exp_f32_e32 v38, v38
	v_exp_f32_e32 v39, v39
	v_exp_f32_e32 v40, v40
	v_exp_f32_e32 v41, v41
	v_exp_f32_e32 v42, v42
	v_exp_f32_e32 v43, v43
	v_exp_f32_e32 v44, v44
	v_exp_f32_e32 v45, v45
	v_exp_f32_e32 v46, v46
	v_exp_f32_e32 v47, v47
	s_add_i32 s90, s76, 192
	v_add_u32_e32 v84, s90, v107
	v_add_u32_e32 v85, 0, v84
	v_add_u32_e32 v86, 1, v84
	v_add_u32_e32 v87, 2, v84
	v_add_u32_e32 v88, 3, v84
	v_cmp_gt_u32_e64 s[30:31], s98, v85
	v_cmp_gt_u32_e64 s[36:37], s98, v86
	v_cmp_gt_u32_e64 s[78:79], s98, v87
	v_cmp_gt_u32_e64 s[50:51], s98, v88
	v_cndmask_b32_e64 v32, 0, v32, s[30:31]
	v_add_u32_e32 v85, 8, v84
	v_cmp_gt_u32_e64 s[30:31], s98, v85
	v_cndmask_b32_e64 v33, 0, v33, s[36:37]
	v_add_u32_e32 v86, 9, v84
	v_cmp_gt_u32_e64 s[36:37], s98, v86
	v_cndmask_b32_e64 v34, 0, v34, s[78:79]
	v_add_u32_e32 v87, 10, v84
	v_cmp_gt_u32_e64 s[78:79], s98, v87
	v_cndmask_b32_e64 v35, 0, v35, s[50:51]
	v_add_u32_e32 v88, 11, v84
	v_cmp_gt_u32_e64 s[50:51], s98, v88
	v_cndmask_b32_e64 v36, 0, v36, s[30:31]
	v_add_u32_e32 v85, 16, v84
	v_cmp_gt_u32_e64 s[30:31], s98, v85
	v_cndmask_b32_e64 v37, 0, v37, s[36:37]
	v_add_u32_e32 v86, 17, v84
	v_cmp_gt_u32_e64 s[36:37], s98, v86
	v_cndmask_b32_e64 v38, 0, v38, s[78:79]
	v_add_u32_e32 v87, 18, v84
	v_cmp_gt_u32_e64 s[78:79], s98, v87
	v_cndmask_b32_e64 v39, 0, v39, s[50:51]
	v_add_u32_e32 v88, 19, v84
	v_cmp_gt_u32_e64 s[50:51], s98, v88
	v_cndmask_b32_e64 v40, 0, v40, s[30:31]
	v_add_u32_e32 v85, 24, v84
	v_cmp_gt_u32_e64 s[30:31], s98, v85
	v_cndmask_b32_e64 v41, 0, v41, s[36:37]
	v_add_u32_e32 v86, 25, v84
	v_cmp_gt_u32_e64 s[36:37], s98, v86
	v_cndmask_b32_e64 v42, 0, v42, s[78:79]
	v_add_u32_e32 v87, 26, v84
	v_cmp_gt_u32_e64 s[78:79], s98, v87
	v_cndmask_b32_e64 v43, 0, v43, s[50:51]
	v_add_u32_e32 v88, 27, v84
	v_cmp_gt_u32_e64 s[50:51], s98, v88
	v_nop
	v_cndmask_b32_e64 v44, 0, v44, s[30:31]
	v_cndmask_b32_e64 v45, 0, v45, s[36:37]
	v_cndmask_b32_e64 v46, 0, v46, s[78:79]
	v_cndmask_b32_e64 v47, 0, v47, s[50:51]
	v_cvt_pk_bf16_f32 v64, v32, v33
	v_cvt_pk_bf16_f32 v65, v34, v35
	v_cvt_pk_bf16_f32 v66, v36, v37
	v_cvt_pk_bf16_f32 v67, v38, v39
	v_cvt_pk_bf16_f32 v68, v40, v41
	v_cvt_pk_bf16_f32 v69, v42, v43
	v_cvt_pk_bf16_f32 v70, v44, v45
	v_cvt_pk_bf16_f32 v71, v46, v47
	v_pk_add_f32 v[232:233], v[232:233], v[32:33]
	v_pk_add_f32 v[232:233], v[232:233], v[34:35]
	v_pk_add_f32 v[232:233], v[232:233], v[36:37]
	v_pk_add_f32 v[232:233], v[232:233], v[38:39]
	v_pk_add_f32 v[232:233], v[232:233], v[40:41]
	v_pk_add_f32 v[232:233], v[232:233], v[42:43]
	v_pk_add_f32 v[232:233], v[232:233], v[44:45]
	v_pk_add_f32 v[232:233], v[232:233], v[46:47]
	ds_read2_b32 v[32:33], v115 offset0:68 offset1:69
	ds_read2_b32 v[34:35], v115 offset0:70 offset1:71
	ds_read2_b32 v[36:37], v115 offset0:76 offset1:77
	ds_read2_b32 v[38:39], v115 offset0:78 offset1:79
	ds_read2_b32 v[40:41], v115 offset0:85 offset1:86
	ds_read2_b32 v[42:43], v115 offset0:87 offset1:88
	ds_read2_b32 v[44:45], v115 offset0:93 offset1:94
	ds_read2_b32 v[46:47], v115 offset0:95 offset1:96
	s_waitcnt lgkmcnt(15)
	v_mfma_f32_32x32x16_bf16 v[0:15], v[64:67], v[72:75], v[0:15]
	v_mfma_f32_32x32x16_bf16 v[16:31], v[64:67], v[76:79], v[16:31]
	v_mfma_f32_32x32x16_bf16 v[0:15], v[68:71], v[220:223], v[0:15]
	v_mfma_f32_32x32x16_bf16 v[16:31], v[68:71], v[224:227], v[16:31]
	s_add_i32 s90, s76, 288
	v_add_u32_e32 v80, s90, v235
	v_add_u32_e32 v83, s90, v236
	v_add_u32_e32 v99, s90, v237
	v_add_u32_e32 v253, s90, v238
	v_add_u32_e32 v254, s90, v100
	v_add_u32_e32 v255, s90, v149
	v_med3_i32 v80, v80, 0, s99
	v_med3_i32 v83, v83, 0, s99
	v_med3_i32 v99, v99, 0, s99
	v_med3_i32 v253, v253, 0, s99
	v_med3_i32 v254, v254, 0, s99
	v_med3_i32 v255, v255, 0, s99
	v_mad_u32_u24 v80, v80, s100, v252
	v_mad_u32_u24 v83, v83, s100, v252
	v_mad_u32_u24 v99, v99, s100, v252
	v_mad_u32_u24 v253, v253, s100, v252
	v_mad_u32_u24 v254, v254, s100, v153
	v_mad_u32_u24 v255, v255, s100, v153
	global_load_dwordx4 v[188:191], v80, s[82:83]
	global_load_dwordx4 v[192:195], v83, s[82:83]
	global_load_dwordx4 v[196:199], v99, s[82:83]
	global_load_dwordx4 v[200:203], v253, s[82:83]
	global_load_dwordx4 v[204:207], v254, s[82:83] offset:768
	global_load_dwordx4 v[208:211], v255, s[82:83] offset:768
	global_load_dwordx4 v[212:215], v254, s[82:83] offset:832
	global_load_dwordx4 v[216:219], v255, s[82:83] offset:832
	s_waitcnt lgkmcnt(0)
	v_mfma_f32_32x32x16_bf16 v[32:47], v[116:119], v[48:51], v[32:47]
	ds_read_b64_tr_b16 v[72:73], v231
	ds_read_b64_tr_b16 v[74:75], v231 offset:512
	ds_read_b64_tr_b16 v[76:77], v231 offset:2048
	ds_read_b64_tr_b16 v[78:79], v231 offset:2560
	ds_read_b64_tr_b16 v[220:221], v231 offset:1024
	ds_read_b64_tr_b16 v[222:223], v231 offset:1536
	ds_read_b64_tr_b16 v[224:225], v231 offset:3072
	ds_read_b64_tr_b16 v[226:227], v231 offset:3584
	s_waitcnt vmcnt(8)
	ds_write_b128 v247, v[156:159]
	ds_write_b128 v247, v[160:163] offset:1024
	ds_write_b128 v247, v[164:167] offset:2048
	ds_write_b128 v247, v[168:171] offset:3072
	ds_read_b128 v[156:159], v248
	ds_read_b128 v[160:163], v249
	ds_read_b128 v[164:167], v250
	ds_read_b128 v[168:171], v251
	ds_write_b128 v112, v[172:175]
	ds_write_b128 v112, v[176:179] offset:1024
	ds_write_b128 v112, v[180:183] offset:2048
	ds_write_b128 v112, v[184:187] offset:3072
	v_mfma_f32_32x32x16_bf16 v[32:47], v[120:123], v[52:55], v[32:47]
	v_mfma_f32_32x32x16_bf16 v[32:47], v[124:127], v[56:59], v[32:47]
	v_mfma_f32_32x32x16_bf16 v[32:47], v[128:131], v[60:63], v[32:47]
	s_nop 11
	v_exp_f32_e32 v32, v32
	v_exp_f32_e32 v33, v33
	v_exp_f32_e32 v34, v34
	v_exp_f32_e32 v35, v35
	v_exp_f32_e32 v36, v36
	v_exp_f32_e32 v37, v37
	v_exp_f32_e32 v38, v38
	v_exp_f32_e32 v39, v39
	v_exp_f32_e32 v40, v40
	v_exp_f32_e32 v41, v41
	v_exp_f32_e32 v42, v42
	v_exp_f32_e32 v43, v43
	v_exp_f32_e32 v44, v44
	v_exp_f32_e32 v45, v45
	v_exp_f32_e32 v46, v46
	v_exp_f32_e32 v47, v47
	s_add_i32 s90, s76, 224
	v_add_u32_e32 v84, s90, v107
	v_add_u32_e32 v85, 0, v84
	v_add_u32_e32 v86, 1, v84
	v_add_u32_e32 v87, 2, v84
	v_add_u32_e32 v88, 3, v84
	v_cmp_gt_u32_e64 s[30:31], s98, v85
	v_cmp_gt_u32_e64 s[36:37], s98, v86
	v_cmp_gt_u32_e64 s[78:79], s98, v87
	v_cmp_gt_u32_e64 s[50:51], s98, v88
	v_cndmask_b32_e64 v32, 0, v32, s[30:31]
	v_add_u32_e32 v85, 8, v84
	v_cmp_gt_u32_e64 s[30:31], s98, v85
	v_cndmask_b32_e64 v33, 0, v33, s[36:37]
	v_add_u32_e32 v86, 9, v84
	v_cmp_gt_u32_e64 s[36:37], s98, v86
	v_cndmask_b32_e64 v34, 0, v34, s[78:79]
	v_add_u32_e32 v87, 10, v84
	v_cmp_gt_u32_e64 s[78:79], s98, v87
	v_cndmask_b32_e64 v35, 0, v35, s[50:51]
	v_add_u32_e32 v88, 11, v84
	v_cmp_gt_u32_e64 s[50:51], s98, v88
	v_cndmask_b32_e64 v36, 0, v36, s[30:31]
	v_add_u32_e32 v85, 16, v84
	v_cmp_gt_u32_e64 s[30:31], s98, v85
	v_cndmask_b32_e64 v37, 0, v37, s[36:37]
	v_add_u32_e32 v86, 17, v84
	v_cmp_gt_u32_e64 s[36:37], s98, v86
	v_cndmask_b32_e64 v38, 0, v38, s[78:79]
	v_add_u32_e32 v87, 18, v84
	v_cmp_gt_u32_e64 s[78:79], s98, v87
	v_cndmask_b32_e64 v39, 0, v39, s[50:51]
	v_add_u32_e32 v88, 19, v84
	v_cmp_gt_u32_e64 s[50:51], s98, v88
	v_cndmask_b32_e64 v40, 0, v40, s[30:31]
	v_add_u32_e32 v85, 24, v84
	v_cmp_gt_u32_e64 s[30:31], s98, v85
	v_cndmask_b32_e64 v41, 0, v41, s[36:37]
	v_add_u32_e32 v86, 25, v84
	v_cmp_gt_u32_e64 s[36:37], s98, v86
	v_cndmask_b32_e64 v42, 0, v42, s[78:79]
	v_add_u32_e32 v87, 26, v84
	v_cmp_gt_u32_e64 s[78:79], s98, v87
	v_cndmask_b32_e64 v43, 0, v43, s[50:51]
	v_add_u32_e32 v88, 27, v84
	v_cmp_gt_u32_e64 s[50:51], s98, v88
	v_nop
	v_cndmask_b32_e64 v44, 0, v44, s[30:31]
	v_cndmask_b32_e64 v45, 0, v45, s[36:37]
	v_cndmask_b32_e64 v46, 0, v46, s[78:79]
	v_cndmask_b32_e64 v47, 0, v47, s[50:51]
	v_cvt_pk_bf16_f32 v64, v32, v33
	v_cvt_pk_bf16_f32 v65, v34, v35
	v_cvt_pk_bf16_f32 v66, v36, v37
	v_cvt_pk_bf16_f32 v67, v38, v39
	v_cvt_pk_bf16_f32 v68, v40, v41
	v_cvt_pk_bf16_f32 v69, v42, v43
	v_cvt_pk_bf16_f32 v70, v44, v45
	v_cvt_pk_bf16_f32 v71, v46, v47
	v_pk_add_f32 v[232:233], v[232:233], v[32:33]
	v_pk_add_f32 v[232:233], v[232:233], v[34:35]
	v_pk_add_f32 v[232:233], v[232:233], v[36:37]
	v_pk_add_f32 v[232:233], v[232:233], v[38:39]
	v_pk_add_f32 v[232:233], v[232:233], v[40:41]
	v_pk_add_f32 v[232:233], v[232:233], v[42:43]
	v_pk_add_f32 v[232:233], v[232:233], v[44:45]
	v_pk_add_f32 v[232:233], v[232:233], v[46:47]
	ds_read2_b32 v[32:33], v115 offset0:102 offset1:103
	ds_read2_b32 v[34:35], v115 offset0:104 offset1:105
	ds_read2_b32 v[36:37], v115 offset0:110 offset1:111
	ds_read2_b32 v[38:39], v115 offset0:112 offset1:113
	ds_read2_b32 v[40:41], v115 offset0:119 offset1:120
	ds_read2_b32 v[42:43], v115 offset0:121 offset1:122
	ds_read2_b32 v[44:45], v115 offset0:127 offset1:128
	ds_read2_b32 v[46:47], v115 offset0:129 offset1:130
	s_waitcnt lgkmcnt(15)
	v_mfma_f32_32x32x16_bf16 v[0:15], v[64:67], v[72:75], v[0:15]
	v_mfma_f32_32x32x16_bf16 v[16:31], v[64:67], v[76:79], v[16:31]
	v_mfma_f32_32x32x16_bf16 v[0:15], v[68:71], v[220:223], v[0:15]
	v_mfma_f32_32x32x16_bf16 v[16:31], v[68:71], v[224:227], v[16:31]
	s_add_i32 s90, s76, 320
	v_add_u32_e32 v80, s90, v235
	v_add_u32_e32 v83, s90, v236
	v_add_u32_e32 v99, s90, v237
	v_add_u32_e32 v253, s90, v238
	v_add_u32_e32 v254, s90, v100
	v_add_u32_e32 v255, s90, v149
	v_med3_i32 v80, v80, 0, s99
	v_med3_i32 v83, v83, 0, s99
	v_med3_i32 v99, v99, 0, s99
	v_med3_i32 v253, v253, 0, s99
	v_med3_i32 v254, v254, 0, s99
	v_med3_i32 v255, v255, 0, s99
	v_mad_u32_u24 v80, v80, s100, v252
	v_mad_u32_u24 v83, v83, s100, v252
	v_mad_u32_u24 v99, v99, s100, v252
	v_mad_u32_u24 v253, v253, s100, v252
	v_mad_u32_u24 v254, v254, s100, v153
	v_mad_u32_u24 v255, v255, s100, v153
	global_load_dwordx4 v[116:119], v80, s[82:83]
	global_load_dwordx4 v[120:123], v83, s[82:83]
	global_load_dwordx4 v[124:127], v99, s[82:83]
	global_load_dwordx4 v[128:131], v253, s[82:83]
	global_load_dwordx4 v[132:135], v254, s[82:83] offset:768
	global_load_dwordx4 v[136:139], v255, s[82:83] offset:768
	global_load_dwordx4 v[140:143], v254, s[82:83] offset:832
	global_load_dwordx4 v[144:147], v255, s[82:83] offset:832
	s_waitcnt lgkmcnt(0)
	v_mfma_f32_32x32x16_bf16 v[32:47], v[156:159], v[48:51], v[32:47]
	ds_read_b64_tr_b16 v[72:73], v231
	ds_read_b64_tr_b16 v[74:75], v231 offset:512
	ds_read_b64_tr_b16 v[76:77], v231 offset:2048
	ds_read_b64_tr_b16 v[78:79], v231 offset:2560
	ds_read_b64_tr_b16 v[220:221], v231 offset:1024
	ds_read_b64_tr_b16 v[222:223], v231 offset:1536
	ds_read_b64_tr_b16 v[224:225], v231 offset:3072
	ds_read_b64_tr_b16 v[226:227], v231 offset:3584
	s_waitcnt vmcnt(8)
	ds_write_b128 v247, v[188:191]
	ds_write_b128 v247, v[192:195] offset:1024
	ds_write_b128 v247, v[196:199] offset:2048
	ds_write_b128 v247, v[200:203] offset:3072
	ds_read_b128 v[188:191], v248
	ds_read_b128 v[192:195], v249
	ds_read_b128 v[196:199], v250
	ds_read_b128 v[200:203], v251
	ds_write_b128 v112, v[204:207]
	ds_write_b128 v112, v[208:211] offset:1024
	ds_write_b128 v112, v[212:215] offset:2048
	ds_write_b128 v112, v[216:219] offset:3072
	v_mfma_f32_32x32x16_bf16 v[32:47], v[160:163], v[52:55], v[32:47]
	v_mfma_f32_32x32x16_bf16 v[32:47], v[164:167], v[56:59], v[32:47]
	v_mfma_f32_32x32x16_bf16 v[32:47], v[168:171], v[60:63], v[32:47]
	s_nop 11
	v_exp_f32_e32 v32, v32
	v_exp_f32_e32 v33, v33
	v_exp_f32_e32 v34, v34
	v_exp_f32_e32 v35, v35
	v_exp_f32_e32 v36, v36
	v_exp_f32_e32 v37, v37
	v_exp_f32_e32 v38, v38
	v_exp_f32_e32 v39, v39
	v_exp_f32_e32 v40, v40
	v_exp_f32_e32 v41, v41
	v_exp_f32_e32 v42, v42
	v_exp_f32_e32 v43, v43
	v_exp_f32_e32 v44, v44
	v_exp_f32_e32 v45, v45
	v_exp_f32_e32 v46, v46
	v_exp_f32_e32 v47, v47
	s_add_i32 s90, s76, 256
	v_add_u32_e32 v84, s90, v107
	v_add_u32_e32 v85, 0, v84
	v_add_u32_e32 v86, 1, v84
	v_add_u32_e32 v87, 2, v84
	v_add_u32_e32 v88, 3, v84
	v_cmp_gt_u32_e64 s[30:31], s98, v85
	v_cmp_gt_u32_e64 s[36:37], s98, v86
	v_cmp_gt_u32_e64 s[78:79], s98, v87
	v_cmp_gt_u32_e64 s[50:51], s98, v88
	v_cndmask_b32_e64 v32, 0, v32, s[30:31]
	v_add_u32_e32 v85, 8, v84
	v_cmp_gt_u32_e64 s[30:31], s98, v85
	v_cndmask_b32_e64 v33, 0, v33, s[36:37]
	v_add_u32_e32 v86, 9, v84
	v_cmp_gt_u32_e64 s[36:37], s98, v86
	v_cndmask_b32_e64 v34, 0, v34, s[78:79]
	v_add_u32_e32 v87, 10, v84
	v_cmp_gt_u32_e64 s[78:79], s98, v87
	v_cndmask_b32_e64 v35, 0, v35, s[50:51]
	v_add_u32_e32 v88, 11, v84
	v_cmp_gt_u32_e64 s[50:51], s98, v88
	v_cndmask_b32_e64 v36, 0, v36, s[30:31]
	v_add_u32_e32 v85, 16, v84
	v_cmp_gt_u32_e64 s[30:31], s98, v85
	v_cndmask_b32_e64 v37, 0, v37, s[36:37]
	v_add_u32_e32 v86, 17, v84
	v_cmp_gt_u32_e64 s[36:37], s98, v86
	v_cndmask_b32_e64 v38, 0, v38, s[78:79]
	v_add_u32_e32 v87, 18, v84
	v_cmp_gt_u32_e64 s[78:79], s98, v87
	v_cndmask_b32_e64 v39, 0, v39, s[50:51]
	v_add_u32_e32 v88, 19, v84
	v_cmp_gt_u32_e64 s[50:51], s98, v88
	v_cndmask_b32_e64 v40, 0, v40, s[30:31]
	v_add_u32_e32 v85, 24, v84
	v_cmp_gt_u32_e64 s[30:31], s98, v85
	v_cndmask_b32_e64 v41, 0, v41, s[36:37]
	v_add_u32_e32 v86, 25, v84
	v_cmp_gt_u32_e64 s[36:37], s98, v86
	v_cndmask_b32_e64 v42, 0, v42, s[78:79]
	v_add_u32_e32 v87, 26, v84
	v_cmp_gt_u32_e64 s[78:79], s98, v87
	v_cndmask_b32_e64 v43, 0, v43, s[50:51]
	v_add_u32_e32 v88, 27, v84
	v_cmp_gt_u32_e64 s[50:51], s98, v88
	v_nop
	v_cndmask_b32_e64 v44, 0, v44, s[30:31]
	v_cndmask_b32_e64 v45, 0, v45, s[36:37]
	v_cndmask_b32_e64 v46, 0, v46, s[78:79]
	v_cndmask_b32_e64 v47, 0, v47, s[50:51]
	v_cvt_pk_bf16_f32 v64, v32, v33
	v_cvt_pk_bf16_f32 v65, v34, v35
	v_cvt_pk_bf16_f32 v66, v36, v37
	v_cvt_pk_bf16_f32 v67, v38, v39
	v_cvt_pk_bf16_f32 v68, v40, v41
	v_cvt_pk_bf16_f32 v69, v42, v43
	v_cvt_pk_bf16_f32 v70, v44, v45
	v_cvt_pk_bf16_f32 v71, v46, v47
	v_pk_add_f32 v[232:233], v[232:233], v[32:33]
	v_pk_add_f32 v[232:233], v[232:233], v[34:35]
	v_pk_add_f32 v[232:233], v[232:233], v[36:37]
	v_pk_add_f32 v[232:233], v[232:233], v[38:39]
	v_pk_add_f32 v[232:233], v[232:233], v[40:41]
	v_pk_add_f32 v[232:233], v[232:233], v[42:43]
	v_pk_add_f32 v[232:233], v[232:233], v[44:45]
	v_pk_add_f32 v[232:233], v[232:233], v[46:47]
	ds_read2_b32 v[32:33], v115 offset0:136 offset1:137
	ds_read2_b32 v[34:35], v115 offset0:138 offset1:139
	ds_read2_b32 v[36:37], v115 offset0:144 offset1:145
	ds_read2_b32 v[38:39], v115 offset0:146 offset1:147
	ds_read2_b32 v[40:41], v115 offset0:153 offset1:154
	ds_read2_b32 v[42:43], v115 offset0:155 offset1:156
	ds_read2_b32 v[44:45], v115 offset0:161 offset1:162
	ds_read2_b32 v[46:47], v115 offset0:163 offset1:164
	s_waitcnt lgkmcnt(15)
	v_mfma_f32_32x32x16_bf16 v[0:15], v[64:67], v[72:75], v[0:15]
	v_mfma_f32_32x32x16_bf16 v[16:31], v[64:67], v[76:79], v[16:31]
	v_mfma_f32_32x32x16_bf16 v[0:15], v[68:71], v[220:223], v[0:15]
	v_mfma_f32_32x32x16_bf16 v[16:31], v[68:71], v[224:227], v[16:31]
	s_add_i32 s90, s76, 352
	v_add_u32_e32 v80, s90, v235
	v_add_u32_e32 v83, s90, v236
	v_add_u32_e32 v99, s90, v237
	v_add_u32_e32 v253, s90, v238
	v_add_u32_e32 v254, s90, v100
	v_add_u32_e32 v255, s90, v149
	v_med3_i32 v80, v80, 0, s99
	v_med3_i32 v83, v83, 0, s99
	v_med3_i32 v99, v99, 0, s99
	v_med3_i32 v253, v253, 0, s99
	v_med3_i32 v254, v254, 0, s99
	v_med3_i32 v255, v255, 0, s99
	v_mad_u32_u24 v80, v80, s100, v252
	v_mad_u32_u24 v83, v83, s100, v252
	v_mad_u32_u24 v99, v99, s100, v252
	v_mad_u32_u24 v253, v253, s100, v252
	v_mad_u32_u24 v254, v254, s100, v153
	v_mad_u32_u24 v255, v255, s100, v153
	global_load_dwordx4 v[156:159], v80, s[82:83]
	global_load_dwordx4 v[160:163], v83, s[82:83]
	global_load_dwordx4 v[164:167], v99, s[82:83]
	global_load_dwordx4 v[168:171], v253, s[82:83]
	global_load_dwordx4 v[172:175], v254, s[82:83] offset:768
	global_load_dwordx4 v[176:179], v255, s[82:83] offset:768
	global_load_dwordx4 v[180:183], v254, s[82:83] offset:832
	global_load_dwordx4 v[184:187], v255, s[82:83] offset:832
	s_waitcnt lgkmcnt(0)
	v_mfma_f32_32x32x16_bf16 v[32:47], v[188:191], v[48:51], v[32:47]
	ds_read_b64_tr_b16 v[72:73], v231
	ds_read_b64_tr_b16 v[74:75], v231 offset:512
	ds_read_b64_tr_b16 v[76:77], v231 offset:2048
	ds_read_b64_tr_b16 v[78:79], v231 offset:2560
	ds_read_b64_tr_b16 v[220:221], v231 offset:1024
	ds_read_b64_tr_b16 v[222:223], v231 offset:1536
	ds_read_b64_tr_b16 v[224:225], v231 offset:3072
	ds_read_b64_tr_b16 v[226:227], v231 offset:3584
	s_waitcnt vmcnt(8)
	ds_write_b128 v247, v[116:119]
	ds_write_b128 v247, v[120:123] offset:1024
	ds_write_b128 v247, v[124:127] offset:2048
	ds_write_b128 v247, v[128:131] offset:3072
	ds_read_b128 v[116:119], v248
	ds_read_b128 v[120:123], v249
	ds_read_b128 v[124:127], v250
	ds_read_b128 v[128:131], v251
	ds_write_b128 v112, v[132:135]
	ds_write_b128 v112, v[136:139] offset:1024
	ds_write_b128 v112, v[140:143] offset:2048
	ds_write_b128 v112, v[144:147] offset:3072
	v_mfma_f32_32x32x16_bf16 v[32:47], v[192:195], v[52:55], v[32:47]
	v_mfma_f32_32x32x16_bf16 v[32:47], v[196:199], v[56:59], v[32:47]
	v_mfma_f32_32x32x16_bf16 v[32:47], v[200:203], v[60:63], v[32:47]
	s_nop 11
	v_exp_f32_e32 v32, v32
	v_exp_f32_e32 v33, v33
	v_exp_f32_e32 v34, v34
	v_exp_f32_e32 v35, v35
	v_exp_f32_e32 v36, v36
	v_exp_f32_e32 v37, v37
	v_exp_f32_e32 v38, v38
	v_exp_f32_e32 v39, v39
	v_exp_f32_e32 v40, v40
	v_exp_f32_e32 v41, v41
	v_exp_f32_e32 v42, v42
	v_exp_f32_e32 v43, v43
	v_exp_f32_e32 v44, v44
	v_exp_f32_e32 v45, v45
	v_exp_f32_e32 v46, v46
	v_exp_f32_e32 v47, v47
	s_add_i32 s90, s76, 288
	v_add_u32_e32 v84, s90, v107
	v_add_u32_e32 v85, 0, v84
	v_add_u32_e32 v86, 1, v84
	v_add_u32_e32 v87, 2, v84
	v_add_u32_e32 v88, 3, v84
	v_cmp_gt_u32_e64 s[30:31], s98, v85
	v_cmp_gt_u32_e64 s[36:37], s98, v86
	v_cmp_gt_u32_e64 s[78:79], s98, v87
	v_cmp_gt_u32_e64 s[50:51], s98, v88
	v_cndmask_b32_e64 v32, 0, v32, s[30:31]
	v_add_u32_e32 v85, 8, v84
	v_cmp_gt_u32_e64 s[30:31], s98, v85
	v_cndmask_b32_e64 v33, 0, v33, s[36:37]
	v_add_u32_e32 v86, 9, v84
	v_cmp_gt_u32_e64 s[36:37], s98, v86
	v_cndmask_b32_e64 v34, 0, v34, s[78:79]
	v_add_u32_e32 v87, 10, v84
	v_cmp_gt_u32_e64 s[78:79], s98, v87
	v_cndmask_b32_e64 v35, 0, v35, s[50:51]
	v_add_u32_e32 v88, 11, v84
	v_cmp_gt_u32_e64 s[50:51], s98, v88
	v_cndmask_b32_e64 v36, 0, v36, s[30:31]
	v_add_u32_e32 v85, 16, v84
	v_cmp_gt_u32_e64 s[30:31], s98, v85
	v_cndmask_b32_e64 v37, 0, v37, s[36:37]
	v_add_u32_e32 v86, 17, v84
	v_cmp_gt_u32_e64 s[36:37], s98, v86
	v_cndmask_b32_e64 v38, 0, v38, s[78:79]
	v_add_u32_e32 v87, 18, v84
	v_cmp_gt_u32_e64 s[78:79], s98, v87
	v_cndmask_b32_e64 v39, 0, v39, s[50:51]
	v_add_u32_e32 v88, 19, v84
	v_cmp_gt_u32_e64 s[50:51], s98, v88
	v_cndmask_b32_e64 v40, 0, v40, s[30:31]
	v_add_u32_e32 v85, 24, v84
	v_cmp_gt_u32_e64 s[30:31], s98, v85
	v_cndmask_b32_e64 v41, 0, v41, s[36:37]
	v_add_u32_e32 v86, 25, v84
	v_cmp_gt_u32_e64 s[36:37], s98, v86
	v_cndmask_b32_e64 v42, 0, v42, s[78:79]
	v_add_u32_e32 v87, 26, v84
	v_cmp_gt_u32_e64 s[78:79], s98, v87
	v_cndmask_b32_e64 v43, 0, v43, s[50:51]
	v_add_u32_e32 v88, 27, v84
	v_cmp_gt_u32_e64 s[50:51], s98, v88
	v_nop
	v_cndmask_b32_e64 v44, 0, v44, s[30:31]
	v_cndmask_b32_e64 v45, 0, v45, s[36:37]
	v_cndmask_b32_e64 v46, 0, v46, s[78:79]
	v_cndmask_b32_e64 v47, 0, v47, s[50:51]
	v_cvt_pk_bf16_f32 v64, v32, v33
	v_cvt_pk_bf16_f32 v65, v34, v35
	v_cvt_pk_bf16_f32 v66, v36, v37
	v_cvt_pk_bf16_f32 v67, v38, v39
	v_cvt_pk_bf16_f32 v68, v40, v41
	v_cvt_pk_bf16_f32 v69, v42, v43
	v_cvt_pk_bf16_f32 v70, v44, v45
	v_cvt_pk_bf16_f32 v71, v46, v47
	v_pk_add_f32 v[232:233], v[232:233], v[32:33]
	v_pk_add_f32 v[232:233], v[232:233], v[34:35]
	v_pk_add_f32 v[232:233], v[232:233], v[36:37]
	v_pk_add_f32 v[232:233], v[232:233], v[38:39]
	v_pk_add_f32 v[232:233], v[232:233], v[40:41]
	v_pk_add_f32 v[232:233], v[232:233], v[42:43]
	v_pk_add_f32 v[232:233], v[232:233], v[44:45]
	v_pk_add_f32 v[232:233], v[232:233], v[46:47]
	ds_read2_b32 v[32:33], v115 offset0:170 offset1:171
	ds_read2_b32 v[34:35], v115 offset0:172 offset1:173
	ds_read2_b32 v[36:37], v115 offset0:178 offset1:179
	ds_read2_b32 v[38:39], v115 offset0:180 offset1:181
	ds_read2_b32 v[40:41], v115 offset0:187 offset1:188
	ds_read2_b32 v[42:43], v115 offset0:189 offset1:190
	ds_read2_b32 v[44:45], v115 offset0:195 offset1:196
	ds_read2_b32 v[46:47], v115 offset0:197 offset1:198
	s_waitcnt lgkmcnt(15)
	v_mfma_f32_32x32x16_bf16 v[0:15], v[64:67], v[72:75], v[0:15]
	v_mfma_f32_32x32x16_bf16 v[16:31], v[64:67], v[76:79], v[16:31]
	v_mfma_f32_32x32x16_bf16 v[0:15], v[68:71], v[220:223], v[0:15]
	v_mfma_f32_32x32x16_bf16 v[16:31], v[68:71], v[224:227], v[16:31]
	s_add_i32 s90, s76, 384
	v_add_u32_e32 v80, s90, v235
	v_add_u32_e32 v83, s90, v236
	v_add_u32_e32 v99, s90, v237
	v_add_u32_e32 v253, s90, v238
	v_add_u32_e32 v254, s90, v100
	v_add_u32_e32 v255, s90, v149
	v_med3_i32 v80, v80, 0, s99
	v_med3_i32 v83, v83, 0, s99
	v_med3_i32 v99, v99, 0, s99
	v_med3_i32 v253, v253, 0, s99
	v_med3_i32 v254, v254, 0, s99
	v_med3_i32 v255, v255, 0, s99
	v_mad_u32_u24 v80, v80, s100, v252
	v_mad_u32_u24 v83, v83, s100, v252
	v_mad_u32_u24 v99, v99, s100, v252
	v_mad_u32_u24 v253, v253, s100, v252
	v_mad_u32_u24 v254, v254, s100, v153
	v_mad_u32_u24 v255, v255, s100, v153
	global_load_dwordx4 v[188:191], v80, s[82:83]
	global_load_dwordx4 v[192:195], v83, s[82:83]
	global_load_dwordx4 v[196:199], v99, s[82:83]
	global_load_dwordx4 v[200:203], v253, s[82:83]
	global_load_dwordx4 v[204:207], v254, s[82:83] offset:768
	global_load_dwordx4 v[208:211], v255, s[82:83] offset:768
	global_load_dwordx4 v[212:215], v254, s[82:83] offset:832
	global_load_dwordx4 v[216:219], v255, s[82:83] offset:832
	s_waitcnt lgkmcnt(0)
	v_mfma_f32_32x32x16_bf16 v[32:47], v[116:119], v[48:51], v[32:47]
	ds_read_b64_tr_b16 v[72:73], v231
	ds_read_b64_tr_b16 v[74:75], v231 offset:512
	ds_read_b64_tr_b16 v[76:77], v231 offset:2048
	ds_read_b64_tr_b16 v[78:79], v231 offset:2560
	ds_read_b64_tr_b16 v[220:221], v231 offset:1024
	ds_read_b64_tr_b16 v[222:223], v231 offset:1536
	ds_read_b64_tr_b16 v[224:225], v231 offset:3072
	ds_read_b64_tr_b16 v[226:227], v231 offset:3584
	s_waitcnt vmcnt(8)
	ds_write_b128 v247, v[156:159]
	ds_write_b128 v247, v[160:163] offset:1024
	ds_write_b128 v247, v[164:167] offset:2048
	ds_write_b128 v247, v[168:171] offset:3072
	ds_read_b128 v[156:159], v248
	ds_read_b128 v[160:163], v249
	ds_read_b128 v[164:167], v250
	ds_read_b128 v[168:171], v251
	ds_write_b128 v112, v[172:175]
	ds_write_b128 v112, v[176:179] offset:1024
	ds_write_b128 v112, v[180:183] offset:2048
	ds_write_b128 v112, v[184:187] offset:3072
	v_mfma_f32_32x32x16_bf16 v[32:47], v[120:123], v[52:55], v[32:47]
	v_mfma_f32_32x32x16_bf16 v[32:47], v[124:127], v[56:59], v[32:47]
	v_mfma_f32_32x32x16_bf16 v[32:47], v[128:131], v[60:63], v[32:47]
	s_nop 11
	v_exp_f32_e32 v32, v32
	v_exp_f32_e32 v33, v33
	v_exp_f32_e32 v34, v34
	v_exp_f32_e32 v35, v35
	v_exp_f32_e32 v36, v36
	v_exp_f32_e32 v37, v37
	v_exp_f32_e32 v38, v38
	v_exp_f32_e32 v39, v39
	v_exp_f32_e32 v40, v40
	v_exp_f32_e32 v41, v41
	v_exp_f32_e32 v42, v42
	v_exp_f32_e32 v43, v43
	v_exp_f32_e32 v44, v44
	v_exp_f32_e32 v45, v45
	v_exp_f32_e32 v46, v46
	v_exp_f32_e32 v47, v47
	s_add_i32 s90, s76, 320
	v_add_u32_e32 v84, s90, v107
	v_add_u32_e32 v85, 0, v84
	v_add_u32_e32 v86, 1, v84
	v_add_u32_e32 v87, 2, v84
	v_add_u32_e32 v88, 3, v84
	v_cmp_gt_u32_e64 s[30:31], s98, v85
	v_cmp_gt_u32_e64 s[36:37], s98, v86
	v_cmp_gt_u32_e64 s[78:79], s98, v87
	v_cmp_gt_u32_e64 s[50:51], s98, v88
	v_cndmask_b32_e64 v32, 0, v32, s[30:31]
	v_add_u32_e32 v85, 8, v84
	v_cmp_gt_u32_e64 s[30:31], s98, v85
	v_cndmask_b32_e64 v33, 0, v33, s[36:37]
	v_add_u32_e32 v86, 9, v84
	v_cmp_gt_u32_e64 s[36:37], s98, v86
	v_cndmask_b32_e64 v34, 0, v34, s[78:79]
	v_add_u32_e32 v87, 10, v84
	v_cmp_gt_u32_e64 s[78:79], s98, v87
	v_cndmask_b32_e64 v35, 0, v35, s[50:51]
	v_add_u32_e32 v88, 11, v84
	v_cmp_gt_u32_e64 s[50:51], s98, v88
	v_cndmask_b32_e64 v36, 0, v36, s[30:31]
	v_add_u32_e32 v85, 16, v84
	v_cmp_gt_u32_e64 s[30:31], s98, v85
	v_cndmask_b32_e64 v37, 0, v37, s[36:37]
	v_add_u32_e32 v86, 17, v84
	v_cmp_gt_u32_e64 s[36:37], s98, v86
	v_cndmask_b32_e64 v38, 0, v38, s[78:79]
	v_add_u32_e32 v87, 18, v84
	v_cmp_gt_u32_e64 s[78:79], s98, v87
	v_cndmask_b32_e64 v39, 0, v39, s[50:51]
	v_add_u32_e32 v88, 19, v84
	v_cmp_gt_u32_e64 s[50:51], s98, v88
	v_cndmask_b32_e64 v40, 0, v40, s[30:31]
	v_add_u32_e32 v85, 24, v84
	v_cmp_gt_u32_e64 s[30:31], s98, v85
	v_cndmask_b32_e64 v41, 0, v41, s[36:37]
	v_add_u32_e32 v86, 25, v84
	v_cmp_gt_u32_e64 s[36:37], s98, v86
	v_cndmask_b32_e64 v42, 0, v42, s[78:79]
	v_add_u32_e32 v87, 26, v84
	v_cmp_gt_u32_e64 s[78:79], s98, v87
	v_cndmask_b32_e64 v43, 0, v43, s[50:51]
	v_add_u32_e32 v88, 27, v84
	v_cmp_gt_u32_e64 s[50:51], s98, v88
	v_nop
	v_cndmask_b32_e64 v44, 0, v44, s[30:31]
	v_cndmask_b32_e64 v45, 0, v45, s[36:37]
	v_cndmask_b32_e64 v46, 0, v46, s[78:79]
	v_cndmask_b32_e64 v47, 0, v47, s[50:51]
	v_cvt_pk_bf16_f32 v64, v32, v33
	v_cvt_pk_bf16_f32 v65, v34, v35
	v_cvt_pk_bf16_f32 v66, v36, v37
	v_cvt_pk_bf16_f32 v67, v38, v39
	v_cvt_pk_bf16_f32 v68, v40, v41
	v_cvt_pk_bf16_f32 v69, v42, v43
	v_cvt_pk_bf16_f32 v70, v44, v45
	v_cvt_pk_bf16_f32 v71, v46, v47
	v_pk_add_f32 v[232:233], v[232:233], v[32:33]
	v_pk_add_f32 v[232:233], v[232:233], v[34:35]
	v_pk_add_f32 v[232:233], v[232:233], v[36:37]
	v_pk_add_f32 v[232:233], v[232:233], v[38:39]
	v_pk_add_f32 v[232:233], v[232:233], v[40:41]
	v_pk_add_f32 v[232:233], v[232:233], v[42:43]
	v_pk_add_f32 v[232:233], v[232:233], v[44:45]
	v_pk_add_f32 v[232:233], v[232:233], v[46:47]
	ds_read2_b32 v[32:33], v115 offset0:204 offset1:205
	ds_read2_b32 v[34:35], v115 offset0:206 offset1:207
	ds_read2_b32 v[36:37], v115 offset0:212 offset1:213
	ds_read2_b32 v[38:39], v115 offset0:214 offset1:215
	ds_read2_b32 v[40:41], v115 offset0:221 offset1:222
	ds_read2_b32 v[42:43], v115 offset0:223 offset1:224
	ds_read2_b32 v[44:45], v115 offset0:229 offset1:230
	ds_read2_b32 v[46:47], v115 offset0:231 offset1:232
	s_waitcnt lgkmcnt(15)
	v_mfma_f32_32x32x16_bf16 v[0:15], v[64:67], v[72:75], v[0:15]
	v_mfma_f32_32x32x16_bf16 v[16:31], v[64:67], v[76:79], v[16:31]
	v_mfma_f32_32x32x16_bf16 v[0:15], v[68:71], v[220:223], v[0:15]
	v_mfma_f32_32x32x16_bf16 v[16:31], v[68:71], v[224:227], v[16:31]
	s_add_i32 s90, s76, 416
	v_add_u32_e32 v80, s90, v235
	v_add_u32_e32 v83, s90, v236
	v_add_u32_e32 v99, s90, v237
	v_add_u32_e32 v253, s90, v238
	v_add_u32_e32 v254, s90, v100
	v_add_u32_e32 v255, s90, v149
	v_med3_i32 v80, v80, 0, s99
	v_med3_i32 v83, v83, 0, s99
	v_med3_i32 v99, v99, 0, s99
	v_med3_i32 v253, v253, 0, s99
	v_med3_i32 v254, v254, 0, s99
	v_med3_i32 v255, v255, 0, s99
	v_mad_u32_u24 v80, v80, s100, v252
	v_mad_u32_u24 v83, v83, s100, v252
	v_mad_u32_u24 v99, v99, s100, v252
	v_mad_u32_u24 v253, v253, s100, v252
	v_mad_u32_u24 v254, v254, s100, v153
	v_mad_u32_u24 v255, v255, s100, v153
	global_load_dwordx4 v[116:119], v80, s[82:83]
	global_load_dwordx4 v[120:123], v83, s[82:83]
	global_load_dwordx4 v[124:127], v99, s[82:83]
	global_load_dwordx4 v[128:131], v253, s[82:83]
	global_load_dwordx4 v[132:135], v254, s[82:83] offset:768
	global_load_dwordx4 v[136:139], v255, s[82:83] offset:768
	global_load_dwordx4 v[140:143], v254, s[82:83] offset:832
	global_load_dwordx4 v[144:147], v255, s[82:83] offset:832
	s_waitcnt lgkmcnt(0)
	v_mfma_f32_32x32x16_bf16 v[32:47], v[156:159], v[48:51], v[32:47]
	ds_read_b64_tr_b16 v[72:73], v231
	ds_read_b64_tr_b16 v[74:75], v231 offset:512
	ds_read_b64_tr_b16 v[76:77], v231 offset:2048
	ds_read_b64_tr_b16 v[78:79], v231 offset:2560
	ds_read_b64_tr_b16 v[220:221], v231 offset:1024
	ds_read_b64_tr_b16 v[222:223], v231 offset:1536
	ds_read_b64_tr_b16 v[224:225], v231 offset:3072
	ds_read_b64_tr_b16 v[226:227], v231 offset:3584
	s_waitcnt vmcnt(8)
	ds_write_b128 v247, v[188:191]
	ds_write_b128 v247, v[192:195] offset:1024
	ds_write_b128 v247, v[196:199] offset:2048
	ds_write_b128 v247, v[200:203] offset:3072
	ds_read_b128 v[188:191], v248
	ds_read_b128 v[192:195], v249
	ds_read_b128 v[196:199], v250
	ds_read_b128 v[200:203], v251
	ds_write_b128 v112, v[204:207]
	ds_write_b128 v112, v[208:211] offset:1024
	ds_write_b128 v112, v[212:215] offset:2048
	ds_write_b128 v112, v[216:219] offset:3072
	v_mfma_f32_32x32x16_bf16 v[32:47], v[160:163], v[52:55], v[32:47]
	v_mfma_f32_32x32x16_bf16 v[32:47], v[164:167], v[56:59], v[32:47]
	v_mfma_f32_32x32x16_bf16 v[32:47], v[168:171], v[60:63], v[32:47]
	s_nop 11
	v_exp_f32_e32 v32, v32
	v_exp_f32_e32 v33, v33
	v_exp_f32_e32 v34, v34
	v_exp_f32_e32 v35, v35
	v_exp_f32_e32 v36, v36
	v_exp_f32_e32 v37, v37
	v_exp_f32_e32 v38, v38
	v_exp_f32_e32 v39, v39
	v_exp_f32_e32 v40, v40
	v_exp_f32_e32 v41, v41
	v_exp_f32_e32 v42, v42
	v_exp_f32_e32 v43, v43
	v_exp_f32_e32 v44, v44
	v_exp_f32_e32 v45, v45
	v_exp_f32_e32 v46, v46
	v_exp_f32_e32 v47, v47
	s_add_i32 s90, s76, 352
	v_add_u32_e32 v84, s90, v107
	v_add_u32_e32 v85, 0, v84
	v_add_u32_e32 v86, 1, v84
	v_add_u32_e32 v87, 2, v84
	v_add_u32_e32 v88, 3, v84
	v_cmp_gt_u32_e64 s[30:31], s98, v85
	v_cmp_gt_u32_e64 s[36:37], s98, v86
	v_cmp_gt_u32_e64 s[78:79], s98, v87
	v_cmp_gt_u32_e64 s[50:51], s98, v88
	v_cndmask_b32_e64 v32, 0, v32, s[30:31]
	v_add_u32_e32 v85, 8, v84
	v_cmp_gt_u32_e64 s[30:31], s98, v85
	v_cndmask_b32_e64 v33, 0, v33, s[36:37]
	v_add_u32_e32 v86, 9, v84
	v_cmp_gt_u32_e64 s[36:37], s98, v86
	v_cndmask_b32_e64 v34, 0, v34, s[78:79]
	v_add_u32_e32 v87, 10, v84
	v_cmp_gt_u32_e64 s[78:79], s98, v87
	v_cndmask_b32_e64 v35, 0, v35, s[50:51]
	v_add_u32_e32 v88, 11, v84
	v_cmp_gt_u32_e64 s[50:51], s98, v88
	v_cndmask_b32_e64 v36, 0, v36, s[30:31]
	v_add_u32_e32 v85, 16, v84
	v_cmp_gt_u32_e64 s[30:31], s98, v85
	v_cndmask_b32_e64 v37, 0, v37, s[36:37]
	v_add_u32_e32 v86, 17, v84
	v_cmp_gt_u32_e64 s[36:37], s98, v86
	v_cndmask_b32_e64 v38, 0, v38, s[78:79]
	v_add_u32_e32 v87, 18, v84
	v_cmp_gt_u32_e64 s[78:79], s98, v87
	v_cndmask_b32_e64 v39, 0, v39, s[50:51]
	v_add_u32_e32 v88, 19, v84
	v_cmp_gt_u32_e64 s[50:51], s98, v88
	v_cndmask_b32_e64 v40, 0, v40, s[30:31]
	v_add_u32_e32 v85, 24, v84
	v_cmp_gt_u32_e64 s[30:31], s98, v85
	v_cndmask_b32_e64 v41, 0, v41, s[36:37]
	v_add_u32_e32 v86, 25, v84
	v_cmp_gt_u32_e64 s[36:37], s98, v86
	v_cndmask_b32_e64 v42, 0, v42, s[78:79]
	v_add_u32_e32 v87, 26, v84
	v_cmp_gt_u32_e64 s[78:79], s98, v87
	v_cndmask_b32_e64 v43, 0, v43, s[50:51]
	v_add_u32_e32 v88, 27, v84
	v_cmp_gt_u32_e64 s[50:51], s98, v88
	v_nop
	v_cndmask_b32_e64 v44, 0, v44, s[30:31]
	v_cndmask_b32_e64 v45, 0, v45, s[36:37]
	v_cndmask_b32_e64 v46, 0, v46, s[78:79]
	v_cndmask_b32_e64 v47, 0, v47, s[50:51]
	v_cvt_pk_bf16_f32 v64, v32, v33
	v_cvt_pk_bf16_f32 v65, v34, v35
	v_cvt_pk_bf16_f32 v66, v36, v37
	v_cvt_pk_bf16_f32 v67, v38, v39
	v_cvt_pk_bf16_f32 v68, v40, v41
	v_cvt_pk_bf16_f32 v69, v42, v43
	v_cvt_pk_bf16_f32 v70, v44, v45
	v_cvt_pk_bf16_f32 v71, v46, v47
	v_pk_add_f32 v[232:233], v[232:233], v[32:33]
	v_pk_add_f32 v[232:233], v[232:233], v[34:35]
	v_pk_add_f32 v[232:233], v[232:233], v[36:37]
	v_pk_add_f32 v[232:233], v[232:233], v[38:39]
	v_pk_add_f32 v[232:233], v[232:233], v[40:41]
	v_pk_add_f32 v[232:233], v[232:233], v[42:43]
	v_pk_add_f32 v[232:233], v[232:233], v[44:45]
	v_pk_add_f32 v[232:233], v[232:233], v[46:47]
	v_add_u32_e32 v115, 952, v115
	ds_read2_b32 v[32:33], v115 offset0:0 offset1:1
	ds_read2_b32 v[34:35], v115 offset0:2 offset1:3
	ds_read2_b32 v[36:37], v115 offset0:8 offset1:9
	ds_read2_b32 v[38:39], v115 offset0:10 offset1:11
	ds_read2_b32 v[40:41], v115 offset0:17 offset1:18
	ds_read2_b32 v[42:43], v115 offset0:19 offset1:20
	ds_read2_b32 v[44:45], v115 offset0:25 offset1:26
	ds_read2_b32 v[46:47], v115 offset0:27 offset1:28
	s_waitcnt lgkmcnt(15)
	v_mfma_f32_32x32x16_bf16 v[0:15], v[64:67], v[72:75], v[0:15]
	v_mfma_f32_32x32x16_bf16 v[16:31], v[64:67], v[76:79], v[16:31]
	v_mfma_f32_32x32x16_bf16 v[0:15], v[68:71], v[220:223], v[0:15]
	v_mfma_f32_32x32x16_bf16 v[16:31], v[68:71], v[224:227], v[16:31]
	s_add_i32 s90, s76, 448
	v_add_u32_e32 v80, s90, v235
	v_add_u32_e32 v83, s90, v236
	v_add_u32_e32 v99, s90, v237
	v_add_u32_e32 v253, s90, v238
	v_add_u32_e32 v254, s90, v100
	v_add_u32_e32 v255, s90, v149
	v_med3_i32 v80, v80, 0, s99
	v_med3_i32 v83, v83, 0, s99
	v_med3_i32 v99, v99, 0, s99
	v_med3_i32 v253, v253, 0, s99
	v_med3_i32 v254, v254, 0, s99
	v_med3_i32 v255, v255, 0, s99
	v_mad_u32_u24 v80, v80, s100, v252
	v_mad_u32_u24 v83, v83, s100, v252
	v_mad_u32_u24 v99, v99, s100, v252
	v_mad_u32_u24 v253, v253, s100, v252
	v_mad_u32_u24 v254, v254, s100, v153
	v_mad_u32_u24 v255, v255, s100, v153
	global_load_dwordx4 v[156:159], v80, s[82:83]
	global_load_dwordx4 v[160:163], v83, s[82:83]
	global_load_dwordx4 v[164:167], v99, s[82:83]
	global_load_dwordx4 v[168:171], v253, s[82:83]
	global_load_dwordx4 v[172:175], v254, s[82:83] offset:768
	global_load_dwordx4 v[176:179], v255, s[82:83] offset:768
	global_load_dwordx4 v[180:183], v254, s[82:83] offset:832
	global_load_dwordx4 v[184:187], v255, s[82:83] offset:832
	s_waitcnt lgkmcnt(0)
	v_mfma_f32_32x32x16_bf16 v[32:47], v[188:191], v[48:51], v[32:47]
	ds_read_b64_tr_b16 v[72:73], v231
	ds_read_b64_tr_b16 v[74:75], v231 offset:512
	ds_read_b64_tr_b16 v[76:77], v231 offset:2048
	ds_read_b64_tr_b16 v[78:79], v231 offset:2560
	ds_read_b64_tr_b16 v[220:221], v231 offset:1024
	ds_read_b64_tr_b16 v[222:223], v231 offset:1536
	ds_read_b64_tr_b16 v[224:225], v231 offset:3072
	ds_read_b64_tr_b16 v[226:227], v231 offset:3584
	s_waitcnt vmcnt(8)
	ds_write_b128 v247, v[116:119]
	ds_write_b128 v247, v[120:123] offset:1024
	ds_write_b128 v247, v[124:127] offset:2048
	ds_write_b128 v247, v[128:131] offset:3072
	ds_read_b128 v[116:119], v248
	ds_read_b128 v[120:123], v249
	ds_read_b128 v[124:127], v250
	ds_read_b128 v[128:131], v251
	ds_write_b128 v112, v[132:135]
	ds_write_b128 v112, v[136:139] offset:1024
	ds_write_b128 v112, v[140:143] offset:2048
	ds_write_b128 v112, v[144:147] offset:3072
	v_mfma_f32_32x32x16_bf16 v[32:47], v[192:195], v[52:55], v[32:47]
	v_mfma_f32_32x32x16_bf16 v[32:47], v[196:199], v[56:59], v[32:47]
	v_mfma_f32_32x32x16_bf16 v[32:47], v[200:203], v[60:63], v[32:47]
	s_nop 11
	v_exp_f32_e32 v32, v32
	v_exp_f32_e32 v33, v33
	v_exp_f32_e32 v34, v34
	v_exp_f32_e32 v35, v35
	v_exp_f32_e32 v36, v36
	v_exp_f32_e32 v37, v37
	v_exp_f32_e32 v38, v38
	v_exp_f32_e32 v39, v39
	v_exp_f32_e32 v40, v40
	v_exp_f32_e32 v41, v41
	v_exp_f32_e32 v42, v42
	v_exp_f32_e32 v43, v43
	v_exp_f32_e32 v44, v44
	v_exp_f32_e32 v45, v45
	v_exp_f32_e32 v46, v46
	v_exp_f32_e32 v47, v47
	s_add_i32 s90, s76, 384
	v_add_u32_e32 v84, s90, v107
	v_add_u32_e32 v85, 0, v84
	v_add_u32_e32 v86, 1, v84
	v_add_u32_e32 v87, 2, v84
	v_add_u32_e32 v88, 3, v84
	v_cmp_gt_u32_e64 s[30:31], s98, v85
	v_cmp_gt_u32_e64 s[36:37], s98, v86
	v_cmp_gt_u32_e64 s[78:79], s98, v87
	v_cmp_gt_u32_e64 s[50:51], s98, v88
	v_cndmask_b32_e64 v32, 0, v32, s[30:31]
	v_add_u32_e32 v85, 8, v84
	v_cmp_gt_u32_e64 s[30:31], s98, v85
	v_cndmask_b32_e64 v33, 0, v33, s[36:37]
	v_add_u32_e32 v86, 9, v84
	v_cmp_gt_u32_e64 s[36:37], s98, v86
	v_cndmask_b32_e64 v34, 0, v34, s[78:79]
	v_add_u32_e32 v87, 10, v84
	v_cmp_gt_u32_e64 s[78:79], s98, v87
	v_cndmask_b32_e64 v35, 0, v35, s[50:51]
	v_add_u32_e32 v88, 11, v84
	v_cmp_gt_u32_e64 s[50:51], s98, v88
	v_cndmask_b32_e64 v36, 0, v36, s[30:31]
	v_add_u32_e32 v85, 16, v84
	v_cmp_gt_u32_e64 s[30:31], s98, v85
	v_cndmask_b32_e64 v37, 0, v37, s[36:37]
	v_add_u32_e32 v86, 17, v84
	v_cmp_gt_u32_e64 s[36:37], s98, v86
	v_cndmask_b32_e64 v38, 0, v38, s[78:79]
	v_add_u32_e32 v87, 18, v84
	v_cmp_gt_u32_e64 s[78:79], s98, v87
	v_cndmask_b32_e64 v39, 0, v39, s[50:51]
	v_add_u32_e32 v88, 19, v84
	v_cmp_gt_u32_e64 s[50:51], s98, v88
	v_cndmask_b32_e64 v40, 0, v40, s[30:31]
	v_add_u32_e32 v85, 24, v84
	v_cmp_gt_u32_e64 s[30:31], s98, v85
	v_cndmask_b32_e64 v41, 0, v41, s[36:37]
	v_add_u32_e32 v86, 25, v84
	v_cmp_gt_u32_e64 s[36:37], s98, v86
	v_cndmask_b32_e64 v42, 0, v42, s[78:79]
	v_add_u32_e32 v87, 26, v84
	v_cmp_gt_u32_e64 s[78:79], s98, v87
	v_cndmask_b32_e64 v43, 0, v43, s[50:51]
	v_add_u32_e32 v88, 27, v84
	v_cmp_gt_u32_e64 s[50:51], s98, v88
	v_nop
	v_cndmask_b32_e64 v44, 0, v44, s[30:31]
	v_cndmask_b32_e64 v45, 0, v45, s[36:37]
	v_cndmask_b32_e64 v46, 0, v46, s[78:79]
	v_cndmask_b32_e64 v47, 0, v47, s[50:51]
	v_cvt_pk_bf16_f32 v64, v32, v33
	v_cvt_pk_bf16_f32 v65, v34, v35
	v_cvt_pk_bf16_f32 v66, v36, v37
	v_cvt_pk_bf16_f32 v67, v38, v39
	v_cvt_pk_bf16_f32 v68, v40, v41
	v_cvt_pk_bf16_f32 v69, v42, v43
	v_cvt_pk_bf16_f32 v70, v44, v45
	v_cvt_pk_bf16_f32 v71, v46, v47
	v_pk_add_f32 v[232:233], v[232:233], v[32:33]
	v_pk_add_f32 v[232:233], v[232:233], v[34:35]
	v_pk_add_f32 v[232:233], v[232:233], v[36:37]
	v_pk_add_f32 v[232:233], v[232:233], v[38:39]
	v_pk_add_f32 v[232:233], v[232:233], v[40:41]
	v_pk_add_f32 v[232:233], v[232:233], v[42:43]
	v_pk_add_f32 v[232:233], v[232:233], v[44:45]
	v_pk_add_f32 v[232:233], v[232:233], v[46:47]
	ds_read2_b32 v[32:33], v115 offset0:34 offset1:35
	ds_read2_b32 v[34:35], v115 offset0:36 offset1:37
	ds_read2_b32 v[36:37], v115 offset0:42 offset1:43
	ds_read2_b32 v[38:39], v115 offset0:44 offset1:45
	ds_read2_b32 v[40:41], v115 offset0:51 offset1:52
	ds_read2_b32 v[42:43], v115 offset0:53 offset1:54
	ds_read2_b32 v[44:45], v115 offset0:59 offset1:60
	ds_read2_b32 v[46:47], v115 offset0:61 offset1:62
	s_waitcnt lgkmcnt(15)
	v_mfma_f32_32x32x16_bf16 v[0:15], v[64:67], v[72:75], v[0:15]
	v_mfma_f32_32x32x16_bf16 v[16:31], v[64:67], v[76:79], v[16:31]
	v_mfma_f32_32x32x16_bf16 v[0:15], v[68:71], v[220:223], v[0:15]
	v_mfma_f32_32x32x16_bf16 v[16:31], v[68:71], v[224:227], v[16:31]
	s_add_i32 s90, s76, 480
	v_add_u32_e32 v80, s90, v235
	v_add_u32_e32 v83, s90, v236
	v_add_u32_e32 v99, s90, v237
	v_add_u32_e32 v253, s90, v238
	v_add_u32_e32 v254, s90, v100
	v_add_u32_e32 v255, s90, v149
	v_med3_i32 v80, v80, 0, s99
	v_med3_i32 v83, v83, 0, s99
	v_med3_i32 v99, v99, 0, s99
	v_med3_i32 v253, v253, 0, s99
	v_med3_i32 v254, v254, 0, s99
	v_med3_i32 v255, v255, 0, s99
	v_mad_u32_u24 v80, v80, s100, v252
	v_mad_u32_u24 v83, v83, s100, v252
	v_mad_u32_u24 v99, v99, s100, v252
	v_mad_u32_u24 v253, v253, s100, v252
	v_mad_u32_u24 v254, v254, s100, v153
	v_mad_u32_u24 v255, v255, s100, v153
	global_load_dwordx4 v[188:191], v80, s[82:83]
	global_load_dwordx4 v[192:195], v83, s[82:83]
	global_load_dwordx4 v[196:199], v99, s[82:83]
	global_load_dwordx4 v[200:203], v253, s[82:83]
	global_load_dwordx4 v[204:207], v254, s[82:83] offset:768
	global_load_dwordx4 v[208:211], v255, s[82:83] offset:768
	global_load_dwordx4 v[212:215], v254, s[82:83] offset:832
	global_load_dwordx4 v[216:219], v255, s[82:83] offset:832
	s_waitcnt lgkmcnt(0)
	v_mfma_f32_32x32x16_bf16 v[32:47], v[116:119], v[48:51], v[32:47]
	ds_read_b64_tr_b16 v[72:73], v231
	ds_read_b64_tr_b16 v[74:75], v231 offset:512
	ds_read_b64_tr_b16 v[76:77], v231 offset:2048
	ds_read_b64_tr_b16 v[78:79], v231 offset:2560
	ds_read_b64_tr_b16 v[220:221], v231 offset:1024
	ds_read_b64_tr_b16 v[222:223], v231 offset:1536
	ds_read_b64_tr_b16 v[224:225], v231 offset:3072
	ds_read_b64_tr_b16 v[226:227], v231 offset:3584
	s_waitcnt vmcnt(8)
	ds_write_b128 v247, v[156:159]
	ds_write_b128 v247, v[160:163] offset:1024
	ds_write_b128 v247, v[164:167] offset:2048
	ds_write_b128 v247, v[168:171] offset:3072
	ds_read_b128 v[156:159], v248
	ds_read_b128 v[160:163], v249
	ds_read_b128 v[164:167], v250
	ds_read_b128 v[168:171], v251
	ds_write_b128 v112, v[172:175]
	ds_write_b128 v112, v[176:179] offset:1024
	ds_write_b128 v112, v[180:183] offset:2048
	ds_write_b128 v112, v[184:187] offset:3072
	v_mfma_f32_32x32x16_bf16 v[32:47], v[120:123], v[52:55], v[32:47]
	v_mfma_f32_32x32x16_bf16 v[32:47], v[124:127], v[56:59], v[32:47]
	v_mfma_f32_32x32x16_bf16 v[32:47], v[128:131], v[60:63], v[32:47]
	s_nop 11
	v_exp_f32_e32 v32, v32
	v_exp_f32_e32 v33, v33
	v_exp_f32_e32 v34, v34
	v_exp_f32_e32 v35, v35
	v_exp_f32_e32 v36, v36
	v_exp_f32_e32 v37, v37
	v_exp_f32_e32 v38, v38
	v_exp_f32_e32 v39, v39
	v_exp_f32_e32 v40, v40
	v_exp_f32_e32 v41, v41
	v_exp_f32_e32 v42, v42
	v_exp_f32_e32 v43, v43
	v_exp_f32_e32 v44, v44
	v_exp_f32_e32 v45, v45
	v_exp_f32_e32 v46, v46
	v_exp_f32_e32 v47, v47
	s_add_i32 s90, s76, 416
	v_add_u32_e32 v84, s90, v107
	v_add_u32_e32 v85, 0, v84
	v_add_u32_e32 v86, 1, v84
	v_add_u32_e32 v87, 2, v84
	v_add_u32_e32 v88, 3, v84
	v_cmp_gt_u32_e64 s[30:31], s98, v85
	v_cmp_gt_u32_e64 s[36:37], s98, v86
	v_cmp_gt_u32_e64 s[78:79], s98, v87
	v_cmp_gt_u32_e64 s[50:51], s98, v88
	v_cndmask_b32_e64 v32, 0, v32, s[30:31]
	v_add_u32_e32 v85, 8, v84
	v_cmp_gt_u32_e64 s[30:31], s98, v85
	v_cndmask_b32_e64 v33, 0, v33, s[36:37]
	v_add_u32_e32 v86, 9, v84
	v_cmp_gt_u32_e64 s[36:37], s98, v86
	v_cndmask_b32_e64 v34, 0, v34, s[78:79]
	v_add_u32_e32 v87, 10, v84
	v_cmp_gt_u32_e64 s[78:79], s98, v87
	v_cndmask_b32_e64 v35, 0, v35, s[50:51]
	v_add_u32_e32 v88, 11, v84
	v_cmp_gt_u32_e64 s[50:51], s98, v88
	v_cndmask_b32_e64 v36, 0, v36, s[30:31]
	v_add_u32_e32 v85, 16, v84
	v_cmp_gt_u32_e64 s[30:31], s98, v85
	v_cndmask_b32_e64 v37, 0, v37, s[36:37]
	v_add_u32_e32 v86, 17, v84
	v_cmp_gt_u32_e64 s[36:37], s98, v86
	v_cndmask_b32_e64 v38, 0, v38, s[78:79]
	v_add_u32_e32 v87, 18, v84
	v_cmp_gt_u32_e64 s[78:79], s98, v87
	v_cndmask_b32_e64 v39, 0, v39, s[50:51]
	v_add_u32_e32 v88, 19, v84
	v_cmp_gt_u32_e64 s[50:51], s98, v88
	v_cndmask_b32_e64 v40, 0, v40, s[30:31]
	v_add_u32_e32 v85, 24, v84
	v_cmp_gt_u32_e64 s[30:31], s98, v85
	v_cndmask_b32_e64 v41, 0, v41, s[36:37]
	v_add_u32_e32 v86, 25, v84
	v_cmp_gt_u32_e64 s[36:37], s98, v86
	v_cndmask_b32_e64 v42, 0, v42, s[78:79]
	v_add_u32_e32 v87, 26, v84
	v_cmp_gt_u32_e64 s[78:79], s98, v87
	v_cndmask_b32_e64 v43, 0, v43, s[50:51]
	v_add_u32_e32 v88, 27, v84
	v_cmp_gt_u32_e64 s[50:51], s98, v88
	v_nop
	v_cndmask_b32_e64 v44, 0, v44, s[30:31]
	v_cndmask_b32_e64 v45, 0, v45, s[36:37]
	v_cndmask_b32_e64 v46, 0, v46, s[78:79]
	v_cndmask_b32_e64 v47, 0, v47, s[50:51]
	v_cvt_pk_bf16_f32 v64, v32, v33
	v_cvt_pk_bf16_f32 v65, v34, v35
	v_cvt_pk_bf16_f32 v66, v36, v37
	v_cvt_pk_bf16_f32 v67, v38, v39
	v_cvt_pk_bf16_f32 v68, v40, v41
	v_cvt_pk_bf16_f32 v69, v42, v43
	v_cvt_pk_bf16_f32 v70, v44, v45
	v_cvt_pk_bf16_f32 v71, v46, v47
	v_pk_add_f32 v[232:233], v[232:233], v[32:33]
	v_pk_add_f32 v[232:233], v[232:233], v[34:35]
	v_pk_add_f32 v[232:233], v[232:233], v[36:37]
	v_pk_add_f32 v[232:233], v[232:233], v[38:39]
	v_pk_add_f32 v[232:233], v[232:233], v[40:41]
	v_pk_add_f32 v[232:233], v[232:233], v[42:43]
	v_pk_add_f32 v[232:233], v[232:233], v[44:45]
	v_pk_add_f32 v[232:233], v[232:233], v[46:47]
	ds_read2_b32 v[32:33], v115 offset0:68 offset1:69
	ds_read2_b32 v[34:35], v115 offset0:70 offset1:71
	ds_read2_b32 v[36:37], v115 offset0:76 offset1:77
	ds_read2_b32 v[38:39], v115 offset0:78 offset1:79
	ds_read2_b32 v[40:41], v115 offset0:85 offset1:86
	ds_read2_b32 v[42:43], v115 offset0:87 offset1:88
	ds_read2_b32 v[44:45], v115 offset0:93 offset1:94
	ds_read2_b32 v[46:47], v115 offset0:95 offset1:96
	s_waitcnt lgkmcnt(15)
	v_mfma_f32_32x32x16_bf16 v[0:15], v[64:67], v[72:75], v[0:15]
	v_mfma_f32_32x32x16_bf16 v[16:31], v[64:67], v[76:79], v[16:31]
	v_mfma_f32_32x32x16_bf16 v[0:15], v[68:71], v[220:223], v[0:15]
	v_mfma_f32_32x32x16_bf16 v[16:31], v[68:71], v[224:227], v[16:31]
	s_add_i32 s90, s76, 512
	v_add_u32_e32 v80, s90, v235
	v_add_u32_e32 v83, s90, v236
	v_add_u32_e32 v99, s90, v237
	v_add_u32_e32 v253, s90, v238
	v_add_u32_e32 v254, s90, v100
	v_add_u32_e32 v255, s90, v149
	v_med3_i32 v80, v80, 0, s99
	v_med3_i32 v83, v83, 0, s99
	v_med3_i32 v99, v99, 0, s99
	v_med3_i32 v253, v253, 0, s99
	v_med3_i32 v254, v254, 0, s99
	v_med3_i32 v255, v255, 0, s99
	v_mad_u32_u24 v80, v80, s100, v252
	v_mad_u32_u24 v83, v83, s100, v252
	v_mad_u32_u24 v99, v99, s100, v252
	v_mad_u32_u24 v253, v253, s100, v252
	v_mad_u32_u24 v254, v254, s100, v153
	v_mad_u32_u24 v255, v255, s100, v153
	global_load_dwordx4 v[116:119], v80, s[82:83]
	global_load_dwordx4 v[120:123], v83, s[82:83]
	global_load_dwordx4 v[124:127], v99, s[82:83]
	global_load_dwordx4 v[128:131], v253, s[82:83]
	global_load_dwordx4 v[132:135], v254, s[82:83] offset:768
	global_load_dwordx4 v[136:139], v255, s[82:83] offset:768
	global_load_dwordx4 v[140:143], v254, s[82:83] offset:832
	global_load_dwordx4 v[144:147], v255, s[82:83] offset:832
	s_waitcnt lgkmcnt(0)
	v_mfma_f32_32x32x16_bf16 v[32:47], v[156:159], v[48:51], v[32:47]
	ds_read_b64_tr_b16 v[72:73], v231
	ds_read_b64_tr_b16 v[74:75], v231 offset:512
	ds_read_b64_tr_b16 v[76:77], v231 offset:2048
	ds_read_b64_tr_b16 v[78:79], v231 offset:2560
	ds_read_b64_tr_b16 v[220:221], v231 offset:1024
	ds_read_b64_tr_b16 v[222:223], v231 offset:1536
	ds_read_b64_tr_b16 v[224:225], v231 offset:3072
	ds_read_b64_tr_b16 v[226:227], v231 offset:3584
	s_waitcnt vmcnt(8)
	ds_write_b128 v247, v[188:191]
	ds_write_b128 v247, v[192:195] offset:1024
	ds_write_b128 v247, v[196:199] offset:2048
	ds_write_b128 v247, v[200:203] offset:3072
	ds_read_b128 v[188:191], v248
	ds_read_b128 v[192:195], v249
	ds_read_b128 v[196:199], v250
	ds_read_b128 v[200:203], v251
	ds_write_b128 v112, v[204:207]
	ds_write_b128 v112, v[208:211] offset:1024
	ds_write_b128 v112, v[212:215] offset:2048
	ds_write_b128 v112, v[216:219] offset:3072
	v_mfma_f32_32x32x16_bf16 v[32:47], v[160:163], v[52:55], v[32:47]
	v_mfma_f32_32x32x16_bf16 v[32:47], v[164:167], v[56:59], v[32:47]
	v_mfma_f32_32x32x16_bf16 v[32:47], v[168:171], v[60:63], v[32:47]
	s_nop 11
	v_exp_f32_e32 v32, v32
	v_exp_f32_e32 v33, v33
	v_exp_f32_e32 v34, v34
	v_exp_f32_e32 v35, v35
	v_exp_f32_e32 v36, v36
	v_exp_f32_e32 v37, v37
	v_exp_f32_e32 v38, v38
	v_exp_f32_e32 v39, v39
	v_exp_f32_e32 v40, v40
	v_exp_f32_e32 v41, v41
	v_exp_f32_e32 v42, v42
	v_exp_f32_e32 v43, v43
	v_exp_f32_e32 v44, v44
	v_exp_f32_e32 v45, v45
	v_exp_f32_e32 v46, v46
	v_exp_f32_e32 v47, v47
	s_add_i32 s90, s76, 448
	v_add_u32_e32 v84, s90, v107
	v_add_u32_e32 v85, 0, v84
	v_add_u32_e32 v86, 1, v84
	v_add_u32_e32 v87, 2, v84
	v_add_u32_e32 v88, 3, v84
	v_cmp_gt_u32_e64 s[30:31], s98, v85
	v_cmp_gt_u32_e64 s[36:37], s98, v86
	v_cmp_gt_u32_e64 s[78:79], s98, v87
	v_cmp_gt_u32_e64 s[50:51], s98, v88
	v_cndmask_b32_e64 v32, 0, v32, s[30:31]
	v_add_u32_e32 v85, 8, v84
	v_cmp_gt_u32_e64 s[30:31], s98, v85
	v_cndmask_b32_e64 v33, 0, v33, s[36:37]
	v_add_u32_e32 v86, 9, v84
	v_cmp_gt_u32_e64 s[36:37], s98, v86
	v_cndmask_b32_e64 v34, 0, v34, s[78:79]
	v_add_u32_e32 v87, 10, v84
	v_cmp_gt_u32_e64 s[78:79], s98, v87
	v_cndmask_b32_e64 v35, 0, v35, s[50:51]
	v_add_u32_e32 v88, 11, v84
	v_cmp_gt_u32_e64 s[50:51], s98, v88
	v_cndmask_b32_e64 v36, 0, v36, s[30:31]
	v_add_u32_e32 v85, 16, v84
	v_cmp_gt_u32_e64 s[30:31], s98, v85
	v_cndmask_b32_e64 v37, 0, v37, s[36:37]
	v_add_u32_e32 v86, 17, v84
	v_cmp_gt_u32_e64 s[36:37], s98, v86
	v_cndmask_b32_e64 v38, 0, v38, s[78:79]
	v_add_u32_e32 v87, 18, v84
	v_cmp_gt_u32_e64 s[78:79], s98, v87
	v_cndmask_b32_e64 v39, 0, v39, s[50:51]
	v_add_u32_e32 v88, 19, v84
	v_cmp_gt_u32_e64 s[50:51], s98, v88
	v_cndmask_b32_e64 v40, 0, v40, s[30:31]
	v_add_u32_e32 v85, 24, v84
	v_cmp_gt_u32_e64 s[30:31], s98, v85
	v_cndmask_b32_e64 v41, 0, v41, s[36:37]
	v_add_u32_e32 v86, 25, v84
	v_cmp_gt_u32_e64 s[36:37], s98, v86
	v_cndmask_b32_e64 v42, 0, v42, s[78:79]
	v_add_u32_e32 v87, 26, v84
	v_cmp_gt_u32_e64 s[78:79], s98, v87
	v_cndmask_b32_e64 v43, 0, v43, s[50:51]
	v_add_u32_e32 v88, 27, v84
	v_cmp_gt_u32_e64 s[50:51], s98, v88
	v_nop
	v_cndmask_b32_e64 v44, 0, v44, s[30:31]
	v_cndmask_b32_e64 v45, 0, v45, s[36:37]
	v_cndmask_b32_e64 v46, 0, v46, s[78:79]
	v_cndmask_b32_e64 v47, 0, v47, s[50:51]
	v_cvt_pk_bf16_f32 v64, v32, v33
	v_cvt_pk_bf16_f32 v65, v34, v35
	v_cvt_pk_bf16_f32 v66, v36, v37
	v_cvt_pk_bf16_f32 v67, v38, v39
	v_cvt_pk_bf16_f32 v68, v40, v41
	v_cvt_pk_bf16_f32 v69, v42, v43
	v_cvt_pk_bf16_f32 v70, v44, v45
	v_cvt_pk_bf16_f32 v71, v46, v47
	v_pk_add_f32 v[232:233], v[232:233], v[32:33]
	v_pk_add_f32 v[232:233], v[232:233], v[34:35]
	v_pk_add_f32 v[232:233], v[232:233], v[36:37]
	v_pk_add_f32 v[232:233], v[232:233], v[38:39]
	v_pk_add_f32 v[232:233], v[232:233], v[40:41]
	v_pk_add_f32 v[232:233], v[232:233], v[42:43]
	v_pk_add_f32 v[232:233], v[232:233], v[44:45]
	v_pk_add_f32 v[232:233], v[232:233], v[46:47]
	ds_read2_b32 v[32:33], v115 offset0:102 offset1:103
	ds_read2_b32 v[34:35], v115 offset0:104 offset1:105
	ds_read2_b32 v[36:37], v115 offset0:110 offset1:111
	ds_read2_b32 v[38:39], v115 offset0:112 offset1:113
	ds_read2_b32 v[40:41], v115 offset0:119 offset1:120
	ds_read2_b32 v[42:43], v115 offset0:121 offset1:122
	ds_read2_b32 v[44:45], v115 offset0:127 offset1:128
	ds_read2_b32 v[46:47], v115 offset0:129 offset1:130
	s_waitcnt lgkmcnt(15)
	v_mfma_f32_32x32x16_bf16 v[0:15], v[64:67], v[72:75], v[0:15]
	v_mfma_f32_32x32x16_bf16 v[16:31], v[64:67], v[76:79], v[16:31]
	v_mfma_f32_32x32x16_bf16 v[0:15], v[68:71], v[220:223], v[0:15]
	v_mfma_f32_32x32x16_bf16 v[16:31], v[68:71], v[224:227], v[16:31]
	s_add_i32 s90, s76, 544
	v_add_u32_e32 v80, s90, v235
	v_add_u32_e32 v83, s90, v236
	v_add_u32_e32 v99, s90, v237
	v_add_u32_e32 v253, s90, v238
	v_add_u32_e32 v254, s90, v100
	v_add_u32_e32 v255, s90, v149
	v_med3_i32 v80, v80, 0, s99
	v_med3_i32 v83, v83, 0, s99
	v_med3_i32 v99, v99, 0, s99
	v_med3_i32 v253, v253, 0, s99
	v_med3_i32 v254, v254, 0, s99
	v_med3_i32 v255, v255, 0, s99
	v_mad_u32_u24 v80, v80, s100, v252
	v_mad_u32_u24 v83, v83, s100, v252
	v_mad_u32_u24 v99, v99, s100, v252
	v_mad_u32_u24 v253, v253, s100, v252
	v_mad_u32_u24 v254, v254, s100, v153
	v_mad_u32_u24 v255, v255, s100, v153
	global_load_dwordx4 v[156:159], v80, s[82:83]
	global_load_dwordx4 v[160:163], v83, s[82:83]
	global_load_dwordx4 v[164:167], v99, s[82:83]
	global_load_dwordx4 v[168:171], v253, s[82:83]
	global_load_dwordx4 v[172:175], v254, s[82:83] offset:768
	global_load_dwordx4 v[176:179], v255, s[82:83] offset:768
	global_load_dwordx4 v[180:183], v254, s[82:83] offset:832
	global_load_dwordx4 v[184:187], v255, s[82:83] offset:832
	s_waitcnt lgkmcnt(0)
	v_mfma_f32_32x32x16_bf16 v[32:47], v[188:191], v[48:51], v[32:47]
	ds_read_b64_tr_b16 v[72:73], v231
	ds_read_b64_tr_b16 v[74:75], v231 offset:512
	ds_read_b64_tr_b16 v[76:77], v231 offset:2048
	ds_read_b64_tr_b16 v[78:79], v231 offset:2560
	ds_read_b64_tr_b16 v[220:221], v231 offset:1024
	ds_read_b64_tr_b16 v[222:223], v231 offset:1536
	ds_read_b64_tr_b16 v[224:225], v231 offset:3072
	ds_read_b64_tr_b16 v[226:227], v231 offset:3584
	s_waitcnt vmcnt(8)
	ds_write_b128 v247, v[116:119]
	ds_write_b128 v247, v[120:123] offset:1024
	ds_write_b128 v247, v[124:127] offset:2048
	ds_write_b128 v247, v[128:131] offset:3072
	ds_read_b128 v[116:119], v248
	ds_read_b128 v[120:123], v249
	ds_read_b128 v[124:127], v250
	ds_read_b128 v[128:131], v251
	ds_write_b128 v112, v[132:135]
	ds_write_b128 v112, v[136:139] offset:1024
	ds_write_b128 v112, v[140:143] offset:2048
	ds_write_b128 v112, v[144:147] offset:3072
	v_mfma_f32_32x32x16_bf16 v[32:47], v[192:195], v[52:55], v[32:47]
	v_mfma_f32_32x32x16_bf16 v[32:47], v[196:199], v[56:59], v[32:47]
	v_mfma_f32_32x32x16_bf16 v[32:47], v[200:203], v[60:63], v[32:47]
	s_nop 11
	v_exp_f32_e32 v32, v32
	v_exp_f32_e32 v33, v33
	v_exp_f32_e32 v34, v34
	v_exp_f32_e32 v35, v35
	v_exp_f32_e32 v36, v36
	v_exp_f32_e32 v37, v37
	v_exp_f32_e32 v38, v38
	v_exp_f32_e32 v39, v39
	v_exp_f32_e32 v40, v40
	v_exp_f32_e32 v41, v41
	v_exp_f32_e32 v42, v42
	v_exp_f32_e32 v43, v43
	v_exp_f32_e32 v44, v44
	v_exp_f32_e32 v45, v45
	v_exp_f32_e32 v46, v46
	v_exp_f32_e32 v47, v47
	s_add_i32 s90, s76, 480
	v_add_u32_e32 v84, s90, v107
	v_add_u32_e32 v85, 0, v84
	v_add_u32_e32 v86, 1, v84
	v_add_u32_e32 v87, 2, v84
	v_add_u32_e32 v88, 3, v84
	v_cmp_gt_u32_e64 s[30:31], s98, v85
	v_cmp_gt_u32_e64 s[36:37], s98, v86
	v_cmp_gt_u32_e64 s[78:79], s98, v87
	v_cmp_gt_u32_e64 s[50:51], s98, v88
	v_cndmask_b32_e64 v32, 0, v32, s[30:31]
	v_add_u32_e32 v85, 8, v84
	v_cmp_gt_u32_e64 s[30:31], s98, v85
	v_cndmask_b32_e64 v33, 0, v33, s[36:37]
	v_add_u32_e32 v86, 9, v84
	v_cmp_gt_u32_e64 s[36:37], s98, v86
	v_cndmask_b32_e64 v34, 0, v34, s[78:79]
	v_add_u32_e32 v87, 10, v84
	v_cmp_gt_u32_e64 s[78:79], s98, v87
	v_cndmask_b32_e64 v35, 0, v35, s[50:51]
	v_add_u32_e32 v88, 11, v84
	v_cmp_gt_u32_e64 s[50:51], s98, v88
	v_cndmask_b32_e64 v36, 0, v36, s[30:31]
	v_add_u32_e32 v85, 16, v84
	v_cmp_gt_u32_e64 s[30:31], s98, v85
	v_cndmask_b32_e64 v37, 0, v37, s[36:37]
	v_add_u32_e32 v86, 17, v84
	v_cmp_gt_u32_e64 s[36:37], s98, v86
	v_cndmask_b32_e64 v38, 0, v38, s[78:79]
	v_add_u32_e32 v87, 18, v84
	v_cmp_gt_u32_e64 s[78:79], s98, v87
	v_cndmask_b32_e64 v39, 0, v39, s[50:51]
	v_add_u32_e32 v88, 19, v84
	v_cmp_gt_u32_e64 s[50:51], s98, v88
	v_cndmask_b32_e64 v40, 0, v40, s[30:31]
	v_add_u32_e32 v85, 24, v84
	v_cmp_gt_u32_e64 s[30:31], s98, v85
	v_cndmask_b32_e64 v41, 0, v41, s[36:37]
	v_add_u32_e32 v86, 25, v84
	v_cmp_gt_u32_e64 s[36:37], s98, v86
	v_cndmask_b32_e64 v42, 0, v42, s[78:79]
	v_add_u32_e32 v87, 26, v84
	v_cmp_gt_u32_e64 s[78:79], s98, v87
	v_cndmask_b32_e64 v43, 0, v43, s[50:51]
	v_add_u32_e32 v88, 27, v84
	v_cmp_gt_u32_e64 s[50:51], s98, v88
	v_nop
	v_cndmask_b32_e64 v44, 0, v44, s[30:31]
	v_cndmask_b32_e64 v45, 0, v45, s[36:37]
	v_cndmask_b32_e64 v46, 0, v46, s[78:79]
	v_cndmask_b32_e64 v47, 0, v47, s[50:51]
	v_cvt_pk_bf16_f32 v64, v32, v33
	v_cvt_pk_bf16_f32 v65, v34, v35
	v_cvt_pk_bf16_f32 v66, v36, v37
	v_cvt_pk_bf16_f32 v67, v38, v39
	v_cvt_pk_bf16_f32 v68, v40, v41
	v_cvt_pk_bf16_f32 v69, v42, v43
	v_cvt_pk_bf16_f32 v70, v44, v45
	v_cvt_pk_bf16_f32 v71, v46, v47
	v_pk_add_f32 v[232:233], v[232:233], v[32:33]
	v_pk_add_f32 v[232:233], v[232:233], v[34:35]
	v_pk_add_f32 v[232:233], v[232:233], v[36:37]
	v_pk_add_f32 v[232:233], v[232:233], v[38:39]
	v_pk_add_f32 v[232:233], v[232:233], v[40:41]
	v_pk_add_f32 v[232:233], v[232:233], v[42:43]
	v_pk_add_f32 v[232:233], v[232:233], v[44:45]
	v_pk_add_f32 v[232:233], v[232:233], v[46:47]
	ds_read2_b32 v[32:33], v115 offset0:136 offset1:137
	ds_read2_b32 v[34:35], v115 offset0:138 offset1:139
	ds_read2_b32 v[36:37], v115 offset0:144 offset1:145
	ds_read2_b32 v[38:39], v115 offset0:146 offset1:147
	ds_read2_b32 v[40:41], v115 offset0:153 offset1:154
	ds_read2_b32 v[42:43], v115 offset0:155 offset1:156
	ds_read2_b32 v[44:45], v115 offset0:161 offset1:162
	ds_read2_b32 v[46:47], v115 offset0:163 offset1:164
	s_waitcnt lgkmcnt(15)
	v_mfma_f32_32x32x16_bf16 v[0:15], v[64:67], v[72:75], v[0:15]
	v_mfma_f32_32x32x16_bf16 v[16:31], v[64:67], v[76:79], v[16:31]
	v_mfma_f32_32x32x16_bf16 v[0:15], v[68:71], v[220:223], v[0:15]
	v_mfma_f32_32x32x16_bf16 v[16:31], v[68:71], v[224:227], v[16:31]
	s_add_i32 s90, s76, -256
	v_add_u32_e32 v80, s90, v239
	v_add_u32_e32 v83, s90, v240
	v_add_u32_e32 v99, s90, v241
	v_add_u32_e32 v253, s90, v242
	v_add_u32_e32 v254, s90, v101
	v_add_u32_e32 v255, s90, v150
	v_med3_i32 v80, v80, 0, s99
	v_med3_i32 v83, v83, 0, s99
	v_med3_i32 v99, v99, 0, s99
	v_med3_i32 v253, v253, 0, s99
	v_med3_i32 v254, v254, 0, s99
	v_med3_i32 v255, v255, 0, s99
	v_mad_u32_u24 v80, v80, s100, v252
	v_mad_u32_u24 v83, v83, s100, v252
	v_mad_u32_u24 v99, v99, s100, v252
	v_mad_u32_u24 v253, v253, s100, v252
	v_mad_u32_u24 v254, v254, s100, v153
	v_mad_u32_u24 v255, v255, s100, v153
	global_load_dwordx4 v[188:191], v80, s[82:83]
	global_load_dwordx4 v[192:195], v83, s[82:83]
	global_load_dwordx4 v[196:199], v99, s[82:83]
	global_load_dwordx4 v[200:203], v253, s[82:83]
	global_load_dwordx4 v[204:207], v254, s[82:83] offset:768
	global_load_dwordx4 v[208:211], v255, s[82:83] offset:768
	global_load_dwordx4 v[212:215], v254, s[82:83] offset:832
	global_load_dwordx4 v[216:219], v255, s[82:83] offset:832
	s_waitcnt lgkmcnt(0)
	v_mfma_f32_32x32x16_bf16 v[32:47], v[116:119], v[48:51], v[32:47]
	ds_read_b64_tr_b16 v[72:73], v231
	ds_read_b64_tr_b16 v[74:75], v231 offset:512
	ds_read_b64_tr_b16 v[76:77], v231 offset:2048
	ds_read_b64_tr_b16 v[78:79], v231 offset:2560
	ds_read_b64_tr_b16 v[220:221], v231 offset:1024
	ds_read_b64_tr_b16 v[222:223], v231 offset:1536
	ds_read_b64_tr_b16 v[224:225], v231 offset:3072
	ds_read_b64_tr_b16 v[226:227], v231 offset:3584
	s_waitcnt vmcnt(8)
	ds_write_b128 v247, v[156:159]
	ds_write_b128 v247, v[160:163] offset:1024
	ds_write_b128 v247, v[164:167] offset:2048
	ds_write_b128 v247, v[168:171] offset:3072
	ds_read_b128 v[156:159], v248
	ds_read_b128 v[160:163], v249
	ds_read_b128 v[164:167], v250
	ds_read_b128 v[168:171], v251
	ds_write_b128 v112, v[172:175]
	ds_write_b128 v112, v[176:179] offset:1024
	ds_write_b128 v112, v[180:183] offset:2048
	ds_write_b128 v112, v[184:187] offset:3072
	v_mfma_f32_32x32x16_bf16 v[32:47], v[120:123], v[52:55], v[32:47]
	v_mfma_f32_32x32x16_bf16 v[32:47], v[124:127], v[56:59], v[32:47]
	v_mfma_f32_32x32x16_bf16 v[32:47], v[128:131], v[60:63], v[32:47]
	s_nop 11
	v_exp_f32_e32 v32, v32
	v_exp_f32_e32 v33, v33
	v_exp_f32_e32 v34, v34
	v_exp_f32_e32 v35, v35
	v_exp_f32_e32 v36, v36
	v_exp_f32_e32 v37, v37
	v_exp_f32_e32 v38, v38
	v_exp_f32_e32 v39, v39
	v_exp_f32_e32 v40, v40
	v_exp_f32_e32 v41, v41
	v_exp_f32_e32 v42, v42
	v_exp_f32_e32 v43, v43
	v_exp_f32_e32 v44, v44
	v_exp_f32_e32 v45, v45
	v_exp_f32_e32 v46, v46
	v_exp_f32_e32 v47, v47
	s_add_i32 s90, s76, 512
	v_add_u32_e32 v84, s90, v107
	v_add_u32_e32 v85, 0, v84
	v_add_u32_e32 v86, 1, v84
	v_add_u32_e32 v87, 2, v84
	v_add_u32_e32 v88, 3, v84
	v_cmp_gt_u32_e64 s[30:31], s98, v85
	v_cmp_gt_u32_e64 s[36:37], s98, v86
	v_cmp_gt_u32_e64 s[78:79], s98, v87
	v_cmp_gt_u32_e64 s[50:51], s98, v88
	v_cndmask_b32_e64 v32, 0, v32, s[30:31]
	v_add_u32_e32 v85, 8, v84
	v_cmp_gt_u32_e64 s[30:31], s98, v85
	v_cndmask_b32_e64 v33, 0, v33, s[36:37]
	v_add_u32_e32 v86, 9, v84
	v_cmp_gt_u32_e64 s[36:37], s98, v86
	v_cndmask_b32_e64 v34, 0, v34, s[78:79]
	v_add_u32_e32 v87, 10, v84
	v_cmp_gt_u32_e64 s[78:79], s98, v87
	v_cndmask_b32_e64 v35, 0, v35, s[50:51]
	v_add_u32_e32 v88, 11, v84
	v_cmp_gt_u32_e64 s[50:51], s98, v88
	v_cndmask_b32_e64 v36, 0, v36, s[30:31]
	v_add_u32_e32 v85, 16, v84
	v_cmp_gt_u32_e64 s[30:31], s98, v85
	v_cndmask_b32_e64 v37, 0, v37, s[36:37]
	v_add_u32_e32 v86, 17, v84
	v_cmp_gt_u32_e64 s[36:37], s98, v86
	v_cndmask_b32_e64 v38, 0, v38, s[78:79]
	v_add_u32_e32 v87, 18, v84
	v_cmp_gt_u32_e64 s[78:79], s98, v87
	v_cndmask_b32_e64 v39, 0, v39, s[50:51]
	v_add_u32_e32 v88, 19, v84
	v_cmp_gt_u32_e64 s[50:51], s98, v88
	v_cndmask_b32_e64 v40, 0, v40, s[30:31]
	v_add_u32_e32 v85, 24, v84
	v_cmp_gt_u32_e64 s[30:31], s98, v85
	v_cndmask_b32_e64 v41, 0, v41, s[36:37]
	v_add_u32_e32 v86, 25, v84
	v_cmp_gt_u32_e64 s[36:37], s98, v86
	v_cndmask_b32_e64 v42, 0, v42, s[78:79]
	v_add_u32_e32 v87, 26, v84
	v_cmp_gt_u32_e64 s[78:79], s98, v87
	v_cndmask_b32_e64 v43, 0, v43, s[50:51]
	v_add_u32_e32 v88, 27, v84
	v_cmp_gt_u32_e64 s[50:51], s98, v88
	v_nop
	v_cndmask_b32_e64 v44, 0, v44, s[30:31]
	v_cndmask_b32_e64 v45, 0, v45, s[36:37]
	v_cndmask_b32_e64 v46, 0, v46, s[78:79]
	v_cndmask_b32_e64 v47, 0, v47, s[50:51]
	v_cvt_pk_bf16_f32 v64, v32, v33
	v_cvt_pk_bf16_f32 v65, v34, v35
	v_cvt_pk_bf16_f32 v66, v36, v37
	v_cvt_pk_bf16_f32 v67, v38, v39
	v_cvt_pk_bf16_f32 v68, v40, v41
	v_cvt_pk_bf16_f32 v69, v42, v43
	v_cvt_pk_bf16_f32 v70, v44, v45
	v_cvt_pk_bf16_f32 v71, v46, v47
	v_pk_add_f32 v[232:233], v[232:233], v[32:33]
	v_pk_add_f32 v[232:233], v[232:233], v[34:35]
	v_pk_add_f32 v[232:233], v[232:233], v[36:37]
	v_pk_add_f32 v[232:233], v[232:233], v[38:39]
	v_pk_add_f32 v[232:233], v[232:233], v[40:41]
	v_pk_add_f32 v[232:233], v[232:233], v[42:43]
	v_pk_add_f32 v[232:233], v[232:233], v[44:45]
	v_pk_add_f32 v[232:233], v[232:233], v[46:47]
	ds_read2_b32 v[32:33], v115 offset0:170 offset1:171
	ds_read2_b32 v[34:35], v115 offset0:172 offset1:173
	ds_read2_b32 v[36:37], v115 offset0:178 offset1:179
	ds_read2_b32 v[38:39], v115 offset0:180 offset1:181
	ds_read2_b32 v[40:41], v115 offset0:187 offset1:188
	ds_read2_b32 v[42:43], v115 offset0:189 offset1:190
	ds_read2_b32 v[44:45], v115 offset0:195 offset1:196
	ds_read2_b32 v[46:47], v115 offset0:197 offset1:198
	s_waitcnt lgkmcnt(15)
	v_mfma_f32_32x32x16_bf16 v[0:15], v[64:67], v[72:75], v[0:15]
	v_mfma_f32_32x32x16_bf16 v[16:31], v[64:67], v[76:79], v[16:31]
	v_mfma_f32_32x32x16_bf16 v[0:15], v[68:71], v[220:223], v[0:15]
	v_mfma_f32_32x32x16_bf16 v[16:31], v[68:71], v[224:227], v[16:31]
	s_add_i32 s90, s76, -128
	v_add_u32_e32 v80, s90, v239
	v_add_u32_e32 v83, s90, v240
	v_add_u32_e32 v99, s90, v241
	v_add_u32_e32 v253, s90, v242
	v_add_u32_e32 v254, s90, v101
	v_add_u32_e32 v255, s90, v150
	v_med3_i32 v80, v80, 0, s99
	v_med3_i32 v83, v83, 0, s99
	v_med3_i32 v99, v99, 0, s99
	v_med3_i32 v253, v253, 0, s99
	v_med3_i32 v254, v254, 0, s99
	v_med3_i32 v255, v255, 0, s99
	v_mad_u32_u24 v80, v80, s100, v252
	v_mad_u32_u24 v83, v83, s100, v252
	v_mad_u32_u24 v99, v99, s100, v252
	v_mad_u32_u24 v253, v253, s100, v252
	v_mad_u32_u24 v254, v254, s100, v153
	v_mad_u32_u24 v255, v255, s100, v153
	global_load_dwordx4 v[116:119], v80, s[82:83]
	global_load_dwordx4 v[120:123], v83, s[82:83]
	global_load_dwordx4 v[124:127], v99, s[82:83]
	global_load_dwordx4 v[128:131], v253, s[82:83]
	global_load_dwordx4 v[132:135], v254, s[82:83] offset:768
	global_load_dwordx4 v[136:139], v255, s[82:83] offset:768
	global_load_dwordx4 v[140:143], v254, s[82:83] offset:832
	global_load_dwordx4 v[144:147], v255, s[82:83] offset:832
	s_waitcnt lgkmcnt(0)
	v_mfma_f32_32x32x16_bf16 v[32:47], v[156:159], v[48:51], v[32:47]
	ds_read_b64_tr_b16 v[72:73], v231
	ds_read_b64_tr_b16 v[74:75], v231 offset:512
	ds_read_b64_tr_b16 v[76:77], v231 offset:2048
	ds_read_b64_tr_b16 v[78:79], v231 offset:2560
	ds_read_b64_tr_b16 v[220:221], v231 offset:1024
	ds_read_b64_tr_b16 v[222:223], v231 offset:1536
	ds_read_b64_tr_b16 v[224:225], v231 offset:3072
	ds_read_b64_tr_b16 v[226:227], v231 offset:3584
	s_waitcnt vmcnt(8)
	ds_write_b128 v247, v[188:191]
	ds_write_b128 v247, v[192:195] offset:1024
	ds_write_b128 v247, v[196:199] offset:2048
	ds_write_b128 v247, v[200:203] offset:3072
	ds_read_b128 v[188:191], v248
	ds_read_b128 v[192:195], v249
	ds_read_b128 v[196:199], v250
	ds_read_b128 v[200:203], v251
	ds_write_b128 v112, v[204:207]
	ds_write_b128 v112, v[208:211] offset:1024
	ds_write_b128 v112, v[212:215] offset:2048
	ds_write_b128 v112, v[216:219] offset:3072
	v_mfma_f32_32x32x16_bf16 v[32:47], v[160:163], v[52:55], v[32:47]
	v_mfma_f32_32x32x16_bf16 v[32:47], v[164:167], v[56:59], v[32:47]
	v_mfma_f32_32x32x16_bf16 v[32:47], v[168:171], v[60:63], v[32:47]
	s_nop 11
	v_exp_f32_e32 v32, v32
	v_exp_f32_e32 v33, v33
	v_exp_f32_e32 v34, v34
	v_exp_f32_e32 v35, v35
	v_exp_f32_e32 v36, v36
	v_exp_f32_e32 v37, v37
	v_exp_f32_e32 v38, v38
	v_exp_f32_e32 v39, v39
	v_exp_f32_e32 v40, v40
	v_exp_f32_e32 v41, v41
	v_exp_f32_e32 v42, v42
	v_exp_f32_e32 v43, v43
	v_exp_f32_e32 v44, v44
	v_exp_f32_e32 v45, v45
	v_exp_f32_e32 v46, v46
	v_exp_f32_e32 v47, v47
	s_add_i32 s90, s76, 544
	v_add_u32_e32 v84, s90, v107
	v_add_u32_e32 v85, 0, v84
	v_add_u32_e32 v86, 1, v84
	v_add_u32_e32 v87, 2, v84
	v_add_u32_e32 v88, 3, v84
	v_cmp_gt_u32_e64 s[30:31], s98, v85
	v_cmp_gt_u32_e64 s[36:37], s98, v86
	v_cmp_gt_u32_e64 s[78:79], s98, v87
	v_cmp_gt_u32_e64 s[50:51], s98, v88
	v_cndmask_b32_e64 v32, 0, v32, s[30:31]
	v_add_u32_e32 v85, 8, v84
	v_cmp_gt_u32_e64 s[30:31], s98, v85
	v_cndmask_b32_e64 v33, 0, v33, s[36:37]
	v_add_u32_e32 v86, 9, v84
	v_cmp_gt_u32_e64 s[36:37], s98, v86
	v_cndmask_b32_e64 v34, 0, v34, s[78:79]
	v_add_u32_e32 v87, 10, v84
	v_cmp_gt_u32_e64 s[78:79], s98, v87
	v_cndmask_b32_e64 v35, 0, v35, s[50:51]
	v_add_u32_e32 v88, 11, v84
	v_cmp_gt_u32_e64 s[50:51], s98, v88
	v_cndmask_b32_e64 v36, 0, v36, s[30:31]
	v_add_u32_e32 v85, 16, v84
	v_cmp_gt_u32_e64 s[30:31], s98, v85
	v_cndmask_b32_e64 v37, 0, v37, s[36:37]
	v_add_u32_e32 v86, 17, v84
	v_cmp_gt_u32_e64 s[36:37], s98, v86
	v_cndmask_b32_e64 v38, 0, v38, s[78:79]
	v_add_u32_e32 v87, 18, v84
	v_cmp_gt_u32_e64 s[78:79], s98, v87
	v_cndmask_b32_e64 v39, 0, v39, s[50:51]
	v_add_u32_e32 v88, 19, v84
	v_cmp_gt_u32_e64 s[50:51], s98, v88
	v_cndmask_b32_e64 v40, 0, v40, s[30:31]
	v_add_u32_e32 v85, 24, v84
	v_cmp_gt_u32_e64 s[30:31], s98, v85
	v_cndmask_b32_e64 v41, 0, v41, s[36:37]
	v_add_u32_e32 v86, 25, v84
	v_cmp_gt_u32_e64 s[36:37], s98, v86
	v_cndmask_b32_e64 v42, 0, v42, s[78:79]
	v_add_u32_e32 v87, 26, v84
	v_cmp_gt_u32_e64 s[78:79], s98, v87
	v_cndmask_b32_e64 v43, 0, v43, s[50:51]
	v_add_u32_e32 v88, 27, v84
	v_cmp_gt_u32_e64 s[50:51], s98, v88
	v_nop
	v_cndmask_b32_e64 v44, 0, v44, s[30:31]
	v_cndmask_b32_e64 v45, 0, v45, s[36:37]
	v_cndmask_b32_e64 v46, 0, v46, s[78:79]
	v_cndmask_b32_e64 v47, 0, v47, s[50:51]
	v_cvt_pk_bf16_f32 v64, v32, v33
	v_cvt_pk_bf16_f32 v65, v34, v35
	v_cvt_pk_bf16_f32 v66, v36, v37
	v_cvt_pk_bf16_f32 v67, v38, v39
	v_cvt_pk_bf16_f32 v68, v40, v41
	v_cvt_pk_bf16_f32 v69, v42, v43
	v_cvt_pk_bf16_f32 v70, v44, v45
	v_cvt_pk_bf16_f32 v71, v46, v47
	v_pk_add_f32 v[232:233], v[232:233], v[32:33]
	v_pk_add_f32 v[232:233], v[232:233], v[34:35]
	v_pk_add_f32 v[232:233], v[232:233], v[36:37]
	v_pk_add_f32 v[232:233], v[232:233], v[38:39]
	v_pk_add_f32 v[232:233], v[232:233], v[40:41]
	v_pk_add_f32 v[232:233], v[232:233], v[42:43]
	v_pk_add_f32 v[232:233], v[232:233], v[44:45]
	v_pk_add_f32 v[232:233], v[232:233], v[46:47]
	v_mov_b32_e32 v115, v229
	ds_read2_b32 v[32:33], v115 offset0:0 offset1:1
	ds_read2_b32 v[34:35], v115 offset0:2 offset1:3
	ds_read2_b32 v[36:37], v115 offset0:8 offset1:9
	ds_read2_b32 v[38:39], v115 offset0:10 offset1:11
	ds_read2_b32 v[40:41], v115 offset0:16 offset1:17
	ds_read2_b32 v[42:43], v115 offset0:18 offset1:19
	ds_read2_b32 v[44:45], v115 offset0:24 offset1:25
	ds_read2_b32 v[46:47], v115 offset0:26 offset1:27
	s_waitcnt lgkmcnt(15)
	v_mfma_f32_32x32x16_bf16 v[0:15], v[64:67], v[72:75], v[0:15]
	v_mfma_f32_32x32x16_bf16 v[16:31], v[64:67], v[76:79], v[16:31]
	v_mfma_f32_32x32x16_bf16 v[0:15], v[68:71], v[220:223], v[0:15]
	v_mfma_f32_32x32x16_bf16 v[16:31], v[68:71], v[224:227], v[16:31]
	s_add_i32 s90, s76, 0
	v_add_u32_e32 v80, s90, v239
	v_add_u32_e32 v83, s90, v240
	v_add_u32_e32 v99, s90, v241
	v_add_u32_e32 v253, s90, v242
	v_add_u32_e32 v254, s90, v101
	v_add_u32_e32 v255, s90, v150
	v_med3_i32 v80, v80, 0, s99
	v_med3_i32 v83, v83, 0, s99
	v_med3_i32 v99, v99, 0, s99
	v_med3_i32 v253, v253, 0, s99
	v_med3_i32 v254, v254, 0, s99
	v_med3_i32 v255, v255, 0, s99
	v_mad_u32_u24 v80, v80, s100, v252
	v_mad_u32_u24 v83, v83, s100, v252
	v_mad_u32_u24 v99, v99, s100, v252
	v_mad_u32_u24 v253, v253, s100, v252
	v_mad_u32_u24 v254, v254, s100, v153
	v_mad_u32_u24 v255, v255, s100, v153
	global_load_dwordx4 v[156:159], v80, s[82:83]
	global_load_dwordx4 v[160:163], v83, s[82:83]
	global_load_dwordx4 v[164:167], v99, s[82:83]
	global_load_dwordx4 v[168:171], v253, s[82:83]
	global_load_dwordx4 v[172:175], v254, s[82:83] offset:768
	global_load_dwordx4 v[176:179], v255, s[82:83] offset:768
	global_load_dwordx4 v[180:183], v254, s[82:83] offset:832
	global_load_dwordx4 v[184:187], v255, s[82:83] offset:832
	s_waitcnt lgkmcnt(0)
	v_mfma_f32_32x32x16_bf16 v[32:47], v[188:191], v[48:51], v[32:47]
	ds_read_b64_tr_b16 v[72:73], v231
	ds_read_b64_tr_b16 v[74:75], v231 offset:512
	ds_read_b64_tr_b16 v[76:77], v231 offset:2048
	ds_read_b64_tr_b16 v[78:79], v231 offset:2560
	ds_read_b64_tr_b16 v[220:221], v231 offset:1024
	ds_read_b64_tr_b16 v[222:223], v231 offset:1536
	ds_read_b64_tr_b16 v[224:225], v231 offset:3072
	ds_read_b64_tr_b16 v[226:227], v231 offset:3584
	s_waitcnt vmcnt(8)
	ds_write_b128 v247, v[116:119]
	ds_write_b128 v247, v[120:123] offset:1024
	ds_write_b128 v247, v[124:127] offset:2048
	ds_write_b128 v247, v[128:131] offset:3072
	ds_read_b128 v[116:119], v248
	ds_read_b128 v[120:123], v249
	ds_read_b128 v[124:127], v250
	ds_read_b128 v[128:131], v251
	ds_write_b128 v112, v[132:135]
	ds_write_b128 v112, v[136:139] offset:1024
	ds_write_b128 v112, v[140:143] offset:2048
	ds_write_b128 v112, v[144:147] offset:3072
	v_mfma_f32_32x32x16_bf16 v[32:47], v[192:195], v[52:55], v[32:47]
	v_mfma_f32_32x32x16_bf16 v[32:47], v[196:199], v[56:59], v[32:47]
	v_mfma_f32_32x32x16_bf16 v[32:47], v[200:203], v[60:63], v[32:47]
	s_nop 11
	v_exp_f32_e32 v32, v32
	v_exp_f32_e32 v33, v33
	v_exp_f32_e32 v34, v34
	v_exp_f32_e32 v35, v35
	v_exp_f32_e32 v36, v36
	v_exp_f32_e32 v37, v37
	v_exp_f32_e32 v38, v38
	v_exp_f32_e32 v39, v39
	v_exp_f32_e32 v40, v40
	v_exp_f32_e32 v41, v41
	v_exp_f32_e32 v42, v42
	v_exp_f32_e32 v43, v43
	v_exp_f32_e32 v44, v44
	v_exp_f32_e32 v45, v45
	v_exp_f32_e32 v46, v46
	v_exp_f32_e32 v47, v47
	s_add_i32 s90, s76, -256
	v_lshlrev_b32_e32 v84, 2, v107
	v_add_u32_e32 v84, s90, v84
	v_add_u32_e32 v85, 0, v84
	v_add_u32_e32 v86, 4, v84
	v_add_u32_e32 v87, 8, v84
	v_add_u32_e32 v88, 12, v84
	v_cmp_gt_u32_e64 s[30:31], s98, v85
	v_cmp_gt_u32_e64 s[36:37], s98, v86
	v_cmp_gt_u32_e64 s[78:79], s98, v87
	v_cmp_gt_u32_e64 s[50:51], s98, v88
	v_cndmask_b32_e64 v32, 0, v32, s[30:31]
	v_add_u32_e32 v85, 32, v84
	v_cmp_gt_u32_e64 s[30:31], s98, v85
	v_cndmask_b32_e64 v33, 0, v33, s[36:37]
	v_add_u32_e32 v86, 36, v84
	v_cmp_gt_u32_e64 s[36:37], s98, v86
	v_cndmask_b32_e64 v34, 0, v34, s[78:79]
	v_add_u32_e32 v87, 40, v84
	v_cmp_gt_u32_e64 s[78:79], s98, v87
	v_cndmask_b32_e64 v35, 0, v35, s[50:51]
	v_add_u32_e32 v88, 44, v84
	v_cmp_gt_u32_e64 s[50:51], s98, v88
	v_cndmask_b32_e64 v36, 0, v36, s[30:31]
	v_add_u32_e32 v85, 64, v84
	v_cmp_gt_u32_e64 s[30:31], s98, v85
	v_cndmask_b32_e64 v37, 0, v37, s[36:37]
	v_add_u32_e32 v86, 68, v84
	v_cmp_gt_u32_e64 s[36:37], s98, v86
	v_cndmask_b32_e64 v38, 0, v38, s[78:79]
	v_add_u32_e32 v87, 72, v84
	v_cmp_gt_u32_e64 s[78:79], s98, v87
	v_cndmask_b32_e64 v39, 0, v39, s[50:51]
	v_add_u32_e32 v88, 76, v84
	v_cmp_gt_u32_e64 s[50:51], s98, v88
	v_cndmask_b32_e64 v40, 0, v40, s[30:31]
	v_add_u32_e32 v85, 96, v84
	v_cmp_gt_u32_e64 s[30:31], s98, v85
	v_cndmask_b32_e64 v41, 0, v41, s[36:37]
	v_add_u32_e32 v86, 100, v84
	v_cmp_gt_u32_e64 s[36:37], s98, v86
	v_cndmask_b32_e64 v42, 0, v42, s[78:79]
	v_add_u32_e32 v87, 104, v84
	v_cmp_gt_u32_e64 s[78:79], s98, v87
	v_cndmask_b32_e64 v43, 0, v43, s[50:51]
	v_add_u32_e32 v88, 108, v84
	v_cmp_gt_u32_e64 s[50:51], s98, v88
	v_nop
	v_cndmask_b32_e64 v44, 0, v44, s[30:31]
	v_cndmask_b32_e64 v45, 0, v45, s[36:37]
	v_cndmask_b32_e64 v46, 0, v46, s[78:79]
	v_cndmask_b32_e64 v47, 0, v47, s[50:51]
	v_cvt_pk_bf16_f32 v64, v32, v33
	v_cvt_pk_bf16_f32 v65, v34, v35
	v_cvt_pk_bf16_f32 v66, v36, v37
	v_cvt_pk_bf16_f32 v67, v38, v39
	v_cvt_pk_bf16_f32 v68, v40, v41
	v_cvt_pk_bf16_f32 v69, v42, v43
	v_cvt_pk_bf16_f32 v70, v44, v45
	v_cvt_pk_bf16_f32 v71, v46, v47
	v_pk_add_f32 v[232:233], v[232:233], v[32:33]
	v_pk_add_f32 v[232:233], v[232:233], v[34:35]
	v_pk_add_f32 v[232:233], v[232:233], v[36:37]
	v_pk_add_f32 v[232:233], v[232:233], v[38:39]
	v_pk_add_f32 v[232:233], v[232:233], v[40:41]
	v_pk_add_f32 v[232:233], v[232:233], v[42:43]
	v_pk_add_f32 v[232:233], v[232:233], v[44:45]
	v_pk_add_f32 v[232:233], v[232:233], v[46:47]
	ds_read2_b32 v[32:33], v115 offset0:32 offset1:33
	ds_read2_b32 v[34:35], v115 offset0:34 offset1:35
	ds_read2_b32 v[36:37], v115 offset0:40 offset1:41
	ds_read2_b32 v[38:39], v115 offset0:42 offset1:43
	ds_read2_b32 v[40:41], v115 offset0:48 offset1:49
	ds_read2_b32 v[42:43], v115 offset0:50 offset1:51
	ds_read2_b32 v[44:45], v115 offset0:56 offset1:57
	ds_read2_b32 v[46:47], v115 offset0:58 offset1:59
	s_waitcnt lgkmcnt(15)
	v_mfma_f32_32x32x16_bf16 v[0:15], v[64:67], v[72:75], v[0:15]
	v_mfma_f32_32x32x16_bf16 v[16:31], v[64:67], v[76:79], v[16:31]
	v_mfma_f32_32x32x16_bf16 v[0:15], v[68:71], v[220:223], v[0:15]
	v_mfma_f32_32x32x16_bf16 v[16:31], v[68:71], v[224:227], v[16:31]
	s_add_i32 s90, s76, 128
	v_add_u32_e32 v80, s90, v239
	v_add_u32_e32 v83, s90, v240
	v_add_u32_e32 v99, s90, v241
	v_add_u32_e32 v253, s90, v242
	v_add_u32_e32 v254, s90, v101
	v_add_u32_e32 v255, s90, v150
	v_med3_i32 v80, v80, 0, s99
	v_med3_i32 v83, v83, 0, s99
	v_med3_i32 v99, v99, 0, s99
	v_med3_i32 v253, v253, 0, s99
	v_med3_i32 v254, v254, 0, s99
	v_med3_i32 v255, v255, 0, s99
	v_mad_u32_u24 v80, v80, s100, v252
	v_mad_u32_u24 v83, v83, s100, v252
	v_mad_u32_u24 v99, v99, s100, v252
	v_mad_u32_u24 v253, v253, s100, v252
	v_mad_u32_u24 v254, v254, s100, v153
	v_mad_u32_u24 v255, v255, s100, v153
	global_load_dwordx4 v[188:191], v80, s[82:83]
	global_load_dwordx4 v[192:195], v83, s[82:83]
	global_load_dwordx4 v[196:199], v99, s[82:83]
	global_load_dwordx4 v[200:203], v253, s[82:83]
	global_load_dwordx4 v[204:207], v254, s[82:83] offset:768
	global_load_dwordx4 v[208:211], v255, s[82:83] offset:768
	global_load_dwordx4 v[212:215], v254, s[82:83] offset:832
	global_load_dwordx4 v[216:219], v255, s[82:83] offset:832
	s_waitcnt lgkmcnt(0)
	v_mfma_f32_32x32x16_bf16 v[32:47], v[116:119], v[48:51], v[32:47]
	ds_read_b64_tr_b16 v[72:73], v231
	ds_read_b64_tr_b16 v[74:75], v231 offset:512
	ds_read_b64_tr_b16 v[76:77], v231 offset:2048
	ds_read_b64_tr_b16 v[78:79], v231 offset:2560
	ds_read_b64_tr_b16 v[220:221], v231 offset:1024
	ds_read_b64_tr_b16 v[222:223], v231 offset:1536
	ds_read_b64_tr_b16 v[224:225], v231 offset:3072
	ds_read_b64_tr_b16 v[226:227], v231 offset:3584
	s_waitcnt vmcnt(8)
	ds_write_b128 v247, v[156:159]
	ds_write_b128 v247, v[160:163] offset:1024
	ds_write_b128 v247, v[164:167] offset:2048
	ds_write_b128 v247, v[168:171] offset:3072
	ds_read_b128 v[156:159], v248
	ds_read_b128 v[160:163], v249
	ds_read_b128 v[164:167], v250
	ds_read_b128 v[168:171], v251
	ds_write_b128 v112, v[172:175]
	ds_write_b128 v112, v[176:179] offset:1024
	ds_write_b128 v112, v[180:183] offset:2048
	ds_write_b128 v112, v[184:187] offset:3072
	v_mfma_f32_32x32x16_bf16 v[32:47], v[120:123], v[52:55], v[32:47]
	v_mfma_f32_32x32x16_bf16 v[32:47], v[124:127], v[56:59], v[32:47]
	v_mfma_f32_32x32x16_bf16 v[32:47], v[128:131], v[60:63], v[32:47]
	s_nop 11
	v_exp_f32_e32 v32, v32
	v_exp_f32_e32 v33, v33
	v_exp_f32_e32 v34, v34
	v_exp_f32_e32 v35, v35
	v_exp_f32_e32 v36, v36
	v_exp_f32_e32 v37, v37
	v_exp_f32_e32 v38, v38
	v_exp_f32_e32 v39, v39
	v_exp_f32_e32 v40, v40
	v_exp_f32_e32 v41, v41
	v_exp_f32_e32 v42, v42
	v_exp_f32_e32 v43, v43
	v_exp_f32_e32 v44, v44
	v_exp_f32_e32 v45, v45
	v_exp_f32_e32 v46, v46
	v_exp_f32_e32 v47, v47
	s_add_i32 s90, s76, -128
	v_lshlrev_b32_e32 v84, 2, v107
	v_add_u32_e32 v84, s90, v84
	v_add_u32_e32 v85, 0, v84
	v_add_u32_e32 v86, 4, v84
	v_add_u32_e32 v87, 8, v84
	v_add_u32_e32 v88, 12, v84
	v_cmp_gt_u32_e64 s[30:31], s98, v85
	v_cmp_gt_u32_e64 s[36:37], s98, v86
	v_cmp_gt_u32_e64 s[78:79], s98, v87
	v_cmp_gt_u32_e64 s[50:51], s98, v88
	v_cndmask_b32_e64 v32, 0, v32, s[30:31]
	v_add_u32_e32 v85, 32, v84
	v_cmp_gt_u32_e64 s[30:31], s98, v85
	v_cndmask_b32_e64 v33, 0, v33, s[36:37]
	v_add_u32_e32 v86, 36, v84
	v_cmp_gt_u32_e64 s[36:37], s98, v86
	v_cndmask_b32_e64 v34, 0, v34, s[78:79]
	v_add_u32_e32 v87, 40, v84
	v_cmp_gt_u32_e64 s[78:79], s98, v87
	v_cndmask_b32_e64 v35, 0, v35, s[50:51]
	v_add_u32_e32 v88, 44, v84
	v_cmp_gt_u32_e64 s[50:51], s98, v88
	v_cndmask_b32_e64 v36, 0, v36, s[30:31]
	v_add_u32_e32 v85, 64, v84
	v_cmp_gt_u32_e64 s[30:31], s98, v85
	v_cndmask_b32_e64 v37, 0, v37, s[36:37]
	v_add_u32_e32 v86, 68, v84
	v_cmp_gt_u32_e64 s[36:37], s98, v86
	v_cndmask_b32_e64 v38, 0, v38, s[78:79]
	v_add_u32_e32 v87, 72, v84
	v_cmp_gt_u32_e64 s[78:79], s98, v87
	v_cndmask_b32_e64 v39, 0, v39, s[50:51]
	v_add_u32_e32 v88, 76, v84
	v_cmp_gt_u32_e64 s[50:51], s98, v88
	v_cndmask_b32_e64 v40, 0, v40, s[30:31]
	v_add_u32_e32 v85, 96, v84
	v_cmp_gt_u32_e64 s[30:31], s98, v85
	v_cndmask_b32_e64 v41, 0, v41, s[36:37]
	v_add_u32_e32 v86, 100, v84
	v_cmp_gt_u32_e64 s[36:37], s98, v86
	v_cndmask_b32_e64 v42, 0, v42, s[78:79]
	v_add_u32_e32 v87, 104, v84
	v_cmp_gt_u32_e64 s[78:79], s98, v87
	v_cndmask_b32_e64 v43, 0, v43, s[50:51]
	v_add_u32_e32 v88, 108, v84
	v_cmp_gt_u32_e64 s[50:51], s98, v88
	v_nop
	v_cndmask_b32_e64 v44, 0, v44, s[30:31]
	v_cndmask_b32_e64 v45, 0, v45, s[36:37]
	v_cndmask_b32_e64 v46, 0, v46, s[78:79]
	v_cndmask_b32_e64 v47, 0, v47, s[50:51]
	v_cvt_pk_bf16_f32 v64, v32, v33
	v_cvt_pk_bf16_f32 v65, v34, v35
	v_cvt_pk_bf16_f32 v66, v36, v37
	v_cvt_pk_bf16_f32 v67, v38, v39
	v_cvt_pk_bf16_f32 v68, v40, v41
	v_cvt_pk_bf16_f32 v69, v42, v43
	v_cvt_pk_bf16_f32 v70, v44, v45
	v_cvt_pk_bf16_f32 v71, v46, v47
	v_pk_add_f32 v[232:233], v[232:233], v[32:33]
	v_pk_add_f32 v[232:233], v[232:233], v[34:35]
	v_pk_add_f32 v[232:233], v[232:233], v[36:37]
	v_pk_add_f32 v[232:233], v[232:233], v[38:39]
	v_pk_add_f32 v[232:233], v[232:233], v[40:41]
	v_pk_add_f32 v[232:233], v[232:233], v[42:43]
	v_pk_add_f32 v[232:233], v[232:233], v[44:45]
	v_pk_add_f32 v[232:233], v[232:233], v[46:47]
	ds_read2_b32 v[32:33], v115 offset0:64 offset1:65
	ds_read2_b32 v[34:35], v115 offset0:66 offset1:67
	ds_read2_b32 v[36:37], v115 offset0:72 offset1:73
	ds_read2_b32 v[38:39], v115 offset0:74 offset1:75
	ds_read2_b32 v[40:41], v115 offset0:80 offset1:81
	ds_read2_b32 v[42:43], v115 offset0:82 offset1:83
	ds_read2_b32 v[44:45], v115 offset0:88 offset1:89
	ds_read2_b32 v[46:47], v115 offset0:90 offset1:91
	s_waitcnt lgkmcnt(15)
	v_mfma_f32_32x32x16_bf16 v[0:15], v[64:67], v[72:75], v[0:15]
	v_mfma_f32_32x32x16_bf16 v[16:31], v[64:67], v[76:79], v[16:31]
	v_mfma_f32_32x32x16_bf16 v[0:15], v[68:71], v[220:223], v[0:15]
	v_mfma_f32_32x32x16_bf16 v[16:31], v[68:71], v[224:227], v[16:31]
	s_add_i32 s90, s76, 256
	v_add_u32_e32 v80, s90, v239
	v_add_u32_e32 v83, s90, v240
	v_add_u32_e32 v99, s90, v241
	v_add_u32_e32 v253, s90, v242
	v_add_u32_e32 v254, s90, v101
	v_add_u32_e32 v255, s90, v150
	v_med3_i32 v80, v80, 0, s99
	v_med3_i32 v83, v83, 0, s99
	v_med3_i32 v99, v99, 0, s99
	v_med3_i32 v253, v253, 0, s99
	v_med3_i32 v254, v254, 0, s99
	v_med3_i32 v255, v255, 0, s99
	v_mad_u32_u24 v80, v80, s100, v252
	v_mad_u32_u24 v83, v83, s100, v252
	v_mad_u32_u24 v99, v99, s100, v252
	v_mad_u32_u24 v253, v253, s100, v252
	v_mad_u32_u24 v254, v254, s100, v153
	v_mad_u32_u24 v255, v255, s100, v153
	global_load_dwordx4 v[116:119], v80, s[82:83]
	global_load_dwordx4 v[120:123], v83, s[82:83]
	global_load_dwordx4 v[124:127], v99, s[82:83]
	global_load_dwordx4 v[128:131], v253, s[82:83]
	global_load_dwordx4 v[132:135], v254, s[82:83] offset:768
	global_load_dwordx4 v[136:139], v255, s[82:83] offset:768
	global_load_dwordx4 v[140:143], v254, s[82:83] offset:832
	global_load_dwordx4 v[144:147], v255, s[82:83] offset:832
	s_waitcnt lgkmcnt(0)
	v_mfma_f32_32x32x16_bf16 v[32:47], v[156:159], v[48:51], v[32:47]
	ds_read_b64_tr_b16 v[72:73], v231
	ds_read_b64_tr_b16 v[74:75], v231 offset:512
	ds_read_b64_tr_b16 v[76:77], v231 offset:2048
	ds_read_b64_tr_b16 v[78:79], v231 offset:2560
	ds_read_b64_tr_b16 v[220:221], v231 offset:1024
	ds_read_b64_tr_b16 v[222:223], v231 offset:1536
	ds_read_b64_tr_b16 v[224:225], v231 offset:3072
	ds_read_b64_tr_b16 v[226:227], v231 offset:3584
	s_waitcnt vmcnt(8)
	ds_write_b128 v247, v[188:191]
	ds_write_b128 v247, v[192:195] offset:1024
	ds_write_b128 v247, v[196:199] offset:2048
	ds_write_b128 v247, v[200:203] offset:3072
	ds_read_b128 v[188:191], v248
	ds_read_b128 v[192:195], v249
	ds_read_b128 v[196:199], v250
	ds_read_b128 v[200:203], v251
	ds_write_b128 v112, v[204:207]
	ds_write_b128 v112, v[208:211] offset:1024
	ds_write_b128 v112, v[212:215] offset:2048
	ds_write_b128 v112, v[216:219] offset:3072
	v_mfma_f32_32x32x16_bf16 v[32:47], v[160:163], v[52:55], v[32:47]
	v_mfma_f32_32x32x16_bf16 v[32:47], v[164:167], v[56:59], v[32:47]
	v_mfma_f32_32x32x16_bf16 v[32:47], v[168:171], v[60:63], v[32:47]
	s_nop 11
	v_exp_f32_e32 v32, v32
	v_exp_f32_e32 v33, v33
	v_exp_f32_e32 v34, v34
	v_exp_f32_e32 v35, v35
	v_exp_f32_e32 v36, v36
	v_exp_f32_e32 v37, v37
	v_exp_f32_e32 v38, v38
	v_exp_f32_e32 v39, v39
	v_exp_f32_e32 v40, v40
	v_exp_f32_e32 v41, v41
	v_exp_f32_e32 v42, v42
	v_exp_f32_e32 v43, v43
	v_exp_f32_e32 v44, v44
	v_exp_f32_e32 v45, v45
	v_exp_f32_e32 v46, v46
	v_exp_f32_e32 v47, v47
	s_add_i32 s90, s76, 0
	v_lshlrev_b32_e32 v84, 2, v107
	v_add_u32_e32 v84, s90, v84
	v_add_u32_e32 v85, 0, v84
	v_add_u32_e32 v86, 4, v84
	v_add_u32_e32 v87, 8, v84
	v_add_u32_e32 v88, 12, v84
	v_cmp_gt_u32_e64 s[30:31], s98, v85
	v_cmp_gt_u32_e64 s[36:37], s98, v86
	v_cmp_gt_u32_e64 s[78:79], s98, v87
	v_cmp_gt_u32_e64 s[50:51], s98, v88
	v_cndmask_b32_e64 v32, 0, v32, s[30:31]
	v_add_u32_e32 v85, 32, v84
	v_cmp_gt_u32_e64 s[30:31], s98, v85
	v_cndmask_b32_e64 v33, 0, v33, s[36:37]
	v_add_u32_e32 v86, 36, v84
	v_cmp_gt_u32_e64 s[36:37], s98, v86
	v_cndmask_b32_e64 v34, 0, v34, s[78:79]
	v_add_u32_e32 v87, 40, v84
	v_cmp_gt_u32_e64 s[78:79], s98, v87
	v_cndmask_b32_e64 v35, 0, v35, s[50:51]
	v_add_u32_e32 v88, 44, v84
	v_cmp_gt_u32_e64 s[50:51], s98, v88
	v_cndmask_b32_e64 v36, 0, v36, s[30:31]
	v_add_u32_e32 v85, 64, v84
	v_cmp_gt_u32_e64 s[30:31], s98, v85
	v_cndmask_b32_e64 v37, 0, v37, s[36:37]
	v_add_u32_e32 v86, 68, v84
	v_cmp_gt_u32_e64 s[36:37], s98, v86
	v_cndmask_b32_e64 v38, 0, v38, s[78:79]
	v_add_u32_e32 v87, 72, v84
	v_cmp_gt_u32_e64 s[78:79], s98, v87
	v_cndmask_b32_e64 v39, 0, v39, s[50:51]
	v_add_u32_e32 v88, 76, v84
	v_cmp_gt_u32_e64 s[50:51], s98, v88
	v_cndmask_b32_e64 v40, 0, v40, s[30:31]
	v_add_u32_e32 v85, 96, v84
	v_cmp_gt_u32_e64 s[30:31], s98, v85
	v_cndmask_b32_e64 v41, 0, v41, s[36:37]
	v_add_u32_e32 v86, 100, v84
	v_cmp_gt_u32_e64 s[36:37], s98, v86
	v_cndmask_b32_e64 v42, 0, v42, s[78:79]
	v_add_u32_e32 v87, 104, v84
	v_cmp_gt_u32_e64 s[78:79], s98, v87
	v_cndmask_b32_e64 v43, 0, v43, s[50:51]
	v_add_u32_e32 v88, 108, v84
	v_cmp_gt_u32_e64 s[50:51], s98, v88
	v_nop
	v_cndmask_b32_e64 v44, 0, v44, s[30:31]
	v_cndmask_b32_e64 v45, 0, v45, s[36:37]
	v_cndmask_b32_e64 v46, 0, v46, s[78:79]
	v_cndmask_b32_e64 v47, 0, v47, s[50:51]
	v_cvt_pk_bf16_f32 v64, v32, v33
	v_cvt_pk_bf16_f32 v65, v34, v35
	v_cvt_pk_bf16_f32 v66, v36, v37
	v_cvt_pk_bf16_f32 v67, v38, v39
	v_cvt_pk_bf16_f32 v68, v40, v41
	v_cvt_pk_bf16_f32 v69, v42, v43
	v_cvt_pk_bf16_f32 v70, v44, v45
	v_cvt_pk_bf16_f32 v71, v46, v47
	v_pk_add_f32 v[232:233], v[232:233], v[32:33]
	v_pk_add_f32 v[232:233], v[232:233], v[34:35]
	v_pk_add_f32 v[232:233], v[232:233], v[36:37]
	v_pk_add_f32 v[232:233], v[232:233], v[38:39]
	v_pk_add_f32 v[232:233], v[232:233], v[40:41]
	v_pk_add_f32 v[232:233], v[232:233], v[42:43]
	v_pk_add_f32 v[232:233], v[232:233], v[44:45]
	v_pk_add_f32 v[232:233], v[232:233], v[46:47]
	ds_read2_b32 v[32:33], v115 offset0:96 offset1:97
	ds_read2_b32 v[34:35], v115 offset0:98 offset1:99
	ds_read2_b32 v[36:37], v115 offset0:104 offset1:105
	ds_read2_b32 v[38:39], v115 offset0:106 offset1:107
	ds_read2_b32 v[40:41], v115 offset0:112 offset1:113
	ds_read2_b32 v[42:43], v115 offset0:114 offset1:115
	ds_read2_b32 v[44:45], v115 offset0:120 offset1:121
	ds_read2_b32 v[46:47], v115 offset0:122 offset1:123
	s_waitcnt lgkmcnt(15)
	v_mfma_f32_32x32x16_bf16 v[0:15], v[64:67], v[72:75], v[0:15]
	v_mfma_f32_32x32x16_bf16 v[16:31], v[64:67], v[76:79], v[16:31]
	v_mfma_f32_32x32x16_bf16 v[0:15], v[68:71], v[220:223], v[0:15]
	v_mfma_f32_32x32x16_bf16 v[16:31], v[68:71], v[224:227], v[16:31]
	s_add_i32 s90, s76, 384
	v_add_u32_e32 v80, s90, v239
	v_add_u32_e32 v83, s90, v240
	v_add_u32_e32 v99, s90, v241
	v_add_u32_e32 v253, s90, v242
	v_add_u32_e32 v254, s90, v101
	v_add_u32_e32 v255, s90, v150
	v_med3_i32 v80, v80, 0, s99
	v_med3_i32 v83, v83, 0, s99
	v_med3_i32 v99, v99, 0, s99
	v_med3_i32 v253, v253, 0, s99
	v_med3_i32 v254, v254, 0, s99
	v_med3_i32 v255, v255, 0, s99
	v_mad_u32_u24 v80, v80, s100, v252
	v_mad_u32_u24 v83, v83, s100, v252
	v_mad_u32_u24 v99, v99, s100, v252
	v_mad_u32_u24 v253, v253, s100, v252
	v_mad_u32_u24 v254, v254, s100, v153
	v_mad_u32_u24 v255, v255, s100, v153
	global_load_dwordx4 v[156:159], v80, s[82:83]
	global_load_dwordx4 v[160:163], v83, s[82:83]
	global_load_dwordx4 v[164:167], v99, s[82:83]
	global_load_dwordx4 v[168:171], v253, s[82:83]
	global_load_dwordx4 v[172:175], v254, s[82:83] offset:768
	global_load_dwordx4 v[176:179], v255, s[82:83] offset:768
	global_load_dwordx4 v[180:183], v254, s[82:83] offset:832
	global_load_dwordx4 v[184:187], v255, s[82:83] offset:832
	s_waitcnt lgkmcnt(0)
	v_mfma_f32_32x32x16_bf16 v[32:47], v[188:191], v[48:51], v[32:47]
	ds_read_b64_tr_b16 v[72:73], v231
	ds_read_b64_tr_b16 v[74:75], v231 offset:512
	ds_read_b64_tr_b16 v[76:77], v231 offset:2048
	ds_read_b64_tr_b16 v[78:79], v231 offset:2560
	ds_read_b64_tr_b16 v[220:221], v231 offset:1024
	ds_read_b64_tr_b16 v[222:223], v231 offset:1536
	ds_read_b64_tr_b16 v[224:225], v231 offset:3072
	ds_read_b64_tr_b16 v[226:227], v231 offset:3584
	s_waitcnt vmcnt(8)
	ds_write_b128 v247, v[116:119]
	ds_write_b128 v247, v[120:123] offset:1024
	ds_write_b128 v247, v[124:127] offset:2048
	ds_write_b128 v247, v[128:131] offset:3072
	ds_read_b128 v[116:119], v248
	ds_read_b128 v[120:123], v249
	ds_read_b128 v[124:127], v250
	ds_read_b128 v[128:131], v251
	ds_write_b128 v112, v[132:135]
	ds_write_b128 v112, v[136:139] offset:1024
	ds_write_b128 v112, v[140:143] offset:2048
	ds_write_b128 v112, v[144:147] offset:3072
	v_mfma_f32_32x32x16_bf16 v[32:47], v[192:195], v[52:55], v[32:47]
	v_mfma_f32_32x32x16_bf16 v[32:47], v[196:199], v[56:59], v[32:47]
	v_mfma_f32_32x32x16_bf16 v[32:47], v[200:203], v[60:63], v[32:47]
	s_nop 11
	v_exp_f32_e32 v32, v32
	v_exp_f32_e32 v33, v33
	v_exp_f32_e32 v34, v34
	v_exp_f32_e32 v35, v35
	v_exp_f32_e32 v36, v36
	v_exp_f32_e32 v37, v37
	v_exp_f32_e32 v38, v38
	v_exp_f32_e32 v39, v39
	v_exp_f32_e32 v40, v40
	v_exp_f32_e32 v41, v41
	v_exp_f32_e32 v42, v42
	v_exp_f32_e32 v43, v43
	v_exp_f32_e32 v44, v44
	v_exp_f32_e32 v45, v45
	v_exp_f32_e32 v46, v46
	v_exp_f32_e32 v47, v47
	s_add_i32 s90, s76, 128
	v_lshlrev_b32_e32 v84, 2, v107
	v_add_u32_e32 v84, s90, v84
	v_add_u32_e32 v85, 0, v84
	v_add_u32_e32 v86, 4, v84
	v_add_u32_e32 v87, 8, v84
	v_add_u32_e32 v88, 12, v84
	v_cmp_gt_u32_e64 s[30:31], s98, v85
	v_cmp_gt_u32_e64 s[36:37], s98, v86
	v_cmp_gt_u32_e64 s[78:79], s98, v87
	v_cmp_gt_u32_e64 s[50:51], s98, v88
	v_cndmask_b32_e64 v32, 0, v32, s[30:31]
	v_add_u32_e32 v85, 32, v84
	v_cmp_gt_u32_e64 s[30:31], s98, v85
	v_cndmask_b32_e64 v33, 0, v33, s[36:37]
	v_add_u32_e32 v86, 36, v84
	v_cmp_gt_u32_e64 s[36:37], s98, v86
	v_cndmask_b32_e64 v34, 0, v34, s[78:79]
	v_add_u32_e32 v87, 40, v84
	v_cmp_gt_u32_e64 s[78:79], s98, v87
	v_cndmask_b32_e64 v35, 0, v35, s[50:51]
	v_add_u32_e32 v88, 44, v84
	v_cmp_gt_u32_e64 s[50:51], s98, v88
	v_cndmask_b32_e64 v36, 0, v36, s[30:31]
	v_add_u32_e32 v85, 64, v84
	v_cmp_gt_u32_e64 s[30:31], s98, v85
	v_cndmask_b32_e64 v37, 0, v37, s[36:37]
	v_add_u32_e32 v86, 68, v84
	v_cmp_gt_u32_e64 s[36:37], s98, v86
	v_cndmask_b32_e64 v38, 0, v38, s[78:79]
	v_add_u32_e32 v87, 72, v84
	v_cmp_gt_u32_e64 s[78:79], s98, v87
	v_cndmask_b32_e64 v39, 0, v39, s[50:51]
	v_add_u32_e32 v88, 76, v84
	v_cmp_gt_u32_e64 s[50:51], s98, v88
	v_cndmask_b32_e64 v40, 0, v40, s[30:31]
	v_add_u32_e32 v85, 96, v84
	v_cmp_gt_u32_e64 s[30:31], s98, v85
	v_cndmask_b32_e64 v41, 0, v41, s[36:37]
	v_add_u32_e32 v86, 100, v84
	v_cmp_gt_u32_e64 s[36:37], s98, v86
	v_cndmask_b32_e64 v42, 0, v42, s[78:79]
	v_add_u32_e32 v87, 104, v84
	v_cmp_gt_u32_e64 s[78:79], s98, v87
	v_cndmask_b32_e64 v43, 0, v43, s[50:51]
	v_add_u32_e32 v88, 108, v84
	v_cmp_gt_u32_e64 s[50:51], s98, v88
	v_nop
	v_cndmask_b32_e64 v44, 0, v44, s[30:31]
	v_cndmask_b32_e64 v45, 0, v45, s[36:37]
	v_cndmask_b32_e64 v46, 0, v46, s[78:79]
	v_cndmask_b32_e64 v47, 0, v47, s[50:51]
	v_cvt_pk_bf16_f32 v64, v32, v33
	v_cvt_pk_bf16_f32 v65, v34, v35
	v_cvt_pk_bf16_f32 v66, v36, v37
	v_cvt_pk_bf16_f32 v67, v38, v39
	v_cvt_pk_bf16_f32 v68, v40, v41
	v_cvt_pk_bf16_f32 v69, v42, v43
	v_cvt_pk_bf16_f32 v70, v44, v45
	v_cvt_pk_bf16_f32 v71, v46, v47
	v_pk_add_f32 v[232:233], v[232:233], v[32:33]
	v_pk_add_f32 v[232:233], v[232:233], v[34:35]
	v_pk_add_f32 v[232:233], v[232:233], v[36:37]
	v_pk_add_f32 v[232:233], v[232:233], v[38:39]
	v_pk_add_f32 v[232:233], v[232:233], v[40:41]
	v_pk_add_f32 v[232:233], v[232:233], v[42:43]
	v_pk_add_f32 v[232:233], v[232:233], v[44:45]
	v_pk_add_f32 v[232:233], v[232:233], v[46:47]
	ds_read2_b32 v[32:33], v115 offset0:128 offset1:129
	ds_read2_b32 v[34:35], v115 offset0:130 offset1:131
	ds_read2_b32 v[36:37], v115 offset0:136 offset1:137
	ds_read2_b32 v[38:39], v115 offset0:138 offset1:139
	ds_read2_b32 v[40:41], v115 offset0:144 offset1:145
	ds_read2_b32 v[42:43], v115 offset0:146 offset1:147
	ds_read2_b32 v[44:45], v115 offset0:152 offset1:153
	ds_read2_b32 v[46:47], v115 offset0:154 offset1:155
	s_waitcnt lgkmcnt(15)
	v_mfma_f32_32x32x16_bf16 v[0:15], v[64:67], v[72:75], v[0:15]
	v_mfma_f32_32x32x16_bf16 v[16:31], v[64:67], v[76:79], v[16:31]
	v_mfma_f32_32x32x16_bf16 v[0:15], v[68:71], v[220:223], v[0:15]
	v_mfma_f32_32x32x16_bf16 v[16:31], v[68:71], v[224:227], v[16:31]
	s_add_i32 s90, s76, 512
	v_add_u32_e32 v80, s90, v239
	v_add_u32_e32 v83, s90, v240
	v_add_u32_e32 v99, s90, v241
	v_add_u32_e32 v253, s90, v242
	v_add_u32_e32 v254, s90, v101
	v_add_u32_e32 v255, s90, v150
	v_med3_i32 v80, v80, 0, s99
	v_med3_i32 v83, v83, 0, s99
	v_med3_i32 v99, v99, 0, s99
	v_med3_i32 v253, v253, 0, s99
	v_med3_i32 v254, v254, 0, s99
	v_med3_i32 v255, v255, 0, s99
	v_mad_u32_u24 v80, v80, s100, v252
	v_mad_u32_u24 v83, v83, s100, v252
	v_mad_u32_u24 v99, v99, s100, v252
	v_mad_u32_u24 v253, v253, s100, v252
	v_mad_u32_u24 v254, v254, s100, v153
	v_mad_u32_u24 v255, v255, s100, v153
	global_load_dwordx4 v[188:191], v80, s[82:83]
	global_load_dwordx4 v[192:195], v83, s[82:83]
	global_load_dwordx4 v[196:199], v99, s[82:83]
	global_load_dwordx4 v[200:203], v253, s[82:83]
	global_load_dwordx4 v[204:207], v254, s[82:83] offset:768
	global_load_dwordx4 v[208:211], v255, s[82:83] offset:768
	global_load_dwordx4 v[212:215], v254, s[82:83] offset:832
	global_load_dwordx4 v[216:219], v255, s[82:83] offset:832
	s_waitcnt lgkmcnt(0)
	v_mfma_f32_32x32x16_bf16 v[32:47], v[116:119], v[48:51], v[32:47]
	ds_read_b64_tr_b16 v[72:73], v231
	ds_read_b64_tr_b16 v[74:75], v231 offset:512
	ds_read_b64_tr_b16 v[76:77], v231 offset:2048
	ds_read_b64_tr_b16 v[78:79], v231 offset:2560
	ds_read_b64_tr_b16 v[220:221], v231 offset:1024
	ds_read_b64_tr_b16 v[222:223], v231 offset:1536
	ds_read_b64_tr_b16 v[224:225], v231 offset:3072
	ds_read_b64_tr_b16 v[226:227], v231 offset:3584
	s_waitcnt vmcnt(8)
	ds_write_b128 v247, v[156:159]
	ds_write_b128 v247, v[160:163] offset:1024
	ds_write_b128 v247, v[164:167] offset:2048
	ds_write_b128 v247, v[168:171] offset:3072
	ds_read_b128 v[156:159], v248
	ds_read_b128 v[160:163], v249
	ds_read_b128 v[164:167], v250
	ds_read_b128 v[168:171], v251
	ds_write_b128 v112, v[172:175]
	ds_write_b128 v112, v[176:179] offset:1024
	ds_write_b128 v112, v[180:183] offset:2048
	ds_write_b128 v112, v[184:187] offset:3072
	v_mfma_f32_32x32x16_bf16 v[32:47], v[120:123], v[52:55], v[32:47]
	v_mfma_f32_32x32x16_bf16 v[32:47], v[124:127], v[56:59], v[32:47]
	v_mfma_f32_32x32x16_bf16 v[32:47], v[128:131], v[60:63], v[32:47]
	s_nop 11
	v_exp_f32_e32 v32, v32
	v_exp_f32_e32 v33, v33
	v_exp_f32_e32 v34, v34
	v_exp_f32_e32 v35, v35
	v_exp_f32_e32 v36, v36
	v_exp_f32_e32 v37, v37
	v_exp_f32_e32 v38, v38
	v_exp_f32_e32 v39, v39
	v_exp_f32_e32 v40, v40
	v_exp_f32_e32 v41, v41
	v_exp_f32_e32 v42, v42
	v_exp_f32_e32 v43, v43
	v_exp_f32_e32 v44, v44
	v_exp_f32_e32 v45, v45
	v_exp_f32_e32 v46, v46
	v_exp_f32_e32 v47, v47
	s_add_i32 s90, s76, 256
	v_lshlrev_b32_e32 v84, 2, v107
	v_add_u32_e32 v84, s90, v84
	v_add_u32_e32 v85, 0, v84
	v_add_u32_e32 v86, 4, v84
	v_add_u32_e32 v87, 8, v84
	v_add_u32_e32 v88, 12, v84
	v_cmp_gt_u32_e64 s[30:31], s98, v85
	v_cmp_gt_u32_e64 s[36:37], s98, v86
	v_cmp_gt_u32_e64 s[78:79], s98, v87
	v_cmp_gt_u32_e64 s[50:51], s98, v88
	v_cndmask_b32_e64 v32, 0, v32, s[30:31]
	v_add_u32_e32 v85, 32, v84
	v_cmp_gt_u32_e64 s[30:31], s98, v85
	v_cndmask_b32_e64 v33, 0, v33, s[36:37]
	v_add_u32_e32 v86, 36, v84
	v_cmp_gt_u32_e64 s[36:37], s98, v86
	v_cndmask_b32_e64 v34, 0, v34, s[78:79]
	v_add_u32_e32 v87, 40, v84
	v_cmp_gt_u32_e64 s[78:79], s98, v87
	v_cndmask_b32_e64 v35, 0, v35, s[50:51]
	v_add_u32_e32 v88, 44, v84
	v_cmp_gt_u32_e64 s[50:51], s98, v88
	v_cndmask_b32_e64 v36, 0, v36, s[30:31]
	v_add_u32_e32 v85, 64, v84
	v_cmp_gt_u32_e64 s[30:31], s98, v85
	v_cndmask_b32_e64 v37, 0, v37, s[36:37]
	v_add_u32_e32 v86, 68, v84
	v_cmp_gt_u32_e64 s[36:37], s98, v86
	v_cndmask_b32_e64 v38, 0, v38, s[78:79]
	v_add_u32_e32 v87, 72, v84
	v_cmp_gt_u32_e64 s[78:79], s98, v87
	v_cndmask_b32_e64 v39, 0, v39, s[50:51]
	v_add_u32_e32 v88, 76, v84
	v_cmp_gt_u32_e64 s[50:51], s98, v88
	v_cndmask_b32_e64 v40, 0, v40, s[30:31]
	v_add_u32_e32 v85, 96, v84
	v_cmp_gt_u32_e64 s[30:31], s98, v85
	v_cndmask_b32_e64 v41, 0, v41, s[36:37]
	v_add_u32_e32 v86, 100, v84
	v_cmp_gt_u32_e64 s[36:37], s98, v86
	v_cndmask_b32_e64 v42, 0, v42, s[78:79]
	v_add_u32_e32 v87, 104, v84
	v_cmp_gt_u32_e64 s[78:79], s98, v87
	v_cndmask_b32_e64 v43, 0, v43, s[50:51]
	v_add_u32_e32 v88, 108, v84
	v_cmp_gt_u32_e64 s[50:51], s98, v88
	v_nop
	v_cndmask_b32_e64 v44, 0, v44, s[30:31]
	v_cndmask_b32_e64 v45, 0, v45, s[36:37]
	v_cndmask_b32_e64 v46, 0, v46, s[78:79]
	v_cndmask_b32_e64 v47, 0, v47, s[50:51]
	v_cvt_pk_bf16_f32 v64, v32, v33
	v_cvt_pk_bf16_f32 v65, v34, v35
	v_cvt_pk_bf16_f32 v66, v36, v37
	v_cvt_pk_bf16_f32 v67, v38, v39
	v_cvt_pk_bf16_f32 v68, v40, v41
	v_cvt_pk_bf16_f32 v69, v42, v43
	v_cvt_pk_bf16_f32 v70, v44, v45
	v_cvt_pk_bf16_f32 v71, v46, v47
	v_pk_add_f32 v[232:233], v[232:233], v[32:33]
	v_pk_add_f32 v[232:233], v[232:233], v[34:35]
	v_pk_add_f32 v[232:233], v[232:233], v[36:37]
	v_pk_add_f32 v[232:233], v[232:233], v[38:39]
	v_pk_add_f32 v[232:233], v[232:233], v[40:41]
	v_pk_add_f32 v[232:233], v[232:233], v[42:43]
	v_pk_add_f32 v[232:233], v[232:233], v[44:45]
	v_pk_add_f32 v[232:233], v[232:233], v[46:47]
	ds_read2_b32 v[32:33], v115 offset0:160 offset1:161
	ds_read2_b32 v[34:35], v115 offset0:162 offset1:163
	ds_read2_b32 v[36:37], v115 offset0:168 offset1:169
	ds_read2_b32 v[38:39], v115 offset0:170 offset1:171
	ds_read2_b32 v[40:41], v115 offset0:176 offset1:177
	ds_read2_b32 v[42:43], v115 offset0:178 offset1:179
	ds_read2_b32 v[44:45], v115 offset0:184 offset1:185
	ds_read2_b32 v[46:47], v115 offset0:186 offset1:187
	s_waitcnt lgkmcnt(15)
	v_mfma_f32_32x32x16_bf16 v[0:15], v[64:67], v[72:75], v[0:15]
	v_mfma_f32_32x32x16_bf16 v[16:31], v[64:67], v[76:79], v[16:31]
	v_mfma_f32_32x32x16_bf16 v[0:15], v[68:71], v[220:223], v[0:15]
	v_mfma_f32_32x32x16_bf16 v[16:31], v[68:71], v[224:227], v[16:31]
	s_add_i32 s90, s76, 640
	v_add_u32_e32 v80, s90, v239
	v_add_u32_e32 v83, s90, v240
	v_add_u32_e32 v99, s90, v241
	v_add_u32_e32 v253, s90, v242
	v_add_u32_e32 v254, s90, v101
	v_add_u32_e32 v255, s90, v150
	v_med3_i32 v80, v80, 0, s99
	v_med3_i32 v83, v83, 0, s99
	v_med3_i32 v99, v99, 0, s99
	v_med3_i32 v253, v253, 0, s99
	v_med3_i32 v254, v254, 0, s99
	v_med3_i32 v255, v255, 0, s99
	v_mad_u32_u24 v80, v80, s100, v252
	v_mad_u32_u24 v83, v83, s100, v252
	v_mad_u32_u24 v99, v99, s100, v252
	v_mad_u32_u24 v253, v253, s100, v252
	v_mad_u32_u24 v254, v254, s100, v153
	v_mad_u32_u24 v255, v255, s100, v153
	global_load_dwordx4 v[116:119], v80, s[82:83]
	global_load_dwordx4 v[120:123], v83, s[82:83]
	global_load_dwordx4 v[124:127], v99, s[82:83]
	global_load_dwordx4 v[128:131], v253, s[82:83]
	global_load_dwordx4 v[132:135], v254, s[82:83] offset:768
	global_load_dwordx4 v[136:139], v255, s[82:83] offset:768
	global_load_dwordx4 v[140:143], v254, s[82:83] offset:832
	global_load_dwordx4 v[144:147], v255, s[82:83] offset:832
	s_waitcnt lgkmcnt(0)
	v_mfma_f32_32x32x16_bf16 v[32:47], v[156:159], v[48:51], v[32:47]
	ds_read_b64_tr_b16 v[72:73], v231
	ds_read_b64_tr_b16 v[74:75], v231 offset:512
	ds_read_b64_tr_b16 v[76:77], v231 offset:2048
	ds_read_b64_tr_b16 v[78:79], v231 offset:2560
	ds_read_b64_tr_b16 v[220:221], v231 offset:1024
	ds_read_b64_tr_b16 v[222:223], v231 offset:1536
	ds_read_b64_tr_b16 v[224:225], v231 offset:3072
	ds_read_b64_tr_b16 v[226:227], v231 offset:3584
	s_waitcnt vmcnt(8)
	ds_write_b128 v247, v[188:191]
	ds_write_b128 v247, v[192:195] offset:1024
	ds_write_b128 v247, v[196:199] offset:2048
	ds_write_b128 v247, v[200:203] offset:3072
	ds_read_b128 v[188:191], v248
	ds_read_b128 v[192:195], v249
	ds_read_b128 v[196:199], v250
	ds_read_b128 v[200:203], v251
	ds_write_b128 v112, v[204:207]
	ds_write_b128 v112, v[208:211] offset:1024
	ds_write_b128 v112, v[212:215] offset:2048
	ds_write_b128 v112, v[216:219] offset:3072
	v_mfma_f32_32x32x16_bf16 v[32:47], v[160:163], v[52:55], v[32:47]
	v_mfma_f32_32x32x16_bf16 v[32:47], v[164:167], v[56:59], v[32:47]
	v_mfma_f32_32x32x16_bf16 v[32:47], v[168:171], v[60:63], v[32:47]
	s_nop 11
	v_exp_f32_e32 v32, v32
	v_exp_f32_e32 v33, v33
	v_exp_f32_e32 v34, v34
	v_exp_f32_e32 v35, v35
	v_exp_f32_e32 v36, v36
	v_exp_f32_e32 v37, v37
	v_exp_f32_e32 v38, v38
	v_exp_f32_e32 v39, v39
	v_exp_f32_e32 v40, v40
	v_exp_f32_e32 v41, v41
	v_exp_f32_e32 v42, v42
	v_exp_f32_e32 v43, v43
	v_exp_f32_e32 v44, v44
	v_exp_f32_e32 v45, v45
	v_exp_f32_e32 v46, v46
	v_exp_f32_e32 v47, v47
	s_add_i32 s90, s76, 384
	v_lshlrev_b32_e32 v84, 2, v107
	v_add_u32_e32 v84, s90, v84
	v_add_u32_e32 v85, 0, v84
	v_add_u32_e32 v86, 4, v84
	v_add_u32_e32 v87, 8, v84
	v_add_u32_e32 v88, 12, v84
	v_cmp_gt_u32_e64 s[30:31], s98, v85
	v_cmp_gt_u32_e64 s[36:37], s98, v86
	v_cmp_gt_u32_e64 s[78:79], s98, v87
	v_cmp_gt_u32_e64 s[50:51], s98, v88
	v_cndmask_b32_e64 v32, 0, v32, s[30:31]
	v_add_u32_e32 v85, 32, v84
	v_cmp_gt_u32_e64 s[30:31], s98, v85
	v_cndmask_b32_e64 v33, 0, v33, s[36:37]
	v_add_u32_e32 v86, 36, v84
	v_cmp_gt_u32_e64 s[36:37], s98, v86
	v_cndmask_b32_e64 v34, 0, v34, s[78:79]
	v_add_u32_e32 v87, 40, v84
	v_cmp_gt_u32_e64 s[78:79], s98, v87
	v_cndmask_b32_e64 v35, 0, v35, s[50:51]
	v_add_u32_e32 v88, 44, v84
	v_cmp_gt_u32_e64 s[50:51], s98, v88
	v_cndmask_b32_e64 v36, 0, v36, s[30:31]
	v_add_u32_e32 v85, 64, v84
	v_cmp_gt_u32_e64 s[30:31], s98, v85
	v_cndmask_b32_e64 v37, 0, v37, s[36:37]
	v_add_u32_e32 v86, 68, v84
	v_cmp_gt_u32_e64 s[36:37], s98, v86
	v_cndmask_b32_e64 v38, 0, v38, s[78:79]
	v_add_u32_e32 v87, 72, v84
	v_cmp_gt_u32_e64 s[78:79], s98, v87
	v_cndmask_b32_e64 v39, 0, v39, s[50:51]
	v_add_u32_e32 v88, 76, v84
	v_cmp_gt_u32_e64 s[50:51], s98, v88
	v_cndmask_b32_e64 v40, 0, v40, s[30:31]
	v_add_u32_e32 v85, 96, v84
	v_cmp_gt_u32_e64 s[30:31], s98, v85
	v_cndmask_b32_e64 v41, 0, v41, s[36:37]
	v_add_u32_e32 v86, 100, v84
	v_cmp_gt_u32_e64 s[36:37], s98, v86
	v_cndmask_b32_e64 v42, 0, v42, s[78:79]
	v_add_u32_e32 v87, 104, v84
	v_cmp_gt_u32_e64 s[78:79], s98, v87
	v_cndmask_b32_e64 v43, 0, v43, s[50:51]
	v_add_u32_e32 v88, 108, v84
	v_cmp_gt_u32_e64 s[50:51], s98, v88
	v_nop
	v_cndmask_b32_e64 v44, 0, v44, s[30:31]
	v_cndmask_b32_e64 v45, 0, v45, s[36:37]
	v_cndmask_b32_e64 v46, 0, v46, s[78:79]
	v_cndmask_b32_e64 v47, 0, v47, s[50:51]
	v_cvt_pk_bf16_f32 v64, v32, v33
	v_cvt_pk_bf16_f32 v65, v34, v35
	v_cvt_pk_bf16_f32 v66, v36, v37
	v_cvt_pk_bf16_f32 v67, v38, v39
	v_cvt_pk_bf16_f32 v68, v40, v41
	v_cvt_pk_bf16_f32 v69, v42, v43
	v_cvt_pk_bf16_f32 v70, v44, v45
	v_cvt_pk_bf16_f32 v71, v46, v47
	v_pk_add_f32 v[232:233], v[232:233], v[32:33]
	v_pk_add_f32 v[232:233], v[232:233], v[34:35]
	v_pk_add_f32 v[232:233], v[232:233], v[36:37]
	v_pk_add_f32 v[232:233], v[232:233], v[38:39]
	v_pk_add_f32 v[232:233], v[232:233], v[40:41]
	v_pk_add_f32 v[232:233], v[232:233], v[42:43]
	v_pk_add_f32 v[232:233], v[232:233], v[44:45]
	v_pk_add_f32 v[232:233], v[232:233], v[46:47]
	ds_read2_b32 v[32:33], v115 offset0:192 offset1:193
	ds_read2_b32 v[34:35], v115 offset0:194 offset1:195
	ds_read2_b32 v[36:37], v115 offset0:200 offset1:201
	ds_read2_b32 v[38:39], v115 offset0:202 offset1:203
	ds_read2_b32 v[40:41], v115 offset0:208 offset1:209
	ds_read2_b32 v[42:43], v115 offset0:210 offset1:211
	ds_read2_b32 v[44:45], v115 offset0:216 offset1:217
	ds_read2_b32 v[46:47], v115 offset0:218 offset1:219
	s_waitcnt lgkmcnt(15)
	v_mfma_f32_32x32x16_bf16 v[0:15], v[64:67], v[72:75], v[0:15]
	v_mfma_f32_32x32x16_bf16 v[16:31], v[64:67], v[76:79], v[16:31]
	v_mfma_f32_32x32x16_bf16 v[0:15], v[68:71], v[220:223], v[0:15]
	v_mfma_f32_32x32x16_bf16 v[16:31], v[68:71], v[224:227], v[16:31]
	s_add_i32 s90, s76, -1024
	v_add_u32_e32 v80, s90, v243
	v_add_u32_e32 v83, s90, v244
	v_add_u32_e32 v99, s90, v245
	v_add_u32_e32 v253, s90, v246
	v_add_u32_e32 v254, s90, v148
	v_add_u32_e32 v255, s90, v151
	v_med3_i32 v80, v80, 0, s99
	v_med3_i32 v83, v83, 0, s99
	v_med3_i32 v99, v99, 0, s99
	v_med3_i32 v253, v253, 0, s99
	v_med3_i32 v254, v254, 0, s99
	v_med3_i32 v255, v255, 0, s99
	v_mad_u32_u24 v80, v80, s100, v252
	v_mad_u32_u24 v83, v83, s100, v252
	v_mad_u32_u24 v99, v99, s100, v252
	v_mad_u32_u24 v253, v253, s100, v252
	v_mad_u32_u24 v254, v254, s100, v153
	v_mad_u32_u24 v255, v255, s100, v153
	global_load_dwordx4 v[156:159], v80, s[82:83]
	global_load_dwordx4 v[160:163], v83, s[82:83]
	global_load_dwordx4 v[164:167], v99, s[82:83]
	global_load_dwordx4 v[168:171], v253, s[82:83]
	global_load_dwordx4 v[172:175], v254, s[82:83] offset:768
	global_load_dwordx4 v[176:179], v255, s[82:83] offset:768
	global_load_dwordx4 v[180:183], v254, s[82:83] offset:832
	global_load_dwordx4 v[184:187], v255, s[82:83] offset:832
	s_waitcnt lgkmcnt(0)
	v_mfma_f32_32x32x16_bf16 v[32:47], v[188:191], v[48:51], v[32:47]
	ds_read_b64_tr_b16 v[72:73], v231
	ds_read_b64_tr_b16 v[74:75], v231 offset:512
	ds_read_b64_tr_b16 v[76:77], v231 offset:2048
	ds_read_b64_tr_b16 v[78:79], v231 offset:2560
	ds_read_b64_tr_b16 v[220:221], v231 offset:1024
	ds_read_b64_tr_b16 v[222:223], v231 offset:1536
	ds_read_b64_tr_b16 v[224:225], v231 offset:3072
	ds_read_b64_tr_b16 v[226:227], v231 offset:3584
	s_waitcnt vmcnt(8)
	ds_write_b128 v247, v[116:119]
	ds_write_b128 v247, v[120:123] offset:1024
	ds_write_b128 v247, v[124:127] offset:2048
	ds_write_b128 v247, v[128:131] offset:3072
	ds_read_b128 v[116:119], v248
	ds_read_b128 v[120:123], v249
	ds_read_b128 v[124:127], v250
	ds_read_b128 v[128:131], v251
	ds_write_b128 v112, v[132:135]
	ds_write_b128 v112, v[136:139] offset:1024
	ds_write_b128 v112, v[140:143] offset:2048
	ds_write_b128 v112, v[144:147] offset:3072
	v_mfma_f32_32x32x16_bf16 v[32:47], v[192:195], v[52:55], v[32:47]
	v_mfma_f32_32x32x16_bf16 v[32:47], v[196:199], v[56:59], v[32:47]
	v_mfma_f32_32x32x16_bf16 v[32:47], v[200:203], v[60:63], v[32:47]
	s_nop 11
	v_exp_f32_e32 v32, v32
	v_exp_f32_e32 v33, v33
	v_exp_f32_e32 v34, v34
	v_exp_f32_e32 v35, v35
	v_exp_f32_e32 v36, v36
	v_exp_f32_e32 v37, v37
	v_exp_f32_e32 v38, v38
	v_exp_f32_e32 v39, v39
	v_exp_f32_e32 v40, v40
	v_exp_f32_e32 v41, v41
	v_exp_f32_e32 v42, v42
	v_exp_f32_e32 v43, v43
	v_exp_f32_e32 v44, v44
	v_exp_f32_e32 v45, v45
	v_exp_f32_e32 v46, v46
	v_exp_f32_e32 v47, v47
	s_add_i32 s90, s76, 512
	v_lshlrev_b32_e32 v84, 2, v107
	v_add_u32_e32 v84, s90, v84
	v_add_u32_e32 v85, 0, v84
	v_add_u32_e32 v86, 4, v84
	v_add_u32_e32 v87, 8, v84
	v_add_u32_e32 v88, 12, v84
	v_cmp_gt_u32_e64 s[30:31], s98, v85
	v_cmp_gt_u32_e64 s[36:37], s98, v86
	v_cmp_gt_u32_e64 s[78:79], s98, v87
	v_cmp_gt_u32_e64 s[50:51], s98, v88
	v_cndmask_b32_e64 v32, 0, v32, s[30:31]
	v_add_u32_e32 v85, 32, v84
	v_cmp_gt_u32_e64 s[30:31], s98, v85
	v_cndmask_b32_e64 v33, 0, v33, s[36:37]
	v_add_u32_e32 v86, 36, v84
	v_cmp_gt_u32_e64 s[36:37], s98, v86
	v_cndmask_b32_e64 v34, 0, v34, s[78:79]
	v_add_u32_e32 v87, 40, v84
	v_cmp_gt_u32_e64 s[78:79], s98, v87
	v_cndmask_b32_e64 v35, 0, v35, s[50:51]
	v_add_u32_e32 v88, 44, v84
	v_cmp_gt_u32_e64 s[50:51], s98, v88
	v_cndmask_b32_e64 v36, 0, v36, s[30:31]
	v_add_u32_e32 v85, 64, v84
	v_cmp_gt_u32_e64 s[30:31], s98, v85
	v_cndmask_b32_e64 v37, 0, v37, s[36:37]
	v_add_u32_e32 v86, 68, v84
	v_cmp_gt_u32_e64 s[36:37], s98, v86
	v_cndmask_b32_e64 v38, 0, v38, s[78:79]
	v_add_u32_e32 v87, 72, v84
	v_cmp_gt_u32_e64 s[78:79], s98, v87
	v_cndmask_b32_e64 v39, 0, v39, s[50:51]
	v_add_u32_e32 v88, 76, v84
	v_cmp_gt_u32_e64 s[50:51], s98, v88
	v_cndmask_b32_e64 v40, 0, v40, s[30:31]
	v_add_u32_e32 v85, 96, v84
	v_cmp_gt_u32_e64 s[30:31], s98, v85
	v_cndmask_b32_e64 v41, 0, v41, s[36:37]
	v_add_u32_e32 v86, 100, v84
	v_cmp_gt_u32_e64 s[36:37], s98, v86
	v_cndmask_b32_e64 v42, 0, v42, s[78:79]
	v_add_u32_e32 v87, 104, v84
	v_cmp_gt_u32_e64 s[78:79], s98, v87
	v_cndmask_b32_e64 v43, 0, v43, s[50:51]
	v_add_u32_e32 v88, 108, v84
	v_cmp_gt_u32_e64 s[50:51], s98, v88
	v_nop
	v_cndmask_b32_e64 v44, 0, v44, s[30:31]
	v_cndmask_b32_e64 v45, 0, v45, s[36:37]
	v_cndmask_b32_e64 v46, 0, v46, s[78:79]
	v_cndmask_b32_e64 v47, 0, v47, s[50:51]
	v_cvt_pk_bf16_f32 v64, v32, v33
	v_cvt_pk_bf16_f32 v65, v34, v35
	v_cvt_pk_bf16_f32 v66, v36, v37
	v_cvt_pk_bf16_f32 v67, v38, v39
	v_cvt_pk_bf16_f32 v68, v40, v41
	v_cvt_pk_bf16_f32 v69, v42, v43
	v_cvt_pk_bf16_f32 v70, v44, v45
	v_cvt_pk_bf16_f32 v71, v46, v47
	v_pk_add_f32 v[232:233], v[232:233], v[32:33]
	v_pk_add_f32 v[232:233], v[232:233], v[34:35]
	v_pk_add_f32 v[232:233], v[232:233], v[36:37]
	v_pk_add_f32 v[232:233], v[232:233], v[38:39]
	v_pk_add_f32 v[232:233], v[232:233], v[40:41]
	v_pk_add_f32 v[232:233], v[232:233], v[42:43]
	v_pk_add_f32 v[232:233], v[232:233], v[44:45]
	v_pk_add_f32 v[232:233], v[232:233], v[46:47]
	ds_read2_b32 v[32:33], v115 offset0:224 offset1:225
	ds_read2_b32 v[34:35], v115 offset0:226 offset1:227
	ds_read2_b32 v[36:37], v115 offset0:232 offset1:233
	ds_read2_b32 v[38:39], v115 offset0:234 offset1:235
	ds_read2_b32 v[40:41], v115 offset0:240 offset1:241
	ds_read2_b32 v[42:43], v115 offset0:242 offset1:243
	ds_read2_b32 v[44:45], v115 offset0:248 offset1:249
	ds_read2_b32 v[46:47], v115 offset0:250 offset1:251
	s_waitcnt lgkmcnt(15)
	v_mfma_f32_32x32x16_bf16 v[0:15], v[64:67], v[72:75], v[0:15]
	v_mfma_f32_32x32x16_bf16 v[16:31], v[64:67], v[76:79], v[16:31]
	v_mfma_f32_32x32x16_bf16 v[0:15], v[68:71], v[220:223], v[0:15]
	v_mfma_f32_32x32x16_bf16 v[16:31], v[68:71], v[224:227], v[16:31]
	s_add_i32 s90, s76, -512
	v_add_u32_e32 v80, s90, v243
	v_add_u32_e32 v83, s90, v244
	v_add_u32_e32 v99, s90, v245
	v_add_u32_e32 v253, s90, v246
	v_add_u32_e32 v254, s90, v148
	v_add_u32_e32 v255, s90, v151
	v_med3_i32 v80, v80, 0, s99
	v_med3_i32 v83, v83, 0, s99
	v_med3_i32 v99, v99, 0, s99
	v_med3_i32 v253, v253, 0, s99
	v_med3_i32 v254, v254, 0, s99
	v_med3_i32 v255, v255, 0, s99
	v_mad_u32_u24 v80, v80, s100, v252
	v_mad_u32_u24 v83, v83, s100, v252
	v_mad_u32_u24 v99, v99, s100, v252
	v_mad_u32_u24 v253, v253, s100, v252
	v_mad_u32_u24 v254, v254, s100, v153
	v_mad_u32_u24 v255, v255, s100, v153
	global_load_dwordx4 v[188:191], v80, s[82:83]
	global_load_dwordx4 v[192:195], v83, s[82:83]
	global_load_dwordx4 v[196:199], v99, s[82:83]
	global_load_dwordx4 v[200:203], v253, s[82:83]
	global_load_dwordx4 v[204:207], v254, s[82:83] offset:768
	global_load_dwordx4 v[208:211], v255, s[82:83] offset:768
	global_load_dwordx4 v[212:215], v254, s[82:83] offset:832
	global_load_dwordx4 v[216:219], v255, s[82:83] offset:832
	s_waitcnt lgkmcnt(0)
	v_mfma_f32_32x32x16_bf16 v[32:47], v[116:119], v[48:51], v[32:47]
	ds_read_b64_tr_b16 v[72:73], v231
	ds_read_b64_tr_b16 v[74:75], v231 offset:512
	ds_read_b64_tr_b16 v[76:77], v231 offset:2048
	ds_read_b64_tr_b16 v[78:79], v231 offset:2560
	ds_read_b64_tr_b16 v[220:221], v231 offset:1024
	ds_read_b64_tr_b16 v[222:223], v231 offset:1536
	ds_read_b64_tr_b16 v[224:225], v231 offset:3072
	ds_read_b64_tr_b16 v[226:227], v231 offset:3584
	s_waitcnt vmcnt(8)
	ds_write_b128 v247, v[156:159]
	ds_write_b128 v247, v[160:163] offset:1024
	ds_write_b128 v247, v[164:167] offset:2048
	ds_write_b128 v247, v[168:171] offset:3072
	ds_read_b128 v[156:159], v248
	ds_read_b128 v[160:163], v249
	ds_read_b128 v[164:167], v250
	ds_read_b128 v[168:171], v251
	ds_write_b128 v112, v[172:175]
	ds_write_b128 v112, v[176:179] offset:1024
	ds_write_b128 v112, v[180:183] offset:2048
	ds_write_b128 v112, v[184:187] offset:3072
	v_mfma_f32_32x32x16_bf16 v[32:47], v[120:123], v[52:55], v[32:47]
	v_mfma_f32_32x32x16_bf16 v[32:47], v[124:127], v[56:59], v[32:47]
	v_mfma_f32_32x32x16_bf16 v[32:47], v[128:131], v[60:63], v[32:47]
	s_nop 11
	v_exp_f32_e32 v32, v32
	v_exp_f32_e32 v33, v33
	v_exp_f32_e32 v34, v34
	v_exp_f32_e32 v35, v35
	v_exp_f32_e32 v36, v36
	v_exp_f32_e32 v37, v37
	v_exp_f32_e32 v38, v38
	v_exp_f32_e32 v39, v39
	v_exp_f32_e32 v40, v40
	v_exp_f32_e32 v41, v41
	v_exp_f32_e32 v42, v42
	v_exp_f32_e32 v43, v43
	v_exp_f32_e32 v44, v44
	v_exp_f32_e32 v45, v45
	v_exp_f32_e32 v46, v46
	v_exp_f32_e32 v47, v47
	s_add_i32 s90, s76, 640
	v_lshlrev_b32_e32 v84, 2, v107
	v_add_u32_e32 v84, s90, v84
	v_add_u32_e32 v85, 0, v84
	v_add_u32_e32 v86, 4, v84
	v_add_u32_e32 v87, 8, v84
	v_add_u32_e32 v88, 12, v84
	v_cmp_gt_u32_e64 s[30:31], s98, v85
	v_cmp_gt_u32_e64 s[36:37], s98, v86
	v_cmp_gt_u32_e64 s[78:79], s98, v87
	v_cmp_gt_u32_e64 s[50:51], s98, v88
	v_cndmask_b32_e64 v32, 0, v32, s[30:31]
	v_add_u32_e32 v85, 32, v84
	v_cmp_gt_u32_e64 s[30:31], s98, v85
	v_cndmask_b32_e64 v33, 0, v33, s[36:37]
	v_add_u32_e32 v86, 36, v84
	v_cmp_gt_u32_e64 s[36:37], s98, v86
	v_cndmask_b32_e64 v34, 0, v34, s[78:79]
	v_add_u32_e32 v87, 40, v84
	v_cmp_gt_u32_e64 s[78:79], s98, v87
	v_cndmask_b32_e64 v35, 0, v35, s[50:51]
	v_add_u32_e32 v88, 44, v84
	v_cmp_gt_u32_e64 s[50:51], s98, v88
	v_cndmask_b32_e64 v36, 0, v36, s[30:31]
	v_add_u32_e32 v85, 64, v84
	v_cmp_gt_u32_e64 s[30:31], s98, v85
	v_cndmask_b32_e64 v37, 0, v37, s[36:37]
	v_add_u32_e32 v86, 68, v84
	v_cmp_gt_u32_e64 s[36:37], s98, v86
	v_cndmask_b32_e64 v38, 0, v38, s[78:79]
	v_add_u32_e32 v87, 72, v84
	v_cmp_gt_u32_e64 s[78:79], s98, v87
	v_cndmask_b32_e64 v39, 0, v39, s[50:51]
	v_add_u32_e32 v88, 76, v84
	v_cmp_gt_u32_e64 s[50:51], s98, v88
	v_cndmask_b32_e64 v40, 0, v40, s[30:31]
	v_add_u32_e32 v85, 96, v84
	v_cmp_gt_u32_e64 s[30:31], s98, v85
	v_cndmask_b32_e64 v41, 0, v41, s[36:37]
	v_add_u32_e32 v86, 100, v84
	v_cmp_gt_u32_e64 s[36:37], s98, v86
	v_cndmask_b32_e64 v42, 0, v42, s[78:79]
	v_add_u32_e32 v87, 104, v84
	v_cmp_gt_u32_e64 s[78:79], s98, v87
	v_cndmask_b32_e64 v43, 0, v43, s[50:51]
	v_add_u32_e32 v88, 108, v84
	v_cmp_gt_u32_e64 s[50:51], s98, v88
	v_nop
	v_cndmask_b32_e64 v44, 0, v44, s[30:31]
	v_cndmask_b32_e64 v45, 0, v45, s[36:37]
	v_cndmask_b32_e64 v46, 0, v46, s[78:79]
	v_cndmask_b32_e64 v47, 0, v47, s[50:51]
	v_cvt_pk_bf16_f32 v64, v32, v33
	v_cvt_pk_bf16_f32 v65, v34, v35
	v_cvt_pk_bf16_f32 v66, v36, v37
	v_cvt_pk_bf16_f32 v67, v38, v39
	v_cvt_pk_bf16_f32 v68, v40, v41
	v_cvt_pk_bf16_f32 v69, v42, v43
	v_cvt_pk_bf16_f32 v70, v44, v45
	v_cvt_pk_bf16_f32 v71, v46, v47
	v_pk_add_f32 v[232:233], v[232:233], v[32:33]
	v_pk_add_f32 v[232:233], v[232:233], v[34:35]
	v_pk_add_f32 v[232:233], v[232:233], v[36:37]
	v_pk_add_f32 v[232:233], v[232:233], v[38:39]
	v_pk_add_f32 v[232:233], v[232:233], v[40:41]
	v_pk_add_f32 v[232:233], v[232:233], v[42:43]
	v_pk_add_f32 v[232:233], v[232:233], v[44:45]
	v_pk_add_f32 v[232:233], v[232:233], v[46:47]
	v_mov_b32_e32 v115, v230
	ds_read2_b32 v[32:33], v115 offset0:0 offset1:1
	ds_read2_b32 v[34:35], v115 offset0:2 offset1:3
	ds_read2_b32 v[36:37], v115 offset0:8 offset1:9
	ds_read2_b32 v[38:39], v115 offset0:10 offset1:11
	ds_read2_b32 v[40:41], v115 offset0:16 offset1:17
	ds_read2_b32 v[42:43], v115 offset0:18 offset1:19
	ds_read2_b32 v[44:45], v115 offset0:24 offset1:25
	ds_read2_b32 v[46:47], v115 offset0:26 offset1:27
	s_waitcnt lgkmcnt(15)
	v_mfma_f32_32x32x16_bf16 v[0:15], v[64:67], v[72:75], v[0:15]
	v_mfma_f32_32x32x16_bf16 v[16:31], v[64:67], v[76:79], v[16:31]
	v_mfma_f32_32x32x16_bf16 v[0:15], v[68:71], v[220:223], v[0:15]
	v_mfma_f32_32x32x16_bf16 v[16:31], v[68:71], v[224:227], v[16:31]
	s_add_i32 s90, s76, 0
	v_add_u32_e32 v80, s90, v243
	v_add_u32_e32 v83, s90, v244
	v_add_u32_e32 v99, s90, v245
	v_add_u32_e32 v253, s90, v246
	v_add_u32_e32 v254, s90, v148
	v_add_u32_e32 v255, s90, v151
	v_med3_i32 v80, v80, 0, s99
	v_med3_i32 v83, v83, 0, s99
	v_med3_i32 v99, v99, 0, s99
	v_med3_i32 v253, v253, 0, s99
	v_med3_i32 v254, v254, 0, s99
	v_med3_i32 v255, v255, 0, s99
	v_mad_u32_u24 v80, v80, s100, v252
	v_mad_u32_u24 v83, v83, s100, v252
	v_mad_u32_u24 v99, v99, s100, v252
	v_mad_u32_u24 v253, v253, s100, v252
	v_mad_u32_u24 v254, v254, s100, v153
	v_mad_u32_u24 v255, v255, s100, v153
	global_load_dwordx4 v[116:119], v80, s[82:83]
	global_load_dwordx4 v[120:123], v83, s[82:83]
	global_load_dwordx4 v[124:127], v99, s[82:83]
	global_load_dwordx4 v[128:131], v253, s[82:83]
	global_load_dwordx4 v[132:135], v254, s[82:83] offset:768
	global_load_dwordx4 v[136:139], v255, s[82:83] offset:768
	global_load_dwordx4 v[140:143], v254, s[82:83] offset:832
	global_load_dwordx4 v[144:147], v255, s[82:83] offset:832
	s_waitcnt lgkmcnt(0)
	v_mfma_f32_32x32x16_bf16 v[32:47], v[156:159], v[48:51], v[32:47]
	ds_read_b64_tr_b16 v[72:73], v231
	ds_read_b64_tr_b16 v[74:75], v231 offset:512
	ds_read_b64_tr_b16 v[76:77], v231 offset:2048
	ds_read_b64_tr_b16 v[78:79], v231 offset:2560
	ds_read_b64_tr_b16 v[220:221], v231 offset:1024
	ds_read_b64_tr_b16 v[222:223], v231 offset:1536
	ds_read_b64_tr_b16 v[224:225], v231 offset:3072
	ds_read_b64_tr_b16 v[226:227], v231 offset:3584
	s_waitcnt vmcnt(8)
	ds_write_b128 v247, v[188:191]
	ds_write_b128 v247, v[192:195] offset:1024
	ds_write_b128 v247, v[196:199] offset:2048
	ds_write_b128 v247, v[200:203] offset:3072
	ds_read_b128 v[188:191], v248
	ds_read_b128 v[192:195], v249
	ds_read_b128 v[196:199], v250
	ds_read_b128 v[200:203], v251
	ds_write_b128 v112, v[204:207]
	ds_write_b128 v112, v[208:211] offset:1024
	ds_write_b128 v112, v[212:215] offset:2048
	ds_write_b128 v112, v[216:219] offset:3072
	v_mfma_f32_32x32x16_bf16 v[32:47], v[160:163], v[52:55], v[32:47]
	v_mfma_f32_32x32x16_bf16 v[32:47], v[164:167], v[56:59], v[32:47]
	v_mfma_f32_32x32x16_bf16 v[32:47], v[168:171], v[60:63], v[32:47]
	s_nop 11
	v_exp_f32_e32 v32, v32
	v_exp_f32_e32 v33, v33
	v_exp_f32_e32 v34, v34
	v_exp_f32_e32 v35, v35
	v_exp_f32_e32 v36, v36
	v_exp_f32_e32 v37, v37
	v_exp_f32_e32 v38, v38
	v_exp_f32_e32 v39, v39
	v_exp_f32_e32 v40, v40
	v_exp_f32_e32 v41, v41
	v_exp_f32_e32 v42, v42
	v_exp_f32_e32 v43, v43
	v_exp_f32_e32 v44, v44
	v_exp_f32_e32 v45, v45
	v_exp_f32_e32 v46, v46
	v_exp_f32_e32 v47, v47
	s_add_i32 s90, s76, -1024
	v_lshlrev_b32_e32 v84, 4, v107
	v_add_u32_e32 v84, s90, v84
	v_add_u32_e32 v85, 0, v84
	v_add_u32_e32 v86, 16, v84
	v_add_u32_e32 v87, 32, v84
	v_add_u32_e32 v88, 48, v84
	v_cmp_gt_u32_e64 s[30:31], s98, v85
	v_cmp_gt_u32_e64 s[36:37], s98, v86
	v_cmp_gt_u32_e64 s[78:79], s98, v87
	v_cmp_gt_u32_e64 s[50:51], s98, v88
	v_cndmask_b32_e64 v32, 0, v32, s[30:31]
	v_add_u32_e32 v85, 128, v84
	v_cmp_gt_u32_e64 s[30:31], s98, v85
	v_cndmask_b32_e64 v33, 0, v33, s[36:37]
	v_add_u32_e32 v86, 144, v84
	v_cmp_gt_u32_e64 s[36:37], s98, v86
	v_cndmask_b32_e64 v34, 0, v34, s[78:79]
	v_add_u32_e32 v87, 160, v84
	v_cmp_gt_u32_e64 s[78:79], s98, v87
	v_cndmask_b32_e64 v35, 0, v35, s[50:51]
	v_add_u32_e32 v88, 176, v84
	v_cmp_gt_u32_e64 s[50:51], s98, v88
	v_cndmask_b32_e64 v36, 0, v36, s[30:31]
	v_add_u32_e32 v85, 256, v84
	v_cmp_gt_u32_e64 s[30:31], s98, v85
	v_cndmask_b32_e64 v37, 0, v37, s[36:37]
	v_add_u32_e32 v86, 272, v84
	v_cmp_gt_u32_e64 s[36:37], s98, v86
	v_cndmask_b32_e64 v38, 0, v38, s[78:79]
	v_add_u32_e32 v87, 288, v84
	v_cmp_gt_u32_e64 s[78:79], s98, v87
	v_cndmask_b32_e64 v39, 0, v39, s[50:51]
	v_add_u32_e32 v88, 304, v84
	v_cmp_gt_u32_e64 s[50:51], s98, v88
	v_cndmask_b32_e64 v40, 0, v40, s[30:31]
	v_add_u32_e32 v85, 384, v84
	v_cmp_gt_u32_e64 s[30:31], s98, v85
	v_cndmask_b32_e64 v41, 0, v41, s[36:37]
	v_add_u32_e32 v86, 400, v84
	v_cmp_gt_u32_e64 s[36:37], s98, v86
	v_cndmask_b32_e64 v42, 0, v42, s[78:79]
	v_add_u32_e32 v87, 416, v84
	v_cmp_gt_u32_e64 s[78:79], s98, v87
	v_cndmask_b32_e64 v43, 0, v43, s[50:51]
	v_add_u32_e32 v88, 432, v84
	v_cmp_gt_u32_e64 s[50:51], s98, v88
	v_nop
	v_cndmask_b32_e64 v44, 0, v44, s[30:31]
	v_cndmask_b32_e64 v45, 0, v45, s[36:37]
	v_cndmask_b32_e64 v46, 0, v46, s[78:79]
	v_cndmask_b32_e64 v47, 0, v47, s[50:51]
	v_cvt_pk_bf16_f32 v64, v32, v33
	v_cvt_pk_bf16_f32 v65, v34, v35
	v_cvt_pk_bf16_f32 v66, v36, v37
	v_cvt_pk_bf16_f32 v67, v38, v39
	v_cvt_pk_bf16_f32 v68, v40, v41
	v_cvt_pk_bf16_f32 v69, v42, v43
	v_cvt_pk_bf16_f32 v70, v44, v45
	v_cvt_pk_bf16_f32 v71, v46, v47
	v_pk_add_f32 v[232:233], v[232:233], v[32:33]
	v_pk_add_f32 v[232:233], v[232:233], v[34:35]
	v_pk_add_f32 v[232:233], v[232:233], v[36:37]
	v_pk_add_f32 v[232:233], v[232:233], v[38:39]
	v_pk_add_f32 v[232:233], v[232:233], v[40:41]
	v_pk_add_f32 v[232:233], v[232:233], v[42:43]
	v_pk_add_f32 v[232:233], v[232:233], v[44:45]
	v_pk_add_f32 v[232:233], v[232:233], v[46:47]
	ds_read2_b32 v[32:33], v115 offset0:32 offset1:33
	ds_read2_b32 v[34:35], v115 offset0:34 offset1:35
	ds_read2_b32 v[36:37], v115 offset0:40 offset1:41
	ds_read2_b32 v[38:39], v115 offset0:42 offset1:43
	ds_read2_b32 v[40:41], v115 offset0:48 offset1:49
	ds_read2_b32 v[42:43], v115 offset0:50 offset1:51
	ds_read2_b32 v[44:45], v115 offset0:56 offset1:57
	ds_read2_b32 v[46:47], v115 offset0:58 offset1:59
	s_waitcnt lgkmcnt(15)
	v_mfma_f32_32x32x16_bf16 v[0:15], v[64:67], v[72:75], v[0:15]
	v_mfma_f32_32x32x16_bf16 v[16:31], v[64:67], v[76:79], v[16:31]
	v_mfma_f32_32x32x16_bf16 v[0:15], v[68:71], v[220:223], v[0:15]
	v_mfma_f32_32x32x16_bf16 v[16:31], v[68:71], v[224:227], v[16:31]
	s_add_i32 s90, s76, 512
	v_add_u32_e32 v80, s90, v243
	v_add_u32_e32 v83, s90, v244
	v_add_u32_e32 v99, s90, v245
	v_add_u32_e32 v253, s90, v246
	v_add_u32_e32 v254, s90, v148
	v_add_u32_e32 v255, s90, v151
	v_med3_i32 v80, v80, 0, s99
	v_med3_i32 v83, v83, 0, s99
	v_med3_i32 v99, v99, 0, s99
	v_med3_i32 v253, v253, 0, s99
	v_med3_i32 v254, v254, 0, s99
	v_med3_i32 v255, v255, 0, s99
	v_mad_u32_u24 v80, v80, s100, v252
	v_mad_u32_u24 v83, v83, s100, v252
	v_mad_u32_u24 v99, v99, s100, v252
	v_mad_u32_u24 v253, v253, s100, v252
	v_mad_u32_u24 v254, v254, s100, v153
	v_mad_u32_u24 v255, v255, s100, v153
	global_load_dwordx4 v[156:159], v80, s[82:83]
	global_load_dwordx4 v[160:163], v83, s[82:83]
	global_load_dwordx4 v[164:167], v99, s[82:83]
	global_load_dwordx4 v[168:171], v253, s[82:83]
	global_load_dwordx4 v[172:175], v254, s[82:83] offset:768
	global_load_dwordx4 v[176:179], v255, s[82:83] offset:768
	global_load_dwordx4 v[180:183], v254, s[82:83] offset:832
	global_load_dwordx4 v[184:187], v255, s[82:83] offset:832
	s_waitcnt lgkmcnt(0)
	v_mfma_f32_32x32x16_bf16 v[32:47], v[188:191], v[48:51], v[32:47]
	ds_read_b64_tr_b16 v[72:73], v231
	ds_read_b64_tr_b16 v[74:75], v231 offset:512
	ds_read_b64_tr_b16 v[76:77], v231 offset:2048
	ds_read_b64_tr_b16 v[78:79], v231 offset:2560
	ds_read_b64_tr_b16 v[220:221], v231 offset:1024
	ds_read_b64_tr_b16 v[222:223], v231 offset:1536
	ds_read_b64_tr_b16 v[224:225], v231 offset:3072
	ds_read_b64_tr_b16 v[226:227], v231 offset:3584
	s_waitcnt vmcnt(8)
	ds_write_b128 v247, v[116:119]
	ds_write_b128 v247, v[120:123] offset:1024
	ds_write_b128 v247, v[124:127] offset:2048
	ds_write_b128 v247, v[128:131] offset:3072
	ds_read_b128 v[116:119], v248
	ds_read_b128 v[120:123], v249
	ds_read_b128 v[124:127], v250
	ds_read_b128 v[128:131], v251
	ds_write_b128 v112, v[132:135]
	ds_write_b128 v112, v[136:139] offset:1024
	ds_write_b128 v112, v[140:143] offset:2048
	ds_write_b128 v112, v[144:147] offset:3072
	v_mfma_f32_32x32x16_bf16 v[32:47], v[192:195], v[52:55], v[32:47]
	v_mfma_f32_32x32x16_bf16 v[32:47], v[196:199], v[56:59], v[32:47]
	v_mfma_f32_32x32x16_bf16 v[32:47], v[200:203], v[60:63], v[32:47]
	s_nop 11
	v_exp_f32_e32 v32, v32
	v_exp_f32_e32 v33, v33
	v_exp_f32_e32 v34, v34
	v_exp_f32_e32 v35, v35
	v_exp_f32_e32 v36, v36
	v_exp_f32_e32 v37, v37
	v_exp_f32_e32 v38, v38
	v_exp_f32_e32 v39, v39
	v_exp_f32_e32 v40, v40
	v_exp_f32_e32 v41, v41
	v_exp_f32_e32 v42, v42
	v_exp_f32_e32 v43, v43
	v_exp_f32_e32 v44, v44
	v_exp_f32_e32 v45, v45
	v_exp_f32_e32 v46, v46
	v_exp_f32_e32 v47, v47
	s_add_i32 s90, s76, -512
	v_lshlrev_b32_e32 v84, 4, v107
	v_add_u32_e32 v84, s90, v84
	v_add_u32_e32 v85, 0, v84
	v_add_u32_e32 v86, 16, v84
	v_add_u32_e32 v87, 32, v84
	v_add_u32_e32 v88, 48, v84
	v_cmp_gt_u32_e64 s[30:31], s98, v85
	v_cmp_gt_u32_e64 s[36:37], s98, v86
	v_cmp_gt_u32_e64 s[78:79], s98, v87
	v_cmp_gt_u32_e64 s[50:51], s98, v88
	v_cndmask_b32_e64 v32, 0, v32, s[30:31]
	v_add_u32_e32 v85, 128, v84
	v_cmp_gt_u32_e64 s[30:31], s98, v85
	v_cndmask_b32_e64 v33, 0, v33, s[36:37]
	v_add_u32_e32 v86, 144, v84
	v_cmp_gt_u32_e64 s[36:37], s98, v86
	v_cndmask_b32_e64 v34, 0, v34, s[78:79]
	v_add_u32_e32 v87, 160, v84
	v_cmp_gt_u32_e64 s[78:79], s98, v87
	v_cndmask_b32_e64 v35, 0, v35, s[50:51]
	v_add_u32_e32 v88, 176, v84
	v_cmp_gt_u32_e64 s[50:51], s98, v88
	v_cndmask_b32_e64 v36, 0, v36, s[30:31]
	v_add_u32_e32 v85, 256, v84
	v_cmp_gt_u32_e64 s[30:31], s98, v85
	v_cndmask_b32_e64 v37, 0, v37, s[36:37]
	v_add_u32_e32 v86, 272, v84
	v_cmp_gt_u32_e64 s[36:37], s98, v86
	v_cndmask_b32_e64 v38, 0, v38, s[78:79]
	v_add_u32_e32 v87, 288, v84
	v_cmp_gt_u32_e64 s[78:79], s98, v87
	v_cndmask_b32_e64 v39, 0, v39, s[50:51]
	v_add_u32_e32 v88, 304, v84
	v_cmp_gt_u32_e64 s[50:51], s98, v88
	v_cndmask_b32_e64 v40, 0, v40, s[30:31]
	v_add_u32_e32 v85, 384, v84
	v_cmp_gt_u32_e64 s[30:31], s98, v85
	v_cndmask_b32_e64 v41, 0, v41, s[36:37]
	v_add_u32_e32 v86, 400, v84
	v_cmp_gt_u32_e64 s[36:37], s98, v86
	v_cndmask_b32_e64 v42, 0, v42, s[78:79]
	v_add_u32_e32 v87, 416, v84
	v_cmp_gt_u32_e64 s[78:79], s98, v87
	v_cndmask_b32_e64 v43, 0, v43, s[50:51]
	v_add_u32_e32 v88, 432, v84
	v_cmp_gt_u32_e64 s[50:51], s98, v88
	v_nop
	v_cndmask_b32_e64 v44, 0, v44, s[30:31]
	v_cndmask_b32_e64 v45, 0, v45, s[36:37]
	v_cndmask_b32_e64 v46, 0, v46, s[78:79]
	v_cndmask_b32_e64 v47, 0, v47, s[50:51]
	v_cvt_pk_bf16_f32 v64, v32, v33
	v_cvt_pk_bf16_f32 v65, v34, v35
	v_cvt_pk_bf16_f32 v66, v36, v37
	v_cvt_pk_bf16_f32 v67, v38, v39
	v_cvt_pk_bf16_f32 v68, v40, v41
	v_cvt_pk_bf16_f32 v69, v42, v43
	v_cvt_pk_bf16_f32 v70, v44, v45
	v_cvt_pk_bf16_f32 v71, v46, v47
	v_pk_add_f32 v[232:233], v[232:233], v[32:33]
	v_pk_add_f32 v[232:233], v[232:233], v[34:35]
	v_pk_add_f32 v[232:233], v[232:233], v[36:37]
	v_pk_add_f32 v[232:233], v[232:233], v[38:39]
	v_pk_add_f32 v[232:233], v[232:233], v[40:41]
	v_pk_add_f32 v[232:233], v[232:233], v[42:43]
	v_pk_add_f32 v[232:233], v[232:233], v[44:45]
	v_pk_add_f32 v[232:233], v[232:233], v[46:47]
	ds_read2_b32 v[32:33], v115 offset0:64 offset1:65
	ds_read2_b32 v[34:35], v115 offset0:66 offset1:67
	ds_read2_b32 v[36:37], v115 offset0:72 offset1:73
	ds_read2_b32 v[38:39], v115 offset0:74 offset1:75
	ds_read2_b32 v[40:41], v115 offset0:80 offset1:81
	ds_read2_b32 v[42:43], v115 offset0:82 offset1:83
	ds_read2_b32 v[44:45], v115 offset0:88 offset1:89
	ds_read2_b32 v[46:47], v115 offset0:90 offset1:91
	s_waitcnt lgkmcnt(15)
	v_mfma_f32_32x32x16_bf16 v[0:15], v[64:67], v[72:75], v[0:15]
	v_mfma_f32_32x32x16_bf16 v[16:31], v[64:67], v[76:79], v[16:31]
	v_mfma_f32_32x32x16_bf16 v[0:15], v[68:71], v[220:223], v[0:15]
	v_mfma_f32_32x32x16_bf16 v[16:31], v[68:71], v[224:227], v[16:31]
	s_add_i32 s90, s76, 1024
	v_add_u32_e32 v80, s90, v243
	v_add_u32_e32 v83, s90, v244
	v_add_u32_e32 v99, s90, v245
	v_add_u32_e32 v253, s90, v246
	v_add_u32_e32 v254, s90, v148
	v_add_u32_e32 v255, s90, v151
	v_med3_i32 v80, v80, 0, s99
	v_med3_i32 v83, v83, 0, s99
	v_med3_i32 v99, v99, 0, s99
	v_med3_i32 v253, v253, 0, s99
	v_med3_i32 v254, v254, 0, s99
	v_med3_i32 v255, v255, 0, s99
	v_mad_u32_u24 v80, v80, s100, v252
	v_mad_u32_u24 v83, v83, s100, v252
	v_mad_u32_u24 v99, v99, s100, v252
	v_mad_u32_u24 v253, v253, s100, v252
	v_mad_u32_u24 v254, v254, s100, v153
	v_mad_u32_u24 v255, v255, s100, v153
	global_load_dwordx4 v[188:191], v80, s[82:83]
	global_load_dwordx4 v[192:195], v83, s[82:83]
	global_load_dwordx4 v[196:199], v99, s[82:83]
	global_load_dwordx4 v[200:203], v253, s[82:83]
	global_load_dwordx4 v[204:207], v254, s[82:83] offset:768
	global_load_dwordx4 v[208:211], v255, s[82:83] offset:768
	global_load_dwordx4 v[212:215], v254, s[82:83] offset:832
	global_load_dwordx4 v[216:219], v255, s[82:83] offset:832
	s_waitcnt lgkmcnt(0)
	v_mfma_f32_32x32x16_bf16 v[32:47], v[116:119], v[48:51], v[32:47]
	ds_read_b64_tr_b16 v[72:73], v231
	ds_read_b64_tr_b16 v[74:75], v231 offset:512
	ds_read_b64_tr_b16 v[76:77], v231 offset:2048
	ds_read_b64_tr_b16 v[78:79], v231 offset:2560
	ds_read_b64_tr_b16 v[220:221], v231 offset:1024
	ds_read_b64_tr_b16 v[222:223], v231 offset:1536
	ds_read_b64_tr_b16 v[224:225], v231 offset:3072
	ds_read_b64_tr_b16 v[226:227], v231 offset:3584
	s_waitcnt vmcnt(8)
	ds_write_b128 v247, v[156:159]
	ds_write_b128 v247, v[160:163] offset:1024
	ds_write_b128 v247, v[164:167] offset:2048
	ds_write_b128 v247, v[168:171] offset:3072
	ds_read_b128 v[156:159], v248
	ds_read_b128 v[160:163], v249
	ds_read_b128 v[164:167], v250
	ds_read_b128 v[168:171], v251
	ds_write_b128 v112, v[172:175]
	ds_write_b128 v112, v[176:179] offset:1024
	ds_write_b128 v112, v[180:183] offset:2048
	ds_write_b128 v112, v[184:187] offset:3072
	v_mfma_f32_32x32x16_bf16 v[32:47], v[120:123], v[52:55], v[32:47]
	v_mfma_f32_32x32x16_bf16 v[32:47], v[124:127], v[56:59], v[32:47]
	v_mfma_f32_32x32x16_bf16 v[32:47], v[128:131], v[60:63], v[32:47]
	s_nop 11
	v_exp_f32_e32 v32, v32
	v_exp_f32_e32 v33, v33
	v_exp_f32_e32 v34, v34
	v_exp_f32_e32 v35, v35
	v_exp_f32_e32 v36, v36
	v_exp_f32_e32 v37, v37
	v_exp_f32_e32 v38, v38
	v_exp_f32_e32 v39, v39
	v_exp_f32_e32 v40, v40
	v_exp_f32_e32 v41, v41
	v_exp_f32_e32 v42, v42
	v_exp_f32_e32 v43, v43
	v_exp_f32_e32 v44, v44
	v_exp_f32_e32 v45, v45
	v_exp_f32_e32 v46, v46
	v_exp_f32_e32 v47, v47
	s_add_i32 s90, s76, 0
	v_lshlrev_b32_e32 v84, 4, v107
	v_add_u32_e32 v84, s90, v84
	v_add_u32_e32 v85, 0, v84
	v_add_u32_e32 v86, 16, v84
	v_add_u32_e32 v87, 32, v84
	v_add_u32_e32 v88, 48, v84
	v_cmp_gt_u32_e64 s[30:31], s98, v85
	v_cmp_gt_u32_e64 s[36:37], s98, v86
	v_cmp_gt_u32_e64 s[78:79], s98, v87
	v_cmp_gt_u32_e64 s[50:51], s98, v88
	v_cndmask_b32_e64 v32, 0, v32, s[30:31]
	v_add_u32_e32 v85, 128, v84
	v_cmp_gt_u32_e64 s[30:31], s98, v85
	v_cndmask_b32_e64 v33, 0, v33, s[36:37]
	v_add_u32_e32 v86, 144, v84
	v_cmp_gt_u32_e64 s[36:37], s98, v86
	v_cndmask_b32_e64 v34, 0, v34, s[78:79]
	v_add_u32_e32 v87, 160, v84
	v_cmp_gt_u32_e64 s[78:79], s98, v87
	v_cndmask_b32_e64 v35, 0, v35, s[50:51]
	v_add_u32_e32 v88, 176, v84
	v_cmp_gt_u32_e64 s[50:51], s98, v88
	v_cndmask_b32_e64 v36, 0, v36, s[30:31]
	v_add_u32_e32 v85, 256, v84
	v_cmp_gt_u32_e64 s[30:31], s98, v85
	v_cndmask_b32_e64 v37, 0, v37, s[36:37]
	v_add_u32_e32 v86, 272, v84
	v_cmp_gt_u32_e64 s[36:37], s98, v86
	v_cndmask_b32_e64 v38, 0, v38, s[78:79]
	v_add_u32_e32 v87, 288, v84
	v_cmp_gt_u32_e64 s[78:79], s98, v87
	v_cndmask_b32_e64 v39, 0, v39, s[50:51]
	v_add_u32_e32 v88, 304, v84
	v_cmp_gt_u32_e64 s[50:51], s98, v88
	v_cndmask_b32_e64 v40, 0, v40, s[30:31]
	v_add_u32_e32 v85, 384, v84
	v_cmp_gt_u32_e64 s[30:31], s98, v85
	v_cndmask_b32_e64 v41, 0, v41, s[36:37]
	v_add_u32_e32 v86, 400, v84
	v_cmp_gt_u32_e64 s[36:37], s98, v86
	v_cndmask_b32_e64 v42, 0, v42, s[78:79]
	v_add_u32_e32 v87, 416, v84
	v_cmp_gt_u32_e64 s[78:79], s98, v87
	v_cndmask_b32_e64 v43, 0, v43, s[50:51]
	v_add_u32_e32 v88, 432, v84
	v_cmp_gt_u32_e64 s[50:51], s98, v88
	v_nop
	v_cndmask_b32_e64 v44, 0, v44, s[30:31]
	v_cndmask_b32_e64 v45, 0, v45, s[36:37]
	v_cndmask_b32_e64 v46, 0, v46, s[78:79]
	v_cndmask_b32_e64 v47, 0, v47, s[50:51]
	v_cvt_pk_bf16_f32 v64, v32, v33
	v_cvt_pk_bf16_f32 v65, v34, v35
	v_cvt_pk_bf16_f32 v66, v36, v37
	v_cvt_pk_bf16_f32 v67, v38, v39
	v_cvt_pk_bf16_f32 v68, v40, v41
	v_cvt_pk_bf16_f32 v69, v42, v43
	v_cvt_pk_bf16_f32 v70, v44, v45
	v_cvt_pk_bf16_f32 v71, v46, v47
	v_pk_add_f32 v[232:233], v[232:233], v[32:33]
	v_pk_add_f32 v[232:233], v[232:233], v[34:35]
	v_pk_add_f32 v[232:233], v[232:233], v[36:37]
	v_pk_add_f32 v[232:233], v[232:233], v[38:39]
	v_pk_add_f32 v[232:233], v[232:233], v[40:41]
	v_pk_add_f32 v[232:233], v[232:233], v[42:43]
	v_pk_add_f32 v[232:233], v[232:233], v[44:45]
	v_pk_add_f32 v[232:233], v[232:233], v[46:47]
	ds_read2_b32 v[32:33], v115 offset0:96 offset1:97
	ds_read2_b32 v[34:35], v115 offset0:98 offset1:99
	ds_read2_b32 v[36:37], v115 offset0:104 offset1:105
	ds_read2_b32 v[38:39], v115 offset0:106 offset1:107
	ds_read2_b32 v[40:41], v115 offset0:112 offset1:113
	ds_read2_b32 v[42:43], v115 offset0:114 offset1:115
	ds_read2_b32 v[44:45], v115 offset0:120 offset1:121
	ds_read2_b32 v[46:47], v115 offset0:122 offset1:123
	s_waitcnt lgkmcnt(15)
	v_mfma_f32_32x32x16_bf16 v[0:15], v[64:67], v[72:75], v[0:15]
	v_mfma_f32_32x32x16_bf16 v[16:31], v[64:67], v[76:79], v[16:31]
	v_mfma_f32_32x32x16_bf16 v[0:15], v[68:71], v[220:223], v[0:15]
	v_mfma_f32_32x32x16_bf16 v[16:31], v[68:71], v[224:227], v[16:31]
	s_waitcnt lgkmcnt(0)
	v_mfma_f32_32x32x16_bf16 v[32:47], v[156:159], v[48:51], v[32:47]
	ds_read_b64_tr_b16 v[72:73], v231
	ds_read_b64_tr_b16 v[74:75], v231 offset:512
	ds_read_b64_tr_b16 v[76:77], v231 offset:2048
	ds_read_b64_tr_b16 v[78:79], v231 offset:2560
	ds_read_b64_tr_b16 v[220:221], v231 offset:1024
	ds_read_b64_tr_b16 v[222:223], v231 offset:1536
	ds_read_b64_tr_b16 v[224:225], v231 offset:3072
	ds_read_b64_tr_b16 v[226:227], v231 offset:3584
	s_waitcnt vmcnt(0)
	ds_write_b128 v247, v[188:191]
	ds_write_b128 v247, v[192:195] offset:1024
	ds_write_b128 v247, v[196:199] offset:2048
	ds_write_b128 v247, v[200:203] offset:3072
	ds_read_b128 v[188:191], v248
	ds_read_b128 v[192:195], v249
	ds_read_b128 v[196:199], v250
	ds_read_b128 v[200:203], v251
	ds_write_b128 v112, v[204:207]
	ds_write_b128 v112, v[208:211] offset:1024
	ds_write_b128 v112, v[212:215] offset:2048
	ds_write_b128 v112, v[216:219] offset:3072
	v_mfma_f32_32x32x16_bf16 v[32:47], v[160:163], v[52:55], v[32:47]
	v_mfma_f32_32x32x16_bf16 v[32:47], v[164:167], v[56:59], v[32:47]
	v_mfma_f32_32x32x16_bf16 v[32:47], v[168:171], v[60:63], v[32:47]
	s_nop 11
	v_exp_f32_e32 v32, v32
	v_exp_f32_e32 v33, v33
	v_exp_f32_e32 v34, v34
	v_exp_f32_e32 v35, v35
	v_exp_f32_e32 v36, v36
	v_exp_f32_e32 v37, v37
	v_exp_f32_e32 v38, v38
	v_exp_f32_e32 v39, v39
	v_exp_f32_e32 v40, v40
	v_exp_f32_e32 v41, v41
	v_exp_f32_e32 v42, v42
	v_exp_f32_e32 v43, v43
	v_exp_f32_e32 v44, v44
	v_exp_f32_e32 v45, v45
	v_exp_f32_e32 v46, v46
	v_exp_f32_e32 v47, v47
	s_add_i32 s90, s76, 512
	v_lshlrev_b32_e32 v84, 4, v107
	v_add_u32_e32 v84, s90, v84
	v_add_u32_e32 v85, 0, v84
	v_add_u32_e32 v86, 16, v84
	v_add_u32_e32 v87, 32, v84
	v_add_u32_e32 v88, 48, v84
	v_cmp_gt_u32_e64 s[30:31], s98, v85
	v_cmp_gt_u32_e64 s[36:37], s98, v86
	v_cmp_gt_u32_e64 s[78:79], s98, v87
	v_cmp_gt_u32_e64 s[50:51], s98, v88
	v_cndmask_b32_e64 v32, 0, v32, s[30:31]
	v_add_u32_e32 v85, 128, v84
	v_cmp_gt_u32_e64 s[30:31], s98, v85
	v_cndmask_b32_e64 v33, 0, v33, s[36:37]
	v_add_u32_e32 v86, 144, v84
	v_cmp_gt_u32_e64 s[36:37], s98, v86
	v_cndmask_b32_e64 v34, 0, v34, s[78:79]
	v_add_u32_e32 v87, 160, v84
	v_cmp_gt_u32_e64 s[78:79], s98, v87
	v_cndmask_b32_e64 v35, 0, v35, s[50:51]
	v_add_u32_e32 v88, 176, v84
	v_cmp_gt_u32_e64 s[50:51], s98, v88
	v_cndmask_b32_e64 v36, 0, v36, s[30:31]
	v_add_u32_e32 v85, 256, v84
	v_cmp_gt_u32_e64 s[30:31], s98, v85
	v_cndmask_b32_e64 v37, 0, v37, s[36:37]
	v_add_u32_e32 v86, 272, v84
	v_cmp_gt_u32_e64 s[36:37], s98, v86
	v_cndmask_b32_e64 v38, 0, v38, s[78:79]
	v_add_u32_e32 v87, 288, v84
	v_cmp_gt_u32_e64 s[78:79], s98, v87
	v_cndmask_b32_e64 v39, 0, v39, s[50:51]
	v_add_u32_e32 v88, 304, v84
	v_cmp_gt_u32_e64 s[50:51], s98, v88
	v_cndmask_b32_e64 v40, 0, v40, s[30:31]
	v_add_u32_e32 v85, 384, v84
	v_cmp_gt_u32_e64 s[30:31], s98, v85
	v_cndmask_b32_e64 v41, 0, v41, s[36:37]
	v_add_u32_e32 v86, 400, v84
	v_cmp_gt_u32_e64 s[36:37], s98, v86
	v_cndmask_b32_e64 v42, 0, v42, s[78:79]
	v_add_u32_e32 v87, 416, v84
	v_cmp_gt_u32_e64 s[78:79], s98, v87
	v_cndmask_b32_e64 v43, 0, v43, s[50:51]
	v_add_u32_e32 v88, 432, v84
	v_cmp_gt_u32_e64 s[50:51], s98, v88
	v_nop
	v_cndmask_b32_e64 v44, 0, v44, s[30:31]
	v_cndmask_b32_e64 v45, 0, v45, s[36:37]
	v_cndmask_b32_e64 v46, 0, v46, s[78:79]
	v_cndmask_b32_e64 v47, 0, v47, s[50:51]
	v_cvt_pk_bf16_f32 v64, v32, v33
	v_cvt_pk_bf16_f32 v65, v34, v35
	v_cvt_pk_bf16_f32 v66, v36, v37
	v_cvt_pk_bf16_f32 v67, v38, v39
	v_cvt_pk_bf16_f32 v68, v40, v41
	v_cvt_pk_bf16_f32 v69, v42, v43
	v_cvt_pk_bf16_f32 v70, v44, v45
	v_cvt_pk_bf16_f32 v71, v46, v47
	v_pk_add_f32 v[232:233], v[232:233], v[32:33]
	v_pk_add_f32 v[232:233], v[232:233], v[34:35]
	v_pk_add_f32 v[232:233], v[232:233], v[36:37]
	v_pk_add_f32 v[232:233], v[232:233], v[38:39]
	v_pk_add_f32 v[232:233], v[232:233], v[40:41]
	v_pk_add_f32 v[232:233], v[232:233], v[42:43]
	v_pk_add_f32 v[232:233], v[232:233], v[44:45]
	v_pk_add_f32 v[232:233], v[232:233], v[46:47]
	ds_read2_b32 v[32:33], v115 offset0:128 offset1:129
	ds_read2_b32 v[34:35], v115 offset0:130 offset1:131
	ds_read2_b32 v[36:37], v115 offset0:136 offset1:137
	ds_read2_b32 v[38:39], v115 offset0:138 offset1:139
	ds_read2_b32 v[40:41], v115 offset0:144 offset1:145
	ds_read2_b32 v[42:43], v115 offset0:146 offset1:147
	ds_read2_b32 v[44:45], v115 offset0:152 offset1:153
	ds_read2_b32 v[46:47], v115 offset0:154 offset1:155
	s_waitcnt lgkmcnt(15)
; __device__ __forceinline__ int crow(int r, int hi) { return (r & 3) + 8 * (r >> 2) + 4 * hi; }
; __device__ __forceinline__ void dil_unit(LAS unsigned char* lds, bf16_t* proj, int seq, int hd, int T0, int rho) {
;     ...
;     l += __shfl_xor(l, 32);
; #pragma unroll
;     for (int rr = 0; rr < 16; ++rr) {
;         const int j = crow(rr, hi);
;         const float il = __builtin_amdgcn_rcpf(__shfl(l, j));
	v_mfma_f32_32x32x16_bf16 v[0:15], v[64:67], v[72:75], v[0:15]
	v_mfma_f32_32x32x16_bf16 v[16:31], v[64:67], v[76:79], v[16:31]
	v_mfma_f32_32x32x16_bf16 v[0:15], v[68:71], v[220:223], v[0:15]
	v_mfma_f32_32x32x16_bf16 v[16:31], v[68:71], v[224:227], v[16:31]
	s_waitcnt lgkmcnt(0)
	v_mfma_f32_32x32x16_bf16 v[32:47], v[188:191], v[48:51], v[32:47]
	ds_read_b64_tr_b16 v[72:73], v231
	ds_read_b64_tr_b16 v[74:75], v231 offset:512
	ds_read_b64_tr_b16 v[76:77], v231 offset:2048
	ds_read_b64_tr_b16 v[78:79], v231 offset:2560
	ds_read_b64_tr_b16 v[220:221], v231 offset:1024
	ds_read_b64_tr_b16 v[222:223], v231 offset:1536
	ds_read_b64_tr_b16 v[224:225], v231 offset:3072
	ds_read_b64_tr_b16 v[226:227], v231 offset:3584
	v_mfma_f32_32x32x16_bf16 v[32:47], v[192:195], v[52:55], v[32:47]
	v_mfma_f32_32x32x16_bf16 v[32:47], v[196:199], v[56:59], v[32:47]
	v_mfma_f32_32x32x16_bf16 v[32:47], v[200:203], v[60:63], v[32:47]
	s_nop 11
	v_exp_f32_e32 v32, v32
	v_exp_f32_e32 v33, v33
	v_exp_f32_e32 v34, v34
	v_exp_f32_e32 v35, v35
	v_exp_f32_e32 v36, v36
	v_exp_f32_e32 v37, v37
	v_exp_f32_e32 v38, v38
	v_exp_f32_e32 v39, v39
	v_exp_f32_e32 v40, v40
	v_exp_f32_e32 v41, v41
	v_exp_f32_e32 v42, v42
	v_exp_f32_e32 v43, v43
	v_exp_f32_e32 v44, v44
	v_exp_f32_e32 v45, v45
	v_exp_f32_e32 v46, v46
	v_exp_f32_e32 v47, v47
	s_add_i32 s90, s76, 1024
	v_lshlrev_b32_e32 v84, 4, v107
	v_add_u32_e32 v84, s90, v84
	v_add_u32_e32 v85, 0, v84
	v_add_u32_e32 v86, 16, v84
	v_add_u32_e32 v87, 32, v84
	v_add_u32_e32 v88, 48, v84
	v_cmp_gt_u32_e64 s[30:31], s98, v85
	v_cmp_gt_u32_e64 s[36:37], s98, v86
	v_cmp_gt_u32_e64 s[78:79], s98, v87
	v_cmp_gt_u32_e64 s[50:51], s98, v88
	v_cndmask_b32_e64 v32, 0, v32, s[30:31]
	v_add_u32_e32 v85, 128, v84
	v_cmp_gt_u32_e64 s[30:31], s98, v85
	v_cndmask_b32_e64 v33, 0, v33, s[36:37]
	v_add_u32_e32 v86, 144, v84
	v_cmp_gt_u32_e64 s[36:37], s98, v86
	v_cndmask_b32_e64 v34, 0, v34, s[78:79]
	v_add_u32_e32 v87, 160, v84
	v_cmp_gt_u32_e64 s[78:79], s98, v87
	v_cndmask_b32_e64 v35, 0, v35, s[50:51]
	v_add_u32_e32 v88, 176, v84
	v_cmp_gt_u32_e64 s[50:51], s98, v88
	v_cndmask_b32_e64 v36, 0, v36, s[30:31]
	v_add_u32_e32 v85, 256, v84
	v_cmp_gt_u32_e64 s[30:31], s98, v85
	v_cndmask_b32_e64 v37, 0, v37, s[36:37]
	v_add_u32_e32 v86, 272, v84
	v_cmp_gt_u32_e64 s[36:37], s98, v86
	v_cndmask_b32_e64 v38, 0, v38, s[78:79]
	v_add_u32_e32 v87, 288, v84
	v_cmp_gt_u32_e64 s[78:79], s98, v87
	v_cndmask_b32_e64 v39, 0, v39, s[50:51]
	v_add_u32_e32 v88, 304, v84
	v_cmp_gt_u32_e64 s[50:51], s98, v88
	v_cndmask_b32_e64 v40, 0, v40, s[30:31]
	v_add_u32_e32 v85, 384, v84
	v_cmp_gt_u32_e64 s[30:31], s98, v85
	v_cndmask_b32_e64 v41, 0, v41, s[36:37]
	v_add_u32_e32 v86, 400, v84
	v_cmp_gt_u32_e64 s[36:37], s98, v86
	v_cndmask_b32_e64 v42, 0, v42, s[78:79]
	v_add_u32_e32 v87, 416, v84
	v_cmp_gt_u32_e64 s[78:79], s98, v87
	v_cndmask_b32_e64 v43, 0, v43, s[50:51]
	v_add_u32_e32 v88, 432, v84
	v_cmp_gt_u32_e64 s[50:51], s98, v88
	v_nop
	v_cndmask_b32_e64 v44, 0, v44, s[30:31]
	v_cndmask_b32_e64 v45, 0, v45, s[36:37]
	v_cndmask_b32_e64 v46, 0, v46, s[78:79]
	v_cndmask_b32_e64 v47, 0, v47, s[50:51]
	v_cvt_pk_bf16_f32 v64, v32, v33
	v_cvt_pk_bf16_f32 v65, v34, v35
	v_cvt_pk_bf16_f32 v66, v36, v37
	v_cvt_pk_bf16_f32 v67, v38, v39
	v_cvt_pk_bf16_f32 v68, v40, v41
	v_cvt_pk_bf16_f32 v69, v42, v43
	v_cvt_pk_bf16_f32 v70, v44, v45
	v_cvt_pk_bf16_f32 v71, v46, v47
	v_pk_add_f32 v[232:233], v[232:233], v[32:33]
	v_pk_add_f32 v[232:233], v[232:233], v[34:35]
	v_pk_add_f32 v[232:233], v[232:233], v[36:37]
	v_pk_add_f32 v[232:233], v[232:233], v[38:39]
	v_pk_add_f32 v[232:233], v[232:233], v[40:41]
	v_pk_add_f32 v[232:233], v[232:233], v[42:43]
	v_pk_add_f32 v[232:233], v[232:233], v[44:45]
	v_pk_add_f32 v[232:233], v[232:233], v[46:47]
	s_waitcnt lgkmcnt(0)
	v_mfma_f32_32x32x16_bf16 v[0:15], v[64:67], v[72:75], v[0:15]
	v_mfma_f32_32x32x16_bf16 v[16:31], v[64:67], v[76:79], v[16:31]
	v_mfma_f32_32x32x16_bf16 v[0:15], v[68:71], v[220:223], v[0:15]
	v_mfma_f32_32x32x16_bf16 v[16:31], v[68:71], v[224:227], v[16:31]
	v_add_f32_e32 v113, v232, v233
	v_or_b32_e32 v114, 1, v107
	v_or_b32_e32 v97, 2, v107
	v_or_b32_e32 v96, 3, v107
	v_or_b32_e32 v95, 8, v107
	v_or_b32_e32 v94, 9, v107
	v_or_b32_e32 v93, 10, v107
	v_or_b32_e32 v92, 11, v107
	v_or_b32_e32 v91, 16, v107
	v_or_b32_e32 v90, 17, v107
	v_or_b32_e32 v89, 18, v107
	v_or_b32_e32 v88, 19, v107
	v_or_b32_e32 v87, 24, v107
	v_or_b32_e32 v86, 25, v107
	v_or_b32_e32 v85, 26, v107
	v_or_b32_e32 v84, 27, v107
	s_nop 11
	s_branch .LBB0_553

; #define LAS __attribute__((address_space(3)))
; #define GAS __attribute__((address_space(1)))
; __device__ __forceinline__ void dil_unit(LAS unsigned char* lds, bf16_t* proj, int seq, int hd, int T0, int rho) {
;     int tid_ = threadIdx.x; asm volatile("" : "+v"(tid_));
;     const int tid = tid_, lane = tid & 63, r32 = lane & 31, hi = lane >> 5, wid = __builtin_amdgcn_readfirstlane(tid >> 6);
;     bf16_t* base = proj + (size_t)seq * SEQ * NIN;
;     LAS unsigned char* wbuf = lds + wid * 4096;
;     const LAS unsigned char* vp = wbuf + ((lane >> 4) & 1) * 32 + (lane & 3) * 8 + (4 * hi + ((lane & 15) >> 2)) * 64;
;     const int P0 = T0 + rho;
;     bf16x8 qr[4];
; #pragma unroll
;     for (int ks = 0; ks < 4; ++ks) qr[ks] = *(const GAS bf16x8*)(base + (size_t)(P0 + 16 * r32) * NIN + PC_LQ + hd * 64 + 16 * ks + 8 * hi);
;     f32x16 o0 = {}, o1 = {}; float l = 0.f;
;     const bool bound = (T0 < 1024) || (T0 >= 15360);
.LBB0_1266:
	s_lshr_b32 s82, s60, 8
	s_mul_i32 s82, s82, 13
	s_add_i32 s82, s82, s60
	s_ashr_i32 s4, s60, 6
	s_mul_hi_i32 s9, s4, 0x2aaaaaab
	s_lshl_b32 s5, s82, 8
	s_lshr_b32 s10, s9, 31
	s_and_b32 s8, s5, 0x3e00
	s_lshl_b32 s5, s82, 3
	s_add_i32 s9, s9, s10
	s_and_b32 s5, s5, 8
	s_mul_i32 s10, s9, 6
	s_add_i32 s5, s5, s61
	s_sub_i32 s10, s4, s10
	s_mul_hi_i32 s4, s9, 0x6000000
	s_mul_i32 s9, s9, 0x6000000
	v_mov_b32_e32 v2, v154
	s_add_u32 s52, s44, s9
	s_addc_u32 s53, s45, s4
	v_and_b32_e32 v105, 31, v2
	s_add_i32 s67, s5, s8
	v_lshl_add_u32 v3, v105, 4, s67
	v_mov_b64_e32 v[0:1], s[52:53]
	s_lshl_b32 s54, s10, 6
	v_bfe_u32 v106, v2, 5, 1
	v_mad_u64_u32 v[0:1], s[4:5], v3, s62, v[0:1]
	s_ashr_i32 s55, s54, 31
	v_lshl_add_u64 v[0:1], s[54:55], 1, v[0:1]
	v_lshlrev_b32_e32 v80, 4, v106
	v_lshl_add_u64 v[0:1], v[0:1], 0, v[80:81]
	global_load_dwordx4 v[48:51], v[0:1], off offset:1280
	global_load_dwordx4 v[52:55], v[0:1], off offset:1312
	global_load_dwordx4 v[56:59], v[0:1], off offset:1344
	global_load_dwordx4 v[60:63], v[0:1], off offset:1376
	v_readfirstlane_b32 s4, v2
	s_lshl_b32 s4, s4, 6
	s_and_b32 s4, s4, 0xfffff000
	v_lshlrev_b32_e32 v0, 1, v2
	v_lshlrev_b32_e32 v104, 3, v2
	v_lshlrev_b32_e32 v107, 2, v106
	v_lshrrev_b32_e32 v1, 2, v2
	v_and_b32_e32 v103, 63, v2
	v_and_b32_e32 v0, 32, v0
	v_and_b32_e32 v98, 24, v104
	v_and_or_b32 v1, v1, 3, v107
	s_add_i32 s69, s4, 0
	v_lshlrev_b32_e32 v108, 6, v1
	v_lshlrev_b32_e32 v1, 3, v106
	v_add3_u32 v109, s69, v0, v98
	s_addk_i32 s8, 0xc400
	v_lshrrev_b32_e32 v110, 2, v103
	v_lshlrev_b32_e32 v0, 4, v103
	s_mov_b64 s[4:5], -1
	s_cmp_gt_u32 s8, 0xffffc7ff
	v_lshlrev_b32_e32 v100, 1, v98
	s_mul_i32 s8, s10, 0x1c00
	v_lshlrev_b32_e32 v82, 1, v1
	v_or_b32_e32 v111, 16, v110
	v_add_u32_e32 v112, s69, v0
	s_cbranch_scc0 .LBB0_1270
	s_movk_i32 s100, 0x1800
	s_add_i32 s101, s8, 0x15c00
	s_lshl_b32 s90, s54, 1
	s_add_u32 s82, s52, s90
	s_addc_u32 s83, s53, 0
	s_add_u32 s82, s82, 0x1200
	s_addc_u32 s83, s83, 0
	s_sub_i32 s90, s67, 64
	s_mul_i32 s90, s90, 0x1800
	s_add_u32 s84, s82, s90
	s_addc_u32 s85, s83, 0
	s_sub_i32 s90, s67, 256
	s_mul_i32 s90, s90, 0x1800
	s_add_u32 s86, s82, s90
	s_addc_u32 s87, s83, 0
	s_sub_i32 s90, s67, 1024
	s_mul_i32 s90, s90, 0x1800
	s_add_u32 s88, s82, s90
	s_addc_u32 s89, s83, 0
	v_lshlrev_b32_e32 v153, 1, v98
	v_mad_u32_u24 v80, v105, s100, v82
	v_mad_u32_u24 v100, v110, s100, v153
	v_add_u32_e32 v149, 0x18000, v100
	v_lshlrev_b32_e32 v83, 2, v105
	v_mad_u32_u24 v83, v83, s100, v82
	v_lshlrev_b32_e32 v101, 2, v110
	v_mad_u32_u24 v101, v101, s100, v153
	v_add_u32_e32 v150, 0x60000, v101
	v_lshlrev_b32_e32 v99, 4, v105
	v_mad_u32_u24 v99, v99, s100, v82
	v_lshlrev_b32_e32 v148, 4, v110
	v_mad_u32_u24 v148, v148, s100, v153
	v_add_u32_e32 v151, 0x180000, v148
	v_lshrrev_b32_e32 v249, 3, v103
	v_and_b32_e32 v250, 7, v103
	v_lshlrev_b32_e32 v250, 4, v250
	v_add_u32_e32 v235, 0, v249
	v_mad_u32_u24 v235, v235, s100, v250
	v_add_u32_e32 v236, 8, v249
	v_mad_u32_u24 v236, v236, s100, v250
	v_add_u32_e32 v237, 16, v249
	v_mad_u32_u24 v237, v237, s100, v250
	v_add_u32_e32 v238, 24, v249
	v_mad_u32_u24 v238, v238, s100, v250
	v_add_u32_e32 v239, 0, v249
	v_lshlrev_b32_e32 v239, 2, v239
	v_mad_u32_u24 v239, v239, s100, v250
	v_add_u32_e32 v240, 8, v249
	v_lshlrev_b32_e32 v240, 2, v240
	v_mad_u32_u24 v240, v240, s100, v250
	v_add_u32_e32 v241, 16, v249
	v_lshlrev_b32_e32 v241, 2, v241
	v_mad_u32_u24 v241, v241, s100, v250
	v_add_u32_e32 v242, 24, v249
	v_lshlrev_b32_e32 v242, 2, v242
	v_mad_u32_u24 v242, v242, s100, v250
	v_add_u32_e32 v243, 0, v249
	v_lshlrev_b32_e32 v243, 4, v243
	v_mad_u32_u24 v243, v243, s100, v250
	v_add_u32_e32 v244, 8, v249
	v_lshlrev_b32_e32 v244, 4, v244
	v_mad_u32_u24 v244, v244, s100, v250
	v_add_u32_e32 v245, 16, v249
	v_lshlrev_b32_e32 v245, 4, v245
	v_mad_u32_u24 v245, v245, s100, v250
	v_add_u32_e32 v246, 24, v249
	v_lshlrev_b32_e32 v246, 4, v246
	v_mad_u32_u24 v246, v246, s100, v250
	v_and_b32_e32 v247, 7, v249
	v_lshlrev_b32_e32 v247, 4, v247
	v_xor_b32_e32 v247, v247, v112
	v_and_b32_e32 v153, 7, v105
	v_or_b32_e32 v248, 0, v106
	v_xor_b32_e32 v248, v248, v153
	v_lshlrev_b32_e32 v248, 4, v248
	v_lshl_add_u32 v248, v105, 7, v248
	v_add_u32_e32 v248, s69, v248
	v_or_b32_e32 v249, 2, v106
	v_xor_b32_e32 v249, v249, v153
	v_lshlrev_b32_e32 v249, 4, v249
	v_lshl_add_u32 v249, v105, 7, v249
	v_add_u32_e32 v249, s69, v249
	v_or_b32_e32 v250, 4, v106
	v_xor_b32_e32 v250, v250, v153
	v_lshlrev_b32_e32 v250, 4, v250
	v_lshl_add_u32 v250, v105, 7, v250
	v_add_u32_e32 v250, s69, v250
	v_or_b32_e32 v251, 6, v106
	v_xor_b32_e32 v251, v251, v153
	v_lshlrev_b32_e32 v251, 4, v251
	v_lshl_add_u32 v251, v105, 7, v251
	v_add_u32_e32 v251, s69, v251
	v_lshlrev_b32_e32 v153, 1, v98
	v_mul_u32_u24_e32 v228, 17, v105
	v_sub_u32_e32 v228, v107, v228
	s_mul_i32 s90, s54, 153
	s_lshr_b32 s90, s90, 1
	s_add_i32 s90, s90, 34876
	v_lshl_add_u32 v228, v228, 2, s90
	v_lshlrev_b32_e32 v229, 2, v105
	v_sub_u32_e32 v229, v107, v229
	s_add_i32 s90, s101, 5104
	v_lshl_add_u32 v229, v229, 2, s90
	v_sub_u32_e32 v230, v107, v105
	s_add_i32 s90, s101, 6364
	v_lshl_add_u32 v230, v230, 2, s90
	v_add_u32_e32 v231, v109, v108
	v_mov_b64_e32 v[232:233], 0
	v_mov_b64_e32 v[0:1], 0
	v_mov_b64_e32 v[2:3], 0
	v_mov_b64_e32 v[4:5], 0
	v_mov_b64_e32 v[6:7], 0
	v_mov_b64_e32 v[8:9], 0
	v_mov_b64_e32 v[10:11], 0
	v_mov_b64_e32 v[12:13], 0
	v_mov_b64_e32 v[14:15], 0
	v_mov_b64_e32 v[16:17], 0
	v_mov_b64_e32 v[18:19], 0
	v_mov_b64_e32 v[20:21], 0
	v_mov_b64_e32 v[22:23], 0
	v_mov_b64_e32 v[24:25], 0
	v_mov_b64_e32 v[26:27], 0
	v_mov_b64_e32 v[28:29], 0
	v_mov_b64_e32 v[30:31], 0
	global_load_dwordx4 v[116:119], v235, s[84:85]
	global_load_dwordx4 v[120:123], v236, s[84:85]
	global_load_dwordx4 v[124:127], v237, s[84:85]
	global_load_dwordx4 v[128:131], v238, s[84:85]
	global_load_dwordx4 v[132:135], v100, s[84:85] offset:768
	global_load_dwordx4 v[136:139], v149, s[84:85] offset:768
	global_load_dwordx4 v[140:143], v100, s[84:85] offset:832
	global_load_dwordx4 v[144:147], v149, s[84:85] offset:832
	s_add_u32 s84, s84, 0x30000
	s_addc_u32 s85, s85, 0
	global_load_dwordx4 v[156:159], v235, s[84:85]
	global_load_dwordx4 v[160:163], v236, s[84:85]
	global_load_dwordx4 v[164:167], v237, s[84:85]
	global_load_dwordx4 v[168:171], v238, s[84:85]
	global_load_dwordx4 v[172:175], v100, s[84:85] offset:768
	global_load_dwordx4 v[176:179], v149, s[84:85] offset:768
	global_load_dwordx4 v[180:183], v100, s[84:85] offset:832
	global_load_dwordx4 v[184:187], v149, s[84:85] offset:832
	s_add_u32 s84, s84, 0x30000
	s_addc_u32 s85, s85, 0
	global_load_dwordx4 v[188:191], v235, s[84:85]
	global_load_dwordx4 v[192:195], v236, s[84:85]
	global_load_dwordx4 v[196:199], v237, s[84:85]
	global_load_dwordx4 v[200:203], v238, s[84:85]
	global_load_dwordx4 v[204:207], v100, s[84:85] offset:768
	global_load_dwordx4 v[208:211], v149, s[84:85] offset:768
	global_load_dwordx4 v[212:215], v100, s[84:85] offset:832
	global_load_dwordx4 v[216:219], v149, s[84:85] offset:832
	s_add_u32 s84, s84, 0x30000
	s_addc_u32 s85, s85, 0
	s_waitcnt vmcnt(16)
	ds_write_b128 v247, v[116:119]
	ds_write_b128 v247, v[120:123] offset:1024
	ds_write_b128 v247, v[124:127] offset:2048
	ds_write_b128 v247, v[128:131] offset:3072
	ds_read_b128 v[116:119], v248
	ds_read_b128 v[120:123], v249
	ds_read_b128 v[124:127], v250
	ds_read_b128 v[128:131], v251
	ds_write_b128 v112, v[132:135]
	ds_write_b128 v112, v[136:139] offset:1024
	ds_write_b128 v112, v[140:143] offset:2048
	ds_write_b128 v112, v[144:147] offset:3072
	v_mov_b32_e32 v115, v228
	ds_read2_b32 v[32:33], v115 offset0:0 offset1:1
	ds_read2_b32 v[34:35], v115 offset0:2 offset1:3
	ds_read2_b32 v[36:37], v115 offset0:8 offset1:9
	ds_read2_b32 v[38:39], v115 offset0:10 offset1:11
	ds_read2_b32 v[40:41], v115 offset0:17 offset1:18
	ds_read2_b32 v[42:43], v115 offset0:19 offset1:20
	ds_read2_b32 v[44:45], v115 offset0:25 offset1:26
	ds_read2_b32 v[46:47], v115 offset0:27 offset1:28
	s_waitcnt lgkmcnt(0)
	v_mfma_f32_32x32x16_bf16 v[32:47], v[116:119], v[48:51], v[32:47]
	ds_read_b64_tr_b16 v[72:73], v231
	ds_read_b64_tr_b16 v[74:75], v231 offset:512
	ds_read_b64_tr_b16 v[76:77], v231 offset:2048
	ds_read_b64_tr_b16 v[78:79], v231 offset:2560
	ds_read_b64_tr_b16 v[220:221], v231 offset:1024
	ds_read_b64_tr_b16 v[222:223], v231 offset:1536
	ds_read_b64_tr_b16 v[224:225], v231 offset:3072
	ds_read_b64_tr_b16 v[226:227], v231 offset:3584
	s_waitcnt vmcnt(8)
	ds_write_b128 v247, v[156:159]
	ds_write_b128 v247, v[160:163] offset:1024
	ds_write_b128 v247, v[164:167] offset:2048
	ds_write_b128 v247, v[168:171] offset:3072
	ds_read_b128 v[156:159], v248
	ds_read_b128 v[160:163], v249
	ds_read_b128 v[164:167], v250
	ds_read_b128 v[168:171], v251
	ds_write_b128 v112, v[172:175]
	ds_write_b128 v112, v[176:179] offset:1024
	ds_write_b128 v112, v[180:183] offset:2048
	ds_write_b128 v112, v[184:187] offset:3072
	v_mfma_f32_32x32x16_bf16 v[32:47], v[120:123], v[52:55], v[32:47]
	v_mfma_f32_32x32x16_bf16 v[32:47], v[124:127], v[56:59], v[32:47]
	v_mfma_f32_32x32x16_bf16 v[32:47], v[128:131], v[60:63], v[32:47]
	s_nop 11
	v_exp_f32_e32 v32, v32
	v_exp_f32_e32 v33, v33
	v_exp_f32_e32 v34, v34
	v_exp_f32_e32 v35, v35
	v_exp_f32_e32 v36, v36
	v_exp_f32_e32 v37, v37
	v_exp_f32_e32 v38, v38
	v_exp_f32_e32 v39, v39
	v_exp_f32_e32 v40, v40
	v_exp_f32_e32 v41, v41
	v_exp_f32_e32 v42, v42
	v_exp_f32_e32 v43, v43
	v_exp_f32_e32 v44, v44
	v_exp_f32_e32 v45, v45
	v_exp_f32_e32 v46, v46
	v_exp_f32_e32 v47, v47
	v_cvt_pk_bf16_f32 v64, v32, v33
	v_cvt_pk_bf16_f32 v65, v34, v35
	v_cvt_pk_bf16_f32 v66, v36, v37
	v_cvt_pk_bf16_f32 v67, v38, v39
	v_cvt_pk_bf16_f32 v68, v40, v41
	v_cvt_pk_bf16_f32 v69, v42, v43
	v_cvt_pk_bf16_f32 v70, v44, v45
	v_cvt_pk_bf16_f32 v71, v46, v47
	v_pk_add_f32 v[232:233], v[232:233], v[32:33]
	v_pk_add_f32 v[232:233], v[232:233], v[34:35]
	v_pk_add_f32 v[232:233], v[232:233], v[36:37]
	v_pk_add_f32 v[232:233], v[232:233], v[38:39]
	v_pk_add_f32 v[232:233], v[232:233], v[40:41]
	v_pk_add_f32 v[232:233], v[232:233], v[42:43]
	v_pk_add_f32 v[232:233], v[232:233], v[44:45]
	v_pk_add_f32 v[232:233], v[232:233], v[46:47]
	ds_read2_b32 v[32:33], v115 offset0:34 offset1:35
	ds_read2_b32 v[34:35], v115 offset0:36 offset1:37
	ds_read2_b32 v[36:37], v115 offset0:42 offset1:43
	ds_read2_b32 v[38:39], v115 offset0:44 offset1:45
	ds_read2_b32 v[40:41], v115 offset0:51 offset1:52
	ds_read2_b32 v[42:43], v115 offset0:53 offset1:54
	ds_read2_b32 v[44:45], v115 offset0:59 offset1:60
	ds_read2_b32 v[46:47], v115 offset0:61 offset1:62
	s_waitcnt lgkmcnt(15)
	v_mfma_f32_32x32x16_bf16 v[0:15], v[64:67], v[72:75], v[0:15]
	v_mfma_f32_32x32x16_bf16 v[16:31], v[64:67], v[76:79], v[16:31]
	v_mfma_f32_32x32x16_bf16 v[0:15], v[68:71], v[220:223], v[0:15]
	v_mfma_f32_32x32x16_bf16 v[16:31], v[68:71], v[224:227], v[16:31]
	global_load_dwordx4 v[116:119], v235, s[84:85]
	global_load_dwordx4 v[120:123], v236, s[84:85]
	global_load_dwordx4 v[124:127], v237, s[84:85]
	global_load_dwordx4 v[128:131], v238, s[84:85]
	global_load_dwordx4 v[132:135], v100, s[84:85] offset:768
	global_load_dwordx4 v[136:139], v149, s[84:85] offset:768
	global_load_dwordx4 v[140:143], v100, s[84:85] offset:832
	global_load_dwordx4 v[144:147], v149, s[84:85] offset:832
	s_add_u32 s84, s84, 0x30000
	s_addc_u32 s85, s85, 0
	s_waitcnt lgkmcnt(0)
	v_mfma_f32_32x32x16_bf16 v[32:47], v[156:159], v[48:51], v[32:47]
	ds_read_b64_tr_b16 v[72:73], v231
	ds_read_b64_tr_b16 v[74:75], v231 offset:512
	ds_read_b64_tr_b16 v[76:77], v231 offset:2048
	ds_read_b64_tr_b16 v[78:79], v231 offset:2560
	ds_read_b64_tr_b16 v[220:221], v231 offset:1024
	ds_read_b64_tr_b16 v[222:223], v231 offset:1536
	ds_read_b64_tr_b16 v[224:225], v231 offset:3072
	ds_read_b64_tr_b16 v[226:227], v231 offset:3584
	s_waitcnt vmcnt(8)
	ds_write_b128 v247, v[188:191]
	ds_write_b128 v247, v[192:195] offset:1024
	ds_write_b128 v247, v[196:199] offset:2048
	ds_write_b128 v247, v[200:203] offset:3072
	ds_read_b128 v[188:191], v248
	ds_read_b128 v[192:195], v249
	ds_read_b128 v[196:199], v250
	ds_read_b128 v[200:203], v251
	ds_write_b128 v112, v[204:207]
	ds_write_b128 v112, v[208:211] offset:1024
	ds_write_b128 v112, v[212:215] offset:2048
	ds_write_b128 v112, v[216:219] offset:3072
	v_mfma_f32_32x32x16_bf16 v[32:47], v[160:163], v[52:55], v[32:47]
	v_mfma_f32_32x32x16_bf16 v[32:47], v[164:167], v[56:59], v[32:47]
	v_mfma_f32_32x32x16_bf16 v[32:47], v[168:171], v[60:63], v[32:47]
	s_nop 11
	v_exp_f32_e32 v32, v32
	v_exp_f32_e32 v33, v33
	v_exp_f32_e32 v34, v34
	v_exp_f32_e32 v35, v35
	v_exp_f32_e32 v36, v36
	v_exp_f32_e32 v37, v37
	v_exp_f32_e32 v38, v38
	v_exp_f32_e32 v39, v39
	v_exp_f32_e32 v40, v40
	v_exp_f32_e32 v41, v41
	v_exp_f32_e32 v42, v42
	v_exp_f32_e32 v43, v43
	v_exp_f32_e32 v44, v44
	v_exp_f32_e32 v45, v45
	v_exp_f32_e32 v46, v46
	v_exp_f32_e32 v47, v47
	v_cvt_pk_bf16_f32 v64, v32, v33
	v_cvt_pk_bf16_f32 v65, v34, v35
	v_cvt_pk_bf16_f32 v66, v36, v37
	v_cvt_pk_bf16_f32 v67, v38, v39
	v_cvt_pk_bf16_f32 v68, v40, v41
	v_cvt_pk_bf16_f32 v69, v42, v43
	v_cvt_pk_bf16_f32 v70, v44, v45
	v_cvt_pk_bf16_f32 v71, v46, v47
	v_pk_add_f32 v[232:233], v[232:233], v[32:33]
	v_pk_add_f32 v[232:233], v[232:233], v[34:35]
	v_pk_add_f32 v[232:233], v[232:233], v[36:37]
	v_pk_add_f32 v[232:233], v[232:233], v[38:39]
	v_pk_add_f32 v[232:233], v[232:233], v[40:41]
	v_pk_add_f32 v[232:233], v[232:233], v[42:43]
	v_pk_add_f32 v[232:233], v[232:233], v[44:45]
	v_pk_add_f32 v[232:233], v[232:233], v[46:47]
	ds_read2_b32 v[32:33], v115 offset0:68 offset1:69
	ds_read2_b32 v[34:35], v115 offset0:70 offset1:71
	ds_read2_b32 v[36:37], v115 offset0:76 offset1:77
	ds_read2_b32 v[38:39], v115 offset0:78 offset1:79
	ds_read2_b32 v[40:41], v115 offset0:85 offset1:86
	ds_read2_b32 v[42:43], v115 offset0:87 offset1:88
	ds_read2_b32 v[44:45], v115 offset0:93 offset1:94
	ds_read2_b32 v[46:47], v115 offset0:95 offset1:96
	s_waitcnt lgkmcnt(15)
	v_mfma_f32_32x32x16_bf16 v[0:15], v[64:67], v[72:75], v[0:15]
	v_mfma_f32_32x32x16_bf16 v[16:31], v[64:67], v[76:79], v[16:31]
	v_mfma_f32_32x32x16_bf16 v[0:15], v[68:71], v[220:223], v[0:15]
	v_mfma_f32_32x32x16_bf16 v[16:31], v[68:71], v[224:227], v[16:31]
	global_load_dwordx4 v[156:159], v235, s[84:85]
	global_load_dwordx4 v[160:163], v236, s[84:85]
	global_load_dwordx4 v[164:167], v237, s[84:85]
	global_load_dwordx4 v[168:171], v238, s[84:85]
	global_load_dwordx4 v[172:175], v100, s[84:85] offset:768
	global_load_dwordx4 v[176:179], v149, s[84:85] offset:768
	global_load_dwordx4 v[180:183], v100, s[84:85] offset:832
	global_load_dwordx4 v[184:187], v149, s[84:85] offset:832
	s_add_u32 s84, s84, 0x30000
	s_addc_u32 s85, s85, 0
	s_waitcnt lgkmcnt(0)
	v_mfma_f32_32x32x16_bf16 v[32:47], v[188:191], v[48:51], v[32:47]
	ds_read_b64_tr_b16 v[72:73], v231
	ds_read_b64_tr_b16 v[74:75], v231 offset:512
	ds_read_b64_tr_b16 v[76:77], v231 offset:2048
	ds_read_b64_tr_b16 v[78:79], v231 offset:2560
	ds_read_b64_tr_b16 v[220:221], v231 offset:1024
	ds_read_b64_tr_b16 v[222:223], v231 offset:1536
	ds_read_b64_tr_b16 v[224:225], v231 offset:3072
	ds_read_b64_tr_b16 v[226:227], v231 offset:3584
	s_waitcnt vmcnt(8)
	ds_write_b128 v247, v[116:119]
	ds_write_b128 v247, v[120:123] offset:1024
	ds_write_b128 v247, v[124:127] offset:2048
	ds_write_b128 v247, v[128:131] offset:3072
	ds_read_b128 v[116:119], v248
	ds_read_b128 v[120:123], v249
	ds_read_b128 v[124:127], v250
	ds_read_b128 v[128:131], v251
	ds_write_b128 v112, v[132:135]
	ds_write_b128 v112, v[136:139] offset:1024
	ds_write_b128 v112, v[140:143] offset:2048
	ds_write_b128 v112, v[144:147] offset:3072
	v_mfma_f32_32x32x16_bf16 v[32:47], v[192:195], v[52:55], v[32:47]
	v_mfma_f32_32x32x16_bf16 v[32:47], v[196:199], v[56:59], v[32:47]
	v_mfma_f32_32x32x16_bf16 v[32:47], v[200:203], v[60:63], v[32:47]
	s_nop 11
	v_exp_f32_e32 v32, v32
	v_exp_f32_e32 v33, v33
	v_exp_f32_e32 v34, v34
	v_exp_f32_e32 v35, v35
	v_exp_f32_e32 v36, v36
	v_exp_f32_e32 v37, v37
	v_exp_f32_e32 v38, v38
	v_exp_f32_e32 v39, v39
	v_exp_f32_e32 v40, v40
	v_exp_f32_e32 v41, v41
	v_exp_f32_e32 v42, v42
	v_exp_f32_e32 v43, v43
	v_exp_f32_e32 v44, v44
	v_exp_f32_e32 v45, v45
	v_exp_f32_e32 v46, v46
	v_exp_f32_e32 v47, v47
	v_cvt_pk_bf16_f32 v64, v32, v33
	v_cvt_pk_bf16_f32 v65, v34, v35
	v_cvt_pk_bf16_f32 v66, v36, v37
	v_cvt_pk_bf16_f32 v67, v38, v39
	v_cvt_pk_bf16_f32 v68, v40, v41
	v_cvt_pk_bf16_f32 v69, v42, v43
	v_cvt_pk_bf16_f32 v70, v44, v45
	v_cvt_pk_bf16_f32 v71, v46, v47
	v_pk_add_f32 v[232:233], v[232:233], v[32:33]
	v_pk_add_f32 v[232:233], v[232:233], v[34:35]
	v_pk_add_f32 v[232:233], v[232:233], v[36:37]
	v_pk_add_f32 v[232:233], v[232:233], v[38:39]
	v_pk_add_f32 v[232:233], v[232:233], v[40:41]
	v_pk_add_f32 v[232:233], v[232:233], v[42:43]
	v_pk_add_f32 v[232:233], v[232:233], v[44:45]
	v_pk_add_f32 v[232:233], v[232:233], v[46:47]
	ds_read2_b32 v[32:33], v115 offset0:102 offset1:103
	ds_read2_b32 v[34:35], v115 offset0:104 offset1:105
	ds_read2_b32 v[36:37], v115 offset0:110 offset1:111
	ds_read2_b32 v[38:39], v115 offset0:112 offset1:113
	ds_read2_b32 v[40:41], v115 offset0:119 offset1:120
	ds_read2_b32 v[42:43], v115 offset0:121 offset1:122
	ds_read2_b32 v[44:45], v115 offset0:127 offset1:128
	ds_read2_b32 v[46:47], v115 offset0:129 offset1:130
	s_waitcnt lgkmcnt(15)
	v_mfma_f32_32x32x16_bf16 v[0:15], v[64:67], v[72:75], v[0:15]
	v_mfma_f32_32x32x16_bf16 v[16:31], v[64:67], v[76:79], v[16:31]
	v_mfma_f32_32x32x16_bf16 v[0:15], v[68:71], v[220:223], v[0:15]
	v_mfma_f32_32x32x16_bf16 v[16:31], v[68:71], v[224:227], v[16:31]
	global_load_dwordx4 v[188:191], v235, s[84:85]
	global_load_dwordx4 v[192:195], v236, s[84:85]
	global_load_dwordx4 v[196:199], v237, s[84:85]
	global_load_dwordx4 v[200:203], v238, s[84:85]
	global_load_dwordx4 v[204:207], v100, s[84:85] offset:768
	global_load_dwordx4 v[208:211], v149, s[84:85] offset:768
	global_load_dwordx4 v[212:215], v100, s[84:85] offset:832
	global_load_dwordx4 v[216:219], v149, s[84:85] offset:832
	s_add_u32 s84, s84, 0x30000
	s_addc_u32 s85, s85, 0
	s_waitcnt lgkmcnt(0)
	v_mfma_f32_32x32x16_bf16 v[32:47], v[116:119], v[48:51], v[32:47]
	ds_read_b64_tr_b16 v[72:73], v231
	ds_read_b64_tr_b16 v[74:75], v231 offset:512
	ds_read_b64_tr_b16 v[76:77], v231 offset:2048
	ds_read_b64_tr_b16 v[78:79], v231 offset:2560
	ds_read_b64_tr_b16 v[220:221], v231 offset:1024
	ds_read_b64_tr_b16 v[222:223], v231 offset:1536
	ds_read_b64_tr_b16 v[224:225], v231 offset:3072
	ds_read_b64_tr_b16 v[226:227], v231 offset:3584
	s_waitcnt vmcnt(8)
	ds_write_b128 v247, v[156:159]
	ds_write_b128 v247, v[160:163] offset:1024
	ds_write_b128 v247, v[164:167] offset:2048
	ds_write_b128 v247, v[168:171] offset:3072
	ds_read_b128 v[156:159], v248
	ds_read_b128 v[160:163], v249
	ds_read_b128 v[164:167], v250
	ds_read_b128 v[168:171], v251
	ds_write_b128 v112, v[172:175]
	ds_write_b128 v112, v[176:179] offset:1024
	ds_write_b128 v112, v[180:183] offset:2048
	ds_write_b128 v112, v[184:187] offset:3072
	v_mfma_f32_32x32x16_bf16 v[32:47], v[120:123], v[52:55], v[32:47]
	v_mfma_f32_32x32x16_bf16 v[32:47], v[124:127], v[56:59], v[32:47]
	v_mfma_f32_32x32x16_bf16 v[32:47], v[128:131], v[60:63], v[32:47]
	s_nop 11
	v_exp_f32_e32 v32, v32
	v_exp_f32_e32 v33, v33
	v_exp_f32_e32 v34, v34
	v_exp_f32_e32 v35, v35
	v_exp_f32_e32 v36, v36
	v_exp_f32_e32 v37, v37
	v_exp_f32_e32 v38, v38
	v_exp_f32_e32 v39, v39
	v_exp_f32_e32 v40, v40
	v_exp_f32_e32 v41, v41
	v_exp_f32_e32 v42, v42
	v_exp_f32_e32 v43, v43
	v_exp_f32_e32 v44, v44
	v_exp_f32_e32 v45, v45
	v_exp_f32_e32 v46, v46
	v_exp_f32_e32 v47, v47
	v_cvt_pk_bf16_f32 v64, v32, v33
	v_cvt_pk_bf16_f32 v65, v34, v35
	v_cvt_pk_bf16_f32 v66, v36, v37
	v_cvt_pk_bf16_f32 v67, v38, v39
	v_cvt_pk_bf16_f32 v68, v40, v41
	v_cvt_pk_bf16_f32 v69, v42, v43
	v_cvt_pk_bf16_f32 v70, v44, v45
	v_cvt_pk_bf16_f32 v71, v46, v47
	v_pk_add_f32 v[232:233], v[232:233], v[32:33]
	v_pk_add_f32 v[232:233], v[232:233], v[34:35]
	v_pk_add_f32 v[232:233], v[232:233], v[36:37]
	v_pk_add_f32 v[232:233], v[232:233], v[38:39]
	v_pk_add_f32 v[232:233], v[232:233], v[40:41]
	v_pk_add_f32 v[232:233], v[232:233], v[42:43]
	v_pk_add_f32 v[232:233], v[232:233], v[44:45]
	v_pk_add_f32 v[232:233], v[232:233], v[46:47]
	ds_read2_b32 v[32:33], v115 offset0:136 offset1:137
	ds_read2_b32 v[34:35], v115 offset0:138 offset1:139
	ds_read2_b32 v[36:37], v115 offset0:144 offset1:145
	ds_read2_b32 v[38:39], v115 offset0:146 offset1:147
	ds_read2_b32 v[40:41], v115 offset0:153 offset1:154
	ds_read2_b32 v[42:43], v115 offset0:155 offset1:156
	ds_read2_b32 v[44:45], v115 offset0:161 offset1:162
	ds_read2_b32 v[46:47], v115 offset0:163 offset1:164
	s_waitcnt lgkmcnt(15)
	v_mfma_f32_32x32x16_bf16 v[0:15], v[64:67], v[72:75], v[0:15]
	v_mfma_f32_32x32x16_bf16 v[16:31], v[64:67], v[76:79], v[16:31]
	v_mfma_f32_32x32x16_bf16 v[0:15], v[68:71], v[220:223], v[0:15]
	v_mfma_f32_32x32x16_bf16 v[16:31], v[68:71], v[224:227], v[16:31]
	global_load_dwordx4 v[116:119], v235, s[84:85]
	global_load_dwordx4 v[120:123], v236, s[84:85]
	global_load_dwordx4 v[124:127], v237, s[84:85]
	global_load_dwordx4 v[128:131], v238, s[84:85]
	global_load_dwordx4 v[132:135], v100, s[84:85] offset:768
	global_load_dwordx4 v[136:139], v149, s[84:85] offset:768
	global_load_dwordx4 v[140:143], v100, s[84:85] offset:832
	global_load_dwordx4 v[144:147], v149, s[84:85] offset:832
	s_add_u32 s84, s84, 0x30000
	s_addc_u32 s85, s85, 0
	s_waitcnt lgkmcnt(0)
	v_mfma_f32_32x32x16_bf16 v[32:47], v[156:159], v[48:51], v[32:47]
	ds_read_b64_tr_b16 v[72:73], v231
	ds_read_b64_tr_b16 v[74:75], v231 offset:512
	ds_read_b64_tr_b16 v[76:77], v231 offset:2048
	ds_read_b64_tr_b16 v[78:79], v231 offset:2560
	ds_read_b64_tr_b16 v[220:221], v231 offset:1024
	ds_read_b64_tr_b16 v[222:223], v231 offset:1536
	ds_read_b64_tr_b16 v[224:225], v231 offset:3072
	ds_read_b64_tr_b16 v[226:227], v231 offset:3584
	s_waitcnt vmcnt(8)
	ds_write_b128 v247, v[188:191]
	ds_write_b128 v247, v[192:195] offset:1024
	ds_write_b128 v247, v[196:199] offset:2048
	ds_write_b128 v247, v[200:203] offset:3072
	ds_read_b128 v[188:191], v248
	ds_read_b128 v[192:195], v249
	ds_read_b128 v[196:199], v250
	ds_read_b128 v[200:203], v251
	ds_write_b128 v112, v[204:207]
	ds_write_b128 v112, v[208:211] offset:1024
	ds_write_b128 v112, v[212:215] offset:2048
	ds_write_b128 v112, v[216:219] offset:3072
	v_mfma_f32_32x32x16_bf16 v[32:47], v[160:163], v[52:55], v[32:47]
	v_mfma_f32_32x32x16_bf16 v[32:47], v[164:167], v[56:59], v[32:47]
	v_mfma_f32_32x32x16_bf16 v[32:47], v[168:171], v[60:63], v[32:47]
	s_nop 11
	v_exp_f32_e32 v32, v32
	v_exp_f32_e32 v33, v33
	v_exp_f32_e32 v34, v34
	v_exp_f32_e32 v35, v35
	v_exp_f32_e32 v36, v36
	v_exp_f32_e32 v37, v37
	v_exp_f32_e32 v38, v38
	v_exp_f32_e32 v39, v39
	v_exp_f32_e32 v40, v40
	v_exp_f32_e32 v41, v41
	v_exp_f32_e32 v42, v42
	v_exp_f32_e32 v43, v43
	v_exp_f32_e32 v44, v44
	v_exp_f32_e32 v45, v45
	v_exp_f32_e32 v46, v46
	v_exp_f32_e32 v47, v47
	v_cvt_pk_bf16_f32 v64, v32, v33
	v_cvt_pk_bf16_f32 v65, v34, v35
	v_cvt_pk_bf16_f32 v66, v36, v37
	v_cvt_pk_bf16_f32 v67, v38, v39
	v_cvt_pk_bf16_f32 v68, v40, v41
	v_cvt_pk_bf16_f32 v69, v42, v43
	v_cvt_pk_bf16_f32 v70, v44, v45
	v_cvt_pk_bf16_f32 v71, v46, v47
	v_pk_add_f32 v[232:233], v[232:233], v[32:33]
	v_pk_add_f32 v[232:233], v[232:233], v[34:35]
	v_pk_add_f32 v[232:233], v[232:233], v[36:37]
	v_pk_add_f32 v[232:233], v[232:233], v[38:39]
	v_pk_add_f32 v[232:233], v[232:233], v[40:41]
	v_pk_add_f32 v[232:233], v[232:233], v[42:43]
	v_pk_add_f32 v[232:233], v[232:233], v[44:45]
	v_pk_add_f32 v[232:233], v[232:233], v[46:47]
	ds_read2_b32 v[32:33], v115 offset0:170 offset1:171
	ds_read2_b32 v[34:35], v115 offset0:172 offset1:173
	ds_read2_b32 v[36:37], v115 offset0:178 offset1:179
	ds_read2_b32 v[38:39], v115 offset0:180 offset1:181
	ds_read2_b32 v[40:41], v115 offset0:187 offset1:188
	ds_read2_b32 v[42:43], v115 offset0:189 offset1:190
	ds_read2_b32 v[44:45], v115 offset0:195 offset1:196
	ds_read2_b32 v[46:47], v115 offset0:197 offset1:198
	s_waitcnt lgkmcnt(15)
	v_mfma_f32_32x32x16_bf16 v[0:15], v[64:67], v[72:75], v[0:15]
	v_mfma_f32_32x32x16_bf16 v[16:31], v[64:67], v[76:79], v[16:31]
	v_mfma_f32_32x32x16_bf16 v[0:15], v[68:71], v[220:223], v[0:15]
	v_mfma_f32_32x32x16_bf16 v[16:31], v[68:71], v[224:227], v[16:31]
	global_load_dwordx4 v[156:159], v235, s[84:85]
	global_load_dwordx4 v[160:163], v236, s[84:85]
	global_load_dwordx4 v[164:167], v237, s[84:85]
	global_load_dwordx4 v[168:171], v238, s[84:85]
	global_load_dwordx4 v[172:175], v100, s[84:85] offset:768
	global_load_dwordx4 v[176:179], v149, s[84:85] offset:768
	global_load_dwordx4 v[180:183], v100, s[84:85] offset:832
	global_load_dwordx4 v[184:187], v149, s[84:85] offset:832
	s_add_u32 s84, s84, 0x30000
	s_addc_u32 s85, s85, 0
	s_waitcnt lgkmcnt(0)
	v_mfma_f32_32x32x16_bf16 v[32:47], v[188:191], v[48:51], v[32:47]
	ds_read_b64_tr_b16 v[72:73], v231
	ds_read_b64_tr_b16 v[74:75], v231 offset:512
	ds_read_b64_tr_b16 v[76:77], v231 offset:2048
	ds_read_b64_tr_b16 v[78:79], v231 offset:2560
	ds_read_b64_tr_b16 v[220:221], v231 offset:1024
	ds_read_b64_tr_b16 v[222:223], v231 offset:1536
	ds_read_b64_tr_b16 v[224:225], v231 offset:3072
	ds_read_b64_tr_b16 v[226:227], v231 offset:3584
	s_waitcnt vmcnt(8)
	ds_write_b128 v247, v[116:119]
	ds_write_b128 v247, v[120:123] offset:1024
	ds_write_b128 v247, v[124:127] offset:2048
	ds_write_b128 v247, v[128:131] offset:3072
	ds_read_b128 v[116:119], v248
	ds_read_b128 v[120:123], v249
	ds_read_b128 v[124:127], v250
	ds_read_b128 v[128:131], v251
	ds_write_b128 v112, v[132:135]
	ds_write_b128 v112, v[136:139] offset:1024
	ds_write_b128 v112, v[140:143] offset:2048
	ds_write_b128 v112, v[144:147] offset:3072
	v_mfma_f32_32x32x16_bf16 v[32:47], v[192:195], v[52:55], v[32:47]
	v_mfma_f32_32x32x16_bf16 v[32:47], v[196:199], v[56:59], v[32:47]
	v_mfma_f32_32x32x16_bf16 v[32:47], v[200:203], v[60:63], v[32:47]
	s_nop 11
	v_exp_f32_e32 v32, v32
	v_exp_f32_e32 v33, v33
	v_exp_f32_e32 v34, v34
	v_exp_f32_e32 v35, v35
	v_exp_f32_e32 v36, v36
	v_exp_f32_e32 v37, v37
	v_exp_f32_e32 v38, v38
	v_exp_f32_e32 v39, v39
	v_exp_f32_e32 v40, v40
	v_exp_f32_e32 v41, v41
	v_exp_f32_e32 v42, v42
	v_exp_f32_e32 v43, v43
	v_exp_f32_e32 v44, v44
	v_exp_f32_e32 v45, v45
	v_exp_f32_e32 v46, v46
	v_exp_f32_e32 v47, v47
	v_cvt_pk_bf16_f32 v64, v32, v33
	v_cvt_pk_bf16_f32 v65, v34, v35
	v_cvt_pk_bf16_f32 v66, v36, v37
	v_cvt_pk_bf16_f32 v67, v38, v39
	v_cvt_pk_bf16_f32 v68, v40, v41
	v_cvt_pk_bf16_f32 v69, v42, v43
	v_cvt_pk_bf16_f32 v70, v44, v45
	v_cvt_pk_bf16_f32 v71, v46, v47
	v_pk_add_f32 v[232:233], v[232:233], v[32:33]
	v_pk_add_f32 v[232:233], v[232:233], v[34:35]
	v_pk_add_f32 v[232:233], v[232:233], v[36:37]
	v_pk_add_f32 v[232:233], v[232:233], v[38:39]
	v_pk_add_f32 v[232:233], v[232:233], v[40:41]
	v_pk_add_f32 v[232:233], v[232:233], v[42:43]
	v_pk_add_f32 v[232:233], v[232:233], v[44:45]
	v_pk_add_f32 v[232:233], v[232:233], v[46:47]
	ds_read2_b32 v[32:33], v115 offset0:204 offset1:205
	ds_read2_b32 v[34:35], v115 offset0:206 offset1:207
	ds_read2_b32 v[36:37], v115 offset0:212 offset1:213
	ds_read2_b32 v[38:39], v115 offset0:214 offset1:215
	ds_read2_b32 v[40:41], v115 offset0:221 offset1:222
	ds_read2_b32 v[42:43], v115 offset0:223 offset1:224
	ds_read2_b32 v[44:45], v115 offset0:229 offset1:230
	ds_read2_b32 v[46:47], v115 offset0:231 offset1:232
	s_waitcnt lgkmcnt(15)
	v_mfma_f32_32x32x16_bf16 v[0:15], v[64:67], v[72:75], v[0:15]
	v_mfma_f32_32x32x16_bf16 v[16:31], v[64:67], v[76:79], v[16:31]
	v_mfma_f32_32x32x16_bf16 v[0:15], v[68:71], v[220:223], v[0:15]
	v_mfma_f32_32x32x16_bf16 v[16:31], v[68:71], v[224:227], v[16:31]
	global_load_dwordx4 v[188:191], v235, s[84:85]
	global_load_dwordx4 v[192:195], v236, s[84:85]
	global_load_dwordx4 v[196:199], v237, s[84:85]
	global_load_dwordx4 v[200:203], v238, s[84:85]
	global_load_dwordx4 v[204:207], v100, s[84:85] offset:768
	global_load_dwordx4 v[208:211], v149, s[84:85] offset:768
	global_load_dwordx4 v[212:215], v100, s[84:85] offset:832
	global_load_dwordx4 v[216:219], v149, s[84:85] offset:832
	s_add_u32 s84, s84, 0x30000
	s_addc_u32 s85, s85, 0
	s_waitcnt lgkmcnt(0)
	v_mfma_f32_32x32x16_bf16 v[32:47], v[116:119], v[48:51], v[32:47]
	ds_read_b64_tr_b16 v[72:73], v231
	ds_read_b64_tr_b16 v[74:75], v231 offset:512
	ds_read_b64_tr_b16 v[76:77], v231 offset:2048
	ds_read_b64_tr_b16 v[78:79], v231 offset:2560
	ds_read_b64_tr_b16 v[220:221], v231 offset:1024
	ds_read_b64_tr_b16 v[222:223], v231 offset:1536
	ds_read_b64_tr_b16 v[224:225], v231 offset:3072
	ds_read_b64_tr_b16 v[226:227], v231 offset:3584
	s_waitcnt vmcnt(8)
	ds_write_b128 v247, v[156:159]
	ds_write_b128 v247, v[160:163] offset:1024
	ds_write_b128 v247, v[164:167] offset:2048
	ds_write_b128 v247, v[168:171] offset:3072
	ds_read_b128 v[156:159], v248
	ds_read_b128 v[160:163], v249
	ds_read_b128 v[164:167], v250
	ds_read_b128 v[168:171], v251
	ds_write_b128 v112, v[172:175]
	ds_write_b128 v112, v[176:179] offset:1024
	ds_write_b128 v112, v[180:183] offset:2048
	ds_write_b128 v112, v[184:187] offset:3072
	v_mfma_f32_32x32x16_bf16 v[32:47], v[120:123], v[52:55], v[32:47]
	v_mfma_f32_32x32x16_bf16 v[32:47], v[124:127], v[56:59], v[32:47]
	v_mfma_f32_32x32x16_bf16 v[32:47], v[128:131], v[60:63], v[32:47]
	s_nop 11
	v_exp_f32_e32 v32, v32
	v_exp_f32_e32 v33, v33
	v_exp_f32_e32 v34, v34
	v_exp_f32_e32 v35, v35
	v_exp_f32_e32 v36, v36
	v_exp_f32_e32 v37, v37
	v_exp_f32_e32 v38, v38
	v_exp_f32_e32 v39, v39
	v_exp_f32_e32 v40, v40
	v_exp_f32_e32 v41, v41
	v_exp_f32_e32 v42, v42
	v_exp_f32_e32 v43, v43
	v_exp_f32_e32 v44, v44
	v_exp_f32_e32 v45, v45
	v_exp_f32_e32 v46, v46
	v_exp_f32_e32 v47, v47
	v_cvt_pk_bf16_f32 v64, v32, v33
	v_cvt_pk_bf16_f32 v65, v34, v35
	v_cvt_pk_bf16_f32 v66, v36, v37
	v_cvt_pk_bf16_f32 v67, v38, v39
	v_cvt_pk_bf16_f32 v68, v40, v41
	v_cvt_pk_bf16_f32 v69, v42, v43
	v_cvt_pk_bf16_f32 v70, v44, v45
	v_cvt_pk_bf16_f32 v71, v46, v47
	v_pk_add_f32 v[232:233], v[232:233], v[32:33]
	v_pk_add_f32 v[232:233], v[232:233], v[34:35]
	v_pk_add_f32 v[232:233], v[232:233], v[36:37]
	v_pk_add_f32 v[232:233], v[232:233], v[38:39]
	v_pk_add_f32 v[232:233], v[232:233], v[40:41]
	v_pk_add_f32 v[232:233], v[232:233], v[42:43]
	v_pk_add_f32 v[232:233], v[232:233], v[44:45]
	v_pk_add_f32 v[232:233], v[232:233], v[46:47]
	v_add_u32_e32 v115, 952, v115
	ds_read2_b32 v[32:33], v115 offset0:0 offset1:1
	ds_read2_b32 v[34:35], v115 offset0:2 offset1:3
	ds_read2_b32 v[36:37], v115 offset0:8 offset1:9
	ds_read2_b32 v[38:39], v115 offset0:10 offset1:11
	ds_read2_b32 v[40:41], v115 offset0:17 offset1:18
	ds_read2_b32 v[42:43], v115 offset0:19 offset1:20
	ds_read2_b32 v[44:45], v115 offset0:25 offset1:26
	ds_read2_b32 v[46:47], v115 offset0:27 offset1:28
	s_waitcnt lgkmcnt(15)
	v_mfma_f32_32x32x16_bf16 v[0:15], v[64:67], v[72:75], v[0:15]
	v_mfma_f32_32x32x16_bf16 v[16:31], v[64:67], v[76:79], v[16:31]
	v_mfma_f32_32x32x16_bf16 v[0:15], v[68:71], v[220:223], v[0:15]
	v_mfma_f32_32x32x16_bf16 v[16:31], v[68:71], v[224:227], v[16:31]
	global_load_dwordx4 v[116:119], v235, s[84:85]
	global_load_dwordx4 v[120:123], v236, s[84:85]
	global_load_dwordx4 v[124:127], v237, s[84:85]
	global_load_dwordx4 v[128:131], v238, s[84:85]
	global_load_dwordx4 v[132:135], v100, s[84:85] offset:768
	global_load_dwordx4 v[136:139], v149, s[84:85] offset:768
	global_load_dwordx4 v[140:143], v100, s[84:85] offset:832
	global_load_dwordx4 v[144:147], v149, s[84:85] offset:832
	s_add_u32 s84, s84, 0x30000
	s_addc_u32 s85, s85, 0
	s_waitcnt lgkmcnt(0)
	v_mfma_f32_32x32x16_bf16 v[32:47], v[156:159], v[48:51], v[32:47]
	ds_read_b64_tr_b16 v[72:73], v231
	ds_read_b64_tr_b16 v[74:75], v231 offset:512
	ds_read_b64_tr_b16 v[76:77], v231 offset:2048
	ds_read_b64_tr_b16 v[78:79], v231 offset:2560
	ds_read_b64_tr_b16 v[220:221], v231 offset:1024
	ds_read_b64_tr_b16 v[222:223], v231 offset:1536
	ds_read_b64_tr_b16 v[224:225], v231 offset:3072
	ds_read_b64_tr_b16 v[226:227], v231 offset:3584
	s_waitcnt vmcnt(8)
	ds_write_b128 v247, v[188:191]
	ds_write_b128 v247, v[192:195] offset:1024
	ds_write_b128 v247, v[196:199] offset:2048
	ds_write_b128 v247, v[200:203] offset:3072
	ds_read_b128 v[188:191], v248
	ds_read_b128 v[192:195], v249
	ds_read_b128 v[196:199], v250
	ds_read_b128 v[200:203], v251
	ds_write_b128 v112, v[204:207]
	ds_write_b128 v112, v[208:211] offset:1024
	ds_write_b128 v112, v[212:215] offset:2048
	ds_write_b128 v112, v[216:219] offset:3072
	v_mfma_f32_32x32x16_bf16 v[32:47], v[160:163], v[52:55], v[32:47]
	v_mfma_f32_32x32x16_bf16 v[32:47], v[164:167], v[56:59], v[32:47]
	v_mfma_f32_32x32x16_bf16 v[32:47], v[168:171], v[60:63], v[32:47]
	s_nop 11
	v_exp_f32_e32 v32, v32
	v_exp_f32_e32 v33, v33
	v_exp_f32_e32 v34, v34
	v_exp_f32_e32 v35, v35
	v_exp_f32_e32 v36, v36
	v_exp_f32_e32 v37, v37
	v_exp_f32_e32 v38, v38
	v_exp_f32_e32 v39, v39
	v_exp_f32_e32 v40, v40
	v_exp_f32_e32 v41, v41
	v_exp_f32_e32 v42, v42
	v_exp_f32_e32 v43, v43
	v_exp_f32_e32 v44, v44
	v_exp_f32_e32 v45, v45
	v_exp_f32_e32 v46, v46
	v_exp_f32_e32 v47, v47
	v_cvt_pk_bf16_f32 v64, v32, v33
	v_cvt_pk_bf16_f32 v65, v34, v35
	v_cvt_pk_bf16_f32 v66, v36, v37
	v_cvt_pk_bf16_f32 v67, v38, v39
	v_cvt_pk_bf16_f32 v68, v40, v41
	v_cvt_pk_bf16_f32 v69, v42, v43
	v_cvt_pk_bf16_f32 v70, v44, v45
	v_cvt_pk_bf16_f32 v71, v46, v47
	v_pk_add_f32 v[232:233], v[232:233], v[32:33]
	v_pk_add_f32 v[232:233], v[232:233], v[34:35]
	v_pk_add_f32 v[232:233], v[232:233], v[36:37]
	v_pk_add_f32 v[232:233], v[232:233], v[38:39]
	v_pk_add_f32 v[232:233], v[232:233], v[40:41]
	v_pk_add_f32 v[232:233], v[232:233], v[42:43]
	v_pk_add_f32 v[232:233], v[232:233], v[44:45]
	v_pk_add_f32 v[232:233], v[232:233], v[46:47]
	ds_read2_b32 v[32:33], v115 offset0:34 offset1:35
	ds_read2_b32 v[34:35], v115 offset0:36 offset1:37
	ds_read2_b32 v[36:37], v115 offset0:42 offset1:43
	ds_read2_b32 v[38:39], v115 offset0:44 offset1:45
	ds_read2_b32 v[40:41], v115 offset0:51 offset1:52
	ds_read2_b32 v[42:43], v115 offset0:53 offset1:54
	ds_read2_b32 v[44:45], v115 offset0:59 offset1:60
	ds_read2_b32 v[46:47], v115 offset0:61 offset1:62
	s_waitcnt lgkmcnt(15)
	v_mfma_f32_32x32x16_bf16 v[0:15], v[64:67], v[72:75], v[0:15]
	v_mfma_f32_32x32x16_bf16 v[16:31], v[64:67], v[76:79], v[16:31]
	v_mfma_f32_32x32x16_bf16 v[0:15], v[68:71], v[220:223], v[0:15]
	v_mfma_f32_32x32x16_bf16 v[16:31], v[68:71], v[224:227], v[16:31]
	global_load_dwordx4 v[156:159], v235, s[84:85]
	global_load_dwordx4 v[160:163], v236, s[84:85]
	global_load_dwordx4 v[164:167], v237, s[84:85]
	global_load_dwordx4 v[168:171], v238, s[84:85]
	global_load_dwordx4 v[172:175], v100, s[84:85] offset:768
	global_load_dwordx4 v[176:179], v149, s[84:85] offset:768
	global_load_dwordx4 v[180:183], v100, s[84:85] offset:832
	global_load_dwordx4 v[184:187], v149, s[84:85] offset:832
	s_add_u32 s84, s84, 0x30000
	s_addc_u32 s85, s85, 0
	s_waitcnt lgkmcnt(0)
	v_mfma_f32_32x32x16_bf16 v[32:47], v[188:191], v[48:51], v[32:47]
	ds_read_b64_tr_b16 v[72:73], v231
	ds_read_b64_tr_b16 v[74:75], v231 offset:512
	ds_read_b64_tr_b16 v[76:77], v231 offset:2048
	ds_read_b64_tr_b16 v[78:79], v231 offset:2560
	ds_read_b64_tr_b16 v[220:221], v231 offset:1024
	ds_read_b64_tr_b16 v[222:223], v231 offset:1536
	ds_read_b64_tr_b16 v[224:225], v231 offset:3072
	ds_read_b64_tr_b16 v[226:227], v231 offset:3584
	s_waitcnt vmcnt(8)
	ds_write_b128 v247, v[116:119]
	ds_write_b128 v247, v[120:123] offset:1024
	ds_write_b128 v247, v[124:127] offset:2048
	ds_write_b128 v247, v[128:131] offset:3072
	ds_read_b128 v[116:119], v248
	ds_read_b128 v[120:123], v249
	ds_read_b128 v[124:127], v250
	ds_read_b128 v[128:131], v251
	ds_write_b128 v112, v[132:135]
	ds_write_b128 v112, v[136:139] offset:1024
	ds_write_b128 v112, v[140:143] offset:2048
	ds_write_b128 v112, v[144:147] offset:3072
	v_mfma_f32_32x32x16_bf16 v[32:47], v[192:195], v[52:55], v[32:47]
	v_mfma_f32_32x32x16_bf16 v[32:47], v[196:199], v[56:59], v[32:47]
	v_mfma_f32_32x32x16_bf16 v[32:47], v[200:203], v[60:63], v[32:47]
	s_nop 11
	v_exp_f32_e32 v32, v32
	v_exp_f32_e32 v33, v33
	v_exp_f32_e32 v34, v34
	v_exp_f32_e32 v35, v35
	v_exp_f32_e32 v36, v36
	v_exp_f32_e32 v37, v37
	v_exp_f32_e32 v38, v38
	v_exp_f32_e32 v39, v39
	v_exp_f32_e32 v40, v40
	v_exp_f32_e32 v41, v41
	v_exp_f32_e32 v42, v42
	v_exp_f32_e32 v43, v43
	v_exp_f32_e32 v44, v44
	v_exp_f32_e32 v45, v45
	v_exp_f32_e32 v46, v46
	v_exp_f32_e32 v47, v47
	v_cvt_pk_bf16_f32 v64, v32, v33
	v_cvt_pk_bf16_f32 v65, v34, v35
	v_cvt_pk_bf16_f32 v66, v36, v37
	v_cvt_pk_bf16_f32 v67, v38, v39
	v_cvt_pk_bf16_f32 v68, v40, v41
	v_cvt_pk_bf16_f32 v69, v42, v43
	v_cvt_pk_bf16_f32 v70, v44, v45
	v_cvt_pk_bf16_f32 v71, v46, v47
	v_pk_add_f32 v[232:233], v[232:233], v[32:33]
	v_pk_add_f32 v[232:233], v[232:233], v[34:35]
	v_pk_add_f32 v[232:233], v[232:233], v[36:37]
	v_pk_add_f32 v[232:233], v[232:233], v[38:39]
	v_pk_add_f32 v[232:233], v[232:233], v[40:41]
	v_pk_add_f32 v[232:233], v[232:233], v[42:43]
	v_pk_add_f32 v[232:233], v[232:233], v[44:45]
	v_pk_add_f32 v[232:233], v[232:233], v[46:47]
	ds_read2_b32 v[32:33], v115 offset0:68 offset1:69
	ds_read2_b32 v[34:35], v115 offset0:70 offset1:71
	ds_read2_b32 v[36:37], v115 offset0:76 offset1:77
	ds_read2_b32 v[38:39], v115 offset0:78 offset1:79
	ds_read2_b32 v[40:41], v115 offset0:85 offset1:86
	ds_read2_b32 v[42:43], v115 offset0:87 offset1:88
	ds_read2_b32 v[44:45], v115 offset0:93 offset1:94
	ds_read2_b32 v[46:47], v115 offset0:95 offset1:96
	s_waitcnt lgkmcnt(15)
	v_mfma_f32_32x32x16_bf16 v[0:15], v[64:67], v[72:75], v[0:15]
	v_mfma_f32_32x32x16_bf16 v[16:31], v[64:67], v[76:79], v[16:31]
	v_mfma_f32_32x32x16_bf16 v[0:15], v[68:71], v[220:223], v[0:15]
	v_mfma_f32_32x32x16_bf16 v[16:31], v[68:71], v[224:227], v[16:31]
	global_load_dwordx4 v[188:191], v235, s[84:85]
	global_load_dwordx4 v[192:195], v236, s[84:85]
	global_load_dwordx4 v[196:199], v237, s[84:85]
	global_load_dwordx4 v[200:203], v238, s[84:85]
	global_load_dwordx4 v[204:207], v100, s[84:85] offset:768
	global_load_dwordx4 v[208:211], v149, s[84:85] offset:768
	global_load_dwordx4 v[212:215], v100, s[84:85] offset:832
	global_load_dwordx4 v[216:219], v149, s[84:85] offset:832
	s_add_u32 s84, s84, 0x30000
	s_addc_u32 s85, s85, 0
	s_waitcnt lgkmcnt(0)
	v_mfma_f32_32x32x16_bf16 v[32:47], v[116:119], v[48:51], v[32:47]
	ds_read_b64_tr_b16 v[72:73], v231
	ds_read_b64_tr_b16 v[74:75], v231 offset:512
	ds_read_b64_tr_b16 v[76:77], v231 offset:2048
	ds_read_b64_tr_b16 v[78:79], v231 offset:2560
	ds_read_b64_tr_b16 v[220:221], v231 offset:1024
	ds_read_b64_tr_b16 v[222:223], v231 offset:1536
	ds_read_b64_tr_b16 v[224:225], v231 offset:3072
	ds_read_b64_tr_b16 v[226:227], v231 offset:3584
	s_waitcnt vmcnt(8)
	ds_write_b128 v247, v[156:159]
	ds_write_b128 v247, v[160:163] offset:1024
	ds_write_b128 v247, v[164:167] offset:2048
	ds_write_b128 v247, v[168:171] offset:3072
	ds_read_b128 v[156:159], v248
	ds_read_b128 v[160:163], v249
	ds_read_b128 v[164:167], v250
	ds_read_b128 v[168:171], v251
	ds_write_b128 v112, v[172:175]
	ds_write_b128 v112, v[176:179] offset:1024
	ds_write_b128 v112, v[180:183] offset:2048
	ds_write_b128 v112, v[184:187] offset:3072
	v_mfma_f32_32x32x16_bf16 v[32:47], v[120:123], v[52:55], v[32:47]
	v_mfma_f32_32x32x16_bf16 v[32:47], v[124:127], v[56:59], v[32:47]
	v_mfma_f32_32x32x16_bf16 v[32:47], v[128:131], v[60:63], v[32:47]
	s_nop 11
	v_exp_f32_e32 v32, v32
	v_exp_f32_e32 v33, v33
	v_exp_f32_e32 v34, v34
	v_exp_f32_e32 v35, v35
	v_exp_f32_e32 v36, v36
	v_exp_f32_e32 v37, v37
	v_exp_f32_e32 v38, v38
	v_exp_f32_e32 v39, v39
	v_exp_f32_e32 v40, v40
	v_exp_f32_e32 v41, v41
	v_exp_f32_e32 v42, v42
	v_exp_f32_e32 v43, v43
	v_exp_f32_e32 v44, v44
	v_exp_f32_e32 v45, v45
	v_exp_f32_e32 v46, v46
	v_exp_f32_e32 v47, v47
	v_cvt_pk_bf16_f32 v64, v32, v33
	v_cvt_pk_bf16_f32 v65, v34, v35
	v_cvt_pk_bf16_f32 v66, v36, v37
	v_cvt_pk_bf16_f32 v67, v38, v39
	v_cvt_pk_bf16_f32 v68, v40, v41
	v_cvt_pk_bf16_f32 v69, v42, v43
	v_cvt_pk_bf16_f32 v70, v44, v45
	v_cvt_pk_bf16_f32 v71, v46, v47
	v_pk_add_f32 v[232:233], v[232:233], v[32:33]
	v_pk_add_f32 v[232:233], v[232:233], v[34:35]
	v_pk_add_f32 v[232:233], v[232:233], v[36:37]
	v_pk_add_f32 v[232:233], v[232:233], v[38:39]
	v_pk_add_f32 v[232:233], v[232:233], v[40:41]
	v_pk_add_f32 v[232:233], v[232:233], v[42:43]
	v_pk_add_f32 v[232:233], v[232:233], v[44:45]
	v_pk_add_f32 v[232:233], v[232:233], v[46:47]
	ds_read2_b32 v[32:33], v115 offset0:102 offset1:103
	ds_read2_b32 v[34:35], v115 offset0:104 offset1:105
	ds_read2_b32 v[36:37], v115 offset0:110 offset1:111
	ds_read2_b32 v[38:39], v115 offset0:112 offset1:113
	ds_read2_b32 v[40:41], v115 offset0:119 offset1:120
	ds_read2_b32 v[42:43], v115 offset0:121 offset1:122
	ds_read2_b32 v[44:45], v115 offset0:127 offset1:128
	ds_read2_b32 v[46:47], v115 offset0:129 offset1:130
	s_waitcnt lgkmcnt(15)
	v_mfma_f32_32x32x16_bf16 v[0:15], v[64:67], v[72:75], v[0:15]
	v_mfma_f32_32x32x16_bf16 v[16:31], v[64:67], v[76:79], v[16:31]
	v_mfma_f32_32x32x16_bf16 v[0:15], v[68:71], v[220:223], v[0:15]
	v_mfma_f32_32x32x16_bf16 v[16:31], v[68:71], v[224:227], v[16:31]
	global_load_dwordx4 v[116:119], v235, s[84:85]
	global_load_dwordx4 v[120:123], v236, s[84:85]
	global_load_dwordx4 v[124:127], v237, s[84:85]
	global_load_dwordx4 v[128:131], v238, s[84:85]
	global_load_dwordx4 v[132:135], v100, s[84:85] offset:768
	global_load_dwordx4 v[136:139], v149, s[84:85] offset:768
	global_load_dwordx4 v[140:143], v100, s[84:85] offset:832
	global_load_dwordx4 v[144:147], v149, s[84:85] offset:832
	s_add_u32 s84, s84, 0x30000
	s_addc_u32 s85, s85, 0
	s_waitcnt lgkmcnt(0)
	v_mfma_f32_32x32x16_bf16 v[32:47], v[156:159], v[48:51], v[32:47]
	ds_read_b64_tr_b16 v[72:73], v231
	ds_read_b64_tr_b16 v[74:75], v231 offset:512
	ds_read_b64_tr_b16 v[76:77], v231 offset:2048
	ds_read_b64_tr_b16 v[78:79], v231 offset:2560
	ds_read_b64_tr_b16 v[220:221], v231 offset:1024
	ds_read_b64_tr_b16 v[222:223], v231 offset:1536
	ds_read_b64_tr_b16 v[224:225], v231 offset:3072
	ds_read_b64_tr_b16 v[226:227], v231 offset:3584
	s_waitcnt vmcnt(8)
	ds_write_b128 v247, v[188:191]
	ds_write_b128 v247, v[192:195] offset:1024
	ds_write_b128 v247, v[196:199] offset:2048
	ds_write_b128 v247, v[200:203] offset:3072
	ds_read_b128 v[188:191], v248
	ds_read_b128 v[192:195], v249
	ds_read_b128 v[196:199], v250
	ds_read_b128 v[200:203], v251
	ds_write_b128 v112, v[204:207]
	ds_write_b128 v112, v[208:211] offset:1024
	ds_write_b128 v112, v[212:215] offset:2048
	ds_write_b128 v112, v[216:219] offset:3072
	v_mfma_f32_32x32x16_bf16 v[32:47], v[160:163], v[52:55], v[32:47]
	v_mfma_f32_32x32x16_bf16 v[32:47], v[164:167], v[56:59], v[32:47]
	v_mfma_f32_32x32x16_bf16 v[32:47], v[168:171], v[60:63], v[32:47]
	s_nop 11
	v_exp_f32_e32 v32, v32
	v_exp_f32_e32 v33, v33
	v_exp_f32_e32 v34, v34
	v_exp_f32_e32 v35, v35
	v_exp_f32_e32 v36, v36
	v_exp_f32_e32 v37, v37
	v_exp_f32_e32 v38, v38
	v_exp_f32_e32 v39, v39
	v_exp_f32_e32 v40, v40
	v_exp_f32_e32 v41, v41
	v_exp_f32_e32 v42, v42
	v_exp_f32_e32 v43, v43
	v_exp_f32_e32 v44, v44
	v_exp_f32_e32 v45, v45
	v_exp_f32_e32 v46, v46
	v_exp_f32_e32 v47, v47
	v_cvt_pk_bf16_f32 v64, v32, v33
	v_cvt_pk_bf16_f32 v65, v34, v35
	v_cvt_pk_bf16_f32 v66, v36, v37
	v_cvt_pk_bf16_f32 v67, v38, v39
	v_cvt_pk_bf16_f32 v68, v40, v41
	v_cvt_pk_bf16_f32 v69, v42, v43
	v_cvt_pk_bf16_f32 v70, v44, v45
	v_cvt_pk_bf16_f32 v71, v46, v47
	v_pk_add_f32 v[232:233], v[232:233], v[32:33]
	v_pk_add_f32 v[232:233], v[232:233], v[34:35]
	v_pk_add_f32 v[232:233], v[232:233], v[36:37]
	v_pk_add_f32 v[232:233], v[232:233], v[38:39]
	v_pk_add_f32 v[232:233], v[232:233], v[40:41]
	v_pk_add_f32 v[232:233], v[232:233], v[42:43]
	v_pk_add_f32 v[232:233], v[232:233], v[44:45]
	v_pk_add_f32 v[232:233], v[232:233], v[46:47]
	ds_read2_b32 v[32:33], v115 offset0:136 offset1:137
	ds_read2_b32 v[34:35], v115 offset0:138 offset1:139
	ds_read2_b32 v[36:37], v115 offset0:144 offset1:145
	ds_read2_b32 v[38:39], v115 offset0:146 offset1:147
	ds_read2_b32 v[40:41], v115 offset0:153 offset1:154
	ds_read2_b32 v[42:43], v115 offset0:155 offset1:156
	ds_read2_b32 v[44:45], v115 offset0:161 offset1:162
	ds_read2_b32 v[46:47], v115 offset0:163 offset1:164
	s_waitcnt lgkmcnt(15)
	v_mfma_f32_32x32x16_bf16 v[0:15], v[64:67], v[72:75], v[0:15]
	v_mfma_f32_32x32x16_bf16 v[16:31], v[64:67], v[76:79], v[16:31]
	v_mfma_f32_32x32x16_bf16 v[0:15], v[68:71], v[220:223], v[0:15]
	v_mfma_f32_32x32x16_bf16 v[16:31], v[68:71], v[224:227], v[16:31]
	global_load_dwordx4 v[156:159], v235, s[84:85]
	global_load_dwordx4 v[160:163], v236, s[84:85]
	global_load_dwordx4 v[164:167], v237, s[84:85]
	global_load_dwordx4 v[168:171], v238, s[84:85]
	global_load_dwordx4 v[172:175], v100, s[84:85] offset:768
	global_load_dwordx4 v[176:179], v149, s[84:85] offset:768
	global_load_dwordx4 v[180:183], v100, s[84:85] offset:832
	global_load_dwordx4 v[184:187], v149, s[84:85] offset:832
	s_add_u32 s84, s84, 0x30000
	s_addc_u32 s85, s85, 0
	s_waitcnt lgkmcnt(0)
	v_mfma_f32_32x32x16_bf16 v[32:47], v[188:191], v[48:51], v[32:47]
	ds_read_b64_tr_b16 v[72:73], v231
	ds_read_b64_tr_b16 v[74:75], v231 offset:512
	ds_read_b64_tr_b16 v[76:77], v231 offset:2048
	ds_read_b64_tr_b16 v[78:79], v231 offset:2560
	ds_read_b64_tr_b16 v[220:221], v231 offset:1024
	ds_read_b64_tr_b16 v[222:223], v231 offset:1536
	ds_read_b64_tr_b16 v[224:225], v231 offset:3072
	ds_read_b64_tr_b16 v[226:227], v231 offset:3584
	s_waitcnt vmcnt(8)
	ds_write_b128 v247, v[116:119]
	ds_write_b128 v247, v[120:123] offset:1024
	ds_write_b128 v247, v[124:127] offset:2048
	ds_write_b128 v247, v[128:131] offset:3072
	ds_read_b128 v[116:119], v248
	ds_read_b128 v[120:123], v249
	ds_read_b128 v[124:127], v250
	ds_read_b128 v[128:131], v251
	ds_write_b128 v112, v[132:135]
	ds_write_b128 v112, v[136:139] offset:1024
	ds_write_b128 v112, v[140:143] offset:2048
	ds_write_b128 v112, v[144:147] offset:3072
	v_mfma_f32_32x32x16_bf16 v[32:47], v[192:195], v[52:55], v[32:47]
	v_mfma_f32_32x32x16_bf16 v[32:47], v[196:199], v[56:59], v[32:47]
	v_mfma_f32_32x32x16_bf16 v[32:47], v[200:203], v[60:63], v[32:47]
	s_nop 11
	v_exp_f32_e32 v32, v32
	v_exp_f32_e32 v33, v33
	v_exp_f32_e32 v34, v34
	v_exp_f32_e32 v35, v35
	v_exp_f32_e32 v36, v36
	v_exp_f32_e32 v37, v37
	v_exp_f32_e32 v38, v38
	v_exp_f32_e32 v39, v39
	v_exp_f32_e32 v40, v40
	v_exp_f32_e32 v41, v41
	v_exp_f32_e32 v42, v42
	v_exp_f32_e32 v43, v43
	v_exp_f32_e32 v44, v44
	v_exp_f32_e32 v45, v45
	v_exp_f32_e32 v46, v46
	v_exp_f32_e32 v47, v47
	v_cvt_pk_bf16_f32 v64, v32, v33
	v_cvt_pk_bf16_f32 v65, v34, v35
	v_cvt_pk_bf16_f32 v66, v36, v37
	v_cvt_pk_bf16_f32 v67, v38, v39
	v_cvt_pk_bf16_f32 v68, v40, v41
	v_cvt_pk_bf16_f32 v69, v42, v43
	v_cvt_pk_bf16_f32 v70, v44, v45
	v_cvt_pk_bf16_f32 v71, v46, v47
	v_pk_add_f32 v[232:233], v[232:233], v[32:33]
	v_pk_add_f32 v[232:233], v[232:233], v[34:35]
	v_pk_add_f32 v[232:233], v[232:233], v[36:37]
	v_pk_add_f32 v[232:233], v[232:233], v[38:39]
	v_pk_add_f32 v[232:233], v[232:233], v[40:41]
	v_pk_add_f32 v[232:233], v[232:233], v[42:43]
	v_pk_add_f32 v[232:233], v[232:233], v[44:45]
	v_pk_add_f32 v[232:233], v[232:233], v[46:47]
	ds_read2_b32 v[32:33], v115 offset0:170 offset1:171
	ds_read2_b32 v[34:35], v115 offset0:172 offset1:173
	ds_read2_b32 v[36:37], v115 offset0:178 offset1:179
	ds_read2_b32 v[38:39], v115 offset0:180 offset1:181
	ds_read2_b32 v[40:41], v115 offset0:187 offset1:188
	ds_read2_b32 v[42:43], v115 offset0:189 offset1:190
	ds_read2_b32 v[44:45], v115 offset0:195 offset1:196
	ds_read2_b32 v[46:47], v115 offset0:197 offset1:198
	s_waitcnt lgkmcnt(15)
	v_mfma_f32_32x32x16_bf16 v[0:15], v[64:67], v[72:75], v[0:15]
	v_mfma_f32_32x32x16_bf16 v[16:31], v[64:67], v[76:79], v[16:31]
	v_mfma_f32_32x32x16_bf16 v[0:15], v[68:71], v[220:223], v[0:15]
	v_mfma_f32_32x32x16_bf16 v[16:31], v[68:71], v[224:227], v[16:31]
	global_load_dwordx4 v[188:191], v235, s[84:85]
	global_load_dwordx4 v[192:195], v236, s[84:85]
	global_load_dwordx4 v[196:199], v237, s[84:85]
	global_load_dwordx4 v[200:203], v238, s[84:85]
	global_load_dwordx4 v[204:207], v100, s[84:85] offset:768
	global_load_dwordx4 v[208:211], v149, s[84:85] offset:768
	global_load_dwordx4 v[212:215], v100, s[84:85] offset:832
	global_load_dwordx4 v[216:219], v149, s[84:85] offset:832
	s_add_u32 s84, s84, 0x30000
	s_addc_u32 s85, s85, 0
	s_waitcnt lgkmcnt(0)
	v_mfma_f32_32x32x16_bf16 v[32:47], v[116:119], v[48:51], v[32:47]
	ds_read_b64_tr_b16 v[72:73], v231
	ds_read_b64_tr_b16 v[74:75], v231 offset:512
	ds_read_b64_tr_b16 v[76:77], v231 offset:2048
	ds_read_b64_tr_b16 v[78:79], v231 offset:2560
	ds_read_b64_tr_b16 v[220:221], v231 offset:1024
	ds_read_b64_tr_b16 v[222:223], v231 offset:1536
	ds_read_b64_tr_b16 v[224:225], v231 offset:3072
	ds_read_b64_tr_b16 v[226:227], v231 offset:3584
	s_waitcnt vmcnt(8)
	ds_write_b128 v247, v[156:159]
	ds_write_b128 v247, v[160:163] offset:1024
	ds_write_b128 v247, v[164:167] offset:2048
	ds_write_b128 v247, v[168:171] offset:3072
	ds_read_b128 v[156:159], v248
	ds_read_b128 v[160:163], v249
	ds_read_b128 v[164:167], v250
	ds_read_b128 v[168:171], v251
	ds_write_b128 v112, v[172:175]
	ds_write_b128 v112, v[176:179] offset:1024
	ds_write_b128 v112, v[180:183] offset:2048
	ds_write_b128 v112, v[184:187] offset:3072
	v_mfma_f32_32x32x16_bf16 v[32:47], v[120:123], v[52:55], v[32:47]
	v_mfma_f32_32x32x16_bf16 v[32:47], v[124:127], v[56:59], v[32:47]
	v_mfma_f32_32x32x16_bf16 v[32:47], v[128:131], v[60:63], v[32:47]
	s_nop 11
	v_exp_f32_e32 v32, v32
	v_exp_f32_e32 v33, v33
	v_exp_f32_e32 v34, v34
	v_exp_f32_e32 v35, v35
	v_exp_f32_e32 v36, v36
	v_exp_f32_e32 v37, v37
	v_exp_f32_e32 v38, v38
	v_exp_f32_e32 v39, v39
	v_exp_f32_e32 v40, v40
	v_exp_f32_e32 v41, v41
	v_exp_f32_e32 v42, v42
	v_exp_f32_e32 v43, v43
	v_exp_f32_e32 v44, v44
	v_exp_f32_e32 v45, v45
	v_exp_f32_e32 v46, v46
	v_exp_f32_e32 v47, v47
	v_cvt_pk_bf16_f32 v64, v32, v33
	v_cvt_pk_bf16_f32 v65, v34, v35
	v_cvt_pk_bf16_f32 v66, v36, v37
	v_cvt_pk_bf16_f32 v67, v38, v39
	v_cvt_pk_bf16_f32 v68, v40, v41
	v_cvt_pk_bf16_f32 v69, v42, v43
	v_cvt_pk_bf16_f32 v70, v44, v45
	v_cvt_pk_bf16_f32 v71, v46, v47
	v_pk_add_f32 v[232:233], v[232:233], v[32:33]
	v_pk_add_f32 v[232:233], v[232:233], v[34:35]
	v_pk_add_f32 v[232:233], v[232:233], v[36:37]
	v_pk_add_f32 v[232:233], v[232:233], v[38:39]
	v_pk_add_f32 v[232:233], v[232:233], v[40:41]
	v_pk_add_f32 v[232:233], v[232:233], v[42:43]
	v_pk_add_f32 v[232:233], v[232:233], v[44:45]
	v_pk_add_f32 v[232:233], v[232:233], v[46:47]
	ds_read2_b32 v[32:33], v115 offset0:204 offset1:205
	ds_read2_b32 v[34:35], v115 offset0:206 offset1:207
	ds_read2_b32 v[36:37], v115 offset0:212 offset1:213
	ds_read2_b32 v[38:39], v115 offset0:214 offset1:215
	ds_read2_b32 v[40:41], v115 offset0:221 offset1:222
	ds_read2_b32 v[42:43], v115 offset0:223 offset1:224
	ds_read2_b32 v[44:45], v115 offset0:229 offset1:230
	ds_read2_b32 v[46:47], v115 offset0:231 offset1:232
	s_waitcnt lgkmcnt(15)
	v_mfma_f32_32x32x16_bf16 v[0:15], v[64:67], v[72:75], v[0:15]
	v_mfma_f32_32x32x16_bf16 v[16:31], v[64:67], v[76:79], v[16:31]
	v_mfma_f32_32x32x16_bf16 v[0:15], v[68:71], v[220:223], v[0:15]
	v_mfma_f32_32x32x16_bf16 v[16:31], v[68:71], v[224:227], v[16:31]
	global_load_dwordx4 v[116:119], v235, s[84:85]
	global_load_dwordx4 v[120:123], v236, s[84:85]
	global_load_dwordx4 v[124:127], v237, s[84:85]
	global_load_dwordx4 v[128:131], v238, s[84:85]
	global_load_dwordx4 v[132:135], v100, s[84:85] offset:768
	global_load_dwordx4 v[136:139], v149, s[84:85] offset:768
	global_load_dwordx4 v[140:143], v100, s[84:85] offset:832
	global_load_dwordx4 v[144:147], v149, s[84:85] offset:832
	s_add_u32 s84, s84, 0x30000
	s_addc_u32 s85, s85, 0
	s_waitcnt lgkmcnt(0)
	v_mfma_f32_32x32x16_bf16 v[32:47], v[156:159], v[48:51], v[32:47]
	ds_read_b64_tr_b16 v[72:73], v231
	ds_read_b64_tr_b16 v[74:75], v231 offset:512
	ds_read_b64_tr_b16 v[76:77], v231 offset:2048
	ds_read_b64_tr_b16 v[78:79], v231 offset:2560
	ds_read_b64_tr_b16 v[220:221], v231 offset:1024
	ds_read_b64_tr_b16 v[222:223], v231 offset:1536
	ds_read_b64_tr_b16 v[224:225], v231 offset:3072
	ds_read_b64_tr_b16 v[226:227], v231 offset:3584
	s_waitcnt vmcnt(8)
	ds_write_b128 v247, v[188:191]
	ds_write_b128 v247, v[192:195] offset:1024
	ds_write_b128 v247, v[196:199] offset:2048
	ds_write_b128 v247, v[200:203] offset:3072
	ds_read_b128 v[188:191], v248
	ds_read_b128 v[192:195], v249
	ds_read_b128 v[196:199], v250
	ds_read_b128 v[200:203], v251
	ds_write_b128 v112, v[204:207]
	ds_write_b128 v112, v[208:211] offset:1024
	ds_write_b128 v112, v[212:215] offset:2048
	ds_write_b128 v112, v[216:219] offset:3072
	v_mfma_f32_32x32x16_bf16 v[32:47], v[160:163], v[52:55], v[32:47]
	v_mfma_f32_32x32x16_bf16 v[32:47], v[164:167], v[56:59], v[32:47]
	v_mfma_f32_32x32x16_bf16 v[32:47], v[168:171], v[60:63], v[32:47]
	s_nop 11
	v_exp_f32_e32 v32, v32
	v_exp_f32_e32 v33, v33
	v_exp_f32_e32 v34, v34
	v_exp_f32_e32 v35, v35
	v_exp_f32_e32 v36, v36
	v_exp_f32_e32 v37, v37
	v_exp_f32_e32 v38, v38
	v_exp_f32_e32 v39, v39
	v_exp_f32_e32 v40, v40
	v_exp_f32_e32 v41, v41
	v_exp_f32_e32 v42, v42
	v_exp_f32_e32 v43, v43
	v_exp_f32_e32 v44, v44
	v_exp_f32_e32 v45, v45
	v_exp_f32_e32 v46, v46
	v_exp_f32_e32 v47, v47
	v_cvt_pk_bf16_f32 v64, v32, v33
	v_cvt_pk_bf16_f32 v65, v34, v35
	v_cvt_pk_bf16_f32 v66, v36, v37
	v_cvt_pk_bf16_f32 v67, v38, v39
	v_cvt_pk_bf16_f32 v68, v40, v41
	v_cvt_pk_bf16_f32 v69, v42, v43
	v_cvt_pk_bf16_f32 v70, v44, v45
	v_cvt_pk_bf16_f32 v71, v46, v47
	v_pk_add_f32 v[232:233], v[232:233], v[32:33]
	v_pk_add_f32 v[232:233], v[232:233], v[34:35]
	v_pk_add_f32 v[232:233], v[232:233], v[36:37]
	v_pk_add_f32 v[232:233], v[232:233], v[38:39]
	v_pk_add_f32 v[232:233], v[232:233], v[40:41]
	v_pk_add_f32 v[232:233], v[232:233], v[42:43]
	v_pk_add_f32 v[232:233], v[232:233], v[44:45]
	v_pk_add_f32 v[232:233], v[232:233], v[46:47]
	v_add_u32_e32 v115, 952, v115
	ds_read2_b32 v[32:33], v115 offset0:0 offset1:1
	ds_read2_b32 v[34:35], v115 offset0:2 offset1:3
	ds_read2_b32 v[36:37], v115 offset0:8 offset1:9
	ds_read2_b32 v[38:39], v115 offset0:10 offset1:11
	ds_read2_b32 v[40:41], v115 offset0:17 offset1:18
	ds_read2_b32 v[42:43], v115 offset0:19 offset1:20
	ds_read2_b32 v[44:45], v115 offset0:25 offset1:26
	ds_read2_b32 v[46:47], v115 offset0:27 offset1:28
	s_waitcnt lgkmcnt(15)
	v_mfma_f32_32x32x16_bf16 v[0:15], v[64:67], v[72:75], v[0:15]
	v_mfma_f32_32x32x16_bf16 v[16:31], v[64:67], v[76:79], v[16:31]
	v_mfma_f32_32x32x16_bf16 v[0:15], v[68:71], v[220:223], v[0:15]
	v_mfma_f32_32x32x16_bf16 v[16:31], v[68:71], v[224:227], v[16:31]
	global_load_dwordx4 v[156:159], v235, s[84:85]
	global_load_dwordx4 v[160:163], v236, s[84:85]
	global_load_dwordx4 v[164:167], v237, s[84:85]
	global_load_dwordx4 v[168:171], v238, s[84:85]
	global_load_dwordx4 v[172:175], v100, s[84:85] offset:768
	global_load_dwordx4 v[176:179], v149, s[84:85] offset:768
	global_load_dwordx4 v[180:183], v100, s[84:85] offset:832
	global_load_dwordx4 v[184:187], v149, s[84:85] offset:832
	s_add_u32 s84, s84, 0x30000
	s_addc_u32 s85, s85, 0
	s_waitcnt lgkmcnt(0)
	v_mfma_f32_32x32x16_bf16 v[32:47], v[188:191], v[48:51], v[32:47]
	ds_read_b64_tr_b16 v[72:73], v231
	ds_read_b64_tr_b16 v[74:75], v231 offset:512
	ds_read_b64_tr_b16 v[76:77], v231 offset:2048
	ds_read_b64_tr_b16 v[78:79], v231 offset:2560
	ds_read_b64_tr_b16 v[220:221], v231 offset:1024
	ds_read_b64_tr_b16 v[222:223], v231 offset:1536
	ds_read_b64_tr_b16 v[224:225], v231 offset:3072
	ds_read_b64_tr_b16 v[226:227], v231 offset:3584
	s_waitcnt vmcnt(8)
	ds_write_b128 v247, v[116:119]
	ds_write_b128 v247, v[120:123] offset:1024
	ds_write_b128 v247, v[124:127] offset:2048
	ds_write_b128 v247, v[128:131] offset:3072
	ds_read_b128 v[116:119], v248
	ds_read_b128 v[120:123], v249
	ds_read_b128 v[124:127], v250
	ds_read_b128 v[128:131], v251
	ds_write_b128 v112, v[132:135]
	ds_write_b128 v112, v[136:139] offset:1024
	ds_write_b128 v112, v[140:143] offset:2048
	ds_write_b128 v112, v[144:147] offset:3072
	v_mfma_f32_32x32x16_bf16 v[32:47], v[192:195], v[52:55], v[32:47]
	v_mfma_f32_32x32x16_bf16 v[32:47], v[196:199], v[56:59], v[32:47]
	v_mfma_f32_32x32x16_bf16 v[32:47], v[200:203], v[60:63], v[32:47]
	s_nop 11
	v_exp_f32_e32 v32, v32
	v_exp_f32_e32 v33, v33
	v_exp_f32_e32 v34, v34
	v_exp_f32_e32 v35, v35
	v_exp_f32_e32 v36, v36
	v_exp_f32_e32 v37, v37
	v_exp_f32_e32 v38, v38
	v_exp_f32_e32 v39, v39
	v_exp_f32_e32 v40, v40
	v_exp_f32_e32 v41, v41
	v_exp_f32_e32 v42, v42
	v_exp_f32_e32 v43, v43
	v_exp_f32_e32 v44, v44
	v_exp_f32_e32 v45, v45
	v_exp_f32_e32 v46, v46
	v_exp_f32_e32 v47, v47
	v_cvt_pk_bf16_f32 v64, v32, v33
	v_cvt_pk_bf16_f32 v65, v34, v35
	v_cvt_pk_bf16_f32 v66, v36, v37
	v_cvt_pk_bf16_f32 v67, v38, v39
	v_cvt_pk_bf16_f32 v68, v40, v41
	v_cvt_pk_bf16_f32 v69, v42, v43
	v_cvt_pk_bf16_f32 v70, v44, v45
	v_cvt_pk_bf16_f32 v71, v46, v47
	v_pk_add_f32 v[232:233], v[232:233], v[32:33]
	v_pk_add_f32 v[232:233], v[232:233], v[34:35]
	v_pk_add_f32 v[232:233], v[232:233], v[36:37]
	v_pk_add_f32 v[232:233], v[232:233], v[38:39]
	v_pk_add_f32 v[232:233], v[232:233], v[40:41]
	v_pk_add_f32 v[232:233], v[232:233], v[42:43]
	v_pk_add_f32 v[232:233], v[232:233], v[44:45]
	v_pk_add_f32 v[232:233], v[232:233], v[46:47]
	ds_read2_b32 v[32:33], v115 offset0:34 offset1:35
	ds_read2_b32 v[34:35], v115 offset0:36 offset1:37
	ds_read2_b32 v[36:37], v115 offset0:42 offset1:43
	ds_read2_b32 v[38:39], v115 offset0:44 offset1:45
	ds_read2_b32 v[40:41], v115 offset0:51 offset1:52
	ds_read2_b32 v[42:43], v115 offset0:53 offset1:54
	ds_read2_b32 v[44:45], v115 offset0:59 offset1:60
	ds_read2_b32 v[46:47], v115 offset0:61 offset1:62
	s_waitcnt lgkmcnt(15)
	v_mfma_f32_32x32x16_bf16 v[0:15], v[64:67], v[72:75], v[0:15]
	v_mfma_f32_32x32x16_bf16 v[16:31], v[64:67], v[76:79], v[16:31]
	v_mfma_f32_32x32x16_bf16 v[0:15], v[68:71], v[220:223], v[0:15]
	v_mfma_f32_32x32x16_bf16 v[16:31], v[68:71], v[224:227], v[16:31]
	global_load_dwordx4 v[188:191], v235, s[84:85]
	global_load_dwordx4 v[192:195], v236, s[84:85]
	global_load_dwordx4 v[196:199], v237, s[84:85]
	global_load_dwordx4 v[200:203], v238, s[84:85]
	global_load_dwordx4 v[204:207], v100, s[84:85] offset:768
	global_load_dwordx4 v[208:211], v149, s[84:85] offset:768
	global_load_dwordx4 v[212:215], v100, s[84:85] offset:832
	global_load_dwordx4 v[216:219], v149, s[84:85] offset:832
	s_add_u32 s84, s84, 0x30000
	s_addc_u32 s85, s85, 0
	s_waitcnt lgkmcnt(0)
	v_mfma_f32_32x32x16_bf16 v[32:47], v[116:119], v[48:51], v[32:47]
	ds_read_b64_tr_b16 v[72:73], v231
	ds_read_b64_tr_b16 v[74:75], v231 offset:512
	ds_read_b64_tr_b16 v[76:77], v231 offset:2048
	ds_read_b64_tr_b16 v[78:79], v231 offset:2560
	ds_read_b64_tr_b16 v[220:221], v231 offset:1024
	ds_read_b64_tr_b16 v[222:223], v231 offset:1536
	ds_read_b64_tr_b16 v[224:225], v231 offset:3072
	ds_read_b64_tr_b16 v[226:227], v231 offset:3584
	s_waitcnt vmcnt(8)
	ds_write_b128 v247, v[156:159]
	ds_write_b128 v247, v[160:163] offset:1024
	ds_write_b128 v247, v[164:167] offset:2048
	ds_write_b128 v247, v[168:171] offset:3072
	ds_read_b128 v[156:159], v248
	ds_read_b128 v[160:163], v249
	ds_read_b128 v[164:167], v250
	ds_read_b128 v[168:171], v251
	ds_write_b128 v112, v[172:175]
	ds_write_b128 v112, v[176:179] offset:1024
	ds_write_b128 v112, v[180:183] offset:2048
	ds_write_b128 v112, v[184:187] offset:3072
	v_mfma_f32_32x32x16_bf16 v[32:47], v[120:123], v[52:55], v[32:47]
	v_mfma_f32_32x32x16_bf16 v[32:47], v[124:127], v[56:59], v[32:47]
	v_mfma_f32_32x32x16_bf16 v[32:47], v[128:131], v[60:63], v[32:47]
	s_nop 11
	v_exp_f32_e32 v32, v32
	v_exp_f32_e32 v33, v33
	v_exp_f32_e32 v34, v34
	v_exp_f32_e32 v35, v35
	v_exp_f32_e32 v36, v36
	v_exp_f32_e32 v37, v37
	v_exp_f32_e32 v38, v38
	v_exp_f32_e32 v39, v39
	v_exp_f32_e32 v40, v40
	v_exp_f32_e32 v41, v41
	v_exp_f32_e32 v42, v42
	v_exp_f32_e32 v43, v43
	v_exp_f32_e32 v44, v44
	v_exp_f32_e32 v45, v45
	v_exp_f32_e32 v46, v46
	v_exp_f32_e32 v47, v47
	v_cvt_pk_bf16_f32 v64, v32, v33
	v_cvt_pk_bf16_f32 v65, v34, v35
	v_cvt_pk_bf16_f32 v66, v36, v37
	v_cvt_pk_bf16_f32 v67, v38, v39
	v_cvt_pk_bf16_f32 v68, v40, v41
	v_cvt_pk_bf16_f32 v69, v42, v43
	v_cvt_pk_bf16_f32 v70, v44, v45
	v_cvt_pk_bf16_f32 v71, v46, v47
	v_pk_add_f32 v[232:233], v[232:233], v[32:33]
	v_pk_add_f32 v[232:233], v[232:233], v[34:35]
	v_pk_add_f32 v[232:233], v[232:233], v[36:37]
	v_pk_add_f32 v[232:233], v[232:233], v[38:39]
	v_pk_add_f32 v[232:233], v[232:233], v[40:41]
	v_pk_add_f32 v[232:233], v[232:233], v[42:43]
	v_pk_add_f32 v[232:233], v[232:233], v[44:45]
	v_pk_add_f32 v[232:233], v[232:233], v[46:47]
	ds_read2_b32 v[32:33], v115 offset0:68 offset1:69
	ds_read2_b32 v[34:35], v115 offset0:70 offset1:71
	ds_read2_b32 v[36:37], v115 offset0:76 offset1:77
	ds_read2_b32 v[38:39], v115 offset0:78 offset1:79
	ds_read2_b32 v[40:41], v115 offset0:85 offset1:86
	ds_read2_b32 v[42:43], v115 offset0:87 offset1:88
	ds_read2_b32 v[44:45], v115 offset0:93 offset1:94
	ds_read2_b32 v[46:47], v115 offset0:95 offset1:96
	s_waitcnt lgkmcnt(15)
	v_mfma_f32_32x32x16_bf16 v[0:15], v[64:67], v[72:75], v[0:15]
	v_mfma_f32_32x32x16_bf16 v[16:31], v[64:67], v[76:79], v[16:31]
	v_mfma_f32_32x32x16_bf16 v[0:15], v[68:71], v[220:223], v[0:15]
	v_mfma_f32_32x32x16_bf16 v[16:31], v[68:71], v[224:227], v[16:31]
	global_load_dwordx4 v[116:119], v235, s[84:85]
	global_load_dwordx4 v[120:123], v236, s[84:85]
	global_load_dwordx4 v[124:127], v237, s[84:85]
	global_load_dwordx4 v[128:131], v238, s[84:85]
	global_load_dwordx4 v[132:135], v100, s[84:85] offset:768
	global_load_dwordx4 v[136:139], v149, s[84:85] offset:768
	global_load_dwordx4 v[140:143], v100, s[84:85] offset:832
	global_load_dwordx4 v[144:147], v149, s[84:85] offset:832
	s_add_u32 s84, s84, 0x30000
	s_addc_u32 s85, s85, 0
	s_waitcnt lgkmcnt(0)
	v_mfma_f32_32x32x16_bf16 v[32:47], v[156:159], v[48:51], v[32:47]
	ds_read_b64_tr_b16 v[72:73], v231
	ds_read_b64_tr_b16 v[74:75], v231 offset:512
	ds_read_b64_tr_b16 v[76:77], v231 offset:2048
	ds_read_b64_tr_b16 v[78:79], v231 offset:2560
	ds_read_b64_tr_b16 v[220:221], v231 offset:1024
	ds_read_b64_tr_b16 v[222:223], v231 offset:1536
	ds_read_b64_tr_b16 v[224:225], v231 offset:3072
	ds_read_b64_tr_b16 v[226:227], v231 offset:3584
	s_waitcnt vmcnt(8)
	ds_write_b128 v247, v[188:191]
	ds_write_b128 v247, v[192:195] offset:1024
	ds_write_b128 v247, v[196:199] offset:2048
	ds_write_b128 v247, v[200:203] offset:3072
	ds_read_b128 v[188:191], v248
	ds_read_b128 v[192:195], v249
	ds_read_b128 v[196:199], v250
	ds_read_b128 v[200:203], v251
	ds_write_b128 v112, v[204:207]
	ds_write_b128 v112, v[208:211] offset:1024
	ds_write_b128 v112, v[212:215] offset:2048
	ds_write_b128 v112, v[216:219] offset:3072
	v_mfma_f32_32x32x16_bf16 v[32:47], v[160:163], v[52:55], v[32:47]
	v_mfma_f32_32x32x16_bf16 v[32:47], v[164:167], v[56:59], v[32:47]
	v_mfma_f32_32x32x16_bf16 v[32:47], v[168:171], v[60:63], v[32:47]
	s_nop 11
	v_exp_f32_e32 v32, v32
	v_exp_f32_e32 v33, v33
	v_exp_f32_e32 v34, v34
	v_exp_f32_e32 v35, v35
	v_exp_f32_e32 v36, v36
	v_exp_f32_e32 v37, v37
	v_exp_f32_e32 v38, v38
	v_exp_f32_e32 v39, v39
	v_exp_f32_e32 v40, v40
	v_exp_f32_e32 v41, v41
	v_exp_f32_e32 v42, v42
	v_exp_f32_e32 v43, v43
	v_exp_f32_e32 v44, v44
	v_exp_f32_e32 v45, v45
	v_exp_f32_e32 v46, v46
	v_exp_f32_e32 v47, v47
	v_cvt_pk_bf16_f32 v64, v32, v33
	v_cvt_pk_bf16_f32 v65, v34, v35
	v_cvt_pk_bf16_f32 v66, v36, v37
	v_cvt_pk_bf16_f32 v67, v38, v39
	v_cvt_pk_bf16_f32 v68, v40, v41
	v_cvt_pk_bf16_f32 v69, v42, v43
	v_cvt_pk_bf16_f32 v70, v44, v45
	v_cvt_pk_bf16_f32 v71, v46, v47
	v_pk_add_f32 v[232:233], v[232:233], v[32:33]
	v_pk_add_f32 v[232:233], v[232:233], v[34:35]
	v_pk_add_f32 v[232:233], v[232:233], v[36:37]
	v_pk_add_f32 v[232:233], v[232:233], v[38:39]
	v_pk_add_f32 v[232:233], v[232:233], v[40:41]
	v_pk_add_f32 v[232:233], v[232:233], v[42:43]
	v_pk_add_f32 v[232:233], v[232:233], v[44:45]
	v_pk_add_f32 v[232:233], v[232:233], v[46:47]
	ds_read2_b32 v[32:33], v115 offset0:102 offset1:103
	ds_read2_b32 v[34:35], v115 offset0:104 offset1:105
	ds_read2_b32 v[36:37], v115 offset0:110 offset1:111
	ds_read2_b32 v[38:39], v115 offset0:112 offset1:113
	ds_read2_b32 v[40:41], v115 offset0:119 offset1:120
	ds_read2_b32 v[42:43], v115 offset0:121 offset1:122
	ds_read2_b32 v[44:45], v115 offset0:127 offset1:128
	ds_read2_b32 v[46:47], v115 offset0:129 offset1:130
	s_waitcnt lgkmcnt(15)
	v_mfma_f32_32x32x16_bf16 v[0:15], v[64:67], v[72:75], v[0:15]
	v_mfma_f32_32x32x16_bf16 v[16:31], v[64:67], v[76:79], v[16:31]
	v_mfma_f32_32x32x16_bf16 v[0:15], v[68:71], v[220:223], v[0:15]
	v_mfma_f32_32x32x16_bf16 v[16:31], v[68:71], v[224:227], v[16:31]
	global_load_dwordx4 v[156:159], v235, s[84:85]
	global_load_dwordx4 v[160:163], v236, s[84:85]
	global_load_dwordx4 v[164:167], v237, s[84:85]
	global_load_dwordx4 v[168:171], v238, s[84:85]
	global_load_dwordx4 v[172:175], v100, s[84:85] offset:768
	global_load_dwordx4 v[176:179], v149, s[84:85] offset:768
	global_load_dwordx4 v[180:183], v100, s[84:85] offset:832
	global_load_dwordx4 v[184:187], v149, s[84:85] offset:832
	s_waitcnt lgkmcnt(0)
	v_mfma_f32_32x32x16_bf16 v[32:47], v[188:191], v[48:51], v[32:47]
	ds_read_b64_tr_b16 v[72:73], v231
	ds_read_b64_tr_b16 v[74:75], v231 offset:512
	ds_read_b64_tr_b16 v[76:77], v231 offset:2048
	ds_read_b64_tr_b16 v[78:79], v231 offset:2560
	ds_read_b64_tr_b16 v[220:221], v231 offset:1024
	ds_read_b64_tr_b16 v[222:223], v231 offset:1536
	ds_read_b64_tr_b16 v[224:225], v231 offset:3072
	ds_read_b64_tr_b16 v[226:227], v231 offset:3584
	s_waitcnt vmcnt(8)
	ds_write_b128 v247, v[116:119]
	ds_write_b128 v247, v[120:123] offset:1024
	ds_write_b128 v247, v[124:127] offset:2048
	ds_write_b128 v247, v[128:131] offset:3072
	ds_read_b128 v[116:119], v248
	ds_read_b128 v[120:123], v249
	ds_read_b128 v[124:127], v250
	ds_read_b128 v[128:131], v251
	ds_write_b128 v112, v[132:135]
	ds_write_b128 v112, v[136:139] offset:1024
	ds_write_b128 v112, v[140:143] offset:2048
	ds_write_b128 v112, v[144:147] offset:3072
	v_mfma_f32_32x32x16_bf16 v[32:47], v[192:195], v[52:55], v[32:47]
	v_mfma_f32_32x32x16_bf16 v[32:47], v[196:199], v[56:59], v[32:47]
	v_mfma_f32_32x32x16_bf16 v[32:47], v[200:203], v[60:63], v[32:47]
	s_nop 11
	v_exp_f32_e32 v32, v32
	v_exp_f32_e32 v33, v33
	v_exp_f32_e32 v34, v34
	v_exp_f32_e32 v35, v35
	v_exp_f32_e32 v36, v36
	v_exp_f32_e32 v37, v37
	v_exp_f32_e32 v38, v38
	v_exp_f32_e32 v39, v39
	v_exp_f32_e32 v40, v40
	v_exp_f32_e32 v41, v41
	v_exp_f32_e32 v42, v42
	v_exp_f32_e32 v43, v43
	v_exp_f32_e32 v44, v44
	v_exp_f32_e32 v45, v45
	v_exp_f32_e32 v46, v46
	v_exp_f32_e32 v47, v47
	v_cvt_pk_bf16_f32 v64, v32, v33
	v_cvt_pk_bf16_f32 v65, v34, v35
	v_cvt_pk_bf16_f32 v66, v36, v37
	v_cvt_pk_bf16_f32 v67, v38, v39
	v_cvt_pk_bf16_f32 v68, v40, v41
	v_cvt_pk_bf16_f32 v69, v42, v43
	v_cvt_pk_bf16_f32 v70, v44, v45
	v_cvt_pk_bf16_f32 v71, v46, v47
	v_pk_add_f32 v[232:233], v[232:233], v[32:33]
	v_pk_add_f32 v[232:233], v[232:233], v[34:35]
	v_pk_add_f32 v[232:233], v[232:233], v[36:37]
	v_pk_add_f32 v[232:233], v[232:233], v[38:39]
	v_pk_add_f32 v[232:233], v[232:233], v[40:41]
	v_pk_add_f32 v[232:233], v[232:233], v[42:43]
	v_pk_add_f32 v[232:233], v[232:233], v[44:45]
	v_pk_add_f32 v[232:233], v[232:233], v[46:47]
	ds_read2_b32 v[32:33], v115 offset0:136 offset1:137
	ds_read2_b32 v[34:35], v115 offset0:138 offset1:139
	ds_read2_b32 v[36:37], v115 offset0:144 offset1:145
	ds_read2_b32 v[38:39], v115 offset0:146 offset1:147
	ds_read2_b32 v[40:41], v115 offset0:153 offset1:154
	ds_read2_b32 v[42:43], v115 offset0:155 offset1:156
	ds_read2_b32 v[44:45], v115 offset0:161 offset1:162
	ds_read2_b32 v[46:47], v115 offset0:163 offset1:164
	s_waitcnt lgkmcnt(15)
	v_mfma_f32_32x32x16_bf16 v[0:15], v[64:67], v[72:75], v[0:15]
	v_mfma_f32_32x32x16_bf16 v[16:31], v[64:67], v[76:79], v[16:31]
	v_mfma_f32_32x32x16_bf16 v[0:15], v[68:71], v[220:223], v[0:15]
	v_mfma_f32_32x32x16_bf16 v[16:31], v[68:71], v[224:227], v[16:31]
	global_load_dwordx4 v[188:191], v239, s[86:87]
	global_load_dwordx4 v[192:195], v240, s[86:87]
	global_load_dwordx4 v[196:199], v241, s[86:87]
	global_load_dwordx4 v[200:203], v242, s[86:87]
	global_load_dwordx4 v[204:207], v101, s[86:87] offset:768
	global_load_dwordx4 v[208:211], v150, s[86:87] offset:768
	global_load_dwordx4 v[212:215], v101, s[86:87] offset:832
	global_load_dwordx4 v[216:219], v150, s[86:87] offset:832
	s_add_u32 s86, s86, 0xc0000
	s_addc_u32 s87, s87, 0
	s_waitcnt lgkmcnt(0)
	v_mfma_f32_32x32x16_bf16 v[32:47], v[116:119], v[48:51], v[32:47]
	ds_read_b64_tr_b16 v[72:73], v231
	ds_read_b64_tr_b16 v[74:75], v231 offset:512
	ds_read_b64_tr_b16 v[76:77], v231 offset:2048
	ds_read_b64_tr_b16 v[78:79], v231 offset:2560
	ds_read_b64_tr_b16 v[220:221], v231 offset:1024
	ds_read_b64_tr_b16 v[222:223], v231 offset:1536
	ds_read_b64_tr_b16 v[224:225], v231 offset:3072
	ds_read_b64_tr_b16 v[226:227], v231 offset:3584
	s_waitcnt vmcnt(8)
	ds_write_b128 v247, v[156:159]
	ds_write_b128 v247, v[160:163] offset:1024
	ds_write_b128 v247, v[164:167] offset:2048
	ds_write_b128 v247, v[168:171] offset:3072
	ds_read_b128 v[156:159], v248
	ds_read_b128 v[160:163], v249
	ds_read_b128 v[164:167], v250
	ds_read_b128 v[168:171], v251
	ds_write_b128 v112, v[172:175]
	ds_write_b128 v112, v[176:179] offset:1024
	ds_write_b128 v112, v[180:183] offset:2048
	ds_write_b128 v112, v[184:187] offset:3072
	v_mfma_f32_32x32x16_bf16 v[32:47], v[120:123], v[52:55], v[32:47]
	v_mfma_f32_32x32x16_bf16 v[32:47], v[124:127], v[56:59], v[32:47]
	v_mfma_f32_32x32x16_bf16 v[32:47], v[128:131], v[60:63], v[32:47]
	s_nop 11
	v_exp_f32_e32 v32, v32
	v_exp_f32_e32 v33, v33
	v_exp_f32_e32 v34, v34
	v_exp_f32_e32 v35, v35
	v_exp_f32_e32 v36, v36
	v_exp_f32_e32 v37, v37
	v_exp_f32_e32 v38, v38
	v_exp_f32_e32 v39, v39
	v_exp_f32_e32 v40, v40
	v_exp_f32_e32 v41, v41
	v_exp_f32_e32 v42, v42
	v_exp_f32_e32 v43, v43
	v_exp_f32_e32 v44, v44
	v_exp_f32_e32 v45, v45
	v_exp_f32_e32 v46, v46
	v_exp_f32_e32 v47, v47
	v_cvt_pk_bf16_f32 v64, v32, v33
	v_cvt_pk_bf16_f32 v65, v34, v35
	v_cvt_pk_bf16_f32 v66, v36, v37
	v_cvt_pk_bf16_f32 v67, v38, v39
	v_cvt_pk_bf16_f32 v68, v40, v41
	v_cvt_pk_bf16_f32 v69, v42, v43
	v_cvt_pk_bf16_f32 v70, v44, v45
	v_cvt_pk_bf16_f32 v71, v46, v47
	v_pk_add_f32 v[232:233], v[232:233], v[32:33]
	v_pk_add_f32 v[232:233], v[232:233], v[34:35]
	v_pk_add_f32 v[232:233], v[232:233], v[36:37]
	v_pk_add_f32 v[232:233], v[232:233], v[38:39]
	v_pk_add_f32 v[232:233], v[232:233], v[40:41]
	v_pk_add_f32 v[232:233], v[232:233], v[42:43]
	v_pk_add_f32 v[232:233], v[232:233], v[44:45]
	v_pk_add_f32 v[232:233], v[232:233], v[46:47]
	ds_read2_b32 v[32:33], v115 offset0:170 offset1:171
	ds_read2_b32 v[34:35], v115 offset0:172 offset1:173
	ds_read2_b32 v[36:37], v115 offset0:178 offset1:179
	ds_read2_b32 v[38:39], v115 offset0:180 offset1:181
	ds_read2_b32 v[40:41], v115 offset0:187 offset1:188
	ds_read2_b32 v[42:43], v115 offset0:189 offset1:190
	ds_read2_b32 v[44:45], v115 offset0:195 offset1:196
	ds_read2_b32 v[46:47], v115 offset0:197 offset1:198
	s_waitcnt lgkmcnt(15)
	v_mfma_f32_32x32x16_bf16 v[0:15], v[64:67], v[72:75], v[0:15]
	v_mfma_f32_32x32x16_bf16 v[16:31], v[64:67], v[76:79], v[16:31]
	v_mfma_f32_32x32x16_bf16 v[0:15], v[68:71], v[220:223], v[0:15]
	v_mfma_f32_32x32x16_bf16 v[16:31], v[68:71], v[224:227], v[16:31]
	global_load_dwordx4 v[116:119], v239, s[86:87]
	global_load_dwordx4 v[120:123], v240, s[86:87]
	global_load_dwordx4 v[124:127], v241, s[86:87]
	global_load_dwordx4 v[128:131], v242, s[86:87]
	global_load_dwordx4 v[132:135], v101, s[86:87] offset:768
	global_load_dwordx4 v[136:139], v150, s[86:87] offset:768
	global_load_dwordx4 v[140:143], v101, s[86:87] offset:832
	global_load_dwordx4 v[144:147], v150, s[86:87] offset:832
	s_add_u32 s86, s86, 0xc0000
	s_addc_u32 s87, s87, 0
	s_waitcnt lgkmcnt(0)
	v_mfma_f32_32x32x16_bf16 v[32:47], v[156:159], v[48:51], v[32:47]
	ds_read_b64_tr_b16 v[72:73], v231
	ds_read_b64_tr_b16 v[74:75], v231 offset:512
	ds_read_b64_tr_b16 v[76:77], v231 offset:2048
	ds_read_b64_tr_b16 v[78:79], v231 offset:2560
	ds_read_b64_tr_b16 v[220:221], v231 offset:1024
	ds_read_b64_tr_b16 v[222:223], v231 offset:1536
	ds_read_b64_tr_b16 v[224:225], v231 offset:3072
	ds_read_b64_tr_b16 v[226:227], v231 offset:3584
	s_waitcnt vmcnt(8)
	ds_write_b128 v247, v[188:191]
	ds_write_b128 v247, v[192:195] offset:1024
	ds_write_b128 v247, v[196:199] offset:2048
	ds_write_b128 v247, v[200:203] offset:3072
	ds_read_b128 v[188:191], v248
	ds_read_b128 v[192:195], v249
	ds_read_b128 v[196:199], v250
	ds_read_b128 v[200:203], v251
	ds_write_b128 v112, v[204:207]
	ds_write_b128 v112, v[208:211] offset:1024
	ds_write_b128 v112, v[212:215] offset:2048
	ds_write_b128 v112, v[216:219] offset:3072
	v_mfma_f32_32x32x16_bf16 v[32:47], v[160:163], v[52:55], v[32:47]
	v_mfma_f32_32x32x16_bf16 v[32:47], v[164:167], v[56:59], v[32:47]
	v_mfma_f32_32x32x16_bf16 v[32:47], v[168:171], v[60:63], v[32:47]
	s_nop 11
	v_exp_f32_e32 v32, v32
	v_exp_f32_e32 v33, v33
	v_exp_f32_e32 v34, v34
	v_exp_f32_e32 v35, v35
	v_exp_f32_e32 v36, v36
	v_exp_f32_e32 v37, v37
	v_exp_f32_e32 v38, v38
	v_exp_f32_e32 v39, v39
	v_exp_f32_e32 v40, v40
	v_exp_f32_e32 v41, v41
	v_exp_f32_e32 v42, v42
	v_exp_f32_e32 v43, v43
	v_exp_f32_e32 v44, v44
	v_exp_f32_e32 v45, v45
	v_exp_f32_e32 v46, v46
	v_exp_f32_e32 v47, v47
	v_cvt_pk_bf16_f32 v64, v32, v33
	v_cvt_pk_bf16_f32 v65, v34, v35
	v_cvt_pk_bf16_f32 v66, v36, v37
	v_cvt_pk_bf16_f32 v67, v38, v39
	v_cvt_pk_bf16_f32 v68, v40, v41
	v_cvt_pk_bf16_f32 v69, v42, v43
	v_cvt_pk_bf16_f32 v70, v44, v45
	v_cvt_pk_bf16_f32 v71, v46, v47
	v_pk_add_f32 v[232:233], v[232:233], v[32:33]
	v_pk_add_f32 v[232:233], v[232:233], v[34:35]
	v_pk_add_f32 v[232:233], v[232:233], v[36:37]
	v_pk_add_f32 v[232:233], v[232:233], v[38:39]
	v_pk_add_f32 v[232:233], v[232:233], v[40:41]
	v_pk_add_f32 v[232:233], v[232:233], v[42:43]
	v_pk_add_f32 v[232:233], v[232:233], v[44:45]
	v_pk_add_f32 v[232:233], v[232:233], v[46:47]
	v_mov_b32_e32 v115, v229
	ds_read2_b32 v[32:33], v115 offset0:0 offset1:1
	ds_read2_b32 v[34:35], v115 offset0:2 offset1:3
	ds_read2_b32 v[36:37], v115 offset0:8 offset1:9
	ds_read2_b32 v[38:39], v115 offset0:10 offset1:11
	ds_read2_b32 v[40:41], v115 offset0:16 offset1:17
	ds_read2_b32 v[42:43], v115 offset0:18 offset1:19
	ds_read2_b32 v[44:45], v115 offset0:24 offset1:25
	ds_read2_b32 v[46:47], v115 offset0:26 offset1:27
	s_waitcnt lgkmcnt(15)
	v_mfma_f32_32x32x16_bf16 v[0:15], v[64:67], v[72:75], v[0:15]
	v_mfma_f32_32x32x16_bf16 v[16:31], v[64:67], v[76:79], v[16:31]
	v_mfma_f32_32x32x16_bf16 v[0:15], v[68:71], v[220:223], v[0:15]
	v_mfma_f32_32x32x16_bf16 v[16:31], v[68:71], v[224:227], v[16:31]
	global_load_dwordx4 v[156:159], v239, s[86:87]
	global_load_dwordx4 v[160:163], v240, s[86:87]
	global_load_dwordx4 v[164:167], v241, s[86:87]
	global_load_dwordx4 v[168:171], v242, s[86:87]
	global_load_dwordx4 v[172:175], v101, s[86:87] offset:768
	global_load_dwordx4 v[176:179], v150, s[86:87] offset:768
	global_load_dwordx4 v[180:183], v101, s[86:87] offset:832
	global_load_dwordx4 v[184:187], v150, s[86:87] offset:832
	s_add_u32 s86, s86, 0xc0000
	s_addc_u32 s87, s87, 0
	s_waitcnt lgkmcnt(0)
	v_mfma_f32_32x32x16_bf16 v[32:47], v[188:191], v[48:51], v[32:47]
	ds_read_b64_tr_b16 v[72:73], v231
	ds_read_b64_tr_b16 v[74:75], v231 offset:512
	ds_read_b64_tr_b16 v[76:77], v231 offset:2048
	ds_read_b64_tr_b16 v[78:79], v231 offset:2560
	ds_read_b64_tr_b16 v[220:221], v231 offset:1024
	ds_read_b64_tr_b16 v[222:223], v231 offset:1536
	ds_read_b64_tr_b16 v[224:225], v231 offset:3072
	ds_read_b64_tr_b16 v[226:227], v231 offset:3584
	s_waitcnt vmcnt(8)
	ds_write_b128 v247, v[116:119]
	ds_write_b128 v247, v[120:123] offset:1024
	ds_write_b128 v247, v[124:127] offset:2048
	ds_write_b128 v247, v[128:131] offset:3072
	ds_read_b128 v[116:119], v248
	ds_read_b128 v[120:123], v249
	ds_read_b128 v[124:127], v250
	ds_read_b128 v[128:131], v251
	ds_write_b128 v112, v[132:135]
	ds_write_b128 v112, v[136:139] offset:1024
	ds_write_b128 v112, v[140:143] offset:2048
	ds_write_b128 v112, v[144:147] offset:3072
	v_mfma_f32_32x32x16_bf16 v[32:47], v[192:195], v[52:55], v[32:47]
	v_mfma_f32_32x32x16_bf16 v[32:47], v[196:199], v[56:59], v[32:47]
	v_mfma_f32_32x32x16_bf16 v[32:47], v[200:203], v[60:63], v[32:47]
	s_nop 11
	v_exp_f32_e32 v32, v32
	v_exp_f32_e32 v33, v33
	v_exp_f32_e32 v34, v34
	v_exp_f32_e32 v35, v35
	v_exp_f32_e32 v36, v36
	v_exp_f32_e32 v37, v37
	v_exp_f32_e32 v38, v38
	v_exp_f32_e32 v39, v39
	v_exp_f32_e32 v40, v40
	v_exp_f32_e32 v41, v41
	v_exp_f32_e32 v42, v42
	v_exp_f32_e32 v43, v43
	v_exp_f32_e32 v44, v44
	v_exp_f32_e32 v45, v45
	v_exp_f32_e32 v46, v46
	v_exp_f32_e32 v47, v47
	v_cvt_pk_bf16_f32 v64, v32, v33
	v_cvt_pk_bf16_f32 v65, v34, v35
	v_cvt_pk_bf16_f32 v66, v36, v37
	v_cvt_pk_bf16_f32 v67, v38, v39
	v_cvt_pk_bf16_f32 v68, v40, v41
	v_cvt_pk_bf16_f32 v69, v42, v43
	v_cvt_pk_bf16_f32 v70, v44, v45
	v_cvt_pk_bf16_f32 v71, v46, v47
	v_pk_add_f32 v[232:233], v[232:233], v[32:33]
	v_pk_add_f32 v[232:233], v[232:233], v[34:35]
	v_pk_add_f32 v[232:233], v[232:233], v[36:37]
	v_pk_add_f32 v[232:233], v[232:233], v[38:39]
	v_pk_add_f32 v[232:233], v[232:233], v[40:41]
	v_pk_add_f32 v[232:233], v[232:233], v[42:43]
	v_pk_add_f32 v[232:233], v[232:233], v[44:45]
	v_pk_add_f32 v[232:233], v[232:233], v[46:47]
	ds_read2_b32 v[32:33], v115 offset0:32 offset1:33
	ds_read2_b32 v[34:35], v115 offset0:34 offset1:35
	ds_read2_b32 v[36:37], v115 offset0:40 offset1:41
	ds_read2_b32 v[38:39], v115 offset0:42 offset1:43
	ds_read2_b32 v[40:41], v115 offset0:48 offset1:49
	ds_read2_b32 v[42:43], v115 offset0:50 offset1:51
	ds_read2_b32 v[44:45], v115 offset0:56 offset1:57
	ds_read2_b32 v[46:47], v115 offset0:58 offset1:59
	s_waitcnt lgkmcnt(15)
	v_mfma_f32_32x32x16_bf16 v[0:15], v[64:67], v[72:75], v[0:15]
	v_mfma_f32_32x32x16_bf16 v[16:31], v[64:67], v[76:79], v[16:31]
	v_mfma_f32_32x32x16_bf16 v[0:15], v[68:71], v[220:223], v[0:15]
	v_mfma_f32_32x32x16_bf16 v[16:31], v[68:71], v[224:227], v[16:31]
	global_load_dwordx4 v[188:191], v239, s[86:87]
	global_load_dwordx4 v[192:195], v240, s[86:87]
	global_load_dwordx4 v[196:199], v241, s[86:87]
	global_load_dwordx4 v[200:203], v242, s[86:87]
	global_load_dwordx4 v[204:207], v101, s[86:87] offset:768
	global_load_dwordx4 v[208:211], v150, s[86:87] offset:768
	global_load_dwordx4 v[212:215], v101, s[86:87] offset:832
	global_load_dwordx4 v[216:219], v150, s[86:87] offset:832
	s_add_u32 s86, s86, 0xc0000
	s_addc_u32 s87, s87, 0
	s_waitcnt lgkmcnt(0)
	v_mfma_f32_32x32x16_bf16 v[32:47], v[116:119], v[48:51], v[32:47]
	ds_read_b64_tr_b16 v[72:73], v231
	ds_read_b64_tr_b16 v[74:75], v231 offset:512
	ds_read_b64_tr_b16 v[76:77], v231 offset:2048
	ds_read_b64_tr_b16 v[78:79], v231 offset:2560
	ds_read_b64_tr_b16 v[220:221], v231 offset:1024
	ds_read_b64_tr_b16 v[222:223], v231 offset:1536
	ds_read_b64_tr_b16 v[224:225], v231 offset:3072
	ds_read_b64_tr_b16 v[226:227], v231 offset:3584
	s_waitcnt vmcnt(8)
	ds_write_b128 v247, v[156:159]
	ds_write_b128 v247, v[160:163] offset:1024
	ds_write_b128 v247, v[164:167] offset:2048
	ds_write_b128 v247, v[168:171] offset:3072
	ds_read_b128 v[156:159], v248
	ds_read_b128 v[160:163], v249
	ds_read_b128 v[164:167], v250
	ds_read_b128 v[168:171], v251
	ds_write_b128 v112, v[172:175]
	ds_write_b128 v112, v[176:179] offset:1024
	ds_write_b128 v112, v[180:183] offset:2048
	ds_write_b128 v112, v[184:187] offset:3072
	v_mfma_f32_32x32x16_bf16 v[32:47], v[120:123], v[52:55], v[32:47]
	v_mfma_f32_32x32x16_bf16 v[32:47], v[124:127], v[56:59], v[32:47]
	v_mfma_f32_32x32x16_bf16 v[32:47], v[128:131], v[60:63], v[32:47]
	s_nop 11
	v_exp_f32_e32 v32, v32
	v_exp_f32_e32 v33, v33
	v_exp_f32_e32 v34, v34
	v_exp_f32_e32 v35, v35
	v_exp_f32_e32 v36, v36
	v_exp_f32_e32 v37, v37
	v_exp_f32_e32 v38, v38
	v_exp_f32_e32 v39, v39
	v_exp_f32_e32 v40, v40
	v_exp_f32_e32 v41, v41
	v_exp_f32_e32 v42, v42
	v_exp_f32_e32 v43, v43
	v_exp_f32_e32 v44, v44
	v_exp_f32_e32 v45, v45
	v_exp_f32_e32 v46, v46
	v_exp_f32_e32 v47, v47
	v_cvt_pk_bf16_f32 v64, v32, v33
	v_cvt_pk_bf16_f32 v65, v34, v35
	v_cvt_pk_bf16_f32 v66, v36, v37
	v_cvt_pk_bf16_f32 v67, v38, v39
	v_cvt_pk_bf16_f32 v68, v40, v41
	v_cvt_pk_bf16_f32 v69, v42, v43
	v_cvt_pk_bf16_f32 v70, v44, v45
	v_cvt_pk_bf16_f32 v71, v46, v47
	v_pk_add_f32 v[232:233], v[232:233], v[32:33]
	v_pk_add_f32 v[232:233], v[232:233], v[34:35]
	v_pk_add_f32 v[232:233], v[232:233], v[36:37]
	v_pk_add_f32 v[232:233], v[232:233], v[38:39]
	v_pk_add_f32 v[232:233], v[232:233], v[40:41]
	v_pk_add_f32 v[232:233], v[232:233], v[42:43]
	v_pk_add_f32 v[232:233], v[232:233], v[44:45]
	v_pk_add_f32 v[232:233], v[232:233], v[46:47]
	ds_read2_b32 v[32:33], v115 offset0:64 offset1:65
	ds_read2_b32 v[34:35], v115 offset0:66 offset1:67
	ds_read2_b32 v[36:37], v115 offset0:72 offset1:73
	ds_read2_b32 v[38:39], v115 offset0:74 offset1:75
	ds_read2_b32 v[40:41], v115 offset0:80 offset1:81
	ds_read2_b32 v[42:43], v115 offset0:82 offset1:83
	ds_read2_b32 v[44:45], v115 offset0:88 offset1:89
	ds_read2_b32 v[46:47], v115 offset0:90 offset1:91
	s_waitcnt lgkmcnt(15)
	v_mfma_f32_32x32x16_bf16 v[0:15], v[64:67], v[72:75], v[0:15]
	v_mfma_f32_32x32x16_bf16 v[16:31], v[64:67], v[76:79], v[16:31]
	v_mfma_f32_32x32x16_bf16 v[0:15], v[68:71], v[220:223], v[0:15]
	v_mfma_f32_32x32x16_bf16 v[16:31], v[68:71], v[224:227], v[16:31]
	global_load_dwordx4 v[116:119], v239, s[86:87]
	global_load_dwordx4 v[120:123], v240, s[86:87]
	global_load_dwordx4 v[124:127], v241, s[86:87]
	global_load_dwordx4 v[128:131], v242, s[86:87]
	global_load_dwordx4 v[132:135], v101, s[86:87] offset:768
	global_load_dwordx4 v[136:139], v150, s[86:87] offset:768
	global_load_dwordx4 v[140:143], v101, s[86:87] offset:832
	global_load_dwordx4 v[144:147], v150, s[86:87] offset:832
	s_add_u32 s86, s86, 0xc0000
	s_addc_u32 s87, s87, 0
	s_waitcnt lgkmcnt(0)
	v_mfma_f32_32x32x16_bf16 v[32:47], v[156:159], v[48:51], v[32:47]
	ds_read_b64_tr_b16 v[72:73], v231
	ds_read_b64_tr_b16 v[74:75], v231 offset:512
	ds_read_b64_tr_b16 v[76:77], v231 offset:2048
	ds_read_b64_tr_b16 v[78:79], v231 offset:2560
	ds_read_b64_tr_b16 v[220:221], v231 offset:1024
	ds_read_b64_tr_b16 v[222:223], v231 offset:1536
	ds_read_b64_tr_b16 v[224:225], v231 offset:3072
	ds_read_b64_tr_b16 v[226:227], v231 offset:3584
	s_waitcnt vmcnt(8)
	ds_write_b128 v247, v[188:191]
	ds_write_b128 v247, v[192:195] offset:1024
	ds_write_b128 v247, v[196:199] offset:2048
	ds_write_b128 v247, v[200:203] offset:3072
	ds_read_b128 v[188:191], v248
	ds_read_b128 v[192:195], v249
	ds_read_b128 v[196:199], v250
	ds_read_b128 v[200:203], v251
	ds_write_b128 v112, v[204:207]
	ds_write_b128 v112, v[208:211] offset:1024
	ds_write_b128 v112, v[212:215] offset:2048
	ds_write_b128 v112, v[216:219] offset:3072
	v_mfma_f32_32x32x16_bf16 v[32:47], v[160:163], v[52:55], v[32:47]
	v_mfma_f32_32x32x16_bf16 v[32:47], v[164:167], v[56:59], v[32:47]
	v_mfma_f32_32x32x16_bf16 v[32:47], v[168:171], v[60:63], v[32:47]
	s_nop 11
	v_exp_f32_e32 v32, v32
	v_exp_f32_e32 v33, v33
	v_exp_f32_e32 v34, v34
	v_exp_f32_e32 v35, v35
	v_exp_f32_e32 v36, v36
	v_exp_f32_e32 v37, v37
	v_exp_f32_e32 v38, v38
	v_exp_f32_e32 v39, v39
	v_exp_f32_e32 v40, v40
	v_exp_f32_e32 v41, v41
	v_exp_f32_e32 v42, v42
	v_exp_f32_e32 v43, v43
	v_exp_f32_e32 v44, v44
	v_exp_f32_e32 v45, v45
	v_exp_f32_e32 v46, v46
	v_exp_f32_e32 v47, v47
	v_cvt_pk_bf16_f32 v64, v32, v33
	v_cvt_pk_bf16_f32 v65, v34, v35
	v_cvt_pk_bf16_f32 v66, v36, v37
	v_cvt_pk_bf16_f32 v67, v38, v39
	v_cvt_pk_bf16_f32 v68, v40, v41
	v_cvt_pk_bf16_f32 v69, v42, v43
	v_cvt_pk_bf16_f32 v70, v44, v45
	v_cvt_pk_bf16_f32 v71, v46, v47
	v_pk_add_f32 v[232:233], v[232:233], v[32:33]
	v_pk_add_f32 v[232:233], v[232:233], v[34:35]
	v_pk_add_f32 v[232:233], v[232:233], v[36:37]
	v_pk_add_f32 v[232:233], v[232:233], v[38:39]
	v_pk_add_f32 v[232:233], v[232:233], v[40:41]
	v_pk_add_f32 v[232:233], v[232:233], v[42:43]
	v_pk_add_f32 v[232:233], v[232:233], v[44:45]
	v_pk_add_f32 v[232:233], v[232:233], v[46:47]
	ds_read2_b32 v[32:33], v115 offset0:96 offset1:97
	ds_read2_b32 v[34:35], v115 offset0:98 offset1:99
	ds_read2_b32 v[36:37], v115 offset0:104 offset1:105
	ds_read2_b32 v[38:39], v115 offset0:106 offset1:107
	ds_read2_b32 v[40:41], v115 offset0:112 offset1:113
	ds_read2_b32 v[42:43], v115 offset0:114 offset1:115
	ds_read2_b32 v[44:45], v115 offset0:120 offset1:121
	ds_read2_b32 v[46:47], v115 offset0:122 offset1:123
	s_waitcnt lgkmcnt(15)
	v_mfma_f32_32x32x16_bf16 v[0:15], v[64:67], v[72:75], v[0:15]
	v_mfma_f32_32x32x16_bf16 v[16:31], v[64:67], v[76:79], v[16:31]
	v_mfma_f32_32x32x16_bf16 v[0:15], v[68:71], v[220:223], v[0:15]
	v_mfma_f32_32x32x16_bf16 v[16:31], v[68:71], v[224:227], v[16:31]
	global_load_dwordx4 v[156:159], v239, s[86:87]
	global_load_dwordx4 v[160:163], v240, s[86:87]
	global_load_dwordx4 v[164:167], v241, s[86:87]
	global_load_dwordx4 v[168:171], v242, s[86:87]
	global_load_dwordx4 v[172:175], v101, s[86:87] offset:768
	global_load_dwordx4 v[176:179], v150, s[86:87] offset:768
	global_load_dwordx4 v[180:183], v101, s[86:87] offset:832
	global_load_dwordx4 v[184:187], v150, s[86:87] offset:832
	s_add_u32 s86, s86, 0xc0000
	s_addc_u32 s87, s87, 0
	s_waitcnt lgkmcnt(0)
	v_mfma_f32_32x32x16_bf16 v[32:47], v[188:191], v[48:51], v[32:47]
	ds_read_b64_tr_b16 v[72:73], v231
	ds_read_b64_tr_b16 v[74:75], v231 offset:512
	ds_read_b64_tr_b16 v[76:77], v231 offset:2048
	ds_read_b64_tr_b16 v[78:79], v231 offset:2560
	ds_read_b64_tr_b16 v[220:221], v231 offset:1024
	ds_read_b64_tr_b16 v[222:223], v231 offset:1536
	ds_read_b64_tr_b16 v[224:225], v231 offset:3072
	ds_read_b64_tr_b16 v[226:227], v231 offset:3584
	s_waitcnt vmcnt(8)
	ds_write_b128 v247, v[116:119]
	ds_write_b128 v247, v[120:123] offset:1024
	ds_write_b128 v247, v[124:127] offset:2048
	ds_write_b128 v247, v[128:131] offset:3072
	ds_read_b128 v[116:119], v248
	ds_read_b128 v[120:123], v249
	ds_read_b128 v[124:127], v250
	ds_read_b128 v[128:131], v251
	ds_write_b128 v112, v[132:135]
	ds_write_b128 v112, v[136:139] offset:1024
	ds_write_b128 v112, v[140:143] offset:2048
	ds_write_b128 v112, v[144:147] offset:3072
	v_mfma_f32_32x32x16_bf16 v[32:47], v[192:195], v[52:55], v[32:47]
	v_mfma_f32_32x32x16_bf16 v[32:47], v[196:199], v[56:59], v[32:47]
	v_mfma_f32_32x32x16_bf16 v[32:47], v[200:203], v[60:63], v[32:47]
	s_nop 11
	v_exp_f32_e32 v32, v32
	v_exp_f32_e32 v33, v33
	v_exp_f32_e32 v34, v34
	v_exp_f32_e32 v35, v35
	v_exp_f32_e32 v36, v36
	v_exp_f32_e32 v37, v37
	v_exp_f32_e32 v38, v38
	v_exp_f32_e32 v39, v39
	v_exp_f32_e32 v40, v40
	v_exp_f32_e32 v41, v41
	v_exp_f32_e32 v42, v42
	v_exp_f32_e32 v43, v43
	v_exp_f32_e32 v44, v44
	v_exp_f32_e32 v45, v45
	v_exp_f32_e32 v46, v46
	v_exp_f32_e32 v47, v47
	v_cvt_pk_bf16_f32 v64, v32, v33
	v_cvt_pk_bf16_f32 v65, v34, v35
	v_cvt_pk_bf16_f32 v66, v36, v37
	v_cvt_pk_bf16_f32 v67, v38, v39
	v_cvt_pk_bf16_f32 v68, v40, v41
	v_cvt_pk_bf16_f32 v69, v42, v43
	v_cvt_pk_bf16_f32 v70, v44, v45
	v_cvt_pk_bf16_f32 v71, v46, v47
	v_pk_add_f32 v[232:233], v[232:233], v[32:33]
	v_pk_add_f32 v[232:233], v[232:233], v[34:35]
	v_pk_add_f32 v[232:233], v[232:233], v[36:37]
	v_pk_add_f32 v[232:233], v[232:233], v[38:39]
	v_pk_add_f32 v[232:233], v[232:233], v[40:41]
	v_pk_add_f32 v[232:233], v[232:233], v[42:43]
	v_pk_add_f32 v[232:233], v[232:233], v[44:45]
	v_pk_add_f32 v[232:233], v[232:233], v[46:47]
	ds_read2_b32 v[32:33], v115 offset0:128 offset1:129
	ds_read2_b32 v[34:35], v115 offset0:130 offset1:131
	ds_read2_b32 v[36:37], v115 offset0:136 offset1:137
	ds_read2_b32 v[38:39], v115 offset0:138 offset1:139
	ds_read2_b32 v[40:41], v115 offset0:144 offset1:145
	ds_read2_b32 v[42:43], v115 offset0:146 offset1:147
	ds_read2_b32 v[44:45], v115 offset0:152 offset1:153
	ds_read2_b32 v[46:47], v115 offset0:154 offset1:155
	s_waitcnt lgkmcnt(15)
	v_mfma_f32_32x32x16_bf16 v[0:15], v[64:67], v[72:75], v[0:15]
	v_mfma_f32_32x32x16_bf16 v[16:31], v[64:67], v[76:79], v[16:31]
	v_mfma_f32_32x32x16_bf16 v[0:15], v[68:71], v[220:223], v[0:15]
	v_mfma_f32_32x32x16_bf16 v[16:31], v[68:71], v[224:227], v[16:31]
	global_load_dwordx4 v[188:191], v239, s[86:87]
	global_load_dwordx4 v[192:195], v240, s[86:87]
	global_load_dwordx4 v[196:199], v241, s[86:87]
	global_load_dwordx4 v[200:203], v242, s[86:87]
	global_load_dwordx4 v[204:207], v101, s[86:87] offset:768
	global_load_dwordx4 v[208:211], v150, s[86:87] offset:768
	global_load_dwordx4 v[212:215], v101, s[86:87] offset:832
	global_load_dwordx4 v[216:219], v150, s[86:87] offset:832
	s_add_u32 s86, s86, 0xc0000
	s_addc_u32 s87, s87, 0
	s_waitcnt lgkmcnt(0)
	v_mfma_f32_32x32x16_bf16 v[32:47], v[116:119], v[48:51], v[32:47]
	ds_read_b64_tr_b16 v[72:73], v231
	ds_read_b64_tr_b16 v[74:75], v231 offset:512
	ds_read_b64_tr_b16 v[76:77], v231 offset:2048
	ds_read_b64_tr_b16 v[78:79], v231 offset:2560
	ds_read_b64_tr_b16 v[220:221], v231 offset:1024
	ds_read_b64_tr_b16 v[222:223], v231 offset:1536
	ds_read_b64_tr_b16 v[224:225], v231 offset:3072
	ds_read_b64_tr_b16 v[226:227], v231 offset:3584
	s_waitcnt vmcnt(8)
	ds_write_b128 v247, v[156:159]
	ds_write_b128 v247, v[160:163] offset:1024
	ds_write_b128 v247, v[164:167] offset:2048
	ds_write_b128 v247, v[168:171] offset:3072
	ds_read_b128 v[156:159], v248
	ds_read_b128 v[160:163], v249
	ds_read_b128 v[164:167], v250
	ds_read_b128 v[168:171], v251
	ds_write_b128 v112, v[172:175]
	ds_write_b128 v112, v[176:179] offset:1024
	ds_write_b128 v112, v[180:183] offset:2048
	ds_write_b128 v112, v[184:187] offset:3072
	v_mfma_f32_32x32x16_bf16 v[32:47], v[120:123], v[52:55], v[32:47]
	v_mfma_f32_32x32x16_bf16 v[32:47], v[124:127], v[56:59], v[32:47]
	v_mfma_f32_32x32x16_bf16 v[32:47], v[128:131], v[60:63], v[32:47]
	s_nop 11
	v_exp_f32_e32 v32, v32
	v_exp_f32_e32 v33, v33
	v_exp_f32_e32 v34, v34
	v_exp_f32_e32 v35, v35
	v_exp_f32_e32 v36, v36
	v_exp_f32_e32 v37, v37
	v_exp_f32_e32 v38, v38
	v_exp_f32_e32 v39, v39
	v_exp_f32_e32 v40, v40
	v_exp_f32_e32 v41, v41
	v_exp_f32_e32 v42, v42
	v_exp_f32_e32 v43, v43
	v_exp_f32_e32 v44, v44
	v_exp_f32_e32 v45, v45
	v_exp_f32_e32 v46, v46
	v_exp_f32_e32 v47, v47
	v_cvt_pk_bf16_f32 v64, v32, v33
	v_cvt_pk_bf16_f32 v65, v34, v35
	v_cvt_pk_bf16_f32 v66, v36, v37
	v_cvt_pk_bf16_f32 v67, v38, v39
	v_cvt_pk_bf16_f32 v68, v40, v41
	v_cvt_pk_bf16_f32 v69, v42, v43
	v_cvt_pk_bf16_f32 v70, v44, v45
	v_cvt_pk_bf16_f32 v71, v46, v47
	v_pk_add_f32 v[232:233], v[232:233], v[32:33]
	v_pk_add_f32 v[232:233], v[232:233], v[34:35]
	v_pk_add_f32 v[232:233], v[232:233], v[36:37]
	v_pk_add_f32 v[232:233], v[232:233], v[38:39]
	v_pk_add_f32 v[232:233], v[232:233], v[40:41]
	v_pk_add_f32 v[232:233], v[232:233], v[42:43]
	v_pk_add_f32 v[232:233], v[232:233], v[44:45]
	v_pk_add_f32 v[232:233], v[232:233], v[46:47]
	ds_read2_b32 v[32:33], v115 offset0:160 offset1:161
	ds_read2_b32 v[34:35], v115 offset0:162 offset1:163
	ds_read2_b32 v[36:37], v115 offset0:168 offset1:169
	ds_read2_b32 v[38:39], v115 offset0:170 offset1:171
	ds_read2_b32 v[40:41], v115 offset0:176 offset1:177
	ds_read2_b32 v[42:43], v115 offset0:178 offset1:179
	ds_read2_b32 v[44:45], v115 offset0:184 offset1:185
	ds_read2_b32 v[46:47], v115 offset0:186 offset1:187
	s_waitcnt lgkmcnt(15)
	v_mfma_f32_32x32x16_bf16 v[0:15], v[64:67], v[72:75], v[0:15]
	v_mfma_f32_32x32x16_bf16 v[16:31], v[64:67], v[76:79], v[16:31]
	v_mfma_f32_32x32x16_bf16 v[0:15], v[68:71], v[220:223], v[0:15]
	v_mfma_f32_32x32x16_bf16 v[16:31], v[68:71], v[224:227], v[16:31]
	global_load_dwordx4 v[116:119], v239, s[86:87]
	global_load_dwordx4 v[120:123], v240, s[86:87]
	global_load_dwordx4 v[124:127], v241, s[86:87]
	global_load_dwordx4 v[128:131], v242, s[86:87]
	global_load_dwordx4 v[132:135], v101, s[86:87] offset:768
	global_load_dwordx4 v[136:139], v150, s[86:87] offset:768
	global_load_dwordx4 v[140:143], v101, s[86:87] offset:832
	global_load_dwordx4 v[144:147], v150, s[86:87] offset:832
	s_waitcnt lgkmcnt(0)
	v_mfma_f32_32x32x16_bf16 v[32:47], v[156:159], v[48:51], v[32:47]
	ds_read_b64_tr_b16 v[72:73], v231
	ds_read_b64_tr_b16 v[74:75], v231 offset:512
	ds_read_b64_tr_b16 v[76:77], v231 offset:2048
	ds_read_b64_tr_b16 v[78:79], v231 offset:2560
	ds_read_b64_tr_b16 v[220:221], v231 offset:1024
	ds_read_b64_tr_b16 v[222:223], v231 offset:1536
	ds_read_b64_tr_b16 v[224:225], v231 offset:3072
	ds_read_b64_tr_b16 v[226:227], v231 offset:3584
	s_waitcnt vmcnt(8)
	ds_write_b128 v247, v[188:191]
	ds_write_b128 v247, v[192:195] offset:1024
	ds_write_b128 v247, v[196:199] offset:2048
	ds_write_b128 v247, v[200:203] offset:3072
	ds_read_b128 v[188:191], v248
	ds_read_b128 v[192:195], v249
	ds_read_b128 v[196:199], v250
	ds_read_b128 v[200:203], v251
	ds_write_b128 v112, v[204:207]
	ds_write_b128 v112, v[208:211] offset:1024
	ds_write_b128 v112, v[212:215] offset:2048
	ds_write_b128 v112, v[216:219] offset:3072
	v_mfma_f32_32x32x16_bf16 v[32:47], v[160:163], v[52:55], v[32:47]
	v_mfma_f32_32x32x16_bf16 v[32:47], v[164:167], v[56:59], v[32:47]
	v_mfma_f32_32x32x16_bf16 v[32:47], v[168:171], v[60:63], v[32:47]
	s_nop 11
	v_exp_f32_e32 v32, v32
	v_exp_f32_e32 v33, v33
	v_exp_f32_e32 v34, v34
	v_exp_f32_e32 v35, v35
	v_exp_f32_e32 v36, v36
	v_exp_f32_e32 v37, v37
	v_exp_f32_e32 v38, v38
	v_exp_f32_e32 v39, v39
	v_exp_f32_e32 v40, v40
	v_exp_f32_e32 v41, v41
	v_exp_f32_e32 v42, v42
	v_exp_f32_e32 v43, v43
	v_exp_f32_e32 v44, v44
	v_exp_f32_e32 v45, v45
	v_exp_f32_e32 v46, v46
	v_exp_f32_e32 v47, v47
	v_cvt_pk_bf16_f32 v64, v32, v33
	v_cvt_pk_bf16_f32 v65, v34, v35
	v_cvt_pk_bf16_f32 v66, v36, v37
	v_cvt_pk_bf16_f32 v67, v38, v39
	v_cvt_pk_bf16_f32 v68, v40, v41
	v_cvt_pk_bf16_f32 v69, v42, v43
	v_cvt_pk_bf16_f32 v70, v44, v45
	v_cvt_pk_bf16_f32 v71, v46, v47
	v_pk_add_f32 v[232:233], v[232:233], v[32:33]
	v_pk_add_f32 v[232:233], v[232:233], v[34:35]
	v_pk_add_f32 v[232:233], v[232:233], v[36:37]
	v_pk_add_f32 v[232:233], v[232:233], v[38:39]
	v_pk_add_f32 v[232:233], v[232:233], v[40:41]
	v_pk_add_f32 v[232:233], v[232:233], v[42:43]
	v_pk_add_f32 v[232:233], v[232:233], v[44:45]
	v_pk_add_f32 v[232:233], v[232:233], v[46:47]
	ds_read2_b32 v[32:33], v115 offset0:192 offset1:193
	ds_read2_b32 v[34:35], v115 offset0:194 offset1:195
	ds_read2_b32 v[36:37], v115 offset0:200 offset1:201
	ds_read2_b32 v[38:39], v115 offset0:202 offset1:203
	ds_read2_b32 v[40:41], v115 offset0:208 offset1:209
	ds_read2_b32 v[42:43], v115 offset0:210 offset1:211
	ds_read2_b32 v[44:45], v115 offset0:216 offset1:217
	ds_read2_b32 v[46:47], v115 offset0:218 offset1:219
	s_waitcnt lgkmcnt(15)
	v_mfma_f32_32x32x16_bf16 v[0:15], v[64:67], v[72:75], v[0:15]
	v_mfma_f32_32x32x16_bf16 v[16:31], v[64:67], v[76:79], v[16:31]
	v_mfma_f32_32x32x16_bf16 v[0:15], v[68:71], v[220:223], v[0:15]
	v_mfma_f32_32x32x16_bf16 v[16:31], v[68:71], v[224:227], v[16:31]
	global_load_dwordx4 v[156:159], v243, s[88:89]
	global_load_dwordx4 v[160:163], v244, s[88:89]
	global_load_dwordx4 v[164:167], v245, s[88:89]
	global_load_dwordx4 v[168:171], v246, s[88:89]
	global_load_dwordx4 v[172:175], v148, s[88:89] offset:768
	global_load_dwordx4 v[176:179], v151, s[88:89] offset:768
	global_load_dwordx4 v[180:183], v148, s[88:89] offset:832
	global_load_dwordx4 v[184:187], v151, s[88:89] offset:832
	s_add_u32 s88, s88, 0x300000
	s_addc_u32 s89, s89, 0
	s_waitcnt lgkmcnt(0)
	v_mfma_f32_32x32x16_bf16 v[32:47], v[188:191], v[48:51], v[32:47]
	ds_read_b64_tr_b16 v[72:73], v231
	ds_read_b64_tr_b16 v[74:75], v231 offset:512
	ds_read_b64_tr_b16 v[76:77], v231 offset:2048
	ds_read_b64_tr_b16 v[78:79], v231 offset:2560
	ds_read_b64_tr_b16 v[220:221], v231 offset:1024
	ds_read_b64_tr_b16 v[222:223], v231 offset:1536
	ds_read_b64_tr_b16 v[224:225], v231 offset:3072
	ds_read_b64_tr_b16 v[226:227], v231 offset:3584
	s_waitcnt vmcnt(8)
	ds_write_b128 v247, v[116:119]
	ds_write_b128 v247, v[120:123] offset:1024
	ds_write_b128 v247, v[124:127] offset:2048
	ds_write_b128 v247, v[128:131] offset:3072
	ds_read_b128 v[116:119], v248
	ds_read_b128 v[120:123], v249
	ds_read_b128 v[124:127], v250
	ds_read_b128 v[128:131], v251
	ds_write_b128 v112, v[132:135]
	ds_write_b128 v112, v[136:139] offset:1024
	ds_write_b128 v112, v[140:143] offset:2048
	ds_write_b128 v112, v[144:147] offset:3072
	v_mfma_f32_32x32x16_bf16 v[32:47], v[192:195], v[52:55], v[32:47]
	v_mfma_f32_32x32x16_bf16 v[32:47], v[196:199], v[56:59], v[32:47]
	v_mfma_f32_32x32x16_bf16 v[32:47], v[200:203], v[60:63], v[32:47]
	s_nop 11
	v_exp_f32_e32 v32, v32
	v_exp_f32_e32 v33, v33
	v_exp_f32_e32 v34, v34
	v_exp_f32_e32 v35, v35
	v_exp_f32_e32 v36, v36
	v_exp_f32_e32 v37, v37
	v_exp_f32_e32 v38, v38
	v_exp_f32_e32 v39, v39
	v_exp_f32_e32 v40, v40
	v_exp_f32_e32 v41, v41
	v_exp_f32_e32 v42, v42
	v_exp_f32_e32 v43, v43
	v_exp_f32_e32 v44, v44
	v_exp_f32_e32 v45, v45
	v_exp_f32_e32 v46, v46
	v_exp_f32_e32 v47, v47
	v_cvt_pk_bf16_f32 v64, v32, v33
	v_cvt_pk_bf16_f32 v65, v34, v35
	v_cvt_pk_bf16_f32 v66, v36, v37
	v_cvt_pk_bf16_f32 v67, v38, v39
	v_cvt_pk_bf16_f32 v68, v40, v41
	v_cvt_pk_bf16_f32 v69, v42, v43
	v_cvt_pk_bf16_f32 v70, v44, v45
	v_cvt_pk_bf16_f32 v71, v46, v47
	v_pk_add_f32 v[232:233], v[232:233], v[32:33]
	v_pk_add_f32 v[232:233], v[232:233], v[34:35]
	v_pk_add_f32 v[232:233], v[232:233], v[36:37]
	v_pk_add_f32 v[232:233], v[232:233], v[38:39]
	v_pk_add_f32 v[232:233], v[232:233], v[40:41]
	v_pk_add_f32 v[232:233], v[232:233], v[42:43]
	v_pk_add_f32 v[232:233], v[232:233], v[44:45]
	v_pk_add_f32 v[232:233], v[232:233], v[46:47]
	ds_read2_b32 v[32:33], v115 offset0:224 offset1:225
	ds_read2_b32 v[34:35], v115 offset0:226 offset1:227
	ds_read2_b32 v[36:37], v115 offset0:232 offset1:233
	ds_read2_b32 v[38:39], v115 offset0:234 offset1:235
	ds_read2_b32 v[40:41], v115 offset0:240 offset1:241
	ds_read2_b32 v[42:43], v115 offset0:242 offset1:243
	ds_read2_b32 v[44:45], v115 offset0:248 offset1:249
	ds_read2_b32 v[46:47], v115 offset0:250 offset1:251
	s_waitcnt lgkmcnt(15)
	v_mfma_f32_32x32x16_bf16 v[0:15], v[64:67], v[72:75], v[0:15]
	v_mfma_f32_32x32x16_bf16 v[16:31], v[64:67], v[76:79], v[16:31]
	v_mfma_f32_32x32x16_bf16 v[0:15], v[68:71], v[220:223], v[0:15]
	v_mfma_f32_32x32x16_bf16 v[16:31], v[68:71], v[224:227], v[16:31]
	global_load_dwordx4 v[188:191], v243, s[88:89]
	global_load_dwordx4 v[192:195], v244, s[88:89]
	global_load_dwordx4 v[196:199], v245, s[88:89]
	global_load_dwordx4 v[200:203], v246, s[88:89]
	global_load_dwordx4 v[204:207], v148, s[88:89] offset:768
	global_load_dwordx4 v[208:211], v151, s[88:89] offset:768
	global_load_dwordx4 v[212:215], v148, s[88:89] offset:832
	global_load_dwordx4 v[216:219], v151, s[88:89] offset:832
	s_add_u32 s88, s88, 0x300000
	s_addc_u32 s89, s89, 0
	s_waitcnt lgkmcnt(0)
	v_mfma_f32_32x32x16_bf16 v[32:47], v[116:119], v[48:51], v[32:47]
	ds_read_b64_tr_b16 v[72:73], v231
	ds_read_b64_tr_b16 v[74:75], v231 offset:512
	ds_read_b64_tr_b16 v[76:77], v231 offset:2048
	ds_read_b64_tr_b16 v[78:79], v231 offset:2560
	ds_read_b64_tr_b16 v[220:221], v231 offset:1024
	ds_read_b64_tr_b16 v[222:223], v231 offset:1536
	ds_read_b64_tr_b16 v[224:225], v231 offset:3072
	ds_read_b64_tr_b16 v[226:227], v231 offset:3584
	s_waitcnt vmcnt(8)
	ds_write_b128 v247, v[156:159]
	ds_write_b128 v247, v[160:163] offset:1024
	ds_write_b128 v247, v[164:167] offset:2048
	ds_write_b128 v247, v[168:171] offset:3072
	ds_read_b128 v[156:159], v248
	ds_read_b128 v[160:163], v249
	ds_read_b128 v[164:167], v250
	ds_read_b128 v[168:171], v251
	ds_write_b128 v112, v[172:175]
	ds_write_b128 v112, v[176:179] offset:1024
	ds_write_b128 v112, v[180:183] offset:2048
	ds_write_b128 v112, v[184:187] offset:3072
	v_mfma_f32_32x32x16_bf16 v[32:47], v[120:123], v[52:55], v[32:47]
	v_mfma_f32_32x32x16_bf16 v[32:47], v[124:127], v[56:59], v[32:47]
	v_mfma_f32_32x32x16_bf16 v[32:47], v[128:131], v[60:63], v[32:47]
	s_nop 11
	v_exp_f32_e32 v32, v32
	v_exp_f32_e32 v33, v33
	v_exp_f32_e32 v34, v34
	v_exp_f32_e32 v35, v35
	v_exp_f32_e32 v36, v36
	v_exp_f32_e32 v37, v37
	v_exp_f32_e32 v38, v38
	v_exp_f32_e32 v39, v39
	v_exp_f32_e32 v40, v40
	v_exp_f32_e32 v41, v41
	v_exp_f32_e32 v42, v42
	v_exp_f32_e32 v43, v43
	v_exp_f32_e32 v44, v44
	v_exp_f32_e32 v45, v45
	v_exp_f32_e32 v46, v46
	v_exp_f32_e32 v47, v47
	v_cvt_pk_bf16_f32 v64, v32, v33
	v_cvt_pk_bf16_f32 v65, v34, v35
	v_cvt_pk_bf16_f32 v66, v36, v37
	v_cvt_pk_bf16_f32 v67, v38, v39
	v_cvt_pk_bf16_f32 v68, v40, v41
	v_cvt_pk_bf16_f32 v69, v42, v43
	v_cvt_pk_bf16_f32 v70, v44, v45
	v_cvt_pk_bf16_f32 v71, v46, v47
	v_pk_add_f32 v[232:233], v[232:233], v[32:33]
	v_pk_add_f32 v[232:233], v[232:233], v[34:35]
	v_pk_add_f32 v[232:233], v[232:233], v[36:37]
	v_pk_add_f32 v[232:233], v[232:233], v[38:39]
	v_pk_add_f32 v[232:233], v[232:233], v[40:41]
	v_pk_add_f32 v[232:233], v[232:233], v[42:43]
	v_pk_add_f32 v[232:233], v[232:233], v[44:45]
	v_pk_add_f32 v[232:233], v[232:233], v[46:47]
	v_mov_b32_e32 v115, v230
	ds_read2_b32 v[32:33], v115 offset0:0 offset1:1
	ds_read2_b32 v[34:35], v115 offset0:2 offset1:3
	ds_read2_b32 v[36:37], v115 offset0:8 offset1:9
	ds_read2_b32 v[38:39], v115 offset0:10 offset1:11
	ds_read2_b32 v[40:41], v115 offset0:16 offset1:17
	ds_read2_b32 v[42:43], v115 offset0:18 offset1:19
	ds_read2_b32 v[44:45], v115 offset0:24 offset1:25
	ds_read2_b32 v[46:47], v115 offset0:26 offset1:27
	s_waitcnt lgkmcnt(15)
	v_mfma_f32_32x32x16_bf16 v[0:15], v[64:67], v[72:75], v[0:15]
	v_mfma_f32_32x32x16_bf16 v[16:31], v[64:67], v[76:79], v[16:31]
	v_mfma_f32_32x32x16_bf16 v[0:15], v[68:71], v[220:223], v[0:15]
	v_mfma_f32_32x32x16_bf16 v[16:31], v[68:71], v[224:227], v[16:31]
	global_load_dwordx4 v[116:119], v243, s[88:89]
	global_load_dwordx4 v[120:123], v244, s[88:89]
	global_load_dwordx4 v[124:127], v245, s[88:89]
	global_load_dwordx4 v[128:131], v246, s[88:89]
	global_load_dwordx4 v[132:135], v148, s[88:89] offset:768
	global_load_dwordx4 v[136:139], v151, s[88:89] offset:768
	global_load_dwordx4 v[140:143], v148, s[88:89] offset:832
	global_load_dwordx4 v[144:147], v151, s[88:89] offset:832
	s_add_u32 s88, s88, 0x300000
	s_addc_u32 s89, s89, 0
	s_waitcnt lgkmcnt(0)
	v_mfma_f32_32x32x16_bf16 v[32:47], v[156:159], v[48:51], v[32:47]
	ds_read_b64_tr_b16 v[72:73], v231
	ds_read_b64_tr_b16 v[74:75], v231 offset:512
	ds_read_b64_tr_b16 v[76:77], v231 offset:2048
	ds_read_b64_tr_b16 v[78:79], v231 offset:2560
	ds_read_b64_tr_b16 v[220:221], v231 offset:1024
	ds_read_b64_tr_b16 v[222:223], v231 offset:1536
	ds_read_b64_tr_b16 v[224:225], v231 offset:3072
	ds_read_b64_tr_b16 v[226:227], v231 offset:3584
	s_waitcnt vmcnt(8)
	ds_write_b128 v247, v[188:191]
	ds_write_b128 v247, v[192:195] offset:1024
	ds_write_b128 v247, v[196:199] offset:2048
	ds_write_b128 v247, v[200:203] offset:3072
	ds_read_b128 v[188:191], v248
	ds_read_b128 v[192:195], v249
	ds_read_b128 v[196:199], v250
	ds_read_b128 v[200:203], v251
	ds_write_b128 v112, v[204:207]
	ds_write_b128 v112, v[208:211] offset:1024
	ds_write_b128 v112, v[212:215] offset:2048
	ds_write_b128 v112, v[216:219] offset:3072
	v_mfma_f32_32x32x16_bf16 v[32:47], v[160:163], v[52:55], v[32:47]
	v_mfma_f32_32x32x16_bf16 v[32:47], v[164:167], v[56:59], v[32:47]
	v_mfma_f32_32x32x16_bf16 v[32:47], v[168:171], v[60:63], v[32:47]
	s_nop 11
	v_exp_f32_e32 v32, v32
	v_exp_f32_e32 v33, v33
	v_exp_f32_e32 v34, v34
	v_exp_f32_e32 v35, v35
	v_exp_f32_e32 v36, v36
	v_exp_f32_e32 v37, v37
	v_exp_f32_e32 v38, v38
	v_exp_f32_e32 v39, v39
	v_exp_f32_e32 v40, v40
	v_exp_f32_e32 v41, v41
	v_exp_f32_e32 v42, v42
	v_exp_f32_e32 v43, v43
	v_exp_f32_e32 v44, v44
	v_exp_f32_e32 v45, v45
	v_exp_f32_e32 v46, v46
	v_exp_f32_e32 v47, v47
	v_cvt_pk_bf16_f32 v64, v32, v33
	v_cvt_pk_bf16_f32 v65, v34, v35
	v_cvt_pk_bf16_f32 v66, v36, v37
	v_cvt_pk_bf16_f32 v67, v38, v39
	v_cvt_pk_bf16_f32 v68, v40, v41
	v_cvt_pk_bf16_f32 v69, v42, v43
	v_cvt_pk_bf16_f32 v70, v44, v45
	v_cvt_pk_bf16_f32 v71, v46, v47
	v_pk_add_f32 v[232:233], v[232:233], v[32:33]
	v_pk_add_f32 v[232:233], v[232:233], v[34:35]
	v_pk_add_f32 v[232:233], v[232:233], v[36:37]
	v_pk_add_f32 v[232:233], v[232:233], v[38:39]
	v_pk_add_f32 v[232:233], v[232:233], v[40:41]
	v_pk_add_f32 v[232:233], v[232:233], v[42:43]
	v_pk_add_f32 v[232:233], v[232:233], v[44:45]
	v_pk_add_f32 v[232:233], v[232:233], v[46:47]
	ds_read2_b32 v[32:33], v115 offset0:32 offset1:33
	ds_read2_b32 v[34:35], v115 offset0:34 offset1:35
	ds_read2_b32 v[36:37], v115 offset0:40 offset1:41
	ds_read2_b32 v[38:39], v115 offset0:42 offset1:43
	ds_read2_b32 v[40:41], v115 offset0:48 offset1:49
	ds_read2_b32 v[42:43], v115 offset0:50 offset1:51
	ds_read2_b32 v[44:45], v115 offset0:56 offset1:57
	ds_read2_b32 v[46:47], v115 offset0:58 offset1:59
	s_waitcnt lgkmcnt(15)
	v_mfma_f32_32x32x16_bf16 v[0:15], v[64:67], v[72:75], v[0:15]
	v_mfma_f32_32x32x16_bf16 v[16:31], v[64:67], v[76:79], v[16:31]
	v_mfma_f32_32x32x16_bf16 v[0:15], v[68:71], v[220:223], v[0:15]
	v_mfma_f32_32x32x16_bf16 v[16:31], v[68:71], v[224:227], v[16:31]
	global_load_dwordx4 v[156:159], v243, s[88:89]
	global_load_dwordx4 v[160:163], v244, s[88:89]
	global_load_dwordx4 v[164:167], v245, s[88:89]
	global_load_dwordx4 v[168:171], v246, s[88:89]
	global_load_dwordx4 v[172:175], v148, s[88:89] offset:768
	global_load_dwordx4 v[176:179], v151, s[88:89] offset:768
	global_load_dwordx4 v[180:183], v148, s[88:89] offset:832
	global_load_dwordx4 v[184:187], v151, s[88:89] offset:832
	s_add_u32 s88, s88, 0x300000
	s_addc_u32 s89, s89, 0
	s_waitcnt lgkmcnt(0)
	v_mfma_f32_32x32x16_bf16 v[32:47], v[188:191], v[48:51], v[32:47]
	ds_read_b64_tr_b16 v[72:73], v231
	ds_read_b64_tr_b16 v[74:75], v231 offset:512
	ds_read_b64_tr_b16 v[76:77], v231 offset:2048
	ds_read_b64_tr_b16 v[78:79], v231 offset:2560
	ds_read_b64_tr_b16 v[220:221], v231 offset:1024
	ds_read_b64_tr_b16 v[222:223], v231 offset:1536
	ds_read_b64_tr_b16 v[224:225], v231 offset:3072
	ds_read_b64_tr_b16 v[226:227], v231 offset:3584
	s_waitcnt vmcnt(8)
	ds_write_b128 v247, v[116:119]
	ds_write_b128 v247, v[120:123] offset:1024
	ds_write_b128 v247, v[124:127] offset:2048
	ds_write_b128 v247, v[128:131] offset:3072
	ds_read_b128 v[116:119], v248
	ds_read_b128 v[120:123], v249
	ds_read_b128 v[124:127], v250
	ds_read_b128 v[128:131], v251
	ds_write_b128 v112, v[132:135]
	ds_write_b128 v112, v[136:139] offset:1024
	ds_write_b128 v112, v[140:143] offset:2048
	ds_write_b128 v112, v[144:147] offset:3072
	v_mfma_f32_32x32x16_bf16 v[32:47], v[192:195], v[52:55], v[32:47]
	v_mfma_f32_32x32x16_bf16 v[32:47], v[196:199], v[56:59], v[32:47]
	v_mfma_f32_32x32x16_bf16 v[32:47], v[200:203], v[60:63], v[32:47]
	s_nop 11
	v_exp_f32_e32 v32, v32
	v_exp_f32_e32 v33, v33
	v_exp_f32_e32 v34, v34
	v_exp_f32_e32 v35, v35
	v_exp_f32_e32 v36, v36
	v_exp_f32_e32 v37, v37
	v_exp_f32_e32 v38, v38
	v_exp_f32_e32 v39, v39
	v_exp_f32_e32 v40, v40
	v_exp_f32_e32 v41, v41
	v_exp_f32_e32 v42, v42
	v_exp_f32_e32 v43, v43
	v_exp_f32_e32 v44, v44
	v_exp_f32_e32 v45, v45
	v_exp_f32_e32 v46, v46
	v_exp_f32_e32 v47, v47
	v_cvt_pk_bf16_f32 v64, v32, v33
	v_cvt_pk_bf16_f32 v65, v34, v35
	v_cvt_pk_bf16_f32 v66, v36, v37
	v_cvt_pk_bf16_f32 v67, v38, v39
	v_cvt_pk_bf16_f32 v68, v40, v41
	v_cvt_pk_bf16_f32 v69, v42, v43
	v_cvt_pk_bf16_f32 v70, v44, v45
	v_cvt_pk_bf16_f32 v71, v46, v47
	v_pk_add_f32 v[232:233], v[232:233], v[32:33]
	v_pk_add_f32 v[232:233], v[232:233], v[34:35]
	v_pk_add_f32 v[232:233], v[232:233], v[36:37]
	v_pk_add_f32 v[232:233], v[232:233], v[38:39]
	v_pk_add_f32 v[232:233], v[232:233], v[40:41]
	v_pk_add_f32 v[232:233], v[232:233], v[42:43]
	v_pk_add_f32 v[232:233], v[232:233], v[44:45]
	v_pk_add_f32 v[232:233], v[232:233], v[46:47]
	ds_read2_b32 v[32:33], v115 offset0:64 offset1:65
	ds_read2_b32 v[34:35], v115 offset0:66 offset1:67
	ds_read2_b32 v[36:37], v115 offset0:72 offset1:73
	ds_read2_b32 v[38:39], v115 offset0:74 offset1:75
	ds_read2_b32 v[40:41], v115 offset0:80 offset1:81
	ds_read2_b32 v[42:43], v115 offset0:82 offset1:83
	ds_read2_b32 v[44:45], v115 offset0:88 offset1:89
	ds_read2_b32 v[46:47], v115 offset0:90 offset1:91
	s_waitcnt lgkmcnt(15)
	v_mfma_f32_32x32x16_bf16 v[0:15], v[64:67], v[72:75], v[0:15]
	v_mfma_f32_32x32x16_bf16 v[16:31], v[64:67], v[76:79], v[16:31]
	v_mfma_f32_32x32x16_bf16 v[0:15], v[68:71], v[220:223], v[0:15]
	v_mfma_f32_32x32x16_bf16 v[16:31], v[68:71], v[224:227], v[16:31]
	global_load_dwordx4 v[188:191], v243, s[88:89]
	global_load_dwordx4 v[192:195], v244, s[88:89]
	global_load_dwordx4 v[196:199], v245, s[88:89]
	global_load_dwordx4 v[200:203], v246, s[88:89]
	global_load_dwordx4 v[204:207], v148, s[88:89] offset:768
	global_load_dwordx4 v[208:211], v151, s[88:89] offset:768
	global_load_dwordx4 v[212:215], v148, s[88:89] offset:832
	global_load_dwordx4 v[216:219], v151, s[88:89] offset:832
	s_waitcnt lgkmcnt(0)
	v_mfma_f32_32x32x16_bf16 v[32:47], v[116:119], v[48:51], v[32:47]
	ds_read_b64_tr_b16 v[72:73], v231
	ds_read_b64_tr_b16 v[74:75], v231 offset:512
	ds_read_b64_tr_b16 v[76:77], v231 offset:2048
	ds_read_b64_tr_b16 v[78:79], v231 offset:2560
	ds_read_b64_tr_b16 v[220:221], v231 offset:1024
	ds_read_b64_tr_b16 v[222:223], v231 offset:1536
	ds_read_b64_tr_b16 v[224:225], v231 offset:3072
	ds_read_b64_tr_b16 v[226:227], v231 offset:3584
	s_waitcnt vmcnt(8)
	ds_write_b128 v247, v[156:159]
	ds_write_b128 v247, v[160:163] offset:1024
	ds_write_b128 v247, v[164:167] offset:2048
	ds_write_b128 v247, v[168:171] offset:3072
	ds_read_b128 v[156:159], v248
	ds_read_b128 v[160:163], v249
	ds_read_b128 v[164:167], v250
	ds_read_b128 v[168:171], v251
	ds_write_b128 v112, v[172:175]
	ds_write_b128 v112, v[176:179] offset:1024
	ds_write_b128 v112, v[180:183] offset:2048
	ds_write_b128 v112, v[184:187] offset:3072
	v_mfma_f32_32x32x16_bf16 v[32:47], v[120:123], v[52:55], v[32:47]
	v_mfma_f32_32x32x16_bf16 v[32:47], v[124:127], v[56:59], v[32:47]
	v_mfma_f32_32x32x16_bf16 v[32:47], v[128:131], v[60:63], v[32:47]
	s_nop 11
	v_exp_f32_e32 v32, v32
	v_exp_f32_e32 v33, v33
	v_exp_f32_e32 v34, v34
	v_exp_f32_e32 v35, v35
	v_exp_f32_e32 v36, v36
	v_exp_f32_e32 v37, v37
	v_exp_f32_e32 v38, v38
	v_exp_f32_e32 v39, v39
	v_exp_f32_e32 v40, v40
	v_exp_f32_e32 v41, v41
	v_exp_f32_e32 v42, v42
	v_exp_f32_e32 v43, v43
	v_exp_f32_e32 v44, v44
	v_exp_f32_e32 v45, v45
	v_exp_f32_e32 v46, v46
	v_exp_f32_e32 v47, v47
	v_cvt_pk_bf16_f32 v64, v32, v33
	v_cvt_pk_bf16_f32 v65, v34, v35
	v_cvt_pk_bf16_f32 v66, v36, v37
	v_cvt_pk_bf16_f32 v67, v38, v39
	v_cvt_pk_bf16_f32 v68, v40, v41
	v_cvt_pk_bf16_f32 v69, v42, v43
	v_cvt_pk_bf16_f32 v70, v44, v45
	v_cvt_pk_bf16_f32 v71, v46, v47
	v_pk_add_f32 v[232:233], v[232:233], v[32:33]
	v_pk_add_f32 v[232:233], v[232:233], v[34:35]
	v_pk_add_f32 v[232:233], v[232:233], v[36:37]
	v_pk_add_f32 v[232:233], v[232:233], v[38:39]
	v_pk_add_f32 v[232:233], v[232:233], v[40:41]
	v_pk_add_f32 v[232:233], v[232:233], v[42:43]
	v_pk_add_f32 v[232:233], v[232:233], v[44:45]
	v_pk_add_f32 v[232:233], v[232:233], v[46:47]
	ds_read2_b32 v[32:33], v115 offset0:96 offset1:97
	ds_read2_b32 v[34:35], v115 offset0:98 offset1:99
	ds_read2_b32 v[36:37], v115 offset0:104 offset1:105
	ds_read2_b32 v[38:39], v115 offset0:106 offset1:107
	ds_read2_b32 v[40:41], v115 offset0:112 offset1:113
	ds_read2_b32 v[42:43], v115 offset0:114 offset1:115
	ds_read2_b32 v[44:45], v115 offset0:120 offset1:121
	ds_read2_b32 v[46:47], v115 offset0:122 offset1:123
	s_waitcnt lgkmcnt(15)
; __device__ __forceinline__ int crow(int r, int hi) { return (r & 3) + 8 * (r >> 2) + 4 * hi; }
; __device__ __forceinline__ void dil_unit(LAS unsigned char* lds, bf16_t* proj, int seq, int hd, int T0, int rho) {
;     ...
;     l += __shfl_xor(l, 32);
; #pragma unroll
;     for (int rr = 0; rr < 16; ++rr) {
;         const int j = crow(rr, hi);
;         const float il = __builtin_amdgcn_rcpf(__shfl(l, j));
	v_mfma_f32_32x32x16_bf16 v[0:15], v[64:67], v[72:75], v[0:15]
	v_mfma_f32_32x32x16_bf16 v[16:31], v[64:67], v[76:79], v[16:31]
	v_mfma_f32_32x32x16_bf16 v[0:15], v[68:71], v[220:223], v[0:15]
	v_mfma_f32_32x32x16_bf16 v[16:31], v[68:71], v[224:227], v[16:31]
	s_waitcnt lgkmcnt(0)
	v_mfma_f32_32x32x16_bf16 v[32:47], v[156:159], v[48:51], v[32:47]
	ds_read_b64_tr_b16 v[72:73], v231
	ds_read_b64_tr_b16 v[74:75], v231 offset:512
	ds_read_b64_tr_b16 v[76:77], v231 offset:2048
	ds_read_b64_tr_b16 v[78:79], v231 offset:2560
	ds_read_b64_tr_b16 v[220:221], v231 offset:1024
	ds_read_b64_tr_b16 v[222:223], v231 offset:1536
	ds_read_b64_tr_b16 v[224:225], v231 offset:3072
	ds_read_b64_tr_b16 v[226:227], v231 offset:3584
	s_waitcnt vmcnt(0)
	ds_write_b128 v247, v[188:191]
	ds_write_b128 v247, v[192:195] offset:1024
	ds_write_b128 v247, v[196:199] offset:2048
	ds_write_b128 v247, v[200:203] offset:3072
	ds_read_b128 v[188:191], v248
	ds_read_b128 v[192:195], v249
	ds_read_b128 v[196:199], v250
	ds_read_b128 v[200:203], v251
	ds_write_b128 v112, v[204:207]
	ds_write_b128 v112, v[208:211] offset:1024
	ds_write_b128 v112, v[212:215] offset:2048
	ds_write_b128 v112, v[216:219] offset:3072
	v_mfma_f32_32x32x16_bf16 v[32:47], v[160:163], v[52:55], v[32:47]
	v_mfma_f32_32x32x16_bf16 v[32:47], v[164:167], v[56:59], v[32:47]
	v_mfma_f32_32x32x16_bf16 v[32:47], v[168:171], v[60:63], v[32:47]
	s_nop 11
	v_exp_f32_e32 v32, v32
	v_exp_f32_e32 v33, v33
	v_exp_f32_e32 v34, v34
	v_exp_f32_e32 v35, v35
	v_exp_f32_e32 v36, v36
	v_exp_f32_e32 v37, v37
	v_exp_f32_e32 v38, v38
	v_exp_f32_e32 v39, v39
	v_exp_f32_e32 v40, v40
	v_exp_f32_e32 v41, v41
	v_exp_f32_e32 v42, v42
	v_exp_f32_e32 v43, v43
	v_exp_f32_e32 v44, v44
	v_exp_f32_e32 v45, v45
	v_exp_f32_e32 v46, v46
	v_exp_f32_e32 v47, v47
	v_cvt_pk_bf16_f32 v64, v32, v33
	v_cvt_pk_bf16_f32 v65, v34, v35
	v_cvt_pk_bf16_f32 v66, v36, v37
	v_cvt_pk_bf16_f32 v67, v38, v39
	v_cvt_pk_bf16_f32 v68, v40, v41
	v_cvt_pk_bf16_f32 v69, v42, v43
	v_cvt_pk_bf16_f32 v70, v44, v45
	v_cvt_pk_bf16_f32 v71, v46, v47
	v_pk_add_f32 v[232:233], v[232:233], v[32:33]
	v_pk_add_f32 v[232:233], v[232:233], v[34:35]
	v_pk_add_f32 v[232:233], v[232:233], v[36:37]
	v_pk_add_f32 v[232:233], v[232:233], v[38:39]
	v_pk_add_f32 v[232:233], v[232:233], v[40:41]
	v_pk_add_f32 v[232:233], v[232:233], v[42:43]
	v_pk_add_f32 v[232:233], v[232:233], v[44:45]
	v_pk_add_f32 v[232:233], v[232:233], v[46:47]
	ds_read2_b32 v[32:33], v115 offset0:128 offset1:129
	ds_read2_b32 v[34:35], v115 offset0:130 offset1:131
	ds_read2_b32 v[36:37], v115 offset0:136 offset1:137
	ds_read2_b32 v[38:39], v115 offset0:138 offset1:139
	ds_read2_b32 v[40:41], v115 offset0:144 offset1:145
	ds_read2_b32 v[42:43], v115 offset0:146 offset1:147
	ds_read2_b32 v[44:45], v115 offset0:152 offset1:153
	ds_read2_b32 v[46:47], v115 offset0:154 offset1:155
	s_waitcnt lgkmcnt(15)
	v_mfma_f32_32x32x16_bf16 v[0:15], v[64:67], v[72:75], v[0:15]
	v_mfma_f32_32x32x16_bf16 v[16:31], v[64:67], v[76:79], v[16:31]
	v_mfma_f32_32x32x16_bf16 v[0:15], v[68:71], v[220:223], v[0:15]
	v_mfma_f32_32x32x16_bf16 v[16:31], v[68:71], v[224:227], v[16:31]
	s_waitcnt lgkmcnt(0)
	v_mfma_f32_32x32x16_bf16 v[32:47], v[188:191], v[48:51], v[32:47]
	ds_read_b64_tr_b16 v[72:73], v231
	ds_read_b64_tr_b16 v[74:75], v231 offset:512
	ds_read_b64_tr_b16 v[76:77], v231 offset:2048
	ds_read_b64_tr_b16 v[78:79], v231 offset:2560
	ds_read_b64_tr_b16 v[220:221], v231 offset:1024
	ds_read_b64_tr_b16 v[222:223], v231 offset:1536
	ds_read_b64_tr_b16 v[224:225], v231 offset:3072
	ds_read_b64_tr_b16 v[226:227], v231 offset:3584
	v_mfma_f32_32x32x16_bf16 v[32:47], v[192:195], v[52:55], v[32:47]
	v_mfma_f32_32x32x16_bf16 v[32:47], v[196:199], v[56:59], v[32:47]
	v_mfma_f32_32x32x16_bf16 v[32:47], v[200:203], v[60:63], v[32:47]
	s_nop 11
	v_exp_f32_e32 v32, v32
	v_exp_f32_e32 v33, v33
	v_exp_f32_e32 v34, v34
	v_exp_f32_e32 v35, v35
	v_exp_f32_e32 v36, v36
	v_exp_f32_e32 v37, v37
	v_exp_f32_e32 v38, v38
	v_exp_f32_e32 v39, v39
	v_exp_f32_e32 v40, v40
	v_exp_f32_e32 v41, v41
	v_exp_f32_e32 v42, v42
	v_exp_f32_e32 v43, v43
	v_exp_f32_e32 v44, v44
	v_exp_f32_e32 v45, v45
	v_exp_f32_e32 v46, v46
	v_exp_f32_e32 v47, v47
	v_cvt_pk_bf16_f32 v64, v32, v33
	v_cvt_pk_bf16_f32 v65, v34, v35
	v_cvt_pk_bf16_f32 v66, v36, v37
	v_cvt_pk_bf16_f32 v67, v38, v39
	v_cvt_pk_bf16_f32 v68, v40, v41
	v_cvt_pk_bf16_f32 v69, v42, v43
	v_cvt_pk_bf16_f32 v70, v44, v45
	v_cvt_pk_bf16_f32 v71, v46, v47
	v_pk_add_f32 v[232:233], v[232:233], v[32:33]
	v_pk_add_f32 v[232:233], v[232:233], v[34:35]
	v_pk_add_f32 v[232:233], v[232:233], v[36:37]
	v_pk_add_f32 v[232:233], v[232:233], v[38:39]
	v_pk_add_f32 v[232:233], v[232:233], v[40:41]
	v_pk_add_f32 v[232:233], v[232:233], v[42:43]
	v_pk_add_f32 v[232:233], v[232:233], v[44:45]
	v_pk_add_f32 v[232:233], v[232:233], v[46:47]
	s_waitcnt lgkmcnt(0)
	v_mfma_f32_32x32x16_bf16 v[0:15], v[64:67], v[72:75], v[0:15]
	v_mfma_f32_32x32x16_bf16 v[16:31], v[64:67], v[76:79], v[16:31]
	v_mfma_f32_32x32x16_bf16 v[0:15], v[68:71], v[220:223], v[0:15]
	v_mfma_f32_32x32x16_bf16 v[16:31], v[68:71], v[224:227], v[16:31]
	v_add_f32_e32 v113, v232, v233
	v_or_b32_e32 v114, 1, v107
	v_or_b32_e32 v97, 2, v107
	v_or_b32_e32 v96, 3, v107
	v_or_b32_e32 v95, 8, v107
	v_or_b32_e32 v94, 9, v107
	v_or_b32_e32 v93, 10, v107
	v_or_b32_e32 v92, 11, v107
	v_or_b32_e32 v91, 16, v107
	v_or_b32_e32 v90, 17, v107
	v_or_b32_e32 v89, 18, v107
	v_or_b32_e32 v88, 19, v107
	v_or_b32_e32 v87, 24, v107
	v_or_b32_e32 v86, 25, v107
	v_or_b32_e32 v85, 26, v107
	v_or_b32_e32 v84, 27, v107
	s_nop 11
	s_branch .LBB0_1265
; #define LAS __attribute__((address_space(3)))
; #define GAS __attribute__((address_space(1)))
; __device__ __forceinline__ void dil_unit(LAS unsigned char* lds, bf16_t* proj, int seq, int hd, int T0, int rho) {
;     ...
;     const int tid = tid_, lane = tid & 63, r32 = lane & 31, hi = lane >> 5, wid = __builtin_amdgcn_readfirstlane(tid >> 6);
;     bf16_t* base = proj + (size_t)seq * SEQ * NIN;
;     LAS unsigned char* wbuf = lds + wid * 4096;
;     const LAS unsigned char* vp = wbuf + ((lane >> 4) & 1) * 32 + (lane & 3) * 8 + (4 * hi + ((lane & 15) >> 2)) * 64;
;     const int P0 = T0 + rho;
;     bf16x8 qr[4];
; #pragma unroll
;     for (int ks = 0; ks < 4; ++ks) qr[ks] = *(const GAS bf16x8*)(base + (size_t)(P0 + 16 * r32) * NIN + PC_LQ + hd * 64 + 16 * ks + 8 * hi);
;     f32x16 o0 = {}, o1 = {}; float l = 0.f;
;     const bool bound = (T0 < 1024) || (T0 >= 15360);
.LBB0_1270:
	s_movk_i32 s100, 0x1800
	s_add_i32 s101, s8, 0x15c00
	s_lshl_b32 s90, s54, 1
	s_add_u32 s82, s52, s90
	s_addc_u32 s83, s53, 0
	s_add_u32 s82, s82, 0x1200
	s_addc_u32 s83, s83, 0
	s_sub_i32 s90, s67, 64
	s_mul_i32 s90, s90, 0x1800
	s_add_u32 s84, s82, s90
	s_addc_u32 s85, s83, 0
	s_sub_i32 s90, s67, 256
	s_mul_i32 s90, s90, 0x1800
	s_add_u32 s86, s82, s90
	s_addc_u32 s87, s83, 0
	s_sub_i32 s90, s67, 1024
	s_mul_i32 s90, s90, 0x1800
	s_add_u32 s88, s82, s90
	s_addc_u32 s89, s83, 0
	v_lshlrev_b32_e32 v153, 1, v98
	v_mad_u32_u24 v80, v105, s100, v82
	v_mad_u32_u24 v100, v110, s100, v153
	v_add_u32_e32 v149, 0x18000, v100
	v_lshlrev_b32_e32 v83, 2, v105
	v_mad_u32_u24 v83, v83, s100, v82
	v_lshlrev_b32_e32 v101, 2, v110
	v_mad_u32_u24 v101, v101, s100, v153
	v_add_u32_e32 v150, 0x60000, v101
	v_lshlrev_b32_e32 v99, 4, v105
	v_mad_u32_u24 v99, v99, s100, v82
	v_lshlrev_b32_e32 v148, 4, v110
	v_mad_u32_u24 v148, v148, s100, v153
	v_add_u32_e32 v151, 0x180000, v148
	v_lshrrev_b32_e32 v249, 3, v103
	v_and_b32_e32 v250, 7, v103
	v_lshlrev_b32_e32 v250, 4, v250
	v_add_u32_e32 v235, 0, v249
	v_add_u32_e32 v236, 8, v249
	v_add_u32_e32 v237, 16, v249
	v_add_u32_e32 v238, 24, v249
	v_add_u32_e32 v239, 0, v249
	v_lshlrev_b32_e32 v239, 2, v239
	v_add_u32_e32 v240, 8, v249
	v_lshlrev_b32_e32 v240, 2, v240
	v_add_u32_e32 v241, 16, v249
	v_lshlrev_b32_e32 v241, 2, v241
	v_add_u32_e32 v242, 24, v249
	v_lshlrev_b32_e32 v242, 2, v242
	v_add_u32_e32 v243, 0, v249
	v_lshlrev_b32_e32 v243, 4, v243
	v_add_u32_e32 v244, 8, v249
	v_lshlrev_b32_e32 v244, 4, v244
	v_add_u32_e32 v245, 16, v249
	v_lshlrev_b32_e32 v245, 4, v245
	v_add_u32_e32 v246, 24, v249
	v_lshlrev_b32_e32 v246, 4, v246
	v_mov_b32_e32 v252, v250
	v_mov_b32_e32 v100, v110
	v_add_u32_e32 v149, 16, v100
	v_lshlrev_b32_e32 v101, 2, v110
	v_add_u32_e32 v150, 64, v101
	v_lshlrev_b32_e32 v148, 4, v110
	v_add_u32_e32 v151, 256, v148
	s_mov_b32 s98, 0x4000
	s_mov_b32 s99, 0x3fff
	v_and_b32_e32 v247, 7, v249
	v_lshlrev_b32_e32 v247, 4, v247
	v_xor_b32_e32 v247, v247, v112
	v_and_b32_e32 v153, 7, v105
	v_or_b32_e32 v248, 0, v106
	v_xor_b32_e32 v248, v248, v153
	v_lshlrev_b32_e32 v248, 4, v248
	v_lshl_add_u32 v248, v105, 7, v248
	v_add_u32_e32 v248, s69, v248
	v_or_b32_e32 v249, 2, v106
	v_xor_b32_e32 v249, v249, v153
	v_lshlrev_b32_e32 v249, 4, v249
	v_lshl_add_u32 v249, v105, 7, v249
	v_add_u32_e32 v249, s69, v249
	v_or_b32_e32 v250, 4, v106
	v_xor_b32_e32 v250, v250, v153
	v_lshlrev_b32_e32 v250, 4, v250
	v_lshl_add_u32 v250, v105, 7, v250
	v_add_u32_e32 v250, s69, v250
	v_or_b32_e32 v251, 6, v106
	v_xor_b32_e32 v251, v251, v153
	v_lshlrev_b32_e32 v251, 4, v251
	v_lshl_add_u32 v251, v105, 7, v251
	v_add_u32_e32 v251, s69, v251
	v_lshlrev_b32_e32 v153, 1, v98
	v_mul_u32_u24_e32 v228, 17, v105
	v_sub_u32_e32 v228, v107, v228
	s_mul_i32 s90, s54, 153
	s_lshr_b32 s90, s90, 1
	s_add_i32 s90, s90, 34876
	v_lshl_add_u32 v228, v228, 2, s90
	v_lshlrev_b32_e32 v229, 2, v105
	v_sub_u32_e32 v229, v107, v229
	s_add_i32 s90, s101, 5104
	v_lshl_add_u32 v229, v229, 2, s90
	v_sub_u32_e32 v230, v107, v105
	s_add_i32 s90, s101, 6364
	v_lshl_add_u32 v230, v230, 2, s90
	v_add_u32_e32 v231, v109, v108
	v_mov_b64_e32 v[232:233], 0
	v_mov_b64_e32 v[0:1], 0
	v_mov_b64_e32 v[2:3], 0
	v_mov_b64_e32 v[4:5], 0
	v_mov_b64_e32 v[6:7], 0
	v_mov_b64_e32 v[8:9], 0
	v_mov_b64_e32 v[10:11], 0
	v_mov_b64_e32 v[12:13], 0
	v_mov_b64_e32 v[14:15], 0
	v_mov_b64_e32 v[16:17], 0
	v_mov_b64_e32 v[18:19], 0
	v_mov_b64_e32 v[20:21], 0
	v_mov_b64_e32 v[22:23], 0
	v_mov_b64_e32 v[24:25], 0
	v_mov_b64_e32 v[26:27], 0
	v_mov_b64_e32 v[28:29], 0
	v_mov_b64_e32 v[30:31], 0
	s_add_i32 s90, s67, -64
	v_add_u32_e32 v80, s90, v235
	v_add_u32_e32 v83, s90, v236
	v_add_u32_e32 v99, s90, v237
	v_add_u32_e32 v253, s90, v238
	v_add_u32_e32 v254, s90, v100
	v_add_u32_e32 v255, s90, v149
	v_med3_i32 v80, v80, 0, s99
	v_med3_i32 v83, v83, 0, s99
	v_med3_i32 v99, v99, 0, s99
	v_med3_i32 v253, v253, 0, s99
	v_med3_i32 v254, v254, 0, s99
	v_med3_i32 v255, v255, 0, s99
	v_mad_u32_u24 v80, v80, s100, v252
	v_mad_u32_u24 v83, v83, s100, v252
	v_mad_u32_u24 v99, v99, s100, v252
	v_mad_u32_u24 v253, v253, s100, v252
	v_mad_u32_u24 v254, v254, s100, v153
	v_mad_u32_u24 v255, v255, s100, v153
	global_load_dwordx4 v[116:119], v80, s[82:83]
	global_load_dwordx4 v[120:123], v83, s[82:83]
	global_load_dwordx4 v[124:127], v99, s[82:83]
	global_load_dwordx4 v[128:131], v253, s[82:83]
	global_load_dwordx4 v[132:135], v254, s[82:83] offset:768
	global_load_dwordx4 v[136:139], v255, s[82:83] offset:768
	global_load_dwordx4 v[140:143], v254, s[82:83] offset:832
	global_load_dwordx4 v[144:147], v255, s[82:83] offset:832
	s_add_i32 s90, s67, -32
	v_add_u32_e32 v80, s90, v235
	v_add_u32_e32 v83, s90, v236
	v_add_u32_e32 v99, s90, v237
	v_add_u32_e32 v253, s90, v238
	v_add_u32_e32 v254, s90, v100
	v_add_u32_e32 v255, s90, v149
	v_med3_i32 v80, v80, 0, s99
	v_med3_i32 v83, v83, 0, s99
	v_med3_i32 v99, v99, 0, s99
	v_med3_i32 v253, v253, 0, s99
	v_med3_i32 v254, v254, 0, s99
	v_med3_i32 v255, v255, 0, s99
	v_mad_u32_u24 v80, v80, s100, v252
	v_mad_u32_u24 v83, v83, s100, v252
	v_mad_u32_u24 v99, v99, s100, v252
	v_mad_u32_u24 v253, v253, s100, v252
	v_mad_u32_u24 v254, v254, s100, v153
	v_mad_u32_u24 v255, v255, s100, v153
	global_load_dwordx4 v[156:159], v80, s[82:83]
	global_load_dwordx4 v[160:163], v83, s[82:83]
	global_load_dwordx4 v[164:167], v99, s[82:83]
	global_load_dwordx4 v[168:171], v253, s[82:83]
	global_load_dwordx4 v[172:175], v254, s[82:83] offset:768
	global_load_dwordx4 v[176:179], v255, s[82:83] offset:768
	global_load_dwordx4 v[180:183], v254, s[82:83] offset:832
	global_load_dwordx4 v[184:187], v255, s[82:83] offset:832
	s_add_i32 s90, s67, 0
	v_add_u32_e32 v80, s90, v235
	v_add_u32_e32 v83, s90, v236
	v_add_u32_e32 v99, s90, v237
	v_add_u32_e32 v253, s90, v238
	v_add_u32_e32 v254, s90, v100
	v_add_u32_e32 v255, s90, v149
	v_med3_i32 v80, v80, 0, s99
	v_med3_i32 v83, v83, 0, s99
	v_med3_i32 v99, v99, 0, s99
	v_med3_i32 v253, v253, 0, s99
	v_med3_i32 v254, v254, 0, s99
	v_med3_i32 v255, v255, 0, s99
	v_mad_u32_u24 v80, v80, s100, v252
	v_mad_u32_u24 v83, v83, s100, v252
	v_mad_u32_u24 v99, v99, s100, v252
	v_mad_u32_u24 v253, v253, s100, v252
	v_mad_u32_u24 v254, v254, s100, v153
	v_mad_u32_u24 v255, v255, s100, v153
	global_load_dwordx4 v[188:191], v80, s[82:83]
	global_load_dwordx4 v[192:195], v83, s[82:83]
	global_load_dwordx4 v[196:199], v99, s[82:83]
	global_load_dwordx4 v[200:203], v253, s[82:83]
	global_load_dwordx4 v[204:207], v254, s[82:83] offset:768
	global_load_dwordx4 v[208:211], v255, s[82:83] offset:768
	global_load_dwordx4 v[212:215], v254, s[82:83] offset:832
	global_load_dwordx4 v[216:219], v255, s[82:83] offset:832
	s_waitcnt vmcnt(16)
	ds_write_b128 v247, v[116:119]
	ds_write_b128 v247, v[120:123] offset:1024
	ds_write_b128 v247, v[124:127] offset:2048
	ds_write_b128 v247, v[128:131] offset:3072
	ds_read_b128 v[116:119], v248
	ds_read_b128 v[120:123], v249
	ds_read_b128 v[124:127], v250
	ds_read_b128 v[128:131], v251
	ds_write_b128 v112, v[132:135]
	ds_write_b128 v112, v[136:139] offset:1024
	ds_write_b128 v112, v[140:143] offset:2048
	ds_write_b128 v112, v[144:147] offset:3072
	v_mov_b32_e32 v115, v228
	ds_read2_b32 v[32:33], v115 offset0:0 offset1:1
	ds_read2_b32 v[34:35], v115 offset0:2 offset1:3
	ds_read2_b32 v[36:37], v115 offset0:8 offset1:9
	ds_read2_b32 v[38:39], v115 offset0:10 offset1:11
	ds_read2_b32 v[40:41], v115 offset0:17 offset1:18
	ds_read2_b32 v[42:43], v115 offset0:19 offset1:20
	ds_read2_b32 v[44:45], v115 offset0:25 offset1:26
	ds_read2_b32 v[46:47], v115 offset0:27 offset1:28
	s_waitcnt lgkmcnt(0)
	v_mfma_f32_32x32x16_bf16 v[32:47], v[116:119], v[48:51], v[32:47]
	ds_read_b64_tr_b16 v[72:73], v231
	ds_read_b64_tr_b16 v[74:75], v231 offset:512
	ds_read_b64_tr_b16 v[76:77], v231 offset:2048
	ds_read_b64_tr_b16 v[78:79], v231 offset:2560
	ds_read_b64_tr_b16 v[220:221], v231 offset:1024
	ds_read_b64_tr_b16 v[222:223], v231 offset:1536
	ds_read_b64_tr_b16 v[224:225], v231 offset:3072
	ds_read_b64_tr_b16 v[226:227], v231 offset:3584
	s_waitcnt vmcnt(8)
	ds_write_b128 v247, v[156:159]
	ds_write_b128 v247, v[160:163] offset:1024
	ds_write_b128 v247, v[164:167] offset:2048
	ds_write_b128 v247, v[168:171] offset:3072
	ds_read_b128 v[156:159], v248
	ds_read_b128 v[160:163], v249
	ds_read_b128 v[164:167], v250
	ds_read_b128 v[168:171], v251
	ds_write_b128 v112, v[172:175]
	ds_write_b128 v112, v[176:179] offset:1024
	ds_write_b128 v112, v[180:183] offset:2048
	ds_write_b128 v112, v[184:187] offset:3072
	v_mfma_f32_32x32x16_bf16 v[32:47], v[120:123], v[52:55], v[32:47]
	v_mfma_f32_32x32x16_bf16 v[32:47], v[124:127], v[56:59], v[32:47]
	v_mfma_f32_32x32x16_bf16 v[32:47], v[128:131], v[60:63], v[32:47]
	s_nop 11
	v_exp_f32_e32 v32, v32
	v_exp_f32_e32 v33, v33
	v_exp_f32_e32 v34, v34
	v_exp_f32_e32 v35, v35
	v_exp_f32_e32 v36, v36
	v_exp_f32_e32 v37, v37
	v_exp_f32_e32 v38, v38
	v_exp_f32_e32 v39, v39
	v_exp_f32_e32 v40, v40
	v_exp_f32_e32 v41, v41
	v_exp_f32_e32 v42, v42
	v_exp_f32_e32 v43, v43
	v_exp_f32_e32 v44, v44
	v_exp_f32_e32 v45, v45
	v_exp_f32_e32 v46, v46
	v_exp_f32_e32 v47, v47
	s_add_i32 s90, s67, -64
	v_add_u32_e32 v84, s90, v107
	v_add_u32_e32 v85, 0, v84
	v_add_u32_e32 v86, 1, v84
	v_add_u32_e32 v87, 2, v84
	v_add_u32_e32 v88, 3, v84
	v_cmp_gt_u32_e64 s[30:31], s98, v85
	v_cmp_gt_u32_e64 s[36:37], s98, v86
	v_cmp_gt_u32_e64 s[78:79], s98, v87
	v_cmp_gt_u32_e64 s[50:51], s98, v88
	v_cndmask_b32_e64 v32, 0, v32, s[30:31]
	v_add_u32_e32 v85, 8, v84
	v_cmp_gt_u32_e64 s[30:31], s98, v85
	v_cndmask_b32_e64 v33, 0, v33, s[36:37]
	v_add_u32_e32 v86, 9, v84
	v_cmp_gt_u32_e64 s[36:37], s98, v86
	v_cndmask_b32_e64 v34, 0, v34, s[78:79]
	v_add_u32_e32 v87, 10, v84
	v_cmp_gt_u32_e64 s[78:79], s98, v87
	v_cndmask_b32_e64 v35, 0, v35, s[50:51]
	v_add_u32_e32 v88, 11, v84
	v_cmp_gt_u32_e64 s[50:51], s98, v88
	v_cndmask_b32_e64 v36, 0, v36, s[30:31]
	v_add_u32_e32 v85, 16, v84
	v_cmp_gt_u32_e64 s[30:31], s98, v85
	v_cndmask_b32_e64 v37, 0, v37, s[36:37]
	v_add_u32_e32 v86, 17, v84
	v_cmp_gt_u32_e64 s[36:37], s98, v86
	v_cndmask_b32_e64 v38, 0, v38, s[78:79]
	v_add_u32_e32 v87, 18, v84
	v_cmp_gt_u32_e64 s[78:79], s98, v87
	v_cndmask_b32_e64 v39, 0, v39, s[50:51]
	v_add_u32_e32 v88, 19, v84
	v_cmp_gt_u32_e64 s[50:51], s98, v88
	v_cndmask_b32_e64 v40, 0, v40, s[30:31]
	v_add_u32_e32 v85, 24, v84
	v_cmp_gt_u32_e64 s[30:31], s98, v85
	v_cndmask_b32_e64 v41, 0, v41, s[36:37]
	v_add_u32_e32 v86, 25, v84
	v_cmp_gt_u32_e64 s[36:37], s98, v86
	v_cndmask_b32_e64 v42, 0, v42, s[78:79]
	v_add_u32_e32 v87, 26, v84
	v_cmp_gt_u32_e64 s[78:79], s98, v87
	v_cndmask_b32_e64 v43, 0, v43, s[50:51]
	v_add_u32_e32 v88, 27, v84
	v_cmp_gt_u32_e64 s[50:51], s98, v88
	v_nop
	v_cndmask_b32_e64 v44, 0, v44, s[30:31]
	v_cndmask_b32_e64 v45, 0, v45, s[36:37]
	v_cndmask_b32_e64 v46, 0, v46, s[78:79]
	v_cndmask_b32_e64 v47, 0, v47, s[50:51]
	v_cvt_pk_bf16_f32 v64, v32, v33
	v_cvt_pk_bf16_f32 v65, v34, v35
	v_cvt_pk_bf16_f32 v66, v36, v37
	v_cvt_pk_bf16_f32 v67, v38, v39
	v_cvt_pk_bf16_f32 v68, v40, v41
	v_cvt_pk_bf16_f32 v69, v42, v43
	v_cvt_pk_bf16_f32 v70, v44, v45
	v_cvt_pk_bf16_f32 v71, v46, v47
	v_pk_add_f32 v[232:233], v[232:233], v[32:33]
	v_pk_add_f32 v[232:233], v[232:233], v[34:35]
	v_pk_add_f32 v[232:233], v[232:233], v[36:37]
	v_pk_add_f32 v[232:233], v[232:233], v[38:39]
	v_pk_add_f32 v[232:233], v[232:233], v[40:41]
	v_pk_add_f32 v[232:233], v[232:233], v[42:43]
	v_pk_add_f32 v[232:233], v[232:233], v[44:45]
	v_pk_add_f32 v[232:233], v[232:233], v[46:47]
	ds_read2_b32 v[32:33], v115 offset0:34 offset1:35
	ds_read2_b32 v[34:35], v115 offset0:36 offset1:37
	ds_read2_b32 v[36:37], v115 offset0:42 offset1:43
	ds_read2_b32 v[38:39], v115 offset0:44 offset1:45
	ds_read2_b32 v[40:41], v115 offset0:51 offset1:52
	ds_read2_b32 v[42:43], v115 offset0:53 offset1:54
	ds_read2_b32 v[44:45], v115 offset0:59 offset1:60
	ds_read2_b32 v[46:47], v115 offset0:61 offset1:62
	s_waitcnt lgkmcnt(15)
	v_mfma_f32_32x32x16_bf16 v[0:15], v[64:67], v[72:75], v[0:15]
	v_mfma_f32_32x32x16_bf16 v[16:31], v[64:67], v[76:79], v[16:31]
	v_mfma_f32_32x32x16_bf16 v[0:15], v[68:71], v[220:223], v[0:15]
	v_mfma_f32_32x32x16_bf16 v[16:31], v[68:71], v[224:227], v[16:31]
	s_add_i32 s90, s67, 32
	v_add_u32_e32 v80, s90, v235
	v_add_u32_e32 v83, s90, v236
	v_add_u32_e32 v99, s90, v237
	v_add_u32_e32 v253, s90, v238
	v_add_u32_e32 v254, s90, v100
	v_add_u32_e32 v255, s90, v149
	v_med3_i32 v80, v80, 0, s99
	v_med3_i32 v83, v83, 0, s99
	v_med3_i32 v99, v99, 0, s99
	v_med3_i32 v253, v253, 0, s99
	v_med3_i32 v254, v254, 0, s99
	v_med3_i32 v255, v255, 0, s99
	v_mad_u32_u24 v80, v80, s100, v252
	v_mad_u32_u24 v83, v83, s100, v252
	v_mad_u32_u24 v99, v99, s100, v252
	v_mad_u32_u24 v253, v253, s100, v252
	v_mad_u32_u24 v254, v254, s100, v153
	v_mad_u32_u24 v255, v255, s100, v153
	global_load_dwordx4 v[116:119], v80, s[82:83]
	global_load_dwordx4 v[120:123], v83, s[82:83]
	global_load_dwordx4 v[124:127], v99, s[82:83]
	global_load_dwordx4 v[128:131], v253, s[82:83]
	global_load_dwordx4 v[132:135], v254, s[82:83] offset:768
	global_load_dwordx4 v[136:139], v255, s[82:83] offset:768
	global_load_dwordx4 v[140:143], v254, s[82:83] offset:832
	global_load_dwordx4 v[144:147], v255, s[82:83] offset:832
	s_waitcnt lgkmcnt(0)
	v_mfma_f32_32x32x16_bf16 v[32:47], v[156:159], v[48:51], v[32:47]
	ds_read_b64_tr_b16 v[72:73], v231
	ds_read_b64_tr_b16 v[74:75], v231 offset:512
	ds_read_b64_tr_b16 v[76:77], v231 offset:2048
	ds_read_b64_tr_b16 v[78:79], v231 offset:2560
	ds_read_b64_tr_b16 v[220:221], v231 offset:1024
	ds_read_b64_tr_b16 v[222:223], v231 offset:1536
	ds_read_b64_tr_b16 v[224:225], v231 offset:3072
	ds_read_b64_tr_b16 v[226:227], v231 offset:3584
	s_waitcnt vmcnt(8)
	ds_write_b128 v247, v[188:191]
	ds_write_b128 v247, v[192:195] offset:1024
	ds_write_b128 v247, v[196:199] offset:2048
	ds_write_b128 v247, v[200:203] offset:3072
	ds_read_b128 v[188:191], v248
	ds_read_b128 v[192:195], v249
	ds_read_b128 v[196:199], v250
	ds_read_b128 v[200:203], v251
	ds_write_b128 v112, v[204:207]
	ds_write_b128 v112, v[208:211] offset:1024
	ds_write_b128 v112, v[212:215] offset:2048
	ds_write_b128 v112, v[216:219] offset:3072
	v_mfma_f32_32x32x16_bf16 v[32:47], v[160:163], v[52:55], v[32:47]
	v_mfma_f32_32x32x16_bf16 v[32:47], v[164:167], v[56:59], v[32:47]
	v_mfma_f32_32x32x16_bf16 v[32:47], v[168:171], v[60:63], v[32:47]
	s_nop 11
	v_exp_f32_e32 v32, v32
	v_exp_f32_e32 v33, v33
	v_exp_f32_e32 v34, v34
	v_exp_f32_e32 v35, v35
	v_exp_f32_e32 v36, v36
	v_exp_f32_e32 v37, v37
	v_exp_f32_e32 v38, v38
	v_exp_f32_e32 v39, v39
	v_exp_f32_e32 v40, v40
	v_exp_f32_e32 v41, v41
	v_exp_f32_e32 v42, v42
	v_exp_f32_e32 v43, v43
	v_exp_f32_e32 v44, v44
	v_exp_f32_e32 v45, v45
	v_exp_f32_e32 v46, v46
	v_exp_f32_e32 v47, v47
	s_add_i32 s90, s67, -32
	v_add_u32_e32 v84, s90, v107
	v_add_u32_e32 v85, 0, v84
	v_add_u32_e32 v86, 1, v84
	v_add_u32_e32 v87, 2, v84
	v_add_u32_e32 v88, 3, v84
	v_cmp_gt_u32_e64 s[30:31], s98, v85
	v_cmp_gt_u32_e64 s[36:37], s98, v86
	v_cmp_gt_u32_e64 s[78:79], s98, v87
	v_cmp_gt_u32_e64 s[50:51], s98, v88
	v_cndmask_b32_e64 v32, 0, v32, s[30:31]
	v_add_u32_e32 v85, 8, v84
	v_cmp_gt_u32_e64 s[30:31], s98, v85
	v_cndmask_b32_e64 v33, 0, v33, s[36:37]
	v_add_u32_e32 v86, 9, v84
	v_cmp_gt_u32_e64 s[36:37], s98, v86
	v_cndmask_b32_e64 v34, 0, v34, s[78:79]
	v_add_u32_e32 v87, 10, v84
	v_cmp_gt_u32_e64 s[78:79], s98, v87
	v_cndmask_b32_e64 v35, 0, v35, s[50:51]
	v_add_u32_e32 v88, 11, v84
	v_cmp_gt_u32_e64 s[50:51], s98, v88
	v_cndmask_b32_e64 v36, 0, v36, s[30:31]
	v_add_u32_e32 v85, 16, v84
	v_cmp_gt_u32_e64 s[30:31], s98, v85
	v_cndmask_b32_e64 v37, 0, v37, s[36:37]
	v_add_u32_e32 v86, 17, v84
	v_cmp_gt_u32_e64 s[36:37], s98, v86
	v_cndmask_b32_e64 v38, 0, v38, s[78:79]
	v_add_u32_e32 v87, 18, v84
	v_cmp_gt_u32_e64 s[78:79], s98, v87
	v_cndmask_b32_e64 v39, 0, v39, s[50:51]
	v_add_u32_e32 v88, 19, v84
	v_cmp_gt_u32_e64 s[50:51], s98, v88
	v_cndmask_b32_e64 v40, 0, v40, s[30:31]
	v_add_u32_e32 v85, 24, v84
	v_cmp_gt_u32_e64 s[30:31], s98, v85
	v_cndmask_b32_e64 v41, 0, v41, s[36:37]
	v_add_u32_e32 v86, 25, v84
	v_cmp_gt_u32_e64 s[36:37], s98, v86
	v_cndmask_b32_e64 v42, 0, v42, s[78:79]
	v_add_u32_e32 v87, 26, v84
	v_cmp_gt_u32_e64 s[78:79], s98, v87
	v_cndmask_b32_e64 v43, 0, v43, s[50:51]
	v_add_u32_e32 v88, 27, v84
	v_cmp_gt_u32_e64 s[50:51], s98, v88
	v_nop
	v_cndmask_b32_e64 v44, 0, v44, s[30:31]
	v_cndmask_b32_e64 v45, 0, v45, s[36:37]
	v_cndmask_b32_e64 v46, 0, v46, s[78:79]
	v_cndmask_b32_e64 v47, 0, v47, s[50:51]
	v_cvt_pk_bf16_f32 v64, v32, v33
	v_cvt_pk_bf16_f32 v65, v34, v35
	v_cvt_pk_bf16_f32 v66, v36, v37
	v_cvt_pk_bf16_f32 v67, v38, v39
	v_cvt_pk_bf16_f32 v68, v40, v41
	v_cvt_pk_bf16_f32 v69, v42, v43
	v_cvt_pk_bf16_f32 v70, v44, v45
	v_cvt_pk_bf16_f32 v71, v46, v47
	v_pk_add_f32 v[232:233], v[232:233], v[32:33]
	v_pk_add_f32 v[232:233], v[232:233], v[34:35]
	v_pk_add_f32 v[232:233], v[232:233], v[36:37]
	v_pk_add_f32 v[232:233], v[232:233], v[38:39]
	v_pk_add_f32 v[232:233], v[232:233], v[40:41]
	v_pk_add_f32 v[232:233], v[232:233], v[42:43]
	v_pk_add_f32 v[232:233], v[232:233], v[44:45]
	v_pk_add_f32 v[232:233], v[232:233], v[46:47]
	ds_read2_b32 v[32:33], v115 offset0:68 offset1:69
	ds_read2_b32 v[34:35], v115 offset0:70 offset1:71
	ds_read2_b32 v[36:37], v115 offset0:76 offset1:77
	ds_read2_b32 v[38:39], v115 offset0:78 offset1:79
	ds_read2_b32 v[40:41], v115 offset0:85 offset1:86
	ds_read2_b32 v[42:43], v115 offset0:87 offset1:88
	ds_read2_b32 v[44:45], v115 offset0:93 offset1:94
	ds_read2_b32 v[46:47], v115 offset0:95 offset1:96
	s_waitcnt lgkmcnt(15)
	v_mfma_f32_32x32x16_bf16 v[0:15], v[64:67], v[72:75], v[0:15]
	v_mfma_f32_32x32x16_bf16 v[16:31], v[64:67], v[76:79], v[16:31]
	v_mfma_f32_32x32x16_bf16 v[0:15], v[68:71], v[220:223], v[0:15]
	v_mfma_f32_32x32x16_bf16 v[16:31], v[68:71], v[224:227], v[16:31]
	s_add_i32 s90, s67, 64
	v_add_u32_e32 v80, s90, v235
	v_add_u32_e32 v83, s90, v236
	v_add_u32_e32 v99, s90, v237
	v_add_u32_e32 v253, s90, v238
	v_add_u32_e32 v254, s90, v100
	v_add_u32_e32 v255, s90, v149
	v_med3_i32 v80, v80, 0, s99
	v_med3_i32 v83, v83, 0, s99
	v_med3_i32 v99, v99, 0, s99
	v_med3_i32 v253, v253, 0, s99
	v_med3_i32 v254, v254, 0, s99
	v_med3_i32 v255, v255, 0, s99
	v_mad_u32_u24 v80, v80, s100, v252
	v_mad_u32_u24 v83, v83, s100, v252
	v_mad_u32_u24 v99, v99, s100, v252
	v_mad_u32_u24 v253, v253, s100, v252
	v_mad_u32_u24 v254, v254, s100, v153
	v_mad_u32_u24 v255, v255, s100, v153
	global_load_dwordx4 v[156:159], v80, s[82:83]
	global_load_dwordx4 v[160:163], v83, s[82:83]
	global_load_dwordx4 v[164:167], v99, s[82:83]
	global_load_dwordx4 v[168:171], v253, s[82:83]
	global_load_dwordx4 v[172:175], v254, s[82:83] offset:768
	global_load_dwordx4 v[176:179], v255, s[82:83] offset:768
	global_load_dwordx4 v[180:183], v254, s[82:83] offset:832
	global_load_dwordx4 v[184:187], v255, s[82:83] offset:832
	s_waitcnt lgkmcnt(0)
	v_mfma_f32_32x32x16_bf16 v[32:47], v[188:191], v[48:51], v[32:47]
	ds_read_b64_tr_b16 v[72:73], v231
	ds_read_b64_tr_b16 v[74:75], v231 offset:512
	ds_read_b64_tr_b16 v[76:77], v231 offset:2048
	ds_read_b64_tr_b16 v[78:79], v231 offset:2560
	ds_read_b64_tr_b16 v[220:221], v231 offset:1024
	ds_read_b64_tr_b16 v[222:223], v231 offset:1536
	ds_read_b64_tr_b16 v[224:225], v231 offset:3072
	ds_read_b64_tr_b16 v[226:227], v231 offset:3584
	s_waitcnt vmcnt(8)
	ds_write_b128 v247, v[116:119]
	ds_write_b128 v247, v[120:123] offset:1024
	ds_write_b128 v247, v[124:127] offset:2048
	ds_write_b128 v247, v[128:131] offset:3072
	ds_read_b128 v[116:119], v248
	ds_read_b128 v[120:123], v249
	ds_read_b128 v[124:127], v250
	ds_read_b128 v[128:131], v251
	ds_write_b128 v112, v[132:135]
	ds_write_b128 v112, v[136:139] offset:1024
	ds_write_b128 v112, v[140:143] offset:2048
	ds_write_b128 v112, v[144:147] offset:3072
	v_mfma_f32_32x32x16_bf16 v[32:47], v[192:195], v[52:55], v[32:47]
	v_mfma_f32_32x32x16_bf16 v[32:47], v[196:199], v[56:59], v[32:47]
	v_mfma_f32_32x32x16_bf16 v[32:47], v[200:203], v[60:63], v[32:47]
	s_nop 11
	v_exp_f32_e32 v32, v32
	v_exp_f32_e32 v33, v33
	v_exp_f32_e32 v34, v34
	v_exp_f32_e32 v35, v35
	v_exp_f32_e32 v36, v36
	v_exp_f32_e32 v37, v37
	v_exp_f32_e32 v38, v38
	v_exp_f32_e32 v39, v39
	v_exp_f32_e32 v40, v40
	v_exp_f32_e32 v41, v41
	v_exp_f32_e32 v42, v42
	v_exp_f32_e32 v43, v43
	v_exp_f32_e32 v44, v44
	v_exp_f32_e32 v45, v45
	v_exp_f32_e32 v46, v46
	v_exp_f32_e32 v47, v47
	s_add_i32 s90, s67, 0
	v_add_u32_e32 v84, s90, v107
	v_add_u32_e32 v85, 0, v84
	v_add_u32_e32 v86, 1, v84
	v_add_u32_e32 v87, 2, v84
	v_add_u32_e32 v88, 3, v84
	v_cmp_gt_u32_e64 s[30:31], s98, v85
	v_cmp_gt_u32_e64 s[36:37], s98, v86
	v_cmp_gt_u32_e64 s[78:79], s98, v87
	v_cmp_gt_u32_e64 s[50:51], s98, v88
	v_cndmask_b32_e64 v32, 0, v32, s[30:31]
	v_add_u32_e32 v85, 8, v84
	v_cmp_gt_u32_e64 s[30:31], s98, v85
	v_cndmask_b32_e64 v33, 0, v33, s[36:37]
	v_add_u32_e32 v86, 9, v84
	v_cmp_gt_u32_e64 s[36:37], s98, v86
	v_cndmask_b32_e64 v34, 0, v34, s[78:79]
	v_add_u32_e32 v87, 10, v84
	v_cmp_gt_u32_e64 s[78:79], s98, v87
	v_cndmask_b32_e64 v35, 0, v35, s[50:51]
	v_add_u32_e32 v88, 11, v84
	v_cmp_gt_u32_e64 s[50:51], s98, v88
	v_cndmask_b32_e64 v36, 0, v36, s[30:31]
	v_add_u32_e32 v85, 16, v84
	v_cmp_gt_u32_e64 s[30:31], s98, v85
	v_cndmask_b32_e64 v37, 0, v37, s[36:37]
	v_add_u32_e32 v86, 17, v84
	v_cmp_gt_u32_e64 s[36:37], s98, v86
	v_cndmask_b32_e64 v38, 0, v38, s[78:79]
	v_add_u32_e32 v87, 18, v84
	v_cmp_gt_u32_e64 s[78:79], s98, v87
	v_cndmask_b32_e64 v39, 0, v39, s[50:51]
	v_add_u32_e32 v88, 19, v84
	v_cmp_gt_u32_e64 s[50:51], s98, v88
	v_cndmask_b32_e64 v40, 0, v40, s[30:31]
	v_add_u32_e32 v85, 24, v84
	v_cmp_gt_u32_e64 s[30:31], s98, v85
	v_cndmask_b32_e64 v41, 0, v41, s[36:37]
	v_add_u32_e32 v86, 25, v84
	v_cmp_gt_u32_e64 s[36:37], s98, v86
	v_cndmask_b32_e64 v42, 0, v42, s[78:79]
	v_add_u32_e32 v87, 26, v84
	v_cmp_gt_u32_e64 s[78:79], s98, v87
	v_cndmask_b32_e64 v43, 0, v43, s[50:51]
	v_add_u32_e32 v88, 27, v84
	v_cmp_gt_u32_e64 s[50:51], s98, v88
	v_nop
	v_cndmask_b32_e64 v44, 0, v44, s[30:31]
	v_cndmask_b32_e64 v45, 0, v45, s[36:37]
	v_cndmask_b32_e64 v46, 0, v46, s[78:79]
	v_cndmask_b32_e64 v47, 0, v47, s[50:51]
	v_cvt_pk_bf16_f32 v64, v32, v33
	v_cvt_pk_bf16_f32 v65, v34, v35
	v_cvt_pk_bf16_f32 v66, v36, v37
	v_cvt_pk_bf16_f32 v67, v38, v39
	v_cvt_pk_bf16_f32 v68, v40, v41
	v_cvt_pk_bf16_f32 v69, v42, v43
	v_cvt_pk_bf16_f32 v70, v44, v45
	v_cvt_pk_bf16_f32 v71, v46, v47
	v_pk_add_f32 v[232:233], v[232:233], v[32:33]
	v_pk_add_f32 v[232:233], v[232:233], v[34:35]
	v_pk_add_f32 v[232:233], v[232:233], v[36:37]
	v_pk_add_f32 v[232:233], v[232:233], v[38:39]
	v_pk_add_f32 v[232:233], v[232:233], v[40:41]
	v_pk_add_f32 v[232:233], v[232:233], v[42:43]
	v_pk_add_f32 v[232:233], v[232:233], v[44:45]
	v_pk_add_f32 v[232:233], v[232:233], v[46:47]
	ds_read2_b32 v[32:33], v115 offset0:102 offset1:103
	ds_read2_b32 v[34:35], v115 offset0:104 offset1:105
	ds_read2_b32 v[36:37], v115 offset0:110 offset1:111
	ds_read2_b32 v[38:39], v115 offset0:112 offset1:113
	ds_read2_b32 v[40:41], v115 offset0:119 offset1:120
	ds_read2_b32 v[42:43], v115 offset0:121 offset1:122
	ds_read2_b32 v[44:45], v115 offset0:127 offset1:128
	ds_read2_b32 v[46:47], v115 offset0:129 offset1:130
	s_waitcnt lgkmcnt(15)
	v_mfma_f32_32x32x16_bf16 v[0:15], v[64:67], v[72:75], v[0:15]
	v_mfma_f32_32x32x16_bf16 v[16:31], v[64:67], v[76:79], v[16:31]
	v_mfma_f32_32x32x16_bf16 v[0:15], v[68:71], v[220:223], v[0:15]
	v_mfma_f32_32x32x16_bf16 v[16:31], v[68:71], v[224:227], v[16:31]
	s_add_i32 s90, s67, 96
	v_add_u32_e32 v80, s90, v235
	v_add_u32_e32 v83, s90, v236
	v_add_u32_e32 v99, s90, v237
	v_add_u32_e32 v253, s90, v238
	v_add_u32_e32 v254, s90, v100
	v_add_u32_e32 v255, s90, v149
	v_med3_i32 v80, v80, 0, s99
	v_med3_i32 v83, v83, 0, s99
	v_med3_i32 v99, v99, 0, s99
	v_med3_i32 v253, v253, 0, s99
	v_med3_i32 v254, v254, 0, s99
	v_med3_i32 v255, v255, 0, s99
	v_mad_u32_u24 v80, v80, s100, v252
	v_mad_u32_u24 v83, v83, s100, v252
	v_mad_u32_u24 v99, v99, s100, v252
	v_mad_u32_u24 v253, v253, s100, v252
	v_mad_u32_u24 v254, v254, s100, v153
	v_mad_u32_u24 v255, v255, s100, v153
	global_load_dwordx4 v[188:191], v80, s[82:83]
	global_load_dwordx4 v[192:195], v83, s[82:83]
	global_load_dwordx4 v[196:199], v99, s[82:83]
	global_load_dwordx4 v[200:203], v253, s[82:83]
	global_load_dwordx4 v[204:207], v254, s[82:83] offset:768
	global_load_dwordx4 v[208:211], v255, s[82:83] offset:768
	global_load_dwordx4 v[212:215], v254, s[82:83] offset:832
	global_load_dwordx4 v[216:219], v255, s[82:83] offset:832
	s_waitcnt lgkmcnt(0)
	v_mfma_f32_32x32x16_bf16 v[32:47], v[116:119], v[48:51], v[32:47]
	ds_read_b64_tr_b16 v[72:73], v231
	ds_read_b64_tr_b16 v[74:75], v231 offset:512
	ds_read_b64_tr_b16 v[76:77], v231 offset:2048
	ds_read_b64_tr_b16 v[78:79], v231 offset:2560
	ds_read_b64_tr_b16 v[220:221], v231 offset:1024
	ds_read_b64_tr_b16 v[222:223], v231 offset:1536
	ds_read_b64_tr_b16 v[224:225], v231 offset:3072
	ds_read_b64_tr_b16 v[226:227], v231 offset:3584
	s_waitcnt vmcnt(8)
	ds_write_b128 v247, v[156:159]
	ds_write_b128 v247, v[160:163] offset:1024
	ds_write_b128 v247, v[164:167] offset:2048
	ds_write_b128 v247, v[168:171] offset:3072
	ds_read_b128 v[156:159], v248
	ds_read_b128 v[160:163], v249
	ds_read_b128 v[164:167], v250
	ds_read_b128 v[168:171], v251
	ds_write_b128 v112, v[172:175]
	ds_write_b128 v112, v[176:179] offset:1024
	ds_write_b128 v112, v[180:183] offset:2048
	ds_write_b128 v112, v[184:187] offset:3072
	v_mfma_f32_32x32x16_bf16 v[32:47], v[120:123], v[52:55], v[32:47]
	v_mfma_f32_32x32x16_bf16 v[32:47], v[124:127], v[56:59], v[32:47]
	v_mfma_f32_32x32x16_bf16 v[32:47], v[128:131], v[60:63], v[32:47]
	s_nop 11
	v_exp_f32_e32 v32, v32
	v_exp_f32_e32 v33, v33
	v_exp_f32_e32 v34, v34
	v_exp_f32_e32 v35, v35
	v_exp_f32_e32 v36, v36
	v_exp_f32_e32 v37, v37
	v_exp_f32_e32 v38, v38
	v_exp_f32_e32 v39, v39
	v_exp_f32_e32 v40, v40
	v_exp_f32_e32 v41, v41
	v_exp_f32_e32 v42, v42
	v_exp_f32_e32 v43, v43
	v_exp_f32_e32 v44, v44
	v_exp_f32_e32 v45, v45
	v_exp_f32_e32 v46, v46
	v_exp_f32_e32 v47, v47
	s_add_i32 s90, s67, 32
	v_add_u32_e32 v84, s90, v107
	v_add_u32_e32 v85, 0, v84
	v_add_u32_e32 v86, 1, v84
	v_add_u32_e32 v87, 2, v84
	v_add_u32_e32 v88, 3, v84
	v_cmp_gt_u32_e64 s[30:31], s98, v85
	v_cmp_gt_u32_e64 s[36:37], s98, v86
	v_cmp_gt_u32_e64 s[78:79], s98, v87
	v_cmp_gt_u32_e64 s[50:51], s98, v88
	v_cndmask_b32_e64 v32, 0, v32, s[30:31]
	v_add_u32_e32 v85, 8, v84
	v_cmp_gt_u32_e64 s[30:31], s98, v85
	v_cndmask_b32_e64 v33, 0, v33, s[36:37]
	v_add_u32_e32 v86, 9, v84
	v_cmp_gt_u32_e64 s[36:37], s98, v86
	v_cndmask_b32_e64 v34, 0, v34, s[78:79]
	v_add_u32_e32 v87, 10, v84
	v_cmp_gt_u32_e64 s[78:79], s98, v87
	v_cndmask_b32_e64 v35, 0, v35, s[50:51]
	v_add_u32_e32 v88, 11, v84
	v_cmp_gt_u32_e64 s[50:51], s98, v88
	v_cndmask_b32_e64 v36, 0, v36, s[30:31]
	v_add_u32_e32 v85, 16, v84
	v_cmp_gt_u32_e64 s[30:31], s98, v85
	v_cndmask_b32_e64 v37, 0, v37, s[36:37]
	v_add_u32_e32 v86, 17, v84
	v_cmp_gt_u32_e64 s[36:37], s98, v86
	v_cndmask_b32_e64 v38, 0, v38, s[78:79]
	v_add_u32_e32 v87, 18, v84
	v_cmp_gt_u32_e64 s[78:79], s98, v87
	v_cndmask_b32_e64 v39, 0, v39, s[50:51]
	v_add_u32_e32 v88, 19, v84
	v_cmp_gt_u32_e64 s[50:51], s98, v88
	v_cndmask_b32_e64 v40, 0, v40, s[30:31]
	v_add_u32_e32 v85, 24, v84
	v_cmp_gt_u32_e64 s[30:31], s98, v85
	v_cndmask_b32_e64 v41, 0, v41, s[36:37]
	v_add_u32_e32 v86, 25, v84
	v_cmp_gt_u32_e64 s[36:37], s98, v86
	v_cndmask_b32_e64 v42, 0, v42, s[78:79]
	v_add_u32_e32 v87, 26, v84
	v_cmp_gt_u32_e64 s[78:79], s98, v87
	v_cndmask_b32_e64 v43, 0, v43, s[50:51]
	v_add_u32_e32 v88, 27, v84
	v_cmp_gt_u32_e64 s[50:51], s98, v88
	v_nop
	v_cndmask_b32_e64 v44, 0, v44, s[30:31]
	v_cndmask_b32_e64 v45, 0, v45, s[36:37]
	v_cndmask_b32_e64 v46, 0, v46, s[78:79]
	v_cndmask_b32_e64 v47, 0, v47, s[50:51]
	v_cvt_pk_bf16_f32 v64, v32, v33
	v_cvt_pk_bf16_f32 v65, v34, v35
	v_cvt_pk_bf16_f32 v66, v36, v37
	v_cvt_pk_bf16_f32 v67, v38, v39
	v_cvt_pk_bf16_f32 v68, v40, v41
	v_cvt_pk_bf16_f32 v69, v42, v43
	v_cvt_pk_bf16_f32 v70, v44, v45
	v_cvt_pk_bf16_f32 v71, v46, v47
	v_pk_add_f32 v[232:233], v[232:233], v[32:33]
	v_pk_add_f32 v[232:233], v[232:233], v[34:35]
	v_pk_add_f32 v[232:233], v[232:233], v[36:37]
	v_pk_add_f32 v[232:233], v[232:233], v[38:39]
	v_pk_add_f32 v[232:233], v[232:233], v[40:41]
	v_pk_add_f32 v[232:233], v[232:233], v[42:43]
	v_pk_add_f32 v[232:233], v[232:233], v[44:45]
	v_pk_add_f32 v[232:233], v[232:233], v[46:47]
	ds_read2_b32 v[32:33], v115 offset0:136 offset1:137
	ds_read2_b32 v[34:35], v115 offset0:138 offset1:139
	ds_read2_b32 v[36:37], v115 offset0:144 offset1:145
	ds_read2_b32 v[38:39], v115 offset0:146 offset1:147
	ds_read2_b32 v[40:41], v115 offset0:153 offset1:154
	ds_read2_b32 v[42:43], v115 offset0:155 offset1:156
	ds_read2_b32 v[44:45], v115 offset0:161 offset1:162
	ds_read2_b32 v[46:47], v115 offset0:163 offset1:164
	s_waitcnt lgkmcnt(15)
	v_mfma_f32_32x32x16_bf16 v[0:15], v[64:67], v[72:75], v[0:15]
	v_mfma_f32_32x32x16_bf16 v[16:31], v[64:67], v[76:79], v[16:31]
	v_mfma_f32_32x32x16_bf16 v[0:15], v[68:71], v[220:223], v[0:15]
	v_mfma_f32_32x32x16_bf16 v[16:31], v[68:71], v[224:227], v[16:31]
	s_add_i32 s90, s67, 128
	v_add_u32_e32 v80, s90, v235
	v_add_u32_e32 v83, s90, v236
	v_add_u32_e32 v99, s90, v237
	v_add_u32_e32 v253, s90, v238
	v_add_u32_e32 v254, s90, v100
	v_add_u32_e32 v255, s90, v149
	v_med3_i32 v80, v80, 0, s99
	v_med3_i32 v83, v83, 0, s99
	v_med3_i32 v99, v99, 0, s99
	v_med3_i32 v253, v253, 0, s99
	v_med3_i32 v254, v254, 0, s99
	v_med3_i32 v255, v255, 0, s99
	v_mad_u32_u24 v80, v80, s100, v252
	v_mad_u32_u24 v83, v83, s100, v252
	v_mad_u32_u24 v99, v99, s100, v252
	v_mad_u32_u24 v253, v253, s100, v252
	v_mad_u32_u24 v254, v254, s100, v153
	v_mad_u32_u24 v255, v255, s100, v153
	global_load_dwordx4 v[116:119], v80, s[82:83]
	global_load_dwordx4 v[120:123], v83, s[82:83]
	global_load_dwordx4 v[124:127], v99, s[82:83]
	global_load_dwordx4 v[128:131], v253, s[82:83]
	global_load_dwordx4 v[132:135], v254, s[82:83] offset:768
	global_load_dwordx4 v[136:139], v255, s[82:83] offset:768
	global_load_dwordx4 v[140:143], v254, s[82:83] offset:832
	global_load_dwordx4 v[144:147], v255, s[82:83] offset:832
	s_waitcnt lgkmcnt(0)
	v_mfma_f32_32x32x16_bf16 v[32:47], v[156:159], v[48:51], v[32:47]
	ds_read_b64_tr_b16 v[72:73], v231
	ds_read_b64_tr_b16 v[74:75], v231 offset:512
	ds_read_b64_tr_b16 v[76:77], v231 offset:2048
	ds_read_b64_tr_b16 v[78:79], v231 offset:2560
	ds_read_b64_tr_b16 v[220:221], v231 offset:1024
	ds_read_b64_tr_b16 v[222:223], v231 offset:1536
	ds_read_b64_tr_b16 v[224:225], v231 offset:3072
	ds_read_b64_tr_b16 v[226:227], v231 offset:3584
	s_waitcnt vmcnt(8)
	ds_write_b128 v247, v[188:191]
	ds_write_b128 v247, v[192:195] offset:1024
	ds_write_b128 v247, v[196:199] offset:2048
	ds_write_b128 v247, v[200:203] offset:3072
	ds_read_b128 v[188:191], v248
	ds_read_b128 v[192:195], v249
	ds_read_b128 v[196:199], v250
	ds_read_b128 v[200:203], v251
	ds_write_b128 v112, v[204:207]
	ds_write_b128 v112, v[208:211] offset:1024
	ds_write_b128 v112, v[212:215] offset:2048
	ds_write_b128 v112, v[216:219] offset:3072
	v_mfma_f32_32x32x16_bf16 v[32:47], v[160:163], v[52:55], v[32:47]
	v_mfma_f32_32x32x16_bf16 v[32:47], v[164:167], v[56:59], v[32:47]
	v_mfma_f32_32x32x16_bf16 v[32:47], v[168:171], v[60:63], v[32:47]
	s_nop 11
	v_exp_f32_e32 v32, v32
	v_exp_f32_e32 v33, v33
	v_exp_f32_e32 v34, v34
	v_exp_f32_e32 v35, v35
	v_exp_f32_e32 v36, v36
	v_exp_f32_e32 v37, v37
	v_exp_f32_e32 v38, v38
	v_exp_f32_e32 v39, v39
	v_exp_f32_e32 v40, v40
	v_exp_f32_e32 v41, v41
	v_exp_f32_e32 v42, v42
	v_exp_f32_e32 v43, v43
	v_exp_f32_e32 v44, v44
	v_exp_f32_e32 v45, v45
	v_exp_f32_e32 v46, v46
	v_exp_f32_e32 v47, v47
	s_add_i32 s90, s67, 64
	v_add_u32_e32 v84, s90, v107
	v_add_u32_e32 v85, 0, v84
	v_add_u32_e32 v86, 1, v84
	v_add_u32_e32 v87, 2, v84
	v_add_u32_e32 v88, 3, v84
	v_cmp_gt_u32_e64 s[30:31], s98, v85
	v_cmp_gt_u32_e64 s[36:37], s98, v86
	v_cmp_gt_u32_e64 s[78:79], s98, v87
	v_cmp_gt_u32_e64 s[50:51], s98, v88
	v_cndmask_b32_e64 v32, 0, v32, s[30:31]
	v_add_u32_e32 v85, 8, v84
	v_cmp_gt_u32_e64 s[30:31], s98, v85
	v_cndmask_b32_e64 v33, 0, v33, s[36:37]
	v_add_u32_e32 v86, 9, v84
	v_cmp_gt_u32_e64 s[36:37], s98, v86
	v_cndmask_b32_e64 v34, 0, v34, s[78:79]
	v_add_u32_e32 v87, 10, v84
	v_cmp_gt_u32_e64 s[78:79], s98, v87
	v_cndmask_b32_e64 v35, 0, v35, s[50:51]
	v_add_u32_e32 v88, 11, v84
	v_cmp_gt_u32_e64 s[50:51], s98, v88
	v_cndmask_b32_e64 v36, 0, v36, s[30:31]
	v_add_u32_e32 v85, 16, v84
	v_cmp_gt_u32_e64 s[30:31], s98, v85
	v_cndmask_b32_e64 v37, 0, v37, s[36:37]
	v_add_u32_e32 v86, 17, v84
	v_cmp_gt_u32_e64 s[36:37], s98, v86
	v_cndmask_b32_e64 v38, 0, v38, s[78:79]
	v_add_u32_e32 v87, 18, v84
	v_cmp_gt_u32_e64 s[78:79], s98, v87
	v_cndmask_b32_e64 v39, 0, v39, s[50:51]
	v_add_u32_e32 v88, 19, v84
	v_cmp_gt_u32_e64 s[50:51], s98, v88
	v_cndmask_b32_e64 v40, 0, v40, s[30:31]
	v_add_u32_e32 v85, 24, v84
	v_cmp_gt_u32_e64 s[30:31], s98, v85
	v_cndmask_b32_e64 v41, 0, v41, s[36:37]
	v_add_u32_e32 v86, 25, v84
	v_cmp_gt_u32_e64 s[36:37], s98, v86
	v_cndmask_b32_e64 v42, 0, v42, s[78:79]
	v_add_u32_e32 v87, 26, v84
	v_cmp_gt_u32_e64 s[78:79], s98, v87
	v_cndmask_b32_e64 v43, 0, v43, s[50:51]
	v_add_u32_e32 v88, 27, v84
	v_cmp_gt_u32_e64 s[50:51], s98, v88
	v_nop
	v_cndmask_b32_e64 v44, 0, v44, s[30:31]
	v_cndmask_b32_e64 v45, 0, v45, s[36:37]
	v_cndmask_b32_e64 v46, 0, v46, s[78:79]
	v_cndmask_b32_e64 v47, 0, v47, s[50:51]
	v_cvt_pk_bf16_f32 v64, v32, v33
	v_cvt_pk_bf16_f32 v65, v34, v35
	v_cvt_pk_bf16_f32 v66, v36, v37
	v_cvt_pk_bf16_f32 v67, v38, v39
	v_cvt_pk_bf16_f32 v68, v40, v41
	v_cvt_pk_bf16_f32 v69, v42, v43
	v_cvt_pk_bf16_f32 v70, v44, v45
	v_cvt_pk_bf16_f32 v71, v46, v47
	v_pk_add_f32 v[232:233], v[232:233], v[32:33]
	v_pk_add_f32 v[232:233], v[232:233], v[34:35]
	v_pk_add_f32 v[232:233], v[232:233], v[36:37]
	v_pk_add_f32 v[232:233], v[232:233], v[38:39]
	v_pk_add_f32 v[232:233], v[232:233], v[40:41]
	v_pk_add_f32 v[232:233], v[232:233], v[42:43]
	v_pk_add_f32 v[232:233], v[232:233], v[44:45]
	v_pk_add_f32 v[232:233], v[232:233], v[46:47]
	ds_read2_b32 v[32:33], v115 offset0:170 offset1:171
	ds_read2_b32 v[34:35], v115 offset0:172 offset1:173
	ds_read2_b32 v[36:37], v115 offset0:178 offset1:179
	ds_read2_b32 v[38:39], v115 offset0:180 offset1:181
	ds_read2_b32 v[40:41], v115 offset0:187 offset1:188
	ds_read2_b32 v[42:43], v115 offset0:189 offset1:190
	ds_read2_b32 v[44:45], v115 offset0:195 offset1:196
	ds_read2_b32 v[46:47], v115 offset0:197 offset1:198
	s_waitcnt lgkmcnt(15)
	v_mfma_f32_32x32x16_bf16 v[0:15], v[64:67], v[72:75], v[0:15]
	v_mfma_f32_32x32x16_bf16 v[16:31], v[64:67], v[76:79], v[16:31]
	v_mfma_f32_32x32x16_bf16 v[0:15], v[68:71], v[220:223], v[0:15]
	v_mfma_f32_32x32x16_bf16 v[16:31], v[68:71], v[224:227], v[16:31]
	s_add_i32 s90, s67, 160
	v_add_u32_e32 v80, s90, v235
	v_add_u32_e32 v83, s90, v236
	v_add_u32_e32 v99, s90, v237
	v_add_u32_e32 v253, s90, v238
	v_add_u32_e32 v254, s90, v100
	v_add_u32_e32 v255, s90, v149
	v_med3_i32 v80, v80, 0, s99
	v_med3_i32 v83, v83, 0, s99
	v_med3_i32 v99, v99, 0, s99
	v_med3_i32 v253, v253, 0, s99
	v_med3_i32 v254, v254, 0, s99
	v_med3_i32 v255, v255, 0, s99
	v_mad_u32_u24 v80, v80, s100, v252
	v_mad_u32_u24 v83, v83, s100, v252
	v_mad_u32_u24 v99, v99, s100, v252
	v_mad_u32_u24 v253, v253, s100, v252
	v_mad_u32_u24 v254, v254, s100, v153
	v_mad_u32_u24 v255, v255, s100, v153
	global_load_dwordx4 v[156:159], v80, s[82:83]
	global_load_dwordx4 v[160:163], v83, s[82:83]
	global_load_dwordx4 v[164:167], v99, s[82:83]
	global_load_dwordx4 v[168:171], v253, s[82:83]
	global_load_dwordx4 v[172:175], v254, s[82:83] offset:768
	global_load_dwordx4 v[176:179], v255, s[82:83] offset:768
	global_load_dwordx4 v[180:183], v254, s[82:83] offset:832
	global_load_dwordx4 v[184:187], v255, s[82:83] offset:832
	s_waitcnt lgkmcnt(0)
	v_mfma_f32_32x32x16_bf16 v[32:47], v[188:191], v[48:51], v[32:47]
	ds_read_b64_tr_b16 v[72:73], v231
	ds_read_b64_tr_b16 v[74:75], v231 offset:512
	ds_read_b64_tr_b16 v[76:77], v231 offset:2048
	ds_read_b64_tr_b16 v[78:79], v231 offset:2560
	ds_read_b64_tr_b16 v[220:221], v231 offset:1024
	ds_read_b64_tr_b16 v[222:223], v231 offset:1536
	ds_read_b64_tr_b16 v[224:225], v231 offset:3072
	ds_read_b64_tr_b16 v[226:227], v231 offset:3584
	s_waitcnt vmcnt(8)
	ds_write_b128 v247, v[116:119]
	ds_write_b128 v247, v[120:123] offset:1024
	ds_write_b128 v247, v[124:127] offset:2048
	ds_write_b128 v247, v[128:131] offset:3072
	ds_read_b128 v[116:119], v248
	ds_read_b128 v[120:123], v249
	ds_read_b128 v[124:127], v250
	ds_read_b128 v[128:131], v251
	ds_write_b128 v112, v[132:135]
	ds_write_b128 v112, v[136:139] offset:1024
	ds_write_b128 v112, v[140:143] offset:2048
	ds_write_b128 v112, v[144:147] offset:3072
	v_mfma_f32_32x32x16_bf16 v[32:47], v[192:195], v[52:55], v[32:47]
	v_mfma_f32_32x32x16_bf16 v[32:47], v[196:199], v[56:59], v[32:47]
	v_mfma_f32_32x32x16_bf16 v[32:47], v[200:203], v[60:63], v[32:47]
	s_nop 11
	v_exp_f32_e32 v32, v32
	v_exp_f32_e32 v33, v33
	v_exp_f32_e32 v34, v34
	v_exp_f32_e32 v35, v35
	v_exp_f32_e32 v36, v36
	v_exp_f32_e32 v37, v37
	v_exp_f32_e32 v38, v38
	v_exp_f32_e32 v39, v39
	v_exp_f32_e32 v40, v40
	v_exp_f32_e32 v41, v41
	v_exp_f32_e32 v42, v42
	v_exp_f32_e32 v43, v43
	v_exp_f32_e32 v44, v44
	v_exp_f32_e32 v45, v45
	v_exp_f32_e32 v46, v46
	v_exp_f32_e32 v47, v47
	s_add_i32 s90, s67, 96
	v_add_u32_e32 v84, s90, v107
	v_add_u32_e32 v85, 0, v84
	v_add_u32_e32 v86, 1, v84
	v_add_u32_e32 v87, 2, v84
	v_add_u32_e32 v88, 3, v84
	v_cmp_gt_u32_e64 s[30:31], s98, v85
	v_cmp_gt_u32_e64 s[36:37], s98, v86
	v_cmp_gt_u32_e64 s[78:79], s98, v87
	v_cmp_gt_u32_e64 s[50:51], s98, v88
	v_cndmask_b32_e64 v32, 0, v32, s[30:31]
	v_add_u32_e32 v85, 8, v84
	v_cmp_gt_u32_e64 s[30:31], s98, v85
	v_cndmask_b32_e64 v33, 0, v33, s[36:37]
	v_add_u32_e32 v86, 9, v84
	v_cmp_gt_u32_e64 s[36:37], s98, v86
	v_cndmask_b32_e64 v34, 0, v34, s[78:79]
	v_add_u32_e32 v87, 10, v84
	v_cmp_gt_u32_e64 s[78:79], s98, v87
	v_cndmask_b32_e64 v35, 0, v35, s[50:51]
	v_add_u32_e32 v88, 11, v84
	v_cmp_gt_u32_e64 s[50:51], s98, v88
	v_cndmask_b32_e64 v36, 0, v36, s[30:31]
	v_add_u32_e32 v85, 16, v84
	v_cmp_gt_u32_e64 s[30:31], s98, v85
	v_cndmask_b32_e64 v37, 0, v37, s[36:37]
	v_add_u32_e32 v86, 17, v84
	v_cmp_gt_u32_e64 s[36:37], s98, v86
	v_cndmask_b32_e64 v38, 0, v38, s[78:79]
	v_add_u32_e32 v87, 18, v84
	v_cmp_gt_u32_e64 s[78:79], s98, v87
	v_cndmask_b32_e64 v39, 0, v39, s[50:51]
	v_add_u32_e32 v88, 19, v84
	v_cmp_gt_u32_e64 s[50:51], s98, v88
	v_cndmask_b32_e64 v40, 0, v40, s[30:31]
	v_add_u32_e32 v85, 24, v84
	v_cmp_gt_u32_e64 s[30:31], s98, v85
	v_cndmask_b32_e64 v41, 0, v41, s[36:37]
	v_add_u32_e32 v86, 25, v84
	v_cmp_gt_u32_e64 s[36:37], s98, v86
	v_cndmask_b32_e64 v42, 0, v42, s[78:79]
	v_add_u32_e32 v87, 26, v84
	v_cmp_gt_u32_e64 s[78:79], s98, v87
	v_cndmask_b32_e64 v43, 0, v43, s[50:51]
	v_add_u32_e32 v88, 27, v84
	v_cmp_gt_u32_e64 s[50:51], s98, v88
	v_nop
	v_cndmask_b32_e64 v44, 0, v44, s[30:31]
	v_cndmask_b32_e64 v45, 0, v45, s[36:37]
	v_cndmask_b32_e64 v46, 0, v46, s[78:79]
	v_cndmask_b32_e64 v47, 0, v47, s[50:51]
	v_cvt_pk_bf16_f32 v64, v32, v33
	v_cvt_pk_bf16_f32 v65, v34, v35
	v_cvt_pk_bf16_f32 v66, v36, v37
	v_cvt_pk_bf16_f32 v67, v38, v39
	v_cvt_pk_bf16_f32 v68, v40, v41
	v_cvt_pk_bf16_f32 v69, v42, v43
	v_cvt_pk_bf16_f32 v70, v44, v45
	v_cvt_pk_bf16_f32 v71, v46, v47
	v_pk_add_f32 v[232:233], v[232:233], v[32:33]
	v_pk_add_f32 v[232:233], v[232:233], v[34:35]
	v_pk_add_f32 v[232:233], v[232:233], v[36:37]
	v_pk_add_f32 v[232:233], v[232:233], v[38:39]
	v_pk_add_f32 v[232:233], v[232:233], v[40:41]
	v_pk_add_f32 v[232:233], v[232:233], v[42:43]
	v_pk_add_f32 v[232:233], v[232:233], v[44:45]
	v_pk_add_f32 v[232:233], v[232:233], v[46:47]
	ds_read2_b32 v[32:33], v115 offset0:204 offset1:205
	ds_read2_b32 v[34:35], v115 offset0:206 offset1:207
	ds_read2_b32 v[36:37], v115 offset0:212 offset1:213
	ds_read2_b32 v[38:39], v115 offset0:214 offset1:215
	ds_read2_b32 v[40:41], v115 offset0:221 offset1:222
	ds_read2_b32 v[42:43], v115 offset0:223 offset1:224
	ds_read2_b32 v[44:45], v115 offset0:229 offset1:230
	ds_read2_b32 v[46:47], v115 offset0:231 offset1:232
	s_waitcnt lgkmcnt(15)
	v_mfma_f32_32x32x16_bf16 v[0:15], v[64:67], v[72:75], v[0:15]
	v_mfma_f32_32x32x16_bf16 v[16:31], v[64:67], v[76:79], v[16:31]
	v_mfma_f32_32x32x16_bf16 v[0:15], v[68:71], v[220:223], v[0:15]
	v_mfma_f32_32x32x16_bf16 v[16:31], v[68:71], v[224:227], v[16:31]
	s_add_i32 s90, s67, 192
	v_add_u32_e32 v80, s90, v235
	v_add_u32_e32 v83, s90, v236
	v_add_u32_e32 v99, s90, v237
	v_add_u32_e32 v253, s90, v238
	v_add_u32_e32 v254, s90, v100
	v_add_u32_e32 v255, s90, v149
	v_med3_i32 v80, v80, 0, s99
	v_med3_i32 v83, v83, 0, s99
	v_med3_i32 v99, v99, 0, s99
	v_med3_i32 v253, v253, 0, s99
	v_med3_i32 v254, v254, 0, s99
	v_med3_i32 v255, v255, 0, s99
	v_mad_u32_u24 v80, v80, s100, v252
	v_mad_u32_u24 v83, v83, s100, v252
	v_mad_u32_u24 v99, v99, s100, v252
	v_mad_u32_u24 v253, v253, s100, v252
	v_mad_u32_u24 v254, v254, s100, v153
	v_mad_u32_u24 v255, v255, s100, v153
	global_load_dwordx4 v[188:191], v80, s[82:83]
	global_load_dwordx4 v[192:195], v83, s[82:83]
	global_load_dwordx4 v[196:199], v99, s[82:83]
	global_load_dwordx4 v[200:203], v253, s[82:83]
	global_load_dwordx4 v[204:207], v254, s[82:83] offset:768
	global_load_dwordx4 v[208:211], v255, s[82:83] offset:768
	global_load_dwordx4 v[212:215], v254, s[82:83] offset:832
	global_load_dwordx4 v[216:219], v255, s[82:83] offset:832
	s_waitcnt lgkmcnt(0)
	v_mfma_f32_32x32x16_bf16 v[32:47], v[116:119], v[48:51], v[32:47]
	ds_read_b64_tr_b16 v[72:73], v231
	ds_read_b64_tr_b16 v[74:75], v231 offset:512
	ds_read_b64_tr_b16 v[76:77], v231 offset:2048
	ds_read_b64_tr_b16 v[78:79], v231 offset:2560
	ds_read_b64_tr_b16 v[220:221], v231 offset:1024
	ds_read_b64_tr_b16 v[222:223], v231 offset:1536
	ds_read_b64_tr_b16 v[224:225], v231 offset:3072
	ds_read_b64_tr_b16 v[226:227], v231 offset:3584
	s_waitcnt vmcnt(8)
	ds_write_b128 v247, v[156:159]
	ds_write_b128 v247, v[160:163] offset:1024
	ds_write_b128 v247, v[164:167] offset:2048
	ds_write_b128 v247, v[168:171] offset:3072
	ds_read_b128 v[156:159], v248
	ds_read_b128 v[160:163], v249
	ds_read_b128 v[164:167], v250
	ds_read_b128 v[168:171], v251
	ds_write_b128 v112, v[172:175]
	ds_write_b128 v112, v[176:179] offset:1024
	ds_write_b128 v112, v[180:183] offset:2048
	ds_write_b128 v112, v[184:187] offset:3072
	v_mfma_f32_32x32x16_bf16 v[32:47], v[120:123], v[52:55], v[32:47]
	v_mfma_f32_32x32x16_bf16 v[32:47], v[124:127], v[56:59], v[32:47]
	v_mfma_f32_32x32x16_bf16 v[32:47], v[128:131], v[60:63], v[32:47]
	s_nop 11
	v_exp_f32_e32 v32, v32
	v_exp_f32_e32 v33, v33
	v_exp_f32_e32 v34, v34
	v_exp_f32_e32 v35, v35
	v_exp_f32_e32 v36, v36
	v_exp_f32_e32 v37, v37
	v_exp_f32_e32 v38, v38
	v_exp_f32_e32 v39, v39
	v_exp_f32_e32 v40, v40
	v_exp_f32_e32 v41, v41
	v_exp_f32_e32 v42, v42
	v_exp_f32_e32 v43, v43
	v_exp_f32_e32 v44, v44
	v_exp_f32_e32 v45, v45
	v_exp_f32_e32 v46, v46
	v_exp_f32_e32 v47, v47
	s_add_i32 s90, s67, 128
	v_add_u32_e32 v84, s90, v107
	v_add_u32_e32 v85, 0, v84
	v_add_u32_e32 v86, 1, v84
	v_add_u32_e32 v87, 2, v84
	v_add_u32_e32 v88, 3, v84
	v_cmp_gt_u32_e64 s[30:31], s98, v85
	v_cmp_gt_u32_e64 s[36:37], s98, v86
	v_cmp_gt_u32_e64 s[78:79], s98, v87
	v_cmp_gt_u32_e64 s[50:51], s98, v88
	v_cndmask_b32_e64 v32, 0, v32, s[30:31]
	v_add_u32_e32 v85, 8, v84
	v_cmp_gt_u32_e64 s[30:31], s98, v85
	v_cndmask_b32_e64 v33, 0, v33, s[36:37]
	v_add_u32_e32 v86, 9, v84
	v_cmp_gt_u32_e64 s[36:37], s98, v86
	v_cndmask_b32_e64 v34, 0, v34, s[78:79]
	v_add_u32_e32 v87, 10, v84
	v_cmp_gt_u32_e64 s[78:79], s98, v87
	v_cndmask_b32_e64 v35, 0, v35, s[50:51]
	v_add_u32_e32 v88, 11, v84
	v_cmp_gt_u32_e64 s[50:51], s98, v88
	v_cndmask_b32_e64 v36, 0, v36, s[30:31]
	v_add_u32_e32 v85, 16, v84
	v_cmp_gt_u32_e64 s[30:31], s98, v85
	v_cndmask_b32_e64 v37, 0, v37, s[36:37]
	v_add_u32_e32 v86, 17, v84
	v_cmp_gt_u32_e64 s[36:37], s98, v86
	v_cndmask_b32_e64 v38, 0, v38, s[78:79]
	v_add_u32_e32 v87, 18, v84
	v_cmp_gt_u32_e64 s[78:79], s98, v87
	v_cndmask_b32_e64 v39, 0, v39, s[50:51]
	v_add_u32_e32 v88, 19, v84
	v_cmp_gt_u32_e64 s[50:51], s98, v88
	v_cndmask_b32_e64 v40, 0, v40, s[30:31]
	v_add_u32_e32 v85, 24, v84
	v_cmp_gt_u32_e64 s[30:31], s98, v85
	v_cndmask_b32_e64 v41, 0, v41, s[36:37]
	v_add_u32_e32 v86, 25, v84
	v_cmp_gt_u32_e64 s[36:37], s98, v86
	v_cndmask_b32_e64 v42, 0, v42, s[78:79]
	v_add_u32_e32 v87, 26, v84
	v_cmp_gt_u32_e64 s[78:79], s98, v87
	v_cndmask_b32_e64 v43, 0, v43, s[50:51]
	v_add_u32_e32 v88, 27, v84
	v_cmp_gt_u32_e64 s[50:51], s98, v88
	v_nop
	v_cndmask_b32_e64 v44, 0, v44, s[30:31]
	v_cndmask_b32_e64 v45, 0, v45, s[36:37]
	v_cndmask_b32_e64 v46, 0, v46, s[78:79]
	v_cndmask_b32_e64 v47, 0, v47, s[50:51]
	v_cvt_pk_bf16_f32 v64, v32, v33
	v_cvt_pk_bf16_f32 v65, v34, v35
	v_cvt_pk_bf16_f32 v66, v36, v37
	v_cvt_pk_bf16_f32 v67, v38, v39
	v_cvt_pk_bf16_f32 v68, v40, v41
	v_cvt_pk_bf16_f32 v69, v42, v43
	v_cvt_pk_bf16_f32 v70, v44, v45
	v_cvt_pk_bf16_f32 v71, v46, v47
	v_pk_add_f32 v[232:233], v[232:233], v[32:33]
	v_pk_add_f32 v[232:233], v[232:233], v[34:35]
	v_pk_add_f32 v[232:233], v[232:233], v[36:37]
	v_pk_add_f32 v[232:233], v[232:233], v[38:39]
	v_pk_add_f32 v[232:233], v[232:233], v[40:41]
	v_pk_add_f32 v[232:233], v[232:233], v[42:43]
	v_pk_add_f32 v[232:233], v[232:233], v[44:45]
	v_pk_add_f32 v[232:233], v[232:233], v[46:47]
	v_add_u32_e32 v115, 952, v115
	ds_read2_b32 v[32:33], v115 offset0:0 offset1:1
	ds_read2_b32 v[34:35], v115 offset0:2 offset1:3
	ds_read2_b32 v[36:37], v115 offset0:8 offset1:9
	ds_read2_b32 v[38:39], v115 offset0:10 offset1:11
	ds_read2_b32 v[40:41], v115 offset0:17 offset1:18
	ds_read2_b32 v[42:43], v115 offset0:19 offset1:20
	ds_read2_b32 v[44:45], v115 offset0:25 offset1:26
	ds_read2_b32 v[46:47], v115 offset0:27 offset1:28
	s_waitcnt lgkmcnt(15)
	v_mfma_f32_32x32x16_bf16 v[0:15], v[64:67], v[72:75], v[0:15]
	v_mfma_f32_32x32x16_bf16 v[16:31], v[64:67], v[76:79], v[16:31]
	v_mfma_f32_32x32x16_bf16 v[0:15], v[68:71], v[220:223], v[0:15]
	v_mfma_f32_32x32x16_bf16 v[16:31], v[68:71], v[224:227], v[16:31]
	s_add_i32 s90, s67, 224
	v_add_u32_e32 v80, s90, v235
	v_add_u32_e32 v83, s90, v236
	v_add_u32_e32 v99, s90, v237
	v_add_u32_e32 v253, s90, v238
	v_add_u32_e32 v254, s90, v100
	v_add_u32_e32 v255, s90, v149
	v_med3_i32 v80, v80, 0, s99
	v_med3_i32 v83, v83, 0, s99
	v_med3_i32 v99, v99, 0, s99
	v_med3_i32 v253, v253, 0, s99
	v_med3_i32 v254, v254, 0, s99
	v_med3_i32 v255, v255, 0, s99
	v_mad_u32_u24 v80, v80, s100, v252
	v_mad_u32_u24 v83, v83, s100, v252
	v_mad_u32_u24 v99, v99, s100, v252
	v_mad_u32_u24 v253, v253, s100, v252
	v_mad_u32_u24 v254, v254, s100, v153
	v_mad_u32_u24 v255, v255, s100, v153
	global_load_dwordx4 v[116:119], v80, s[82:83]
	global_load_dwordx4 v[120:123], v83, s[82:83]
	global_load_dwordx4 v[124:127], v99, s[82:83]
	global_load_dwordx4 v[128:131], v253, s[82:83]
	global_load_dwordx4 v[132:135], v254, s[82:83] offset:768
	global_load_dwordx4 v[136:139], v255, s[82:83] offset:768
	global_load_dwordx4 v[140:143], v254, s[82:83] offset:832
	global_load_dwordx4 v[144:147], v255, s[82:83] offset:832
	s_waitcnt lgkmcnt(0)
	v_mfma_f32_32x32x16_bf16 v[32:47], v[156:159], v[48:51], v[32:47]
	ds_read_b64_tr_b16 v[72:73], v231
	ds_read_b64_tr_b16 v[74:75], v231 offset:512
	ds_read_b64_tr_b16 v[76:77], v231 offset:2048
	ds_read_b64_tr_b16 v[78:79], v231 offset:2560
	ds_read_b64_tr_b16 v[220:221], v231 offset:1024
	ds_read_b64_tr_b16 v[222:223], v231 offset:1536
	ds_read_b64_tr_b16 v[224:225], v231 offset:3072
	ds_read_b64_tr_b16 v[226:227], v231 offset:3584
	s_waitcnt vmcnt(8)
	ds_write_b128 v247, v[188:191]
	ds_write_b128 v247, v[192:195] offset:1024
	ds_write_b128 v247, v[196:199] offset:2048
	ds_write_b128 v247, v[200:203] offset:3072
	ds_read_b128 v[188:191], v248
	ds_read_b128 v[192:195], v249
	ds_read_b128 v[196:199], v250
	ds_read_b128 v[200:203], v251
	ds_write_b128 v112, v[204:207]
	ds_write_b128 v112, v[208:211] offset:1024
	ds_write_b128 v112, v[212:215] offset:2048
	ds_write_b128 v112, v[216:219] offset:3072
	v_mfma_f32_32x32x16_bf16 v[32:47], v[160:163], v[52:55], v[32:47]
	v_mfma_f32_32x32x16_bf16 v[32:47], v[164:167], v[56:59], v[32:47]
	v_mfma_f32_32x32x16_bf16 v[32:47], v[168:171], v[60:63], v[32:47]
	s_nop 11
	v_exp_f32_e32 v32, v32
	v_exp_f32_e32 v33, v33
	v_exp_f32_e32 v34, v34
	v_exp_f32_e32 v35, v35
	v_exp_f32_e32 v36, v36
	v_exp_f32_e32 v37, v37
	v_exp_f32_e32 v38, v38
	v_exp_f32_e32 v39, v39
	v_exp_f32_e32 v40, v40
	v_exp_f32_e32 v41, v41
	v_exp_f32_e32 v42, v42
	v_exp_f32_e32 v43, v43
	v_exp_f32_e32 v44, v44
	v_exp_f32_e32 v45, v45
	v_exp_f32_e32 v46, v46
	v_exp_f32_e32 v47, v47
	s_add_i32 s90, s67, 160
	v_add_u32_e32 v84, s90, v107
	v_add_u32_e32 v85, 0, v84
	v_add_u32_e32 v86, 1, v84
	v_add_u32_e32 v87, 2, v84
	v_add_u32_e32 v88, 3, v84
	v_cmp_gt_u32_e64 s[30:31], s98, v85
	v_cmp_gt_u32_e64 s[36:37], s98, v86
	v_cmp_gt_u32_e64 s[78:79], s98, v87
	v_cmp_gt_u32_e64 s[50:51], s98, v88
	v_cndmask_b32_e64 v32, 0, v32, s[30:31]
	v_add_u32_e32 v85, 8, v84
	v_cmp_gt_u32_e64 s[30:31], s98, v85
	v_cndmask_b32_e64 v33, 0, v33, s[36:37]
	v_add_u32_e32 v86, 9, v84
	v_cmp_gt_u32_e64 s[36:37], s98, v86
	v_cndmask_b32_e64 v34, 0, v34, s[78:79]
	v_add_u32_e32 v87, 10, v84
	v_cmp_gt_u32_e64 s[78:79], s98, v87
	v_cndmask_b32_e64 v35, 0, v35, s[50:51]
	v_add_u32_e32 v88, 11, v84
	v_cmp_gt_u32_e64 s[50:51], s98, v88
	v_cndmask_b32_e64 v36, 0, v36, s[30:31]
	v_add_u32_e32 v85, 16, v84
	v_cmp_gt_u32_e64 s[30:31], s98, v85
	v_cndmask_b32_e64 v37, 0, v37, s[36:37]
	v_add_u32_e32 v86, 17, v84
	v_cmp_gt_u32_e64 s[36:37], s98, v86
	v_cndmask_b32_e64 v38, 0, v38, s[78:79]
	v_add_u32_e32 v87, 18, v84
	v_cmp_gt_u32_e64 s[78:79], s98, v87
	v_cndmask_b32_e64 v39, 0, v39, s[50:51]
	v_add_u32_e32 v88, 19, v84
	v_cmp_gt_u32_e64 s[50:51], s98, v88
	v_cndmask_b32_e64 v40, 0, v40, s[30:31]
	v_add_u32_e32 v85, 24, v84
	v_cmp_gt_u32_e64 s[30:31], s98, v85
	v_cndmask_b32_e64 v41, 0, v41, s[36:37]
	v_add_u32_e32 v86, 25, v84
	v_cmp_gt_u32_e64 s[36:37], s98, v86
	v_cndmask_b32_e64 v42, 0, v42, s[78:79]
	v_add_u32_e32 v87, 26, v84
	v_cmp_gt_u32_e64 s[78:79], s98, v87
	v_cndmask_b32_e64 v43, 0, v43, s[50:51]
	v_add_u32_e32 v88, 27, v84
	v_cmp_gt_u32_e64 s[50:51], s98, v88
	v_nop
	v_cndmask_b32_e64 v44, 0, v44, s[30:31]
	v_cndmask_b32_e64 v45, 0, v45, s[36:37]
	v_cndmask_b32_e64 v46, 0, v46, s[78:79]
	v_cndmask_b32_e64 v47, 0, v47, s[50:51]
	v_cvt_pk_bf16_f32 v64, v32, v33
	v_cvt_pk_bf16_f32 v65, v34, v35
	v_cvt_pk_bf16_f32 v66, v36, v37
	v_cvt_pk_bf16_f32 v67, v38, v39
	v_cvt_pk_bf16_f32 v68, v40, v41
	v_cvt_pk_bf16_f32 v69, v42, v43
	v_cvt_pk_bf16_f32 v70, v44, v45
	v_cvt_pk_bf16_f32 v71, v46, v47
	v_pk_add_f32 v[232:233], v[232:233], v[32:33]
	v_pk_add_f32 v[232:233], v[232:233], v[34:35]
	v_pk_add_f32 v[232:233], v[232:233], v[36:37]
	v_pk_add_f32 v[232:233], v[232:233], v[38:39]
	v_pk_add_f32 v[232:233], v[232:233], v[40:41]
	v_pk_add_f32 v[232:233], v[232:233], v[42:43]
	v_pk_add_f32 v[232:233], v[232:233], v[44:45]
	v_pk_add_f32 v[232:233], v[232:233], v[46:47]
	ds_read2_b32 v[32:33], v115 offset0:34 offset1:35
	ds_read2_b32 v[34:35], v115 offset0:36 offset1:37
	ds_read2_b32 v[36:37], v115 offset0:42 offset1:43
	ds_read2_b32 v[38:39], v115 offset0:44 offset1:45
	ds_read2_b32 v[40:41], v115 offset0:51 offset1:52
	ds_read2_b32 v[42:43], v115 offset0:53 offset1:54
	ds_read2_b32 v[44:45], v115 offset0:59 offset1:60
	ds_read2_b32 v[46:47], v115 offset0:61 offset1:62
	s_waitcnt lgkmcnt(15)
	v_mfma_f32_32x32x16_bf16 v[0:15], v[64:67], v[72:75], v[0:15]
	v_mfma_f32_32x32x16_bf16 v[16:31], v[64:67], v[76:79], v[16:31]
	v_mfma_f32_32x32x16_bf16 v[0:15], v[68:71], v[220:223], v[0:15]
	v_mfma_f32_32x32x16_bf16 v[16:31], v[68:71], v[224:227], v[16:31]
	s_add_i32 s90, s67, 256
	v_add_u32_e32 v80, s90, v235
	v_add_u32_e32 v83, s90, v236
	v_add_u32_e32 v99, s90, v237
	v_add_u32_e32 v253, s90, v238
	v_add_u32_e32 v254, s90, v100
	v_add_u32_e32 v255, s90, v149
	v_med3_i32 v80, v80, 0, s99
	v_med3_i32 v83, v83, 0, s99
	v_med3_i32 v99, v99, 0, s99
	v_med3_i32 v253, v253, 0, s99
	v_med3_i32 v254, v254, 0, s99
	v_med3_i32 v255, v255, 0, s99
	v_mad_u32_u24 v80, v80, s100, v252
	v_mad_u32_u24 v83, v83, s100, v252
	v_mad_u32_u24 v99, v99, s100, v252
	v_mad_u32_u24 v253, v253, s100, v252
	v_mad_u32_u24 v254, v254, s100, v153
	v_mad_u32_u24 v255, v255, s100, v153
	global_load_dwordx4 v[156:159], v80, s[82:83]
	global_load_dwordx4 v[160:163], v83, s[82:83]
	global_load_dwordx4 v[164:167], v99, s[82:83]
	global_load_dwordx4 v[168:171], v253, s[82:83]
	global_load_dwordx4 v[172:175], v254, s[82:83] offset:768
	global_load_dwordx4 v[176:179], v255, s[82:83] offset:768
	global_load_dwordx4 v[180:183], v254, s[82:83] offset:832
	global_load_dwordx4 v[184:187], v255, s[82:83] offset:832
	s_waitcnt lgkmcnt(0)
	v_mfma_f32_32x32x16_bf16 v[32:47], v[188:191], v[48:51], v[32:47]
	ds_read_b64_tr_b16 v[72:73], v231
	ds_read_b64_tr_b16 v[74:75], v231 offset:512
	ds_read_b64_tr_b16 v[76:77], v231 offset:2048
	ds_read_b64_tr_b16 v[78:79], v231 offset:2560
	ds_read_b64_tr_b16 v[220:221], v231 offset:1024
	ds_read_b64_tr_b16 v[222:223], v231 offset:1536
	ds_read_b64_tr_b16 v[224:225], v231 offset:3072
	ds_read_b64_tr_b16 v[226:227], v231 offset:3584
	s_waitcnt vmcnt(8)
	ds_write_b128 v247, v[116:119]
	ds_write_b128 v247, v[120:123] offset:1024
	ds_write_b128 v247, v[124:127] offset:2048
	ds_write_b128 v247, v[128:131] offset:3072
	ds_read_b128 v[116:119], v248
	ds_read_b128 v[120:123], v249
	ds_read_b128 v[124:127], v250
	ds_read_b128 v[128:131], v251
	ds_write_b128 v112, v[132:135]
	ds_write_b128 v112, v[136:139] offset:1024
	ds_write_b128 v112, v[140:143] offset:2048
	ds_write_b128 v112, v[144:147] offset:3072
	v_mfma_f32_32x32x16_bf16 v[32:47], v[192:195], v[52:55], v[32:47]
	v_mfma_f32_32x32x16_bf16 v[32:47], v[196:199], v[56:59], v[32:47]
	v_mfma_f32_32x32x16_bf16 v[32:47], v[200:203], v[60:63], v[32:47]
	s_nop 11
	v_exp_f32_e32 v32, v32
	v_exp_f32_e32 v33, v33
	v_exp_f32_e32 v34, v34
	v_exp_f32_e32 v35, v35
	v_exp_f32_e32 v36, v36
	v_exp_f32_e32 v37, v37
	v_exp_f32_e32 v38, v38
	v_exp_f32_e32 v39, v39
	v_exp_f32_e32 v40, v40
	v_exp_f32_e32 v41, v41
	v_exp_f32_e32 v42, v42
	v_exp_f32_e32 v43, v43
	v_exp_f32_e32 v44, v44
	v_exp_f32_e32 v45, v45
	v_exp_f32_e32 v46, v46
	v_exp_f32_e32 v47, v47
	s_add_i32 s90, s67, 192
	v_add_u32_e32 v84, s90, v107
	v_add_u32_e32 v85, 0, v84
	v_add_u32_e32 v86, 1, v84
	v_add_u32_e32 v87, 2, v84
	v_add_u32_e32 v88, 3, v84
	v_cmp_gt_u32_e64 s[30:31], s98, v85
	v_cmp_gt_u32_e64 s[36:37], s98, v86
	v_cmp_gt_u32_e64 s[78:79], s98, v87
	v_cmp_gt_u32_e64 s[50:51], s98, v88
	v_cndmask_b32_e64 v32, 0, v32, s[30:31]
	v_add_u32_e32 v85, 8, v84
	v_cmp_gt_u32_e64 s[30:31], s98, v85
	v_cndmask_b32_e64 v33, 0, v33, s[36:37]
	v_add_u32_e32 v86, 9, v84
	v_cmp_gt_u32_e64 s[36:37], s98, v86
	v_cndmask_b32_e64 v34, 0, v34, s[78:79]
	v_add_u32_e32 v87, 10, v84
	v_cmp_gt_u32_e64 s[78:79], s98, v87
	v_cndmask_b32_e64 v35, 0, v35, s[50:51]
	v_add_u32_e32 v88, 11, v84
	v_cmp_gt_u32_e64 s[50:51], s98, v88
	v_cndmask_b32_e64 v36, 0, v36, s[30:31]
	v_add_u32_e32 v85, 16, v84
	v_cmp_gt_u32_e64 s[30:31], s98, v85
	v_cndmask_b32_e64 v37, 0, v37, s[36:37]
	v_add_u32_e32 v86, 17, v84
	v_cmp_gt_u32_e64 s[36:37], s98, v86
	v_cndmask_b32_e64 v38, 0, v38, s[78:79]
	v_add_u32_e32 v87, 18, v84
	v_cmp_gt_u32_e64 s[78:79], s98, v87
	v_cndmask_b32_e64 v39, 0, v39, s[50:51]
	v_add_u32_e32 v88, 19, v84
	v_cmp_gt_u32_e64 s[50:51], s98, v88
	v_cndmask_b32_e64 v40, 0, v40, s[30:31]
	v_add_u32_e32 v85, 24, v84
	v_cmp_gt_u32_e64 s[30:31], s98, v85
	v_cndmask_b32_e64 v41, 0, v41, s[36:37]
	v_add_u32_e32 v86, 25, v84
	v_cmp_gt_u32_e64 s[36:37], s98, v86
	v_cndmask_b32_e64 v42, 0, v42, s[78:79]
	v_add_u32_e32 v87, 26, v84
	v_cmp_gt_u32_e64 s[78:79], s98, v87
	v_cndmask_b32_e64 v43, 0, v43, s[50:51]
	v_add_u32_e32 v88, 27, v84
	v_cmp_gt_u32_e64 s[50:51], s98, v88
	v_nop
	v_cndmask_b32_e64 v44, 0, v44, s[30:31]
	v_cndmask_b32_e64 v45, 0, v45, s[36:37]
	v_cndmask_b32_e64 v46, 0, v46, s[78:79]
	v_cndmask_b32_e64 v47, 0, v47, s[50:51]
	v_cvt_pk_bf16_f32 v64, v32, v33
	v_cvt_pk_bf16_f32 v65, v34, v35
	v_cvt_pk_bf16_f32 v66, v36, v37
	v_cvt_pk_bf16_f32 v67, v38, v39
	v_cvt_pk_bf16_f32 v68, v40, v41
	v_cvt_pk_bf16_f32 v69, v42, v43
	v_cvt_pk_bf16_f32 v70, v44, v45
	v_cvt_pk_bf16_f32 v71, v46, v47
	v_pk_add_f32 v[232:233], v[232:233], v[32:33]
	v_pk_add_f32 v[232:233], v[232:233], v[34:35]
	v_pk_add_f32 v[232:233], v[232:233], v[36:37]
	v_pk_add_f32 v[232:233], v[232:233], v[38:39]
	v_pk_add_f32 v[232:233], v[232:233], v[40:41]
	v_pk_add_f32 v[232:233], v[232:233], v[42:43]
	v_pk_add_f32 v[232:233], v[232:233], v[44:45]
	v_pk_add_f32 v[232:233], v[232:233], v[46:47]
	ds_read2_b32 v[32:33], v115 offset0:68 offset1:69
	ds_read2_b32 v[34:35], v115 offset0:70 offset1:71
	ds_read2_b32 v[36:37], v115 offset0:76 offset1:77
	ds_read2_b32 v[38:39], v115 offset0:78 offset1:79
	ds_read2_b32 v[40:41], v115 offset0:85 offset1:86
	ds_read2_b32 v[42:43], v115 offset0:87 offset1:88
	ds_read2_b32 v[44:45], v115 offset0:93 offset1:94
	ds_read2_b32 v[46:47], v115 offset0:95 offset1:96
	s_waitcnt lgkmcnt(15)
	v_mfma_f32_32x32x16_bf16 v[0:15], v[64:67], v[72:75], v[0:15]
	v_mfma_f32_32x32x16_bf16 v[16:31], v[64:67], v[76:79], v[16:31]
	v_mfma_f32_32x32x16_bf16 v[0:15], v[68:71], v[220:223], v[0:15]
	v_mfma_f32_32x32x16_bf16 v[16:31], v[68:71], v[224:227], v[16:31]
	s_add_i32 s90, s67, 288
	v_add_u32_e32 v80, s90, v235
	v_add_u32_e32 v83, s90, v236
	v_add_u32_e32 v99, s90, v237
	v_add_u32_e32 v253, s90, v238
	v_add_u32_e32 v254, s90, v100
	v_add_u32_e32 v255, s90, v149
	v_med3_i32 v80, v80, 0, s99
	v_med3_i32 v83, v83, 0, s99
	v_med3_i32 v99, v99, 0, s99
	v_med3_i32 v253, v253, 0, s99
	v_med3_i32 v254, v254, 0, s99
	v_med3_i32 v255, v255, 0, s99
	v_mad_u32_u24 v80, v80, s100, v252
	v_mad_u32_u24 v83, v83, s100, v252
	v_mad_u32_u24 v99, v99, s100, v252
	v_mad_u32_u24 v253, v253, s100, v252
	v_mad_u32_u24 v254, v254, s100, v153
	v_mad_u32_u24 v255, v255, s100, v153
	global_load_dwordx4 v[188:191], v80, s[82:83]
	global_load_dwordx4 v[192:195], v83, s[82:83]
	global_load_dwordx4 v[196:199], v99, s[82:83]
	global_load_dwordx4 v[200:203], v253, s[82:83]
	global_load_dwordx4 v[204:207], v254, s[82:83] offset:768
	global_load_dwordx4 v[208:211], v255, s[82:83] offset:768
	global_load_dwordx4 v[212:215], v254, s[82:83] offset:832
	global_load_dwordx4 v[216:219], v255, s[82:83] offset:832
	s_waitcnt lgkmcnt(0)
	v_mfma_f32_32x32x16_bf16 v[32:47], v[116:119], v[48:51], v[32:47]
	ds_read_b64_tr_b16 v[72:73], v231
	ds_read_b64_tr_b16 v[74:75], v231 offset:512
	ds_read_b64_tr_b16 v[76:77], v231 offset:2048
	ds_read_b64_tr_b16 v[78:79], v231 offset:2560
	ds_read_b64_tr_b16 v[220:221], v231 offset:1024
	ds_read_b64_tr_b16 v[222:223], v231 offset:1536
	ds_read_b64_tr_b16 v[224:225], v231 offset:3072
	ds_read_b64_tr_b16 v[226:227], v231 offset:3584
	s_waitcnt vmcnt(8)
	ds_write_b128 v247, v[156:159]
	ds_write_b128 v247, v[160:163] offset:1024
	ds_write_b128 v247, v[164:167] offset:2048
	ds_write_b128 v247, v[168:171] offset:3072
	ds_read_b128 v[156:159], v248
	ds_read_b128 v[160:163], v249
	ds_read_b128 v[164:167], v250
	ds_read_b128 v[168:171], v251
	ds_write_b128 v112, v[172:175]
	ds_write_b128 v112, v[176:179] offset:1024
	ds_write_b128 v112, v[180:183] offset:2048
	ds_write_b128 v112, v[184:187] offset:3072
	v_mfma_f32_32x32x16_bf16 v[32:47], v[120:123], v[52:55], v[32:47]
	v_mfma_f32_32x32x16_bf16 v[32:47], v[124:127], v[56:59], v[32:47]
	v_mfma_f32_32x32x16_bf16 v[32:47], v[128:131], v[60:63], v[32:47]
	s_nop 11
	v_exp_f32_e32 v32, v32
	v_exp_f32_e32 v33, v33
	v_exp_f32_e32 v34, v34
	v_exp_f32_e32 v35, v35
	v_exp_f32_e32 v36, v36
	v_exp_f32_e32 v37, v37
	v_exp_f32_e32 v38, v38
	v_exp_f32_e32 v39, v39
	v_exp_f32_e32 v40, v40
	v_exp_f32_e32 v41, v41
	v_exp_f32_e32 v42, v42
	v_exp_f32_e32 v43, v43
	v_exp_f32_e32 v44, v44
	v_exp_f32_e32 v45, v45
	v_exp_f32_e32 v46, v46
	v_exp_f32_e32 v47, v47
	s_add_i32 s90, s67, 224
	v_add_u32_e32 v84, s90, v107
	v_add_u32_e32 v85, 0, v84
	v_add_u32_e32 v86, 1, v84
	v_add_u32_e32 v87, 2, v84
	v_add_u32_e32 v88, 3, v84
	v_cmp_gt_u32_e64 s[30:31], s98, v85
	v_cmp_gt_u32_e64 s[36:37], s98, v86
	v_cmp_gt_u32_e64 s[78:79], s98, v87
	v_cmp_gt_u32_e64 s[50:51], s98, v88
	v_cndmask_b32_e64 v32, 0, v32, s[30:31]
	v_add_u32_e32 v85, 8, v84
	v_cmp_gt_u32_e64 s[30:31], s98, v85
	v_cndmask_b32_e64 v33, 0, v33, s[36:37]
	v_add_u32_e32 v86, 9, v84
	v_cmp_gt_u32_e64 s[36:37], s98, v86
	v_cndmask_b32_e64 v34, 0, v34, s[78:79]
	v_add_u32_e32 v87, 10, v84
	v_cmp_gt_u32_e64 s[78:79], s98, v87
	v_cndmask_b32_e64 v35, 0, v35, s[50:51]
	v_add_u32_e32 v88, 11, v84
	v_cmp_gt_u32_e64 s[50:51], s98, v88
	v_cndmask_b32_e64 v36, 0, v36, s[30:31]
	v_add_u32_e32 v85, 16, v84
	v_cmp_gt_u32_e64 s[30:31], s98, v85
	v_cndmask_b32_e64 v37, 0, v37, s[36:37]
	v_add_u32_e32 v86, 17, v84
	v_cmp_gt_u32_e64 s[36:37], s98, v86
	v_cndmask_b32_e64 v38, 0, v38, s[78:79]
	v_add_u32_e32 v87, 18, v84
	v_cmp_gt_u32_e64 s[78:79], s98, v87
	v_cndmask_b32_e64 v39, 0, v39, s[50:51]
	v_add_u32_e32 v88, 19, v84
	v_cmp_gt_u32_e64 s[50:51], s98, v88
	v_cndmask_b32_e64 v40, 0, v40, s[30:31]
	v_add_u32_e32 v85, 24, v84
	v_cmp_gt_u32_e64 s[30:31], s98, v85
	v_cndmask_b32_e64 v41, 0, v41, s[36:37]
	v_add_u32_e32 v86, 25, v84
	v_cmp_gt_u32_e64 s[36:37], s98, v86
	v_cndmask_b32_e64 v42, 0, v42, s[78:79]
	v_add_u32_e32 v87, 26, v84
	v_cmp_gt_u32_e64 s[78:79], s98, v87
	v_cndmask_b32_e64 v43, 0, v43, s[50:51]
	v_add_u32_e32 v88, 27, v84
	v_cmp_gt_u32_e64 s[50:51], s98, v88
	v_nop
	v_cndmask_b32_e64 v44, 0, v44, s[30:31]
	v_cndmask_b32_e64 v45, 0, v45, s[36:37]
	v_cndmask_b32_e64 v46, 0, v46, s[78:79]
	v_cndmask_b32_e64 v47, 0, v47, s[50:51]
	v_cvt_pk_bf16_f32 v64, v32, v33
	v_cvt_pk_bf16_f32 v65, v34, v35
	v_cvt_pk_bf16_f32 v66, v36, v37
	v_cvt_pk_bf16_f32 v67, v38, v39
	v_cvt_pk_bf16_f32 v68, v40, v41
	v_cvt_pk_bf16_f32 v69, v42, v43
	v_cvt_pk_bf16_f32 v70, v44, v45
	v_cvt_pk_bf16_f32 v71, v46, v47
	v_pk_add_f32 v[232:233], v[232:233], v[32:33]
	v_pk_add_f32 v[232:233], v[232:233], v[34:35]
	v_pk_add_f32 v[232:233], v[232:233], v[36:37]
	v_pk_add_f32 v[232:233], v[232:233], v[38:39]
	v_pk_add_f32 v[232:233], v[232:233], v[40:41]
	v_pk_add_f32 v[232:233], v[232:233], v[42:43]
	v_pk_add_f32 v[232:233], v[232:233], v[44:45]
	v_pk_add_f32 v[232:233], v[232:233], v[46:47]
	ds_read2_b32 v[32:33], v115 offset0:102 offset1:103
	ds_read2_b32 v[34:35], v115 offset0:104 offset1:105
	ds_read2_b32 v[36:37], v115 offset0:110 offset1:111
	ds_read2_b32 v[38:39], v115 offset0:112 offset1:113
	ds_read2_b32 v[40:41], v115 offset0:119 offset1:120
	ds_read2_b32 v[42:43], v115 offset0:121 offset1:122
	ds_read2_b32 v[44:45], v115 offset0:127 offset1:128
	ds_read2_b32 v[46:47], v115 offset0:129 offset1:130
	s_waitcnt lgkmcnt(15)
	v_mfma_f32_32x32x16_bf16 v[0:15], v[64:67], v[72:75], v[0:15]
	v_mfma_f32_32x32x16_bf16 v[16:31], v[64:67], v[76:79], v[16:31]
	v_mfma_f32_32x32x16_bf16 v[0:15], v[68:71], v[220:223], v[0:15]
	v_mfma_f32_32x32x16_bf16 v[16:31], v[68:71], v[224:227], v[16:31]
	s_add_i32 s90, s67, 320
	v_add_u32_e32 v80, s90, v235
	v_add_u32_e32 v83, s90, v236
	v_add_u32_e32 v99, s90, v237
	v_add_u32_e32 v253, s90, v238
	v_add_u32_e32 v254, s90, v100
	v_add_u32_e32 v255, s90, v149
	v_med3_i32 v80, v80, 0, s99
	v_med3_i32 v83, v83, 0, s99
	v_med3_i32 v99, v99, 0, s99
	v_med3_i32 v253, v253, 0, s99
	v_med3_i32 v254, v254, 0, s99
	v_med3_i32 v255, v255, 0, s99
	v_mad_u32_u24 v80, v80, s100, v252
	v_mad_u32_u24 v83, v83, s100, v252
	v_mad_u32_u24 v99, v99, s100, v252
	v_mad_u32_u24 v253, v253, s100, v252
	v_mad_u32_u24 v254, v254, s100, v153
	v_mad_u32_u24 v255, v255, s100, v153
	global_load_dwordx4 v[116:119], v80, s[82:83]
	global_load_dwordx4 v[120:123], v83, s[82:83]
	global_load_dwordx4 v[124:127], v99, s[82:83]
	global_load_dwordx4 v[128:131], v253, s[82:83]
	global_load_dwordx4 v[132:135], v254, s[82:83] offset:768
	global_load_dwordx4 v[136:139], v255, s[82:83] offset:768
	global_load_dwordx4 v[140:143], v254, s[82:83] offset:832
	global_load_dwordx4 v[144:147], v255, s[82:83] offset:832
	s_waitcnt lgkmcnt(0)
	v_mfma_f32_32x32x16_bf16 v[32:47], v[156:159], v[48:51], v[32:47]
	ds_read_b64_tr_b16 v[72:73], v231
	ds_read_b64_tr_b16 v[74:75], v231 offset:512
	ds_read_b64_tr_b16 v[76:77], v231 offset:2048
	ds_read_b64_tr_b16 v[78:79], v231 offset:2560
	ds_read_b64_tr_b16 v[220:221], v231 offset:1024
	ds_read_b64_tr_b16 v[222:223], v231 offset:1536
	ds_read_b64_tr_b16 v[224:225], v231 offset:3072
	ds_read_b64_tr_b16 v[226:227], v231 offset:3584
	s_waitcnt vmcnt(8)
	ds_write_b128 v247, v[188:191]
	ds_write_b128 v247, v[192:195] offset:1024
	ds_write_b128 v247, v[196:199] offset:2048
	ds_write_b128 v247, v[200:203] offset:3072
	ds_read_b128 v[188:191], v248
	ds_read_b128 v[192:195], v249
	ds_read_b128 v[196:199], v250
	ds_read_b128 v[200:203], v251
	ds_write_b128 v112, v[204:207]
	ds_write_b128 v112, v[208:211] offset:1024
	ds_write_b128 v112, v[212:215] offset:2048
	ds_write_b128 v112, v[216:219] offset:3072
	v_mfma_f32_32x32x16_bf16 v[32:47], v[160:163], v[52:55], v[32:47]
	v_mfma_f32_32x32x16_bf16 v[32:47], v[164:167], v[56:59], v[32:47]
	v_mfma_f32_32x32x16_bf16 v[32:47], v[168:171], v[60:63], v[32:47]
	s_nop 11
	v_exp_f32_e32 v32, v32
	v_exp_f32_e32 v33, v33
	v_exp_f32_e32 v34, v34
	v_exp_f32_e32 v35, v35
	v_exp_f32_e32 v36, v36
	v_exp_f32_e32 v37, v37
	v_exp_f32_e32 v38, v38
	v_exp_f32_e32 v39, v39
	v_exp_f32_e32 v40, v40
	v_exp_f32_e32 v41, v41
	v_exp_f32_e32 v42, v42
	v_exp_f32_e32 v43, v43
	v_exp_f32_e32 v44, v44
	v_exp_f32_e32 v45, v45
	v_exp_f32_e32 v46, v46
	v_exp_f32_e32 v47, v47
	s_add_i32 s90, s67, 256
	v_add_u32_e32 v84, s90, v107
	v_add_u32_e32 v85, 0, v84
	v_add_u32_e32 v86, 1, v84
	v_add_u32_e32 v87, 2, v84
	v_add_u32_e32 v88, 3, v84
	v_cmp_gt_u32_e64 s[30:31], s98, v85
	v_cmp_gt_u32_e64 s[36:37], s98, v86
	v_cmp_gt_u32_e64 s[78:79], s98, v87
	v_cmp_gt_u32_e64 s[50:51], s98, v88
	v_cndmask_b32_e64 v32, 0, v32, s[30:31]
	v_add_u32_e32 v85, 8, v84
	v_cmp_gt_u32_e64 s[30:31], s98, v85
	v_cndmask_b32_e64 v33, 0, v33, s[36:37]
	v_add_u32_e32 v86, 9, v84
	v_cmp_gt_u32_e64 s[36:37], s98, v86
	v_cndmask_b32_e64 v34, 0, v34, s[78:79]
	v_add_u32_e32 v87, 10, v84
	v_cmp_gt_u32_e64 s[78:79], s98, v87
	v_cndmask_b32_e64 v35, 0, v35, s[50:51]
	v_add_u32_e32 v88, 11, v84
	v_cmp_gt_u32_e64 s[50:51], s98, v88
	v_cndmask_b32_e64 v36, 0, v36, s[30:31]
	v_add_u32_e32 v85, 16, v84
	v_cmp_gt_u32_e64 s[30:31], s98, v85
	v_cndmask_b32_e64 v37, 0, v37, s[36:37]
	v_add_u32_e32 v86, 17, v84
	v_cmp_gt_u32_e64 s[36:37], s98, v86
	v_cndmask_b32_e64 v38, 0, v38, s[78:79]
	v_add_u32_e32 v87, 18, v84
	v_cmp_gt_u32_e64 s[78:79], s98, v87
	v_cndmask_b32_e64 v39, 0, v39, s[50:51]
	v_add_u32_e32 v88, 19, v84
	v_cmp_gt_u32_e64 s[50:51], s98, v88
	v_cndmask_b32_e64 v40, 0, v40, s[30:31]
	v_add_u32_e32 v85, 24, v84
	v_cmp_gt_u32_e64 s[30:31], s98, v85
	v_cndmask_b32_e64 v41, 0, v41, s[36:37]
	v_add_u32_e32 v86, 25, v84
	v_cmp_gt_u32_e64 s[36:37], s98, v86
	v_cndmask_b32_e64 v42, 0, v42, s[78:79]
	v_add_u32_e32 v87, 26, v84
	v_cmp_gt_u32_e64 s[78:79], s98, v87
	v_cndmask_b32_e64 v43, 0, v43, s[50:51]
	v_add_u32_e32 v88, 27, v84
	v_cmp_gt_u32_e64 s[50:51], s98, v88
	v_nop
	v_cndmask_b32_e64 v44, 0, v44, s[30:31]
	v_cndmask_b32_e64 v45, 0, v45, s[36:37]
	v_cndmask_b32_e64 v46, 0, v46, s[78:79]
	v_cndmask_b32_e64 v47, 0, v47, s[50:51]
	v_cvt_pk_bf16_f32 v64, v32, v33
	v_cvt_pk_bf16_f32 v65, v34, v35
	v_cvt_pk_bf16_f32 v66, v36, v37
	v_cvt_pk_bf16_f32 v67, v38, v39
	v_cvt_pk_bf16_f32 v68, v40, v41
	v_cvt_pk_bf16_f32 v69, v42, v43
	v_cvt_pk_bf16_f32 v70, v44, v45
	v_cvt_pk_bf16_f32 v71, v46, v47
	v_pk_add_f32 v[232:233], v[232:233], v[32:33]
	v_pk_add_f32 v[232:233], v[232:233], v[34:35]
	v_pk_add_f32 v[232:233], v[232:233], v[36:37]
	v_pk_add_f32 v[232:233], v[232:233], v[38:39]
	v_pk_add_f32 v[232:233], v[232:233], v[40:41]
	v_pk_add_f32 v[232:233], v[232:233], v[42:43]
	v_pk_add_f32 v[232:233], v[232:233], v[44:45]
	v_pk_add_f32 v[232:233], v[232:233], v[46:47]
	ds_read2_b32 v[32:33], v115 offset0:136 offset1:137
	ds_read2_b32 v[34:35], v115 offset0:138 offset1:139
	ds_read2_b32 v[36:37], v115 offset0:144 offset1:145
	ds_read2_b32 v[38:39], v115 offset0:146 offset1:147
	ds_read2_b32 v[40:41], v115 offset0:153 offset1:154
	ds_read2_b32 v[42:43], v115 offset0:155 offset1:156
	ds_read2_b32 v[44:45], v115 offset0:161 offset1:162
	ds_read2_b32 v[46:47], v115 offset0:163 offset1:164
	s_waitcnt lgkmcnt(15)
	v_mfma_f32_32x32x16_bf16 v[0:15], v[64:67], v[72:75], v[0:15]
	v_mfma_f32_32x32x16_bf16 v[16:31], v[64:67], v[76:79], v[16:31]
	v_mfma_f32_32x32x16_bf16 v[0:15], v[68:71], v[220:223], v[0:15]
	v_mfma_f32_32x32x16_bf16 v[16:31], v[68:71], v[224:227], v[16:31]
	s_add_i32 s90, s67, 352
	v_add_u32_e32 v80, s90, v235
	v_add_u32_e32 v83, s90, v236
	v_add_u32_e32 v99, s90, v237
	v_add_u32_e32 v253, s90, v238
	v_add_u32_e32 v254, s90, v100
	v_add_u32_e32 v255, s90, v149
	v_med3_i32 v80, v80, 0, s99
	v_med3_i32 v83, v83, 0, s99
	v_med3_i32 v99, v99, 0, s99
	v_med3_i32 v253, v253, 0, s99
	v_med3_i32 v254, v254, 0, s99
	v_med3_i32 v255, v255, 0, s99
	v_mad_u32_u24 v80, v80, s100, v252
	v_mad_u32_u24 v83, v83, s100, v252
	v_mad_u32_u24 v99, v99, s100, v252
	v_mad_u32_u24 v253, v253, s100, v252
	v_mad_u32_u24 v254, v254, s100, v153
	v_mad_u32_u24 v255, v255, s100, v153
	global_load_dwordx4 v[156:159], v80, s[82:83]
	global_load_dwordx4 v[160:163], v83, s[82:83]
	global_load_dwordx4 v[164:167], v99, s[82:83]
	global_load_dwordx4 v[168:171], v253, s[82:83]
	global_load_dwordx4 v[172:175], v254, s[82:83] offset:768
	global_load_dwordx4 v[176:179], v255, s[82:83] offset:768
	global_load_dwordx4 v[180:183], v254, s[82:83] offset:832
	global_load_dwordx4 v[184:187], v255, s[82:83] offset:832
	s_waitcnt lgkmcnt(0)
	v_mfma_f32_32x32x16_bf16 v[32:47], v[188:191], v[48:51], v[32:47]
	ds_read_b64_tr_b16 v[72:73], v231
	ds_read_b64_tr_b16 v[74:75], v231 offset:512
	ds_read_b64_tr_b16 v[76:77], v231 offset:2048
	ds_read_b64_tr_b16 v[78:79], v231 offset:2560
	ds_read_b64_tr_b16 v[220:221], v231 offset:1024
	ds_read_b64_tr_b16 v[222:223], v231 offset:1536
	ds_read_b64_tr_b16 v[224:225], v231 offset:3072
	ds_read_b64_tr_b16 v[226:227], v231 offset:3584
	s_waitcnt vmcnt(8)
	ds_write_b128 v247, v[116:119]
	ds_write_b128 v247, v[120:123] offset:1024
	ds_write_b128 v247, v[124:127] offset:2048
	ds_write_b128 v247, v[128:131] offset:3072
	ds_read_b128 v[116:119], v248
	ds_read_b128 v[120:123], v249
	ds_read_b128 v[124:127], v250
	ds_read_b128 v[128:131], v251
	ds_write_b128 v112, v[132:135]
	ds_write_b128 v112, v[136:139] offset:1024
	ds_write_b128 v112, v[140:143] offset:2048
	ds_write_b128 v112, v[144:147] offset:3072
	v_mfma_f32_32x32x16_bf16 v[32:47], v[192:195], v[52:55], v[32:47]
	v_mfma_f32_32x32x16_bf16 v[32:47], v[196:199], v[56:59], v[32:47]
	v_mfma_f32_32x32x16_bf16 v[32:47], v[200:203], v[60:63], v[32:47]
	s_nop 11
	v_exp_f32_e32 v32, v32
	v_exp_f32_e32 v33, v33
	v_exp_f32_e32 v34, v34
	v_exp_f32_e32 v35, v35
	v_exp_f32_e32 v36, v36
	v_exp_f32_e32 v37, v37
	v_exp_f32_e32 v38, v38
	v_exp_f32_e32 v39, v39
	v_exp_f32_e32 v40, v40
	v_exp_f32_e32 v41, v41
	v_exp_f32_e32 v42, v42
	v_exp_f32_e32 v43, v43
	v_exp_f32_e32 v44, v44
	v_exp_f32_e32 v45, v45
	v_exp_f32_e32 v46, v46
	v_exp_f32_e32 v47, v47
	s_add_i32 s90, s67, 288
	v_add_u32_e32 v84, s90, v107
	v_add_u32_e32 v85, 0, v84
	v_add_u32_e32 v86, 1, v84
	v_add_u32_e32 v87, 2, v84
	v_add_u32_e32 v88, 3, v84
	v_cmp_gt_u32_e64 s[30:31], s98, v85
	v_cmp_gt_u32_e64 s[36:37], s98, v86
	v_cmp_gt_u32_e64 s[78:79], s98, v87
	v_cmp_gt_u32_e64 s[50:51], s98, v88
	v_cndmask_b32_e64 v32, 0, v32, s[30:31]
	v_add_u32_e32 v85, 8, v84
	v_cmp_gt_u32_e64 s[30:31], s98, v85
	v_cndmask_b32_e64 v33, 0, v33, s[36:37]
	v_add_u32_e32 v86, 9, v84
	v_cmp_gt_u32_e64 s[36:37], s98, v86
	v_cndmask_b32_e64 v34, 0, v34, s[78:79]
	v_add_u32_e32 v87, 10, v84
	v_cmp_gt_u32_e64 s[78:79], s98, v87
	v_cndmask_b32_e64 v35, 0, v35, s[50:51]
	v_add_u32_e32 v88, 11, v84
	v_cmp_gt_u32_e64 s[50:51], s98, v88
	v_cndmask_b32_e64 v36, 0, v36, s[30:31]
	v_add_u32_e32 v85, 16, v84
	v_cmp_gt_u32_e64 s[30:31], s98, v85
	v_cndmask_b32_e64 v37, 0, v37, s[36:37]
	v_add_u32_e32 v86, 17, v84
	v_cmp_gt_u32_e64 s[36:37], s98, v86
	v_cndmask_b32_e64 v38, 0, v38, s[78:79]
	v_add_u32_e32 v87, 18, v84
	v_cmp_gt_u32_e64 s[78:79], s98, v87
	v_cndmask_b32_e64 v39, 0, v39, s[50:51]
	v_add_u32_e32 v88, 19, v84
	v_cmp_gt_u32_e64 s[50:51], s98, v88
	v_cndmask_b32_e64 v40, 0, v40, s[30:31]
	v_add_u32_e32 v85, 24, v84
	v_cmp_gt_u32_e64 s[30:31], s98, v85
	v_cndmask_b32_e64 v41, 0, v41, s[36:37]
	v_add_u32_e32 v86, 25, v84
	v_cmp_gt_u32_e64 s[36:37], s98, v86
	v_cndmask_b32_e64 v42, 0, v42, s[78:79]
	v_add_u32_e32 v87, 26, v84
	v_cmp_gt_u32_e64 s[78:79], s98, v87
	v_cndmask_b32_e64 v43, 0, v43, s[50:51]
	v_add_u32_e32 v88, 27, v84
	v_cmp_gt_u32_e64 s[50:51], s98, v88
	v_nop
	v_cndmask_b32_e64 v44, 0, v44, s[30:31]
	v_cndmask_b32_e64 v45, 0, v45, s[36:37]
	v_cndmask_b32_e64 v46, 0, v46, s[78:79]
	v_cndmask_b32_e64 v47, 0, v47, s[50:51]
	v_cvt_pk_bf16_f32 v64, v32, v33
	v_cvt_pk_bf16_f32 v65, v34, v35
	v_cvt_pk_bf16_f32 v66, v36, v37
	v_cvt_pk_bf16_f32 v67, v38, v39
	v_cvt_pk_bf16_f32 v68, v40, v41
	v_cvt_pk_bf16_f32 v69, v42, v43
	v_cvt_pk_bf16_f32 v70, v44, v45
	v_cvt_pk_bf16_f32 v71, v46, v47
	v_pk_add_f32 v[232:233], v[232:233], v[32:33]
	v_pk_add_f32 v[232:233], v[232:233], v[34:35]
	v_pk_add_f32 v[232:233], v[232:233], v[36:37]
	v_pk_add_f32 v[232:233], v[232:233], v[38:39]
	v_pk_add_f32 v[232:233], v[232:233], v[40:41]
	v_pk_add_f32 v[232:233], v[232:233], v[42:43]
	v_pk_add_f32 v[232:233], v[232:233], v[44:45]
	v_pk_add_f32 v[232:233], v[232:233], v[46:47]
	ds_read2_b32 v[32:33], v115 offset0:170 offset1:171
	ds_read2_b32 v[34:35], v115 offset0:172 offset1:173
	ds_read2_b32 v[36:37], v115 offset0:178 offset1:179
	ds_read2_b32 v[38:39], v115 offset0:180 offset1:181
	ds_read2_b32 v[40:41], v115 offset0:187 offset1:188
	ds_read2_b32 v[42:43], v115 offset0:189 offset1:190
	ds_read2_b32 v[44:45], v115 offset0:195 offset1:196
	ds_read2_b32 v[46:47], v115 offset0:197 offset1:198
	s_waitcnt lgkmcnt(15)
	v_mfma_f32_32x32x16_bf16 v[0:15], v[64:67], v[72:75], v[0:15]
	v_mfma_f32_32x32x16_bf16 v[16:31], v[64:67], v[76:79], v[16:31]
	v_mfma_f32_32x32x16_bf16 v[0:15], v[68:71], v[220:223], v[0:15]
	v_mfma_f32_32x32x16_bf16 v[16:31], v[68:71], v[224:227], v[16:31]
	s_add_i32 s90, s67, 384
	v_add_u32_e32 v80, s90, v235
	v_add_u32_e32 v83, s90, v236
	v_add_u32_e32 v99, s90, v237
	v_add_u32_e32 v253, s90, v238
	v_add_u32_e32 v254, s90, v100
	v_add_u32_e32 v255, s90, v149
	v_med3_i32 v80, v80, 0, s99
	v_med3_i32 v83, v83, 0, s99
	v_med3_i32 v99, v99, 0, s99
	v_med3_i32 v253, v253, 0, s99
	v_med3_i32 v254, v254, 0, s99
	v_med3_i32 v255, v255, 0, s99
	v_mad_u32_u24 v80, v80, s100, v252
	v_mad_u32_u24 v83, v83, s100, v252
	v_mad_u32_u24 v99, v99, s100, v252
	v_mad_u32_u24 v253, v253, s100, v252
	v_mad_u32_u24 v254, v254, s100, v153
	v_mad_u32_u24 v255, v255, s100, v153
	global_load_dwordx4 v[188:191], v80, s[82:83]
	global_load_dwordx4 v[192:195], v83, s[82:83]
	global_load_dwordx4 v[196:199], v99, s[82:83]
	global_load_dwordx4 v[200:203], v253, s[82:83]
	global_load_dwordx4 v[204:207], v254, s[82:83] offset:768
	global_load_dwordx4 v[208:211], v255, s[82:83] offset:768
	global_load_dwordx4 v[212:215], v254, s[82:83] offset:832
	global_load_dwordx4 v[216:219], v255, s[82:83] offset:832
	s_waitcnt lgkmcnt(0)
	v_mfma_f32_32x32x16_bf16 v[32:47], v[116:119], v[48:51], v[32:47]
	ds_read_b64_tr_b16 v[72:73], v231
	ds_read_b64_tr_b16 v[74:75], v231 offset:512
	ds_read_b64_tr_b16 v[76:77], v231 offset:2048
	ds_read_b64_tr_b16 v[78:79], v231 offset:2560
	ds_read_b64_tr_b16 v[220:221], v231 offset:1024
	ds_read_b64_tr_b16 v[222:223], v231 offset:1536
	ds_read_b64_tr_b16 v[224:225], v231 offset:3072
	ds_read_b64_tr_b16 v[226:227], v231 offset:3584
	s_waitcnt vmcnt(8)
	ds_write_b128 v247, v[156:159]
	ds_write_b128 v247, v[160:163] offset:1024
	ds_write_b128 v247, v[164:167] offset:2048
	ds_write_b128 v247, v[168:171] offset:3072
	ds_read_b128 v[156:159], v248
	ds_read_b128 v[160:163], v249
	ds_read_b128 v[164:167], v250
	ds_read_b128 v[168:171], v251
	ds_write_b128 v112, v[172:175]
	ds_write_b128 v112, v[176:179] offset:1024
	ds_write_b128 v112, v[180:183] offset:2048
	ds_write_b128 v112, v[184:187] offset:3072
	v_mfma_f32_32x32x16_bf16 v[32:47], v[120:123], v[52:55], v[32:47]
	v_mfma_f32_32x32x16_bf16 v[32:47], v[124:127], v[56:59], v[32:47]
	v_mfma_f32_32x32x16_bf16 v[32:47], v[128:131], v[60:63], v[32:47]
	s_nop 11
	v_exp_f32_e32 v32, v32
	v_exp_f32_e32 v33, v33
	v_exp_f32_e32 v34, v34
	v_exp_f32_e32 v35, v35
	v_exp_f32_e32 v36, v36
	v_exp_f32_e32 v37, v37
	v_exp_f32_e32 v38, v38
	v_exp_f32_e32 v39, v39
	v_exp_f32_e32 v40, v40
	v_exp_f32_e32 v41, v41
	v_exp_f32_e32 v42, v42
	v_exp_f32_e32 v43, v43
	v_exp_f32_e32 v44, v44
	v_exp_f32_e32 v45, v45
	v_exp_f32_e32 v46, v46
	v_exp_f32_e32 v47, v47
	s_add_i32 s90, s67, 320
	v_add_u32_e32 v84, s90, v107
	v_add_u32_e32 v85, 0, v84
	v_add_u32_e32 v86, 1, v84
	v_add_u32_e32 v87, 2, v84
	v_add_u32_e32 v88, 3, v84
	v_cmp_gt_u32_e64 s[30:31], s98, v85
	v_cmp_gt_u32_e64 s[36:37], s98, v86
	v_cmp_gt_u32_e64 s[78:79], s98, v87
	v_cmp_gt_u32_e64 s[50:51], s98, v88
	v_cndmask_b32_e64 v32, 0, v32, s[30:31]
	v_add_u32_e32 v85, 8, v84
	v_cmp_gt_u32_e64 s[30:31], s98, v85
	v_cndmask_b32_e64 v33, 0, v33, s[36:37]
	v_add_u32_e32 v86, 9, v84
	v_cmp_gt_u32_e64 s[36:37], s98, v86
	v_cndmask_b32_e64 v34, 0, v34, s[78:79]
	v_add_u32_e32 v87, 10, v84
	v_cmp_gt_u32_e64 s[78:79], s98, v87
	v_cndmask_b32_e64 v35, 0, v35, s[50:51]
	v_add_u32_e32 v88, 11, v84
	v_cmp_gt_u32_e64 s[50:51], s98, v88
	v_cndmask_b32_e64 v36, 0, v36, s[30:31]
	v_add_u32_e32 v85, 16, v84
	v_cmp_gt_u32_e64 s[30:31], s98, v85
	v_cndmask_b32_e64 v37, 0, v37, s[36:37]
	v_add_u32_e32 v86, 17, v84
	v_cmp_gt_u32_e64 s[36:37], s98, v86
	v_cndmask_b32_e64 v38, 0, v38, s[78:79]
	v_add_u32_e32 v87, 18, v84
	v_cmp_gt_u32_e64 s[78:79], s98, v87
	v_cndmask_b32_e64 v39, 0, v39, s[50:51]
	v_add_u32_e32 v88, 19, v84
	v_cmp_gt_u32_e64 s[50:51], s98, v88
	v_cndmask_b32_e64 v40, 0, v40, s[30:31]
	v_add_u32_e32 v85, 24, v84
	v_cmp_gt_u32_e64 s[30:31], s98, v85
	v_cndmask_b32_e64 v41, 0, v41, s[36:37]
	v_add_u32_e32 v86, 25, v84
	v_cmp_gt_u32_e64 s[36:37], s98, v86
	v_cndmask_b32_e64 v42, 0, v42, s[78:79]
	v_add_u32_e32 v87, 26, v84
	v_cmp_gt_u32_e64 s[78:79], s98, v87
	v_cndmask_b32_e64 v43, 0, v43, s[50:51]
	v_add_u32_e32 v88, 27, v84
	v_cmp_gt_u32_e64 s[50:51], s98, v88
	v_nop
	v_cndmask_b32_e64 v44, 0, v44, s[30:31]
	v_cndmask_b32_e64 v45, 0, v45, s[36:37]
	v_cndmask_b32_e64 v46, 0, v46, s[78:79]
	v_cndmask_b32_e64 v47, 0, v47, s[50:51]
	v_cvt_pk_bf16_f32 v64, v32, v33
	v_cvt_pk_bf16_f32 v65, v34, v35
	v_cvt_pk_bf16_f32 v66, v36, v37
	v_cvt_pk_bf16_f32 v67, v38, v39
	v_cvt_pk_bf16_f32 v68, v40, v41
	v_cvt_pk_bf16_f32 v69, v42, v43
	v_cvt_pk_bf16_f32 v70, v44, v45
	v_cvt_pk_bf16_f32 v71, v46, v47
	v_pk_add_f32 v[232:233], v[232:233], v[32:33]
	v_pk_add_f32 v[232:233], v[232:233], v[34:35]
	v_pk_add_f32 v[232:233], v[232:233], v[36:37]
	v_pk_add_f32 v[232:233], v[232:233], v[38:39]
	v_pk_add_f32 v[232:233], v[232:233], v[40:41]
	v_pk_add_f32 v[232:233], v[232:233], v[42:43]
	v_pk_add_f32 v[232:233], v[232:233], v[44:45]
	v_pk_add_f32 v[232:233], v[232:233], v[46:47]
	ds_read2_b32 v[32:33], v115 offset0:204 offset1:205
	ds_read2_b32 v[34:35], v115 offset0:206 offset1:207
	ds_read2_b32 v[36:37], v115 offset0:212 offset1:213
	ds_read2_b32 v[38:39], v115 offset0:214 offset1:215
	ds_read2_b32 v[40:41], v115 offset0:221 offset1:222
	ds_read2_b32 v[42:43], v115 offset0:223 offset1:224
	ds_read2_b32 v[44:45], v115 offset0:229 offset1:230
	ds_read2_b32 v[46:47], v115 offset0:231 offset1:232
	s_waitcnt lgkmcnt(15)
	v_mfma_f32_32x32x16_bf16 v[0:15], v[64:67], v[72:75], v[0:15]
	v_mfma_f32_32x32x16_bf16 v[16:31], v[64:67], v[76:79], v[16:31]
	v_mfma_f32_32x32x16_bf16 v[0:15], v[68:71], v[220:223], v[0:15]
	v_mfma_f32_32x32x16_bf16 v[16:31], v[68:71], v[224:227], v[16:31]
	s_add_i32 s90, s67, 416
	v_add_u32_e32 v80, s90, v235
	v_add_u32_e32 v83, s90, v236
	v_add_u32_e32 v99, s90, v237
	v_add_u32_e32 v253, s90, v238
	v_add_u32_e32 v254, s90, v100
	v_add_u32_e32 v255, s90, v149
	v_med3_i32 v80, v80, 0, s99
	v_med3_i32 v83, v83, 0, s99
	v_med3_i32 v99, v99, 0, s99
	v_med3_i32 v253, v253, 0, s99
	v_med3_i32 v254, v254, 0, s99
	v_med3_i32 v255, v255, 0, s99
	v_mad_u32_u24 v80, v80, s100, v252
	v_mad_u32_u24 v83, v83, s100, v252
	v_mad_u32_u24 v99, v99, s100, v252
	v_mad_u32_u24 v253, v253, s100, v252
	v_mad_u32_u24 v254, v254, s100, v153
	v_mad_u32_u24 v255, v255, s100, v153
	global_load_dwordx4 v[116:119], v80, s[82:83]
	global_load_dwordx4 v[120:123], v83, s[82:83]
	global_load_dwordx4 v[124:127], v99, s[82:83]
	global_load_dwordx4 v[128:131], v253, s[82:83]
	global_load_dwordx4 v[132:135], v254, s[82:83] offset:768
	global_load_dwordx4 v[136:139], v255, s[82:83] offset:768
	global_load_dwordx4 v[140:143], v254, s[82:83] offset:832
	global_load_dwordx4 v[144:147], v255, s[82:83] offset:832
	s_waitcnt lgkmcnt(0)
	v_mfma_f32_32x32x16_bf16 v[32:47], v[156:159], v[48:51], v[32:47]
	ds_read_b64_tr_b16 v[72:73], v231
	ds_read_b64_tr_b16 v[74:75], v231 offset:512
	ds_read_b64_tr_b16 v[76:77], v231 offset:2048
	ds_read_b64_tr_b16 v[78:79], v231 offset:2560
	ds_read_b64_tr_b16 v[220:221], v231 offset:1024
	ds_read_b64_tr_b16 v[222:223], v231 offset:1536
	ds_read_b64_tr_b16 v[224:225], v231 offset:3072
	ds_read_b64_tr_b16 v[226:227], v231 offset:3584
	s_waitcnt vmcnt(8)
	ds_write_b128 v247, v[188:191]
	ds_write_b128 v247, v[192:195] offset:1024
	ds_write_b128 v247, v[196:199] offset:2048
	ds_write_b128 v247, v[200:203] offset:3072
	ds_read_b128 v[188:191], v248
	ds_read_b128 v[192:195], v249
	ds_read_b128 v[196:199], v250
	ds_read_b128 v[200:203], v251
	ds_write_b128 v112, v[204:207]
	ds_write_b128 v112, v[208:211] offset:1024
	ds_write_b128 v112, v[212:215] offset:2048
	ds_write_b128 v112, v[216:219] offset:3072
	v_mfma_f32_32x32x16_bf16 v[32:47], v[160:163], v[52:55], v[32:47]
	v_mfma_f32_32x32x16_bf16 v[32:47], v[164:167], v[56:59], v[32:47]
	v_mfma_f32_32x32x16_bf16 v[32:47], v[168:171], v[60:63], v[32:47]
	s_nop 11
	v_exp_f32_e32 v32, v32
	v_exp_f32_e32 v33, v33
	v_exp_f32_e32 v34, v34
	v_exp_f32_e32 v35, v35
	v_exp_f32_e32 v36, v36
	v_exp_f32_e32 v37, v37
	v_exp_f32_e32 v38, v38
	v_exp_f32_e32 v39, v39
	v_exp_f32_e32 v40, v40
	v_exp_f32_e32 v41, v41
	v_exp_f32_e32 v42, v42
	v_exp_f32_e32 v43, v43
	v_exp_f32_e32 v44, v44
	v_exp_f32_e32 v45, v45
	v_exp_f32_e32 v46, v46
	v_exp_f32_e32 v47, v47
	s_add_i32 s90, s67, 352
	v_add_u32_e32 v84, s90, v107
	v_add_u32_e32 v85, 0, v84
	v_add_u32_e32 v86, 1, v84
	v_add_u32_e32 v87, 2, v84
	v_add_u32_e32 v88, 3, v84
	v_cmp_gt_u32_e64 s[30:31], s98, v85
	v_cmp_gt_u32_e64 s[36:37], s98, v86
	v_cmp_gt_u32_e64 s[78:79], s98, v87
	v_cmp_gt_u32_e64 s[50:51], s98, v88
	v_cndmask_b32_e64 v32, 0, v32, s[30:31]
	v_add_u32_e32 v85, 8, v84
	v_cmp_gt_u32_e64 s[30:31], s98, v85
	v_cndmask_b32_e64 v33, 0, v33, s[36:37]
	v_add_u32_e32 v86, 9, v84
	v_cmp_gt_u32_e64 s[36:37], s98, v86
	v_cndmask_b32_e64 v34, 0, v34, s[78:79]
	v_add_u32_e32 v87, 10, v84
	v_cmp_gt_u32_e64 s[78:79], s98, v87
	v_cndmask_b32_e64 v35, 0, v35, s[50:51]
	v_add_u32_e32 v88, 11, v84
	v_cmp_gt_u32_e64 s[50:51], s98, v88
	v_cndmask_b32_e64 v36, 0, v36, s[30:31]
	v_add_u32_e32 v85, 16, v84
	v_cmp_gt_u32_e64 s[30:31], s98, v85
	v_cndmask_b32_e64 v37, 0, v37, s[36:37]
	v_add_u32_e32 v86, 17, v84
	v_cmp_gt_u32_e64 s[36:37], s98, v86
	v_cndmask_b32_e64 v38, 0, v38, s[78:79]
	v_add_u32_e32 v87, 18, v84
	v_cmp_gt_u32_e64 s[78:79], s98, v87
	v_cndmask_b32_e64 v39, 0, v39, s[50:51]
	v_add_u32_e32 v88, 19, v84
	v_cmp_gt_u32_e64 s[50:51], s98, v88
	v_cndmask_b32_e64 v40, 0, v40, s[30:31]
	v_add_u32_e32 v85, 24, v84
	v_cmp_gt_u32_e64 s[30:31], s98, v85
	v_cndmask_b32_e64 v41, 0, v41, s[36:37]
	v_add_u32_e32 v86, 25, v84
	v_cmp_gt_u32_e64 s[36:37], s98, v86
	v_cndmask_b32_e64 v42, 0, v42, s[78:79]
	v_add_u32_e32 v87, 26, v84
	v_cmp_gt_u32_e64 s[78:79], s98, v87
	v_cndmask_b32_e64 v43, 0, v43, s[50:51]
	v_add_u32_e32 v88, 27, v84
	v_cmp_gt_u32_e64 s[50:51], s98, v88
	v_nop
	v_cndmask_b32_e64 v44, 0, v44, s[30:31]
	v_cndmask_b32_e64 v45, 0, v45, s[36:37]
	v_cndmask_b32_e64 v46, 0, v46, s[78:79]
	v_cndmask_b32_e64 v47, 0, v47, s[50:51]
	v_cvt_pk_bf16_f32 v64, v32, v33
	v_cvt_pk_bf16_f32 v65, v34, v35
	v_cvt_pk_bf16_f32 v66, v36, v37
	v_cvt_pk_bf16_f32 v67, v38, v39
	v_cvt_pk_bf16_f32 v68, v40, v41
	v_cvt_pk_bf16_f32 v69, v42, v43
	v_cvt_pk_bf16_f32 v70, v44, v45
	v_cvt_pk_bf16_f32 v71, v46, v47
	v_pk_add_f32 v[232:233], v[232:233], v[32:33]
	v_pk_add_f32 v[232:233], v[232:233], v[34:35]
	v_pk_add_f32 v[232:233], v[232:233], v[36:37]
	v_pk_add_f32 v[232:233], v[232:233], v[38:39]
	v_pk_add_f32 v[232:233], v[232:233], v[40:41]
	v_pk_add_f32 v[232:233], v[232:233], v[42:43]
	v_pk_add_f32 v[232:233], v[232:233], v[44:45]
	v_pk_add_f32 v[232:233], v[232:233], v[46:47]
	v_add_u32_e32 v115, 952, v115
	ds_read2_b32 v[32:33], v115 offset0:0 offset1:1
	ds_read2_b32 v[34:35], v115 offset0:2 offset1:3
	ds_read2_b32 v[36:37], v115 offset0:8 offset1:9
	ds_read2_b32 v[38:39], v115 offset0:10 offset1:11
	ds_read2_b32 v[40:41], v115 offset0:17 offset1:18
	ds_read2_b32 v[42:43], v115 offset0:19 offset1:20
	ds_read2_b32 v[44:45], v115 offset0:25 offset1:26
	ds_read2_b32 v[46:47], v115 offset0:27 offset1:28
	s_waitcnt lgkmcnt(15)
	v_mfma_f32_32x32x16_bf16 v[0:15], v[64:67], v[72:75], v[0:15]
	v_mfma_f32_32x32x16_bf16 v[16:31], v[64:67], v[76:79], v[16:31]
	v_mfma_f32_32x32x16_bf16 v[0:15], v[68:71], v[220:223], v[0:15]
	v_mfma_f32_32x32x16_bf16 v[16:31], v[68:71], v[224:227], v[16:31]
	s_add_i32 s90, s67, 448
	v_add_u32_e32 v80, s90, v235
	v_add_u32_e32 v83, s90, v236
	v_add_u32_e32 v99, s90, v237
	v_add_u32_e32 v253, s90, v238
	v_add_u32_e32 v254, s90, v100
	v_add_u32_e32 v255, s90, v149
	v_med3_i32 v80, v80, 0, s99
	v_med3_i32 v83, v83, 0, s99
	v_med3_i32 v99, v99, 0, s99
	v_med3_i32 v253, v253, 0, s99
	v_med3_i32 v254, v254, 0, s99
	v_med3_i32 v255, v255, 0, s99
	v_mad_u32_u24 v80, v80, s100, v252
	v_mad_u32_u24 v83, v83, s100, v252
	v_mad_u32_u24 v99, v99, s100, v252
	v_mad_u32_u24 v253, v253, s100, v252
	v_mad_u32_u24 v254, v254, s100, v153
	v_mad_u32_u24 v255, v255, s100, v153
	global_load_dwordx4 v[156:159], v80, s[82:83]
	global_load_dwordx4 v[160:163], v83, s[82:83]
	global_load_dwordx4 v[164:167], v99, s[82:83]
	global_load_dwordx4 v[168:171], v253, s[82:83]
	global_load_dwordx4 v[172:175], v254, s[82:83] offset:768
	global_load_dwordx4 v[176:179], v255, s[82:83] offset:768
	global_load_dwordx4 v[180:183], v254, s[82:83] offset:832
	global_load_dwordx4 v[184:187], v255, s[82:83] offset:832
	s_waitcnt lgkmcnt(0)
	v_mfma_f32_32x32x16_bf16 v[32:47], v[188:191], v[48:51], v[32:47]
	ds_read_b64_tr_b16 v[72:73], v231
	ds_read_b64_tr_b16 v[74:75], v231 offset:512
	ds_read_b64_tr_b16 v[76:77], v231 offset:2048
	ds_read_b64_tr_b16 v[78:79], v231 offset:2560
	ds_read_b64_tr_b16 v[220:221], v231 offset:1024
	ds_read_b64_tr_b16 v[222:223], v231 offset:1536
	ds_read_b64_tr_b16 v[224:225], v231 offset:3072
	ds_read_b64_tr_b16 v[226:227], v231 offset:3584
	s_waitcnt vmcnt(8)
	ds_write_b128 v247, v[116:119]
	ds_write_b128 v247, v[120:123] offset:1024
	ds_write_b128 v247, v[124:127] offset:2048
	ds_write_b128 v247, v[128:131] offset:3072
	ds_read_b128 v[116:119], v248
	ds_read_b128 v[120:123], v249
	ds_read_b128 v[124:127], v250
	ds_read_b128 v[128:131], v251
	ds_write_b128 v112, v[132:135]
	ds_write_b128 v112, v[136:139] offset:1024
	ds_write_b128 v112, v[140:143] offset:2048
	ds_write_b128 v112, v[144:147] offset:3072
	v_mfma_f32_32x32x16_bf16 v[32:47], v[192:195], v[52:55], v[32:47]
	v_mfma_f32_32x32x16_bf16 v[32:47], v[196:199], v[56:59], v[32:47]
	v_mfma_f32_32x32x16_bf16 v[32:47], v[200:203], v[60:63], v[32:47]
	s_nop 11
	v_exp_f32_e32 v32, v32
	v_exp_f32_e32 v33, v33
	v_exp_f32_e32 v34, v34
	v_exp_f32_e32 v35, v35
	v_exp_f32_e32 v36, v36
	v_exp_f32_e32 v37, v37
	v_exp_f32_e32 v38, v38
	v_exp_f32_e32 v39, v39
	v_exp_f32_e32 v40, v40
	v_exp_f32_e32 v41, v41
	v_exp_f32_e32 v42, v42
	v_exp_f32_e32 v43, v43
	v_exp_f32_e32 v44, v44
	v_exp_f32_e32 v45, v45
	v_exp_f32_e32 v46, v46
	v_exp_f32_e32 v47, v47
	s_add_i32 s90, s67, 384
	v_add_u32_e32 v84, s90, v107
	v_add_u32_e32 v85, 0, v84
	v_add_u32_e32 v86, 1, v84
	v_add_u32_e32 v87, 2, v84
	v_add_u32_e32 v88, 3, v84
	v_cmp_gt_u32_e64 s[30:31], s98, v85
	v_cmp_gt_u32_e64 s[36:37], s98, v86
	v_cmp_gt_u32_e64 s[78:79], s98, v87
	v_cmp_gt_u32_e64 s[50:51], s98, v88
	v_cndmask_b32_e64 v32, 0, v32, s[30:31]
	v_add_u32_e32 v85, 8, v84
	v_cmp_gt_u32_e64 s[30:31], s98, v85
	v_cndmask_b32_e64 v33, 0, v33, s[36:37]
	v_add_u32_e32 v86, 9, v84
	v_cmp_gt_u32_e64 s[36:37], s98, v86
	v_cndmask_b32_e64 v34, 0, v34, s[78:79]
	v_add_u32_e32 v87, 10, v84
	v_cmp_gt_u32_e64 s[78:79], s98, v87
	v_cndmask_b32_e64 v35, 0, v35, s[50:51]
	v_add_u32_e32 v88, 11, v84
	v_cmp_gt_u32_e64 s[50:51], s98, v88
	v_cndmask_b32_e64 v36, 0, v36, s[30:31]
	v_add_u32_e32 v85, 16, v84
	v_cmp_gt_u32_e64 s[30:31], s98, v85
	v_cndmask_b32_e64 v37, 0, v37, s[36:37]
	v_add_u32_e32 v86, 17, v84
	v_cmp_gt_u32_e64 s[36:37], s98, v86
	v_cndmask_b32_e64 v38, 0, v38, s[78:79]
	v_add_u32_e32 v87, 18, v84
	v_cmp_gt_u32_e64 s[78:79], s98, v87
	v_cndmask_b32_e64 v39, 0, v39, s[50:51]
	v_add_u32_e32 v88, 19, v84
	v_cmp_gt_u32_e64 s[50:51], s98, v88
	v_cndmask_b32_e64 v40, 0, v40, s[30:31]
	v_add_u32_e32 v85, 24, v84
	v_cmp_gt_u32_e64 s[30:31], s98, v85
	v_cndmask_b32_e64 v41, 0, v41, s[36:37]
	v_add_u32_e32 v86, 25, v84
	v_cmp_gt_u32_e64 s[36:37], s98, v86
	v_cndmask_b32_e64 v42, 0, v42, s[78:79]
	v_add_u32_e32 v87, 26, v84
	v_cmp_gt_u32_e64 s[78:79], s98, v87
	v_cndmask_b32_e64 v43, 0, v43, s[50:51]
	v_add_u32_e32 v88, 27, v84
	v_cmp_gt_u32_e64 s[50:51], s98, v88
	v_nop
	v_cndmask_b32_e64 v44, 0, v44, s[30:31]
	v_cndmask_b32_e64 v45, 0, v45, s[36:37]
	v_cndmask_b32_e64 v46, 0, v46, s[78:79]
	v_cndmask_b32_e64 v47, 0, v47, s[50:51]
	v_cvt_pk_bf16_f32 v64, v32, v33
	v_cvt_pk_bf16_f32 v65, v34, v35
	v_cvt_pk_bf16_f32 v66, v36, v37
	v_cvt_pk_bf16_f32 v67, v38, v39
	v_cvt_pk_bf16_f32 v68, v40, v41
	v_cvt_pk_bf16_f32 v69, v42, v43
	v_cvt_pk_bf16_f32 v70, v44, v45
	v_cvt_pk_bf16_f32 v71, v46, v47
	v_pk_add_f32 v[232:233], v[232:233], v[32:33]
	v_pk_add_f32 v[232:233], v[232:233], v[34:35]
	v_pk_add_f32 v[232:233], v[232:233], v[36:37]
	v_pk_add_f32 v[232:233], v[232:233], v[38:39]
	v_pk_add_f32 v[232:233], v[232:233], v[40:41]
	v_pk_add_f32 v[232:233], v[232:233], v[42:43]
	v_pk_add_f32 v[232:233], v[232:233], v[44:45]
	v_pk_add_f32 v[232:233], v[232:233], v[46:47]
	ds_read2_b32 v[32:33], v115 offset0:34 offset1:35
	ds_read2_b32 v[34:35], v115 offset0:36 offset1:37
	ds_read2_b32 v[36:37], v115 offset0:42 offset1:43
	ds_read2_b32 v[38:39], v115 offset0:44 offset1:45
	ds_read2_b32 v[40:41], v115 offset0:51 offset1:52
	ds_read2_b32 v[42:43], v115 offset0:53 offset1:54
	ds_read2_b32 v[44:45], v115 offset0:59 offset1:60
	ds_read2_b32 v[46:47], v115 offset0:61 offset1:62
	s_waitcnt lgkmcnt(15)
	v_mfma_f32_32x32x16_bf16 v[0:15], v[64:67], v[72:75], v[0:15]
	v_mfma_f32_32x32x16_bf16 v[16:31], v[64:67], v[76:79], v[16:31]
	v_mfma_f32_32x32x16_bf16 v[0:15], v[68:71], v[220:223], v[0:15]
	v_mfma_f32_32x32x16_bf16 v[16:31], v[68:71], v[224:227], v[16:31]
	s_add_i32 s90, s67, 480
	v_add_u32_e32 v80, s90, v235
	v_add_u32_e32 v83, s90, v236
	v_add_u32_e32 v99, s90, v237
	v_add_u32_e32 v253, s90, v238
	v_add_u32_e32 v254, s90, v100
	v_add_u32_e32 v255, s90, v149
	v_med3_i32 v80, v80, 0, s99
	v_med3_i32 v83, v83, 0, s99
	v_med3_i32 v99, v99, 0, s99
	v_med3_i32 v253, v253, 0, s99
	v_med3_i32 v254, v254, 0, s99
	v_med3_i32 v255, v255, 0, s99
	v_mad_u32_u24 v80, v80, s100, v252
	v_mad_u32_u24 v83, v83, s100, v252
	v_mad_u32_u24 v99, v99, s100, v252
	v_mad_u32_u24 v253, v253, s100, v252
	v_mad_u32_u24 v254, v254, s100, v153
	v_mad_u32_u24 v255, v255, s100, v153
	global_load_dwordx4 v[188:191], v80, s[82:83]
	global_load_dwordx4 v[192:195], v83, s[82:83]
	global_load_dwordx4 v[196:199], v99, s[82:83]
	global_load_dwordx4 v[200:203], v253, s[82:83]
	global_load_dwordx4 v[204:207], v254, s[82:83] offset:768
	global_load_dwordx4 v[208:211], v255, s[82:83] offset:768
	global_load_dwordx4 v[212:215], v254, s[82:83] offset:832
	global_load_dwordx4 v[216:219], v255, s[82:83] offset:832
	s_waitcnt lgkmcnt(0)
	v_mfma_f32_32x32x16_bf16 v[32:47], v[116:119], v[48:51], v[32:47]
	ds_read_b64_tr_b16 v[72:73], v231
	ds_read_b64_tr_b16 v[74:75], v231 offset:512
	ds_read_b64_tr_b16 v[76:77], v231 offset:2048
	ds_read_b64_tr_b16 v[78:79], v231 offset:2560
	ds_read_b64_tr_b16 v[220:221], v231 offset:1024
	ds_read_b64_tr_b16 v[222:223], v231 offset:1536
	ds_read_b64_tr_b16 v[224:225], v231 offset:3072
	ds_read_b64_tr_b16 v[226:227], v231 offset:3584
	s_waitcnt vmcnt(8)
	ds_write_b128 v247, v[156:159]
	ds_write_b128 v247, v[160:163] offset:1024
	ds_write_b128 v247, v[164:167] offset:2048
	ds_write_b128 v247, v[168:171] offset:3072
	ds_read_b128 v[156:159], v248
	ds_read_b128 v[160:163], v249
	ds_read_b128 v[164:167], v250
	ds_read_b128 v[168:171], v251
	ds_write_b128 v112, v[172:175]
	ds_write_b128 v112, v[176:179] offset:1024
	ds_write_b128 v112, v[180:183] offset:2048
	ds_write_b128 v112, v[184:187] offset:3072
	v_mfma_f32_32x32x16_bf16 v[32:47], v[120:123], v[52:55], v[32:47]
	v_mfma_f32_32x32x16_bf16 v[32:47], v[124:127], v[56:59], v[32:47]
	v_mfma_f32_32x32x16_bf16 v[32:47], v[128:131], v[60:63], v[32:47]
	s_nop 11
	v_exp_f32_e32 v32, v32
	v_exp_f32_e32 v33, v33
	v_exp_f32_e32 v34, v34
	v_exp_f32_e32 v35, v35
	v_exp_f32_e32 v36, v36
	v_exp_f32_e32 v37, v37
	v_exp_f32_e32 v38, v38
	v_exp_f32_e32 v39, v39
	v_exp_f32_e32 v40, v40
	v_exp_f32_e32 v41, v41
	v_exp_f32_e32 v42, v42
	v_exp_f32_e32 v43, v43
	v_exp_f32_e32 v44, v44
	v_exp_f32_e32 v45, v45
	v_exp_f32_e32 v46, v46
	v_exp_f32_e32 v47, v47
	s_add_i32 s90, s67, 416
	v_add_u32_e32 v84, s90, v107
	v_add_u32_e32 v85, 0, v84
	v_add_u32_e32 v86, 1, v84
	v_add_u32_e32 v87, 2, v84
	v_add_u32_e32 v88, 3, v84
	v_cmp_gt_u32_e64 s[30:31], s98, v85
	v_cmp_gt_u32_e64 s[36:37], s98, v86
	v_cmp_gt_u32_e64 s[78:79], s98, v87
	v_cmp_gt_u32_e64 s[50:51], s98, v88
	v_cndmask_b32_e64 v32, 0, v32, s[30:31]
	v_add_u32_e32 v85, 8, v84
	v_cmp_gt_u32_e64 s[30:31], s98, v85
	v_cndmask_b32_e64 v33, 0, v33, s[36:37]
	v_add_u32_e32 v86, 9, v84
	v_cmp_gt_u32_e64 s[36:37], s98, v86
	v_cndmask_b32_e64 v34, 0, v34, s[78:79]
	v_add_u32_e32 v87, 10, v84
	v_cmp_gt_u32_e64 s[78:79], s98, v87
	v_cndmask_b32_e64 v35, 0, v35, s[50:51]
	v_add_u32_e32 v88, 11, v84
	v_cmp_gt_u32_e64 s[50:51], s98, v88
	v_cndmask_b32_e64 v36, 0, v36, s[30:31]
	v_add_u32_e32 v85, 16, v84
	v_cmp_gt_u32_e64 s[30:31], s98, v85
	v_cndmask_b32_e64 v37, 0, v37, s[36:37]
	v_add_u32_e32 v86, 17, v84
	v_cmp_gt_u32_e64 s[36:37], s98, v86
	v_cndmask_b32_e64 v38, 0, v38, s[78:79]
	v_add_u32_e32 v87, 18, v84
	v_cmp_gt_u32_e64 s[78:79], s98, v87
	v_cndmask_b32_e64 v39, 0, v39, s[50:51]
	v_add_u32_e32 v88, 19, v84
	v_cmp_gt_u32_e64 s[50:51], s98, v88
	v_cndmask_b32_e64 v40, 0, v40, s[30:31]
	v_add_u32_e32 v85, 24, v84
	v_cmp_gt_u32_e64 s[30:31], s98, v85
	v_cndmask_b32_e64 v41, 0, v41, s[36:37]
	v_add_u32_e32 v86, 25, v84
	v_cmp_gt_u32_e64 s[36:37], s98, v86
	v_cndmask_b32_e64 v42, 0, v42, s[78:79]
	v_add_u32_e32 v87, 26, v84
	v_cmp_gt_u32_e64 s[78:79], s98, v87
	v_cndmask_b32_e64 v43, 0, v43, s[50:51]
	v_add_u32_e32 v88, 27, v84
	v_cmp_gt_u32_e64 s[50:51], s98, v88
	v_nop
	v_cndmask_b32_e64 v44, 0, v44, s[30:31]
	v_cndmask_b32_e64 v45, 0, v45, s[36:37]
	v_cndmask_b32_e64 v46, 0, v46, s[78:79]
	v_cndmask_b32_e64 v47, 0, v47, s[50:51]
	v_cvt_pk_bf16_f32 v64, v32, v33
	v_cvt_pk_bf16_f32 v65, v34, v35
	v_cvt_pk_bf16_f32 v66, v36, v37
	v_cvt_pk_bf16_f32 v67, v38, v39
	v_cvt_pk_bf16_f32 v68, v40, v41
	v_cvt_pk_bf16_f32 v69, v42, v43
	v_cvt_pk_bf16_f32 v70, v44, v45
	v_cvt_pk_bf16_f32 v71, v46, v47
	v_pk_add_f32 v[232:233], v[232:233], v[32:33]
	v_pk_add_f32 v[232:233], v[232:233], v[34:35]
	v_pk_add_f32 v[232:233], v[232:233], v[36:37]
	v_pk_add_f32 v[232:233], v[232:233], v[38:39]
	v_pk_add_f32 v[232:233], v[232:233], v[40:41]
	v_pk_add_f32 v[232:233], v[232:233], v[42:43]
	v_pk_add_f32 v[232:233], v[232:233], v[44:45]
	v_pk_add_f32 v[232:233], v[232:233], v[46:47]
	ds_read2_b32 v[32:33], v115 offset0:68 offset1:69
	ds_read2_b32 v[34:35], v115 offset0:70 offset1:71
	ds_read2_b32 v[36:37], v115 offset0:76 offset1:77
	ds_read2_b32 v[38:39], v115 offset0:78 offset1:79
	ds_read2_b32 v[40:41], v115 offset0:85 offset1:86
	ds_read2_b32 v[42:43], v115 offset0:87 offset1:88
	ds_read2_b32 v[44:45], v115 offset0:93 offset1:94
	ds_read2_b32 v[46:47], v115 offset0:95 offset1:96
	s_waitcnt lgkmcnt(15)
	v_mfma_f32_32x32x16_bf16 v[0:15], v[64:67], v[72:75], v[0:15]
	v_mfma_f32_32x32x16_bf16 v[16:31], v[64:67], v[76:79], v[16:31]
	v_mfma_f32_32x32x16_bf16 v[0:15], v[68:71], v[220:223], v[0:15]
	v_mfma_f32_32x32x16_bf16 v[16:31], v[68:71], v[224:227], v[16:31]
	s_add_i32 s90, s67, 512
	v_add_u32_e32 v80, s90, v235
	v_add_u32_e32 v83, s90, v236
	v_add_u32_e32 v99, s90, v237
	v_add_u32_e32 v253, s90, v238
	v_add_u32_e32 v254, s90, v100
	v_add_u32_e32 v255, s90, v149
	v_med3_i32 v80, v80, 0, s99
	v_med3_i32 v83, v83, 0, s99
	v_med3_i32 v99, v99, 0, s99
	v_med3_i32 v253, v253, 0, s99
	v_med3_i32 v254, v254, 0, s99
	v_med3_i32 v255, v255, 0, s99
	v_mad_u32_u24 v80, v80, s100, v252
	v_mad_u32_u24 v83, v83, s100, v252
	v_mad_u32_u24 v99, v99, s100, v252
	v_mad_u32_u24 v253, v253, s100, v252
	v_mad_u32_u24 v254, v254, s100, v153
	v_mad_u32_u24 v255, v255, s100, v153
	global_load_dwordx4 v[116:119], v80, s[82:83]
	global_load_dwordx4 v[120:123], v83, s[82:83]
	global_load_dwordx4 v[124:127], v99, s[82:83]
	global_load_dwordx4 v[128:131], v253, s[82:83]
	global_load_dwordx4 v[132:135], v254, s[82:83] offset:768
	global_load_dwordx4 v[136:139], v255, s[82:83] offset:768
	global_load_dwordx4 v[140:143], v254, s[82:83] offset:832
	global_load_dwordx4 v[144:147], v255, s[82:83] offset:832
	s_waitcnt lgkmcnt(0)
	v_mfma_f32_32x32x16_bf16 v[32:47], v[156:159], v[48:51], v[32:47]
	ds_read_b64_tr_b16 v[72:73], v231
	ds_read_b64_tr_b16 v[74:75], v231 offset:512
	ds_read_b64_tr_b16 v[76:77], v231 offset:2048
	ds_read_b64_tr_b16 v[78:79], v231 offset:2560
	ds_read_b64_tr_b16 v[220:221], v231 offset:1024
	ds_read_b64_tr_b16 v[222:223], v231 offset:1536
	ds_read_b64_tr_b16 v[224:225], v231 offset:3072
	ds_read_b64_tr_b16 v[226:227], v231 offset:3584
	s_waitcnt vmcnt(8)
	ds_write_b128 v247, v[188:191]
	ds_write_b128 v247, v[192:195] offset:1024
	ds_write_b128 v247, v[196:199] offset:2048
	ds_write_b128 v247, v[200:203] offset:3072
	ds_read_b128 v[188:191], v248
	ds_read_b128 v[192:195], v249
	ds_read_b128 v[196:199], v250
	ds_read_b128 v[200:203], v251
	ds_write_b128 v112, v[204:207]
	ds_write_b128 v112, v[208:211] offset:1024
	ds_write_b128 v112, v[212:215] offset:2048
	ds_write_b128 v112, v[216:219] offset:3072
	v_mfma_f32_32x32x16_bf16 v[32:47], v[160:163], v[52:55], v[32:47]
	v_mfma_f32_32x32x16_bf16 v[32:47], v[164:167], v[56:59], v[32:47]
	v_mfma_f32_32x32x16_bf16 v[32:47], v[168:171], v[60:63], v[32:47]
	s_nop 11
	v_exp_f32_e32 v32, v32
	v_exp_f32_e32 v33, v33
	v_exp_f32_e32 v34, v34
	v_exp_f32_e32 v35, v35
	v_exp_f32_e32 v36, v36
	v_exp_f32_e32 v37, v37
	v_exp_f32_e32 v38, v38
	v_exp_f32_e32 v39, v39
	v_exp_f32_e32 v40, v40
	v_exp_f32_e32 v41, v41
	v_exp_f32_e32 v42, v42
	v_exp_f32_e32 v43, v43
	v_exp_f32_e32 v44, v44
	v_exp_f32_e32 v45, v45
	v_exp_f32_e32 v46, v46
	v_exp_f32_e32 v47, v47
	s_add_i32 s90, s67, 448
	v_add_u32_e32 v84, s90, v107
	v_add_u32_e32 v85, 0, v84
	v_add_u32_e32 v86, 1, v84
	v_add_u32_e32 v87, 2, v84
	v_add_u32_e32 v88, 3, v84
	v_cmp_gt_u32_e64 s[30:31], s98, v85
	v_cmp_gt_u32_e64 s[36:37], s98, v86
	v_cmp_gt_u32_e64 s[78:79], s98, v87
	v_cmp_gt_u32_e64 s[50:51], s98, v88
	v_cndmask_b32_e64 v32, 0, v32, s[30:31]
	v_add_u32_e32 v85, 8, v84
	v_cmp_gt_u32_e64 s[30:31], s98, v85
	v_cndmask_b32_e64 v33, 0, v33, s[36:37]
	v_add_u32_e32 v86, 9, v84
	v_cmp_gt_u32_e64 s[36:37], s98, v86
	v_cndmask_b32_e64 v34, 0, v34, s[78:79]
	v_add_u32_e32 v87, 10, v84
	v_cmp_gt_u32_e64 s[78:79], s98, v87
	v_cndmask_b32_e64 v35, 0, v35, s[50:51]
	v_add_u32_e32 v88, 11, v84
	v_cmp_gt_u32_e64 s[50:51], s98, v88
	v_cndmask_b32_e64 v36, 0, v36, s[30:31]
	v_add_u32_e32 v85, 16, v84
	v_cmp_gt_u32_e64 s[30:31], s98, v85
	v_cndmask_b32_e64 v37, 0, v37, s[36:37]
	v_add_u32_e32 v86, 17, v84
	v_cmp_gt_u32_e64 s[36:37], s98, v86
	v_cndmask_b32_e64 v38, 0, v38, s[78:79]
	v_add_u32_e32 v87, 18, v84
	v_cmp_gt_u32_e64 s[78:79], s98, v87
	v_cndmask_b32_e64 v39, 0, v39, s[50:51]
	v_add_u32_e32 v88, 19, v84
	v_cmp_gt_u32_e64 s[50:51], s98, v88
	v_cndmask_b32_e64 v40, 0, v40, s[30:31]
	v_add_u32_e32 v85, 24, v84
	v_cmp_gt_u32_e64 s[30:31], s98, v85
	v_cndmask_b32_e64 v41, 0, v41, s[36:37]
	v_add_u32_e32 v86, 25, v84
	v_cmp_gt_u32_e64 s[36:37], s98, v86
	v_cndmask_b32_e64 v42, 0, v42, s[78:79]
	v_add_u32_e32 v87, 26, v84
	v_cmp_gt_u32_e64 s[78:79], s98, v87
	v_cndmask_b32_e64 v43, 0, v43, s[50:51]
	v_add_u32_e32 v88, 27, v84
	v_cmp_gt_u32_e64 s[50:51], s98, v88
	v_nop
	v_cndmask_b32_e64 v44, 0, v44, s[30:31]
	v_cndmask_b32_e64 v45, 0, v45, s[36:37]
	v_cndmask_b32_e64 v46, 0, v46, s[78:79]
	v_cndmask_b32_e64 v47, 0, v47, s[50:51]
	v_cvt_pk_bf16_f32 v64, v32, v33
	v_cvt_pk_bf16_f32 v65, v34, v35
	v_cvt_pk_bf16_f32 v66, v36, v37
	v_cvt_pk_bf16_f32 v67, v38, v39
	v_cvt_pk_bf16_f32 v68, v40, v41
	v_cvt_pk_bf16_f32 v69, v42, v43
	v_cvt_pk_bf16_f32 v70, v44, v45
	v_cvt_pk_bf16_f32 v71, v46, v47
	v_pk_add_f32 v[232:233], v[232:233], v[32:33]
	v_pk_add_f32 v[232:233], v[232:233], v[34:35]
	v_pk_add_f32 v[232:233], v[232:233], v[36:37]
	v_pk_add_f32 v[232:233], v[232:233], v[38:39]
	v_pk_add_f32 v[232:233], v[232:233], v[40:41]
	v_pk_add_f32 v[232:233], v[232:233], v[42:43]
	v_pk_add_f32 v[232:233], v[232:233], v[44:45]
	v_pk_add_f32 v[232:233], v[232:233], v[46:47]
	ds_read2_b32 v[32:33], v115 offset0:102 offset1:103
	ds_read2_b32 v[34:35], v115 offset0:104 offset1:105
	ds_read2_b32 v[36:37], v115 offset0:110 offset1:111
	ds_read2_b32 v[38:39], v115 offset0:112 offset1:113
	ds_read2_b32 v[40:41], v115 offset0:119 offset1:120
	ds_read2_b32 v[42:43], v115 offset0:121 offset1:122
	ds_read2_b32 v[44:45], v115 offset0:127 offset1:128
	ds_read2_b32 v[46:47], v115 offset0:129 offset1:130
	s_waitcnt lgkmcnt(15)
	v_mfma_f32_32x32x16_bf16 v[0:15], v[64:67], v[72:75], v[0:15]
	v_mfma_f32_32x32x16_bf16 v[16:31], v[64:67], v[76:79], v[16:31]
	v_mfma_f32_32x32x16_bf16 v[0:15], v[68:71], v[220:223], v[0:15]
	v_mfma_f32_32x32x16_bf16 v[16:31], v[68:71], v[224:227], v[16:31]
	s_add_i32 s90, s67, 544
	v_add_u32_e32 v80, s90, v235
	v_add_u32_e32 v83, s90, v236
	v_add_u32_e32 v99, s90, v237
	v_add_u32_e32 v253, s90, v238
	v_add_u32_e32 v254, s90, v100
	v_add_u32_e32 v255, s90, v149
	v_med3_i32 v80, v80, 0, s99
	v_med3_i32 v83, v83, 0, s99
	v_med3_i32 v99, v99, 0, s99
	v_med3_i32 v253, v253, 0, s99
	v_med3_i32 v254, v254, 0, s99
	v_med3_i32 v255, v255, 0, s99
	v_mad_u32_u24 v80, v80, s100, v252
	v_mad_u32_u24 v83, v83, s100, v252
	v_mad_u32_u24 v99, v99, s100, v252
	v_mad_u32_u24 v253, v253, s100, v252
	v_mad_u32_u24 v254, v254, s100, v153
	v_mad_u32_u24 v255, v255, s100, v153
	global_load_dwordx4 v[156:159], v80, s[82:83]
	global_load_dwordx4 v[160:163], v83, s[82:83]
	global_load_dwordx4 v[164:167], v99, s[82:83]
	global_load_dwordx4 v[168:171], v253, s[82:83]
	global_load_dwordx4 v[172:175], v254, s[82:83] offset:768
	global_load_dwordx4 v[176:179], v255, s[82:83] offset:768
	global_load_dwordx4 v[180:183], v254, s[82:83] offset:832
	global_load_dwordx4 v[184:187], v255, s[82:83] offset:832
	s_waitcnt lgkmcnt(0)
	v_mfma_f32_32x32x16_bf16 v[32:47], v[188:191], v[48:51], v[32:47]
	ds_read_b64_tr_b16 v[72:73], v231
	ds_read_b64_tr_b16 v[74:75], v231 offset:512
	ds_read_b64_tr_b16 v[76:77], v231 offset:2048
	ds_read_b64_tr_b16 v[78:79], v231 offset:2560
	ds_read_b64_tr_b16 v[220:221], v231 offset:1024
	ds_read_b64_tr_b16 v[222:223], v231 offset:1536
	ds_read_b64_tr_b16 v[224:225], v231 offset:3072
	ds_read_b64_tr_b16 v[226:227], v231 offset:3584
	s_waitcnt vmcnt(8)
	ds_write_b128 v247, v[116:119]
	ds_write_b128 v247, v[120:123] offset:1024
	ds_write_b128 v247, v[124:127] offset:2048
	ds_write_b128 v247, v[128:131] offset:3072
	ds_read_b128 v[116:119], v248
	ds_read_b128 v[120:123], v249
	ds_read_b128 v[124:127], v250
	ds_read_b128 v[128:131], v251
	ds_write_b128 v112, v[132:135]
	ds_write_b128 v112, v[136:139] offset:1024
	ds_write_b128 v112, v[140:143] offset:2048
	ds_write_b128 v112, v[144:147] offset:3072
	v_mfma_f32_32x32x16_bf16 v[32:47], v[192:195], v[52:55], v[32:47]
	v_mfma_f32_32x32x16_bf16 v[32:47], v[196:199], v[56:59], v[32:47]
	v_mfma_f32_32x32x16_bf16 v[32:47], v[200:203], v[60:63], v[32:47]
	s_nop 11
	v_exp_f32_e32 v32, v32
	v_exp_f32_e32 v33, v33
	v_exp_f32_e32 v34, v34
	v_exp_f32_e32 v35, v35
	v_exp_f32_e32 v36, v36
	v_exp_f32_e32 v37, v37
	v_exp_f32_e32 v38, v38
	v_exp_f32_e32 v39, v39
	v_exp_f32_e32 v40, v40
	v_exp_f32_e32 v41, v41
	v_exp_f32_e32 v42, v42
	v_exp_f32_e32 v43, v43
	v_exp_f32_e32 v44, v44
	v_exp_f32_e32 v45, v45
	v_exp_f32_e32 v46, v46
	v_exp_f32_e32 v47, v47
	s_add_i32 s90, s67, 480
	v_add_u32_e32 v84, s90, v107
	v_add_u32_e32 v85, 0, v84
	v_add_u32_e32 v86, 1, v84
	v_add_u32_e32 v87, 2, v84
	v_add_u32_e32 v88, 3, v84
	v_cmp_gt_u32_e64 s[30:31], s98, v85
	v_cmp_gt_u32_e64 s[36:37], s98, v86
	v_cmp_gt_u32_e64 s[78:79], s98, v87
	v_cmp_gt_u32_e64 s[50:51], s98, v88
	v_cndmask_b32_e64 v32, 0, v32, s[30:31]
	v_add_u32_e32 v85, 8, v84
	v_cmp_gt_u32_e64 s[30:31], s98, v85
	v_cndmask_b32_e64 v33, 0, v33, s[36:37]
	v_add_u32_e32 v86, 9, v84
	v_cmp_gt_u32_e64 s[36:37], s98, v86
	v_cndmask_b32_e64 v34, 0, v34, s[78:79]
	v_add_u32_e32 v87, 10, v84
	v_cmp_gt_u32_e64 s[78:79], s98, v87
	v_cndmask_b32_e64 v35, 0, v35, s[50:51]
	v_add_u32_e32 v88, 11, v84
	v_cmp_gt_u32_e64 s[50:51], s98, v88
	v_cndmask_b32_e64 v36, 0, v36, s[30:31]
	v_add_u32_e32 v85, 16, v84
	v_cmp_gt_u32_e64 s[30:31], s98, v85
	v_cndmask_b32_e64 v37, 0, v37, s[36:37]
	v_add_u32_e32 v86, 17, v84
	v_cmp_gt_u32_e64 s[36:37], s98, v86
	v_cndmask_b32_e64 v38, 0, v38, s[78:79]
	v_add_u32_e32 v87, 18, v84
	v_cmp_gt_u32_e64 s[78:79], s98, v87
	v_cndmask_b32_e64 v39, 0, v39, s[50:51]
	v_add_u32_e32 v88, 19, v84
	v_cmp_gt_u32_e64 s[50:51], s98, v88
	v_cndmask_b32_e64 v40, 0, v40, s[30:31]
	v_add_u32_e32 v85, 24, v84
	v_cmp_gt_u32_e64 s[30:31], s98, v85
	v_cndmask_b32_e64 v41, 0, v41, s[36:37]
	v_add_u32_e32 v86, 25, v84
	v_cmp_gt_u32_e64 s[36:37], s98, v86
	v_cndmask_b32_e64 v42, 0, v42, s[78:79]
	v_add_u32_e32 v87, 26, v84
	v_cmp_gt_u32_e64 s[78:79], s98, v87
	v_cndmask_b32_e64 v43, 0, v43, s[50:51]
	v_add_u32_e32 v88, 27, v84
	v_cmp_gt_u32_e64 s[50:51], s98, v88
	v_nop
	v_cndmask_b32_e64 v44, 0, v44, s[30:31]
	v_cndmask_b32_e64 v45, 0, v45, s[36:37]
	v_cndmask_b32_e64 v46, 0, v46, s[78:79]
	v_cndmask_b32_e64 v47, 0, v47, s[50:51]
	v_cvt_pk_bf16_f32 v64, v32, v33
	v_cvt_pk_bf16_f32 v65, v34, v35
	v_cvt_pk_bf16_f32 v66, v36, v37
	v_cvt_pk_bf16_f32 v67, v38, v39
	v_cvt_pk_bf16_f32 v68, v40, v41
	v_cvt_pk_bf16_f32 v69, v42, v43
	v_cvt_pk_bf16_f32 v70, v44, v45
	v_cvt_pk_bf16_f32 v71, v46, v47
	v_pk_add_f32 v[232:233], v[232:233], v[32:33]
	v_pk_add_f32 v[232:233], v[232:233], v[34:35]
	v_pk_add_f32 v[232:233], v[232:233], v[36:37]
	v_pk_add_f32 v[232:233], v[232:233], v[38:39]
	v_pk_add_f32 v[232:233], v[232:233], v[40:41]
	v_pk_add_f32 v[232:233], v[232:233], v[42:43]
	v_pk_add_f32 v[232:233], v[232:233], v[44:45]
	v_pk_add_f32 v[232:233], v[232:233], v[46:47]
	ds_read2_b32 v[32:33], v115 offset0:136 offset1:137
	ds_read2_b32 v[34:35], v115 offset0:138 offset1:139
	ds_read2_b32 v[36:37], v115 offset0:144 offset1:145
	ds_read2_b32 v[38:39], v115 offset0:146 offset1:147
	ds_read2_b32 v[40:41], v115 offset0:153 offset1:154
	ds_read2_b32 v[42:43], v115 offset0:155 offset1:156
	ds_read2_b32 v[44:45], v115 offset0:161 offset1:162
	ds_read2_b32 v[46:47], v115 offset0:163 offset1:164
	s_waitcnt lgkmcnt(15)
	v_mfma_f32_32x32x16_bf16 v[0:15], v[64:67], v[72:75], v[0:15]
	v_mfma_f32_32x32x16_bf16 v[16:31], v[64:67], v[76:79], v[16:31]
	v_mfma_f32_32x32x16_bf16 v[0:15], v[68:71], v[220:223], v[0:15]
	v_mfma_f32_32x32x16_bf16 v[16:31], v[68:71], v[224:227], v[16:31]
	s_add_i32 s90, s67, -256
	v_add_u32_e32 v80, s90, v239
	v_add_u32_e32 v83, s90, v240
	v_add_u32_e32 v99, s90, v241
	v_add_u32_e32 v253, s90, v242
	v_add_u32_e32 v254, s90, v101
	v_add_u32_e32 v255, s90, v150
	v_med3_i32 v80, v80, 0, s99
	v_med3_i32 v83, v83, 0, s99
	v_med3_i32 v99, v99, 0, s99
	v_med3_i32 v253, v253, 0, s99
	v_med3_i32 v254, v254, 0, s99
	v_med3_i32 v255, v255, 0, s99
	v_mad_u32_u24 v80, v80, s100, v252
	v_mad_u32_u24 v83, v83, s100, v252
	v_mad_u32_u24 v99, v99, s100, v252
	v_mad_u32_u24 v253, v253, s100, v252
	v_mad_u32_u24 v254, v254, s100, v153
	v_mad_u32_u24 v255, v255, s100, v153
	global_load_dwordx4 v[188:191], v80, s[82:83]
	global_load_dwordx4 v[192:195], v83, s[82:83]
	global_load_dwordx4 v[196:199], v99, s[82:83]
	global_load_dwordx4 v[200:203], v253, s[82:83]
	global_load_dwordx4 v[204:207], v254, s[82:83] offset:768
	global_load_dwordx4 v[208:211], v255, s[82:83] offset:768
	global_load_dwordx4 v[212:215], v254, s[82:83] offset:832
	global_load_dwordx4 v[216:219], v255, s[82:83] offset:832
	s_waitcnt lgkmcnt(0)
	v_mfma_f32_32x32x16_bf16 v[32:47], v[116:119], v[48:51], v[32:47]
	ds_read_b64_tr_b16 v[72:73], v231
	ds_read_b64_tr_b16 v[74:75], v231 offset:512
	ds_read_b64_tr_b16 v[76:77], v231 offset:2048
	ds_read_b64_tr_b16 v[78:79], v231 offset:2560
	ds_read_b64_tr_b16 v[220:221], v231 offset:1024
	ds_read_b64_tr_b16 v[222:223], v231 offset:1536
	ds_read_b64_tr_b16 v[224:225], v231 offset:3072
	ds_read_b64_tr_b16 v[226:227], v231 offset:3584
	s_waitcnt vmcnt(8)
	ds_write_b128 v247, v[156:159]
	ds_write_b128 v247, v[160:163] offset:1024
	ds_write_b128 v247, v[164:167] offset:2048
	ds_write_b128 v247, v[168:171] offset:3072
	ds_read_b128 v[156:159], v248
	ds_read_b128 v[160:163], v249
	ds_read_b128 v[164:167], v250
	ds_read_b128 v[168:171], v251
	ds_write_b128 v112, v[172:175]
	ds_write_b128 v112, v[176:179] offset:1024
	ds_write_b128 v112, v[180:183] offset:2048
	ds_write_b128 v112, v[184:187] offset:3072
	v_mfma_f32_32x32x16_bf16 v[32:47], v[120:123], v[52:55], v[32:47]
	v_mfma_f32_32x32x16_bf16 v[32:47], v[124:127], v[56:59], v[32:47]
	v_mfma_f32_32x32x16_bf16 v[32:47], v[128:131], v[60:63], v[32:47]
	s_nop 11
	v_exp_f32_e32 v32, v32
	v_exp_f32_e32 v33, v33
	v_exp_f32_e32 v34, v34
	v_exp_f32_e32 v35, v35
	v_exp_f32_e32 v36, v36
	v_exp_f32_e32 v37, v37
	v_exp_f32_e32 v38, v38
	v_exp_f32_e32 v39, v39
	v_exp_f32_e32 v40, v40
	v_exp_f32_e32 v41, v41
	v_exp_f32_e32 v42, v42
	v_exp_f32_e32 v43, v43
	v_exp_f32_e32 v44, v44
	v_exp_f32_e32 v45, v45
	v_exp_f32_e32 v46, v46
	v_exp_f32_e32 v47, v47
	s_add_i32 s90, s67, 512
	v_add_u32_e32 v84, s90, v107
	v_add_u32_e32 v85, 0, v84
	v_add_u32_e32 v86, 1, v84
	v_add_u32_e32 v87, 2, v84
	v_add_u32_e32 v88, 3, v84
	v_cmp_gt_u32_e64 s[30:31], s98, v85
	v_cmp_gt_u32_e64 s[36:37], s98, v86
	v_cmp_gt_u32_e64 s[78:79], s98, v87
	v_cmp_gt_u32_e64 s[50:51], s98, v88
	v_cndmask_b32_e64 v32, 0, v32, s[30:31]
	v_add_u32_e32 v85, 8, v84
	v_cmp_gt_u32_e64 s[30:31], s98, v85
	v_cndmask_b32_e64 v33, 0, v33, s[36:37]
	v_add_u32_e32 v86, 9, v84
	v_cmp_gt_u32_e64 s[36:37], s98, v86
	v_cndmask_b32_e64 v34, 0, v34, s[78:79]
	v_add_u32_e32 v87, 10, v84
	v_cmp_gt_u32_e64 s[78:79], s98, v87
	v_cndmask_b32_e64 v35, 0, v35, s[50:51]
	v_add_u32_e32 v88, 11, v84
	v_cmp_gt_u32_e64 s[50:51], s98, v88
	v_cndmask_b32_e64 v36, 0, v36, s[30:31]
	v_add_u32_e32 v85, 16, v84
	v_cmp_gt_u32_e64 s[30:31], s98, v85
	v_cndmask_b32_e64 v37, 0, v37, s[36:37]
	v_add_u32_e32 v86, 17, v84
	v_cmp_gt_u32_e64 s[36:37], s98, v86
	v_cndmask_b32_e64 v38, 0, v38, s[78:79]
	v_add_u32_e32 v87, 18, v84
	v_cmp_gt_u32_e64 s[78:79], s98, v87
	v_cndmask_b32_e64 v39, 0, v39, s[50:51]
	v_add_u32_e32 v88, 19, v84
	v_cmp_gt_u32_e64 s[50:51], s98, v88
	v_cndmask_b32_e64 v40, 0, v40, s[30:31]
	v_add_u32_e32 v85, 24, v84
	v_cmp_gt_u32_e64 s[30:31], s98, v85
	v_cndmask_b32_e64 v41, 0, v41, s[36:37]
	v_add_u32_e32 v86, 25, v84
	v_cmp_gt_u32_e64 s[36:37], s98, v86
	v_cndmask_b32_e64 v42, 0, v42, s[78:79]
	v_add_u32_e32 v87, 26, v84
	v_cmp_gt_u32_e64 s[78:79], s98, v87
	v_cndmask_b32_e64 v43, 0, v43, s[50:51]
	v_add_u32_e32 v88, 27, v84
	v_cmp_gt_u32_e64 s[50:51], s98, v88
	v_nop
	v_cndmask_b32_e64 v44, 0, v44, s[30:31]
	v_cndmask_b32_e64 v45, 0, v45, s[36:37]
	v_cndmask_b32_e64 v46, 0, v46, s[78:79]
	v_cndmask_b32_e64 v47, 0, v47, s[50:51]
	v_cvt_pk_bf16_f32 v64, v32, v33
	v_cvt_pk_bf16_f32 v65, v34, v35
	v_cvt_pk_bf16_f32 v66, v36, v37
	v_cvt_pk_bf16_f32 v67, v38, v39
	v_cvt_pk_bf16_f32 v68, v40, v41
	v_cvt_pk_bf16_f32 v69, v42, v43
	v_cvt_pk_bf16_f32 v70, v44, v45
	v_cvt_pk_bf16_f32 v71, v46, v47
	v_pk_add_f32 v[232:233], v[232:233], v[32:33]
	v_pk_add_f32 v[232:233], v[232:233], v[34:35]
	v_pk_add_f32 v[232:233], v[232:233], v[36:37]
	v_pk_add_f32 v[232:233], v[232:233], v[38:39]
	v_pk_add_f32 v[232:233], v[232:233], v[40:41]
	v_pk_add_f32 v[232:233], v[232:233], v[42:43]
	v_pk_add_f32 v[232:233], v[232:233], v[44:45]
	v_pk_add_f32 v[232:233], v[232:233], v[46:47]
	ds_read2_b32 v[32:33], v115 offset0:170 offset1:171
	ds_read2_b32 v[34:35], v115 offset0:172 offset1:173
	ds_read2_b32 v[36:37], v115 offset0:178 offset1:179
	ds_read2_b32 v[38:39], v115 offset0:180 offset1:181
	ds_read2_b32 v[40:41], v115 offset0:187 offset1:188
	ds_read2_b32 v[42:43], v115 offset0:189 offset1:190
	ds_read2_b32 v[44:45], v115 offset0:195 offset1:196
	ds_read2_b32 v[46:47], v115 offset0:197 offset1:198
	s_waitcnt lgkmcnt(15)
	v_mfma_f32_32x32x16_bf16 v[0:15], v[64:67], v[72:75], v[0:15]
	v_mfma_f32_32x32x16_bf16 v[16:31], v[64:67], v[76:79], v[16:31]
	v_mfma_f32_32x32x16_bf16 v[0:15], v[68:71], v[220:223], v[0:15]
	v_mfma_f32_32x32x16_bf16 v[16:31], v[68:71], v[224:227], v[16:31]
	s_add_i32 s90, s67, -128
	v_add_u32_e32 v80, s90, v239
	v_add_u32_e32 v83, s90, v240
	v_add_u32_e32 v99, s90, v241
	v_add_u32_e32 v253, s90, v242
	v_add_u32_e32 v254, s90, v101
	v_add_u32_e32 v255, s90, v150
	v_med3_i32 v80, v80, 0, s99
	v_med3_i32 v83, v83, 0, s99
	v_med3_i32 v99, v99, 0, s99
	v_med3_i32 v253, v253, 0, s99
	v_med3_i32 v254, v254, 0, s99
	v_med3_i32 v255, v255, 0, s99
	v_mad_u32_u24 v80, v80, s100, v252
	v_mad_u32_u24 v83, v83, s100, v252
	v_mad_u32_u24 v99, v99, s100, v252
	v_mad_u32_u24 v253, v253, s100, v252
	v_mad_u32_u24 v254, v254, s100, v153
	v_mad_u32_u24 v255, v255, s100, v153
	global_load_dwordx4 v[116:119], v80, s[82:83]
	global_load_dwordx4 v[120:123], v83, s[82:83]
	global_load_dwordx4 v[124:127], v99, s[82:83]
	global_load_dwordx4 v[128:131], v253, s[82:83]
	global_load_dwordx4 v[132:135], v254, s[82:83] offset:768
	global_load_dwordx4 v[136:139], v255, s[82:83] offset:768
	global_load_dwordx4 v[140:143], v254, s[82:83] offset:832
	global_load_dwordx4 v[144:147], v255, s[82:83] offset:832
	s_waitcnt lgkmcnt(0)
	v_mfma_f32_32x32x16_bf16 v[32:47], v[156:159], v[48:51], v[32:47]
	ds_read_b64_tr_b16 v[72:73], v231
	ds_read_b64_tr_b16 v[74:75], v231 offset:512
	ds_read_b64_tr_b16 v[76:77], v231 offset:2048
	ds_read_b64_tr_b16 v[78:79], v231 offset:2560
	ds_read_b64_tr_b16 v[220:221], v231 offset:1024
	ds_read_b64_tr_b16 v[222:223], v231 offset:1536
	ds_read_b64_tr_b16 v[224:225], v231 offset:3072
	ds_read_b64_tr_b16 v[226:227], v231 offset:3584
	s_waitcnt vmcnt(8)
	ds_write_b128 v247, v[188:191]
	ds_write_b128 v247, v[192:195] offset:1024
	ds_write_b128 v247, v[196:199] offset:2048
	ds_write_b128 v247, v[200:203] offset:3072
	ds_read_b128 v[188:191], v248
	ds_read_b128 v[192:195], v249
	ds_read_b128 v[196:199], v250
	ds_read_b128 v[200:203], v251
	ds_write_b128 v112, v[204:207]
	ds_write_b128 v112, v[208:211] offset:1024
	ds_write_b128 v112, v[212:215] offset:2048
	ds_write_b128 v112, v[216:219] offset:3072
	v_mfma_f32_32x32x16_bf16 v[32:47], v[160:163], v[52:55], v[32:47]
	v_mfma_f32_32x32x16_bf16 v[32:47], v[164:167], v[56:59], v[32:47]
	v_mfma_f32_32x32x16_bf16 v[32:47], v[168:171], v[60:63], v[32:47]
	s_nop 11
	v_exp_f32_e32 v32, v32
	v_exp_f32_e32 v33, v33
	v_exp_f32_e32 v34, v34
	v_exp_f32_e32 v35, v35
	v_exp_f32_e32 v36, v36
	v_exp_f32_e32 v37, v37
	v_exp_f32_e32 v38, v38
	v_exp_f32_e32 v39, v39
	v_exp_f32_e32 v40, v40
	v_exp_f32_e32 v41, v41
	v_exp_f32_e32 v42, v42
	v_exp_f32_e32 v43, v43
	v_exp_f32_e32 v44, v44
	v_exp_f32_e32 v45, v45
	v_exp_f32_e32 v46, v46
	v_exp_f32_e32 v47, v47
	s_add_i32 s90, s67, 544
	v_add_u32_e32 v84, s90, v107
	v_add_u32_e32 v85, 0, v84
	v_add_u32_e32 v86, 1, v84
	v_add_u32_e32 v87, 2, v84
	v_add_u32_e32 v88, 3, v84
	v_cmp_gt_u32_e64 s[30:31], s98, v85
	v_cmp_gt_u32_e64 s[36:37], s98, v86
	v_cmp_gt_u32_e64 s[78:79], s98, v87
	v_cmp_gt_u32_e64 s[50:51], s98, v88
	v_cndmask_b32_e64 v32, 0, v32, s[30:31]
	v_add_u32_e32 v85, 8, v84
	v_cmp_gt_u32_e64 s[30:31], s98, v85
	v_cndmask_b32_e64 v33, 0, v33, s[36:37]
	v_add_u32_e32 v86, 9, v84
	v_cmp_gt_u32_e64 s[36:37], s98, v86
	v_cndmask_b32_e64 v34, 0, v34, s[78:79]
	v_add_u32_e32 v87, 10, v84
	v_cmp_gt_u32_e64 s[78:79], s98, v87
	v_cndmask_b32_e64 v35, 0, v35, s[50:51]
	v_add_u32_e32 v88, 11, v84
	v_cmp_gt_u32_e64 s[50:51], s98, v88
	v_cndmask_b32_e64 v36, 0, v36, s[30:31]
	v_add_u32_e32 v85, 16, v84
	v_cmp_gt_u32_e64 s[30:31], s98, v85
	v_cndmask_b32_e64 v37, 0, v37, s[36:37]
	v_add_u32_e32 v86, 17, v84
	v_cmp_gt_u32_e64 s[36:37], s98, v86
	v_cndmask_b32_e64 v38, 0, v38, s[78:79]
	v_add_u32_e32 v87, 18, v84
	v_cmp_gt_u32_e64 s[78:79], s98, v87
	v_cndmask_b32_e64 v39, 0, v39, s[50:51]
	v_add_u32_e32 v88, 19, v84
	v_cmp_gt_u32_e64 s[50:51], s98, v88
	v_cndmask_b32_e64 v40, 0, v40, s[30:31]
	v_add_u32_e32 v85, 24, v84
	v_cmp_gt_u32_e64 s[30:31], s98, v85
	v_cndmask_b32_e64 v41, 0, v41, s[36:37]
	v_add_u32_e32 v86, 25, v84
	v_cmp_gt_u32_e64 s[36:37], s98, v86
	v_cndmask_b32_e64 v42, 0, v42, s[78:79]
	v_add_u32_e32 v87, 26, v84
	v_cmp_gt_u32_e64 s[78:79], s98, v87
	v_cndmask_b32_e64 v43, 0, v43, s[50:51]
	v_add_u32_e32 v88, 27, v84
	v_cmp_gt_u32_e64 s[50:51], s98, v88
	v_nop
	v_cndmask_b32_e64 v44, 0, v44, s[30:31]
	v_cndmask_b32_e64 v45, 0, v45, s[36:37]
	v_cndmask_b32_e64 v46, 0, v46, s[78:79]
	v_cndmask_b32_e64 v47, 0, v47, s[50:51]
	v_cvt_pk_bf16_f32 v64, v32, v33
	v_cvt_pk_bf16_f32 v65, v34, v35
	v_cvt_pk_bf16_f32 v66, v36, v37
	v_cvt_pk_bf16_f32 v67, v38, v39
	v_cvt_pk_bf16_f32 v68, v40, v41
	v_cvt_pk_bf16_f32 v69, v42, v43
	v_cvt_pk_bf16_f32 v70, v44, v45
	v_cvt_pk_bf16_f32 v71, v46, v47
	v_pk_add_f32 v[232:233], v[232:233], v[32:33]
	v_pk_add_f32 v[232:233], v[232:233], v[34:35]
	v_pk_add_f32 v[232:233], v[232:233], v[36:37]
	v_pk_add_f32 v[232:233], v[232:233], v[38:39]
	v_pk_add_f32 v[232:233], v[232:233], v[40:41]
	v_pk_add_f32 v[232:233], v[232:233], v[42:43]
	v_pk_add_f32 v[232:233], v[232:233], v[44:45]
	v_pk_add_f32 v[232:233], v[232:233], v[46:47]
	v_mov_b32_e32 v115, v229
	ds_read2_b32 v[32:33], v115 offset0:0 offset1:1
	ds_read2_b32 v[34:35], v115 offset0:2 offset1:3
	ds_read2_b32 v[36:37], v115 offset0:8 offset1:9
	ds_read2_b32 v[38:39], v115 offset0:10 offset1:11
	ds_read2_b32 v[40:41], v115 offset0:16 offset1:17
	ds_read2_b32 v[42:43], v115 offset0:18 offset1:19
	ds_read2_b32 v[44:45], v115 offset0:24 offset1:25
	ds_read2_b32 v[46:47], v115 offset0:26 offset1:27
	s_waitcnt lgkmcnt(15)
	v_mfma_f32_32x32x16_bf16 v[0:15], v[64:67], v[72:75], v[0:15]
	v_mfma_f32_32x32x16_bf16 v[16:31], v[64:67], v[76:79], v[16:31]
	v_mfma_f32_32x32x16_bf16 v[0:15], v[68:71], v[220:223], v[0:15]
	v_mfma_f32_32x32x16_bf16 v[16:31], v[68:71], v[224:227], v[16:31]
	s_add_i32 s90, s67, 0
	v_add_u32_e32 v80, s90, v239
	v_add_u32_e32 v83, s90, v240
	v_add_u32_e32 v99, s90, v241
	v_add_u32_e32 v253, s90, v242
	v_add_u32_e32 v254, s90, v101
	v_add_u32_e32 v255, s90, v150
	v_med3_i32 v80, v80, 0, s99
	v_med3_i32 v83, v83, 0, s99
	v_med3_i32 v99, v99, 0, s99
	v_med3_i32 v253, v253, 0, s99
	v_med3_i32 v254, v254, 0, s99
	v_med3_i32 v255, v255, 0, s99
	v_mad_u32_u24 v80, v80, s100, v252
	v_mad_u32_u24 v83, v83, s100, v252
	v_mad_u32_u24 v99, v99, s100, v252
	v_mad_u32_u24 v253, v253, s100, v252
	v_mad_u32_u24 v254, v254, s100, v153
	v_mad_u32_u24 v255, v255, s100, v153
	global_load_dwordx4 v[156:159], v80, s[82:83]
	global_load_dwordx4 v[160:163], v83, s[82:83]
	global_load_dwordx4 v[164:167], v99, s[82:83]
	global_load_dwordx4 v[168:171], v253, s[82:83]
	global_load_dwordx4 v[172:175], v254, s[82:83] offset:768
	global_load_dwordx4 v[176:179], v255, s[82:83] offset:768
	global_load_dwordx4 v[180:183], v254, s[82:83] offset:832
	global_load_dwordx4 v[184:187], v255, s[82:83] offset:832
	s_waitcnt lgkmcnt(0)
	v_mfma_f32_32x32x16_bf16 v[32:47], v[188:191], v[48:51], v[32:47]
	ds_read_b64_tr_b16 v[72:73], v231
	ds_read_b64_tr_b16 v[74:75], v231 offset:512
	ds_read_b64_tr_b16 v[76:77], v231 offset:2048
	ds_read_b64_tr_b16 v[78:79], v231 offset:2560
	ds_read_b64_tr_b16 v[220:221], v231 offset:1024
	ds_read_b64_tr_b16 v[222:223], v231 offset:1536
	ds_read_b64_tr_b16 v[224:225], v231 offset:3072
	ds_read_b64_tr_b16 v[226:227], v231 offset:3584
	s_waitcnt vmcnt(8)
	ds_write_b128 v247, v[116:119]
	ds_write_b128 v247, v[120:123] offset:1024
	ds_write_b128 v247, v[124:127] offset:2048
	ds_write_b128 v247, v[128:131] offset:3072
	ds_read_b128 v[116:119], v248
	ds_read_b128 v[120:123], v249
	ds_read_b128 v[124:127], v250
	ds_read_b128 v[128:131], v251
	ds_write_b128 v112, v[132:135]
	ds_write_b128 v112, v[136:139] offset:1024
	ds_write_b128 v112, v[140:143] offset:2048
	ds_write_b128 v112, v[144:147] offset:3072
	v_mfma_f32_32x32x16_bf16 v[32:47], v[192:195], v[52:55], v[32:47]
	v_mfma_f32_32x32x16_bf16 v[32:47], v[196:199], v[56:59], v[32:47]
	v_mfma_f32_32x32x16_bf16 v[32:47], v[200:203], v[60:63], v[32:47]
	s_nop 11
	v_exp_f32_e32 v32, v32
	v_exp_f32_e32 v33, v33
	v_exp_f32_e32 v34, v34
	v_exp_f32_e32 v35, v35
	v_exp_f32_e32 v36, v36
	v_exp_f32_e32 v37, v37
	v_exp_f32_e32 v38, v38
	v_exp_f32_e32 v39, v39
	v_exp_f32_e32 v40, v40
	v_exp_f32_e32 v41, v41
	v_exp_f32_e32 v42, v42
	v_exp_f32_e32 v43, v43
	v_exp_f32_e32 v44, v44
	v_exp_f32_e32 v45, v45
	v_exp_f32_e32 v46, v46
	v_exp_f32_e32 v47, v47
	s_add_i32 s90, s67, -256
	v_lshlrev_b32_e32 v84, 2, v107
	v_add_u32_e32 v84, s90, v84
	v_add_u32_e32 v85, 0, v84
	v_add_u32_e32 v86, 4, v84
	v_add_u32_e32 v87, 8, v84
	v_add_u32_e32 v88, 12, v84
	v_cmp_gt_u32_e64 s[30:31], s98, v85
	v_cmp_gt_u32_e64 s[36:37], s98, v86
	v_cmp_gt_u32_e64 s[78:79], s98, v87
	v_cmp_gt_u32_e64 s[50:51], s98, v88
	v_cndmask_b32_e64 v32, 0, v32, s[30:31]
	v_add_u32_e32 v85, 32, v84
	v_cmp_gt_u32_e64 s[30:31], s98, v85
	v_cndmask_b32_e64 v33, 0, v33, s[36:37]
	v_add_u32_e32 v86, 36, v84
	v_cmp_gt_u32_e64 s[36:37], s98, v86
	v_cndmask_b32_e64 v34, 0, v34, s[78:79]
	v_add_u32_e32 v87, 40, v84
	v_cmp_gt_u32_e64 s[78:79], s98, v87
	v_cndmask_b32_e64 v35, 0, v35, s[50:51]
	v_add_u32_e32 v88, 44, v84
	v_cmp_gt_u32_e64 s[50:51], s98, v88
	v_cndmask_b32_e64 v36, 0, v36, s[30:31]
	v_add_u32_e32 v85, 64, v84
	v_cmp_gt_u32_e64 s[30:31], s98, v85
	v_cndmask_b32_e64 v37, 0, v37, s[36:37]
	v_add_u32_e32 v86, 68, v84
	v_cmp_gt_u32_e64 s[36:37], s98, v86
	v_cndmask_b32_e64 v38, 0, v38, s[78:79]
	v_add_u32_e32 v87, 72, v84
	v_cmp_gt_u32_e64 s[78:79], s98, v87
	v_cndmask_b32_e64 v39, 0, v39, s[50:51]
	v_add_u32_e32 v88, 76, v84
	v_cmp_gt_u32_e64 s[50:51], s98, v88
	v_cndmask_b32_e64 v40, 0, v40, s[30:31]
	v_add_u32_e32 v85, 96, v84
	v_cmp_gt_u32_e64 s[30:31], s98, v85
	v_cndmask_b32_e64 v41, 0, v41, s[36:37]
	v_add_u32_e32 v86, 100, v84
	v_cmp_gt_u32_e64 s[36:37], s98, v86
	v_cndmask_b32_e64 v42, 0, v42, s[78:79]
	v_add_u32_e32 v87, 104, v84
	v_cmp_gt_u32_e64 s[78:79], s98, v87
	v_cndmask_b32_e64 v43, 0, v43, s[50:51]
	v_add_u32_e32 v88, 108, v84
	v_cmp_gt_u32_e64 s[50:51], s98, v88
	v_nop
	v_cndmask_b32_e64 v44, 0, v44, s[30:31]
	v_cndmask_b32_e64 v45, 0, v45, s[36:37]
	v_cndmask_b32_e64 v46, 0, v46, s[78:79]
	v_cndmask_b32_e64 v47, 0, v47, s[50:51]
	v_cvt_pk_bf16_f32 v64, v32, v33
	v_cvt_pk_bf16_f32 v65, v34, v35
	v_cvt_pk_bf16_f32 v66, v36, v37
	v_cvt_pk_bf16_f32 v67, v38, v39
	v_cvt_pk_bf16_f32 v68, v40, v41
	v_cvt_pk_bf16_f32 v69, v42, v43
	v_cvt_pk_bf16_f32 v70, v44, v45
	v_cvt_pk_bf16_f32 v71, v46, v47
	v_pk_add_f32 v[232:233], v[232:233], v[32:33]
	v_pk_add_f32 v[232:233], v[232:233], v[34:35]
	v_pk_add_f32 v[232:233], v[232:233], v[36:37]
	v_pk_add_f32 v[232:233], v[232:233], v[38:39]
	v_pk_add_f32 v[232:233], v[232:233], v[40:41]
	v_pk_add_f32 v[232:233], v[232:233], v[42:43]
	v_pk_add_f32 v[232:233], v[232:233], v[44:45]
	v_pk_add_f32 v[232:233], v[232:233], v[46:47]
	ds_read2_b32 v[32:33], v115 offset0:32 offset1:33
	ds_read2_b32 v[34:35], v115 offset0:34 offset1:35
	ds_read2_b32 v[36:37], v115 offset0:40 offset1:41
	ds_read2_b32 v[38:39], v115 offset0:42 offset1:43
	ds_read2_b32 v[40:41], v115 offset0:48 offset1:49
	ds_read2_b32 v[42:43], v115 offset0:50 offset1:51
	ds_read2_b32 v[44:45], v115 offset0:56 offset1:57
	ds_read2_b32 v[46:47], v115 offset0:58 offset1:59
	s_waitcnt lgkmcnt(15)
	v_mfma_f32_32x32x16_bf16 v[0:15], v[64:67], v[72:75], v[0:15]
	v_mfma_f32_32x32x16_bf16 v[16:31], v[64:67], v[76:79], v[16:31]
	v_mfma_f32_32x32x16_bf16 v[0:15], v[68:71], v[220:223], v[0:15]
	v_mfma_f32_32x32x16_bf16 v[16:31], v[68:71], v[224:227], v[16:31]
	s_add_i32 s90, s67, 128
	v_add_u32_e32 v80, s90, v239
	v_add_u32_e32 v83, s90, v240
	v_add_u32_e32 v99, s90, v241
	v_add_u32_e32 v253, s90, v242
	v_add_u32_e32 v254, s90, v101
	v_add_u32_e32 v255, s90, v150
	v_med3_i32 v80, v80, 0, s99
	v_med3_i32 v83, v83, 0, s99
	v_med3_i32 v99, v99, 0, s99
	v_med3_i32 v253, v253, 0, s99
	v_med3_i32 v254, v254, 0, s99
	v_med3_i32 v255, v255, 0, s99
	v_mad_u32_u24 v80, v80, s100, v252
	v_mad_u32_u24 v83, v83, s100, v252
	v_mad_u32_u24 v99, v99, s100, v252
	v_mad_u32_u24 v253, v253, s100, v252
	v_mad_u32_u24 v254, v254, s100, v153
	v_mad_u32_u24 v255, v255, s100, v153
	global_load_dwordx4 v[188:191], v80, s[82:83]
	global_load_dwordx4 v[192:195], v83, s[82:83]
	global_load_dwordx4 v[196:199], v99, s[82:83]
	global_load_dwordx4 v[200:203], v253, s[82:83]
	global_load_dwordx4 v[204:207], v254, s[82:83] offset:768
	global_load_dwordx4 v[208:211], v255, s[82:83] offset:768
	global_load_dwordx4 v[212:215], v254, s[82:83] offset:832
	global_load_dwordx4 v[216:219], v255, s[82:83] offset:832
	s_waitcnt lgkmcnt(0)
	v_mfma_f32_32x32x16_bf16 v[32:47], v[116:119], v[48:51], v[32:47]
	ds_read_b64_tr_b16 v[72:73], v231
	ds_read_b64_tr_b16 v[74:75], v231 offset:512
	ds_read_b64_tr_b16 v[76:77], v231 offset:2048
	ds_read_b64_tr_b16 v[78:79], v231 offset:2560
	ds_read_b64_tr_b16 v[220:221], v231 offset:1024
	ds_read_b64_tr_b16 v[222:223], v231 offset:1536
	ds_read_b64_tr_b16 v[224:225], v231 offset:3072
	ds_read_b64_tr_b16 v[226:227], v231 offset:3584
	s_waitcnt vmcnt(8)
	ds_write_b128 v247, v[156:159]
	ds_write_b128 v247, v[160:163] offset:1024
	ds_write_b128 v247, v[164:167] offset:2048
	ds_write_b128 v247, v[168:171] offset:3072
	ds_read_b128 v[156:159], v248
	ds_read_b128 v[160:163], v249
	ds_read_b128 v[164:167], v250
	ds_read_b128 v[168:171], v251
	ds_write_b128 v112, v[172:175]
	ds_write_b128 v112, v[176:179] offset:1024
	ds_write_b128 v112, v[180:183] offset:2048
	ds_write_b128 v112, v[184:187] offset:3072
	v_mfma_f32_32x32x16_bf16 v[32:47], v[120:123], v[52:55], v[32:47]
	v_mfma_f32_32x32x16_bf16 v[32:47], v[124:127], v[56:59], v[32:47]
	v_mfma_f32_32x32x16_bf16 v[32:47], v[128:131], v[60:63], v[32:47]
	s_nop 11
	v_exp_f32_e32 v32, v32
	v_exp_f32_e32 v33, v33
	v_exp_f32_e32 v34, v34
	v_exp_f32_e32 v35, v35
	v_exp_f32_e32 v36, v36
	v_exp_f32_e32 v37, v37
	v_exp_f32_e32 v38, v38
	v_exp_f32_e32 v39, v39
	v_exp_f32_e32 v40, v40
	v_exp_f32_e32 v41, v41
	v_exp_f32_e32 v42, v42
	v_exp_f32_e32 v43, v43
	v_exp_f32_e32 v44, v44
	v_exp_f32_e32 v45, v45
	v_exp_f32_e32 v46, v46
	v_exp_f32_e32 v47, v47
	s_add_i32 s90, s67, -128
	v_lshlrev_b32_e32 v84, 2, v107
	v_add_u32_e32 v84, s90, v84
	v_add_u32_e32 v85, 0, v84
	v_add_u32_e32 v86, 4, v84
	v_add_u32_e32 v87, 8, v84
	v_add_u32_e32 v88, 12, v84
	v_cmp_gt_u32_e64 s[30:31], s98, v85
	v_cmp_gt_u32_e64 s[36:37], s98, v86
	v_cmp_gt_u32_e64 s[78:79], s98, v87
	v_cmp_gt_u32_e64 s[50:51], s98, v88
	v_cndmask_b32_e64 v32, 0, v32, s[30:31]
	v_add_u32_e32 v85, 32, v84
	v_cmp_gt_u32_e64 s[30:31], s98, v85
	v_cndmask_b32_e64 v33, 0, v33, s[36:37]
	v_add_u32_e32 v86, 36, v84
	v_cmp_gt_u32_e64 s[36:37], s98, v86
	v_cndmask_b32_e64 v34, 0, v34, s[78:79]
	v_add_u32_e32 v87, 40, v84
	v_cmp_gt_u32_e64 s[78:79], s98, v87
	v_cndmask_b32_e64 v35, 0, v35, s[50:51]
	v_add_u32_e32 v88, 44, v84
	v_cmp_gt_u32_e64 s[50:51], s98, v88
	v_cndmask_b32_e64 v36, 0, v36, s[30:31]
	v_add_u32_e32 v85, 64, v84
	v_cmp_gt_u32_e64 s[30:31], s98, v85
	v_cndmask_b32_e64 v37, 0, v37, s[36:37]
	v_add_u32_e32 v86, 68, v84
	v_cmp_gt_u32_e64 s[36:37], s98, v86
	v_cndmask_b32_e64 v38, 0, v38, s[78:79]
	v_add_u32_e32 v87, 72, v84
	v_cmp_gt_u32_e64 s[78:79], s98, v87
	v_cndmask_b32_e64 v39, 0, v39, s[50:51]
	v_add_u32_e32 v88, 76, v84
	v_cmp_gt_u32_e64 s[50:51], s98, v88
	v_cndmask_b32_e64 v40, 0, v40, s[30:31]
	v_add_u32_e32 v85, 96, v84
	v_cmp_gt_u32_e64 s[30:31], s98, v85
	v_cndmask_b32_e64 v41, 0, v41, s[36:37]
	v_add_u32_e32 v86, 100, v84
	v_cmp_gt_u32_e64 s[36:37], s98, v86
	v_cndmask_b32_e64 v42, 0, v42, s[78:79]
	v_add_u32_e32 v87, 104, v84
	v_cmp_gt_u32_e64 s[78:79], s98, v87
	v_cndmask_b32_e64 v43, 0, v43, s[50:51]
	v_add_u32_e32 v88, 108, v84
	v_cmp_gt_u32_e64 s[50:51], s98, v88
	v_nop
	v_cndmask_b32_e64 v44, 0, v44, s[30:31]
	v_cndmask_b32_e64 v45, 0, v45, s[36:37]
	v_cndmask_b32_e64 v46, 0, v46, s[78:79]
	v_cndmask_b32_e64 v47, 0, v47, s[50:51]
	v_cvt_pk_bf16_f32 v64, v32, v33
	v_cvt_pk_bf16_f32 v65, v34, v35
	v_cvt_pk_bf16_f32 v66, v36, v37
	v_cvt_pk_bf16_f32 v67, v38, v39
	v_cvt_pk_bf16_f32 v68, v40, v41
	v_cvt_pk_bf16_f32 v69, v42, v43
	v_cvt_pk_bf16_f32 v70, v44, v45
	v_cvt_pk_bf16_f32 v71, v46, v47
	v_pk_add_f32 v[232:233], v[232:233], v[32:33]
	v_pk_add_f32 v[232:233], v[232:233], v[34:35]
	v_pk_add_f32 v[232:233], v[232:233], v[36:37]
	v_pk_add_f32 v[232:233], v[232:233], v[38:39]
	v_pk_add_f32 v[232:233], v[232:233], v[40:41]
	v_pk_add_f32 v[232:233], v[232:233], v[42:43]
	v_pk_add_f32 v[232:233], v[232:233], v[44:45]
	v_pk_add_f32 v[232:233], v[232:233], v[46:47]
	ds_read2_b32 v[32:33], v115 offset0:64 offset1:65
	ds_read2_b32 v[34:35], v115 offset0:66 offset1:67
	ds_read2_b32 v[36:37], v115 offset0:72 offset1:73
	ds_read2_b32 v[38:39], v115 offset0:74 offset1:75
	ds_read2_b32 v[40:41], v115 offset0:80 offset1:81
	ds_read2_b32 v[42:43], v115 offset0:82 offset1:83
	ds_read2_b32 v[44:45], v115 offset0:88 offset1:89
	ds_read2_b32 v[46:47], v115 offset0:90 offset1:91
	s_waitcnt lgkmcnt(15)
	v_mfma_f32_32x32x16_bf16 v[0:15], v[64:67], v[72:75], v[0:15]
	v_mfma_f32_32x32x16_bf16 v[16:31], v[64:67], v[76:79], v[16:31]
	v_mfma_f32_32x32x16_bf16 v[0:15], v[68:71], v[220:223], v[0:15]
	v_mfma_f32_32x32x16_bf16 v[16:31], v[68:71], v[224:227], v[16:31]
	s_add_i32 s90, s67, 256
	v_add_u32_e32 v80, s90, v239
	v_add_u32_e32 v83, s90, v240
	v_add_u32_e32 v99, s90, v241
	v_add_u32_e32 v253, s90, v242
	v_add_u32_e32 v254, s90, v101
	v_add_u32_e32 v255, s90, v150
	v_med3_i32 v80, v80, 0, s99
	v_med3_i32 v83, v83, 0, s99
	v_med3_i32 v99, v99, 0, s99
	v_med3_i32 v253, v253, 0, s99
	v_med3_i32 v254, v254, 0, s99
	v_med3_i32 v255, v255, 0, s99
	v_mad_u32_u24 v80, v80, s100, v252
	v_mad_u32_u24 v83, v83, s100, v252
	v_mad_u32_u24 v99, v99, s100, v252
	v_mad_u32_u24 v253, v253, s100, v252
	v_mad_u32_u24 v254, v254, s100, v153
	v_mad_u32_u24 v255, v255, s100, v153
	global_load_dwordx4 v[116:119], v80, s[82:83]
	global_load_dwordx4 v[120:123], v83, s[82:83]
	global_load_dwordx4 v[124:127], v99, s[82:83]
	global_load_dwordx4 v[128:131], v253, s[82:83]
	global_load_dwordx4 v[132:135], v254, s[82:83] offset:768
	global_load_dwordx4 v[136:139], v255, s[82:83] offset:768
	global_load_dwordx4 v[140:143], v254, s[82:83] offset:832
	global_load_dwordx4 v[144:147], v255, s[82:83] offset:832
	s_waitcnt lgkmcnt(0)
	v_mfma_f32_32x32x16_bf16 v[32:47], v[156:159], v[48:51], v[32:47]
	ds_read_b64_tr_b16 v[72:73], v231
	ds_read_b64_tr_b16 v[74:75], v231 offset:512
	ds_read_b64_tr_b16 v[76:77], v231 offset:2048
	ds_read_b64_tr_b16 v[78:79], v231 offset:2560
	ds_read_b64_tr_b16 v[220:221], v231 offset:1024
	ds_read_b64_tr_b16 v[222:223], v231 offset:1536
	ds_read_b64_tr_b16 v[224:225], v231 offset:3072
	ds_read_b64_tr_b16 v[226:227], v231 offset:3584
	s_waitcnt vmcnt(8)
	ds_write_b128 v247, v[188:191]
	ds_write_b128 v247, v[192:195] offset:1024
	ds_write_b128 v247, v[196:199] offset:2048
	ds_write_b128 v247, v[200:203] offset:3072
	ds_read_b128 v[188:191], v248
	ds_read_b128 v[192:195], v249
	ds_read_b128 v[196:199], v250
	ds_read_b128 v[200:203], v251
	ds_write_b128 v112, v[204:207]
	ds_write_b128 v112, v[208:211] offset:1024
	ds_write_b128 v112, v[212:215] offset:2048
	ds_write_b128 v112, v[216:219] offset:3072
	v_mfma_f32_32x32x16_bf16 v[32:47], v[160:163], v[52:55], v[32:47]
	v_mfma_f32_32x32x16_bf16 v[32:47], v[164:167], v[56:59], v[32:47]
	v_mfma_f32_32x32x16_bf16 v[32:47], v[168:171], v[60:63], v[32:47]
	s_nop 11
	v_exp_f32_e32 v32, v32
	v_exp_f32_e32 v33, v33
	v_exp_f32_e32 v34, v34
	v_exp_f32_e32 v35, v35
	v_exp_f32_e32 v36, v36
	v_exp_f32_e32 v37, v37
	v_exp_f32_e32 v38, v38
	v_exp_f32_e32 v39, v39
	v_exp_f32_e32 v40, v40
	v_exp_f32_e32 v41, v41
	v_exp_f32_e32 v42, v42
	v_exp_f32_e32 v43, v43
	v_exp_f32_e32 v44, v44
	v_exp_f32_e32 v45, v45
	v_exp_f32_e32 v46, v46
	v_exp_f32_e32 v47, v47
	s_add_i32 s90, s67, 0
	v_lshlrev_b32_e32 v84, 2, v107
	v_add_u32_e32 v84, s90, v84
	v_add_u32_e32 v85, 0, v84
	v_add_u32_e32 v86, 4, v84
	v_add_u32_e32 v87, 8, v84
	v_add_u32_e32 v88, 12, v84
	v_cmp_gt_u32_e64 s[30:31], s98, v85
	v_cmp_gt_u32_e64 s[36:37], s98, v86
	v_cmp_gt_u32_e64 s[78:79], s98, v87
	v_cmp_gt_u32_e64 s[50:51], s98, v88
	v_cndmask_b32_e64 v32, 0, v32, s[30:31]
	v_add_u32_e32 v85, 32, v84
	v_cmp_gt_u32_e64 s[30:31], s98, v85
	v_cndmask_b32_e64 v33, 0, v33, s[36:37]
	v_add_u32_e32 v86, 36, v84
	v_cmp_gt_u32_e64 s[36:37], s98, v86
	v_cndmask_b32_e64 v34, 0, v34, s[78:79]
	v_add_u32_e32 v87, 40, v84
	v_cmp_gt_u32_e64 s[78:79], s98, v87
	v_cndmask_b32_e64 v35, 0, v35, s[50:51]
	v_add_u32_e32 v88, 44, v84
	v_cmp_gt_u32_e64 s[50:51], s98, v88
	v_cndmask_b32_e64 v36, 0, v36, s[30:31]
	v_add_u32_e32 v85, 64, v84
	v_cmp_gt_u32_e64 s[30:31], s98, v85
	v_cndmask_b32_e64 v37, 0, v37, s[36:37]
	v_add_u32_e32 v86, 68, v84
	v_cmp_gt_u32_e64 s[36:37], s98, v86
	v_cndmask_b32_e64 v38, 0, v38, s[78:79]
	v_add_u32_e32 v87, 72, v84
	v_cmp_gt_u32_e64 s[78:79], s98, v87
	v_cndmask_b32_e64 v39, 0, v39, s[50:51]
	v_add_u32_e32 v88, 76, v84
	v_cmp_gt_u32_e64 s[50:51], s98, v88
	v_cndmask_b32_e64 v40, 0, v40, s[30:31]
	v_add_u32_e32 v85, 96, v84
	v_cmp_gt_u32_e64 s[30:31], s98, v85
	v_cndmask_b32_e64 v41, 0, v41, s[36:37]
	v_add_u32_e32 v86, 100, v84
	v_cmp_gt_u32_e64 s[36:37], s98, v86
	v_cndmask_b32_e64 v42, 0, v42, s[78:79]
	v_add_u32_e32 v87, 104, v84
	v_cmp_gt_u32_e64 s[78:79], s98, v87
	v_cndmask_b32_e64 v43, 0, v43, s[50:51]
	v_add_u32_e32 v88, 108, v84
	v_cmp_gt_u32_e64 s[50:51], s98, v88
	v_nop
	v_cndmask_b32_e64 v44, 0, v44, s[30:31]
	v_cndmask_b32_e64 v45, 0, v45, s[36:37]
	v_cndmask_b32_e64 v46, 0, v46, s[78:79]
	v_cndmask_b32_e64 v47, 0, v47, s[50:51]
	v_cvt_pk_bf16_f32 v64, v32, v33
	v_cvt_pk_bf16_f32 v65, v34, v35
	v_cvt_pk_bf16_f32 v66, v36, v37
	v_cvt_pk_bf16_f32 v67, v38, v39
	v_cvt_pk_bf16_f32 v68, v40, v41
	v_cvt_pk_bf16_f32 v69, v42, v43
	v_cvt_pk_bf16_f32 v70, v44, v45
	v_cvt_pk_bf16_f32 v71, v46, v47
	v_pk_add_f32 v[232:233], v[232:233], v[32:33]
	v_pk_add_f32 v[232:233], v[232:233], v[34:35]
	v_pk_add_f32 v[232:233], v[232:233], v[36:37]
	v_pk_add_f32 v[232:233], v[232:233], v[38:39]
	v_pk_add_f32 v[232:233], v[232:233], v[40:41]
	v_pk_add_f32 v[232:233], v[232:233], v[42:43]
	v_pk_add_f32 v[232:233], v[232:233], v[44:45]
	v_pk_add_f32 v[232:233], v[232:233], v[46:47]
	ds_read2_b32 v[32:33], v115 offset0:96 offset1:97
	ds_read2_b32 v[34:35], v115 offset0:98 offset1:99
	ds_read2_b32 v[36:37], v115 offset0:104 offset1:105
	ds_read2_b32 v[38:39], v115 offset0:106 offset1:107
	ds_read2_b32 v[40:41], v115 offset0:112 offset1:113
	ds_read2_b32 v[42:43], v115 offset0:114 offset1:115
	ds_read2_b32 v[44:45], v115 offset0:120 offset1:121
	ds_read2_b32 v[46:47], v115 offset0:122 offset1:123
	s_waitcnt lgkmcnt(15)
	v_mfma_f32_32x32x16_bf16 v[0:15], v[64:67], v[72:75], v[0:15]
	v_mfma_f32_32x32x16_bf16 v[16:31], v[64:67], v[76:79], v[16:31]
	v_mfma_f32_32x32x16_bf16 v[0:15], v[68:71], v[220:223], v[0:15]
	v_mfma_f32_32x32x16_bf16 v[16:31], v[68:71], v[224:227], v[16:31]
	s_add_i32 s90, s67, 384
	v_add_u32_e32 v80, s90, v239
	v_add_u32_e32 v83, s90, v240
	v_add_u32_e32 v99, s90, v241
	v_add_u32_e32 v253, s90, v242
	v_add_u32_e32 v254, s90, v101
	v_add_u32_e32 v255, s90, v150
	v_med3_i32 v80, v80, 0, s99
	v_med3_i32 v83, v83, 0, s99
	v_med3_i32 v99, v99, 0, s99
	v_med3_i32 v253, v253, 0, s99
	v_med3_i32 v254, v254, 0, s99
	v_med3_i32 v255, v255, 0, s99
	v_mad_u32_u24 v80, v80, s100, v252
	v_mad_u32_u24 v83, v83, s100, v252
	v_mad_u32_u24 v99, v99, s100, v252
	v_mad_u32_u24 v253, v253, s100, v252
	v_mad_u32_u24 v254, v254, s100, v153
	v_mad_u32_u24 v255, v255, s100, v153
	global_load_dwordx4 v[156:159], v80, s[82:83]
	global_load_dwordx4 v[160:163], v83, s[82:83]
	global_load_dwordx4 v[164:167], v99, s[82:83]
	global_load_dwordx4 v[168:171], v253, s[82:83]
	global_load_dwordx4 v[172:175], v254, s[82:83] offset:768
	global_load_dwordx4 v[176:179], v255, s[82:83] offset:768
	global_load_dwordx4 v[180:183], v254, s[82:83] offset:832
	global_load_dwordx4 v[184:187], v255, s[82:83] offset:832
	s_waitcnt lgkmcnt(0)
	v_mfma_f32_32x32x16_bf16 v[32:47], v[188:191], v[48:51], v[32:47]
	ds_read_b64_tr_b16 v[72:73], v231
	ds_read_b64_tr_b16 v[74:75], v231 offset:512
	ds_read_b64_tr_b16 v[76:77], v231 offset:2048
	ds_read_b64_tr_b16 v[78:79], v231 offset:2560
	ds_read_b64_tr_b16 v[220:221], v231 offset:1024
	ds_read_b64_tr_b16 v[222:223], v231 offset:1536
	ds_read_b64_tr_b16 v[224:225], v231 offset:3072
	ds_read_b64_tr_b16 v[226:227], v231 offset:3584
	s_waitcnt vmcnt(8)
	ds_write_b128 v247, v[116:119]
	ds_write_b128 v247, v[120:123] offset:1024
	ds_write_b128 v247, v[124:127] offset:2048
	ds_write_b128 v247, v[128:131] offset:3072
	ds_read_b128 v[116:119], v248
	ds_read_b128 v[120:123], v249
	ds_read_b128 v[124:127], v250
	ds_read_b128 v[128:131], v251
	ds_write_b128 v112, v[132:135]
	ds_write_b128 v112, v[136:139] offset:1024
	ds_write_b128 v112, v[140:143] offset:2048
	ds_write_b128 v112, v[144:147] offset:3072
	v_mfma_f32_32x32x16_bf16 v[32:47], v[192:195], v[52:55], v[32:47]
	v_mfma_f32_32x32x16_bf16 v[32:47], v[196:199], v[56:59], v[32:47]
	v_mfma_f32_32x32x16_bf16 v[32:47], v[200:203], v[60:63], v[32:47]
	s_nop 11
	v_exp_f32_e32 v32, v32
	v_exp_f32_e32 v33, v33
	v_exp_f32_e32 v34, v34
	v_exp_f32_e32 v35, v35
	v_exp_f32_e32 v36, v36
	v_exp_f32_e32 v37, v37
	v_exp_f32_e32 v38, v38
	v_exp_f32_e32 v39, v39
	v_exp_f32_e32 v40, v40
	v_exp_f32_e32 v41, v41
	v_exp_f32_e32 v42, v42
	v_exp_f32_e32 v43, v43
	v_exp_f32_e32 v44, v44
	v_exp_f32_e32 v45, v45
	v_exp_f32_e32 v46, v46
	v_exp_f32_e32 v47, v47
	s_add_i32 s90, s67, 128
	v_lshlrev_b32_e32 v84, 2, v107
	v_add_u32_e32 v84, s90, v84
	v_add_u32_e32 v85, 0, v84
	v_add_u32_e32 v86, 4, v84
	v_add_u32_e32 v87, 8, v84
	v_add_u32_e32 v88, 12, v84
	v_cmp_gt_u32_e64 s[30:31], s98, v85
	v_cmp_gt_u32_e64 s[36:37], s98, v86
	v_cmp_gt_u32_e64 s[78:79], s98, v87
	v_cmp_gt_u32_e64 s[50:51], s98, v88
	v_cndmask_b32_e64 v32, 0, v32, s[30:31]
	v_add_u32_e32 v85, 32, v84
	v_cmp_gt_u32_e64 s[30:31], s98, v85
	v_cndmask_b32_e64 v33, 0, v33, s[36:37]
	v_add_u32_e32 v86, 36, v84
	v_cmp_gt_u32_e64 s[36:37], s98, v86
	v_cndmask_b32_e64 v34, 0, v34, s[78:79]
	v_add_u32_e32 v87, 40, v84
	v_cmp_gt_u32_e64 s[78:79], s98, v87
	v_cndmask_b32_e64 v35, 0, v35, s[50:51]
	v_add_u32_e32 v88, 44, v84
	v_cmp_gt_u32_e64 s[50:51], s98, v88
	v_cndmask_b32_e64 v36, 0, v36, s[30:31]
	v_add_u32_e32 v85, 64, v84
	v_cmp_gt_u32_e64 s[30:31], s98, v85
	v_cndmask_b32_e64 v37, 0, v37, s[36:37]
	v_add_u32_e32 v86, 68, v84
	v_cmp_gt_u32_e64 s[36:37], s98, v86
	v_cndmask_b32_e64 v38, 0, v38, s[78:79]
	v_add_u32_e32 v87, 72, v84
	v_cmp_gt_u32_e64 s[78:79], s98, v87
	v_cndmask_b32_e64 v39, 0, v39, s[50:51]
	v_add_u32_e32 v88, 76, v84
	v_cmp_gt_u32_e64 s[50:51], s98, v88
	v_cndmask_b32_e64 v40, 0, v40, s[30:31]
	v_add_u32_e32 v85, 96, v84
	v_cmp_gt_u32_e64 s[30:31], s98, v85
	v_cndmask_b32_e64 v41, 0, v41, s[36:37]
	v_add_u32_e32 v86, 100, v84
	v_cmp_gt_u32_e64 s[36:37], s98, v86
	v_cndmask_b32_e64 v42, 0, v42, s[78:79]
	v_add_u32_e32 v87, 104, v84
	v_cmp_gt_u32_e64 s[78:79], s98, v87
	v_cndmask_b32_e64 v43, 0, v43, s[50:51]
	v_add_u32_e32 v88, 108, v84
	v_cmp_gt_u32_e64 s[50:51], s98, v88
	v_nop
	v_cndmask_b32_e64 v44, 0, v44, s[30:31]
	v_cndmask_b32_e64 v45, 0, v45, s[36:37]
	v_cndmask_b32_e64 v46, 0, v46, s[78:79]
	v_cndmask_b32_e64 v47, 0, v47, s[50:51]
	v_cvt_pk_bf16_f32 v64, v32, v33
	v_cvt_pk_bf16_f32 v65, v34, v35
	v_cvt_pk_bf16_f32 v66, v36, v37
	v_cvt_pk_bf16_f32 v67, v38, v39
	v_cvt_pk_bf16_f32 v68, v40, v41
	v_cvt_pk_bf16_f32 v69, v42, v43
	v_cvt_pk_bf16_f32 v70, v44, v45
	v_cvt_pk_bf16_f32 v71, v46, v47
	v_pk_add_f32 v[232:233], v[232:233], v[32:33]
	v_pk_add_f32 v[232:233], v[232:233], v[34:35]
	v_pk_add_f32 v[232:233], v[232:233], v[36:37]
	v_pk_add_f32 v[232:233], v[232:233], v[38:39]
	v_pk_add_f32 v[232:233], v[232:233], v[40:41]
	v_pk_add_f32 v[232:233], v[232:233], v[42:43]
	v_pk_add_f32 v[232:233], v[232:233], v[44:45]
	v_pk_add_f32 v[232:233], v[232:233], v[46:47]
	ds_read2_b32 v[32:33], v115 offset0:128 offset1:129
	ds_read2_b32 v[34:35], v115 offset0:130 offset1:131
	ds_read2_b32 v[36:37], v115 offset0:136 offset1:137
	ds_read2_b32 v[38:39], v115 offset0:138 offset1:139
	ds_read2_b32 v[40:41], v115 offset0:144 offset1:145
	ds_read2_b32 v[42:43], v115 offset0:146 offset1:147
	ds_read2_b32 v[44:45], v115 offset0:152 offset1:153
	ds_read2_b32 v[46:47], v115 offset0:154 offset1:155
	s_waitcnt lgkmcnt(15)
	v_mfma_f32_32x32x16_bf16 v[0:15], v[64:67], v[72:75], v[0:15]
	v_mfma_f32_32x32x16_bf16 v[16:31], v[64:67], v[76:79], v[16:31]
	v_mfma_f32_32x32x16_bf16 v[0:15], v[68:71], v[220:223], v[0:15]
	v_mfma_f32_32x32x16_bf16 v[16:31], v[68:71], v[224:227], v[16:31]
	s_add_i32 s90, s67, 512
	v_add_u32_e32 v80, s90, v239
	v_add_u32_e32 v83, s90, v240
	v_add_u32_e32 v99, s90, v241
	v_add_u32_e32 v253, s90, v242
	v_add_u32_e32 v254, s90, v101
	v_add_u32_e32 v255, s90, v150
	v_med3_i32 v80, v80, 0, s99
	v_med3_i32 v83, v83, 0, s99
	v_med3_i32 v99, v99, 0, s99
	v_med3_i32 v253, v253, 0, s99
	v_med3_i32 v254, v254, 0, s99
	v_med3_i32 v255, v255, 0, s99
	v_mad_u32_u24 v80, v80, s100, v252
	v_mad_u32_u24 v83, v83, s100, v252
	v_mad_u32_u24 v99, v99, s100, v252
	v_mad_u32_u24 v253, v253, s100, v252
	v_mad_u32_u24 v254, v254, s100, v153
	v_mad_u32_u24 v255, v255, s100, v153
	global_load_dwordx4 v[188:191], v80, s[82:83]
	global_load_dwordx4 v[192:195], v83, s[82:83]
	global_load_dwordx4 v[196:199], v99, s[82:83]
	global_load_dwordx4 v[200:203], v253, s[82:83]
	global_load_dwordx4 v[204:207], v254, s[82:83] offset:768
	global_load_dwordx4 v[208:211], v255, s[82:83] offset:768
	global_load_dwordx4 v[212:215], v254, s[82:83] offset:832
	global_load_dwordx4 v[216:219], v255, s[82:83] offset:832
	s_waitcnt lgkmcnt(0)
	v_mfma_f32_32x32x16_bf16 v[32:47], v[116:119], v[48:51], v[32:47]
	ds_read_b64_tr_b16 v[72:73], v231
	ds_read_b64_tr_b16 v[74:75], v231 offset:512
	ds_read_b64_tr_b16 v[76:77], v231 offset:2048
	ds_read_b64_tr_b16 v[78:79], v231 offset:2560
	ds_read_b64_tr_b16 v[220:221], v231 offset:1024
	ds_read_b64_tr_b16 v[222:223], v231 offset:1536
	ds_read_b64_tr_b16 v[224:225], v231 offset:3072
	ds_read_b64_tr_b16 v[226:227], v231 offset:3584
	s_waitcnt vmcnt(8)
	ds_write_b128 v247, v[156:159]
	ds_write_b128 v247, v[160:163] offset:1024
	ds_write_b128 v247, v[164:167] offset:2048
	ds_write_b128 v247, v[168:171] offset:3072
	ds_read_b128 v[156:159], v248
	ds_read_b128 v[160:163], v249
	ds_read_b128 v[164:167], v250
	ds_read_b128 v[168:171], v251
	ds_write_b128 v112, v[172:175]
	ds_write_b128 v112, v[176:179] offset:1024
	ds_write_b128 v112, v[180:183] offset:2048
	ds_write_b128 v112, v[184:187] offset:3072
	v_mfma_f32_32x32x16_bf16 v[32:47], v[120:123], v[52:55], v[32:47]
	v_mfma_f32_32x32x16_bf16 v[32:47], v[124:127], v[56:59], v[32:47]
	v_mfma_f32_32x32x16_bf16 v[32:47], v[128:131], v[60:63], v[32:47]
	s_nop 11
	v_exp_f32_e32 v32, v32
	v_exp_f32_e32 v33, v33
	v_exp_f32_e32 v34, v34
	v_exp_f32_e32 v35, v35
	v_exp_f32_e32 v36, v36
	v_exp_f32_e32 v37, v37
	v_exp_f32_e32 v38, v38
	v_exp_f32_e32 v39, v39
	v_exp_f32_e32 v40, v40
	v_exp_f32_e32 v41, v41
	v_exp_f32_e32 v42, v42
	v_exp_f32_e32 v43, v43
	v_exp_f32_e32 v44, v44
	v_exp_f32_e32 v45, v45
	v_exp_f32_e32 v46, v46
	v_exp_f32_e32 v47, v47
	s_add_i32 s90, s67, 256
	v_lshlrev_b32_e32 v84, 2, v107
	v_add_u32_e32 v84, s90, v84
	v_add_u32_e32 v85, 0, v84
	v_add_u32_e32 v86, 4, v84
	v_add_u32_e32 v87, 8, v84
	v_add_u32_e32 v88, 12, v84
	v_cmp_gt_u32_e64 s[30:31], s98, v85
	v_cmp_gt_u32_e64 s[36:37], s98, v86
	v_cmp_gt_u32_e64 s[78:79], s98, v87
	v_cmp_gt_u32_e64 s[50:51], s98, v88
	v_cndmask_b32_e64 v32, 0, v32, s[30:31]
	v_add_u32_e32 v85, 32, v84
	v_cmp_gt_u32_e64 s[30:31], s98, v85
	v_cndmask_b32_e64 v33, 0, v33, s[36:37]
	v_add_u32_e32 v86, 36, v84
	v_cmp_gt_u32_e64 s[36:37], s98, v86
	v_cndmask_b32_e64 v34, 0, v34, s[78:79]
	v_add_u32_e32 v87, 40, v84
	v_cmp_gt_u32_e64 s[78:79], s98, v87
	v_cndmask_b32_e64 v35, 0, v35, s[50:51]
	v_add_u32_e32 v88, 44, v84
	v_cmp_gt_u32_e64 s[50:51], s98, v88
	v_cndmask_b32_e64 v36, 0, v36, s[30:31]
	v_add_u32_e32 v85, 64, v84
	v_cmp_gt_u32_e64 s[30:31], s98, v85
	v_cndmask_b32_e64 v37, 0, v37, s[36:37]
	v_add_u32_e32 v86, 68, v84
	v_cmp_gt_u32_e64 s[36:37], s98, v86
	v_cndmask_b32_e64 v38, 0, v38, s[78:79]
	v_add_u32_e32 v87, 72, v84
	v_cmp_gt_u32_e64 s[78:79], s98, v87
	v_cndmask_b32_e64 v39, 0, v39, s[50:51]
	v_add_u32_e32 v88, 76, v84
	v_cmp_gt_u32_e64 s[50:51], s98, v88
	v_cndmask_b32_e64 v40, 0, v40, s[30:31]
	v_add_u32_e32 v85, 96, v84
	v_cmp_gt_u32_e64 s[30:31], s98, v85
	v_cndmask_b32_e64 v41, 0, v41, s[36:37]
	v_add_u32_e32 v86, 100, v84
	v_cmp_gt_u32_e64 s[36:37], s98, v86
	v_cndmask_b32_e64 v42, 0, v42, s[78:79]
	v_add_u32_e32 v87, 104, v84
	v_cmp_gt_u32_e64 s[78:79], s98, v87
	v_cndmask_b32_e64 v43, 0, v43, s[50:51]
	v_add_u32_e32 v88, 108, v84
	v_cmp_gt_u32_e64 s[50:51], s98, v88
	v_nop
	v_cndmask_b32_e64 v44, 0, v44, s[30:31]
	v_cndmask_b32_e64 v45, 0, v45, s[36:37]
	v_cndmask_b32_e64 v46, 0, v46, s[78:79]
	v_cndmask_b32_e64 v47, 0, v47, s[50:51]
	v_cvt_pk_bf16_f32 v64, v32, v33
	v_cvt_pk_bf16_f32 v65, v34, v35
	v_cvt_pk_bf16_f32 v66, v36, v37
	v_cvt_pk_bf16_f32 v67, v38, v39
	v_cvt_pk_bf16_f32 v68, v40, v41
	v_cvt_pk_bf16_f32 v69, v42, v43
	v_cvt_pk_bf16_f32 v70, v44, v45
	v_cvt_pk_bf16_f32 v71, v46, v47
	v_pk_add_f32 v[232:233], v[232:233], v[32:33]
	v_pk_add_f32 v[232:233], v[232:233], v[34:35]
	v_pk_add_f32 v[232:233], v[232:233], v[36:37]
	v_pk_add_f32 v[232:233], v[232:233], v[38:39]
	v_pk_add_f32 v[232:233], v[232:233], v[40:41]
	v_pk_add_f32 v[232:233], v[232:233], v[42:43]
	v_pk_add_f32 v[232:233], v[232:233], v[44:45]
	v_pk_add_f32 v[232:233], v[232:233], v[46:47]
	ds_read2_b32 v[32:33], v115 offset0:160 offset1:161
	ds_read2_b32 v[34:35], v115 offset0:162 offset1:163
	ds_read2_b32 v[36:37], v115 offset0:168 offset1:169
	ds_read2_b32 v[38:39], v115 offset0:170 offset1:171
	ds_read2_b32 v[40:41], v115 offset0:176 offset1:177
	ds_read2_b32 v[42:43], v115 offset0:178 offset1:179
	ds_read2_b32 v[44:45], v115 offset0:184 offset1:185
	ds_read2_b32 v[46:47], v115 offset0:186 offset1:187
	s_waitcnt lgkmcnt(15)
	v_mfma_f32_32x32x16_bf16 v[0:15], v[64:67], v[72:75], v[0:15]
	v_mfma_f32_32x32x16_bf16 v[16:31], v[64:67], v[76:79], v[16:31]
	v_mfma_f32_32x32x16_bf16 v[0:15], v[68:71], v[220:223], v[0:15]
	v_mfma_f32_32x32x16_bf16 v[16:31], v[68:71], v[224:227], v[16:31]
	s_add_i32 s90, s67, 640
	v_add_u32_e32 v80, s90, v239
	v_add_u32_e32 v83, s90, v240
	v_add_u32_e32 v99, s90, v241
	v_add_u32_e32 v253, s90, v242
	v_add_u32_e32 v254, s90, v101
	v_add_u32_e32 v255, s90, v150
	v_med3_i32 v80, v80, 0, s99
	v_med3_i32 v83, v83, 0, s99
	v_med3_i32 v99, v99, 0, s99
	v_med3_i32 v253, v253, 0, s99
	v_med3_i32 v254, v254, 0, s99
	v_med3_i32 v255, v255, 0, s99
	v_mad_u32_u24 v80, v80, s100, v252
	v_mad_u32_u24 v83, v83, s100, v252
	v_mad_u32_u24 v99, v99, s100, v252
	v_mad_u32_u24 v253, v253, s100, v252
	v_mad_u32_u24 v254, v254, s100, v153
	v_mad_u32_u24 v255, v255, s100, v153
	global_load_dwordx4 v[116:119], v80, s[82:83]
	global_load_dwordx4 v[120:123], v83, s[82:83]
	global_load_dwordx4 v[124:127], v99, s[82:83]
	global_load_dwordx4 v[128:131], v253, s[82:83]
	global_load_dwordx4 v[132:135], v254, s[82:83] offset:768
	global_load_dwordx4 v[136:139], v255, s[82:83] offset:768
	global_load_dwordx4 v[140:143], v254, s[82:83] offset:832
	global_load_dwordx4 v[144:147], v255, s[82:83] offset:832
	s_waitcnt lgkmcnt(0)
	v_mfma_f32_32x32x16_bf16 v[32:47], v[156:159], v[48:51], v[32:47]
	ds_read_b64_tr_b16 v[72:73], v231
	ds_read_b64_tr_b16 v[74:75], v231 offset:512
	ds_read_b64_tr_b16 v[76:77], v231 offset:2048
	ds_read_b64_tr_b16 v[78:79], v231 offset:2560
	ds_read_b64_tr_b16 v[220:221], v231 offset:1024
	ds_read_b64_tr_b16 v[222:223], v231 offset:1536
	ds_read_b64_tr_b16 v[224:225], v231 offset:3072
	ds_read_b64_tr_b16 v[226:227], v231 offset:3584
	s_waitcnt vmcnt(8)
	ds_write_b128 v247, v[188:191]
	ds_write_b128 v247, v[192:195] offset:1024
	ds_write_b128 v247, v[196:199] offset:2048
	ds_write_b128 v247, v[200:203] offset:3072
	ds_read_b128 v[188:191], v248
	ds_read_b128 v[192:195], v249
	ds_read_b128 v[196:199], v250
	ds_read_b128 v[200:203], v251
	ds_write_b128 v112, v[204:207]
	ds_write_b128 v112, v[208:211] offset:1024
	ds_write_b128 v112, v[212:215] offset:2048
	ds_write_b128 v112, v[216:219] offset:3072
	v_mfma_f32_32x32x16_bf16 v[32:47], v[160:163], v[52:55], v[32:47]
	v_mfma_f32_32x32x16_bf16 v[32:47], v[164:167], v[56:59], v[32:47]
	v_mfma_f32_32x32x16_bf16 v[32:47], v[168:171], v[60:63], v[32:47]
	s_nop 11
	v_exp_f32_e32 v32, v32
	v_exp_f32_e32 v33, v33
	v_exp_f32_e32 v34, v34
	v_exp_f32_e32 v35, v35
	v_exp_f32_e32 v36, v36
	v_exp_f32_e32 v37, v37
	v_exp_f32_e32 v38, v38
	v_exp_f32_e32 v39, v39
	v_exp_f32_e32 v40, v40
	v_exp_f32_e32 v41, v41
	v_exp_f32_e32 v42, v42
	v_exp_f32_e32 v43, v43
	v_exp_f32_e32 v44, v44
	v_exp_f32_e32 v45, v45
	v_exp_f32_e32 v46, v46
	v_exp_f32_e32 v47, v47
	s_add_i32 s90, s67, 384
	v_lshlrev_b32_e32 v84, 2, v107
	v_add_u32_e32 v84, s90, v84
	v_add_u32_e32 v85, 0, v84
	v_add_u32_e32 v86, 4, v84
	v_add_u32_e32 v87, 8, v84
	v_add_u32_e32 v88, 12, v84
	v_cmp_gt_u32_e64 s[30:31], s98, v85
	v_cmp_gt_u32_e64 s[36:37], s98, v86
	v_cmp_gt_u32_e64 s[78:79], s98, v87
	v_cmp_gt_u32_e64 s[50:51], s98, v88
	v_cndmask_b32_e64 v32, 0, v32, s[30:31]
	v_add_u32_e32 v85, 32, v84
	v_cmp_gt_u32_e64 s[30:31], s98, v85
	v_cndmask_b32_e64 v33, 0, v33, s[36:37]
	v_add_u32_e32 v86, 36, v84
	v_cmp_gt_u32_e64 s[36:37], s98, v86
	v_cndmask_b32_e64 v34, 0, v34, s[78:79]
	v_add_u32_e32 v87, 40, v84
	v_cmp_gt_u32_e64 s[78:79], s98, v87
	v_cndmask_b32_e64 v35, 0, v35, s[50:51]
	v_add_u32_e32 v88, 44, v84
	v_cmp_gt_u32_e64 s[50:51], s98, v88
	v_cndmask_b32_e64 v36, 0, v36, s[30:31]
	v_add_u32_e32 v85, 64, v84
	v_cmp_gt_u32_e64 s[30:31], s98, v85
	v_cndmask_b32_e64 v37, 0, v37, s[36:37]
	v_add_u32_e32 v86, 68, v84
	v_cmp_gt_u32_e64 s[36:37], s98, v86
	v_cndmask_b32_e64 v38, 0, v38, s[78:79]
	v_add_u32_e32 v87, 72, v84
	v_cmp_gt_u32_e64 s[78:79], s98, v87
	v_cndmask_b32_e64 v39, 0, v39, s[50:51]
	v_add_u32_e32 v88, 76, v84
	v_cmp_gt_u32_e64 s[50:51], s98, v88
	v_cndmask_b32_e64 v40, 0, v40, s[30:31]
	v_add_u32_e32 v85, 96, v84
	v_cmp_gt_u32_e64 s[30:31], s98, v85
	v_cndmask_b32_e64 v41, 0, v41, s[36:37]
	v_add_u32_e32 v86, 100, v84
	v_cmp_gt_u32_e64 s[36:37], s98, v86
	v_cndmask_b32_e64 v42, 0, v42, s[78:79]
	v_add_u32_e32 v87, 104, v84
	v_cmp_gt_u32_e64 s[78:79], s98, v87
	v_cndmask_b32_e64 v43, 0, v43, s[50:51]
	v_add_u32_e32 v88, 108, v84
	v_cmp_gt_u32_e64 s[50:51], s98, v88
	v_nop
	v_cndmask_b32_e64 v44, 0, v44, s[30:31]
	v_cndmask_b32_e64 v45, 0, v45, s[36:37]
	v_cndmask_b32_e64 v46, 0, v46, s[78:79]
	v_cndmask_b32_e64 v47, 0, v47, s[50:51]
	v_cvt_pk_bf16_f32 v64, v32, v33
	v_cvt_pk_bf16_f32 v65, v34, v35
	v_cvt_pk_bf16_f32 v66, v36, v37
	v_cvt_pk_bf16_f32 v67, v38, v39
	v_cvt_pk_bf16_f32 v68, v40, v41
	v_cvt_pk_bf16_f32 v69, v42, v43
	v_cvt_pk_bf16_f32 v70, v44, v45
	v_cvt_pk_bf16_f32 v71, v46, v47
	v_pk_add_f32 v[232:233], v[232:233], v[32:33]
	v_pk_add_f32 v[232:233], v[232:233], v[34:35]
	v_pk_add_f32 v[232:233], v[232:233], v[36:37]
	v_pk_add_f32 v[232:233], v[232:233], v[38:39]
	v_pk_add_f32 v[232:233], v[232:233], v[40:41]
	v_pk_add_f32 v[232:233], v[232:233], v[42:43]
	v_pk_add_f32 v[232:233], v[232:233], v[44:45]
	v_pk_add_f32 v[232:233], v[232:233], v[46:47]
	ds_read2_b32 v[32:33], v115 offset0:192 offset1:193
	ds_read2_b32 v[34:35], v115 offset0:194 offset1:195
	ds_read2_b32 v[36:37], v115 offset0:200 offset1:201
	ds_read2_b32 v[38:39], v115 offset0:202 offset1:203
	ds_read2_b32 v[40:41], v115 offset0:208 offset1:209
	ds_read2_b32 v[42:43], v115 offset0:210 offset1:211
	ds_read2_b32 v[44:45], v115 offset0:216 offset1:217
	ds_read2_b32 v[46:47], v115 offset0:218 offset1:219
	s_waitcnt lgkmcnt(15)
	v_mfma_f32_32x32x16_bf16 v[0:15], v[64:67], v[72:75], v[0:15]
	v_mfma_f32_32x32x16_bf16 v[16:31], v[64:67], v[76:79], v[16:31]
	v_mfma_f32_32x32x16_bf16 v[0:15], v[68:71], v[220:223], v[0:15]
	v_mfma_f32_32x32x16_bf16 v[16:31], v[68:71], v[224:227], v[16:31]
	s_add_i32 s90, s67, -1024
	v_add_u32_e32 v80, s90, v243
	v_add_u32_e32 v83, s90, v244
	v_add_u32_e32 v99, s90, v245
	v_add_u32_e32 v253, s90, v246
	v_add_u32_e32 v254, s90, v148
	v_add_u32_e32 v255, s90, v151
	v_med3_i32 v80, v80, 0, s99
	v_med3_i32 v83, v83, 0, s99
	v_med3_i32 v99, v99, 0, s99
	v_med3_i32 v253, v253, 0, s99
	v_med3_i32 v254, v254, 0, s99
	v_med3_i32 v255, v255, 0, s99
	v_mad_u32_u24 v80, v80, s100, v252
	v_mad_u32_u24 v83, v83, s100, v252
	v_mad_u32_u24 v99, v99, s100, v252
	v_mad_u32_u24 v253, v253, s100, v252
	v_mad_u32_u24 v254, v254, s100, v153
	v_mad_u32_u24 v255, v255, s100, v153
	global_load_dwordx4 v[156:159], v80, s[82:83]
	global_load_dwordx4 v[160:163], v83, s[82:83]
	global_load_dwordx4 v[164:167], v99, s[82:83]
	global_load_dwordx4 v[168:171], v253, s[82:83]
	global_load_dwordx4 v[172:175], v254, s[82:83] offset:768
	global_load_dwordx4 v[176:179], v255, s[82:83] offset:768
	global_load_dwordx4 v[180:183], v254, s[82:83] offset:832
	global_load_dwordx4 v[184:187], v255, s[82:83] offset:832
	s_waitcnt lgkmcnt(0)
	v_mfma_f32_32x32x16_bf16 v[32:47], v[188:191], v[48:51], v[32:47]
	ds_read_b64_tr_b16 v[72:73], v231
	ds_read_b64_tr_b16 v[74:75], v231 offset:512
	ds_read_b64_tr_b16 v[76:77], v231 offset:2048
	ds_read_b64_tr_b16 v[78:79], v231 offset:2560
	ds_read_b64_tr_b16 v[220:221], v231 offset:1024
	ds_read_b64_tr_b16 v[222:223], v231 offset:1536
	ds_read_b64_tr_b16 v[224:225], v231 offset:3072
	ds_read_b64_tr_b16 v[226:227], v231 offset:3584
	s_waitcnt vmcnt(8)
	ds_write_b128 v247, v[116:119]
	ds_write_b128 v247, v[120:123] offset:1024
	ds_write_b128 v247, v[124:127] offset:2048
	ds_write_b128 v247, v[128:131] offset:3072
	ds_read_b128 v[116:119], v248
	ds_read_b128 v[120:123], v249
	ds_read_b128 v[124:127], v250
	ds_read_b128 v[128:131], v251
	ds_write_b128 v112, v[132:135]
	ds_write_b128 v112, v[136:139] offset:1024
	ds_write_b128 v112, v[140:143] offset:2048
	ds_write_b128 v112, v[144:147] offset:3072
	v_mfma_f32_32x32x16_bf16 v[32:47], v[192:195], v[52:55], v[32:47]
	v_mfma_f32_32x32x16_bf16 v[32:47], v[196:199], v[56:59], v[32:47]
	v_mfma_f32_32x32x16_bf16 v[32:47], v[200:203], v[60:63], v[32:47]
	s_nop 11
	v_exp_f32_e32 v32, v32
	v_exp_f32_e32 v33, v33
	v_exp_f32_e32 v34, v34
	v_exp_f32_e32 v35, v35
	v_exp_f32_e32 v36, v36
	v_exp_f32_e32 v37, v37
	v_exp_f32_e32 v38, v38
	v_exp_f32_e32 v39, v39
	v_exp_f32_e32 v40, v40
	v_exp_f32_e32 v41, v41
	v_exp_f32_e32 v42, v42
	v_exp_f32_e32 v43, v43
	v_exp_f32_e32 v44, v44
	v_exp_f32_e32 v45, v45
	v_exp_f32_e32 v46, v46
	v_exp_f32_e32 v47, v47
	s_add_i32 s90, s67, 512
	v_lshlrev_b32_e32 v84, 2, v107
	v_add_u32_e32 v84, s90, v84
	v_add_u32_e32 v85, 0, v84
	v_add_u32_e32 v86, 4, v84
	v_add_u32_e32 v87, 8, v84
	v_add_u32_e32 v88, 12, v84
	v_cmp_gt_u32_e64 s[30:31], s98, v85
	v_cmp_gt_u32_e64 s[36:37], s98, v86
	v_cmp_gt_u32_e64 s[78:79], s98, v87
	v_cmp_gt_u32_e64 s[50:51], s98, v88
	v_cndmask_b32_e64 v32, 0, v32, s[30:31]
	v_add_u32_e32 v85, 32, v84
	v_cmp_gt_u32_e64 s[30:31], s98, v85
	v_cndmask_b32_e64 v33, 0, v33, s[36:37]
	v_add_u32_e32 v86, 36, v84
	v_cmp_gt_u32_e64 s[36:37], s98, v86
	v_cndmask_b32_e64 v34, 0, v34, s[78:79]
	v_add_u32_e32 v87, 40, v84
	v_cmp_gt_u32_e64 s[78:79], s98, v87
	v_cndmask_b32_e64 v35, 0, v35, s[50:51]
	v_add_u32_e32 v88, 44, v84
	v_cmp_gt_u32_e64 s[50:51], s98, v88
	v_cndmask_b32_e64 v36, 0, v36, s[30:31]
	v_add_u32_e32 v85, 64, v84
	v_cmp_gt_u32_e64 s[30:31], s98, v85
	v_cndmask_b32_e64 v37, 0, v37, s[36:37]
	v_add_u32_e32 v86, 68, v84
	v_cmp_gt_u32_e64 s[36:37], s98, v86
	v_cndmask_b32_e64 v38, 0, v38, s[78:79]
	v_add_u32_e32 v87, 72, v84
	v_cmp_gt_u32_e64 s[78:79], s98, v87
	v_cndmask_b32_e64 v39, 0, v39, s[50:51]
	v_add_u32_e32 v88, 76, v84
	v_cmp_gt_u32_e64 s[50:51], s98, v88
	v_cndmask_b32_e64 v40, 0, v40, s[30:31]
	v_add_u32_e32 v85, 96, v84
	v_cmp_gt_u32_e64 s[30:31], s98, v85
	v_cndmask_b32_e64 v41, 0, v41, s[36:37]
	v_add_u32_e32 v86, 100, v84
	v_cmp_gt_u32_e64 s[36:37], s98, v86
	v_cndmask_b32_e64 v42, 0, v42, s[78:79]
	v_add_u32_e32 v87, 104, v84
	v_cmp_gt_u32_e64 s[78:79], s98, v87
	v_cndmask_b32_e64 v43, 0, v43, s[50:51]
	v_add_u32_e32 v88, 108, v84
	v_cmp_gt_u32_e64 s[50:51], s98, v88
	v_nop
	v_cndmask_b32_e64 v44, 0, v44, s[30:31]
	v_cndmask_b32_e64 v45, 0, v45, s[36:37]
	v_cndmask_b32_e64 v46, 0, v46, s[78:79]
	v_cndmask_b32_e64 v47, 0, v47, s[50:51]
	v_cvt_pk_bf16_f32 v64, v32, v33
	v_cvt_pk_bf16_f32 v65, v34, v35
	v_cvt_pk_bf16_f32 v66, v36, v37
	v_cvt_pk_bf16_f32 v67, v38, v39
	v_cvt_pk_bf16_f32 v68, v40, v41
	v_cvt_pk_bf16_f32 v69, v42, v43
	v_cvt_pk_bf16_f32 v70, v44, v45
	v_cvt_pk_bf16_f32 v71, v46, v47
	v_pk_add_f32 v[232:233], v[232:233], v[32:33]
	v_pk_add_f32 v[232:233], v[232:233], v[34:35]
	v_pk_add_f32 v[232:233], v[232:233], v[36:37]
	v_pk_add_f32 v[232:233], v[232:233], v[38:39]
	v_pk_add_f32 v[232:233], v[232:233], v[40:41]
	v_pk_add_f32 v[232:233], v[232:233], v[42:43]
	v_pk_add_f32 v[232:233], v[232:233], v[44:45]
	v_pk_add_f32 v[232:233], v[232:233], v[46:47]
	ds_read2_b32 v[32:33], v115 offset0:224 offset1:225
	ds_read2_b32 v[34:35], v115 offset0:226 offset1:227
	ds_read2_b32 v[36:37], v115 offset0:232 offset1:233
	ds_read2_b32 v[38:39], v115 offset0:234 offset1:235
	ds_read2_b32 v[40:41], v115 offset0:240 offset1:241
	ds_read2_b32 v[42:43], v115 offset0:242 offset1:243
	ds_read2_b32 v[44:45], v115 offset0:248 offset1:249
	ds_read2_b32 v[46:47], v115 offset0:250 offset1:251
	s_waitcnt lgkmcnt(15)
	v_mfma_f32_32x32x16_bf16 v[0:15], v[64:67], v[72:75], v[0:15]
	v_mfma_f32_32x32x16_bf16 v[16:31], v[64:67], v[76:79], v[16:31]
	v_mfma_f32_32x32x16_bf16 v[0:15], v[68:71], v[220:223], v[0:15]
	v_mfma_f32_32x32x16_bf16 v[16:31], v[68:71], v[224:227], v[16:31]
	s_add_i32 s90, s67, -512
	v_add_u32_e32 v80, s90, v243
	v_add_u32_e32 v83, s90, v244
	v_add_u32_e32 v99, s90, v245
	v_add_u32_e32 v253, s90, v246
	v_add_u32_e32 v254, s90, v148
	v_add_u32_e32 v255, s90, v151
	v_med3_i32 v80, v80, 0, s99
	v_med3_i32 v83, v83, 0, s99
	v_med3_i32 v99, v99, 0, s99
	v_med3_i32 v253, v253, 0, s99
	v_med3_i32 v254, v254, 0, s99
	v_med3_i32 v255, v255, 0, s99
	v_mad_u32_u24 v80, v80, s100, v252
	v_mad_u32_u24 v83, v83, s100, v252
	v_mad_u32_u24 v99, v99, s100, v252
	v_mad_u32_u24 v253, v253, s100, v252
	v_mad_u32_u24 v254, v254, s100, v153
	v_mad_u32_u24 v255, v255, s100, v153
	global_load_dwordx4 v[188:191], v80, s[82:83]
	global_load_dwordx4 v[192:195], v83, s[82:83]
	global_load_dwordx4 v[196:199], v99, s[82:83]
	global_load_dwordx4 v[200:203], v253, s[82:83]
	global_load_dwordx4 v[204:207], v254, s[82:83] offset:768
	global_load_dwordx4 v[208:211], v255, s[82:83] offset:768
	global_load_dwordx4 v[212:215], v254, s[82:83] offset:832
	global_load_dwordx4 v[216:219], v255, s[82:83] offset:832
	s_waitcnt lgkmcnt(0)
	v_mfma_f32_32x32x16_bf16 v[32:47], v[116:119], v[48:51], v[32:47]
	ds_read_b64_tr_b16 v[72:73], v231
	ds_read_b64_tr_b16 v[74:75], v231 offset:512
	ds_read_b64_tr_b16 v[76:77], v231 offset:2048
	ds_read_b64_tr_b16 v[78:79], v231 offset:2560
	ds_read_b64_tr_b16 v[220:221], v231 offset:1024
	ds_read_b64_tr_b16 v[222:223], v231 offset:1536
	ds_read_b64_tr_b16 v[224:225], v231 offset:3072
	ds_read_b64_tr_b16 v[226:227], v231 offset:3584
	s_waitcnt vmcnt(8)
	ds_write_b128 v247, v[156:159]
	ds_write_b128 v247, v[160:163] offset:1024
	ds_write_b128 v247, v[164:167] offset:2048
	ds_write_b128 v247, v[168:171] offset:3072
	ds_read_b128 v[156:159], v248
	ds_read_b128 v[160:163], v249
	ds_read_b128 v[164:167], v250
	ds_read_b128 v[168:171], v251
	ds_write_b128 v112, v[172:175]
	ds_write_b128 v112, v[176:179] offset:1024
	ds_write_b128 v112, v[180:183] offset:2048
	ds_write_b128 v112, v[184:187] offset:3072
	v_mfma_f32_32x32x16_bf16 v[32:47], v[120:123], v[52:55], v[32:47]
	v_mfma_f32_32x32x16_bf16 v[32:47], v[124:127], v[56:59], v[32:47]
	v_mfma_f32_32x32x16_bf16 v[32:47], v[128:131], v[60:63], v[32:47]
	s_nop 11
	v_exp_f32_e32 v32, v32
	v_exp_f32_e32 v33, v33
	v_exp_f32_e32 v34, v34
	v_exp_f32_e32 v35, v35
	v_exp_f32_e32 v36, v36
	v_exp_f32_e32 v37, v37
	v_exp_f32_e32 v38, v38
	v_exp_f32_e32 v39, v39
	v_exp_f32_e32 v40, v40
	v_exp_f32_e32 v41, v41
	v_exp_f32_e32 v42, v42
	v_exp_f32_e32 v43, v43
	v_exp_f32_e32 v44, v44
	v_exp_f32_e32 v45, v45
	v_exp_f32_e32 v46, v46
	v_exp_f32_e32 v47, v47
	s_add_i32 s90, s67, 640
	v_lshlrev_b32_e32 v84, 2, v107
	v_add_u32_e32 v84, s90, v84
	v_add_u32_e32 v85, 0, v84
	v_add_u32_e32 v86, 4, v84
	v_add_u32_e32 v87, 8, v84
	v_add_u32_e32 v88, 12, v84
	v_cmp_gt_u32_e64 s[30:31], s98, v85
	v_cmp_gt_u32_e64 s[36:37], s98, v86
	v_cmp_gt_u32_e64 s[78:79], s98, v87
	v_cmp_gt_u32_e64 s[50:51], s98, v88
	v_cndmask_b32_e64 v32, 0, v32, s[30:31]
	v_add_u32_e32 v85, 32, v84
	v_cmp_gt_u32_e64 s[30:31], s98, v85
	v_cndmask_b32_e64 v33, 0, v33, s[36:37]
	v_add_u32_e32 v86, 36, v84
	v_cmp_gt_u32_e64 s[36:37], s98, v86
	v_cndmask_b32_e64 v34, 0, v34, s[78:79]
	v_add_u32_e32 v87, 40, v84
	v_cmp_gt_u32_e64 s[78:79], s98, v87
	v_cndmask_b32_e64 v35, 0, v35, s[50:51]
	v_add_u32_e32 v88, 44, v84
	v_cmp_gt_u32_e64 s[50:51], s98, v88
	v_cndmask_b32_e64 v36, 0, v36, s[30:31]
	v_add_u32_e32 v85, 64, v84
	v_cmp_gt_u32_e64 s[30:31], s98, v85
	v_cndmask_b32_e64 v37, 0, v37, s[36:37]
	v_add_u32_e32 v86, 68, v84
	v_cmp_gt_u32_e64 s[36:37], s98, v86
	v_cndmask_b32_e64 v38, 0, v38, s[78:79]
	v_add_u32_e32 v87, 72, v84
	v_cmp_gt_u32_e64 s[78:79], s98, v87
	v_cndmask_b32_e64 v39, 0, v39, s[50:51]
	v_add_u32_e32 v88, 76, v84
	v_cmp_gt_u32_e64 s[50:51], s98, v88
	v_cndmask_b32_e64 v40, 0, v40, s[30:31]
	v_add_u32_e32 v85, 96, v84
	v_cmp_gt_u32_e64 s[30:31], s98, v85
	v_cndmask_b32_e64 v41, 0, v41, s[36:37]
	v_add_u32_e32 v86, 100, v84
	v_cmp_gt_u32_e64 s[36:37], s98, v86
	v_cndmask_b32_e64 v42, 0, v42, s[78:79]
	v_add_u32_e32 v87, 104, v84
	v_cmp_gt_u32_e64 s[78:79], s98, v87
	v_cndmask_b32_e64 v43, 0, v43, s[50:51]
	v_add_u32_e32 v88, 108, v84
	v_cmp_gt_u32_e64 s[50:51], s98, v88
	v_nop
	v_cndmask_b32_e64 v44, 0, v44, s[30:31]
	v_cndmask_b32_e64 v45, 0, v45, s[36:37]
	v_cndmask_b32_e64 v46, 0, v46, s[78:79]
	v_cndmask_b32_e64 v47, 0, v47, s[50:51]
	v_cvt_pk_bf16_f32 v64, v32, v33
	v_cvt_pk_bf16_f32 v65, v34, v35
	v_cvt_pk_bf16_f32 v66, v36, v37
	v_cvt_pk_bf16_f32 v67, v38, v39
	v_cvt_pk_bf16_f32 v68, v40, v41
	v_cvt_pk_bf16_f32 v69, v42, v43
	v_cvt_pk_bf16_f32 v70, v44, v45
	v_cvt_pk_bf16_f32 v71, v46, v47
	v_pk_add_f32 v[232:233], v[232:233], v[32:33]
	v_pk_add_f32 v[232:233], v[232:233], v[34:35]
	v_pk_add_f32 v[232:233], v[232:233], v[36:37]
	v_pk_add_f32 v[232:233], v[232:233], v[38:39]
	v_pk_add_f32 v[232:233], v[232:233], v[40:41]
	v_pk_add_f32 v[232:233], v[232:233], v[42:43]
	v_pk_add_f32 v[232:233], v[232:233], v[44:45]
	v_pk_add_f32 v[232:233], v[232:233], v[46:47]
	v_mov_b32_e32 v115, v230
	ds_read2_b32 v[32:33], v115 offset0:0 offset1:1
	ds_read2_b32 v[34:35], v115 offset0:2 offset1:3
	ds_read2_b32 v[36:37], v115 offset0:8 offset1:9
	ds_read2_b32 v[38:39], v115 offset0:10 offset1:11
	ds_read2_b32 v[40:41], v115 offset0:16 offset1:17
	ds_read2_b32 v[42:43], v115 offset0:18 offset1:19
	ds_read2_b32 v[44:45], v115 offset0:24 offset1:25
	ds_read2_b32 v[46:47], v115 offset0:26 offset1:27
	s_waitcnt lgkmcnt(15)
	v_mfma_f32_32x32x16_bf16 v[0:15], v[64:67], v[72:75], v[0:15]
	v_mfma_f32_32x32x16_bf16 v[16:31], v[64:67], v[76:79], v[16:31]
	v_mfma_f32_32x32x16_bf16 v[0:15], v[68:71], v[220:223], v[0:15]
	v_mfma_f32_32x32x16_bf16 v[16:31], v[68:71], v[224:227], v[16:31]
	s_add_i32 s90, s67, 0
	v_add_u32_e32 v80, s90, v243
	v_add_u32_e32 v83, s90, v244
	v_add_u32_e32 v99, s90, v245
	v_add_u32_e32 v253, s90, v246
	v_add_u32_e32 v254, s90, v148
	v_add_u32_e32 v255, s90, v151
	v_med3_i32 v80, v80, 0, s99
	v_med3_i32 v83, v83, 0, s99
	v_med3_i32 v99, v99, 0, s99
	v_med3_i32 v253, v253, 0, s99
	v_med3_i32 v254, v254, 0, s99
	v_med3_i32 v255, v255, 0, s99
	v_mad_u32_u24 v80, v80, s100, v252
	v_mad_u32_u24 v83, v83, s100, v252
	v_mad_u32_u24 v99, v99, s100, v252
	v_mad_u32_u24 v253, v253, s100, v252
	v_mad_u32_u24 v254, v254, s100, v153
	v_mad_u32_u24 v255, v255, s100, v153
	global_load_dwordx4 v[116:119], v80, s[82:83]
	global_load_dwordx4 v[120:123], v83, s[82:83]
	global_load_dwordx4 v[124:127], v99, s[82:83]
	global_load_dwordx4 v[128:131], v253, s[82:83]
	global_load_dwordx4 v[132:135], v254, s[82:83] offset:768
	global_load_dwordx4 v[136:139], v255, s[82:83] offset:768
	global_load_dwordx4 v[140:143], v254, s[82:83] offset:832
	global_load_dwordx4 v[144:147], v255, s[82:83] offset:832
	s_waitcnt lgkmcnt(0)
	v_mfma_f32_32x32x16_bf16 v[32:47], v[156:159], v[48:51], v[32:47]
	ds_read_b64_tr_b16 v[72:73], v231
	ds_read_b64_tr_b16 v[74:75], v231 offset:512
	ds_read_b64_tr_b16 v[76:77], v231 offset:2048
	ds_read_b64_tr_b16 v[78:79], v231 offset:2560
	ds_read_b64_tr_b16 v[220:221], v231 offset:1024
	ds_read_b64_tr_b16 v[222:223], v231 offset:1536
	ds_read_b64_tr_b16 v[224:225], v231 offset:3072
	ds_read_b64_tr_b16 v[226:227], v231 offset:3584
	s_waitcnt vmcnt(8)
	ds_write_b128 v247, v[188:191]
	ds_write_b128 v247, v[192:195] offset:1024
	ds_write_b128 v247, v[196:199] offset:2048
	ds_write_b128 v247, v[200:203] offset:3072
	ds_read_b128 v[188:191], v248
	ds_read_b128 v[192:195], v249
	ds_read_b128 v[196:199], v250
	ds_read_b128 v[200:203], v251
	ds_write_b128 v112, v[204:207]
	ds_write_b128 v112, v[208:211] offset:1024
	ds_write_b128 v112, v[212:215] offset:2048
	ds_write_b128 v112, v[216:219] offset:3072
	v_mfma_f32_32x32x16_bf16 v[32:47], v[160:163], v[52:55], v[32:47]
	v_mfma_f32_32x32x16_bf16 v[32:47], v[164:167], v[56:59], v[32:47]
	v_mfma_f32_32x32x16_bf16 v[32:47], v[168:171], v[60:63], v[32:47]
	s_nop 11
	v_exp_f32_e32 v32, v32
	v_exp_f32_e32 v33, v33
	v_exp_f32_e32 v34, v34
	v_exp_f32_e32 v35, v35
	v_exp_f32_e32 v36, v36
	v_exp_f32_e32 v37, v37
	v_exp_f32_e32 v38, v38
	v_exp_f32_e32 v39, v39
	v_exp_f32_e32 v40, v40
	v_exp_f32_e32 v41, v41
	v_exp_f32_e32 v42, v42
	v_exp_f32_e32 v43, v43
	v_exp_f32_e32 v44, v44
	v_exp_f32_e32 v45, v45
	v_exp_f32_e32 v46, v46
	v_exp_f32_e32 v47, v47
	s_add_i32 s90, s67, -1024
	v_lshlrev_b32_e32 v84, 4, v107
	v_add_u32_e32 v84, s90, v84
	v_add_u32_e32 v85, 0, v84
	v_add_u32_e32 v86, 16, v84
	v_add_u32_e32 v87, 32, v84
	v_add_u32_e32 v88, 48, v84
	v_cmp_gt_u32_e64 s[30:31], s98, v85
	v_cmp_gt_u32_e64 s[36:37], s98, v86
	v_cmp_gt_u32_e64 s[78:79], s98, v87
	v_cmp_gt_u32_e64 s[50:51], s98, v88
	v_cndmask_b32_e64 v32, 0, v32, s[30:31]
	v_add_u32_e32 v85, 128, v84
	v_cmp_gt_u32_e64 s[30:31], s98, v85
	v_cndmask_b32_e64 v33, 0, v33, s[36:37]
	v_add_u32_e32 v86, 144, v84
	v_cmp_gt_u32_e64 s[36:37], s98, v86
	v_cndmask_b32_e64 v34, 0, v34, s[78:79]
	v_add_u32_e32 v87, 160, v84
	v_cmp_gt_u32_e64 s[78:79], s98, v87
	v_cndmask_b32_e64 v35, 0, v35, s[50:51]
	v_add_u32_e32 v88, 176, v84
	v_cmp_gt_u32_e64 s[50:51], s98, v88
	v_cndmask_b32_e64 v36, 0, v36, s[30:31]
	v_add_u32_e32 v85, 256, v84
	v_cmp_gt_u32_e64 s[30:31], s98, v85
	v_cndmask_b32_e64 v37, 0, v37, s[36:37]
	v_add_u32_e32 v86, 272, v84
	v_cmp_gt_u32_e64 s[36:37], s98, v86
	v_cndmask_b32_e64 v38, 0, v38, s[78:79]
	v_add_u32_e32 v87, 288, v84
	v_cmp_gt_u32_e64 s[78:79], s98, v87
	v_cndmask_b32_e64 v39, 0, v39, s[50:51]
	v_add_u32_e32 v88, 304, v84
	v_cmp_gt_u32_e64 s[50:51], s98, v88
	v_cndmask_b32_e64 v40, 0, v40, s[30:31]
	v_add_u32_e32 v85, 384, v84
	v_cmp_gt_u32_e64 s[30:31], s98, v85
	v_cndmask_b32_e64 v41, 0, v41, s[36:37]
	v_add_u32_e32 v86, 400, v84
	v_cmp_gt_u32_e64 s[36:37], s98, v86
	v_cndmask_b32_e64 v42, 0, v42, s[78:79]
	v_add_u32_e32 v87, 416, v84
	v_cmp_gt_u32_e64 s[78:79], s98, v87
	v_cndmask_b32_e64 v43, 0, v43, s[50:51]
	v_add_u32_e32 v88, 432, v84
	v_cmp_gt_u32_e64 s[50:51], s98, v88
	v_nop
	v_cndmask_b32_e64 v44, 0, v44, s[30:31]
	v_cndmask_b32_e64 v45, 0, v45, s[36:37]
	v_cndmask_b32_e64 v46, 0, v46, s[78:79]
	v_cndmask_b32_e64 v47, 0, v47, s[50:51]
	v_cvt_pk_bf16_f32 v64, v32, v33
	v_cvt_pk_bf16_f32 v65, v34, v35
	v_cvt_pk_bf16_f32 v66, v36, v37
	v_cvt_pk_bf16_f32 v67, v38, v39
	v_cvt_pk_bf16_f32 v68, v40, v41
	v_cvt_pk_bf16_f32 v69, v42, v43
	v_cvt_pk_bf16_f32 v70, v44, v45
	v_cvt_pk_bf16_f32 v71, v46, v47
	v_pk_add_f32 v[232:233], v[232:233], v[32:33]
	v_pk_add_f32 v[232:233], v[232:233], v[34:35]
	v_pk_add_f32 v[232:233], v[232:233], v[36:37]
	v_pk_add_f32 v[232:233], v[232:233], v[38:39]
	v_pk_add_f32 v[232:233], v[232:233], v[40:41]
	v_pk_add_f32 v[232:233], v[232:233], v[42:43]
	v_pk_add_f32 v[232:233], v[232:233], v[44:45]
	v_pk_add_f32 v[232:233], v[232:233], v[46:47]
	ds_read2_b32 v[32:33], v115 offset0:32 offset1:33
	ds_read2_b32 v[34:35], v115 offset0:34 offset1:35
	ds_read2_b32 v[36:37], v115 offset0:40 offset1:41
	ds_read2_b32 v[38:39], v115 offset0:42 offset1:43
	ds_read2_b32 v[40:41], v115 offset0:48 offset1:49
	ds_read2_b32 v[42:43], v115 offset0:50 offset1:51
	ds_read2_b32 v[44:45], v115 offset0:56 offset1:57
	ds_read2_b32 v[46:47], v115 offset0:58 offset1:59
	s_waitcnt lgkmcnt(15)
	v_mfma_f32_32x32x16_bf16 v[0:15], v[64:67], v[72:75], v[0:15]
	v_mfma_f32_32x32x16_bf16 v[16:31], v[64:67], v[76:79], v[16:31]
	v_mfma_f32_32x32x16_bf16 v[0:15], v[68:71], v[220:223], v[0:15]
	v_mfma_f32_32x32x16_bf16 v[16:31], v[68:71], v[224:227], v[16:31]
	s_add_i32 s90, s67, 512
	v_add_u32_e32 v80, s90, v243
	v_add_u32_e32 v83, s90, v244
	v_add_u32_e32 v99, s90, v245
	v_add_u32_e32 v253, s90, v246
	v_add_u32_e32 v254, s90, v148
	v_add_u32_e32 v255, s90, v151
	v_med3_i32 v80, v80, 0, s99
	v_med3_i32 v83, v83, 0, s99
	v_med3_i32 v99, v99, 0, s99
	v_med3_i32 v253, v253, 0, s99
	v_med3_i32 v254, v254, 0, s99
	v_med3_i32 v255, v255, 0, s99
	v_mad_u32_u24 v80, v80, s100, v252
	v_mad_u32_u24 v83, v83, s100, v252
	v_mad_u32_u24 v99, v99, s100, v252
	v_mad_u32_u24 v253, v253, s100, v252
	v_mad_u32_u24 v254, v254, s100, v153
	v_mad_u32_u24 v255, v255, s100, v153
	global_load_dwordx4 v[156:159], v80, s[82:83]
	global_load_dwordx4 v[160:163], v83, s[82:83]
	global_load_dwordx4 v[164:167], v99, s[82:83]
	global_load_dwordx4 v[168:171], v253, s[82:83]
	global_load_dwordx4 v[172:175], v254, s[82:83] offset:768
	global_load_dwordx4 v[176:179], v255, s[82:83] offset:768
	global_load_dwordx4 v[180:183], v254, s[82:83] offset:832
	global_load_dwordx4 v[184:187], v255, s[82:83] offset:832
	s_waitcnt lgkmcnt(0)
	v_mfma_f32_32x32x16_bf16 v[32:47], v[188:191], v[48:51], v[32:47]
	ds_read_b64_tr_b16 v[72:73], v231
	ds_read_b64_tr_b16 v[74:75], v231 offset:512
	ds_read_b64_tr_b16 v[76:77], v231 offset:2048
	ds_read_b64_tr_b16 v[78:79], v231 offset:2560
	ds_read_b64_tr_b16 v[220:221], v231 offset:1024
	ds_read_b64_tr_b16 v[222:223], v231 offset:1536
	ds_read_b64_tr_b16 v[224:225], v231 offset:3072
	ds_read_b64_tr_b16 v[226:227], v231 offset:3584
	s_waitcnt vmcnt(8)
	ds_write_b128 v247, v[116:119]
	ds_write_b128 v247, v[120:123] offset:1024
	ds_write_b128 v247, v[124:127] offset:2048
	ds_write_b128 v247, v[128:131] offset:3072
	ds_read_b128 v[116:119], v248
	ds_read_b128 v[120:123], v249
	ds_read_b128 v[124:127], v250
	ds_read_b128 v[128:131], v251
	ds_write_b128 v112, v[132:135]
	ds_write_b128 v112, v[136:139] offset:1024
	ds_write_b128 v112, v[140:143] offset:2048
	ds_write_b128 v112, v[144:147] offset:3072
	v_mfma_f32_32x32x16_bf16 v[32:47], v[192:195], v[52:55], v[32:47]
	v_mfma_f32_32x32x16_bf16 v[32:47], v[196:199], v[56:59], v[32:47]
	v_mfma_f32_32x32x16_bf16 v[32:47], v[200:203], v[60:63], v[32:47]
	s_nop 11
	v_exp_f32_e32 v32, v32
	v_exp_f32_e32 v33, v33
	v_exp_f32_e32 v34, v34
	v_exp_f32_e32 v35, v35
	v_exp_f32_e32 v36, v36
	v_exp_f32_e32 v37, v37
	v_exp_f32_e32 v38, v38
	v_exp_f32_e32 v39, v39
	v_exp_f32_e32 v40, v40
	v_exp_f32_e32 v41, v41
	v_exp_f32_e32 v42, v42
	v_exp_f32_e32 v43, v43
	v_exp_f32_e32 v44, v44
	v_exp_f32_e32 v45, v45
	v_exp_f32_e32 v46, v46
	v_exp_f32_e32 v47, v47
	s_add_i32 s90, s67, -512
	v_lshlrev_b32_e32 v84, 4, v107
	v_add_u32_e32 v84, s90, v84
	v_add_u32_e32 v85, 0, v84
	v_add_u32_e32 v86, 16, v84
	v_add_u32_e32 v87, 32, v84
	v_add_u32_e32 v88, 48, v84
	v_cmp_gt_u32_e64 s[30:31], s98, v85
	v_cmp_gt_u32_e64 s[36:37], s98, v86
	v_cmp_gt_u32_e64 s[78:79], s98, v87
	v_cmp_gt_u32_e64 s[50:51], s98, v88
	v_cndmask_b32_e64 v32, 0, v32, s[30:31]
	v_add_u32_e32 v85, 128, v84
	v_cmp_gt_u32_e64 s[30:31], s98, v85
	v_cndmask_b32_e64 v33, 0, v33, s[36:37]
	v_add_u32_e32 v86, 144, v84
	v_cmp_gt_u32_e64 s[36:37], s98, v86
	v_cndmask_b32_e64 v34, 0, v34, s[78:79]
	v_add_u32_e32 v87, 160, v84
	v_cmp_gt_u32_e64 s[78:79], s98, v87
	v_cndmask_b32_e64 v35, 0, v35, s[50:51]
	v_add_u32_e32 v88, 176, v84
	v_cmp_gt_u32_e64 s[50:51], s98, v88
	v_cndmask_b32_e64 v36, 0, v36, s[30:31]
	v_add_u32_e32 v85, 256, v84
	v_cmp_gt_u32_e64 s[30:31], s98, v85
	v_cndmask_b32_e64 v37, 0, v37, s[36:37]
	v_add_u32_e32 v86, 272, v84
	v_cmp_gt_u32_e64 s[36:37], s98, v86
	v_cndmask_b32_e64 v38, 0, v38, s[78:79]
	v_add_u32_e32 v87, 288, v84
	v_cmp_gt_u32_e64 s[78:79], s98, v87
	v_cndmask_b32_e64 v39, 0, v39, s[50:51]
	v_add_u32_e32 v88, 304, v84
	v_cmp_gt_u32_e64 s[50:51], s98, v88
	v_cndmask_b32_e64 v40, 0, v40, s[30:31]
	v_add_u32_e32 v85, 384, v84
	v_cmp_gt_u32_e64 s[30:31], s98, v85
	v_cndmask_b32_e64 v41, 0, v41, s[36:37]
	v_add_u32_e32 v86, 400, v84
	v_cmp_gt_u32_e64 s[36:37], s98, v86
	v_cndmask_b32_e64 v42, 0, v42, s[78:79]
	v_add_u32_e32 v87, 416, v84
	v_cmp_gt_u32_e64 s[78:79], s98, v87
	v_cndmask_b32_e64 v43, 0, v43, s[50:51]
	v_add_u32_e32 v88, 432, v84
	v_cmp_gt_u32_e64 s[50:51], s98, v88
	v_nop
	v_cndmask_b32_e64 v44, 0, v44, s[30:31]
	v_cndmask_b32_e64 v45, 0, v45, s[36:37]
	v_cndmask_b32_e64 v46, 0, v46, s[78:79]
	v_cndmask_b32_e64 v47, 0, v47, s[50:51]
	v_cvt_pk_bf16_f32 v64, v32, v33
	v_cvt_pk_bf16_f32 v65, v34, v35
	v_cvt_pk_bf16_f32 v66, v36, v37
	v_cvt_pk_bf16_f32 v67, v38, v39
	v_cvt_pk_bf16_f32 v68, v40, v41
	v_cvt_pk_bf16_f32 v69, v42, v43
	v_cvt_pk_bf16_f32 v70, v44, v45
	v_cvt_pk_bf16_f32 v71, v46, v47
	v_pk_add_f32 v[232:233], v[232:233], v[32:33]
	v_pk_add_f32 v[232:233], v[232:233], v[34:35]
	v_pk_add_f32 v[232:233], v[232:233], v[36:37]
	v_pk_add_f32 v[232:233], v[232:233], v[38:39]
	v_pk_add_f32 v[232:233], v[232:233], v[40:41]
	v_pk_add_f32 v[232:233], v[232:233], v[42:43]
	v_pk_add_f32 v[232:233], v[232:233], v[44:45]
	v_pk_add_f32 v[232:233], v[232:233], v[46:47]
	ds_read2_b32 v[32:33], v115 offset0:64 offset1:65
	ds_read2_b32 v[34:35], v115 offset0:66 offset1:67
	ds_read2_b32 v[36:37], v115 offset0:72 offset1:73
	ds_read2_b32 v[38:39], v115 offset0:74 offset1:75
	ds_read2_b32 v[40:41], v115 offset0:80 offset1:81
	ds_read2_b32 v[42:43], v115 offset0:82 offset1:83
	ds_read2_b32 v[44:45], v115 offset0:88 offset1:89
	ds_read2_b32 v[46:47], v115 offset0:90 offset1:91
	s_waitcnt lgkmcnt(15)
	v_mfma_f32_32x32x16_bf16 v[0:15], v[64:67], v[72:75], v[0:15]
	v_mfma_f32_32x32x16_bf16 v[16:31], v[64:67], v[76:79], v[16:31]
	v_mfma_f32_32x32x16_bf16 v[0:15], v[68:71], v[220:223], v[0:15]
	v_mfma_f32_32x32x16_bf16 v[16:31], v[68:71], v[224:227], v[16:31]
	s_add_i32 s90, s67, 1024
	v_add_u32_e32 v80, s90, v243
	v_add_u32_e32 v83, s90, v244
	v_add_u32_e32 v99, s90, v245
	v_add_u32_e32 v253, s90, v246
	v_add_u32_e32 v254, s90, v148
	v_add_u32_e32 v255, s90, v151
	v_med3_i32 v80, v80, 0, s99
	v_med3_i32 v83, v83, 0, s99
	v_med3_i32 v99, v99, 0, s99
	v_med3_i32 v253, v253, 0, s99
	v_med3_i32 v254, v254, 0, s99
	v_med3_i32 v255, v255, 0, s99
	v_mad_u32_u24 v80, v80, s100, v252
	v_mad_u32_u24 v83, v83, s100, v252
	v_mad_u32_u24 v99, v99, s100, v252
	v_mad_u32_u24 v253, v253, s100, v252
	v_mad_u32_u24 v254, v254, s100, v153
	v_mad_u32_u24 v255, v255, s100, v153
	global_load_dwordx4 v[188:191], v80, s[82:83]
	global_load_dwordx4 v[192:195], v83, s[82:83]
	global_load_dwordx4 v[196:199], v99, s[82:83]
	global_load_dwordx4 v[200:203], v253, s[82:83]
	global_load_dwordx4 v[204:207], v254, s[82:83] offset:768
	global_load_dwordx4 v[208:211], v255, s[82:83] offset:768
	global_load_dwordx4 v[212:215], v254, s[82:83] offset:832
	global_load_dwordx4 v[216:219], v255, s[82:83] offset:832
	s_waitcnt lgkmcnt(0)
	v_mfma_f32_32x32x16_bf16 v[32:47], v[116:119], v[48:51], v[32:47]
	ds_read_b64_tr_b16 v[72:73], v231
	ds_read_b64_tr_b16 v[74:75], v231 offset:512
	ds_read_b64_tr_b16 v[76:77], v231 offset:2048
	ds_read_b64_tr_b16 v[78:79], v231 offset:2560
	ds_read_b64_tr_b16 v[220:221], v231 offset:1024
	ds_read_b64_tr_b16 v[222:223], v231 offset:1536
	ds_read_b64_tr_b16 v[224:225], v231 offset:3072
	ds_read_b64_tr_b16 v[226:227], v231 offset:3584
	s_waitcnt vmcnt(8)
	ds_write_b128 v247, v[156:159]
	ds_write_b128 v247, v[160:163] offset:1024
	ds_write_b128 v247, v[164:167] offset:2048
	ds_write_b128 v247, v[168:171] offset:3072
	ds_read_b128 v[156:159], v248
	ds_read_b128 v[160:163], v249
	ds_read_b128 v[164:167], v250
	ds_read_b128 v[168:171], v251
	ds_write_b128 v112, v[172:175]
	ds_write_b128 v112, v[176:179] offset:1024
	ds_write_b128 v112, v[180:183] offset:2048
	ds_write_b128 v112, v[184:187] offset:3072
	v_mfma_f32_32x32x16_bf16 v[32:47], v[120:123], v[52:55], v[32:47]
	v_mfma_f32_32x32x16_bf16 v[32:47], v[124:127], v[56:59], v[32:47]
	v_mfma_f32_32x32x16_bf16 v[32:47], v[128:131], v[60:63], v[32:47]
	s_nop 11
	v_exp_f32_e32 v32, v32
	v_exp_f32_e32 v33, v33
	v_exp_f32_e32 v34, v34
	v_exp_f32_e32 v35, v35
	v_exp_f32_e32 v36, v36
	v_exp_f32_e32 v37, v37
	v_exp_f32_e32 v38, v38
	v_exp_f32_e32 v39, v39
	v_exp_f32_e32 v40, v40
	v_exp_f32_e32 v41, v41
	v_exp_f32_e32 v42, v42
	v_exp_f32_e32 v43, v43
	v_exp_f32_e32 v44, v44
	v_exp_f32_e32 v45, v45
	v_exp_f32_e32 v46, v46
	v_exp_f32_e32 v47, v47
	s_add_i32 s90, s67, 0
	v_lshlrev_b32_e32 v84, 4, v107
	v_add_u32_e32 v84, s90, v84
	v_add_u32_e32 v85, 0, v84
	v_add_u32_e32 v86, 16, v84
	v_add_u32_e32 v87, 32, v84
	v_add_u32_e32 v88, 48, v84
	v_cmp_gt_u32_e64 s[30:31], s98, v85
	v_cmp_gt_u32_e64 s[36:37], s98, v86
	v_cmp_gt_u32_e64 s[78:79], s98, v87
	v_cmp_gt_u32_e64 s[50:51], s98, v88
	v_cndmask_b32_e64 v32, 0, v32, s[30:31]
	v_add_u32_e32 v85, 128, v84
	v_cmp_gt_u32_e64 s[30:31], s98, v85
	v_cndmask_b32_e64 v33, 0, v33, s[36:37]
	v_add_u32_e32 v86, 144, v84
	v_cmp_gt_u32_e64 s[36:37], s98, v86
	v_cndmask_b32_e64 v34, 0, v34, s[78:79]
	v_add_u32_e32 v87, 160, v84
	v_cmp_gt_u32_e64 s[78:79], s98, v87
	v_cndmask_b32_e64 v35, 0, v35, s[50:51]
	v_add_u32_e32 v88, 176, v84
	v_cmp_gt_u32_e64 s[50:51], s98, v88
	v_cndmask_b32_e64 v36, 0, v36, s[30:31]
	v_add_u32_e32 v85, 256, v84
	v_cmp_gt_u32_e64 s[30:31], s98, v85
	v_cndmask_b32_e64 v37, 0, v37, s[36:37]
	v_add_u32_e32 v86, 272, v84
	v_cmp_gt_u32_e64 s[36:37], s98, v86
	v_cndmask_b32_e64 v38, 0, v38, s[78:79]
	v_add_u32_e32 v87, 288, v84
	v_cmp_gt_u32_e64 s[78:79], s98, v87
	v_cndmask_b32_e64 v39, 0, v39, s[50:51]
	v_add_u32_e32 v88, 304, v84
	v_cmp_gt_u32_e64 s[50:51], s98, v88
	v_cndmask_b32_e64 v40, 0, v40, s[30:31]
	v_add_u32_e32 v85, 384, v84
	v_cmp_gt_u32_e64 s[30:31], s98, v85
	v_cndmask_b32_e64 v41, 0, v41, s[36:37]
	v_add_u32_e32 v86, 400, v84
	v_cmp_gt_u32_e64 s[36:37], s98, v86
	v_cndmask_b32_e64 v42, 0, v42, s[78:79]
	v_add_u32_e32 v87, 416, v84
	v_cmp_gt_u32_e64 s[78:79], s98, v87
	v_cndmask_b32_e64 v43, 0, v43, s[50:51]
	v_add_u32_e32 v88, 432, v84
	v_cmp_gt_u32_e64 s[50:51], s98, v88
	v_nop
	v_cndmask_b32_e64 v44, 0, v44, s[30:31]
	v_cndmask_b32_e64 v45, 0, v45, s[36:37]
	v_cndmask_b32_e64 v46, 0, v46, s[78:79]
	v_cndmask_b32_e64 v47, 0, v47, s[50:51]
	v_cvt_pk_bf16_f32 v64, v32, v33
	v_cvt_pk_bf16_f32 v65, v34, v35
	v_cvt_pk_bf16_f32 v66, v36, v37
	v_cvt_pk_bf16_f32 v67, v38, v39
	v_cvt_pk_bf16_f32 v68, v40, v41
	v_cvt_pk_bf16_f32 v69, v42, v43
	v_cvt_pk_bf16_f32 v70, v44, v45
	v_cvt_pk_bf16_f32 v71, v46, v47
	v_pk_add_f32 v[232:233], v[232:233], v[32:33]
	v_pk_add_f32 v[232:233], v[232:233], v[34:35]
	v_pk_add_f32 v[232:233], v[232:233], v[36:37]
	v_pk_add_f32 v[232:233], v[232:233], v[38:39]
	v_pk_add_f32 v[232:233], v[232:233], v[40:41]
	v_pk_add_f32 v[232:233], v[232:233], v[42:43]
	v_pk_add_f32 v[232:233], v[232:233], v[44:45]
	v_pk_add_f32 v[232:233], v[232:233], v[46:47]
	ds_read2_b32 v[32:33], v115 offset0:96 offset1:97
	ds_read2_b32 v[34:35], v115 offset0:98 offset1:99
	ds_read2_b32 v[36:37], v115 offset0:104 offset1:105
	ds_read2_b32 v[38:39], v115 offset0:106 offset1:107
	ds_read2_b32 v[40:41], v115 offset0:112 offset1:113
	ds_read2_b32 v[42:43], v115 offset0:114 offset1:115
	ds_read2_b32 v[44:45], v115 offset0:120 offset1:121
	ds_read2_b32 v[46:47], v115 offset0:122 offset1:123
	s_waitcnt lgkmcnt(15)
	v_mfma_f32_32x32x16_bf16 v[0:15], v[64:67], v[72:75], v[0:15]
	v_mfma_f32_32x32x16_bf16 v[16:31], v[64:67], v[76:79], v[16:31]
	v_mfma_f32_32x32x16_bf16 v[0:15], v[68:71], v[220:223], v[0:15]
	v_mfma_f32_32x32x16_bf16 v[16:31], v[68:71], v[224:227], v[16:31]
	s_waitcnt lgkmcnt(0)
	v_mfma_f32_32x32x16_bf16 v[32:47], v[156:159], v[48:51], v[32:47]
	ds_read_b64_tr_b16 v[72:73], v231
	ds_read_b64_tr_b16 v[74:75], v231 offset:512
	ds_read_b64_tr_b16 v[76:77], v231 offset:2048
	ds_read_b64_tr_b16 v[78:79], v231 offset:2560
	ds_read_b64_tr_b16 v[220:221], v231 offset:1024
	ds_read_b64_tr_b16 v[222:223], v231 offset:1536
	ds_read_b64_tr_b16 v[224:225], v231 offset:3072
	ds_read_b64_tr_b16 v[226:227], v231 offset:3584
	s_waitcnt vmcnt(0)
	ds_write_b128 v247, v[188:191]
	ds_write_b128 v247, v[192:195] offset:1024
	ds_write_b128 v247, v[196:199] offset:2048
	ds_write_b128 v247, v[200:203] offset:3072
	ds_read_b128 v[188:191], v248
	ds_read_b128 v[192:195], v249
	ds_read_b128 v[196:199], v250
	ds_read_b128 v[200:203], v251
	ds_write_b128 v112, v[204:207]
	ds_write_b128 v112, v[208:211] offset:1024
	ds_write_b128 v112, v[212:215] offset:2048
	ds_write_b128 v112, v[216:219] offset:3072
	v_mfma_f32_32x32x16_bf16 v[32:47], v[160:163], v[52:55], v[32:47]
	v_mfma_f32_32x32x16_bf16 v[32:47], v[164:167], v[56:59], v[32:47]
	v_mfma_f32_32x32x16_bf16 v[32:47], v[168:171], v[60:63], v[32:47]
	s_nop 11
	v_exp_f32_e32 v32, v32
	v_exp_f32_e32 v33, v33
	v_exp_f32_e32 v34, v34
	v_exp_f32_e32 v35, v35
	v_exp_f32_e32 v36, v36
	v_exp_f32_e32 v37, v37
	v_exp_f32_e32 v38, v38
	v_exp_f32_e32 v39, v39
	v_exp_f32_e32 v40, v40
	v_exp_f32_e32 v41, v41
	v_exp_f32_e32 v42, v42
	v_exp_f32_e32 v43, v43
	v_exp_f32_e32 v44, v44
	v_exp_f32_e32 v45, v45
	v_exp_f32_e32 v46, v46
	v_exp_f32_e32 v47, v47
	s_add_i32 s90, s67, 512
	v_lshlrev_b32_e32 v84, 4, v107
	v_add_u32_e32 v84, s90, v84
	v_add_u32_e32 v85, 0, v84
	v_add_u32_e32 v86, 16, v84
	v_add_u32_e32 v87, 32, v84
	v_add_u32_e32 v88, 48, v84
	v_cmp_gt_u32_e64 s[30:31], s98, v85
	v_cmp_gt_u32_e64 s[36:37], s98, v86
	v_cmp_gt_u32_e64 s[78:79], s98, v87
	v_cmp_gt_u32_e64 s[50:51], s98, v88
	v_cndmask_b32_e64 v32, 0, v32, s[30:31]
	v_add_u32_e32 v85, 128, v84
	v_cmp_gt_u32_e64 s[30:31], s98, v85
	v_cndmask_b32_e64 v33, 0, v33, s[36:37]
	v_add_u32_e32 v86, 144, v84
	v_cmp_gt_u32_e64 s[36:37], s98, v86
	v_cndmask_b32_e64 v34, 0, v34, s[78:79]
	v_add_u32_e32 v87, 160, v84
	v_cmp_gt_u32_e64 s[78:79], s98, v87
	v_cndmask_b32_e64 v35, 0, v35, s[50:51]
	v_add_u32_e32 v88, 176, v84
	v_cmp_gt_u32_e64 s[50:51], s98, v88
	v_cndmask_b32_e64 v36, 0, v36, s[30:31]
	v_add_u32_e32 v85, 256, v84
	v_cmp_gt_u32_e64 s[30:31], s98, v85
	v_cndmask_b32_e64 v37, 0, v37, s[36:37]
	v_add_u32_e32 v86, 272, v84
	v_cmp_gt_u32_e64 s[36:37], s98, v86
	v_cndmask_b32_e64 v38, 0, v38, s[78:79]
	v_add_u32_e32 v87, 288, v84
	v_cmp_gt_u32_e64 s[78:79], s98, v87
	v_cndmask_b32_e64 v39, 0, v39, s[50:51]
	v_add_u32_e32 v88, 304, v84
	v_cmp_gt_u32_e64 s[50:51], s98, v88
	v_cndmask_b32_e64 v40, 0, v40, s[30:31]
	v_add_u32_e32 v85, 384, v84
	v_cmp_gt_u32_e64 s[30:31], s98, v85
	v_cndmask_b32_e64 v41, 0, v41, s[36:37]
	v_add_u32_e32 v86, 400, v84
	v_cmp_gt_u32_e64 s[36:37], s98, v86
	v_cndmask_b32_e64 v42, 0, v42, s[78:79]
	v_add_u32_e32 v87, 416, v84
	v_cmp_gt_u32_e64 s[78:79], s98, v87
	v_cndmask_b32_e64 v43, 0, v43, s[50:51]
	v_add_u32_e32 v88, 432, v84
	v_cmp_gt_u32_e64 s[50:51], s98, v88
	v_nop
	v_cndmask_b32_e64 v44, 0, v44, s[30:31]
	v_cndmask_b32_e64 v45, 0, v45, s[36:37]
	v_cndmask_b32_e64 v46, 0, v46, s[78:79]
	v_cndmask_b32_e64 v47, 0, v47, s[50:51]
	v_cvt_pk_bf16_f32 v64, v32, v33
	v_cvt_pk_bf16_f32 v65, v34, v35
	v_cvt_pk_bf16_f32 v66, v36, v37
	v_cvt_pk_bf16_f32 v67, v38, v39
	v_cvt_pk_bf16_f32 v68, v40, v41
	v_cvt_pk_bf16_f32 v69, v42, v43
	v_cvt_pk_bf16_f32 v70, v44, v45
	v_cvt_pk_bf16_f32 v71, v46, v47
	v_pk_add_f32 v[232:233], v[232:233], v[32:33]
	v_pk_add_f32 v[232:233], v[232:233], v[34:35]
	v_pk_add_f32 v[232:233], v[232:233], v[36:37]
	v_pk_add_f32 v[232:233], v[232:233], v[38:39]
	v_pk_add_f32 v[232:233], v[232:233], v[40:41]
	v_pk_add_f32 v[232:233], v[232:233], v[42:43]
	v_pk_add_f32 v[232:233], v[232:233], v[44:45]
	v_pk_add_f32 v[232:233], v[232:233], v[46:47]
	ds_read2_b32 v[32:33], v115 offset0:128 offset1:129
	ds_read2_b32 v[34:35], v115 offset0:130 offset1:131
	ds_read2_b32 v[36:37], v115 offset0:136 offset1:137
	ds_read2_b32 v[38:39], v115 offset0:138 offset1:139
	ds_read2_b32 v[40:41], v115 offset0:144 offset1:145
	ds_read2_b32 v[42:43], v115 offset0:146 offset1:147
	ds_read2_b32 v[44:45], v115 offset0:152 offset1:153
	ds_read2_b32 v[46:47], v115 offset0:154 offset1:155
	s_waitcnt lgkmcnt(15)
; __device__ __forceinline__ int crow(int r, int hi) { return (r & 3) + 8 * (r >> 2) + 4 * hi; }
; __device__ __forceinline__ void dil_unit(LAS unsigned char* lds, bf16_t* proj, int seq, int hd, int T0, int rho) {
;     ...
;     l += __shfl_xor(l, 32);
; #pragma unroll
;     for (int rr = 0; rr < 16; ++rr) {
;         const int j = crow(rr, hi);
;         const float il = __builtin_amdgcn_rcpf(__shfl(l, j));
	v_mfma_f32_32x32x16_bf16 v[0:15], v[64:67], v[72:75], v[0:15]
	v_mfma_f32_32x32x16_bf16 v[16:31], v[64:67], v[76:79], v[16:31]
	v_mfma_f32_32x32x16_bf16 v[0:15], v[68:71], v[220:223], v[0:15]
	v_mfma_f32_32x32x16_bf16 v[16:31], v[68:71], v[224:227], v[16:31]
	s_waitcnt lgkmcnt(0)
	v_mfma_f32_32x32x16_bf16 v[32:47], v[188:191], v[48:51], v[32:47]
	ds_read_b64_tr_b16 v[72:73], v231
	ds_read_b64_tr_b16 v[74:75], v231 offset:512
	ds_read_b64_tr_b16 v[76:77], v231 offset:2048
	ds_read_b64_tr_b16 v[78:79], v231 offset:2560
	ds_read_b64_tr_b16 v[220:221], v231 offset:1024
	ds_read_b64_tr_b16 v[222:223], v231 offset:1536
	ds_read_b64_tr_b16 v[224:225], v231 offset:3072
	ds_read_b64_tr_b16 v[226:227], v231 offset:3584
	v_mfma_f32_32x32x16_bf16 v[32:47], v[192:195], v[52:55], v[32:47]
	v_mfma_f32_32x32x16_bf16 v[32:47], v[196:199], v[56:59], v[32:47]
	v_mfma_f32_32x32x16_bf16 v[32:47], v[200:203], v[60:63], v[32:47]
	s_nop 11
	v_exp_f32_e32 v32, v32
	v_exp_f32_e32 v33, v33
	v_exp_f32_e32 v34, v34
	v_exp_f32_e32 v35, v35
	v_exp_f32_e32 v36, v36
	v_exp_f32_e32 v37, v37
	v_exp_f32_e32 v38, v38
	v_exp_f32_e32 v39, v39
	v_exp_f32_e32 v40, v40
	v_exp_f32_e32 v41, v41
	v_exp_f32_e32 v42, v42
	v_exp_f32_e32 v43, v43
	v_exp_f32_e32 v44, v44
	v_exp_f32_e32 v45, v45
	v_exp_f32_e32 v46, v46
	v_exp_f32_e32 v47, v47
	s_add_i32 s90, s67, 1024
	v_lshlrev_b32_e32 v84, 4, v107
	v_add_u32_e32 v84, s90, v84
	v_add_u32_e32 v85, 0, v84
	v_add_u32_e32 v86, 16, v84
	v_add_u32_e32 v87, 32, v84
	v_add_u32_e32 v88, 48, v84
	v_cmp_gt_u32_e64 s[30:31], s98, v85
	v_cmp_gt_u32_e64 s[36:37], s98, v86
	v_cmp_gt_u32_e64 s[78:79], s98, v87
	v_cmp_gt_u32_e64 s[50:51], s98, v88
	v_cndmask_b32_e64 v32, 0, v32, s[30:31]
	v_add_u32_e32 v85, 128, v84
	v_cmp_gt_u32_e64 s[30:31], s98, v85
	v_cndmask_b32_e64 v33, 0, v33, s[36:37]
	v_add_u32_e32 v86, 144, v84
	v_cmp_gt_u32_e64 s[36:37], s98, v86
	v_cndmask_b32_e64 v34, 0, v34, s[78:79]
	v_add_u32_e32 v87, 160, v84
	v_cmp_gt_u32_e64 s[78:79], s98, v87
	v_cndmask_b32_e64 v35, 0, v35, s[50:51]
	v_add_u32_e32 v88, 176, v84
	v_cmp_gt_u32_e64 s[50:51], s98, v88
	v_cndmask_b32_e64 v36, 0, v36, s[30:31]
	v_add_u32_e32 v85, 256, v84
	v_cmp_gt_u32_e64 s[30:31], s98, v85
	v_cndmask_b32_e64 v37, 0, v37, s[36:37]
	v_add_u32_e32 v86, 272, v84
	v_cmp_gt_u32_e64 s[36:37], s98, v86
	v_cndmask_b32_e64 v38, 0, v38, s[78:79]
	v_add_u32_e32 v87, 288, v84
	v_cmp_gt_u32_e64 s[78:79], s98, v87
	v_cndmask_b32_e64 v39, 0, v39, s[50:51]
	v_add_u32_e32 v88, 304, v84
	v_cmp_gt_u32_e64 s[50:51], s98, v88
	v_cndmask_b32_e64 v40, 0, v40, s[30:31]
	v_add_u32_e32 v85, 384, v84
	v_cmp_gt_u32_e64 s[30:31], s98, v85
	v_cndmask_b32_e64 v41, 0, v41, s[36:37]
	v_add_u32_e32 v86, 400, v84
	v_cmp_gt_u32_e64 s[36:37], s98, v86
	v_cndmask_b32_e64 v42, 0, v42, s[78:79]
	v_add_u32_e32 v87, 416, v84
	v_cmp_gt_u32_e64 s[78:79], s98, v87
	v_cndmask_b32_e64 v43, 0, v43, s[50:51]
	v_add_u32_e32 v88, 432, v84
	v_cmp_gt_u32_e64 s[50:51], s98, v88
	v_nop
	v_cndmask_b32_e64 v44, 0, v44, s[30:31]
	v_cndmask_b32_e64 v45, 0, v45, s[36:37]
	v_cndmask_b32_e64 v46, 0, v46, s[78:79]
	v_cndmask_b32_e64 v47, 0, v47, s[50:51]
	v_cvt_pk_bf16_f32 v64, v32, v33
	v_cvt_pk_bf16_f32 v65, v34, v35
	v_cvt_pk_bf16_f32 v66, v36, v37
	v_cvt_pk_bf16_f32 v67, v38, v39
	v_cvt_pk_bf16_f32 v68, v40, v41
	v_cvt_pk_bf16_f32 v69, v42, v43
	v_cvt_pk_bf16_f32 v70, v44, v45
	v_cvt_pk_bf16_f32 v71, v46, v47
	v_pk_add_f32 v[232:233], v[232:233], v[32:33]
	v_pk_add_f32 v[232:233], v[232:233], v[34:35]
	v_pk_add_f32 v[232:233], v[232:233], v[36:37]
	v_pk_add_f32 v[232:233], v[232:233], v[38:39]
	v_pk_add_f32 v[232:233], v[232:233], v[40:41]
	v_pk_add_f32 v[232:233], v[232:233], v[42:43]
	v_pk_add_f32 v[232:233], v[232:233], v[44:45]
	v_pk_add_f32 v[232:233], v[232:233], v[46:47]
	s_waitcnt lgkmcnt(0)
	v_mfma_f32_32x32x16_bf16 v[0:15], v[64:67], v[72:75], v[0:15]
	v_mfma_f32_32x32x16_bf16 v[16:31], v[64:67], v[76:79], v[16:31]
	v_mfma_f32_32x32x16_bf16 v[0:15], v[68:71], v[220:223], v[0:15]
	v_mfma_f32_32x32x16_bf16 v[16:31], v[68:71], v[224:227], v[16:31]
	v_add_f32_e32 v113, v232, v233
	v_or_b32_e32 v114, 1, v107
	v_or_b32_e32 v97, 2, v107
	v_or_b32_e32 v96, 3, v107
	v_or_b32_e32 v95, 8, v107
	v_or_b32_e32 v94, 9, v107
	v_or_b32_e32 v93, 10, v107
	v_or_b32_e32 v92, 11, v107
	v_or_b32_e32 v91, 16, v107
	v_or_b32_e32 v90, 17, v107
	v_or_b32_e32 v89, 18, v107
	v_or_b32_e32 v88, 19, v107
	v_or_b32_e32 v87, 24, v107
	v_or_b32_e32 v86, 25, v107
	v_or_b32_e32 v85, 26, v107
	v_or_b32_e32 v84, 27, v107
	s_nop 11
	s_branch .LBB0_1265
